# GEMM phases: non-nt epilogue stores of each workgroup's last tile issued write-through (sc1) to shorten the barrier release fence
# baseline (speedup 1.0000x reference)
; #define PG8_STAGE(bufoff, gbase, voff) do { _Pragma("unroll") for (int _i = 0; _i < 2; ++_i) \
;         __builtin_amdgcn_global_load_lds((const unsigned*)((const char*)(gbase) + (voff)[_i]), (LAS unsigned*)(lds + (bufoff) + ldsw + _i * 8192), 16, 0, 0); } while (0)
; #define PG8_LDA(dst, b, h) do { _Pragma("unroll") for (int m = 0; m < 4; ++m) _Pragma("unroll") for (int k = 0; k < 2; ++k) dst[m][k] = *(const LAS bf16x8*)(lds + PG8_SA(b, h) + aoff + m * 2048 + k * 1024); } while (0)
; #define PG8_LDB(dst, b, h) do { _Pragma("unroll") for (int n = 0; n < 2; ++n) _Pragma("unroll") for (int k = 0; k < 2; ++k) dst[n][k] = *(const LAS bf16x8*)(lds + PG8_SB(b, h) + boff + n * 2048 + k * 1024); } while (0)
; #define PG8_MMA(ai, bj, At, Bt) do { __builtin_amdgcn_s_setprio(1); _Pragma("unroll") for (int m = 0; m < 4; ++m) _Pragma("unroll") for (int n = 0; n < 2; ++n) _Pragma("unroll") for (int k = 0; k < 2; ++k) \
;         acc[ai][bj][m][n] = __builtin_amdgcn_mfma_f32_16x16x32_bf16(Bt[n][k], At[m][k], acc[ai][bj][m][n], 0, 0, 0); __builtin_amdgcn_s_setprio(0); } while (0)
; #define PG8_WAIT_V(n) asm volatile("s_waitcnt vmcnt(" #n ")" ::: "memory")
; #define PG8_WAIT_L(n) asm volatile("s_waitcnt lgkmcnt(" #n ")" ::: "memory")
; #define PG8_BAR __builtin_amdgcn_s_barrier()
; #define PG8_SCHED __builtin_amdgcn_sched_barrier(0)
; template <class Epi>
; __device__ __forceinline__ void gemm_phase(LAS unsigned char* lds, const Gemm g, const StaticOrder& S, const Epi& E) {
;     ...
;         for (int t = 0; t < nt; t += 2) {
;             const bool last = (t == nt - 2);
;             const char* a1 = cA + (size_t)(t + 1) * kstep;
;             const char* a2 = last ? nA : cA + (size_t)(t + 2) * kstep; const char* b2 = last ? nB : cB + (size_t)(t + 2) * kstep;
;             const char* a3 = a2 + kstep; const char* b3 = b2 + kstep;
;             PG8_LDB(B0, 0, 0); PG8_LDB(B1, 0, 1); PG8_SCHED; PG8_LDA(At, 0, 0); PG8_STAGE(PG8_SA(1, 1), a1 + hstepA, voffA);
;             PG8_WAIT_V(8); PG8_WAIT_L(0); PG8_BAR; PG8_MMA(0, 0, At, B0); PG8_MMA(0, 1, At, B1); PG8_BAR; PG8_SCHED;
;             PG8_LDA(At, 0, 1); PG8_STAGE(PG8_SB(0, 0), b2, voffB); PG8_STAGE(PG8_SB(0, 1), b2 + hstepB, voffB); PG8_STAGE(PG8_SA(0, 0), a2, voffA);
;             PG8_WAIT_V(8); PG8_WAIT_L(0); PG8_BAR; PG8_MMA(1, 0, At, B0); PG8_MMA(1, 1, At, B1); PG8_BAR; PG8_SCHED;
.LBB0_192:
	ds_read_b128 v[144:147], v153
	ds_read_b128 v[158:161], v153 offset:1024
	ds_read_b128 v[162:165], v153 offset:2048
	ds_read_b128 v[166:169], v153 offset:3072
	ds_read_b128 v[170:173], v154
	ds_read_b128 v[178:181], v154 offset:1024
	ds_read_b128 v[182:185], v154 offset:2048
	ds_read_b128 v[186:189], v154 offset:3072
	s_add_u32 s76, s74, 0xfffc0080
	s_addc_u32 s77, s75, -1
	s_cmp_eq_u32 s89, 12
	s_cselect_b32 s79, s7, s77
	s_cselect_b32 s78, s65, s76
	s_cselect_b32 s77, s63, s88
	s_cselect_b32 s76, s73, s87
	v_lshl_add_u64 v[148:149], s[74:75], 0, v[136:137]
	s_add_i32 m0, s19, 0xc000
	ds_read_b128 v[190:193], v155
	ds_read_b128 v[194:197], v155 offset:1024
	ds_read_b128 v[198:201], v155 offset:2048
	ds_read_b128 v[202:205], v155 offset:3072
	ds_read_b128 v[206:209], v155 offset:4096
	ds_read_b128 v[210:213], v155 offset:5120
	ds_read_b128 v[214:217], v155 offset:6144
	ds_read_b128 v[218:221], v155 offset:7168
	global_load_lds_dwordx4 v[148:149], off
	v_lshl_add_u64 v[148:149], s[74:75], 0, v[138:139]
	s_add_i32 m0, s19, 0xe000
	s_nop 0
	global_load_lds_dwordx4 v[148:149], off
	s_waitcnt vmcnt(8)
	s_waitcnt lgkmcnt(0)
	s_barrier
	s_setprio 1
	s_waitcnt lgkmcnt(0)
	v_mfma_f32_16x16x32_bf16 v[124:127], v[144:147], v[190:193], v[124:127]
	v_mfma_f32_16x16x32_bf16 v[120:123], v[162:165], v[190:193], v[120:123]
	v_mfma_f32_16x16x32_bf16 v[108:111], v[144:147], v[198:201], v[108:111]
	v_mfma_f32_16x16x32_bf16 v[104:107], v[162:165], v[198:201], v[104:107]
	v_mfma_f32_16x16x32_bf16 v[92:95], v[144:147], v[206:209], v[92:95]
	v_mfma_f32_16x16x32_bf16 v[88:91], v[162:165], v[206:209], v[88:91]
	v_mfma_f32_16x16x32_bf16 v[76:79], v[144:147], v[214:217], v[76:79]
	v_mfma_f32_16x16x32_bf16 v[72:75], v[162:165], v[214:217], v[72:75]
	v_mfma_f32_16x16x32_bf16 v[124:127], v[158:161], v[194:197], v[124:127]
	v_mfma_f32_16x16x32_bf16 v[120:123], v[166:169], v[194:197], v[120:123]
	v_mfma_f32_16x16x32_bf16 v[108:111], v[158:161], v[202:205], v[108:111]
	v_mfma_f32_16x16x32_bf16 v[104:107], v[166:169], v[202:205], v[104:107]
	v_mfma_f32_16x16x32_bf16 v[92:95], v[158:161], v[210:213], v[92:95]
	v_mfma_f32_16x16x32_bf16 v[88:91], v[166:169], v[210:213], v[88:91]
	v_mfma_f32_16x16x32_bf16 v[76:79], v[158:161], v[218:221], v[76:79]
	v_mfma_f32_16x16x32_bf16 v[72:75], v[166:169], v[218:221], v[72:75]
	s_setprio 0
	s_setprio 1
	v_mfma_f32_16x16x32_bf16 v[116:119], v[170:173], v[190:193], v[116:119]
	v_mfma_f32_16x16x32_bf16 v[112:115], v[182:185], v[190:193], v[112:115]
	v_mfma_f32_16x16x32_bf16 v[100:103], v[170:173], v[198:201], v[100:103]
	v_mfma_f32_16x16x32_bf16 v[96:99], v[182:185], v[198:201], v[96:99]
	v_mfma_f32_16x16x32_bf16 v[84:87], v[170:173], v[206:209], v[84:87]
	v_mfma_f32_16x16x32_bf16 v[80:83], v[182:185], v[206:209], v[80:83]
	v_mfma_f32_16x16x32_bf16 v[68:71], v[170:173], v[214:217], v[68:71]
	v_mfma_f32_16x16x32_bf16 v[64:67], v[182:185], v[214:217], v[64:67]
	v_mfma_f32_16x16x32_bf16 v[116:119], v[178:181], v[194:197], v[116:119]
	v_mfma_f32_16x16x32_bf16 v[112:115], v[186:189], v[194:197], v[112:115]
	v_mfma_f32_16x16x32_bf16 v[100:103], v[178:181], v[202:205], v[100:103]
	v_mfma_f32_16x16x32_bf16 v[96:99], v[186:189], v[202:205], v[96:99]
	v_mfma_f32_16x16x32_bf16 v[84:87], v[178:181], v[210:213], v[84:87]
	v_mfma_f32_16x16x32_bf16 v[80:83], v[186:189], v[210:213], v[80:83]
	v_mfma_f32_16x16x32_bf16 v[68:71], v[178:181], v[218:221], v[68:71]
	v_mfma_f32_16x16x32_bf16 v[64:67], v[186:189], v[218:221], v[64:67]
	s_setprio 0
	s_barrier
	s_add_i32 s90, s84, s3
	v_lshl_add_u64 v[148:149], s[76:77], 0, v[130:131]
	s_mov_b32 m0, s90
	ds_read_b128 v[190:193], v155 offset:16384
	ds_read_b128 v[194:197], v155 offset:17408
	ds_read_b128 v[198:201], v155 offset:18432
	ds_read_b128 v[202:205], v155 offset:19456
	ds_read_b128 v[206:209], v155 offset:20480
	ds_read_b128 v[210:213], v155 offset:21504
	ds_read_b128 v[214:217], v155 offset:22528
	ds_read_b128 v[218:221], v155 offset:23552
	global_load_lds_dwordx4 v[148:149], off
	s_add_i32 m0, s90, 0x2000
	s_add_u32 s90, s76, 0x40000
	v_lshl_add_u64 v[174:175], s[76:77], 0, v[134:135]
	s_addc_u32 s91, s77, 0
	s_add_i32 s92, s85, s3
	global_load_lds_dwordx4 v[174:175], off
	v_lshl_add_u64 v[222:223], s[90:91], 0, v[130:131]
	s_mov_b32 m0, s92
	v_lshl_add_u64 v[226:227], s[78:79], 0, v[132:133]
	global_load_lds_dwordx4 v[222:223], off
	v_lshl_add_u64 v[222:223], s[90:91], 0, v[134:135]
	s_add_i32 m0, s92, 0x2000
	s_nop 0
	global_load_lds_dwordx4 v[222:223], off
	v_lshl_add_u64 v[222:223], s[78:79], 0, v[128:129]
	s_mov_b32 m0, s19
	s_nop 0
	global_load_lds_dwordx4 v[222:223], off
	s_mov_b32 m0, s23
	s_nop 0
	global_load_lds_dwordx4 v[226:227], off
	s_waitcnt vmcnt(8)
	s_waitcnt lgkmcnt(0)
	s_barrier
; #define PG8_STAGE(bufoff, gbase, voff) do { _Pragma("unroll") for (int _i = 0; _i < 2; ++_i) \
;         __builtin_amdgcn_global_load_lds((const unsigned*)((const char*)(gbase) + (voff)[_i]), (LAS unsigned*)(lds + (bufoff) + ldsw + _i * 8192), 16, 0, 0); } while (0)
; #define PG8_LDA(dst, b, h) do { _Pragma("unroll") for (int m = 0; m < 4; ++m) _Pragma("unroll") for (int k = 0; k < 2; ++k) dst[m][k] = *(const LAS bf16x8*)(lds + PG8_SA(b, h) + aoff + m * 2048 + k * 1024); } while (0)
; #define PG8_LDB(dst, b, h) do { _Pragma("unroll") for (int n = 0; n < 2; ++n) _Pragma("unroll") for (int k = 0; k < 2; ++k) dst[n][k] = *(const LAS bf16x8*)(lds + PG8_SB(b, h) + boff + n * 2048 + k * 1024); } while (0)
; #define PG8_MMA(ai, bj, At, Bt) do { __builtin_amdgcn_s_setprio(1); _Pragma("unroll") for (int m = 0; m < 4; ++m) _Pragma("unroll") for (int n = 0; n < 2; ++n) _Pragma("unroll") for (int k = 0; k < 2; ++k) \
;         acc[ai][bj][m][n] = __builtin_amdgcn_mfma_f32_16x16x32_bf16(Bt[n][k], At[m][k], acc[ai][bj][m][n], 0, 0, 0); __builtin_amdgcn_s_setprio(0); } while (0)
; #define PG8_WAIT_V(n) asm volatile("s_waitcnt vmcnt(" #n ")" ::: "memory")
; #define PG8_WAIT_L(n) asm volatile("s_waitcnt lgkmcnt(" #n ")" ::: "memory")
; #define PG8_BAR __builtin_amdgcn_s_barrier()
; #define PG8_SCHED __builtin_amdgcn_sched_barrier(0)
; template <class Epi>
; __device__ __forceinline__ void gemm_phase(LAS unsigned char* lds, const Gemm g, const StaticOrder& S, const Epi& E) {
;     ...
;             PG8_WAIT_V(8); PG8_WAIT_L(0); PG8_BAR; PG8_MMA(1, 0, At, B0); PG8_MMA(1, 1, At, B1); PG8_BAR; PG8_SCHED;
;             PG8_LDB(B0, 1, 0); PG8_LDB(B1, 1, 1); PG8_SCHED; PG8_LDA(At, 1, 0); PG8_STAGE(PG8_SA(0, 1), a2 + hstepA, voffA);
;             PG8_WAIT_V(8); PG8_WAIT_L(0); PG8_BAR; PG8_MMA(0, 0, At, B0); PG8_MMA(0, 1, At, B1); PG8_BAR; PG8_SCHED;
	s_setprio 1
	s_waitcnt lgkmcnt(0)
	v_mfma_f32_16x16x32_bf16 v[60:63], v[144:147], v[190:193], v[60:63]
	v_mfma_f32_16x16x32_bf16 v[56:59], v[162:165], v[190:193], v[56:59]
	v_mfma_f32_16x16x32_bf16 v[44:47], v[144:147], v[198:201], v[44:47]
	v_mfma_f32_16x16x32_bf16 v[40:43], v[162:165], v[198:201], v[40:43]
	v_mfma_f32_16x16x32_bf16 v[28:31], v[144:147], v[206:209], v[28:31]
	v_mfma_f32_16x16x32_bf16 v[24:27], v[162:165], v[206:209], v[24:27]
	v_mfma_f32_16x16x32_bf16 v[12:15], v[144:147], v[214:217], v[12:15]
	v_mfma_f32_16x16x32_bf16 v[8:11], v[162:165], v[214:217], v[8:11]
	v_mfma_f32_16x16x32_bf16 v[60:63], v[158:161], v[194:197], v[60:63]
	v_mfma_f32_16x16x32_bf16 v[56:59], v[166:169], v[194:197], v[56:59]
	v_mfma_f32_16x16x32_bf16 v[44:47], v[158:161], v[202:205], v[44:47]
	v_mfma_f32_16x16x32_bf16 v[40:43], v[166:169], v[202:205], v[40:43]
	v_mfma_f32_16x16x32_bf16 v[28:31], v[158:161], v[210:213], v[28:31]
	v_mfma_f32_16x16x32_bf16 v[24:27], v[166:169], v[210:213], v[24:27]
	v_mfma_f32_16x16x32_bf16 v[12:15], v[158:161], v[218:221], v[12:15]
	v_mfma_f32_16x16x32_bf16 v[8:11], v[166:169], v[218:221], v[8:11]
	s_setprio 0
	s_setprio 1
	v_mfma_f32_16x16x32_bf16 v[52:55], v[170:173], v[190:193], v[52:55]
	v_mfma_f32_16x16x32_bf16 v[48:51], v[182:185], v[190:193], v[48:51]
	v_mfma_f32_16x16x32_bf16 v[36:39], v[170:173], v[198:201], v[36:39]
	v_mfma_f32_16x16x32_bf16 v[32:35], v[182:185], v[198:201], v[32:35]
	v_mfma_f32_16x16x32_bf16 v[20:23], v[170:173], v[206:209], v[20:23]
	v_mfma_f32_16x16x32_bf16 v[16:19], v[182:185], v[206:209], v[16:19]
	v_mfma_f32_16x16x32_bf16 v[4:7], v[170:173], v[214:217], v[4:7]
	v_mfma_f32_16x16x32_bf16 v[0:3], v[182:185], v[214:217], v[0:3]
	v_mfma_f32_16x16x32_bf16 v[52:55], v[178:181], v[194:197], v[52:55]
	v_mfma_f32_16x16x32_bf16 v[48:51], v[186:189], v[194:197], v[48:51]
	v_mfma_f32_16x16x32_bf16 v[36:39], v[178:181], v[202:205], v[36:39]
	v_mfma_f32_16x16x32_bf16 v[32:35], v[186:189], v[202:205], v[32:35]
	v_mfma_f32_16x16x32_bf16 v[20:23], v[178:181], v[210:213], v[20:23]
	v_mfma_f32_16x16x32_bf16 v[16:19], v[186:189], v[210:213], v[16:19]
	v_mfma_f32_16x16x32_bf16 v[4:7], v[178:181], v[218:221], v[4:7]
	v_mfma_f32_16x16x32_bf16 v[0:3], v[186:189], v[218:221], v[0:3]
	s_setprio 0
	s_barrier
	s_add_i32 s90, 0, 0x18000
	v_add_u32_e32 v157, s90, v152
	s_add_i32 s91, 0, 0x1c000
	ds_read_b128 v[144:147], v157
	ds_read_b128 v[158:161], v157 offset:1024
	ds_read_b128 v[162:165], v157 offset:2048
	ds_read_b128 v[166:169], v157 offset:3072
	v_add_u32_e32 v157, s91, v152
	ds_read_b128 v[170:173], v157
	ds_read_b128 v[178:181], v157 offset:1024
	ds_read_b128 v[182:185], v157 offset:2048
	ds_read_b128 v[186:189], v157 offset:3072
	s_add_u32 s78, s78, 0x40000
	s_addc_u32 s79, s79, 0
	s_mov_b32 m0, s33
	v_lshl_add_u64 v[228:229], s[78:79], 0, v[128:129]
	ds_read_b128 v[190:193], v155 offset:32768
	ds_read_b128 v[194:197], v155 offset:33792
	ds_read_b128 v[198:201], v155 offset:34816
	ds_read_b128 v[202:205], v155 offset:35840
	ds_read_b128 v[206:209], v155 offset:36864
	ds_read_b128 v[210:213], v155 offset:37888
	ds_read_b128 v[214:217], v155 offset:38912
	ds_read_b128 v[218:221], v155 offset:39936
	global_load_lds_dwordx4 v[228:229], off
	v_lshl_add_u64 v[228:229], s[78:79], 0, v[132:133]
	s_mov_b32 m0, s35
	s_nop 0
	global_load_lds_dwordx4 v[228:229], off
	s_waitcnt vmcnt(8)
	s_waitcnt lgkmcnt(0)
	s_barrier
	s_setprio 1
	s_waitcnt lgkmcnt(0)
	v_mfma_f32_16x16x32_bf16 v[124:127], v[144:147], v[190:193], v[124:127]
	v_mfma_f32_16x16x32_bf16 v[120:123], v[162:165], v[190:193], v[120:123]
	v_mfma_f32_16x16x32_bf16 v[108:111], v[144:147], v[198:201], v[108:111]
	v_mfma_f32_16x16x32_bf16 v[104:107], v[162:165], v[198:201], v[104:107]
	v_mfma_f32_16x16x32_bf16 v[92:95], v[144:147], v[206:209], v[92:95]
	v_mfma_f32_16x16x32_bf16 v[88:91], v[162:165], v[206:209], v[88:91]
	v_mfma_f32_16x16x32_bf16 v[76:79], v[144:147], v[214:217], v[76:79]
	v_mfma_f32_16x16x32_bf16 v[72:75], v[162:165], v[214:217], v[72:75]
	v_mfma_f32_16x16x32_bf16 v[124:127], v[158:161], v[194:197], v[124:127]
	v_mfma_f32_16x16x32_bf16 v[120:123], v[166:169], v[194:197], v[120:123]
	v_mfma_f32_16x16x32_bf16 v[108:111], v[158:161], v[202:205], v[108:111]
	v_mfma_f32_16x16x32_bf16 v[104:107], v[166:169], v[202:205], v[104:107]
	v_mfma_f32_16x16x32_bf16 v[92:95], v[158:161], v[210:213], v[92:95]
	v_mfma_f32_16x16x32_bf16 v[88:91], v[166:169], v[210:213], v[88:91]
	v_mfma_f32_16x16x32_bf16 v[76:79], v[158:161], v[218:221], v[76:79]
	v_mfma_f32_16x16x32_bf16 v[72:75], v[166:169], v[218:221], v[72:75]
	s_setprio 0
	s_setprio 1
	v_mfma_f32_16x16x32_bf16 v[116:119], v[170:173], v[190:193], v[116:119]
	v_mfma_f32_16x16x32_bf16 v[112:115], v[182:185], v[190:193], v[112:115]
	v_mfma_f32_16x16x32_bf16 v[100:103], v[170:173], v[198:201], v[100:103]
	v_mfma_f32_16x16x32_bf16 v[96:99], v[182:185], v[198:201], v[96:99]
	v_mfma_f32_16x16x32_bf16 v[84:87], v[170:173], v[206:209], v[84:87]
	v_mfma_f32_16x16x32_bf16 v[80:83], v[182:185], v[206:209], v[80:83]
	v_mfma_f32_16x16x32_bf16 v[68:71], v[170:173], v[214:217], v[68:71]
	v_mfma_f32_16x16x32_bf16 v[64:67], v[182:185], v[214:217], v[64:67]
	v_mfma_f32_16x16x32_bf16 v[116:119], v[178:181], v[194:197], v[116:119]
	v_mfma_f32_16x16x32_bf16 v[112:115], v[186:189], v[194:197], v[112:115]
	v_mfma_f32_16x16x32_bf16 v[100:103], v[178:181], v[202:205], v[100:103]
	v_mfma_f32_16x16x32_bf16 v[96:99], v[186:189], v[202:205], v[96:99]
	v_mfma_f32_16x16x32_bf16 v[84:87], v[178:181], v[210:213], v[84:87]
	v_mfma_f32_16x16x32_bf16 v[80:83], v[186:189], v[210:213], v[80:83]
	v_mfma_f32_16x16x32_bf16 v[68:71], v[178:181], v[218:221], v[68:71]
	v_mfma_f32_16x16x32_bf16 v[64:67], v[186:189], v[218:221], v[64:67]
	s_setprio 0
	s_barrier
; #define PG8_STAGE(bufoff, gbase, voff) do { _Pragma("unroll") for (int _i = 0; _i < 2; ++_i) \
;         __builtin_amdgcn_global_load_lds((const unsigned*)((const char*)(gbase) + (voff)[_i]), (LAS unsigned*)(lds + (bufoff) + ldsw + _i * 8192), 16, 0, 0); } while (0)
; #define PG8_LDA(dst, b, h) do { _Pragma("unroll") for (int m = 0; m < 4; ++m) _Pragma("unroll") for (int k = 0; k < 2; ++k) dst[m][k] = *(const LAS bf16x8*)(lds + PG8_SA(b, h) + aoff + m * 2048 + k * 1024); } while (0)
; #define PG8_MMA(ai, bj, At, Bt) do { __builtin_amdgcn_s_setprio(1); _Pragma("unroll") for (int m = 0; m < 4; ++m) _Pragma("unroll") for (int n = 0; n < 2; ++n) _Pragma("unroll") for (int k = 0; k < 2; ++k) \
;         acc[ai][bj][m][n] = __builtin_amdgcn_mfma_f32_16x16x32_bf16(Bt[n][k], At[m][k], acc[ai][bj][m][n], 0, 0, 0); __builtin_amdgcn_s_setprio(0); } while (0)
; #define PG8_WAIT_V(n) asm volatile("s_waitcnt vmcnt(" #n ")" ::: "memory")
; #define PG8_WAIT_L(n) asm volatile("s_waitcnt lgkmcnt(" #n ")" ::: "memory")
; #define PG8_BAR __builtin_amdgcn_s_barrier()
; #define PG8_SCHED __builtin_amdgcn_sched_barrier(0)
; template <class Epi>
; __device__ __forceinline__ void gemm_phase(LAS unsigned char* lds, const Gemm g, const StaticOrder& S, const Epi& E) {
;     ...
;             PG8_LDA(At, 1, 1); PG8_STAGE(PG8_SB(1, 0), b3, voffB); PG8_STAGE(PG8_SB(1, 1), b3 + hstepB, voffB); PG8_STAGE(PG8_SA(1, 0), a3, voffA);
;             PG8_WAIT_V(8); PG8_WAIT_L(0); PG8_BAR; PG8_MMA(1, 0, At, B0); PG8_MMA(1, 1, At, B1); PG8_BAR; PG8_SCHED;
;         }
;         if (wr == 0) PG8_BAR;
	s_add_i32 s78, s90, s3
	v_lshl_add_u64 v[148:149], v[148:149], 0, s[12:13]
	s_mov_b32 m0, s78
	ds_read_b128 v[190:193], v155 offset:49152
	ds_read_b128 v[194:197], v155 offset:50176
	ds_read_b128 v[198:201], v155 offset:51200
	ds_read_b128 v[202:205], v155 offset:52224
	ds_read_b128 v[206:209], v155 offset:53248
	ds_read_b128 v[210:213], v155 offset:54272
	ds_read_b128 v[214:217], v155 offset:55296
	ds_read_b128 v[218:221], v155 offset:56320
	global_load_lds_dwordx4 v[148:149], off
	s_add_i32 m0, s78, 0x2000
	s_add_u32 s76, s76, 0x40080
	v_lshl_add_u64 v[148:149], v[174:175], 0, s[12:13]
	s_addc_u32 s77, s77, 0
	s_add_i32 s78, s91, s3
	global_load_lds_dwordx4 v[148:149], off
	v_lshl_add_u64 v[148:149], s[76:77], 0, v[130:131]
	s_mov_b32 m0, s78
	s_nop 0
	global_load_lds_dwordx4 v[148:149], off
	v_lshl_add_u64 v[148:149], s[76:77], 0, v[134:135]
	s_add_i32 m0, s78, 0x2000
	s_nop 0
	global_load_lds_dwordx4 v[148:149], off
	v_lshl_add_u64 v[148:149], v[222:223], 0, s[12:13]
	s_mov_b32 m0, s57
	s_nop 0
	global_load_lds_dwordx4 v[148:149], off
	v_lshl_add_u64 v[148:149], v[226:227], 0, s[12:13]
	s_mov_b32 m0, s80
	s_nop 0
	global_load_lds_dwordx4 v[148:149], off
	s_waitcnt vmcnt(8)
	s_waitcnt lgkmcnt(0)
	s_barrier
	s_setprio 1
	s_waitcnt lgkmcnt(0)
	v_mfma_f32_16x16x32_bf16 v[60:63], v[144:147], v[190:193], v[60:63]
	v_mfma_f32_16x16x32_bf16 v[56:59], v[162:165], v[190:193], v[56:59]
	v_mfma_f32_16x16x32_bf16 v[44:47], v[144:147], v[198:201], v[44:47]
	v_mfma_f32_16x16x32_bf16 v[40:43], v[162:165], v[198:201], v[40:43]
	v_mfma_f32_16x16x32_bf16 v[28:31], v[144:147], v[206:209], v[28:31]
	v_mfma_f32_16x16x32_bf16 v[24:27], v[162:165], v[206:209], v[24:27]
	v_mfma_f32_16x16x32_bf16 v[12:15], v[144:147], v[214:217], v[12:15]
	v_mfma_f32_16x16x32_bf16 v[8:11], v[162:165], v[214:217], v[8:11]
	v_mfma_f32_16x16x32_bf16 v[60:63], v[158:161], v[194:197], v[60:63]
	v_mfma_f32_16x16x32_bf16 v[56:59], v[166:169], v[194:197], v[56:59]
	v_mfma_f32_16x16x32_bf16 v[44:47], v[158:161], v[202:205], v[44:47]
	v_mfma_f32_16x16x32_bf16 v[40:43], v[166:169], v[202:205], v[40:43]
	v_mfma_f32_16x16x32_bf16 v[28:31], v[158:161], v[210:213], v[28:31]
	v_mfma_f32_16x16x32_bf16 v[24:27], v[166:169], v[210:213], v[24:27]
	v_mfma_f32_16x16x32_bf16 v[12:15], v[158:161], v[218:221], v[12:15]
	v_mfma_f32_16x16x32_bf16 v[8:11], v[166:169], v[218:221], v[8:11]
	s_setprio 0
	s_setprio 1
	v_mfma_f32_16x16x32_bf16 v[52:55], v[170:173], v[190:193], v[52:55]
	v_mfma_f32_16x16x32_bf16 v[48:51], v[182:185], v[190:193], v[48:51]
	v_mfma_f32_16x16x32_bf16 v[36:39], v[170:173], v[198:201], v[36:39]
	v_mfma_f32_16x16x32_bf16 v[32:35], v[182:185], v[198:201], v[32:35]
	v_mfma_f32_16x16x32_bf16 v[20:23], v[170:173], v[206:209], v[20:23]
	v_mfma_f32_16x16x32_bf16 v[16:19], v[182:185], v[206:209], v[16:19]
	v_mfma_f32_16x16x32_bf16 v[4:7], v[170:173], v[214:217], v[4:7]
	v_mfma_f32_16x16x32_bf16 v[0:3], v[182:185], v[214:217], v[0:3]
	v_mfma_f32_16x16x32_bf16 v[52:55], v[178:181], v[194:197], v[52:55]
	v_mfma_f32_16x16x32_bf16 v[48:51], v[186:189], v[194:197], v[48:51]
	v_mfma_f32_16x16x32_bf16 v[36:39], v[178:181], v[202:205], v[36:39]
	v_mfma_f32_16x16x32_bf16 v[32:35], v[186:189], v[202:205], v[32:35]
	v_mfma_f32_16x16x32_bf16 v[20:23], v[178:181], v[210:213], v[20:23]
	v_mfma_f32_16x16x32_bf16 v[16:19], v[186:189], v[210:213], v[16:19]
	v_mfma_f32_16x16x32_bf16 v[4:7], v[178:181], v[218:221], v[4:7]
	v_mfma_f32_16x16x32_bf16 v[0:3], v[186:189], v[218:221], v[0:3]
	s_setprio 0
	s_barrier
	s_add_i32 s89, s89, 2
	s_add_u32 s74, s74, 0x100
	s_addc_u32 s75, s75, 0
	s_add_u32 s87, s87, 0x100
	s_addc_u32 s88, s88, 0
	s_cmp_gt_u32 s89, 13
	s_cbranch_scc0 .LBB0_192
	s_cmp_eq_u64 s[4:5], 0
	s_cselect_b32 s99, 1, 0
	s_and_b64 vcc, exec, s[14:15]
	s_cbranch_vccz .LBB0_195
	s_barrier

; #define EPI_IT_ROW(it) EPI_ROW((it) >> 2, (it) & 3)
; #define EPI_PACK8(v0, v1) (u32x4){pk2((v0)[0], (v0)[1]), pk2((v0)[2], (v0)[3]), pk2((v1)[0], (v1)[1]), pk2((v1)[2], (v1)[3])}
; __device__ __forceinline__ f32x2 gelu_pk(f32x2 v) {
;     const f32x2 av = __builtin_elementwise_abs(v), d = av * 0.2316418882f + 1.0f;
;     f32x2 t; t.x = __builtin_amdgcn_rcpf(d.x); t.y = __builtin_amdgcn_rcpf(d.y);
;     f32x2 q = t * 0.5307027145f + (-0.7265760135f); q = q * t + 0.7107068705f; q = q * t + (-0.142248368f); q = q * t + 0.127414796f; q = q * t;
;     const f32x2 s = (v * v) * (-0.72134752044f);
;     f32x2 e; e.x = __builtin_amdgcn_exp2f(s.x); e.y = __builtin_amdgcn_exp2f(s.y);
;     const f32x2 m = v * (q * e), r = v - m;
;     f32x2 o; o.x = v.x < 0.f ? m.x : r.x; o.y = v.y < 0.f ? m.y : r.y; return o;
; }
; __device__ __forceinline__ f32x4 gelu4(f32x4 v) { const f32x2 a = gelu_pk((f32x2){v[0], v[1]}), b = gelu_pk((f32x2){v[2], v[3]}); return (f32x4){a.x, a.y, b.x, b.y}; }
;     __device__ __forceinline__ void operator()(AccRef acc, const Unit& u, int wr, int wc, int fr, int fq) const {
;     ...
;         for (int it = 0; it < 8; ++it) { const int ai = it >> 2, m = it & 3, row = EPI_IT_ROW(it);
; #pragma unroll
;             for (int bj = 0; bj < 2; ++bj) { f32x4 v0 = acc[ai][bj][m][0] * rr[it], v1 = acc[ai][bj][m][1] * rr[it];
;                 if (act) { v0 = gelu4(v0); v1 = gelu4(v1); }
;                 *(u32x4*)(O + (size_t)row * AB_IN + EPI_COL(bj)) = EPI_PACK8(v0, v1); } }
.LBB0_197:
	s_lshl_b32 s6, s6, 8
	s_or_b32 s6, s6, s43
	v_lshl_add_u32 v120, v163, 3, s6
	v_cvt_pk_bf16_f32 v124, v124, v125
	v_cvt_pk_bf16_f32 v125, v126, v127
	v_cvt_pk_bf16_f32 v127, v122, v123
	v_mov_b64_e32 v[122:123], s[26:27]
	v_mad_i64_i32 v[122:123], s[6:7], v144, s86, v[122:123]
	v_ashrrev_i32_e32 v121, 31, v120
	v_lshl_add_u64 v[122:123], v[120:121], 1, v[122:123]
	v_cvt_pk_bf16_f32 v126, v148, v149
	s_cmp_lg_u32 s99, 0
	s_cbranch_scc1 .Lwt192_4151
	global_store_dwordx4 v[122:123], v[124:127], off
	s_branch .Lwj192_4151
.Lwt192_4151:
	global_store_dwordx4 v[122:123], v[124:127], off sc1
.Lwj192_4151:
	v_mov_b32_e32 v147, v146
	v_pk_mul_f32 v[116:117], v[116:117], v[146:147]
	v_mov_b32_e32 v124, v146
	v_mov_b32_e32 v125, v146
	v_pk_mul_f32 v[118:119], v[118:119], v[124:125]
	v_pk_mul_f32 v[114:115], v[114:115], v[124:125]
	v_cndmask_b32_e64 v124, 0, 1, s[72:73]
	v_cmp_ne_u32_e64 s[6:7], 1, v124
	s_andn2_b64 vcc, exec, s[72:73]
	v_pk_mul_f32 v[124:125], v[112:113], v[146:147]
	s_cbranch_vccnz .LBB0_199
	v_and_b32_e32 v113, 0x7fffffff, v117
	v_and_b32_e32 v112, 0x7fffffff, v116
	v_pk_fma_f32 v[112:113], v[112:113], s[18:19], 1.0 op_sel_hi:[1,0,0]
	v_mov_b64_e32 v[126:127], s[34:35]
	v_rcp_f32_e32 v112, v112
	v_rcp_f32_e32 v113, v113
	v_pk_mul_f32 v[148:149], v[116:117], v[116:117]
	v_and_b32_e32 v165, 0x7fffffff, v119
	v_pk_mul_f32 v[148:149], v[148:149], s[56:57] op_sel_hi:[1,0]
	v_pk_fma_f32 v[146:147], v[112:113], s[22:23], v[126:127] op_sel_hi:[1,0,0]
	v_exp_f32_e32 v148, v148
	v_pk_fma_f32 v[146:147], v[112:113], v[146:147], s[38:39] op_sel_hi:[1,1,0]
	v_exp_f32_e32 v149, v149
	v_pk_fma_f32 v[146:147], v[112:113], v[146:147], s[40:41] op_sel_hi:[1,1,0]
	v_and_b32_e32 v164, 0x7fffffff, v118
	v_pk_fma_f32 v[146:147], v[112:113], v[146:147], s[42:43] op_sel_hi:[1,1,0]
	v_pk_fma_f32 v[164:165], v[164:165], s[18:19], 1.0 op_sel_hi:[1,0,0]
	v_pk_mul_f32 v[112:113], v[112:113], v[146:147]
	v_rcp_f32_e32 v164, v164
	v_rcp_f32_e32 v165, v165
	v_pk_mul_f32 v[112:113], v[148:149], v[112:113]
	v_cmp_gt_f32_e32 vcc, 0, v116
	v_pk_mul_f32 v[148:149], v[116:117], v[112:113]
	v_pk_fma_f32 v[112:113], v[116:117], v[112:113], v[116:117] neg_lo:[1,0,0] neg_hi:[1,0,0]
	v_pk_mul_f32 v[146:147], v[118:119], v[118:119]
	v_cndmask_b32_e32 v116, v112, v148, vcc
	v_cmp_gt_f32_e32 vcc, 0, v117
	v_pk_mul_f32 v[146:147], v[146:147], s[56:57] op_sel_hi:[1,0]
	v_and_b32_e32 v148, 0x7fffffff, v124
	v_cndmask_b32_e32 v117, v113, v149, vcc
	v_pk_fma_f32 v[112:113], v[164:165], s[22:23], v[126:127] op_sel_hi:[1,0,0]
	v_exp_f32_e32 v146, v146
	v_pk_fma_f32 v[112:113], v[164:165], v[112:113], s[38:39] op_sel_hi:[1,1,0]
	v_exp_f32_e32 v147, v147
	v_pk_fma_f32 v[112:113], v[164:165], v[112:113], s[40:41] op_sel_hi:[1,1,0]
	v_and_b32_e32 v149, 0x7fffffff, v125
	v_pk_fma_f32 v[112:113], v[164:165], v[112:113], s[42:43] op_sel_hi:[1,1,0]
	v_pk_fma_f32 v[148:149], v[148:149], s[18:19], 1.0 op_sel_hi:[1,0,0]
	v_pk_mul_f32 v[112:113], v[164:165], v[112:113]
	v_rcp_f32_e32 v148, v148
	v_pk_mul_f32 v[112:113], v[146:147], v[112:113]
	v_rcp_f32_e32 v149, v149
	v_pk_mul_f32 v[146:147], v[118:119], v[112:113]
	v_pk_fma_f32 v[112:113], v[118:119], v[112:113], v[118:119] neg_lo:[1,0,0] neg_hi:[1,0,0]
	v_cmp_gt_f32_e32 vcc, 0, v118
	v_and_b32_e32 v165, 0x7fffffff, v115
	v_and_b32_e32 v164, 0x7fffffff, v114
	v_cndmask_b32_e32 v118, v112, v146, vcc
	v_cmp_gt_f32_e32 vcc, 0, v119
	v_pk_fma_f32 v[164:165], v[164:165], s[18:19], 1.0 op_sel_hi:[1,0,0]
	s_nop 0
	v_cndmask_b32_e32 v119, v113, v147, vcc
	v_pk_mul_f32 v[146:147], v[124:125], v[124:125]
	v_pk_fma_f32 v[112:113], v[148:149], s[22:23], v[126:127] op_sel_hi:[1,0,0]
	v_pk_mul_f32 v[146:147], v[146:147], s[56:57] op_sel_hi:[1,0]
	v_pk_fma_f32 v[112:113], v[148:149], v[112:113], s[38:39] op_sel_hi:[1,1,0]
	v_exp_f32_e32 v146, v146
	v_exp_f32_e32 v147, v147
	v_pk_fma_f32 v[112:113], v[148:149], v[112:113], s[40:41] op_sel_hi:[1,1,0]
	v_rcp_f32_e32 v164, v164
	v_pk_fma_f32 v[112:113], v[148:149], v[112:113], s[42:43] op_sel_hi:[1,1,0]
	v_rcp_f32_e32 v165, v165
	v_pk_mul_f32 v[112:113], v[148:149], v[112:113]
	v_cmp_gt_f32_e32 vcc, 0, v124
	v_pk_mul_f32 v[112:113], v[146:147], v[112:113]
	v_pk_mul_f32 v[148:149], v[114:115], v[114:115]
	v_pk_mul_f32 v[146:147], v[124:125], v[112:113]
	v_pk_fma_f32 v[112:113], v[124:125], v[112:113], v[124:125] neg_lo:[1,0,0] neg_hi:[1,0,0]
	s_nop 0
	v_cndmask_b32_e32 v124, v112, v146, vcc
	v_cmp_gt_f32_e32 vcc, 0, v125
	s_nop 1
	v_cndmask_b32_e32 v125, v113, v147, vcc
	v_pk_fma_f32 v[112:113], v[164:165], s[22:23], v[126:127] op_sel_hi:[1,0,0]
	v_pk_mul_f32 v[126:127], v[148:149], s[56:57] op_sel_hi:[1,0]
	v_pk_fma_f32 v[112:113], v[164:165], v[112:113], s[38:39] op_sel_hi:[1,1,0]
	v_exp_f32_e32 v126, v126
	v_exp_f32_e32 v127, v127
	v_pk_fma_f32 v[112:113], v[164:165], v[112:113], s[40:41] op_sel_hi:[1,1,0]
	v_cmp_gt_f32_e32 vcc, 0, v114
	v_pk_fma_f32 v[112:113], v[164:165], v[112:113], s[42:43] op_sel_hi:[1,1,0]
	s_nop 0
	v_pk_mul_f32 v[112:113], v[164:165], v[112:113]
	s_nop 0
	v_pk_mul_f32 v[112:113], v[126:127], v[112:113]
	s_nop 0
	v_pk_mul_f32 v[126:127], v[114:115], v[112:113]
	v_pk_fma_f32 v[112:113], v[114:115], v[112:113], v[114:115] neg_lo:[1,0,0] neg_hi:[1,0,0]
	s_nop 0
	v_cndmask_b32_e32 v114, v112, v126, vcc
	v_cmp_gt_f32_e32 vcc, 0, v115
	s_nop 1
	v_cndmask_b32_e32 v115, v113, v127, vcc
; #define EPI_IT_ROW(it) EPI_ROW((it) >> 2, (it) & 3)
; #define EPI_LOAD_RR(ssp) float rr[8]; _Pragma("unroll") for (int it = 0; it < 8; ++it) rr[it] = (ssp)[EPI_IT_ROW(it)]; _Pragma("unroll") for (int it = 0; it < 8; ++it) rr[it] = rms_r(rr[it])
; #define EPI_PACK8(v0, v1) (u32x4){pk2((v0)[0], (v0)[1]), pk2((v0)[2], (v0)[3]), pk2((v1)[0], (v1)[1]), pk2((v1)[2], (v1)[3])}
; __device__ __forceinline__ f32x2 gelu_pk(f32x2 v) {
;     const f32x2 av = __builtin_elementwise_abs(v), d = av * 0.2316418882f + 1.0f;
;     f32x2 t; t.x = __builtin_amdgcn_rcpf(d.x); t.y = __builtin_amdgcn_rcpf(d.y);
;     f32x2 q = t * 0.5307027145f + (-0.7265760135f); q = q * t + 0.7107068705f; q = q * t + (-0.142248368f); q = q * t + 0.127414796f; q = q * t;
;     const f32x2 s = (v * v) * (-0.72134752044f);
;     f32x2 e; e.x = __builtin_amdgcn_exp2f(s.x); e.y = __builtin_amdgcn_exp2f(s.y);
;     const f32x2 m = v * (q * e), r = v - m;
;     f32x2 o; o.x = v.x < 0.f ? m.x : r.x; o.y = v.y < 0.f ? m.y : r.y; return o;
; }
; __device__ __forceinline__ f32x4 gelu4(f32x4 v) { const f32x2 a = gelu_pk((f32x2){v[0], v[1]}), b = gelu_pk((f32x2){v[2], v[3]}); return (f32x4){a.x, a.y, b.x, b.y}; }
;     __device__ __forceinline__ void operator()(AccRef acc, const Unit& u, int wr, int wc, int fr, int fq) const {
;         asm volatile("" : "+v"(fr), "+v"(fq));
;         const bool act = u.pn < 4;
;         EPI_LOAD_RR(ss);
; #pragma unroll
;         for (int it = 0; it < 8; ++it) { const int ai = it >> 2, m = it & 3, row = EPI_IT_ROW(it);
; #pragma unroll
;             for (int bj = 0; bj < 2; ++bj) { f32x4 v0 = acc[ai][bj][m][0] * rr[it], v1 = acc[ai][bj][m][1] * rr[it];
;                 if (act) { v0 = gelu4(v0); v1 = gelu4(v1); }
;                 *(u32x4*)(O + (size_t)row * AB_IN + EPI_COL(bj)) = EPI_PACK8(v0, v1); } }
.LBB0_199:
	v_fmamk_f32 v112, v162, 0x3a800000, v156
	v_rsq_f32_e32 v112, v112
	s_and_b64 vcc, exec, s[6:7]
	v_cvt_pk_bf16_f32 v116, v116, v117
	v_cvt_pk_bf16_f32 v117, v118, v119
	v_pk_mul_f32 v[110:111], v[110:111], v[112:113] op_sel_hi:[1,0]
	v_pk_mul_f32 v[108:109], v[108:109], v[112:113] op_sel_hi:[1,0]
	v_pk_mul_f32 v[106:107], v[106:107], v[112:113] op_sel_hi:[1,0]
	v_pk_mul_f32 v[104:105], v[104:105], v[112:113] op_sel_hi:[1,0]
	v_cvt_pk_bf16_f32 v118, v124, v125
	v_cvt_pk_bf16_f32 v119, v114, v115
	s_cmp_lg_u32 s99, 0
	s_cbranch_scc1 .Lwt192_4277
	global_store_dwordx4 v[122:123], v[116:119], off offset:256
	s_branch .Lwj192_4277
.Lwt192_4277:
	global_store_dwordx4 v[122:123], v[116:119], off offset:256 sc1
.Lwj192_4277:
	s_cbranch_vccnz .LBB0_201
	v_and_b32_e32 v115, 0x7fffffff, v109
	v_and_b32_e32 v114, 0x7fffffff, v108
	v_pk_fma_f32 v[114:115], v[114:115], s[18:19], 1.0 op_sel_hi:[1,0,0]
	v_mov_b64_e32 v[116:117], s[34:35]
	v_rcp_f32_e32 v114, v114
	v_rcp_f32_e32 v115, v115
	v_pk_mul_f32 v[122:123], v[108:109], v[108:109]
	v_and_b32_e32 v125, 0x7fffffff, v111
	v_pk_mul_f32 v[122:123], v[122:123], s[56:57] op_sel_hi:[1,0]
	v_pk_fma_f32 v[118:119], v[114:115], s[22:23], v[116:117] op_sel_hi:[1,0,0]
	v_exp_f32_e32 v122, v122
	v_pk_fma_f32 v[118:119], v[114:115], v[118:119], s[38:39] op_sel_hi:[1,1,0]
	v_exp_f32_e32 v123, v123
	v_pk_fma_f32 v[118:119], v[114:115], v[118:119], s[40:41] op_sel_hi:[1,1,0]
	v_and_b32_e32 v124, 0x7fffffff, v110
	v_pk_fma_f32 v[118:119], v[114:115], v[118:119], s[42:43] op_sel_hi:[1,1,0]
	v_pk_fma_f32 v[124:125], v[124:125], s[18:19], 1.0 op_sel_hi:[1,0,0]
	v_pk_mul_f32 v[114:115], v[114:115], v[118:119]
	v_rcp_f32_e32 v124, v124
	v_rcp_f32_e32 v125, v125
	v_pk_mul_f32 v[114:115], v[122:123], v[114:115]
	v_cmp_gt_f32_e32 vcc, 0, v108
	v_pk_mul_f32 v[122:123], v[108:109], v[114:115]
	v_pk_fma_f32 v[114:115], v[108:109], v[114:115], v[108:109] neg_lo:[1,0,0] neg_hi:[1,0,0]
	v_pk_mul_f32 v[118:119], v[110:111], v[110:111]
	v_cndmask_b32_e32 v108, v114, v122, vcc
	v_cmp_gt_f32_e32 vcc, 0, v109
	v_pk_mul_f32 v[118:119], v[118:119], s[56:57] op_sel_hi:[1,0]
	v_and_b32_e32 v122, 0x7fffffff, v104
	v_cndmask_b32_e32 v109, v115, v123, vcc
	v_pk_fma_f32 v[114:115], v[124:125], s[22:23], v[116:117] op_sel_hi:[1,0,0]
	v_exp_f32_e32 v118, v118
	v_pk_fma_f32 v[114:115], v[124:125], v[114:115], s[38:39] op_sel_hi:[1,1,0]
	v_exp_f32_e32 v119, v119
	v_pk_fma_f32 v[114:115], v[124:125], v[114:115], s[40:41] op_sel_hi:[1,1,0]
	v_and_b32_e32 v123, 0x7fffffff, v105
	v_pk_fma_f32 v[114:115], v[124:125], v[114:115], s[42:43] op_sel_hi:[1,1,0]
	v_pk_fma_f32 v[122:123], v[122:123], s[18:19], 1.0 op_sel_hi:[1,0,0]
	v_pk_mul_f32 v[114:115], v[124:125], v[114:115]
	v_rcp_f32_e32 v122, v122
	v_pk_mul_f32 v[114:115], v[118:119], v[114:115]
	v_rcp_f32_e32 v123, v123
	v_pk_mul_f32 v[118:119], v[110:111], v[114:115]
	v_pk_fma_f32 v[114:115], v[110:111], v[114:115], v[110:111] neg_lo:[1,0,0] neg_hi:[1,0,0]
	v_cmp_gt_f32_e32 vcc, 0, v110
	v_and_b32_e32 v125, 0x7fffffff, v107
	v_and_b32_e32 v124, 0x7fffffff, v106
	v_cndmask_b32_e32 v110, v114, v118, vcc
	v_cmp_gt_f32_e32 vcc, 0, v111
	v_pk_fma_f32 v[124:125], v[124:125], s[18:19], 1.0 op_sel_hi:[1,0,0]
	s_nop 0
	v_cndmask_b32_e32 v111, v115, v119, vcc
	v_pk_mul_f32 v[118:119], v[104:105], v[104:105]
	v_pk_fma_f32 v[114:115], v[122:123], s[22:23], v[116:117] op_sel_hi:[1,0,0]
	v_pk_mul_f32 v[118:119], v[118:119], s[56:57] op_sel_hi:[1,0]
	v_pk_fma_f32 v[114:115], v[122:123], v[114:115], s[38:39] op_sel_hi:[1,1,0]
	v_exp_f32_e32 v118, v118
	v_exp_f32_e32 v119, v119
	v_pk_fma_f32 v[114:115], v[122:123], v[114:115], s[40:41] op_sel_hi:[1,1,0]
	v_rcp_f32_e32 v124, v124
	v_pk_fma_f32 v[114:115], v[122:123], v[114:115], s[42:43] op_sel_hi:[1,1,0]
	v_rcp_f32_e32 v125, v125
	v_pk_mul_f32 v[114:115], v[122:123], v[114:115]
	v_cmp_gt_f32_e32 vcc, 0, v104
	v_pk_mul_f32 v[114:115], v[118:119], v[114:115]
	v_pk_mul_f32 v[122:123], v[106:107], v[106:107]
	v_pk_mul_f32 v[118:119], v[104:105], v[114:115]
	v_pk_fma_f32 v[114:115], v[104:105], v[114:115], v[104:105] neg_lo:[1,0,0] neg_hi:[1,0,0]
	s_nop 0
	v_cndmask_b32_e32 v104, v114, v118, vcc
	v_cmp_gt_f32_e32 vcc, 0, v105
	s_nop 1
	v_cndmask_b32_e32 v105, v115, v119, vcc
	v_pk_fma_f32 v[114:115], v[124:125], s[22:23], v[116:117] op_sel_hi:[1,0,0]
	v_pk_mul_f32 v[116:117], v[122:123], s[56:57] op_sel_hi:[1,0]
	v_pk_fma_f32 v[114:115], v[124:125], v[114:115], s[38:39] op_sel_hi:[1,1,0]
	v_exp_f32_e32 v116, v116
	v_exp_f32_e32 v117, v117
	v_pk_fma_f32 v[114:115], v[124:125], v[114:115], s[40:41] op_sel_hi:[1,1,0]
	v_cmp_gt_f32_e32 vcc, 0, v106
	v_pk_fma_f32 v[114:115], v[124:125], v[114:115], s[42:43] op_sel_hi:[1,1,0]
	s_nop 0
	v_pk_mul_f32 v[114:115], v[124:125], v[114:115]
	s_nop 0
	v_pk_mul_f32 v[114:115], v[116:117], v[114:115]
	s_nop 0
	v_pk_mul_f32 v[116:117], v[106:107], v[114:115]
	v_pk_fma_f32 v[114:115], v[106:107], v[114:115], v[106:107] neg_lo:[1,0,0] neg_hi:[1,0,0]
	s_nop 0
	v_cndmask_b32_e32 v106, v114, v116, vcc
	v_cmp_gt_f32_e32 vcc, 0, v107
	s_nop 1
	v_cndmask_b32_e32 v107, v115, v117, vcc
.LBB0_201:
	v_add_u32_e32 v114, 16, v144
	v_cvt_pk_bf16_f32 v108, v108, v109
	v_cvt_pk_bf16_f32 v109, v110, v111
	v_cvt_pk_bf16_f32 v110, v104, v105
	v_mov_b64_e32 v[104:105], s[26:27]
	v_mov_b32_e32 v113, v112
	v_cvt_pk_bf16_f32 v111, v106, v107
	v_mad_i64_i32 v[104:105], s[72:73], v114, s86, v[104:105]
	v_mov_b32_e32 v106, v112
	v_mov_b32_e32 v107, v112
	v_lshl_add_u64 v[104:105], v[120:121], 1, v[104:105]
	v_pk_mul_f32 v[102:103], v[102:103], v[106:107]
	v_pk_mul_f32 v[100:101], v[100:101], v[112:113]
	v_pk_mul_f32 v[98:99], v[98:99], v[106:107]
	s_and_b64 vcc, exec, s[6:7]
	v_pk_mul_f32 v[106:107], v[96:97], v[112:113]
	s_cmp_lg_u32 s99, 0
	s_cbranch_scc1 .Lwt192_4398
	global_store_dwordx4 v[104:105], v[108:111], off
	s_branch .Lwj192_4398
; #define EPI_IT_ROW(it) EPI_ROW((it) >> 2, (it) & 3)
; #define EPI_PACK8(v0, v1) (u32x4){pk2((v0)[0], (v0)[1]), pk2((v0)[2], (v0)[3]), pk2((v1)[0], (v1)[1]), pk2((v1)[2], (v1)[3])}
; __device__ __forceinline__ f32x2 gelu_pk(f32x2 v) {
;     const f32x2 av = __builtin_elementwise_abs(v), d = av * 0.2316418882f + 1.0f;
;     f32x2 t; t.x = __builtin_amdgcn_rcpf(d.x); t.y = __builtin_amdgcn_rcpf(d.y);
;     f32x2 q = t * 0.5307027145f + (-0.7265760135f); q = q * t + 0.7107068705f; q = q * t + (-0.142248368f); q = q * t + 0.127414796f; q = q * t;
;     const f32x2 s = (v * v) * (-0.72134752044f);
;     f32x2 e; e.x = __builtin_amdgcn_exp2f(s.x); e.y = __builtin_amdgcn_exp2f(s.y);
;     const f32x2 m = v * (q * e), r = v - m;
;     f32x2 o; o.x = v.x < 0.f ? m.x : r.x; o.y = v.y < 0.f ? m.y : r.y; return o;
; }
; __device__ __forceinline__ f32x4 gelu4(f32x4 v) { const f32x2 a = gelu_pk((f32x2){v[0], v[1]}), b = gelu_pk((f32x2){v[2], v[3]}); return (f32x4){a.x, a.y, b.x, b.y}; }
;     __device__ __forceinline__ void operator()(AccRef acc, const Unit& u, int wr, int wc, int fr, int fq) const {
;     ...
;         for (int it = 0; it < 8; ++it) { const int ai = it >> 2, m = it & 3, row = EPI_IT_ROW(it);
; #pragma unroll
;             for (int bj = 0; bj < 2; ++bj) { f32x4 v0 = acc[ai][bj][m][0] * rr[it], v1 = acc[ai][bj][m][1] * rr[it];
;                 if (act) { v0 = gelu4(v0); v1 = gelu4(v1); }
;                 *(u32x4*)(O + (size_t)row * AB_IN + EPI_COL(bj)) = EPI_PACK8(v0, v1); } }
.Lwt192_4398:
	global_store_dwordx4 v[104:105], v[108:111], off sc1
.Lwj192_4398:
	s_cbranch_vccnz .LBB0_203
	v_and_b32_e32 v97, 0x7fffffff, v101
	v_and_b32_e32 v96, 0x7fffffff, v100
	v_pk_fma_f32 v[96:97], v[96:97], s[18:19], 1.0 op_sel_hi:[1,0,0]
	v_mov_b64_e32 v[108:109], s[34:35]
	v_rcp_f32_e32 v96, v96
	v_rcp_f32_e32 v97, v97
	v_pk_mul_f32 v[112:113], v[100:101], v[100:101]
	v_and_b32_e32 v115, 0x7fffffff, v103
	v_pk_mul_f32 v[112:113], v[112:113], s[56:57] op_sel_hi:[1,0]
	v_pk_fma_f32 v[110:111], v[96:97], s[22:23], v[108:109] op_sel_hi:[1,0,0]
	v_exp_f32_e32 v112, v112
	v_pk_fma_f32 v[110:111], v[96:97], v[110:111], s[38:39] op_sel_hi:[1,1,0]
	v_exp_f32_e32 v113, v113
	v_pk_fma_f32 v[110:111], v[96:97], v[110:111], s[40:41] op_sel_hi:[1,1,0]
	v_and_b32_e32 v114, 0x7fffffff, v102
	v_pk_fma_f32 v[110:111], v[96:97], v[110:111], s[42:43] op_sel_hi:[1,1,0]
	v_pk_fma_f32 v[114:115], v[114:115], s[18:19], 1.0 op_sel_hi:[1,0,0]
	v_pk_mul_f32 v[96:97], v[96:97], v[110:111]
	v_rcp_f32_e32 v114, v114
	v_rcp_f32_e32 v115, v115
	v_pk_mul_f32 v[96:97], v[112:113], v[96:97]
	v_cmp_gt_f32_e32 vcc, 0, v100
	v_pk_mul_f32 v[112:113], v[100:101], v[96:97]
	v_pk_fma_f32 v[96:97], v[100:101], v[96:97], v[100:101] neg_lo:[1,0,0] neg_hi:[1,0,0]
	v_pk_mul_f32 v[110:111], v[102:103], v[102:103]
	v_cndmask_b32_e32 v100, v96, v112, vcc
	v_cmp_gt_f32_e32 vcc, 0, v101
	v_pk_mul_f32 v[110:111], v[110:111], s[56:57] op_sel_hi:[1,0]
	v_and_b32_e32 v112, 0x7fffffff, v106
	v_cndmask_b32_e32 v101, v97, v113, vcc
	v_pk_fma_f32 v[96:97], v[114:115], s[22:23], v[108:109] op_sel_hi:[1,0,0]
	v_exp_f32_e32 v110, v110
	v_pk_fma_f32 v[96:97], v[114:115], v[96:97], s[38:39] op_sel_hi:[1,1,0]
	v_exp_f32_e32 v111, v111
	v_pk_fma_f32 v[96:97], v[114:115], v[96:97], s[40:41] op_sel_hi:[1,1,0]
	v_and_b32_e32 v113, 0x7fffffff, v107
	v_pk_fma_f32 v[96:97], v[114:115], v[96:97], s[42:43] op_sel_hi:[1,1,0]
	v_pk_fma_f32 v[112:113], v[112:113], s[18:19], 1.0 op_sel_hi:[1,0,0]
	v_pk_mul_f32 v[96:97], v[114:115], v[96:97]
	v_rcp_f32_e32 v112, v112
	v_pk_mul_f32 v[96:97], v[110:111], v[96:97]
	v_rcp_f32_e32 v113, v113
	v_pk_mul_f32 v[110:111], v[102:103], v[96:97]
	v_pk_fma_f32 v[96:97], v[102:103], v[96:97], v[102:103] neg_lo:[1,0,0] neg_hi:[1,0,0]
	v_cmp_gt_f32_e32 vcc, 0, v102
	v_and_b32_e32 v115, 0x7fffffff, v99
	v_and_b32_e32 v114, 0x7fffffff, v98
	v_cndmask_b32_e32 v102, v96, v110, vcc
	v_cmp_gt_f32_e32 vcc, 0, v103
	v_pk_fma_f32 v[114:115], v[114:115], s[18:19], 1.0 op_sel_hi:[1,0,0]
	s_nop 0
	v_cndmask_b32_e32 v103, v97, v111, vcc
	v_pk_mul_f32 v[110:111], v[106:107], v[106:107]
	v_pk_fma_f32 v[96:97], v[112:113], s[22:23], v[108:109] op_sel_hi:[1,0,0]
	v_pk_mul_f32 v[110:111], v[110:111], s[56:57] op_sel_hi:[1,0]
	v_pk_fma_f32 v[96:97], v[112:113], v[96:97], s[38:39] op_sel_hi:[1,1,0]
	v_exp_f32_e32 v110, v110
	v_exp_f32_e32 v111, v111
	v_pk_fma_f32 v[96:97], v[112:113], v[96:97], s[40:41] op_sel_hi:[1,1,0]
	v_rcp_f32_e32 v114, v114
	v_pk_fma_f32 v[96:97], v[112:113], v[96:97], s[42:43] op_sel_hi:[1,1,0]
	v_rcp_f32_e32 v115, v115
	v_pk_mul_f32 v[96:97], v[112:113], v[96:97]
	v_cmp_gt_f32_e32 vcc, 0, v106
	v_pk_mul_f32 v[96:97], v[110:111], v[96:97]
	v_pk_mul_f32 v[112:113], v[98:99], v[98:99]
	v_pk_mul_f32 v[110:111], v[106:107], v[96:97]
	v_pk_fma_f32 v[96:97], v[106:107], v[96:97], v[106:107] neg_lo:[1,0,0] neg_hi:[1,0,0]
	s_nop 0
	v_cndmask_b32_e32 v106, v96, v110, vcc
	v_cmp_gt_f32_e32 vcc, 0, v107
	s_nop 1
	v_cndmask_b32_e32 v107, v97, v111, vcc
	v_pk_fma_f32 v[96:97], v[114:115], s[22:23], v[108:109] op_sel_hi:[1,0,0]
	v_pk_mul_f32 v[108:109], v[112:113], s[56:57] op_sel_hi:[1,0]
	v_pk_fma_f32 v[96:97], v[114:115], v[96:97], s[38:39] op_sel_hi:[1,1,0]
	v_exp_f32_e32 v108, v108
	v_exp_f32_e32 v109, v109
	v_pk_fma_f32 v[96:97], v[114:115], v[96:97], s[40:41] op_sel_hi:[1,1,0]
	v_cmp_gt_f32_e32 vcc, 0, v98
	v_pk_fma_f32 v[96:97], v[114:115], v[96:97], s[42:43] op_sel_hi:[1,1,0]
	s_nop 0
	v_pk_mul_f32 v[96:97], v[114:115], v[96:97]
	s_nop 0
	v_pk_mul_f32 v[96:97], v[108:109], v[96:97]
	s_nop 0
	v_pk_mul_f32 v[108:109], v[98:99], v[96:97]
	v_pk_fma_f32 v[96:97], v[98:99], v[96:97], v[98:99] neg_lo:[1,0,0] neg_hi:[1,0,0]
	s_nop 0
	v_cndmask_b32_e32 v98, v96, v108, vcc
	v_cmp_gt_f32_e32 vcc, 0, v99
	s_nop 1
	v_cndmask_b32_e32 v99, v97, v109, vcc
.LBB0_203:
	v_fmamk_f32 v96, v161, 0x3a800000, v156
	v_rsq_f32_e32 v96, v96
	s_and_b64 vcc, exec, s[6:7]
	v_cvt_pk_bf16_f32 v100, v100, v101
	v_cvt_pk_bf16_f32 v101, v102, v103
	v_pk_mul_f32 v[94:95], v[94:95], v[96:97] op_sel_hi:[1,0]
	v_pk_mul_f32 v[92:93], v[92:93], v[96:97] op_sel_hi:[1,0]
	v_pk_mul_f32 v[90:91], v[90:91], v[96:97] op_sel_hi:[1,0]
	v_pk_mul_f32 v[88:89], v[88:89], v[96:97] op_sel_hi:[1,0]
	v_cvt_pk_bf16_f32 v102, v106, v107
	v_cvt_pk_bf16_f32 v103, v98, v99
	s_cmp_lg_u32 s99, 0
	s_cbranch_scc1 .Lwt192_4514
	global_store_dwordx4 v[104:105], v[100:103], off offset:256
	s_branch .Lwj192_4514
.Lwt192_4514:
	global_store_dwordx4 v[104:105], v[100:103], off offset:256 sc1
; #define EPI_IT_ROW(it) EPI_ROW((it) >> 2, (it) & 3)
; #define EPI_PACK8(v0, v1) (u32x4){pk2((v0)[0], (v0)[1]), pk2((v0)[2], (v0)[3]), pk2((v1)[0], (v1)[1]), pk2((v1)[2], (v1)[3])}
; __device__ __forceinline__ f32x2 gelu_pk(f32x2 v) {
;     const f32x2 av = __builtin_elementwise_abs(v), d = av * 0.2316418882f + 1.0f;
;     f32x2 t; t.x = __builtin_amdgcn_rcpf(d.x); t.y = __builtin_amdgcn_rcpf(d.y);
;     f32x2 q = t * 0.5307027145f + (-0.7265760135f); q = q * t + 0.7107068705f; q = q * t + (-0.142248368f); q = q * t + 0.127414796f; q = q * t;
;     const f32x2 s = (v * v) * (-0.72134752044f);
;     f32x2 e; e.x = __builtin_amdgcn_exp2f(s.x); e.y = __builtin_amdgcn_exp2f(s.y);
;     const f32x2 m = v * (q * e), r = v - m;
;     f32x2 o; o.x = v.x < 0.f ? m.x : r.x; o.y = v.y < 0.f ? m.y : r.y; return o;
; }
; __device__ __forceinline__ f32x4 gelu4(f32x4 v) { const f32x2 a = gelu_pk((f32x2){v[0], v[1]}), b = gelu_pk((f32x2){v[2], v[3]}); return (f32x4){a.x, a.y, b.x, b.y}; }
;     __device__ __forceinline__ void operator()(AccRef acc, const Unit& u, int wr, int wc, int fr, int fq) const {
;     ...
;         for (int it = 0; it < 8; ++it) { const int ai = it >> 2, m = it & 3, row = EPI_IT_ROW(it);
; #pragma unroll
;             for (int bj = 0; bj < 2; ++bj) { f32x4 v0 = acc[ai][bj][m][0] * rr[it], v1 = acc[ai][bj][m][1] * rr[it];
;                 if (act) { v0 = gelu4(v0); v1 = gelu4(v1); }
;                 *(u32x4*)(O + (size_t)row * AB_IN + EPI_COL(bj)) = EPI_PACK8(v0, v1); } }
.Lwj192_4514:
	s_cbranch_vccnz .LBB0_205
	v_and_b32_e32 v99, 0x7fffffff, v93
	v_and_b32_e32 v98, 0x7fffffff, v92
	v_pk_fma_f32 v[98:99], v[98:99], s[18:19], 1.0 op_sel_hi:[1,0,0]
	v_mov_b64_e32 v[100:101], s[34:35]
	v_rcp_f32_e32 v98, v98
	v_rcp_f32_e32 v99, v99
	v_pk_mul_f32 v[104:105], v[92:93], v[92:93]
	v_and_b32_e32 v107, 0x7fffffff, v95
	v_pk_mul_f32 v[104:105], v[104:105], s[56:57] op_sel_hi:[1,0]
	v_pk_fma_f32 v[102:103], v[98:99], s[22:23], v[100:101] op_sel_hi:[1,0,0]
	v_exp_f32_e32 v104, v104
	v_pk_fma_f32 v[102:103], v[98:99], v[102:103], s[38:39] op_sel_hi:[1,1,0]
	v_exp_f32_e32 v105, v105
	v_pk_fma_f32 v[102:103], v[98:99], v[102:103], s[40:41] op_sel_hi:[1,1,0]
	v_and_b32_e32 v106, 0x7fffffff, v94
	v_pk_fma_f32 v[102:103], v[98:99], v[102:103], s[42:43] op_sel_hi:[1,1,0]
	v_pk_fma_f32 v[106:107], v[106:107], s[18:19], 1.0 op_sel_hi:[1,0,0]
	v_pk_mul_f32 v[98:99], v[98:99], v[102:103]
	v_rcp_f32_e32 v106, v106
	v_rcp_f32_e32 v107, v107
	v_pk_mul_f32 v[98:99], v[104:105], v[98:99]
	v_cmp_gt_f32_e32 vcc, 0, v92
	v_pk_mul_f32 v[104:105], v[92:93], v[98:99]
	v_pk_fma_f32 v[98:99], v[92:93], v[98:99], v[92:93] neg_lo:[1,0,0] neg_hi:[1,0,0]
	v_pk_mul_f32 v[102:103], v[94:95], v[94:95]
	v_cndmask_b32_e32 v92, v98, v104, vcc
	v_cmp_gt_f32_e32 vcc, 0, v93
	v_pk_mul_f32 v[102:103], v[102:103], s[56:57] op_sel_hi:[1,0]
	v_and_b32_e32 v104, 0x7fffffff, v88
	v_cndmask_b32_e32 v93, v99, v105, vcc
	v_pk_fma_f32 v[98:99], v[106:107], s[22:23], v[100:101] op_sel_hi:[1,0,0]
	v_exp_f32_e32 v102, v102
	v_pk_fma_f32 v[98:99], v[106:107], v[98:99], s[38:39] op_sel_hi:[1,1,0]
	v_exp_f32_e32 v103, v103
	v_pk_fma_f32 v[98:99], v[106:107], v[98:99], s[40:41] op_sel_hi:[1,1,0]
	v_and_b32_e32 v105, 0x7fffffff, v89
	v_pk_fma_f32 v[98:99], v[106:107], v[98:99], s[42:43] op_sel_hi:[1,1,0]
	v_pk_fma_f32 v[104:105], v[104:105], s[18:19], 1.0 op_sel_hi:[1,0,0]
	v_pk_mul_f32 v[98:99], v[106:107], v[98:99]
	v_rcp_f32_e32 v104, v104
	v_pk_mul_f32 v[98:99], v[102:103], v[98:99]
	v_rcp_f32_e32 v105, v105
	v_pk_mul_f32 v[102:103], v[94:95], v[98:99]
	v_pk_fma_f32 v[98:99], v[94:95], v[98:99], v[94:95] neg_lo:[1,0,0] neg_hi:[1,0,0]
	v_cmp_gt_f32_e32 vcc, 0, v94
	v_and_b32_e32 v107, 0x7fffffff, v91
	v_and_b32_e32 v106, 0x7fffffff, v90
	v_cndmask_b32_e32 v94, v98, v102, vcc
	v_cmp_gt_f32_e32 vcc, 0, v95
	v_pk_fma_f32 v[106:107], v[106:107], s[18:19], 1.0 op_sel_hi:[1,0,0]
	s_nop 0
	v_cndmask_b32_e32 v95, v99, v103, vcc
	v_pk_mul_f32 v[102:103], v[88:89], v[88:89]
	v_pk_fma_f32 v[98:99], v[104:105], s[22:23], v[100:101] op_sel_hi:[1,0,0]
	v_pk_mul_f32 v[102:103], v[102:103], s[56:57] op_sel_hi:[1,0]
	v_pk_fma_f32 v[98:99], v[104:105], v[98:99], s[38:39] op_sel_hi:[1,1,0]
	v_exp_f32_e32 v102, v102
	v_exp_f32_e32 v103, v103
	v_pk_fma_f32 v[98:99], v[104:105], v[98:99], s[40:41] op_sel_hi:[1,1,0]
	v_rcp_f32_e32 v106, v106
	v_pk_fma_f32 v[98:99], v[104:105], v[98:99], s[42:43] op_sel_hi:[1,1,0]
	v_rcp_f32_e32 v107, v107
	v_pk_mul_f32 v[98:99], v[104:105], v[98:99]
	v_cmp_gt_f32_e32 vcc, 0, v88
	v_pk_mul_f32 v[98:99], v[102:103], v[98:99]
	v_pk_mul_f32 v[104:105], v[90:91], v[90:91]
	v_pk_mul_f32 v[102:103], v[88:89], v[98:99]
	v_pk_fma_f32 v[98:99], v[88:89], v[98:99], v[88:89] neg_lo:[1,0,0] neg_hi:[1,0,0]
	s_nop 0
	v_cndmask_b32_e32 v88, v98, v102, vcc
	v_cmp_gt_f32_e32 vcc, 0, v89
	s_nop 1
	v_cndmask_b32_e32 v89, v99, v103, vcc
	v_pk_fma_f32 v[98:99], v[106:107], s[22:23], v[100:101] op_sel_hi:[1,0,0]
	v_pk_mul_f32 v[100:101], v[104:105], s[56:57] op_sel_hi:[1,0]
	v_pk_fma_f32 v[98:99], v[106:107], v[98:99], s[38:39] op_sel_hi:[1,1,0]
	v_exp_f32_e32 v100, v100
	v_exp_f32_e32 v101, v101
	v_pk_fma_f32 v[98:99], v[106:107], v[98:99], s[40:41] op_sel_hi:[1,1,0]
	v_cmp_gt_f32_e32 vcc, 0, v90
	v_pk_fma_f32 v[98:99], v[106:107], v[98:99], s[42:43] op_sel_hi:[1,1,0]
	s_nop 0
	v_pk_mul_f32 v[98:99], v[106:107], v[98:99]
	s_nop 0
	v_pk_mul_f32 v[98:99], v[100:101], v[98:99]
	s_nop 0
	v_pk_mul_f32 v[100:101], v[90:91], v[98:99]
	v_pk_fma_f32 v[98:99], v[90:91], v[98:99], v[90:91] neg_lo:[1,0,0] neg_hi:[1,0,0]
	s_nop 0
	v_cndmask_b32_e32 v90, v98, v100, vcc
	v_cmp_gt_f32_e32 vcc, 0, v91
	s_nop 1
	v_cndmask_b32_e32 v91, v99, v101, vcc
.LBB0_205:
	v_add_u32_e32 v98, 32, v144
	v_cvt_pk_bf16_f32 v92, v92, v93
	v_cvt_pk_bf16_f32 v93, v94, v95
	v_cvt_pk_bf16_f32 v94, v88, v89
	v_mov_b64_e32 v[88:89], s[26:27]
	v_mov_b32_e32 v97, v96
	v_cvt_pk_bf16_f32 v95, v90, v91
	v_mad_i64_i32 v[88:89], s[72:73], v98, s86, v[88:89]
	v_mov_b32_e32 v90, v96
	v_mov_b32_e32 v91, v96
	v_lshl_add_u64 v[88:89], v[120:121], 1, v[88:89]
	v_pk_mul_f32 v[86:87], v[86:87], v[90:91]
	v_pk_mul_f32 v[84:85], v[84:85], v[96:97]
	v_pk_mul_f32 v[82:83], v[82:83], v[90:91]
	s_and_b64 vcc, exec, s[6:7]
	v_pk_mul_f32 v[90:91], v[80:81], v[96:97]
	s_cmp_lg_u32 s99, 0
	s_cbranch_scc1 .Lwt192_4635
	global_store_dwordx4 v[88:89], v[92:95], off
	s_branch .Lwj192_4635
.Lwt192_4635:
	global_store_dwordx4 v[88:89], v[92:95], off sc1
; __device__ __forceinline__ f32x4 gelu4(f32x4 v) { const f32x2 a = gelu_pk((f32x2){v[0], v[1]}), b = gelu_pk((f32x2){v[2], v[3]}); return (f32x4){a.x, a.y, b.x, b.y}; }
; #define EPI_IT_ROW(it) EPI_ROW((it) >> 2, (it) & 3)
; #define EPI_LOAD_RR(ssp) float rr[8]; _Pragma("unroll") for (int it = 0; it < 8; ++it) rr[it] = (ssp)[EPI_IT_ROW(it)]; _Pragma("unroll") for (int it = 0; it < 8; ++it) rr[it] = rms_r(rr[it])
; #define EPI_PACK8(v0, v1) (u32x4){pk2((v0)[0], (v0)[1]), pk2((v0)[2], (v0)[3]), pk2((v1)[0], (v1)[1]), pk2((v1)[2], (v1)[3])}
; __device__ __forceinline__ f32x2 gelu_pk(f32x2 v) {
;     const f32x2 av = __builtin_elementwise_abs(v), d = av * 0.2316418882f + 1.0f;
;     f32x2 t; t.x = __builtin_amdgcn_rcpf(d.x); t.y = __builtin_amdgcn_rcpf(d.y);
;     f32x2 q = t * 0.5307027145f + (-0.7265760135f); q = q * t + 0.7107068705f; q = q * t + (-0.142248368f); q = q * t + 0.127414796f; q = q * t;
;     const f32x2 s = (v * v) * (-0.72134752044f);
;     f32x2 e; e.x = __builtin_amdgcn_exp2f(s.x); e.y = __builtin_amdgcn_exp2f(s.y);
;     const f32x2 m = v * (q * e), r = v - m;
;     f32x2 o; o.x = v.x < 0.f ? m.x : r.x; o.y = v.y < 0.f ? m.y : r.y; return o;
;     __device__ __forceinline__ void operator()(AccRef acc, const Unit& u, int wr, int wc, int fr, int fq) const {
;         asm volatile("" : "+v"(fr), "+v"(fq));
;         const bool act = u.pn < 4;
;         EPI_LOAD_RR(ss);
; #pragma unroll
;         for (int it = 0; it < 8; ++it) { const int ai = it >> 2, m = it & 3, row = EPI_IT_ROW(it);
; #pragma unroll
;             for (int bj = 0; bj < 2; ++bj) { f32x4 v0 = acc[ai][bj][m][0] * rr[it], v1 = acc[ai][bj][m][1] * rr[it];
;                 if (act) { v0 = gelu4(v0); v1 = gelu4(v1); }
;                 *(u32x4*)(O + (size_t)row * AB_IN + EPI_COL(bj)) = EPI_PACK8(v0, v1); } }
.Lwj192_4635:
	s_cbranch_vccnz .LBB0_207
	v_and_b32_e32 v81, 0x7fffffff, v85
	v_and_b32_e32 v80, 0x7fffffff, v84
	v_pk_fma_f32 v[80:81], v[80:81], s[18:19], 1.0 op_sel_hi:[1,0,0]
	v_mov_b64_e32 v[92:93], s[34:35]
	v_rcp_f32_e32 v80, v80
	v_rcp_f32_e32 v81, v81
	v_pk_mul_f32 v[96:97], v[84:85], v[84:85]
	v_and_b32_e32 v99, 0x7fffffff, v87
	v_pk_mul_f32 v[96:97], v[96:97], s[56:57] op_sel_hi:[1,0]
	v_pk_fma_f32 v[94:95], v[80:81], s[22:23], v[92:93] op_sel_hi:[1,0,0]
	v_exp_f32_e32 v96, v96
	v_pk_fma_f32 v[94:95], v[80:81], v[94:95], s[38:39] op_sel_hi:[1,1,0]
	v_exp_f32_e32 v97, v97
	v_pk_fma_f32 v[94:95], v[80:81], v[94:95], s[40:41] op_sel_hi:[1,1,0]
	v_and_b32_e32 v98, 0x7fffffff, v86
	v_pk_fma_f32 v[94:95], v[80:81], v[94:95], s[42:43] op_sel_hi:[1,1,0]
	v_pk_fma_f32 v[98:99], v[98:99], s[18:19], 1.0 op_sel_hi:[1,0,0]
	v_pk_mul_f32 v[80:81], v[80:81], v[94:95]
	v_rcp_f32_e32 v98, v98
	v_rcp_f32_e32 v99, v99
	v_pk_mul_f32 v[80:81], v[96:97], v[80:81]
	v_cmp_gt_f32_e32 vcc, 0, v84
	v_pk_mul_f32 v[96:97], v[84:85], v[80:81]
	v_pk_fma_f32 v[80:81], v[84:85], v[80:81], v[84:85] neg_lo:[1,0,0] neg_hi:[1,0,0]
	v_pk_mul_f32 v[94:95], v[86:87], v[86:87]
	v_cndmask_b32_e32 v84, v80, v96, vcc
	v_cmp_gt_f32_e32 vcc, 0, v85
	v_pk_mul_f32 v[94:95], v[94:95], s[56:57] op_sel_hi:[1,0]
	v_and_b32_e32 v96, 0x7fffffff, v90
	v_cndmask_b32_e32 v85, v81, v97, vcc
	v_pk_fma_f32 v[80:81], v[98:99], s[22:23], v[92:93] op_sel_hi:[1,0,0]
	v_exp_f32_e32 v94, v94
	v_pk_fma_f32 v[80:81], v[98:99], v[80:81], s[38:39] op_sel_hi:[1,1,0]
	v_exp_f32_e32 v95, v95
	v_pk_fma_f32 v[80:81], v[98:99], v[80:81], s[40:41] op_sel_hi:[1,1,0]
	v_and_b32_e32 v97, 0x7fffffff, v91
	v_pk_fma_f32 v[80:81], v[98:99], v[80:81], s[42:43] op_sel_hi:[1,1,0]
	v_pk_fma_f32 v[96:97], v[96:97], s[18:19], 1.0 op_sel_hi:[1,0,0]
	v_pk_mul_f32 v[80:81], v[98:99], v[80:81]
	v_rcp_f32_e32 v96, v96
	v_pk_mul_f32 v[80:81], v[94:95], v[80:81]
	v_rcp_f32_e32 v97, v97
	v_pk_mul_f32 v[94:95], v[86:87], v[80:81]
	v_pk_fma_f32 v[80:81], v[86:87], v[80:81], v[86:87] neg_lo:[1,0,0] neg_hi:[1,0,0]
	v_cmp_gt_f32_e32 vcc, 0, v86
	v_and_b32_e32 v99, 0x7fffffff, v83
	v_and_b32_e32 v98, 0x7fffffff, v82
	v_cndmask_b32_e32 v86, v80, v94, vcc
	v_cmp_gt_f32_e32 vcc, 0, v87
	v_pk_fma_f32 v[98:99], v[98:99], s[18:19], 1.0 op_sel_hi:[1,0,0]
	s_nop 0
	v_cndmask_b32_e32 v87, v81, v95, vcc
	v_pk_mul_f32 v[94:95], v[90:91], v[90:91]
	v_pk_fma_f32 v[80:81], v[96:97], s[22:23], v[92:93] op_sel_hi:[1,0,0]
	v_pk_mul_f32 v[94:95], v[94:95], s[56:57] op_sel_hi:[1,0]
	v_pk_fma_f32 v[80:81], v[96:97], v[80:81], s[38:39] op_sel_hi:[1,1,0]
	v_exp_f32_e32 v94, v94
	v_exp_f32_e32 v95, v95
	v_pk_fma_f32 v[80:81], v[96:97], v[80:81], s[40:41] op_sel_hi:[1,1,0]
	v_rcp_f32_e32 v98, v98
	v_pk_fma_f32 v[80:81], v[96:97], v[80:81], s[42:43] op_sel_hi:[1,1,0]
	v_rcp_f32_e32 v99, v99
	v_pk_mul_f32 v[80:81], v[96:97], v[80:81]
	v_cmp_gt_f32_e32 vcc, 0, v90
	v_pk_mul_f32 v[80:81], v[94:95], v[80:81]
	v_pk_mul_f32 v[96:97], v[82:83], v[82:83]
	v_pk_mul_f32 v[94:95], v[90:91], v[80:81]
	v_pk_fma_f32 v[80:81], v[90:91], v[80:81], v[90:91] neg_lo:[1,0,0] neg_hi:[1,0,0]
	s_nop 0
	v_cndmask_b32_e32 v90, v80, v94, vcc
	v_cmp_gt_f32_e32 vcc, 0, v91
	s_nop 1
	v_cndmask_b32_e32 v91, v81, v95, vcc
	v_pk_fma_f32 v[80:81], v[98:99], s[22:23], v[92:93] op_sel_hi:[1,0,0]
	v_pk_mul_f32 v[92:93], v[96:97], s[56:57] op_sel_hi:[1,0]
	v_pk_fma_f32 v[80:81], v[98:99], v[80:81], s[38:39] op_sel_hi:[1,1,0]
	v_exp_f32_e32 v92, v92
	v_exp_f32_e32 v93, v93
	v_pk_fma_f32 v[80:81], v[98:99], v[80:81], s[40:41] op_sel_hi:[1,1,0]
	v_cmp_gt_f32_e32 vcc, 0, v82
	v_pk_fma_f32 v[80:81], v[98:99], v[80:81], s[42:43] op_sel_hi:[1,1,0]
	s_nop 0
	v_pk_mul_f32 v[80:81], v[98:99], v[80:81]
	s_nop 0
	v_pk_mul_f32 v[80:81], v[92:93], v[80:81]
	s_nop 0
	v_pk_mul_f32 v[92:93], v[82:83], v[80:81]
	v_pk_fma_f32 v[80:81], v[82:83], v[80:81], v[82:83] neg_lo:[1,0,0] neg_hi:[1,0,0]
	s_nop 0
	v_cndmask_b32_e32 v82, v80, v92, vcc
	v_cmp_gt_f32_e32 vcc, 0, v83
	s_nop 1
	v_cndmask_b32_e32 v83, v81, v93, vcc
.LBB0_207:
	v_fmamk_f32 v80, v160, 0x3a800000, v156
	v_rsq_f32_e32 v80, v80
	s_and_b64 vcc, exec, s[6:7]
	v_cvt_pk_bf16_f32 v84, v84, v85
	v_cvt_pk_bf16_f32 v85, v86, v87
	v_pk_mul_f32 v[78:79], v[78:79], v[80:81] op_sel_hi:[1,0]
	v_pk_mul_f32 v[76:77], v[76:77], v[80:81] op_sel_hi:[1,0]
	v_pk_mul_f32 v[74:75], v[74:75], v[80:81] op_sel_hi:[1,0]
	v_pk_mul_f32 v[72:73], v[72:73], v[80:81] op_sel_hi:[1,0]
	v_cvt_pk_bf16_f32 v86, v90, v91
	v_cvt_pk_bf16_f32 v87, v82, v83
	s_cmp_lg_u32 s99, 0
	s_cbranch_scc1 .Lwt192_4751
	global_store_dwordx4 v[88:89], v[84:87], off offset:256
	s_branch .Lwj192_4751
.Lwt192_4751:
	global_store_dwordx4 v[88:89], v[84:87], off offset:256 sc1
; __device__ __forceinline__ f32x4 gelu4(f32x4 v) { const f32x2 a = gelu_pk((f32x2){v[0], v[1]}), b = gelu_pk((f32x2){v[2], v[3]}); return (f32x4){a.x, a.y, b.x, b.y}; }
; #define EPI_IT_ROW(it) EPI_ROW((it) >> 2, (it) & 3)
; #define EPI_LOAD_RR(ssp) float rr[8]; _Pragma("unroll") for (int it = 0; it < 8; ++it) rr[it] = (ssp)[EPI_IT_ROW(it)]; _Pragma("unroll") for (int it = 0; it < 8; ++it) rr[it] = rms_r(rr[it])
; #define EPI_PACK8(v0, v1) (u32x4){pk2((v0)[0], (v0)[1]), pk2((v0)[2], (v0)[3]), pk2((v1)[0], (v1)[1]), pk2((v1)[2], (v1)[3])}
; __device__ __forceinline__ f32x2 gelu_pk(f32x2 v) {
;     const f32x2 av = __builtin_elementwise_abs(v), d = av * 0.2316418882f + 1.0f;
;     f32x2 t; t.x = __builtin_amdgcn_rcpf(d.x); t.y = __builtin_amdgcn_rcpf(d.y);
;     f32x2 q = t * 0.5307027145f + (-0.7265760135f); q = q * t + 0.7107068705f; q = q * t + (-0.142248368f); q = q * t + 0.127414796f; q = q * t;
;     const f32x2 s = (v * v) * (-0.72134752044f);
;     f32x2 e; e.x = __builtin_amdgcn_exp2f(s.x); e.y = __builtin_amdgcn_exp2f(s.y);
;     const f32x2 m = v * (q * e), r = v - m;
;     f32x2 o; o.x = v.x < 0.f ? m.x : r.x; o.y = v.y < 0.f ? m.y : r.y; return o;
;     __device__ __forceinline__ void operator()(AccRef acc, const Unit& u, int wr, int wc, int fr, int fq) const {
;         asm volatile("" : "+v"(fr), "+v"(fq));
;         const bool act = u.pn < 4;
;         EPI_LOAD_RR(ss);
; #pragma unroll
;         for (int it = 0; it < 8; ++it) { const int ai = it >> 2, m = it & 3, row = EPI_IT_ROW(it);
; #pragma unroll
;             for (int bj = 0; bj < 2; ++bj) { f32x4 v0 = acc[ai][bj][m][0] * rr[it], v1 = acc[ai][bj][m][1] * rr[it];
;                 if (act) { v0 = gelu4(v0); v1 = gelu4(v1); }
;                 *(u32x4*)(O + (size_t)row * AB_IN + EPI_COL(bj)) = EPI_PACK8(v0, v1); } }
.Lwj192_4751:
	s_cbranch_vccnz .LBB0_209
	v_and_b32_e32 v83, 0x7fffffff, v77
	v_and_b32_e32 v82, 0x7fffffff, v76
	v_pk_fma_f32 v[82:83], v[82:83], s[18:19], 1.0 op_sel_hi:[1,0,0]
	v_mov_b64_e32 v[84:85], s[34:35]
	v_rcp_f32_e32 v82, v82
	v_rcp_f32_e32 v83, v83
	v_pk_mul_f32 v[88:89], v[76:77], v[76:77]
	v_and_b32_e32 v91, 0x7fffffff, v79
	v_pk_mul_f32 v[88:89], v[88:89], s[56:57] op_sel_hi:[1,0]
	v_pk_fma_f32 v[86:87], v[82:83], s[22:23], v[84:85] op_sel_hi:[1,0,0]
	v_exp_f32_e32 v88, v88
	v_pk_fma_f32 v[86:87], v[82:83], v[86:87], s[38:39] op_sel_hi:[1,1,0]
	v_exp_f32_e32 v89, v89
	v_pk_fma_f32 v[86:87], v[82:83], v[86:87], s[40:41] op_sel_hi:[1,1,0]
	v_and_b32_e32 v90, 0x7fffffff, v78
	v_pk_fma_f32 v[86:87], v[82:83], v[86:87], s[42:43] op_sel_hi:[1,1,0]
	v_pk_fma_f32 v[90:91], v[90:91], s[18:19], 1.0 op_sel_hi:[1,0,0]
	v_pk_mul_f32 v[82:83], v[82:83], v[86:87]
	v_rcp_f32_e32 v90, v90
	v_rcp_f32_e32 v91, v91
	v_pk_mul_f32 v[82:83], v[88:89], v[82:83]
	v_cmp_gt_f32_e32 vcc, 0, v76
	v_pk_mul_f32 v[88:89], v[76:77], v[82:83]
	v_pk_fma_f32 v[82:83], v[76:77], v[82:83], v[76:77] neg_lo:[1,0,0] neg_hi:[1,0,0]
	v_pk_mul_f32 v[86:87], v[78:79], v[78:79]
	v_cndmask_b32_e32 v76, v82, v88, vcc
	v_cmp_gt_f32_e32 vcc, 0, v77
	v_pk_mul_f32 v[86:87], v[86:87], s[56:57] op_sel_hi:[1,0]
	v_and_b32_e32 v88, 0x7fffffff, v72
	v_cndmask_b32_e32 v77, v83, v89, vcc
	v_pk_fma_f32 v[82:83], v[90:91], s[22:23], v[84:85] op_sel_hi:[1,0,0]
	v_exp_f32_e32 v86, v86
	v_pk_fma_f32 v[82:83], v[90:91], v[82:83], s[38:39] op_sel_hi:[1,1,0]
	v_exp_f32_e32 v87, v87
	v_pk_fma_f32 v[82:83], v[90:91], v[82:83], s[40:41] op_sel_hi:[1,1,0]
	v_and_b32_e32 v89, 0x7fffffff, v73
	v_pk_fma_f32 v[82:83], v[90:91], v[82:83], s[42:43] op_sel_hi:[1,1,0]
	v_pk_fma_f32 v[88:89], v[88:89], s[18:19], 1.0 op_sel_hi:[1,0,0]
	v_pk_mul_f32 v[82:83], v[90:91], v[82:83]
	v_rcp_f32_e32 v88, v88
	v_pk_mul_f32 v[82:83], v[86:87], v[82:83]
	v_rcp_f32_e32 v89, v89
	v_pk_mul_f32 v[86:87], v[78:79], v[82:83]
	v_pk_fma_f32 v[82:83], v[78:79], v[82:83], v[78:79] neg_lo:[1,0,0] neg_hi:[1,0,0]
	v_cmp_gt_f32_e32 vcc, 0, v78
	v_and_b32_e32 v91, 0x7fffffff, v75
	v_and_b32_e32 v90, 0x7fffffff, v74
	v_cndmask_b32_e32 v78, v82, v86, vcc
	v_cmp_gt_f32_e32 vcc, 0, v79
	v_pk_fma_f32 v[90:91], v[90:91], s[18:19], 1.0 op_sel_hi:[1,0,0]
	s_nop 0
	v_cndmask_b32_e32 v79, v83, v87, vcc
	v_pk_mul_f32 v[86:87], v[72:73], v[72:73]
	v_pk_fma_f32 v[82:83], v[88:89], s[22:23], v[84:85] op_sel_hi:[1,0,0]
	v_pk_mul_f32 v[86:87], v[86:87], s[56:57] op_sel_hi:[1,0]
	v_pk_fma_f32 v[82:83], v[88:89], v[82:83], s[38:39] op_sel_hi:[1,1,0]
	v_exp_f32_e32 v86, v86
	v_exp_f32_e32 v87, v87
	v_pk_fma_f32 v[82:83], v[88:89], v[82:83], s[40:41] op_sel_hi:[1,1,0]
	v_rcp_f32_e32 v90, v90
	v_pk_fma_f32 v[82:83], v[88:89], v[82:83], s[42:43] op_sel_hi:[1,1,0]
	v_rcp_f32_e32 v91, v91
	v_pk_mul_f32 v[82:83], v[88:89], v[82:83]
	v_cmp_gt_f32_e32 vcc, 0, v72
	v_pk_mul_f32 v[82:83], v[86:87], v[82:83]
	v_pk_mul_f32 v[88:89], v[74:75], v[74:75]
	v_pk_mul_f32 v[86:87], v[72:73], v[82:83]
	v_pk_fma_f32 v[82:83], v[72:73], v[82:83], v[72:73] neg_lo:[1,0,0] neg_hi:[1,0,0]
	s_nop 0
	v_cndmask_b32_e32 v72, v82, v86, vcc
	v_cmp_gt_f32_e32 vcc, 0, v73
	s_nop 1
	v_cndmask_b32_e32 v73, v83, v87, vcc
	v_pk_fma_f32 v[82:83], v[90:91], s[22:23], v[84:85] op_sel_hi:[1,0,0]
	v_pk_mul_f32 v[84:85], v[88:89], s[56:57] op_sel_hi:[1,0]
	v_pk_fma_f32 v[82:83], v[90:91], v[82:83], s[38:39] op_sel_hi:[1,1,0]
	v_exp_f32_e32 v84, v84
	v_exp_f32_e32 v85, v85
	v_pk_fma_f32 v[82:83], v[90:91], v[82:83], s[40:41] op_sel_hi:[1,1,0]
	v_cmp_gt_f32_e32 vcc, 0, v74
	v_pk_fma_f32 v[82:83], v[90:91], v[82:83], s[42:43] op_sel_hi:[1,1,0]
	s_nop 0
	v_pk_mul_f32 v[82:83], v[90:91], v[82:83]
	s_nop 0
	v_pk_mul_f32 v[82:83], v[84:85], v[82:83]
	s_nop 0
	v_pk_mul_f32 v[84:85], v[74:75], v[82:83]
	v_pk_fma_f32 v[82:83], v[74:75], v[82:83], v[74:75] neg_lo:[1,0,0] neg_hi:[1,0,0]
	s_nop 0
	v_cndmask_b32_e32 v74, v82, v84, vcc
	v_cmp_gt_f32_e32 vcc, 0, v75
	s_nop 1
	v_cndmask_b32_e32 v75, v83, v85, vcc
.LBB0_209:
	v_add_u32_e32 v82, 48, v144
	v_cvt_pk_bf16_f32 v76, v76, v77
	v_cvt_pk_bf16_f32 v77, v78, v79
	v_cvt_pk_bf16_f32 v78, v72, v73
	v_mov_b64_e32 v[72:73], s[26:27]
	v_mov_b32_e32 v81, v80
	v_cvt_pk_bf16_f32 v79, v74, v75
	v_mad_i64_i32 v[72:73], s[72:73], v82, s86, v[72:73]
	v_mov_b32_e32 v74, v80
	v_mov_b32_e32 v75, v80
	v_lshl_add_u64 v[72:73], v[120:121], 1, v[72:73]
	v_pk_mul_f32 v[70:71], v[70:71], v[74:75]
	v_pk_mul_f32 v[68:69], v[68:69], v[80:81]
	v_pk_mul_f32 v[66:67], v[66:67], v[74:75]
	s_and_b64 vcc, exec, s[6:7]
	v_pk_mul_f32 v[74:75], v[64:65], v[80:81]
	s_cmp_lg_u32 s99, 0
	s_cbranch_scc1 .Lwt192_4872
	global_store_dwordx4 v[72:73], v[76:79], off
	s_branch .Lwj192_4872
.Lwt192_4872:
	global_store_dwordx4 v[72:73], v[76:79], off sc1
; __device__ __forceinline__ f32x4 gelu4(f32x4 v) { const f32x2 a = gelu_pk((f32x2){v[0], v[1]}), b = gelu_pk((f32x2){v[2], v[3]}); return (f32x4){a.x, a.y, b.x, b.y}; }
; #define EPI_IT_ROW(it) EPI_ROW((it) >> 2, (it) & 3)
; #define EPI_LOAD_RR(ssp) float rr[8]; _Pragma("unroll") for (int it = 0; it < 8; ++it) rr[it] = (ssp)[EPI_IT_ROW(it)]; _Pragma("unroll") for (int it = 0; it < 8; ++it) rr[it] = rms_r(rr[it])
; #define EPI_PACK8(v0, v1) (u32x4){pk2((v0)[0], (v0)[1]), pk2((v0)[2], (v0)[3]), pk2((v1)[0], (v1)[1]), pk2((v1)[2], (v1)[3])}
; __device__ __forceinline__ f32x2 gelu_pk(f32x2 v) {
;     const f32x2 av = __builtin_elementwise_abs(v), d = av * 0.2316418882f + 1.0f;
;     f32x2 t; t.x = __builtin_amdgcn_rcpf(d.x); t.y = __builtin_amdgcn_rcpf(d.y);
;     f32x2 q = t * 0.5307027145f + (-0.7265760135f); q = q * t + 0.7107068705f; q = q * t + (-0.142248368f); q = q * t + 0.127414796f; q = q * t;
;     const f32x2 s = (v * v) * (-0.72134752044f);
;     f32x2 e; e.x = __builtin_amdgcn_exp2f(s.x); e.y = __builtin_amdgcn_exp2f(s.y);
;     const f32x2 m = v * (q * e), r = v - m;
;     f32x2 o; o.x = v.x < 0.f ? m.x : r.x; o.y = v.y < 0.f ? m.y : r.y; return o;
;     __device__ __forceinline__ void operator()(AccRef acc, const Unit& u, int wr, int wc, int fr, int fq) const {
;         asm volatile("" : "+v"(fr), "+v"(fq));
;         const bool act = u.pn < 4;
;         EPI_LOAD_RR(ss);
; #pragma unroll
;         for (int it = 0; it < 8; ++it) { const int ai = it >> 2, m = it & 3, row = EPI_IT_ROW(it);
; #pragma unroll
;             for (int bj = 0; bj < 2; ++bj) { f32x4 v0 = acc[ai][bj][m][0] * rr[it], v1 = acc[ai][bj][m][1] * rr[it];
;                 if (act) { v0 = gelu4(v0); v1 = gelu4(v1); }
;                 *(u32x4*)(O + (size_t)row * AB_IN + EPI_COL(bj)) = EPI_PACK8(v0, v1); } }
.Lwj192_4872:
	s_cbranch_vccnz .LBB0_211
	v_and_b32_e32 v65, 0x7fffffff, v69
	v_and_b32_e32 v64, 0x7fffffff, v68
	v_pk_fma_f32 v[64:65], v[64:65], s[18:19], 1.0 op_sel_hi:[1,0,0]
	v_mov_b64_e32 v[76:77], s[34:35]
	v_rcp_f32_e32 v64, v64
	v_rcp_f32_e32 v65, v65
	v_pk_mul_f32 v[80:81], v[68:69], v[68:69]
	v_and_b32_e32 v83, 0x7fffffff, v71
	v_pk_mul_f32 v[80:81], v[80:81], s[56:57] op_sel_hi:[1,0]
	v_pk_fma_f32 v[78:79], v[64:65], s[22:23], v[76:77] op_sel_hi:[1,0,0]
	v_exp_f32_e32 v80, v80
	v_pk_fma_f32 v[78:79], v[64:65], v[78:79], s[38:39] op_sel_hi:[1,1,0]
	v_exp_f32_e32 v81, v81
	v_pk_fma_f32 v[78:79], v[64:65], v[78:79], s[40:41] op_sel_hi:[1,1,0]
	v_and_b32_e32 v82, 0x7fffffff, v70
	v_pk_fma_f32 v[78:79], v[64:65], v[78:79], s[42:43] op_sel_hi:[1,1,0]
	v_pk_fma_f32 v[82:83], v[82:83], s[18:19], 1.0 op_sel_hi:[1,0,0]
	v_pk_mul_f32 v[64:65], v[64:65], v[78:79]
	v_rcp_f32_e32 v82, v82
	v_rcp_f32_e32 v83, v83
	v_pk_mul_f32 v[64:65], v[80:81], v[64:65]
	v_cmp_gt_f32_e32 vcc, 0, v68
	v_pk_mul_f32 v[80:81], v[68:69], v[64:65]
	v_pk_fma_f32 v[64:65], v[68:69], v[64:65], v[68:69] neg_lo:[1,0,0] neg_hi:[1,0,0]
	v_pk_mul_f32 v[78:79], v[70:71], v[70:71]
	v_cndmask_b32_e32 v68, v64, v80, vcc
	v_cmp_gt_f32_e32 vcc, 0, v69
	v_pk_mul_f32 v[78:79], v[78:79], s[56:57] op_sel_hi:[1,0]
	v_and_b32_e32 v80, 0x7fffffff, v74
	v_cndmask_b32_e32 v69, v65, v81, vcc
	v_pk_fma_f32 v[64:65], v[82:83], s[22:23], v[76:77] op_sel_hi:[1,0,0]
	v_exp_f32_e32 v78, v78
	v_pk_fma_f32 v[64:65], v[82:83], v[64:65], s[38:39] op_sel_hi:[1,1,0]
	v_exp_f32_e32 v79, v79
	v_pk_fma_f32 v[64:65], v[82:83], v[64:65], s[40:41] op_sel_hi:[1,1,0]
	v_and_b32_e32 v81, 0x7fffffff, v75
	v_pk_fma_f32 v[64:65], v[82:83], v[64:65], s[42:43] op_sel_hi:[1,1,0]
	v_pk_fma_f32 v[80:81], v[80:81], s[18:19], 1.0 op_sel_hi:[1,0,0]
	v_pk_mul_f32 v[64:65], v[82:83], v[64:65]
	v_rcp_f32_e32 v80, v80
	v_pk_mul_f32 v[64:65], v[78:79], v[64:65]
	v_rcp_f32_e32 v81, v81
	v_pk_mul_f32 v[78:79], v[70:71], v[64:65]
	v_pk_fma_f32 v[64:65], v[70:71], v[64:65], v[70:71] neg_lo:[1,0,0] neg_hi:[1,0,0]
	v_cmp_gt_f32_e32 vcc, 0, v70
	v_and_b32_e32 v83, 0x7fffffff, v67
	v_and_b32_e32 v82, 0x7fffffff, v66
	v_cndmask_b32_e32 v70, v64, v78, vcc
	v_cmp_gt_f32_e32 vcc, 0, v71
	v_pk_fma_f32 v[82:83], v[82:83], s[18:19], 1.0 op_sel_hi:[1,0,0]
	s_nop 0
	v_cndmask_b32_e32 v71, v65, v79, vcc
	v_pk_mul_f32 v[78:79], v[74:75], v[74:75]
	v_pk_fma_f32 v[64:65], v[80:81], s[22:23], v[76:77] op_sel_hi:[1,0,0]
	v_pk_mul_f32 v[78:79], v[78:79], s[56:57] op_sel_hi:[1,0]
	v_pk_fma_f32 v[64:65], v[80:81], v[64:65], s[38:39] op_sel_hi:[1,1,0]
	v_exp_f32_e32 v78, v78
	v_exp_f32_e32 v79, v79
	v_pk_fma_f32 v[64:65], v[80:81], v[64:65], s[40:41] op_sel_hi:[1,1,0]
	v_rcp_f32_e32 v82, v82
	v_pk_fma_f32 v[64:65], v[80:81], v[64:65], s[42:43] op_sel_hi:[1,1,0]
	v_rcp_f32_e32 v83, v83
	v_pk_mul_f32 v[64:65], v[80:81], v[64:65]
	v_cmp_gt_f32_e32 vcc, 0, v74
	v_pk_mul_f32 v[64:65], v[78:79], v[64:65]
	v_pk_mul_f32 v[80:81], v[66:67], v[66:67]
	v_pk_mul_f32 v[78:79], v[74:75], v[64:65]
	v_pk_fma_f32 v[64:65], v[74:75], v[64:65], v[74:75] neg_lo:[1,0,0] neg_hi:[1,0,0]
	s_nop 0
	v_cndmask_b32_e32 v74, v64, v78, vcc
	v_cmp_gt_f32_e32 vcc, 0, v75
	s_nop 1
	v_cndmask_b32_e32 v75, v65, v79, vcc
	v_pk_fma_f32 v[64:65], v[82:83], s[22:23], v[76:77] op_sel_hi:[1,0,0]
	v_pk_mul_f32 v[76:77], v[80:81], s[56:57] op_sel_hi:[1,0]
	v_pk_fma_f32 v[64:65], v[82:83], v[64:65], s[38:39] op_sel_hi:[1,1,0]
	v_exp_f32_e32 v76, v76
	v_exp_f32_e32 v77, v77
	v_pk_fma_f32 v[64:65], v[82:83], v[64:65], s[40:41] op_sel_hi:[1,1,0]
	v_cmp_gt_f32_e32 vcc, 0, v66
	v_pk_fma_f32 v[64:65], v[82:83], v[64:65], s[42:43] op_sel_hi:[1,1,0]
	s_nop 0
	v_pk_mul_f32 v[64:65], v[82:83], v[64:65]
	s_nop 0
	v_pk_mul_f32 v[64:65], v[76:77], v[64:65]
	s_nop 0
	v_pk_mul_f32 v[76:77], v[66:67], v[64:65]
	v_pk_fma_f32 v[64:65], v[66:67], v[64:65], v[66:67] neg_lo:[1,0,0] neg_hi:[1,0,0]
	s_nop 0
	v_cndmask_b32_e32 v66, v64, v76, vcc
	v_cmp_gt_f32_e32 vcc, 0, v67
	s_nop 1
	v_cndmask_b32_e32 v67, v65, v77, vcc
.LBB0_211:
	v_fmamk_f32 v64, v159, 0x3a800000, v156
	v_rsq_f32_e32 v64, v64
	s_and_b64 vcc, exec, s[6:7]
	v_cvt_pk_bf16_f32 v68, v68, v69
	v_cvt_pk_bf16_f32 v69, v70, v71
	v_pk_mul_f32 v[62:63], v[62:63], v[64:65] op_sel_hi:[1,0]
	v_pk_mul_f32 v[60:61], v[60:61], v[64:65] op_sel_hi:[1,0]
	v_pk_mul_f32 v[58:59], v[58:59], v[64:65] op_sel_hi:[1,0]
	v_pk_mul_f32 v[56:57], v[56:57], v[64:65] op_sel_hi:[1,0]
	v_cvt_pk_bf16_f32 v70, v74, v75
	v_cvt_pk_bf16_f32 v71, v66, v67
	s_cmp_lg_u32 s99, 0
	s_cbranch_scc1 .Lwt192_4988
	global_store_dwordx4 v[72:73], v[68:71], off offset:256
	s_branch .Lwj192_4988
.Lwt192_4988:
	global_store_dwordx4 v[72:73], v[68:71], off offset:256 sc1
; __device__ __forceinline__ f32x4 gelu4(f32x4 v) { const f32x2 a = gelu_pk((f32x2){v[0], v[1]}), b = gelu_pk((f32x2){v[2], v[3]}); return (f32x4){a.x, a.y, b.x, b.y}; }
; #define EPI_IT_ROW(it) EPI_ROW((it) >> 2, (it) & 3)
; #define EPI_LOAD_RR(ssp) float rr[8]; _Pragma("unroll") for (int it = 0; it < 8; ++it) rr[it] = (ssp)[EPI_IT_ROW(it)]; _Pragma("unroll") for (int it = 0; it < 8; ++it) rr[it] = rms_r(rr[it])
; #define EPI_PACK8(v0, v1) (u32x4){pk2((v0)[0], (v0)[1]), pk2((v0)[2], (v0)[3]), pk2((v1)[0], (v1)[1]), pk2((v1)[2], (v1)[3])}
; __device__ __forceinline__ f32x2 gelu_pk(f32x2 v) {
;     const f32x2 av = __builtin_elementwise_abs(v), d = av * 0.2316418882f + 1.0f;
;     f32x2 t; t.x = __builtin_amdgcn_rcpf(d.x); t.y = __builtin_amdgcn_rcpf(d.y);
;     f32x2 q = t * 0.5307027145f + (-0.7265760135f); q = q * t + 0.7107068705f; q = q * t + (-0.142248368f); q = q * t + 0.127414796f; q = q * t;
;     const f32x2 s = (v * v) * (-0.72134752044f);
;     f32x2 e; e.x = __builtin_amdgcn_exp2f(s.x); e.y = __builtin_amdgcn_exp2f(s.y);
;     const f32x2 m = v * (q * e), r = v - m;
;     f32x2 o; o.x = v.x < 0.f ? m.x : r.x; o.y = v.y < 0.f ? m.y : r.y; return o;
;     __device__ __forceinline__ void operator()(AccRef acc, const Unit& u, int wr, int wc, int fr, int fq) const {
;         asm volatile("" : "+v"(fr), "+v"(fq));
;         const bool act = u.pn < 4;
;         EPI_LOAD_RR(ss);
; #pragma unroll
;         for (int it = 0; it < 8; ++it) { const int ai = it >> 2, m = it & 3, row = EPI_IT_ROW(it);
; #pragma unroll
;             for (int bj = 0; bj < 2; ++bj) { f32x4 v0 = acc[ai][bj][m][0] * rr[it], v1 = acc[ai][bj][m][1] * rr[it];
;                 if (act) { v0 = gelu4(v0); v1 = gelu4(v1); }
;                 *(u32x4*)(O + (size_t)row * AB_IN + EPI_COL(bj)) = EPI_PACK8(v0, v1); } }
.Lwj192_4988:
	s_cbranch_vccnz .LBB0_213
	v_and_b32_e32 v67, 0x7fffffff, v61
	v_and_b32_e32 v66, 0x7fffffff, v60
	v_pk_fma_f32 v[66:67], v[66:67], s[18:19], 1.0 op_sel_hi:[1,0,0]
	v_mov_b64_e32 v[68:69], s[34:35]
	v_rcp_f32_e32 v66, v66
	v_rcp_f32_e32 v67, v67
	v_pk_mul_f32 v[72:73], v[60:61], v[60:61]
	v_and_b32_e32 v75, 0x7fffffff, v63
	v_pk_mul_f32 v[72:73], v[72:73], s[56:57] op_sel_hi:[1,0]
	v_pk_fma_f32 v[70:71], v[66:67], s[22:23], v[68:69] op_sel_hi:[1,0,0]
	v_exp_f32_e32 v72, v72
	v_pk_fma_f32 v[70:71], v[66:67], v[70:71], s[38:39] op_sel_hi:[1,1,0]
	v_exp_f32_e32 v73, v73
	v_pk_fma_f32 v[70:71], v[66:67], v[70:71], s[40:41] op_sel_hi:[1,1,0]
	v_and_b32_e32 v74, 0x7fffffff, v62
	v_pk_fma_f32 v[70:71], v[66:67], v[70:71], s[42:43] op_sel_hi:[1,1,0]
	v_pk_fma_f32 v[74:75], v[74:75], s[18:19], 1.0 op_sel_hi:[1,0,0]
	v_pk_mul_f32 v[66:67], v[66:67], v[70:71]
	v_rcp_f32_e32 v74, v74
	v_rcp_f32_e32 v75, v75
	v_pk_mul_f32 v[66:67], v[72:73], v[66:67]
	v_cmp_gt_f32_e32 vcc, 0, v60
	v_pk_mul_f32 v[72:73], v[60:61], v[66:67]
	v_pk_fma_f32 v[66:67], v[60:61], v[66:67], v[60:61] neg_lo:[1,0,0] neg_hi:[1,0,0]
	v_pk_mul_f32 v[70:71], v[62:63], v[62:63]
	v_cndmask_b32_e32 v60, v66, v72, vcc
	v_cmp_gt_f32_e32 vcc, 0, v61
	v_pk_mul_f32 v[70:71], v[70:71], s[56:57] op_sel_hi:[1,0]
	v_and_b32_e32 v72, 0x7fffffff, v56
	v_cndmask_b32_e32 v61, v67, v73, vcc
	v_pk_fma_f32 v[66:67], v[74:75], s[22:23], v[68:69] op_sel_hi:[1,0,0]
	v_exp_f32_e32 v70, v70
	v_pk_fma_f32 v[66:67], v[74:75], v[66:67], s[38:39] op_sel_hi:[1,1,0]
	v_exp_f32_e32 v71, v71
	v_pk_fma_f32 v[66:67], v[74:75], v[66:67], s[40:41] op_sel_hi:[1,1,0]
	v_and_b32_e32 v73, 0x7fffffff, v57
	v_pk_fma_f32 v[66:67], v[74:75], v[66:67], s[42:43] op_sel_hi:[1,1,0]
	v_pk_fma_f32 v[72:73], v[72:73], s[18:19], 1.0 op_sel_hi:[1,0,0]
	v_pk_mul_f32 v[66:67], v[74:75], v[66:67]
	v_rcp_f32_e32 v72, v72
	v_pk_mul_f32 v[66:67], v[70:71], v[66:67]
	v_rcp_f32_e32 v73, v73
	v_pk_mul_f32 v[70:71], v[62:63], v[66:67]
	v_pk_fma_f32 v[66:67], v[62:63], v[66:67], v[62:63] neg_lo:[1,0,0] neg_hi:[1,0,0]
	v_cmp_gt_f32_e32 vcc, 0, v62
	v_and_b32_e32 v75, 0x7fffffff, v59
	v_and_b32_e32 v74, 0x7fffffff, v58
	v_cndmask_b32_e32 v62, v66, v70, vcc
	v_cmp_gt_f32_e32 vcc, 0, v63
	v_pk_fma_f32 v[74:75], v[74:75], s[18:19], 1.0 op_sel_hi:[1,0,0]
	s_nop 0
	v_cndmask_b32_e32 v63, v67, v71, vcc
	v_pk_mul_f32 v[70:71], v[56:57], v[56:57]
	v_pk_fma_f32 v[66:67], v[72:73], s[22:23], v[68:69] op_sel_hi:[1,0,0]
	v_pk_mul_f32 v[70:71], v[70:71], s[56:57] op_sel_hi:[1,0]
	v_pk_fma_f32 v[66:67], v[72:73], v[66:67], s[38:39] op_sel_hi:[1,1,0]
	v_exp_f32_e32 v70, v70
	v_exp_f32_e32 v71, v71
	v_pk_fma_f32 v[66:67], v[72:73], v[66:67], s[40:41] op_sel_hi:[1,1,0]
	v_rcp_f32_e32 v74, v74
	v_pk_fma_f32 v[66:67], v[72:73], v[66:67], s[42:43] op_sel_hi:[1,1,0]
	v_rcp_f32_e32 v75, v75
	v_pk_mul_f32 v[66:67], v[72:73], v[66:67]
	v_cmp_gt_f32_e32 vcc, 0, v56
	v_pk_mul_f32 v[66:67], v[70:71], v[66:67]
	v_pk_mul_f32 v[72:73], v[58:59], v[58:59]
	v_pk_mul_f32 v[70:71], v[56:57], v[66:67]
	v_pk_fma_f32 v[66:67], v[56:57], v[66:67], v[56:57] neg_lo:[1,0,0] neg_hi:[1,0,0]
	s_nop 0
	v_cndmask_b32_e32 v56, v66, v70, vcc
	v_cmp_gt_f32_e32 vcc, 0, v57
	s_nop 1
	v_cndmask_b32_e32 v57, v67, v71, vcc
	v_pk_fma_f32 v[66:67], v[74:75], s[22:23], v[68:69] op_sel_hi:[1,0,0]
	v_pk_mul_f32 v[68:69], v[72:73], s[56:57] op_sel_hi:[1,0]
	v_pk_fma_f32 v[66:67], v[74:75], v[66:67], s[38:39] op_sel_hi:[1,1,0]
	v_exp_f32_e32 v68, v68
	v_exp_f32_e32 v69, v69
	v_pk_fma_f32 v[66:67], v[74:75], v[66:67], s[40:41] op_sel_hi:[1,1,0]
	v_cmp_gt_f32_e32 vcc, 0, v58
	v_pk_fma_f32 v[66:67], v[74:75], v[66:67], s[42:43] op_sel_hi:[1,1,0]
	s_nop 0
	v_pk_mul_f32 v[66:67], v[74:75], v[66:67]
	s_nop 0
	v_pk_mul_f32 v[66:67], v[68:69], v[66:67]
	s_nop 0
	v_pk_mul_f32 v[68:69], v[58:59], v[66:67]
	v_pk_fma_f32 v[66:67], v[58:59], v[66:67], v[58:59] neg_lo:[1,0,0] neg_hi:[1,0,0]
	s_nop 0
	v_cndmask_b32_e32 v58, v66, v68, vcc
	v_cmp_gt_f32_e32 vcc, 0, v59
	s_nop 1
	v_cndmask_b32_e32 v59, v67, v69, vcc
.LBB0_213:
	v_add_u32_e32 v66, 0x80, v144
	v_cvt_pk_bf16_f32 v60, v60, v61
	v_cvt_pk_bf16_f32 v61, v62, v63
	v_cvt_pk_bf16_f32 v62, v56, v57
	v_mov_b64_e32 v[56:57], s[26:27]
	v_mov_b32_e32 v65, v64
	v_cvt_pk_bf16_f32 v63, v58, v59
	v_mad_i64_i32 v[56:57], s[72:73], v66, s86, v[56:57]
	v_mov_b32_e32 v58, v64
	v_mov_b32_e32 v59, v64
	v_lshl_add_u64 v[56:57], v[120:121], 1, v[56:57]
	v_pk_mul_f32 v[54:55], v[54:55], v[58:59]
	v_pk_mul_f32 v[52:53], v[52:53], v[64:65]
	v_pk_mul_f32 v[50:51], v[50:51], v[58:59]
	s_and_b64 vcc, exec, s[6:7]
	v_pk_mul_f32 v[58:59], v[48:49], v[64:65]
	s_cmp_lg_u32 s99, 0
	s_cbranch_scc1 .Lwt192_5109
	global_store_dwordx4 v[56:57], v[60:63], off
	s_branch .Lwj192_5109
.Lwt192_5109:
	global_store_dwordx4 v[56:57], v[60:63], off sc1
; __device__ __forceinline__ f32x4 gelu4(f32x4 v) { const f32x2 a = gelu_pk((f32x2){v[0], v[1]}), b = gelu_pk((f32x2){v[2], v[3]}); return (f32x4){a.x, a.y, b.x, b.y}; }
; #define EPI_IT_ROW(it) EPI_ROW((it) >> 2, (it) & 3)
; #define EPI_LOAD_RR(ssp) float rr[8]; _Pragma("unroll") for (int it = 0; it < 8; ++it) rr[it] = (ssp)[EPI_IT_ROW(it)]; _Pragma("unroll") for (int it = 0; it < 8; ++it) rr[it] = rms_r(rr[it])
; #define EPI_PACK8(v0, v1) (u32x4){pk2((v0)[0], (v0)[1]), pk2((v0)[2], (v0)[3]), pk2((v1)[0], (v1)[1]), pk2((v1)[2], (v1)[3])}
; __device__ __forceinline__ f32x2 gelu_pk(f32x2 v) {
;     const f32x2 av = __builtin_elementwise_abs(v), d = av * 0.2316418882f + 1.0f;
;     f32x2 t; t.x = __builtin_amdgcn_rcpf(d.x); t.y = __builtin_amdgcn_rcpf(d.y);
;     f32x2 q = t * 0.5307027145f + (-0.7265760135f); q = q * t + 0.7107068705f; q = q * t + (-0.142248368f); q = q * t + 0.127414796f; q = q * t;
;     const f32x2 s = (v * v) * (-0.72134752044f);
;     f32x2 e; e.x = __builtin_amdgcn_exp2f(s.x); e.y = __builtin_amdgcn_exp2f(s.y);
;     const f32x2 m = v * (q * e), r = v - m;
;     f32x2 o; o.x = v.x < 0.f ? m.x : r.x; o.y = v.y < 0.f ? m.y : r.y; return o;
;     __device__ __forceinline__ void operator()(AccRef acc, const Unit& u, int wr, int wc, int fr, int fq) const {
;         asm volatile("" : "+v"(fr), "+v"(fq));
;         const bool act = u.pn < 4;
;         EPI_LOAD_RR(ss);
; #pragma unroll
;         for (int it = 0; it < 8; ++it) { const int ai = it >> 2, m = it & 3, row = EPI_IT_ROW(it);
; #pragma unroll
;             for (int bj = 0; bj < 2; ++bj) { f32x4 v0 = acc[ai][bj][m][0] * rr[it], v1 = acc[ai][bj][m][1] * rr[it];
;                 if (act) { v0 = gelu4(v0); v1 = gelu4(v1); }
;                 *(u32x4*)(O + (size_t)row * AB_IN + EPI_COL(bj)) = EPI_PACK8(v0, v1); } }
.Lwj192_5109:
	s_cbranch_vccnz .LBB0_215
	v_and_b32_e32 v49, 0x7fffffff, v53
	v_and_b32_e32 v48, 0x7fffffff, v52
	v_pk_fma_f32 v[48:49], v[48:49], s[18:19], 1.0 op_sel_hi:[1,0,0]
	v_mov_b64_e32 v[60:61], s[34:35]
	v_rcp_f32_e32 v48, v48
	v_rcp_f32_e32 v49, v49
	v_pk_mul_f32 v[64:65], v[52:53], v[52:53]
	v_and_b32_e32 v67, 0x7fffffff, v55
	v_pk_mul_f32 v[64:65], v[64:65], s[56:57] op_sel_hi:[1,0]
	v_pk_fma_f32 v[62:63], v[48:49], s[22:23], v[60:61] op_sel_hi:[1,0,0]
	v_exp_f32_e32 v64, v64
	v_pk_fma_f32 v[62:63], v[48:49], v[62:63], s[38:39] op_sel_hi:[1,1,0]
	v_exp_f32_e32 v65, v65
	v_pk_fma_f32 v[62:63], v[48:49], v[62:63], s[40:41] op_sel_hi:[1,1,0]
	v_and_b32_e32 v66, 0x7fffffff, v54
	v_pk_fma_f32 v[62:63], v[48:49], v[62:63], s[42:43] op_sel_hi:[1,1,0]
	v_pk_fma_f32 v[66:67], v[66:67], s[18:19], 1.0 op_sel_hi:[1,0,0]
	v_pk_mul_f32 v[48:49], v[48:49], v[62:63]
	v_rcp_f32_e32 v66, v66
	v_rcp_f32_e32 v67, v67
	v_pk_mul_f32 v[48:49], v[64:65], v[48:49]
	v_cmp_gt_f32_e32 vcc, 0, v52
	v_pk_mul_f32 v[64:65], v[52:53], v[48:49]
	v_pk_fma_f32 v[48:49], v[52:53], v[48:49], v[52:53] neg_lo:[1,0,0] neg_hi:[1,0,0]
	v_pk_mul_f32 v[62:63], v[54:55], v[54:55]
	v_cndmask_b32_e32 v52, v48, v64, vcc
	v_cmp_gt_f32_e32 vcc, 0, v53
	v_pk_mul_f32 v[62:63], v[62:63], s[56:57] op_sel_hi:[1,0]
	v_and_b32_e32 v64, 0x7fffffff, v58
	v_cndmask_b32_e32 v53, v49, v65, vcc
	v_pk_fma_f32 v[48:49], v[66:67], s[22:23], v[60:61] op_sel_hi:[1,0,0]
	v_exp_f32_e32 v62, v62
	v_pk_fma_f32 v[48:49], v[66:67], v[48:49], s[38:39] op_sel_hi:[1,1,0]
	v_exp_f32_e32 v63, v63
	v_pk_fma_f32 v[48:49], v[66:67], v[48:49], s[40:41] op_sel_hi:[1,1,0]
	v_and_b32_e32 v65, 0x7fffffff, v59
	v_pk_fma_f32 v[48:49], v[66:67], v[48:49], s[42:43] op_sel_hi:[1,1,0]
	v_pk_fma_f32 v[64:65], v[64:65], s[18:19], 1.0 op_sel_hi:[1,0,0]
	v_pk_mul_f32 v[48:49], v[66:67], v[48:49]
	v_rcp_f32_e32 v64, v64
	v_pk_mul_f32 v[48:49], v[62:63], v[48:49]
	v_rcp_f32_e32 v65, v65
	v_pk_mul_f32 v[62:63], v[54:55], v[48:49]
	v_pk_fma_f32 v[48:49], v[54:55], v[48:49], v[54:55] neg_lo:[1,0,0] neg_hi:[1,0,0]
	v_cmp_gt_f32_e32 vcc, 0, v54
	v_and_b32_e32 v67, 0x7fffffff, v51
	v_and_b32_e32 v66, 0x7fffffff, v50
	v_cndmask_b32_e32 v54, v48, v62, vcc
	v_cmp_gt_f32_e32 vcc, 0, v55
	v_pk_fma_f32 v[66:67], v[66:67], s[18:19], 1.0 op_sel_hi:[1,0,0]
	s_nop 0
	v_cndmask_b32_e32 v55, v49, v63, vcc
	v_pk_mul_f32 v[62:63], v[58:59], v[58:59]
	v_pk_fma_f32 v[48:49], v[64:65], s[22:23], v[60:61] op_sel_hi:[1,0,0]
	v_pk_mul_f32 v[62:63], v[62:63], s[56:57] op_sel_hi:[1,0]
	v_pk_fma_f32 v[48:49], v[64:65], v[48:49], s[38:39] op_sel_hi:[1,1,0]
	v_exp_f32_e32 v62, v62
	v_exp_f32_e32 v63, v63
	v_pk_fma_f32 v[48:49], v[64:65], v[48:49], s[40:41] op_sel_hi:[1,1,0]
	v_rcp_f32_e32 v66, v66
	v_pk_fma_f32 v[48:49], v[64:65], v[48:49], s[42:43] op_sel_hi:[1,1,0]
	v_rcp_f32_e32 v67, v67
	v_pk_mul_f32 v[48:49], v[64:65], v[48:49]
	v_cmp_gt_f32_e32 vcc, 0, v58
	v_pk_mul_f32 v[48:49], v[62:63], v[48:49]
	v_pk_mul_f32 v[64:65], v[50:51], v[50:51]
	v_pk_mul_f32 v[62:63], v[58:59], v[48:49]
	v_pk_fma_f32 v[48:49], v[58:59], v[48:49], v[58:59] neg_lo:[1,0,0] neg_hi:[1,0,0]
	s_nop 0
	v_cndmask_b32_e32 v58, v48, v62, vcc
	v_cmp_gt_f32_e32 vcc, 0, v59
	s_nop 1
	v_cndmask_b32_e32 v59, v49, v63, vcc
	v_pk_fma_f32 v[48:49], v[66:67], s[22:23], v[60:61] op_sel_hi:[1,0,0]
	v_pk_mul_f32 v[60:61], v[64:65], s[56:57] op_sel_hi:[1,0]
	v_pk_fma_f32 v[48:49], v[66:67], v[48:49], s[38:39] op_sel_hi:[1,1,0]
	v_exp_f32_e32 v60, v60
	v_exp_f32_e32 v61, v61
	v_pk_fma_f32 v[48:49], v[66:67], v[48:49], s[40:41] op_sel_hi:[1,1,0]
	v_cmp_gt_f32_e32 vcc, 0, v50
	v_pk_fma_f32 v[48:49], v[66:67], v[48:49], s[42:43] op_sel_hi:[1,1,0]
	s_nop 0
	v_pk_mul_f32 v[48:49], v[66:67], v[48:49]
	s_nop 0
	v_pk_mul_f32 v[48:49], v[60:61], v[48:49]
	s_nop 0
	v_pk_mul_f32 v[60:61], v[50:51], v[48:49]
	v_pk_fma_f32 v[48:49], v[50:51], v[48:49], v[50:51] neg_lo:[1,0,0] neg_hi:[1,0,0]
	s_nop 0
	v_cndmask_b32_e32 v50, v48, v60, vcc
	v_cmp_gt_f32_e32 vcc, 0, v51
	s_nop 1
	v_cndmask_b32_e32 v51, v49, v61, vcc
.LBB0_215:
	v_fmamk_f32 v48, v158, 0x3a800000, v156
	v_rsq_f32_e32 v48, v48
	s_and_b64 vcc, exec, s[6:7]
	v_cvt_pk_bf16_f32 v52, v52, v53
	v_cvt_pk_bf16_f32 v53, v54, v55
	v_pk_mul_f32 v[46:47], v[46:47], v[48:49] op_sel_hi:[1,0]
	v_pk_mul_f32 v[44:45], v[44:45], v[48:49] op_sel_hi:[1,0]
	v_pk_mul_f32 v[42:43], v[42:43], v[48:49] op_sel_hi:[1,0]
	v_pk_mul_f32 v[40:41], v[40:41], v[48:49] op_sel_hi:[1,0]
	v_cvt_pk_bf16_f32 v54, v58, v59
	v_cvt_pk_bf16_f32 v55, v50, v51
	s_cmp_lg_u32 s99, 0
	s_cbranch_scc1 .Lwt192_5225
	global_store_dwordx4 v[56:57], v[52:55], off offset:256
	s_branch .Lwj192_5225
.Lwt192_5225:
	global_store_dwordx4 v[56:57], v[52:55], off offset:256 sc1
; __device__ __forceinline__ f32x4 gelu4(f32x4 v) { const f32x2 a = gelu_pk((f32x2){v[0], v[1]}), b = gelu_pk((f32x2){v[2], v[3]}); return (f32x4){a.x, a.y, b.x, b.y}; }
; #define EPI_IT_ROW(it) EPI_ROW((it) >> 2, (it) & 3)
; #define EPI_LOAD_RR(ssp) float rr[8]; _Pragma("unroll") for (int it = 0; it < 8; ++it) rr[it] = (ssp)[EPI_IT_ROW(it)]; _Pragma("unroll") for (int it = 0; it < 8; ++it) rr[it] = rms_r(rr[it])
; #define EPI_PACK8(v0, v1) (u32x4){pk2((v0)[0], (v0)[1]), pk2((v0)[2], (v0)[3]), pk2((v1)[0], (v1)[1]), pk2((v1)[2], (v1)[3])}
; __device__ __forceinline__ f32x2 gelu_pk(f32x2 v) {
;     const f32x2 av = __builtin_elementwise_abs(v), d = av * 0.2316418882f + 1.0f;
;     f32x2 t; t.x = __builtin_amdgcn_rcpf(d.x); t.y = __builtin_amdgcn_rcpf(d.y);
;     f32x2 q = t * 0.5307027145f + (-0.7265760135f); q = q * t + 0.7107068705f; q = q * t + (-0.142248368f); q = q * t + 0.127414796f; q = q * t;
;     const f32x2 s = (v * v) * (-0.72134752044f);
;     f32x2 e; e.x = __builtin_amdgcn_exp2f(s.x); e.y = __builtin_amdgcn_exp2f(s.y);
;     const f32x2 m = v * (q * e), r = v - m;
;     f32x2 o; o.x = v.x < 0.f ? m.x : r.x; o.y = v.y < 0.f ? m.y : r.y; return o;
;     __device__ __forceinline__ void operator()(AccRef acc, const Unit& u, int wr, int wc, int fr, int fq) const {
;         asm volatile("" : "+v"(fr), "+v"(fq));
;         const bool act = u.pn < 4;
;         EPI_LOAD_RR(ss);
; #pragma unroll
;         for (int it = 0; it < 8; ++it) { const int ai = it >> 2, m = it & 3, row = EPI_IT_ROW(it);
; #pragma unroll
;             for (int bj = 0; bj < 2; ++bj) { f32x4 v0 = acc[ai][bj][m][0] * rr[it], v1 = acc[ai][bj][m][1] * rr[it];
;                 if (act) { v0 = gelu4(v0); v1 = gelu4(v1); }
;                 *(u32x4*)(O + (size_t)row * AB_IN + EPI_COL(bj)) = EPI_PACK8(v0, v1); } }
.Lwj192_5225:
	s_cbranch_vccnz .LBB0_217
	v_and_b32_e32 v51, 0x7fffffff, v45
	v_and_b32_e32 v50, 0x7fffffff, v44
	v_pk_fma_f32 v[50:51], v[50:51], s[18:19], 1.0 op_sel_hi:[1,0,0]
	v_mov_b64_e32 v[52:53], s[34:35]
	v_rcp_f32_e32 v50, v50
	v_rcp_f32_e32 v51, v51
	v_pk_mul_f32 v[56:57], v[44:45], v[44:45]
	v_and_b32_e32 v59, 0x7fffffff, v47
	v_pk_mul_f32 v[56:57], v[56:57], s[56:57] op_sel_hi:[1,0]
	v_pk_fma_f32 v[54:55], v[50:51], s[22:23], v[52:53] op_sel_hi:[1,0,0]
	v_exp_f32_e32 v56, v56
	v_pk_fma_f32 v[54:55], v[50:51], v[54:55], s[38:39] op_sel_hi:[1,1,0]
	v_exp_f32_e32 v57, v57
	v_pk_fma_f32 v[54:55], v[50:51], v[54:55], s[40:41] op_sel_hi:[1,1,0]
	v_and_b32_e32 v58, 0x7fffffff, v46
	v_pk_fma_f32 v[54:55], v[50:51], v[54:55], s[42:43] op_sel_hi:[1,1,0]
	v_pk_fma_f32 v[58:59], v[58:59], s[18:19], 1.0 op_sel_hi:[1,0,0]
	v_pk_mul_f32 v[50:51], v[50:51], v[54:55]
	v_rcp_f32_e32 v58, v58
	v_rcp_f32_e32 v59, v59
	v_pk_mul_f32 v[50:51], v[56:57], v[50:51]
	v_cmp_gt_f32_e32 vcc, 0, v44
	v_pk_mul_f32 v[56:57], v[44:45], v[50:51]
	v_pk_fma_f32 v[50:51], v[44:45], v[50:51], v[44:45] neg_lo:[1,0,0] neg_hi:[1,0,0]
	v_pk_mul_f32 v[54:55], v[46:47], v[46:47]
	v_cndmask_b32_e32 v44, v50, v56, vcc
	v_cmp_gt_f32_e32 vcc, 0, v45
	v_pk_mul_f32 v[54:55], v[54:55], s[56:57] op_sel_hi:[1,0]
	v_and_b32_e32 v56, 0x7fffffff, v40
	v_cndmask_b32_e32 v45, v51, v57, vcc
	v_pk_fma_f32 v[50:51], v[58:59], s[22:23], v[52:53] op_sel_hi:[1,0,0]
	v_exp_f32_e32 v54, v54
	v_pk_fma_f32 v[50:51], v[58:59], v[50:51], s[38:39] op_sel_hi:[1,1,0]
	v_exp_f32_e32 v55, v55
	v_pk_fma_f32 v[50:51], v[58:59], v[50:51], s[40:41] op_sel_hi:[1,1,0]
	v_and_b32_e32 v57, 0x7fffffff, v41
	v_pk_fma_f32 v[50:51], v[58:59], v[50:51], s[42:43] op_sel_hi:[1,1,0]
	v_pk_fma_f32 v[56:57], v[56:57], s[18:19], 1.0 op_sel_hi:[1,0,0]
	v_pk_mul_f32 v[50:51], v[58:59], v[50:51]
	v_rcp_f32_e32 v56, v56
	v_pk_mul_f32 v[50:51], v[54:55], v[50:51]
	v_rcp_f32_e32 v57, v57
	v_pk_mul_f32 v[54:55], v[46:47], v[50:51]
	v_pk_fma_f32 v[50:51], v[46:47], v[50:51], v[46:47] neg_lo:[1,0,0] neg_hi:[1,0,0]
	v_cmp_gt_f32_e32 vcc, 0, v46
	v_and_b32_e32 v59, 0x7fffffff, v43
	v_and_b32_e32 v58, 0x7fffffff, v42
	v_cndmask_b32_e32 v46, v50, v54, vcc
	v_cmp_gt_f32_e32 vcc, 0, v47
	v_pk_fma_f32 v[58:59], v[58:59], s[18:19], 1.0 op_sel_hi:[1,0,0]
	s_nop 0
	v_cndmask_b32_e32 v47, v51, v55, vcc
	v_pk_mul_f32 v[54:55], v[40:41], v[40:41]
	v_pk_fma_f32 v[50:51], v[56:57], s[22:23], v[52:53] op_sel_hi:[1,0,0]
	v_pk_mul_f32 v[54:55], v[54:55], s[56:57] op_sel_hi:[1,0]
	v_pk_fma_f32 v[50:51], v[56:57], v[50:51], s[38:39] op_sel_hi:[1,1,0]
	v_exp_f32_e32 v54, v54
	v_exp_f32_e32 v55, v55
	v_pk_fma_f32 v[50:51], v[56:57], v[50:51], s[40:41] op_sel_hi:[1,1,0]
	v_rcp_f32_e32 v58, v58
	v_pk_fma_f32 v[50:51], v[56:57], v[50:51], s[42:43] op_sel_hi:[1,1,0]
	v_rcp_f32_e32 v59, v59
	v_pk_mul_f32 v[50:51], v[56:57], v[50:51]
	v_cmp_gt_f32_e32 vcc, 0, v40
	v_pk_mul_f32 v[50:51], v[54:55], v[50:51]
	v_pk_mul_f32 v[56:57], v[42:43], v[42:43]
	v_pk_mul_f32 v[54:55], v[40:41], v[50:51]
	v_pk_fma_f32 v[50:51], v[40:41], v[50:51], v[40:41] neg_lo:[1,0,0] neg_hi:[1,0,0]
	s_nop 0
	v_cndmask_b32_e32 v40, v50, v54, vcc
	v_cmp_gt_f32_e32 vcc, 0, v41
	s_nop 1
	v_cndmask_b32_e32 v41, v51, v55, vcc
	v_pk_fma_f32 v[50:51], v[58:59], s[22:23], v[52:53] op_sel_hi:[1,0,0]
	v_pk_mul_f32 v[52:53], v[56:57], s[56:57] op_sel_hi:[1,0]
	v_pk_fma_f32 v[50:51], v[58:59], v[50:51], s[38:39] op_sel_hi:[1,1,0]
	v_exp_f32_e32 v52, v52
	v_exp_f32_e32 v53, v53
	v_pk_fma_f32 v[50:51], v[58:59], v[50:51], s[40:41] op_sel_hi:[1,1,0]
	v_cmp_gt_f32_e32 vcc, 0, v42
	v_pk_fma_f32 v[50:51], v[58:59], v[50:51], s[42:43] op_sel_hi:[1,1,0]
	s_nop 0
	v_pk_mul_f32 v[50:51], v[58:59], v[50:51]
	s_nop 0
	v_pk_mul_f32 v[50:51], v[52:53], v[50:51]
	s_nop 0
	v_pk_mul_f32 v[52:53], v[42:43], v[50:51]
	v_pk_fma_f32 v[50:51], v[42:43], v[50:51], v[42:43] neg_lo:[1,0,0] neg_hi:[1,0,0]
	s_nop 0
	v_cndmask_b32_e32 v42, v50, v52, vcc
	v_cmp_gt_f32_e32 vcc, 0, v43
	s_nop 1
	v_cndmask_b32_e32 v43, v51, v53, vcc
.LBB0_217:
	v_add_u32_e32 v50, 0x90, v144
	v_cvt_pk_bf16_f32 v44, v44, v45
	v_cvt_pk_bf16_f32 v45, v46, v47
	v_cvt_pk_bf16_f32 v46, v40, v41
	v_mov_b64_e32 v[40:41], s[26:27]
	v_mov_b32_e32 v49, v48
	v_cvt_pk_bf16_f32 v47, v42, v43
	v_mad_i64_i32 v[40:41], s[72:73], v50, s86, v[40:41]
	v_mov_b32_e32 v42, v48
	v_mov_b32_e32 v43, v48
	v_lshl_add_u64 v[40:41], v[120:121], 1, v[40:41]
	v_pk_mul_f32 v[38:39], v[38:39], v[42:43]
	v_pk_mul_f32 v[36:37], v[36:37], v[48:49]
	v_pk_mul_f32 v[34:35], v[34:35], v[42:43]
	s_and_b64 vcc, exec, s[6:7]
	v_pk_mul_f32 v[42:43], v[32:33], v[48:49]
	s_cmp_lg_u32 s99, 0
	s_cbranch_scc1 .Lwt192_5346
	global_store_dwordx4 v[40:41], v[44:47], off
	s_branch .Lwj192_5346
.Lwt192_5346:
	global_store_dwordx4 v[40:41], v[44:47], off sc1
; __device__ __forceinline__ f32x4 gelu4(f32x4 v) { const f32x2 a = gelu_pk((f32x2){v[0], v[1]}), b = gelu_pk((f32x2){v[2], v[3]}); return (f32x4){a.x, a.y, b.x, b.y}; }
; #define EPI_IT_ROW(it) EPI_ROW((it) >> 2, (it) & 3)
; #define EPI_LOAD_RR(ssp) float rr[8]; _Pragma("unroll") for (int it = 0; it < 8; ++it) rr[it] = (ssp)[EPI_IT_ROW(it)]; _Pragma("unroll") for (int it = 0; it < 8; ++it) rr[it] = rms_r(rr[it])
; #define EPI_PACK8(v0, v1) (u32x4){pk2((v0)[0], (v0)[1]), pk2((v0)[2], (v0)[3]), pk2((v1)[0], (v1)[1]), pk2((v1)[2], (v1)[3])}
; __device__ __forceinline__ f32x2 gelu_pk(f32x2 v) {
;     const f32x2 av = __builtin_elementwise_abs(v), d = av * 0.2316418882f + 1.0f;
;     f32x2 t; t.x = __builtin_amdgcn_rcpf(d.x); t.y = __builtin_amdgcn_rcpf(d.y);
;     f32x2 q = t * 0.5307027145f + (-0.7265760135f); q = q * t + 0.7107068705f; q = q * t + (-0.142248368f); q = q * t + 0.127414796f; q = q * t;
;     const f32x2 s = (v * v) * (-0.72134752044f);
;     f32x2 e; e.x = __builtin_amdgcn_exp2f(s.x); e.y = __builtin_amdgcn_exp2f(s.y);
;     const f32x2 m = v * (q * e), r = v - m;
;     f32x2 o; o.x = v.x < 0.f ? m.x : r.x; o.y = v.y < 0.f ? m.y : r.y; return o;
;     __device__ __forceinline__ void operator()(AccRef acc, const Unit& u, int wr, int wc, int fr, int fq) const {
;         asm volatile("" : "+v"(fr), "+v"(fq));
;         const bool act = u.pn < 4;
;         EPI_LOAD_RR(ss);
; #pragma unroll
;         for (int it = 0; it < 8; ++it) { const int ai = it >> 2, m = it & 3, row = EPI_IT_ROW(it);
; #pragma unroll
;             for (int bj = 0; bj < 2; ++bj) { f32x4 v0 = acc[ai][bj][m][0] * rr[it], v1 = acc[ai][bj][m][1] * rr[it];
;                 if (act) { v0 = gelu4(v0); v1 = gelu4(v1); }
;                 *(u32x4*)(O + (size_t)row * AB_IN + EPI_COL(bj)) = EPI_PACK8(v0, v1); } }
.Lwj192_5346:
	s_cbranch_vccnz .LBB0_219
	v_and_b32_e32 v33, 0x7fffffff, v37
	v_and_b32_e32 v32, 0x7fffffff, v36
	v_pk_fma_f32 v[32:33], v[32:33], s[18:19], 1.0 op_sel_hi:[1,0,0]
	v_mov_b64_e32 v[44:45], s[34:35]
	v_rcp_f32_e32 v32, v32
	v_rcp_f32_e32 v33, v33
	v_pk_mul_f32 v[48:49], v[36:37], v[36:37]
	v_and_b32_e32 v51, 0x7fffffff, v39
	v_pk_mul_f32 v[48:49], v[48:49], s[56:57] op_sel_hi:[1,0]
	v_pk_fma_f32 v[46:47], v[32:33], s[22:23], v[44:45] op_sel_hi:[1,0,0]
	v_exp_f32_e32 v48, v48
	v_pk_fma_f32 v[46:47], v[32:33], v[46:47], s[38:39] op_sel_hi:[1,1,0]
	v_exp_f32_e32 v49, v49
	v_pk_fma_f32 v[46:47], v[32:33], v[46:47], s[40:41] op_sel_hi:[1,1,0]
	v_and_b32_e32 v50, 0x7fffffff, v38
	v_pk_fma_f32 v[46:47], v[32:33], v[46:47], s[42:43] op_sel_hi:[1,1,0]
	v_pk_fma_f32 v[50:51], v[50:51], s[18:19], 1.0 op_sel_hi:[1,0,0]
	v_pk_mul_f32 v[32:33], v[32:33], v[46:47]
	v_rcp_f32_e32 v50, v50
	v_rcp_f32_e32 v51, v51
	v_pk_mul_f32 v[32:33], v[48:49], v[32:33]
	v_cmp_gt_f32_e32 vcc, 0, v36
	v_pk_mul_f32 v[48:49], v[36:37], v[32:33]
	v_pk_fma_f32 v[32:33], v[36:37], v[32:33], v[36:37] neg_lo:[1,0,0] neg_hi:[1,0,0]
	v_pk_mul_f32 v[46:47], v[38:39], v[38:39]
	v_cndmask_b32_e32 v36, v32, v48, vcc
	v_cmp_gt_f32_e32 vcc, 0, v37
	v_pk_mul_f32 v[46:47], v[46:47], s[56:57] op_sel_hi:[1,0]
	v_and_b32_e32 v48, 0x7fffffff, v42
	v_cndmask_b32_e32 v37, v33, v49, vcc
	v_pk_fma_f32 v[32:33], v[50:51], s[22:23], v[44:45] op_sel_hi:[1,0,0]
	v_exp_f32_e32 v46, v46
	v_pk_fma_f32 v[32:33], v[50:51], v[32:33], s[38:39] op_sel_hi:[1,1,0]
	v_exp_f32_e32 v47, v47
	v_pk_fma_f32 v[32:33], v[50:51], v[32:33], s[40:41] op_sel_hi:[1,1,0]
	v_and_b32_e32 v49, 0x7fffffff, v43
	v_pk_fma_f32 v[32:33], v[50:51], v[32:33], s[42:43] op_sel_hi:[1,1,0]
	v_pk_fma_f32 v[48:49], v[48:49], s[18:19], 1.0 op_sel_hi:[1,0,0]
	v_pk_mul_f32 v[32:33], v[50:51], v[32:33]
	v_rcp_f32_e32 v48, v48
	v_pk_mul_f32 v[32:33], v[46:47], v[32:33]
	v_rcp_f32_e32 v49, v49
	v_pk_mul_f32 v[46:47], v[38:39], v[32:33]
	v_pk_fma_f32 v[32:33], v[38:39], v[32:33], v[38:39] neg_lo:[1,0,0] neg_hi:[1,0,0]
	v_cmp_gt_f32_e32 vcc, 0, v38
	v_and_b32_e32 v51, 0x7fffffff, v35
	v_and_b32_e32 v50, 0x7fffffff, v34
	v_cndmask_b32_e32 v38, v32, v46, vcc
	v_cmp_gt_f32_e32 vcc, 0, v39
	v_pk_fma_f32 v[50:51], v[50:51], s[18:19], 1.0 op_sel_hi:[1,0,0]
	s_nop 0
	v_cndmask_b32_e32 v39, v33, v47, vcc
	v_pk_mul_f32 v[46:47], v[42:43], v[42:43]
	v_pk_fma_f32 v[32:33], v[48:49], s[22:23], v[44:45] op_sel_hi:[1,0,0]
	v_pk_mul_f32 v[46:47], v[46:47], s[56:57] op_sel_hi:[1,0]
	v_pk_fma_f32 v[32:33], v[48:49], v[32:33], s[38:39] op_sel_hi:[1,1,0]
	v_exp_f32_e32 v46, v46
	v_exp_f32_e32 v47, v47
	v_pk_fma_f32 v[32:33], v[48:49], v[32:33], s[40:41] op_sel_hi:[1,1,0]
	v_rcp_f32_e32 v50, v50
	v_pk_fma_f32 v[32:33], v[48:49], v[32:33], s[42:43] op_sel_hi:[1,1,0]
	v_rcp_f32_e32 v51, v51
	v_pk_mul_f32 v[32:33], v[48:49], v[32:33]
	v_cmp_gt_f32_e32 vcc, 0, v42
	v_pk_mul_f32 v[32:33], v[46:47], v[32:33]
	v_pk_mul_f32 v[48:49], v[34:35], v[34:35]
	v_pk_mul_f32 v[46:47], v[42:43], v[32:33]
	v_pk_fma_f32 v[32:33], v[42:43], v[32:33], v[42:43] neg_lo:[1,0,0] neg_hi:[1,0,0]
	s_nop 0
	v_cndmask_b32_e32 v42, v32, v46, vcc
	v_cmp_gt_f32_e32 vcc, 0, v43
	s_nop 1
	v_cndmask_b32_e32 v43, v33, v47, vcc
	v_pk_fma_f32 v[32:33], v[50:51], s[22:23], v[44:45] op_sel_hi:[1,0,0]
	v_pk_mul_f32 v[44:45], v[48:49], s[56:57] op_sel_hi:[1,0]
	v_pk_fma_f32 v[32:33], v[50:51], v[32:33], s[38:39] op_sel_hi:[1,1,0]
	v_exp_f32_e32 v44, v44
	v_exp_f32_e32 v45, v45
	v_pk_fma_f32 v[32:33], v[50:51], v[32:33], s[40:41] op_sel_hi:[1,1,0]
	v_cmp_gt_f32_e32 vcc, 0, v34
	v_pk_fma_f32 v[32:33], v[50:51], v[32:33], s[42:43] op_sel_hi:[1,1,0]
	s_nop 0
	v_pk_mul_f32 v[32:33], v[50:51], v[32:33]
	s_nop 0
	v_pk_mul_f32 v[32:33], v[44:45], v[32:33]
	s_nop 0
	v_pk_mul_f32 v[44:45], v[34:35], v[32:33]
	v_pk_fma_f32 v[32:33], v[34:35], v[32:33], v[34:35] neg_lo:[1,0,0] neg_hi:[1,0,0]
	s_nop 0
	v_cndmask_b32_e32 v34, v32, v44, vcc
	v_cmp_gt_f32_e32 vcc, 0, v35
	s_nop 1
	v_cndmask_b32_e32 v35, v33, v45, vcc
.LBB0_219:
	v_fmamk_f32 v32, v157, 0x3a800000, v156
	v_rsq_f32_e32 v32, v32
	s_and_b64 vcc, exec, s[6:7]
	v_cvt_pk_bf16_f32 v36, v36, v37
	v_cvt_pk_bf16_f32 v37, v38, v39
	v_pk_mul_f32 v[30:31], v[30:31], v[32:33] op_sel_hi:[1,0]
	v_pk_mul_f32 v[28:29], v[28:29], v[32:33] op_sel_hi:[1,0]
	v_pk_mul_f32 v[26:27], v[26:27], v[32:33] op_sel_hi:[1,0]
	v_pk_mul_f32 v[24:25], v[24:25], v[32:33] op_sel_hi:[1,0]
	v_cvt_pk_bf16_f32 v38, v42, v43
	v_cvt_pk_bf16_f32 v39, v34, v35
	s_cmp_lg_u32 s99, 0
	s_cbranch_scc1 .Lwt192_5462
	global_store_dwordx4 v[40:41], v[36:39], off offset:256
	s_branch .Lwj192_5462
.Lwt192_5462:
	global_store_dwordx4 v[40:41], v[36:39], off offset:256 sc1
; __device__ __forceinline__ f32x4 gelu4(f32x4 v) { const f32x2 a = gelu_pk((f32x2){v[0], v[1]}), b = gelu_pk((f32x2){v[2], v[3]}); return (f32x4){a.x, a.y, b.x, b.y}; }
; #define EPI_IT_ROW(it) EPI_ROW((it) >> 2, (it) & 3)
; #define EPI_LOAD_RR(ssp) float rr[8]; _Pragma("unroll") for (int it = 0; it < 8; ++it) rr[it] = (ssp)[EPI_IT_ROW(it)]; _Pragma("unroll") for (int it = 0; it < 8; ++it) rr[it] = rms_r(rr[it])
; #define EPI_PACK8(v0, v1) (u32x4){pk2((v0)[0], (v0)[1]), pk2((v0)[2], (v0)[3]), pk2((v1)[0], (v1)[1]), pk2((v1)[2], (v1)[3])}
; __device__ __forceinline__ f32x2 gelu_pk(f32x2 v) {
;     const f32x2 av = __builtin_elementwise_abs(v), d = av * 0.2316418882f + 1.0f;
;     f32x2 t; t.x = __builtin_amdgcn_rcpf(d.x); t.y = __builtin_amdgcn_rcpf(d.y);
;     f32x2 q = t * 0.5307027145f + (-0.7265760135f); q = q * t + 0.7107068705f; q = q * t + (-0.142248368f); q = q * t + 0.127414796f; q = q * t;
;     const f32x2 s = (v * v) * (-0.72134752044f);
;     f32x2 e; e.x = __builtin_amdgcn_exp2f(s.x); e.y = __builtin_amdgcn_exp2f(s.y);
;     const f32x2 m = v * (q * e), r = v - m;
;     f32x2 o; o.x = v.x < 0.f ? m.x : r.x; o.y = v.y < 0.f ? m.y : r.y; return o;
;     __device__ __forceinline__ void operator()(AccRef acc, const Unit& u, int wr, int wc, int fr, int fq) const {
;         asm volatile("" : "+v"(fr), "+v"(fq));
;         const bool act = u.pn < 4;
;         EPI_LOAD_RR(ss);
; #pragma unroll
;         for (int it = 0; it < 8; ++it) { const int ai = it >> 2, m = it & 3, row = EPI_IT_ROW(it);
; #pragma unroll
;             for (int bj = 0; bj < 2; ++bj) { f32x4 v0 = acc[ai][bj][m][0] * rr[it], v1 = acc[ai][bj][m][1] * rr[it];
;                 if (act) { v0 = gelu4(v0); v1 = gelu4(v1); }
;                 *(u32x4*)(O + (size_t)row * AB_IN + EPI_COL(bj)) = EPI_PACK8(v0, v1); } }
.Lwj192_5462:
	s_cbranch_vccnz .LBB0_221
	v_and_b32_e32 v35, 0x7fffffff, v29
	v_and_b32_e32 v34, 0x7fffffff, v28
	v_pk_fma_f32 v[34:35], v[34:35], s[18:19], 1.0 op_sel_hi:[1,0,0]
	v_mov_b64_e32 v[36:37], s[34:35]
	v_rcp_f32_e32 v34, v34
	v_rcp_f32_e32 v35, v35
	v_pk_mul_f32 v[40:41], v[28:29], v[28:29]
	v_and_b32_e32 v43, 0x7fffffff, v31
	v_pk_mul_f32 v[40:41], v[40:41], s[56:57] op_sel_hi:[1,0]
	v_pk_fma_f32 v[38:39], v[34:35], s[22:23], v[36:37] op_sel_hi:[1,0,0]
	v_exp_f32_e32 v40, v40
	v_pk_fma_f32 v[38:39], v[34:35], v[38:39], s[38:39] op_sel_hi:[1,1,0]
	v_exp_f32_e32 v41, v41
	v_pk_fma_f32 v[38:39], v[34:35], v[38:39], s[40:41] op_sel_hi:[1,1,0]
	v_and_b32_e32 v42, 0x7fffffff, v30
	v_pk_fma_f32 v[38:39], v[34:35], v[38:39], s[42:43] op_sel_hi:[1,1,0]
	v_pk_fma_f32 v[42:43], v[42:43], s[18:19], 1.0 op_sel_hi:[1,0,0]
	v_pk_mul_f32 v[34:35], v[34:35], v[38:39]
	v_rcp_f32_e32 v42, v42
	v_rcp_f32_e32 v43, v43
	v_pk_mul_f32 v[34:35], v[40:41], v[34:35]
	v_cmp_gt_f32_e32 vcc, 0, v28
	v_pk_mul_f32 v[40:41], v[28:29], v[34:35]
	v_pk_fma_f32 v[34:35], v[28:29], v[34:35], v[28:29] neg_lo:[1,0,0] neg_hi:[1,0,0]
	v_pk_mul_f32 v[38:39], v[30:31], v[30:31]
	v_cndmask_b32_e32 v28, v34, v40, vcc
	v_cmp_gt_f32_e32 vcc, 0, v29
	v_pk_mul_f32 v[38:39], v[38:39], s[56:57] op_sel_hi:[1,0]
	v_and_b32_e32 v40, 0x7fffffff, v24
	v_cndmask_b32_e32 v29, v35, v41, vcc
	v_pk_fma_f32 v[34:35], v[42:43], s[22:23], v[36:37] op_sel_hi:[1,0,0]
	v_exp_f32_e32 v38, v38
	v_pk_fma_f32 v[34:35], v[42:43], v[34:35], s[38:39] op_sel_hi:[1,1,0]
	v_exp_f32_e32 v39, v39
	v_pk_fma_f32 v[34:35], v[42:43], v[34:35], s[40:41] op_sel_hi:[1,1,0]
	v_and_b32_e32 v41, 0x7fffffff, v25
	v_pk_fma_f32 v[34:35], v[42:43], v[34:35], s[42:43] op_sel_hi:[1,1,0]
	v_pk_fma_f32 v[40:41], v[40:41], s[18:19], 1.0 op_sel_hi:[1,0,0]
	v_pk_mul_f32 v[34:35], v[42:43], v[34:35]
	v_rcp_f32_e32 v40, v40
	v_pk_mul_f32 v[34:35], v[38:39], v[34:35]
	v_rcp_f32_e32 v41, v41
	v_pk_mul_f32 v[38:39], v[30:31], v[34:35]
	v_pk_fma_f32 v[34:35], v[30:31], v[34:35], v[30:31] neg_lo:[1,0,0] neg_hi:[1,0,0]
	v_cmp_gt_f32_e32 vcc, 0, v30
	v_and_b32_e32 v43, 0x7fffffff, v27
	v_and_b32_e32 v42, 0x7fffffff, v26
	v_cndmask_b32_e32 v30, v34, v38, vcc
	v_cmp_gt_f32_e32 vcc, 0, v31
	v_pk_fma_f32 v[42:43], v[42:43], s[18:19], 1.0 op_sel_hi:[1,0,0]
	s_nop 0
	v_cndmask_b32_e32 v31, v35, v39, vcc
	v_pk_mul_f32 v[38:39], v[24:25], v[24:25]
	v_pk_fma_f32 v[34:35], v[40:41], s[22:23], v[36:37] op_sel_hi:[1,0,0]
	v_pk_mul_f32 v[38:39], v[38:39], s[56:57] op_sel_hi:[1,0]
	v_pk_fma_f32 v[34:35], v[40:41], v[34:35], s[38:39] op_sel_hi:[1,1,0]
	v_exp_f32_e32 v38, v38
	v_exp_f32_e32 v39, v39
	v_pk_fma_f32 v[34:35], v[40:41], v[34:35], s[40:41] op_sel_hi:[1,1,0]
	v_rcp_f32_e32 v42, v42
	v_pk_fma_f32 v[34:35], v[40:41], v[34:35], s[42:43] op_sel_hi:[1,1,0]
	v_rcp_f32_e32 v43, v43
	v_pk_mul_f32 v[34:35], v[40:41], v[34:35]
	v_cmp_gt_f32_e32 vcc, 0, v24
	v_pk_mul_f32 v[34:35], v[38:39], v[34:35]
	v_pk_mul_f32 v[40:41], v[26:27], v[26:27]
	v_pk_mul_f32 v[38:39], v[24:25], v[34:35]
	v_pk_fma_f32 v[34:35], v[24:25], v[34:35], v[24:25] neg_lo:[1,0,0] neg_hi:[1,0,0]
	s_nop 0
	v_cndmask_b32_e32 v24, v34, v38, vcc
	v_cmp_gt_f32_e32 vcc, 0, v25
	s_nop 1
	v_cndmask_b32_e32 v25, v35, v39, vcc
	v_pk_fma_f32 v[34:35], v[42:43], s[22:23], v[36:37] op_sel_hi:[1,0,0]
	v_pk_mul_f32 v[36:37], v[40:41], s[56:57] op_sel_hi:[1,0]
	v_pk_fma_f32 v[34:35], v[42:43], v[34:35], s[38:39] op_sel_hi:[1,1,0]
	v_exp_f32_e32 v36, v36
	v_exp_f32_e32 v37, v37
	v_pk_fma_f32 v[34:35], v[42:43], v[34:35], s[40:41] op_sel_hi:[1,1,0]
	v_cmp_gt_f32_e32 vcc, 0, v26
	v_pk_fma_f32 v[34:35], v[42:43], v[34:35], s[42:43] op_sel_hi:[1,1,0]
	s_nop 0
	v_pk_mul_f32 v[34:35], v[42:43], v[34:35]
	s_nop 0
	v_pk_mul_f32 v[34:35], v[36:37], v[34:35]
	s_nop 0
	v_pk_mul_f32 v[36:37], v[26:27], v[34:35]
	v_pk_fma_f32 v[34:35], v[26:27], v[34:35], v[26:27] neg_lo:[1,0,0] neg_hi:[1,0,0]
	s_nop 0
	v_cndmask_b32_e32 v26, v34, v36, vcc
	v_cmp_gt_f32_e32 vcc, 0, v27
	s_nop 1
	v_cndmask_b32_e32 v27, v35, v37, vcc
.LBB0_221:
	v_add_u32_e32 v34, 0xa0, v144
	v_cvt_pk_bf16_f32 v28, v28, v29
	v_cvt_pk_bf16_f32 v29, v30, v31
	v_cvt_pk_bf16_f32 v30, v24, v25
	v_mov_b64_e32 v[24:25], s[26:27]
	v_mov_b32_e32 v33, v32
	v_cvt_pk_bf16_f32 v31, v26, v27
	v_mad_i64_i32 v[24:25], s[72:73], v34, s86, v[24:25]
	v_mov_b32_e32 v26, v32
	v_mov_b32_e32 v27, v32
	v_lshl_add_u64 v[24:25], v[120:121], 1, v[24:25]
	v_pk_mul_f32 v[22:23], v[22:23], v[26:27]
	v_pk_mul_f32 v[20:21], v[20:21], v[32:33]
	v_pk_mul_f32 v[18:19], v[18:19], v[26:27]
	s_and_b64 vcc, exec, s[6:7]
	v_pk_mul_f32 v[26:27], v[16:17], v[32:33]
	s_cmp_lg_u32 s99, 0
	s_cbranch_scc1 .Lwt192_5583
	global_store_dwordx4 v[24:25], v[28:31], off
	s_branch .Lwj192_5583
.Lwt192_5583:
	global_store_dwordx4 v[24:25], v[28:31], off sc1
; __device__ __forceinline__ f32x4 gelu4(f32x4 v) { const f32x2 a = gelu_pk((f32x2){v[0], v[1]}), b = gelu_pk((f32x2){v[2], v[3]}); return (f32x4){a.x, a.y, b.x, b.y}; }
; #define EPI_IT_ROW(it) EPI_ROW((it) >> 2, (it) & 3)
; #define EPI_LOAD_RR(ssp) float rr[8]; _Pragma("unroll") for (int it = 0; it < 8; ++it) rr[it] = (ssp)[EPI_IT_ROW(it)]; _Pragma("unroll") for (int it = 0; it < 8; ++it) rr[it] = rms_r(rr[it])
; #define EPI_PACK8(v0, v1) (u32x4){pk2((v0)[0], (v0)[1]), pk2((v0)[2], (v0)[3]), pk2((v1)[0], (v1)[1]), pk2((v1)[2], (v1)[3])}
; __device__ __forceinline__ f32x2 gelu_pk(f32x2 v) {
;     const f32x2 av = __builtin_elementwise_abs(v), d = av * 0.2316418882f + 1.0f;
;     f32x2 t; t.x = __builtin_amdgcn_rcpf(d.x); t.y = __builtin_amdgcn_rcpf(d.y);
;     f32x2 q = t * 0.5307027145f + (-0.7265760135f); q = q * t + 0.7107068705f; q = q * t + (-0.142248368f); q = q * t + 0.127414796f; q = q * t;
;     const f32x2 s = (v * v) * (-0.72134752044f);
;     f32x2 e; e.x = __builtin_amdgcn_exp2f(s.x); e.y = __builtin_amdgcn_exp2f(s.y);
;     const f32x2 m = v * (q * e), r = v - m;
;     f32x2 o; o.x = v.x < 0.f ? m.x : r.x; o.y = v.y < 0.f ? m.y : r.y; return o;
;     __device__ __forceinline__ void operator()(AccRef acc, const Unit& u, int wr, int wc, int fr, int fq) const {
;         asm volatile("" : "+v"(fr), "+v"(fq));
;         const bool act = u.pn < 4;
;         EPI_LOAD_RR(ss);
; #pragma unroll
;         for (int it = 0; it < 8; ++it) { const int ai = it >> 2, m = it & 3, row = EPI_IT_ROW(it);
; #pragma unroll
;             for (int bj = 0; bj < 2; ++bj) { f32x4 v0 = acc[ai][bj][m][0] * rr[it], v1 = acc[ai][bj][m][1] * rr[it];
;                 if (act) { v0 = gelu4(v0); v1 = gelu4(v1); }
;                 *(u32x4*)(O + (size_t)row * AB_IN + EPI_COL(bj)) = EPI_PACK8(v0, v1); } }
.Lwj192_5583:
	s_cbranch_vccnz .LBB0_223
	v_and_b32_e32 v17, 0x7fffffff, v21
	v_and_b32_e32 v16, 0x7fffffff, v20
	v_pk_fma_f32 v[16:17], v[16:17], s[18:19], 1.0 op_sel_hi:[1,0,0]
	v_mov_b64_e32 v[28:29], s[34:35]
	v_rcp_f32_e32 v16, v16
	v_rcp_f32_e32 v17, v17
	v_pk_mul_f32 v[32:33], v[20:21], v[20:21]
	v_and_b32_e32 v35, 0x7fffffff, v23
	v_pk_mul_f32 v[32:33], v[32:33], s[56:57] op_sel_hi:[1,0]
	v_pk_fma_f32 v[30:31], v[16:17], s[22:23], v[28:29] op_sel_hi:[1,0,0]
	v_exp_f32_e32 v32, v32
	v_pk_fma_f32 v[30:31], v[16:17], v[30:31], s[38:39] op_sel_hi:[1,1,0]
	v_exp_f32_e32 v33, v33
	v_pk_fma_f32 v[30:31], v[16:17], v[30:31], s[40:41] op_sel_hi:[1,1,0]
	v_and_b32_e32 v34, 0x7fffffff, v22
	v_pk_fma_f32 v[30:31], v[16:17], v[30:31], s[42:43] op_sel_hi:[1,1,0]
	v_pk_fma_f32 v[34:35], v[34:35], s[18:19], 1.0 op_sel_hi:[1,0,0]
	v_pk_mul_f32 v[16:17], v[16:17], v[30:31]
	v_rcp_f32_e32 v34, v34
	v_rcp_f32_e32 v35, v35
	v_pk_mul_f32 v[16:17], v[32:33], v[16:17]
	v_cmp_gt_f32_e32 vcc, 0, v20
	v_pk_mul_f32 v[32:33], v[20:21], v[16:17]
	v_pk_fma_f32 v[16:17], v[20:21], v[16:17], v[20:21] neg_lo:[1,0,0] neg_hi:[1,0,0]
	v_pk_mul_f32 v[30:31], v[22:23], v[22:23]
	v_cndmask_b32_e32 v20, v16, v32, vcc
	v_cmp_gt_f32_e32 vcc, 0, v21
	v_pk_mul_f32 v[30:31], v[30:31], s[56:57] op_sel_hi:[1,0]
	v_and_b32_e32 v32, 0x7fffffff, v26
	v_cndmask_b32_e32 v21, v17, v33, vcc
	v_pk_fma_f32 v[16:17], v[34:35], s[22:23], v[28:29] op_sel_hi:[1,0,0]
	v_exp_f32_e32 v30, v30
	v_pk_fma_f32 v[16:17], v[34:35], v[16:17], s[38:39] op_sel_hi:[1,1,0]
	v_exp_f32_e32 v31, v31
	v_pk_fma_f32 v[16:17], v[34:35], v[16:17], s[40:41] op_sel_hi:[1,1,0]
	v_and_b32_e32 v33, 0x7fffffff, v27
	v_pk_fma_f32 v[16:17], v[34:35], v[16:17], s[42:43] op_sel_hi:[1,1,0]
	v_pk_fma_f32 v[32:33], v[32:33], s[18:19], 1.0 op_sel_hi:[1,0,0]
	v_pk_mul_f32 v[16:17], v[34:35], v[16:17]
	v_rcp_f32_e32 v32, v32
	v_pk_mul_f32 v[16:17], v[30:31], v[16:17]
	v_rcp_f32_e32 v33, v33
	v_pk_mul_f32 v[30:31], v[22:23], v[16:17]
	v_pk_fma_f32 v[16:17], v[22:23], v[16:17], v[22:23] neg_lo:[1,0,0] neg_hi:[1,0,0]
	v_cmp_gt_f32_e32 vcc, 0, v22
	v_and_b32_e32 v35, 0x7fffffff, v19
	v_and_b32_e32 v34, 0x7fffffff, v18
	v_cndmask_b32_e32 v22, v16, v30, vcc
	v_cmp_gt_f32_e32 vcc, 0, v23
	v_pk_fma_f32 v[34:35], v[34:35], s[18:19], 1.0 op_sel_hi:[1,0,0]
	s_nop 0
	v_cndmask_b32_e32 v23, v17, v31, vcc
	v_pk_mul_f32 v[30:31], v[26:27], v[26:27]
	v_pk_fma_f32 v[16:17], v[32:33], s[22:23], v[28:29] op_sel_hi:[1,0,0]
	v_pk_mul_f32 v[30:31], v[30:31], s[56:57] op_sel_hi:[1,0]
	v_pk_fma_f32 v[16:17], v[32:33], v[16:17], s[38:39] op_sel_hi:[1,1,0]
	v_exp_f32_e32 v30, v30
	v_exp_f32_e32 v31, v31
	v_pk_fma_f32 v[16:17], v[32:33], v[16:17], s[40:41] op_sel_hi:[1,1,0]
	v_rcp_f32_e32 v34, v34
	v_pk_fma_f32 v[16:17], v[32:33], v[16:17], s[42:43] op_sel_hi:[1,1,0]
	v_rcp_f32_e32 v35, v35
	v_pk_mul_f32 v[16:17], v[32:33], v[16:17]
	v_cmp_gt_f32_e32 vcc, 0, v26
	v_pk_mul_f32 v[16:17], v[30:31], v[16:17]
	v_pk_mul_f32 v[32:33], v[18:19], v[18:19]
	v_pk_mul_f32 v[30:31], v[26:27], v[16:17]
	v_pk_fma_f32 v[16:17], v[26:27], v[16:17], v[26:27] neg_lo:[1,0,0] neg_hi:[1,0,0]
	s_nop 0
	v_cndmask_b32_e32 v26, v16, v30, vcc
	v_cmp_gt_f32_e32 vcc, 0, v27
	s_nop 1
	v_cndmask_b32_e32 v27, v17, v31, vcc
	v_pk_fma_f32 v[16:17], v[34:35], s[22:23], v[28:29] op_sel_hi:[1,0,0]
	v_pk_mul_f32 v[28:29], v[32:33], s[56:57] op_sel_hi:[1,0]
	v_pk_fma_f32 v[16:17], v[34:35], v[16:17], s[38:39] op_sel_hi:[1,1,0]
	v_exp_f32_e32 v28, v28
	v_exp_f32_e32 v29, v29
	v_pk_fma_f32 v[16:17], v[34:35], v[16:17], s[40:41] op_sel_hi:[1,1,0]
	v_cmp_gt_f32_e32 vcc, 0, v18
	v_pk_fma_f32 v[16:17], v[34:35], v[16:17], s[42:43] op_sel_hi:[1,1,0]
	s_nop 0
	v_pk_mul_f32 v[16:17], v[34:35], v[16:17]
	s_nop 0
	v_pk_mul_f32 v[16:17], v[28:29], v[16:17]
	s_nop 0
	v_pk_mul_f32 v[28:29], v[18:19], v[16:17]
	v_pk_fma_f32 v[16:17], v[18:19], v[16:17], v[18:19] neg_lo:[1,0,0] neg_hi:[1,0,0]
	s_nop 0
	v_cndmask_b32_e32 v18, v16, v28, vcc
	v_cmp_gt_f32_e32 vcc, 0, v19
	s_nop 1
	v_cndmask_b32_e32 v19, v17, v29, vcc
.LBB0_223:
	v_fmamk_f32 v16, v145, 0x3a800000, v156
	v_rsq_f32_e32 v16, v16
	s_and_b64 vcc, exec, s[6:7]
	v_cvt_pk_bf16_f32 v20, v20, v21
	v_cvt_pk_bf16_f32 v21, v22, v23
	v_pk_mul_f32 v[14:15], v[14:15], v[16:17] op_sel_hi:[1,0]
	v_pk_mul_f32 v[12:13], v[12:13], v[16:17] op_sel_hi:[1,0]
	v_pk_mul_f32 v[10:11], v[10:11], v[16:17] op_sel_hi:[1,0]
	v_pk_mul_f32 v[8:9], v[8:9], v[16:17] op_sel_hi:[1,0]
	v_cvt_pk_bf16_f32 v22, v26, v27
	v_cvt_pk_bf16_f32 v23, v18, v19
	s_cmp_lg_u32 s99, 0
	s_cbranch_scc1 .Lwt192_5699
	global_store_dwordx4 v[24:25], v[20:23], off offset:256
	s_branch .Lwj192_5699
.Lwt192_5699:
	global_store_dwordx4 v[24:25], v[20:23], off offset:256 sc1
; __device__ __forceinline__ f32x4 gelu4(f32x4 v) { const f32x2 a = gelu_pk((f32x2){v[0], v[1]}), b = gelu_pk((f32x2){v[2], v[3]}); return (f32x4){a.x, a.y, b.x, b.y}; }
; #define EPI_IT_ROW(it) EPI_ROW((it) >> 2, (it) & 3)
; #define EPI_LOAD_RR(ssp) float rr[8]; _Pragma("unroll") for (int it = 0; it < 8; ++it) rr[it] = (ssp)[EPI_IT_ROW(it)]; _Pragma("unroll") for (int it = 0; it < 8; ++it) rr[it] = rms_r(rr[it])
; #define EPI_PACK8(v0, v1) (u32x4){pk2((v0)[0], (v0)[1]), pk2((v0)[2], (v0)[3]), pk2((v1)[0], (v1)[1]), pk2((v1)[2], (v1)[3])}
; __device__ __forceinline__ f32x2 gelu_pk(f32x2 v) {
;     const f32x2 av = __builtin_elementwise_abs(v), d = av * 0.2316418882f + 1.0f;
;     f32x2 t; t.x = __builtin_amdgcn_rcpf(d.x); t.y = __builtin_amdgcn_rcpf(d.y);
;     f32x2 q = t * 0.5307027145f + (-0.7265760135f); q = q * t + 0.7107068705f; q = q * t + (-0.142248368f); q = q * t + 0.127414796f; q = q * t;
;     const f32x2 s = (v * v) * (-0.72134752044f);
;     f32x2 e; e.x = __builtin_amdgcn_exp2f(s.x); e.y = __builtin_amdgcn_exp2f(s.y);
;     const f32x2 m = v * (q * e), r = v - m;
;     f32x2 o; o.x = v.x < 0.f ? m.x : r.x; o.y = v.y < 0.f ? m.y : r.y; return o;
;     __device__ __forceinline__ void operator()(AccRef acc, const Unit& u, int wr, int wc, int fr, int fq) const {
;         asm volatile("" : "+v"(fr), "+v"(fq));
;         const bool act = u.pn < 4;
;         EPI_LOAD_RR(ss);
; #pragma unroll
;         for (int it = 0; it < 8; ++it) { const int ai = it >> 2, m = it & 3, row = EPI_IT_ROW(it);
; #pragma unroll
;             for (int bj = 0; bj < 2; ++bj) { f32x4 v0 = acc[ai][bj][m][0] * rr[it], v1 = acc[ai][bj][m][1] * rr[it];
;                 if (act) { v0 = gelu4(v0); v1 = gelu4(v1); }
;                 *(u32x4*)(O + (size_t)row * AB_IN + EPI_COL(bj)) = EPI_PACK8(v0, v1); } }
.Lwj192_5699:
	s_cbranch_vccnz .LBB0_225
	v_and_b32_e32 v19, 0x7fffffff, v13
	v_and_b32_e32 v18, 0x7fffffff, v12
	v_pk_fma_f32 v[18:19], v[18:19], s[18:19], 1.0 op_sel_hi:[1,0,0]
	v_mov_b64_e32 v[20:21], s[34:35]
	v_rcp_f32_e32 v18, v18
	v_rcp_f32_e32 v19, v19
	v_pk_mul_f32 v[24:25], v[12:13], v[12:13]
	v_and_b32_e32 v27, 0x7fffffff, v15
	v_pk_mul_f32 v[24:25], v[24:25], s[56:57] op_sel_hi:[1,0]
	v_pk_fma_f32 v[22:23], v[18:19], s[22:23], v[20:21] op_sel_hi:[1,0,0]
	v_exp_f32_e32 v24, v24
	v_pk_fma_f32 v[22:23], v[18:19], v[22:23], s[38:39] op_sel_hi:[1,1,0]
	v_exp_f32_e32 v25, v25
	v_pk_fma_f32 v[22:23], v[18:19], v[22:23], s[40:41] op_sel_hi:[1,1,0]
	v_and_b32_e32 v26, 0x7fffffff, v14
	v_pk_fma_f32 v[22:23], v[18:19], v[22:23], s[42:43] op_sel_hi:[1,1,0]
	v_pk_fma_f32 v[26:27], v[26:27], s[18:19], 1.0 op_sel_hi:[1,0,0]
	v_pk_mul_f32 v[18:19], v[18:19], v[22:23]
	v_rcp_f32_e32 v26, v26
	v_rcp_f32_e32 v27, v27
	v_pk_mul_f32 v[18:19], v[24:25], v[18:19]
	v_cmp_gt_f32_e32 vcc, 0, v12
	v_pk_mul_f32 v[24:25], v[12:13], v[18:19]
	v_pk_fma_f32 v[18:19], v[12:13], v[18:19], v[12:13] neg_lo:[1,0,0] neg_hi:[1,0,0]
	v_pk_mul_f32 v[22:23], v[14:15], v[14:15]
	v_cndmask_b32_e32 v12, v18, v24, vcc
	v_cmp_gt_f32_e32 vcc, 0, v13
	v_pk_mul_f32 v[22:23], v[22:23], s[56:57] op_sel_hi:[1,0]
	v_and_b32_e32 v24, 0x7fffffff, v8
	v_cndmask_b32_e32 v13, v19, v25, vcc
	v_pk_fma_f32 v[18:19], v[26:27], s[22:23], v[20:21] op_sel_hi:[1,0,0]
	v_exp_f32_e32 v22, v22
	v_pk_fma_f32 v[18:19], v[26:27], v[18:19], s[38:39] op_sel_hi:[1,1,0]
	v_exp_f32_e32 v23, v23
	v_pk_fma_f32 v[18:19], v[26:27], v[18:19], s[40:41] op_sel_hi:[1,1,0]
	v_and_b32_e32 v25, 0x7fffffff, v9
	v_pk_fma_f32 v[18:19], v[26:27], v[18:19], s[42:43] op_sel_hi:[1,1,0]
	v_pk_fma_f32 v[24:25], v[24:25], s[18:19], 1.0 op_sel_hi:[1,0,0]
	v_pk_mul_f32 v[18:19], v[26:27], v[18:19]
	v_rcp_f32_e32 v24, v24
	v_pk_mul_f32 v[18:19], v[22:23], v[18:19]
	v_rcp_f32_e32 v25, v25
	v_pk_mul_f32 v[22:23], v[14:15], v[18:19]
	v_pk_fma_f32 v[18:19], v[14:15], v[18:19], v[14:15] neg_lo:[1,0,0] neg_hi:[1,0,0]
	v_cmp_gt_f32_e32 vcc, 0, v14
	v_and_b32_e32 v27, 0x7fffffff, v11
	v_and_b32_e32 v26, 0x7fffffff, v10
	v_cndmask_b32_e32 v14, v18, v22, vcc
	v_cmp_gt_f32_e32 vcc, 0, v15
	v_pk_fma_f32 v[26:27], v[26:27], s[18:19], 1.0 op_sel_hi:[1,0,0]
	s_nop 0
	v_cndmask_b32_e32 v15, v19, v23, vcc
	v_pk_mul_f32 v[22:23], v[8:9], v[8:9]
	v_pk_fma_f32 v[18:19], v[24:25], s[22:23], v[20:21] op_sel_hi:[1,0,0]
	v_pk_mul_f32 v[22:23], v[22:23], s[56:57] op_sel_hi:[1,0]
	v_pk_fma_f32 v[18:19], v[24:25], v[18:19], s[38:39] op_sel_hi:[1,1,0]
	v_exp_f32_e32 v22, v22
	v_exp_f32_e32 v23, v23
	v_pk_fma_f32 v[18:19], v[24:25], v[18:19], s[40:41] op_sel_hi:[1,1,0]
	v_rcp_f32_e32 v26, v26
	v_pk_fma_f32 v[18:19], v[24:25], v[18:19], s[42:43] op_sel_hi:[1,1,0]
	v_rcp_f32_e32 v27, v27
	v_pk_mul_f32 v[18:19], v[24:25], v[18:19]
	v_cmp_gt_f32_e32 vcc, 0, v8
	v_pk_mul_f32 v[18:19], v[22:23], v[18:19]
	v_pk_mul_f32 v[24:25], v[10:11], v[10:11]
	v_pk_mul_f32 v[22:23], v[8:9], v[18:19]
	v_pk_fma_f32 v[18:19], v[8:9], v[18:19], v[8:9] neg_lo:[1,0,0] neg_hi:[1,0,0]
	s_nop 0
	v_cndmask_b32_e32 v8, v18, v22, vcc
	v_cmp_gt_f32_e32 vcc, 0, v9
	s_nop 1
	v_cndmask_b32_e32 v9, v19, v23, vcc
	v_pk_fma_f32 v[18:19], v[26:27], s[22:23], v[20:21] op_sel_hi:[1,0,0]
	v_pk_mul_f32 v[20:21], v[24:25], s[56:57] op_sel_hi:[1,0]
	v_pk_fma_f32 v[18:19], v[26:27], v[18:19], s[38:39] op_sel_hi:[1,1,0]
	v_exp_f32_e32 v20, v20
	v_exp_f32_e32 v21, v21
	v_pk_fma_f32 v[18:19], v[26:27], v[18:19], s[40:41] op_sel_hi:[1,1,0]
	v_cmp_gt_f32_e32 vcc, 0, v10
	v_pk_fma_f32 v[18:19], v[26:27], v[18:19], s[42:43] op_sel_hi:[1,1,0]
	s_nop 0
	v_pk_mul_f32 v[18:19], v[26:27], v[18:19]
	s_nop 0
	v_pk_mul_f32 v[18:19], v[20:21], v[18:19]
	s_nop 0
	v_pk_mul_f32 v[20:21], v[10:11], v[18:19]
	v_pk_fma_f32 v[18:19], v[10:11], v[18:19], v[10:11] neg_lo:[1,0,0] neg_hi:[1,0,0]
	s_nop 0
	v_cndmask_b32_e32 v10, v18, v20, vcc
	v_cmp_gt_f32_e32 vcc, 0, v11
	s_nop 1
	v_cndmask_b32_e32 v11, v19, v21, vcc
.LBB0_225:
	v_add_u32_e32 v18, 0xb0, v144
	v_cvt_pk_bf16_f32 v12, v12, v13
	v_cvt_pk_bf16_f32 v13, v14, v15
	v_cvt_pk_bf16_f32 v14, v8, v9
	v_mov_b64_e32 v[8:9], s[26:27]
	v_mov_b32_e32 v17, v16
	v_cvt_pk_bf16_f32 v15, v10, v11
	v_mad_i64_i32 v[8:9], s[72:73], v18, s86, v[8:9]
	v_mov_b32_e32 v10, v16
	v_mov_b32_e32 v11, v16
	v_lshl_add_u64 v[8:9], v[120:121], 1, v[8:9]
	v_pk_mul_f32 v[6:7], v[6:7], v[10:11]
	v_pk_mul_f32 v[4:5], v[4:5], v[16:17]
	v_pk_mul_f32 v[2:3], v[2:3], v[10:11]
	s_and_b64 vcc, exec, s[6:7]
	v_pk_mul_f32 v[0:1], v[0:1], v[16:17]
	s_cmp_lg_u32 s99, 0
	s_cbranch_scc1 .Lwt192_5820
	global_store_dwordx4 v[8:9], v[12:15], off
	s_branch .Lwj192_5820
; __device__ __forceinline__ f32x4 gelu4(f32x4 v) { const f32x2 a = gelu_pk((f32x2){v[0], v[1]}), b = gelu_pk((f32x2){v[2], v[3]}); return (f32x4){a.x, a.y, b.x, b.y}; }
; #define PG8_BAR __builtin_amdgcn_s_barrier()
; #define EPI_PACK8(v0, v1) (u32x4){pk2((v0)[0], (v0)[1]), pk2((v0)[2], (v0)[3]), pk2((v1)[0], (v1)[1]), pk2((v1)[2], (v1)[3])}
; template <class Epi>
; __device__ __forceinline__ void gemm_phase(LAS unsigned char* lds, const Gemm g, const StaticOrder& S, const Epi& E) {
;     ...
;         if (!has_next) break;
; #pragma unroll
;         for (int a = 0; a < 2; ++a)
; #pragma unroll
;             for (int b = 0; b < 2; ++b)
; #pragma unroll
;                 for (int m = 0; m < 4; ++m)
; #pragma unroll
;                     for (int n = 0; n < 2; ++n) acc[a][b][m][n] = (f32x4){0.f, 0.f, 0.f, 0.f};
;         cur = nxt; cA = nA; cB = nB; ++ui;
;         if (wr == 1) PG8_BAR;
;     __device__ __forceinline__ void operator()(AccRef acc, const Unit& u, int wr, int wc, int fr, int fq) const {
;     ...
;             for (int bj = 0; bj < 2; ++bj) { f32x4 v0 = acc[ai][bj][m][0] * rr[it], v1 = acc[ai][bj][m][1] * rr[it];
;                 if (act) { v0 = gelu4(v0); v1 = gelu4(v1); }
;                 *(u32x4*)(O + (size_t)row * AB_IN + EPI_COL(bj)) = EPI_PACK8(v0, v1); } }
.Lwt192_5820:
	global_store_dwordx4 v[8:9], v[12:15], off sc1
.Lwj192_5820:
	s_cbranch_vccnz .LBB0_227
	v_and_b32_e32 v11, 0x7fffffff, v5
	v_and_b32_e32 v10, 0x7fffffff, v4
	v_pk_fma_f32 v[10:11], v[10:11], s[18:19], 1.0 op_sel_hi:[1,0,0]
	v_mov_b64_e32 v[12:13], s[34:35]
	v_rcp_f32_e32 v10, v10
	v_rcp_f32_e32 v11, v11
	v_pk_mul_f32 v[16:17], v[4:5], v[4:5]
	v_and_b32_e32 v19, 0x7fffffff, v7
	v_pk_mul_f32 v[16:17], v[16:17], s[56:57] op_sel_hi:[1,0]
	v_pk_fma_f32 v[14:15], v[10:11], s[22:23], v[12:13] op_sel_hi:[1,0,0]
	v_exp_f32_e32 v16, v16
	v_pk_fma_f32 v[14:15], v[10:11], v[14:15], s[38:39] op_sel_hi:[1,1,0]
	v_exp_f32_e32 v17, v17
	v_pk_fma_f32 v[14:15], v[10:11], v[14:15], s[40:41] op_sel_hi:[1,1,0]
	v_and_b32_e32 v18, 0x7fffffff, v6
	v_pk_fma_f32 v[14:15], v[10:11], v[14:15], s[42:43] op_sel_hi:[1,1,0]
	v_pk_fma_f32 v[18:19], v[18:19], s[18:19], 1.0 op_sel_hi:[1,0,0]
	v_pk_mul_f32 v[10:11], v[10:11], v[14:15]
	v_rcp_f32_e32 v18, v18
	v_rcp_f32_e32 v19, v19
	v_pk_mul_f32 v[10:11], v[16:17], v[10:11]
	v_cmp_gt_f32_e32 vcc, 0, v4
	v_pk_mul_f32 v[16:17], v[4:5], v[10:11]
	v_pk_fma_f32 v[10:11], v[4:5], v[10:11], v[4:5] neg_lo:[1,0,0] neg_hi:[1,0,0]
	v_pk_mul_f32 v[14:15], v[6:7], v[6:7]
	v_cndmask_b32_e32 v4, v10, v16, vcc
	v_cmp_gt_f32_e32 vcc, 0, v5
	v_pk_mul_f32 v[14:15], v[14:15], s[56:57] op_sel_hi:[1,0]
	v_and_b32_e32 v16, 0x7fffffff, v0
	v_cndmask_b32_e32 v5, v11, v17, vcc
	v_pk_fma_f32 v[10:11], v[18:19], s[22:23], v[12:13] op_sel_hi:[1,0,0]
	v_exp_f32_e32 v14, v14
	v_pk_fma_f32 v[10:11], v[18:19], v[10:11], s[38:39] op_sel_hi:[1,1,0]
	v_exp_f32_e32 v15, v15
	v_pk_fma_f32 v[10:11], v[18:19], v[10:11], s[40:41] op_sel_hi:[1,1,0]
	v_and_b32_e32 v17, 0x7fffffff, v1
	v_pk_fma_f32 v[10:11], v[18:19], v[10:11], s[42:43] op_sel_hi:[1,1,0]
	v_pk_fma_f32 v[16:17], v[16:17], s[18:19], 1.0 op_sel_hi:[1,0,0]
	v_pk_mul_f32 v[10:11], v[18:19], v[10:11]
	v_rcp_f32_e32 v16, v16
	v_pk_mul_f32 v[10:11], v[14:15], v[10:11]
	v_rcp_f32_e32 v17, v17
	v_pk_mul_f32 v[14:15], v[6:7], v[10:11]
	v_pk_fma_f32 v[10:11], v[6:7], v[10:11], v[6:7] neg_lo:[1,0,0] neg_hi:[1,0,0]
	v_cmp_gt_f32_e32 vcc, 0, v6
	v_and_b32_e32 v19, 0x7fffffff, v3
	v_and_b32_e32 v18, 0x7fffffff, v2
	v_cndmask_b32_e32 v6, v10, v14, vcc
	v_cmp_gt_f32_e32 vcc, 0, v7
	v_pk_fma_f32 v[18:19], v[18:19], s[18:19], 1.0 op_sel_hi:[1,0,0]
	s_nop 0
	v_cndmask_b32_e32 v7, v11, v15, vcc
	v_pk_mul_f32 v[14:15], v[0:1], v[0:1]
	v_pk_fma_f32 v[10:11], v[16:17], s[22:23], v[12:13] op_sel_hi:[1,0,0]
	v_pk_mul_f32 v[14:15], v[14:15], s[56:57] op_sel_hi:[1,0]
	v_pk_fma_f32 v[10:11], v[16:17], v[10:11], s[38:39] op_sel_hi:[1,1,0]
	v_exp_f32_e32 v14, v14
	v_exp_f32_e32 v15, v15
	v_pk_fma_f32 v[10:11], v[16:17], v[10:11], s[40:41] op_sel_hi:[1,1,0]
	v_rcp_f32_e32 v18, v18
	v_pk_fma_f32 v[10:11], v[16:17], v[10:11], s[42:43] op_sel_hi:[1,1,0]
	v_rcp_f32_e32 v19, v19
	v_pk_mul_f32 v[10:11], v[16:17], v[10:11]
	v_cmp_gt_f32_e32 vcc, 0, v0
	v_pk_mul_f32 v[10:11], v[14:15], v[10:11]
	v_pk_mul_f32 v[16:17], v[2:3], v[2:3]
	v_pk_mul_f32 v[14:15], v[0:1], v[10:11]
	v_pk_fma_f32 v[10:11], v[0:1], v[10:11], v[0:1] neg_lo:[1,0,0] neg_hi:[1,0,0]
	s_nop 0
	v_cndmask_b32_e32 v0, v10, v14, vcc
	v_cmp_gt_f32_e32 vcc, 0, v1
	s_nop 1
	v_cndmask_b32_e32 v1, v11, v15, vcc
	v_pk_fma_f32 v[10:11], v[18:19], s[22:23], v[12:13] op_sel_hi:[1,0,0]
	v_pk_mul_f32 v[12:13], v[16:17], s[56:57] op_sel_hi:[1,0]
	v_pk_fma_f32 v[10:11], v[18:19], v[10:11], s[38:39] op_sel_hi:[1,1,0]
	v_exp_f32_e32 v12, v12
	v_exp_f32_e32 v13, v13
	v_pk_fma_f32 v[10:11], v[18:19], v[10:11], s[40:41] op_sel_hi:[1,1,0]
	v_cmp_gt_f32_e32 vcc, 0, v2
	v_pk_fma_f32 v[10:11], v[18:19], v[10:11], s[42:43] op_sel_hi:[1,1,0]
	s_nop 0
	v_pk_mul_f32 v[10:11], v[18:19], v[10:11]
	s_nop 0
	v_pk_mul_f32 v[10:11], v[12:13], v[10:11]
	s_nop 0
	v_pk_mul_f32 v[12:13], v[2:3], v[10:11]
	v_pk_fma_f32 v[10:11], v[2:3], v[10:11], v[2:3] neg_lo:[1,0,0] neg_hi:[1,0,0]
	s_nop 0
	v_cndmask_b32_e32 v2, v10, v12, vcc
	v_cmp_gt_f32_e32 vcc, 0, v3
	s_nop 1
	v_cndmask_b32_e32 v3, v11, v13, vcc
.LBB0_227:
	s_andn2_b64 vcc, exec, s[4:5]
	s_mov_b64 s[4:5], -1
	v_cvt_pk_bf16_f32 v4, v4, v5
	v_cvt_pk_bf16_f32 v5, v6, v7
	v_cvt_pk_bf16_f32 v6, v0, v1
	v_cvt_pk_bf16_f32 v7, v2, v3
	s_cmp_lg_u32 s99, 0
	s_cbranch_scc1 .Lwt192_5931
	global_store_dwordx4 v[8:9], v[4:7], off offset:256
	s_branch .Lwj192_5931
.Lwt192_5931:
	global_store_dwordx4 v[8:9], v[4:7], off offset:256 sc1
.Lwj192_5931:
	s_cbranch_vccnz .LBB0_188
	s_andn2_b64 vcc, exec, s[8:9]
	s_cbranch_vccnz .LBB0_187
	s_barrier
	s_branch .LBB0_187

; #define PG8_STAGE(bufoff, gbase, voff) do { _Pragma("unroll") for (int _i = 0; _i < 2; ++_i) \
;         __builtin_amdgcn_global_load_lds((const unsigned*)((const char*)(gbase) + (voff)[_i]), (LAS unsigned*)(lds + (bufoff) + ldsw + _i * 8192), 16, 0, 0); } while (0)
; #define PG8_LDA(dst, b, h) do { _Pragma("unroll") for (int m = 0; m < 4; ++m) _Pragma("unroll") for (int k = 0; k < 2; ++k) dst[m][k] = *(const LAS bf16x8*)(lds + PG8_SA(b, h) + aoff + m * 2048 + k * 1024); } while (0)
; #define PG8_LDB(dst, b, h) do { _Pragma("unroll") for (int n = 0; n < 2; ++n) _Pragma("unroll") for (int k = 0; k < 2; ++k) dst[n][k] = *(const LAS bf16x8*)(lds + PG8_SB(b, h) + boff + n * 2048 + k * 1024); } while (0)
; #define PG8_MMA(ai, bj, At, Bt) do { __builtin_amdgcn_s_setprio(1); _Pragma("unroll") for (int m = 0; m < 4; ++m) _Pragma("unroll") for (int n = 0; n < 2; ++n) _Pragma("unroll") for (int k = 0; k < 2; ++k) \
;         acc[ai][bj][m][n] = __builtin_amdgcn_mfma_f32_16x16x32_bf16(Bt[n][k], At[m][k], acc[ai][bj][m][n], 0, 0, 0); __builtin_amdgcn_s_setprio(0); } while (0)
; #define PG8_WAIT_V(n) asm volatile("s_waitcnt vmcnt(" #n ")" ::: "memory")
; #define PG8_WAIT_L(n) asm volatile("s_waitcnt lgkmcnt(" #n ")" ::: "memory")
; #define PG8_BAR __builtin_amdgcn_s_barrier()
; #define PG8_SCHED __builtin_amdgcn_sched_barrier(0)
; template <class Epi>
; __device__ __forceinline__ void gemm_phase(LAS unsigned char* lds, const Gemm g, const StaticOrder& S, const Epi& E) {
;     ...
;             PG8_LDB(B0, 0, 0); PG8_LDB(B1, 0, 1); PG8_SCHED; PG8_LDA(At, 0, 0); PG8_STAGE(PG8_SA(1, 1), a1 + hstepA, voffA);
;             PG8_WAIT_V(8); PG8_WAIT_L(0); PG8_BAR; PG8_MMA(0, 0, At, B0); PG8_MMA(0, 1, At, B1); PG8_BAR; PG8_SCHED;
;             PG8_LDA(At, 0, 1); PG8_STAGE(PG8_SB(0, 0), b2, voffB); PG8_STAGE(PG8_SB(0, 1), b2 + hstepB, voffB); PG8_STAGE(PG8_SA(0, 0), a2, voffA);
;             PG8_WAIT_V(8); PG8_WAIT_L(0); PG8_BAR; PG8_MMA(1, 0, At, B0); PG8_MMA(1, 1, At, B1); PG8_BAR; PG8_SCHED;
.LBB0_457:
	ds_read_b128 v[128:131], v173
	ds_read_b128 v[132:135], v173 offset:1024
	ds_read_b128 v[136:139], v173 offset:2048
	ds_read_b128 v[140:143], v173 offset:3072
	ds_read_b128 v[160:163], v174
	ds_read_b128 v[164:167], v174 offset:1024
	ds_read_b128 v[178:181], v174 offset:2048
	ds_read_b128 v[182:185], v174 offset:3072
	s_add_u32 s42, s38, 0xfffc0080
	s_addc_u32 s43, s39, -1
	s_cmp_eq_u32 s77, 12
	s_cselect_b32 s53, s1, s43
	s_cselect_b32 s52, s23, s42
	s_cselect_b32 s43, s19, s76
	s_cselect_b32 s42, s74, s75
	v_lshl_add_u64 v[168:169], s[38:39], 0, v[152:153]
	s_add_i32 m0, s35, 0xc000
	ds_read_b128 v[186:189], v175
	ds_read_b128 v[190:193], v175 offset:1024
	ds_read_b128 v[194:197], v175 offset:2048
	ds_read_b128 v[198:201], v175 offset:3072
	ds_read_b128 v[202:205], v175 offset:4096
	ds_read_b128 v[206:209], v175 offset:5120
	ds_read_b128 v[210:213], v175 offset:6144
	ds_read_b128 v[214:217], v175 offset:7168
	global_load_lds_dwordx4 v[168:169], off
	v_lshl_add_u64 v[168:169], s[38:39], 0, v[154:155]
	s_add_i32 m0, s35, 0xe000
	s_nop 0
	global_load_lds_dwordx4 v[168:169], off
	s_waitcnt vmcnt(8)
	s_waitcnt lgkmcnt(0)
	s_barrier
	s_setprio 1
	s_waitcnt lgkmcnt(0)
	v_mfma_f32_16x16x32_bf16 v[124:127], v[128:131], v[186:189], v[124:127]
	v_mfma_f32_16x16x32_bf16 v[120:123], v[136:139], v[186:189], v[120:123]
	v_mfma_f32_16x16x32_bf16 v[108:111], v[128:131], v[194:197], v[108:111]
	v_mfma_f32_16x16x32_bf16 v[104:107], v[136:139], v[194:197], v[104:107]
	v_mfma_f32_16x16x32_bf16 v[92:95], v[128:131], v[202:205], v[92:95]
	v_mfma_f32_16x16x32_bf16 v[88:91], v[136:139], v[202:205], v[88:91]
	v_mfma_f32_16x16x32_bf16 v[76:79], v[128:131], v[210:213], v[76:79]
	v_mfma_f32_16x16x32_bf16 v[72:75], v[136:139], v[210:213], v[72:75]
	v_mfma_f32_16x16x32_bf16 v[124:127], v[132:135], v[190:193], v[124:127]
	v_mfma_f32_16x16x32_bf16 v[120:123], v[140:143], v[190:193], v[120:123]
	v_mfma_f32_16x16x32_bf16 v[108:111], v[132:135], v[198:201], v[108:111]
	v_mfma_f32_16x16x32_bf16 v[104:107], v[140:143], v[198:201], v[104:107]
	v_mfma_f32_16x16x32_bf16 v[92:95], v[132:135], v[206:209], v[92:95]
	v_mfma_f32_16x16x32_bf16 v[88:91], v[140:143], v[206:209], v[88:91]
	v_mfma_f32_16x16x32_bf16 v[76:79], v[132:135], v[214:217], v[76:79]
	v_mfma_f32_16x16x32_bf16 v[72:75], v[140:143], v[214:217], v[72:75]
	s_setprio 0
	s_setprio 1
	v_mfma_f32_16x16x32_bf16 v[116:119], v[160:163], v[186:189], v[116:119]
	v_mfma_f32_16x16x32_bf16 v[112:115], v[178:181], v[186:189], v[112:115]
	v_mfma_f32_16x16x32_bf16 v[100:103], v[160:163], v[194:197], v[100:103]
	v_mfma_f32_16x16x32_bf16 v[96:99], v[178:181], v[194:197], v[96:99]
	v_mfma_f32_16x16x32_bf16 v[84:87], v[160:163], v[202:205], v[84:87]
	v_mfma_f32_16x16x32_bf16 v[80:83], v[178:181], v[202:205], v[80:83]
	v_mfma_f32_16x16x32_bf16 v[68:71], v[160:163], v[210:213], v[68:71]
	v_mfma_f32_16x16x32_bf16 v[64:67], v[178:181], v[210:213], v[64:67]
	v_mfma_f32_16x16x32_bf16 v[116:119], v[164:167], v[190:193], v[116:119]
	v_mfma_f32_16x16x32_bf16 v[112:115], v[182:185], v[190:193], v[112:115]
	v_mfma_f32_16x16x32_bf16 v[100:103], v[164:167], v[198:201], v[100:103]
	v_mfma_f32_16x16x32_bf16 v[96:99], v[182:185], v[198:201], v[96:99]
	v_mfma_f32_16x16x32_bf16 v[84:87], v[164:167], v[206:209], v[84:87]
	v_mfma_f32_16x16x32_bf16 v[80:83], v[182:185], v[206:209], v[80:83]
	v_mfma_f32_16x16x32_bf16 v[68:71], v[164:167], v[214:217], v[68:71]
	v_mfma_f32_16x16x32_bf16 v[64:67], v[182:185], v[214:217], v[64:67]
	s_setprio 0
	s_barrier
	s_add_i32 s78, s72, s54
	v_lshl_add_u64 v[168:169], s[42:43], 0, v[146:147]
	s_mov_b32 m0, s78
	ds_read_b128 v[186:189], v175 offset:16384
	ds_read_b128 v[190:193], v175 offset:17408
	ds_read_b128 v[194:197], v175 offset:18432
	ds_read_b128 v[198:201], v175 offset:19456
	ds_read_b128 v[202:205], v175 offset:20480
	ds_read_b128 v[206:209], v175 offset:21504
	ds_read_b128 v[210:213], v175 offset:22528
	ds_read_b128 v[214:217], v175 offset:23552
	global_load_lds_dwordx4 v[168:169], off
	s_add_i32 m0, s78, 0x2000
	s_add_u32 s78, s42, 0x40000
	v_lshl_add_u64 v[218:219], s[42:43], 0, v[150:151]
	s_addc_u32 s79, s43, 0
	s_add_i32 s80, s73, s54
	global_load_lds_dwordx4 v[218:219], off
	v_lshl_add_u64 v[220:221], s[78:79], 0, v[146:147]
	s_mov_b32 m0, s80
	v_lshl_add_u64 v[222:223], s[52:53], 0, v[148:149]
	global_load_lds_dwordx4 v[220:221], off
	v_lshl_add_u64 v[220:221], s[78:79], 0, v[150:151]
	s_add_i32 m0, s80, 0x2000
	s_nop 0
	global_load_lds_dwordx4 v[220:221], off
	v_lshl_add_u64 v[220:221], s[52:53], 0, v[144:145]
	s_mov_b32 m0, s35
	s_nop 0
	global_load_lds_dwordx4 v[220:221], off
	s_mov_b32 m0, s55
	s_nop 0
	global_load_lds_dwordx4 v[222:223], off
	s_waitcnt vmcnt(8)
	s_waitcnt lgkmcnt(0)
	s_barrier
; #define PG8_STAGE(bufoff, gbase, voff) do { _Pragma("unroll") for (int _i = 0; _i < 2; ++_i) \
;         __builtin_amdgcn_global_load_lds((const unsigned*)((const char*)(gbase) + (voff)[_i]), (LAS unsigned*)(lds + (bufoff) + ldsw + _i * 8192), 16, 0, 0); } while (0)
; #define PG8_LDA(dst, b, h) do { _Pragma("unroll") for (int m = 0; m < 4; ++m) _Pragma("unroll") for (int k = 0; k < 2; ++k) dst[m][k] = *(const LAS bf16x8*)(lds + PG8_SA(b, h) + aoff + m * 2048 + k * 1024); } while (0)
; #define PG8_LDB(dst, b, h) do { _Pragma("unroll") for (int n = 0; n < 2; ++n) _Pragma("unroll") for (int k = 0; k < 2; ++k) dst[n][k] = *(const LAS bf16x8*)(lds + PG8_SB(b, h) + boff + n * 2048 + k * 1024); } while (0)
; #define PG8_MMA(ai, bj, At, Bt) do { __builtin_amdgcn_s_setprio(1); _Pragma("unroll") for (int m = 0; m < 4; ++m) _Pragma("unroll") for (int n = 0; n < 2; ++n) _Pragma("unroll") for (int k = 0; k < 2; ++k) \
;         acc[ai][bj][m][n] = __builtin_amdgcn_mfma_f32_16x16x32_bf16(Bt[n][k], At[m][k], acc[ai][bj][m][n], 0, 0, 0); __builtin_amdgcn_s_setprio(0); } while (0)
; #define PG8_WAIT_V(n) asm volatile("s_waitcnt vmcnt(" #n ")" ::: "memory")
; #define PG8_WAIT_L(n) asm volatile("s_waitcnt lgkmcnt(" #n ")" ::: "memory")
; #define PG8_BAR __builtin_amdgcn_s_barrier()
; #define PG8_SCHED __builtin_amdgcn_sched_barrier(0)
; template <class Epi>
; __device__ __forceinline__ void gemm_phase(LAS unsigned char* lds, const Gemm g, const StaticOrder& S, const Epi& E) {
;     ...
;             PG8_WAIT_V(8); PG8_WAIT_L(0); PG8_BAR; PG8_MMA(1, 0, At, B0); PG8_MMA(1, 1, At, B1); PG8_BAR; PG8_SCHED;
;             PG8_LDB(B0, 1, 0); PG8_LDB(B1, 1, 1); PG8_SCHED; PG8_LDA(At, 1, 0); PG8_STAGE(PG8_SA(0, 1), a2 + hstepA, voffA);
;             PG8_WAIT_V(8); PG8_WAIT_L(0); PG8_BAR; PG8_MMA(0, 0, At, B0); PG8_MMA(0, 1, At, B1); PG8_BAR; PG8_SCHED;
	s_setprio 1
	s_waitcnt lgkmcnt(0)
	v_mfma_f32_16x16x32_bf16 v[60:63], v[128:131], v[186:189], v[60:63]
	v_mfma_f32_16x16x32_bf16 v[56:59], v[136:139], v[186:189], v[56:59]
	v_mfma_f32_16x16x32_bf16 v[44:47], v[128:131], v[194:197], v[44:47]
	v_mfma_f32_16x16x32_bf16 v[40:43], v[136:139], v[194:197], v[40:43]
	v_mfma_f32_16x16x32_bf16 v[28:31], v[128:131], v[202:205], v[28:31]
	v_mfma_f32_16x16x32_bf16 v[24:27], v[136:139], v[202:205], v[24:27]
	v_mfma_f32_16x16x32_bf16 v[12:15], v[128:131], v[210:213], v[12:15]
	v_mfma_f32_16x16x32_bf16 v[8:11], v[136:139], v[210:213], v[8:11]
	v_mfma_f32_16x16x32_bf16 v[60:63], v[132:135], v[190:193], v[60:63]
	v_mfma_f32_16x16x32_bf16 v[56:59], v[140:143], v[190:193], v[56:59]
	v_mfma_f32_16x16x32_bf16 v[44:47], v[132:135], v[198:201], v[44:47]
	v_mfma_f32_16x16x32_bf16 v[40:43], v[140:143], v[198:201], v[40:43]
	v_mfma_f32_16x16x32_bf16 v[28:31], v[132:135], v[206:209], v[28:31]
	v_mfma_f32_16x16x32_bf16 v[24:27], v[140:143], v[206:209], v[24:27]
	v_mfma_f32_16x16x32_bf16 v[12:15], v[132:135], v[214:217], v[12:15]
	v_mfma_f32_16x16x32_bf16 v[8:11], v[140:143], v[214:217], v[8:11]
	s_setprio 0
	s_setprio 1
	v_mfma_f32_16x16x32_bf16 v[52:55], v[160:163], v[186:189], v[52:55]
	v_mfma_f32_16x16x32_bf16 v[48:51], v[178:181], v[186:189], v[48:51]
	v_mfma_f32_16x16x32_bf16 v[36:39], v[160:163], v[194:197], v[36:39]
	v_mfma_f32_16x16x32_bf16 v[32:35], v[178:181], v[194:197], v[32:35]
	v_mfma_f32_16x16x32_bf16 v[20:23], v[160:163], v[202:205], v[20:23]
	v_mfma_f32_16x16x32_bf16 v[16:19], v[178:181], v[202:205], v[16:19]
	v_mfma_f32_16x16x32_bf16 v[4:7], v[160:163], v[210:213], v[4:7]
	v_mfma_f32_16x16x32_bf16 v[0:3], v[178:181], v[210:213], v[0:3]
	v_mfma_f32_16x16x32_bf16 v[52:55], v[164:167], v[190:193], v[52:55]
	v_mfma_f32_16x16x32_bf16 v[48:51], v[182:185], v[190:193], v[48:51]
	v_mfma_f32_16x16x32_bf16 v[36:39], v[164:167], v[198:201], v[36:39]
	v_mfma_f32_16x16x32_bf16 v[32:35], v[182:185], v[198:201], v[32:35]
	v_mfma_f32_16x16x32_bf16 v[20:23], v[164:167], v[206:209], v[20:23]
	v_mfma_f32_16x16x32_bf16 v[16:19], v[182:185], v[206:209], v[16:19]
	v_mfma_f32_16x16x32_bf16 v[4:7], v[164:167], v[214:217], v[4:7]
	v_mfma_f32_16x16x32_bf16 v[0:3], v[182:185], v[214:217], v[0:3]
	s_setprio 0
	s_barrier
	s_add_i32 s78, 0, 0x18000
	s_add_i32 s79, 0, 0x1c000
	v_add_u32_e32 v140, s78, v172
	v_add_u32_e32 v182, s79, v172
	ds_read_b128 v[128:131], v140
	ds_read_b128 v[132:135], v140 offset:1024
	ds_read_b128 v[136:139], v140 offset:2048
	ds_read_b128 v[140:143], v140 offset:3072
	ds_read_b128 v[160:163], v182
	ds_read_b128 v[164:167], v182 offset:1024
	ds_read_b128 v[178:181], v182 offset:2048
	ds_read_b128 v[182:185], v182 offset:3072
	s_add_u32 s52, s52, 0x40000
	s_addc_u32 s53, s53, 0
	s_mov_b32 m0, s56
	v_lshl_add_u64 v[226:227], s[52:53], 0, v[144:145]
	ds_read_b128 v[186:189], v175 offset:32768
	ds_read_b128 v[190:193], v175 offset:33792
	ds_read_b128 v[194:197], v175 offset:34816
	ds_read_b128 v[198:201], v175 offset:35840
	ds_read_b128 v[202:205], v175 offset:36864
	ds_read_b128 v[206:209], v175 offset:37888
	ds_read_b128 v[210:213], v175 offset:38912
	ds_read_b128 v[214:217], v175 offset:39936
	global_load_lds_dwordx4 v[226:227], off
	v_lshl_add_u64 v[226:227], s[52:53], 0, v[148:149]
	s_mov_b32 m0, s57
	s_nop 0
	global_load_lds_dwordx4 v[226:227], off
	s_waitcnt vmcnt(8)
	s_waitcnt lgkmcnt(0)
	s_barrier
	s_setprio 1
	s_waitcnt lgkmcnt(0)
	v_mfma_f32_16x16x32_bf16 v[124:127], v[128:131], v[186:189], v[124:127]
	v_mfma_f32_16x16x32_bf16 v[120:123], v[136:139], v[186:189], v[120:123]
	v_mfma_f32_16x16x32_bf16 v[108:111], v[128:131], v[194:197], v[108:111]
	v_mfma_f32_16x16x32_bf16 v[104:107], v[136:139], v[194:197], v[104:107]
	v_mfma_f32_16x16x32_bf16 v[92:95], v[128:131], v[202:205], v[92:95]
	v_mfma_f32_16x16x32_bf16 v[88:91], v[136:139], v[202:205], v[88:91]
	v_mfma_f32_16x16x32_bf16 v[76:79], v[128:131], v[210:213], v[76:79]
	v_mfma_f32_16x16x32_bf16 v[72:75], v[136:139], v[210:213], v[72:75]
	v_mfma_f32_16x16x32_bf16 v[124:127], v[132:135], v[190:193], v[124:127]
	v_mfma_f32_16x16x32_bf16 v[120:123], v[140:143], v[190:193], v[120:123]
	v_mfma_f32_16x16x32_bf16 v[108:111], v[132:135], v[198:201], v[108:111]
	v_mfma_f32_16x16x32_bf16 v[104:107], v[140:143], v[198:201], v[104:107]
	v_mfma_f32_16x16x32_bf16 v[92:95], v[132:135], v[206:209], v[92:95]
	v_mfma_f32_16x16x32_bf16 v[88:91], v[140:143], v[206:209], v[88:91]
	v_mfma_f32_16x16x32_bf16 v[76:79], v[132:135], v[214:217], v[76:79]
	v_mfma_f32_16x16x32_bf16 v[72:75], v[140:143], v[214:217], v[72:75]
	s_setprio 0
	s_setprio 1
	v_mfma_f32_16x16x32_bf16 v[116:119], v[160:163], v[186:189], v[116:119]
	v_mfma_f32_16x16x32_bf16 v[112:115], v[178:181], v[186:189], v[112:115]
	v_mfma_f32_16x16x32_bf16 v[100:103], v[160:163], v[194:197], v[100:103]
	v_mfma_f32_16x16x32_bf16 v[96:99], v[178:181], v[194:197], v[96:99]
	v_mfma_f32_16x16x32_bf16 v[84:87], v[160:163], v[202:205], v[84:87]
	v_mfma_f32_16x16x32_bf16 v[80:83], v[178:181], v[202:205], v[80:83]
	v_mfma_f32_16x16x32_bf16 v[68:71], v[160:163], v[210:213], v[68:71]
	v_mfma_f32_16x16x32_bf16 v[64:67], v[178:181], v[210:213], v[64:67]
	v_mfma_f32_16x16x32_bf16 v[116:119], v[164:167], v[190:193], v[116:119]
	v_mfma_f32_16x16x32_bf16 v[112:115], v[182:185], v[190:193], v[112:115]
	v_mfma_f32_16x16x32_bf16 v[100:103], v[164:167], v[198:201], v[100:103]
	v_mfma_f32_16x16x32_bf16 v[96:99], v[182:185], v[198:201], v[96:99]
	v_mfma_f32_16x16x32_bf16 v[84:87], v[164:167], v[206:209], v[84:87]
	v_mfma_f32_16x16x32_bf16 v[80:83], v[182:185], v[206:209], v[80:83]
	v_mfma_f32_16x16x32_bf16 v[68:71], v[164:167], v[214:217], v[68:71]
	v_mfma_f32_16x16x32_bf16 v[64:67], v[182:185], v[214:217], v[64:67]
	s_setprio 0
	s_barrier
; #define PG8_STAGE(bufoff, gbase, voff) do { _Pragma("unroll") for (int _i = 0; _i < 2; ++_i) \
;         __builtin_amdgcn_global_load_lds((const unsigned*)((const char*)(gbase) + (voff)[_i]), (LAS unsigned*)(lds + (bufoff) + ldsw + _i * 8192), 16, 0, 0); } while (0)
; #define PG8_LDA(dst, b, h) do { _Pragma("unroll") for (int m = 0; m < 4; ++m) _Pragma("unroll") for (int k = 0; k < 2; ++k) dst[m][k] = *(const LAS bf16x8*)(lds + PG8_SA(b, h) + aoff + m * 2048 + k * 1024); } while (0)
; #define PG8_MMA(ai, bj, At, Bt) do { __builtin_amdgcn_s_setprio(1); _Pragma("unroll") for (int m = 0; m < 4; ++m) _Pragma("unroll") for (int n = 0; n < 2; ++n) _Pragma("unroll") for (int k = 0; k < 2; ++k) \
;         acc[ai][bj][m][n] = __builtin_amdgcn_mfma_f32_16x16x32_bf16(Bt[n][k], At[m][k], acc[ai][bj][m][n], 0, 0, 0); __builtin_amdgcn_s_setprio(0); } while (0)
; #define PG8_WAIT_V(n) asm volatile("s_waitcnt vmcnt(" #n ")" ::: "memory")
; #define PG8_WAIT_L(n) asm volatile("s_waitcnt lgkmcnt(" #n ")" ::: "memory")
; #define PG8_BAR __builtin_amdgcn_s_barrier()
; #define PG8_SCHED __builtin_amdgcn_sched_barrier(0)
; template <class Epi>
; __device__ __forceinline__ void gemm_phase(LAS unsigned char* lds, const Gemm g, const StaticOrder& S, const Epi& E) {
;     ...
;             PG8_LDA(At, 1, 1); PG8_STAGE(PG8_SB(1, 0), b3, voffB); PG8_STAGE(PG8_SB(1, 1), b3 + hstepB, voffB); PG8_STAGE(PG8_SA(1, 0), a3, voffA);
;             PG8_WAIT_V(8); PG8_WAIT_L(0); PG8_BAR; PG8_MMA(1, 0, At, B0); PG8_MMA(1, 1, At, B1); PG8_BAR; PG8_SCHED;
;         }
;         if (wr == 0) PG8_BAR;
;         E(acc, cur, wr, wc, fr, fq);
;         if (!has_next) break;
;     __device__ __forceinline__ void operator()(AccRef acc, const Unit& u, int wr, int wc, int fr, int fq) const {
;     ...
;         f32x4 xc[2][2], xn[2][2];
; #pragma unroll
;         for (int bj = 0; bj < 2; ++bj) { const size_t p = (size_t)EPI_IT_ROW(0) * DM + EPI_COL(bj); xc[bj][0] = *(const f32x4*)(xin + p); xc[bj][1] = *(const f32x4*)(xin + p + 4); }
; #pragma unroll
;         for (int it = 0; it < 8; ++it) { const int ai = it >> 2, m = it & 3, row = EPI_IT_ROW(it);
;             if (it + 1 < 8) {
; #pragma unroll
;                 for (int bj = 0; bj < 2; ++bj) { const size_t p = (size_t)EPI_IT_ROW(it + 1) * DM + EPI_COL(bj); xn[bj][0] = *(const f32x4*)(xin + p); xn[bj][1] = *(const f32x4*)(xin + p + 4); } }
	s_add_i32 s52, s78, s54
	v_lshl_add_u64 v[168:169], v[168:169], 0, s[12:13]
	s_mov_b32 m0, s52
	ds_read_b128 v[186:189], v175 offset:49152
	ds_read_b128 v[190:193], v175 offset:50176
	ds_read_b128 v[194:197], v175 offset:51200
	ds_read_b128 v[198:201], v175 offset:52224
	ds_read_b128 v[202:205], v175 offset:53248
	ds_read_b128 v[206:209], v175 offset:54272
	ds_read_b128 v[210:213], v175 offset:55296
	ds_read_b128 v[214:217], v175 offset:56320
	global_load_lds_dwordx4 v[168:169], off
	s_add_i32 m0, s52, 0x2000
	s_add_u32 s42, s42, 0x40080
	v_lshl_add_u64 v[168:169], v[218:219], 0, s[12:13]
	s_addc_u32 s43, s43, 0
	s_add_i32 s52, s79, s54
	global_load_lds_dwordx4 v[168:169], off
	v_lshl_add_u64 v[168:169], s[42:43], 0, v[146:147]
	s_mov_b32 m0, s52
	s_nop 0
	global_load_lds_dwordx4 v[168:169], off
	v_lshl_add_u64 v[168:169], s[42:43], 0, v[150:151]
	s_add_i32 m0, s52, 0x2000
	s_nop 0
	global_load_lds_dwordx4 v[168:169], off
	v_lshl_add_u64 v[168:169], v[220:221], 0, s[12:13]
	s_mov_b32 m0, s65
	s_nop 0
	global_load_lds_dwordx4 v[168:169], off
	v_lshl_add_u64 v[168:169], v[222:223], 0, s[12:13]
	s_mov_b32 m0, s68
	s_nop 0
	global_load_lds_dwordx4 v[168:169], off
	s_waitcnt vmcnt(8)
	s_waitcnt lgkmcnt(0)
	s_barrier
	s_setprio 1
	s_waitcnt lgkmcnt(0)
	v_mfma_f32_16x16x32_bf16 v[60:63], v[128:131], v[186:189], v[60:63]
	v_mfma_f32_16x16x32_bf16 v[56:59], v[136:139], v[186:189], v[56:59]
	v_mfma_f32_16x16x32_bf16 v[44:47], v[128:131], v[194:197], v[44:47]
	v_mfma_f32_16x16x32_bf16 v[40:43], v[136:139], v[194:197], v[40:43]
	v_mfma_f32_16x16x32_bf16 v[28:31], v[128:131], v[202:205], v[28:31]
	v_mfma_f32_16x16x32_bf16 v[24:27], v[136:139], v[202:205], v[24:27]
	v_mfma_f32_16x16x32_bf16 v[12:15], v[128:131], v[210:213], v[12:15]
	v_mfma_f32_16x16x32_bf16 v[8:11], v[136:139], v[210:213], v[8:11]
	v_mfma_f32_16x16x32_bf16 v[60:63], v[132:135], v[190:193], v[60:63]
	v_mfma_f32_16x16x32_bf16 v[56:59], v[140:143], v[190:193], v[56:59]
	v_mfma_f32_16x16x32_bf16 v[44:47], v[132:135], v[198:201], v[44:47]
	v_mfma_f32_16x16x32_bf16 v[40:43], v[140:143], v[198:201], v[40:43]
	v_mfma_f32_16x16x32_bf16 v[28:31], v[132:135], v[206:209], v[28:31]
	v_mfma_f32_16x16x32_bf16 v[24:27], v[140:143], v[206:209], v[24:27]
	v_mfma_f32_16x16x32_bf16 v[12:15], v[132:135], v[214:217], v[12:15]
	v_mfma_f32_16x16x32_bf16 v[8:11], v[140:143], v[214:217], v[8:11]
	s_setprio 0
	s_setprio 1
	v_mfma_f32_16x16x32_bf16 v[52:55], v[160:163], v[186:189], v[52:55]
	v_mfma_f32_16x16x32_bf16 v[48:51], v[178:181], v[186:189], v[48:51]
	v_mfma_f32_16x16x32_bf16 v[36:39], v[160:163], v[194:197], v[36:39]
	v_mfma_f32_16x16x32_bf16 v[32:35], v[178:181], v[194:197], v[32:35]
	v_mfma_f32_16x16x32_bf16 v[20:23], v[160:163], v[202:205], v[20:23]
	v_mfma_f32_16x16x32_bf16 v[16:19], v[178:181], v[202:205], v[16:19]
	v_mfma_f32_16x16x32_bf16 v[4:7], v[160:163], v[210:213], v[4:7]
	v_mfma_f32_16x16x32_bf16 v[0:3], v[178:181], v[210:213], v[0:3]
	v_mfma_f32_16x16x32_bf16 v[52:55], v[164:167], v[190:193], v[52:55]
	v_mfma_f32_16x16x32_bf16 v[48:51], v[182:185], v[190:193], v[48:51]
	v_mfma_f32_16x16x32_bf16 v[36:39], v[164:167], v[198:201], v[36:39]
	v_mfma_f32_16x16x32_bf16 v[32:35], v[182:185], v[198:201], v[32:35]
	v_mfma_f32_16x16x32_bf16 v[20:23], v[164:167], v[206:209], v[20:23]
	v_mfma_f32_16x16x32_bf16 v[16:19], v[182:185], v[206:209], v[16:19]
	v_mfma_f32_16x16x32_bf16 v[4:7], v[164:167], v[214:217], v[4:7]
	v_mfma_f32_16x16x32_bf16 v[0:3], v[182:185], v[214:217], v[0:3]
	s_setprio 0
	s_barrier
	s_add_i32 s77, s77, 2
	s_add_u32 s38, s38, 0x100
	s_addc_u32 s39, s39, 0
	s_add_u32 s75, s75, 0x100
	s_addc_u32 s76, s76, 0
	s_cmp_gt_u32 s77, 13
	s_cbranch_scc0 .LBB0_457
	s_cmp_eq_u64 s[4:5], 0
	s_cselect_b32 s99, 1, 0
	s_and_b64 vcc, exec, s[14:15]
	s_cbranch_vccz .LBB0_460
	s_barrier
.LBB0_460:
	s_lshl_b32 s1, s34, 8
	v_mov_b32_e32 v128, v171
	v_mov_b32_e32 v168, v170
	s_add_i32 s1, s1, s63
	s_lshl_b32 s0, s0, 8
	s_or_b32 s0, s0, s64
	v_add_u32_e32 v164, s1, v128
	v_ashrrev_i32_e32 v165, 31, v164
	v_lshl_add_u32 v162, v168, 3, s0
	v_lshlrev_b64 v[128:129], 12, v[164:165]
	v_ashrrev_i32_e32 v163, 31, v162
	v_lshl_add_u64 v[128:129], s[16:17], 0, v[128:129]
	v_lshlrev_b64 v[130:131], 2, v[162:163]
	v_add_u32_e32 v160, 0x80, v162
	v_lshl_add_u64 v[132:133], v[128:129], 0, v[130:131]
	v_ashrrev_i32_e32 v161, 31, v160
	global_load_dwordx4 v[180:183], v[132:133], off offset:16
	global_load_dwordx4 v[184:187], v[132:133], off
	v_lshlrev_b64 v[132:133], 2, v[160:161]
	v_lshl_add_u64 v[128:129], v[128:129], 0, v[132:133]
	global_load_dwordx4 v[188:191], v[128:129], off
	global_load_dwordx4 v[192:195], v[128:129], off offset:16
	v_add_u32_e32 v166, 16, v164
	v_ashrrev_i32_e32 v167, 31, v166
	v_lshlrev_b64 v[128:129], 12, v[166:167]
	v_lshl_add_u64 v[128:129], s[16:17], 0, v[128:129]
	v_lshl_add_u64 v[130:131], v[128:129], 0, v[130:131]
	v_lshl_add_u64 v[132:133], v[128:129], 0, v[132:133]
	global_load_dwordx4 v[136:139], v[130:131], off offset:16
	global_load_dwordx4 v[140:143], v[130:131], off
	s_nop 0
	global_load_dwordx4 v[128:131], v[132:133], off offset:16
	s_nop 0
	global_load_dwordx4 v[132:135], v[132:133], off
	v_and_b32_e32 v178, 64, v177
	v_xor_b32_e32 v169, 16, v177
	v_add_u32_e32 v178, 64, v178
	v_cmp_lt_i32_e64 s[0:1], v169, v178
	v_xor_b32_e32 v179, 32, v177
	v_cmp_eq_u32_e32 vcc, 0, v168
	v_cndmask_b32_e64 v168, v177, v169, s[0:1]
	v_cmp_lt_i32_e64 s[0:1], v179, v178
	v_lshlrev_b32_e32 v178, 2, v168
	v_lshlrev_b64 v[168:169], 10, v[164:165]
	v_lshl_add_u64 v[196:197], v[168:169], 0, v[162:163]
	v_lshl_add_u64 v[198:199], v[196:197], 2, s[48:49]
	v_cndmask_b32_e64 v179, v177, v179, s[0:1]
	v_lshl_add_u64 v[168:169], v[168:169], 0, v[160:161]
	v_lshl_add_u64 v[196:197], v[196:197], 1, s[24:25]
	v_lshl_add_u64 v[200:201], v[168:169], 2, s[48:49]
	v_lshlrev_b32_e32 v179, 2, v179
	s_waitcnt vmcnt(0)
; #define EPI_IT_ROW(it) EPI_ROW((it) >> 2, (it) & 3)
; #define EPI_PACK8(v0, v1) (u32x4){pk2((v0)[0], (v0)[1]), pk2((v0)[2], (v0)[3]), pk2((v1)[0], (v1)[1]), pk2((v1)[2], (v1)[3])}
;     __device__ __forceinline__ void operator()(AccRef acc, const Unit& u, int wr, int wc, int fr, int fq) const {
;     ...
;         for (int it = 0; it < 8; ++it) { const int ai = it >> 2, m = it & 3, row = EPI_IT_ROW(it);
;             if (it + 1 < 8) {
; #pragma unroll
;                 for (int bj = 0; bj < 2; ++bj) { const size_t p = (size_t)EPI_IT_ROW(it + 1) * DM + EPI_COL(bj); xn[bj][0] = *(const f32x4*)(xin + p); xn[bj][1] = *(const f32x4*)(xin + p + 4); } }
;             float q = 0.f;
; #pragma unroll
;             for (int bj = 0; bj < 2; ++bj) { const size_t p = (size_t)row * DM + EPI_COL(bj);
;                 const f32x4 x0 = xc[bj][0] + acc[ai][bj][m][0], x1 = xc[bj][1] + acc[ai][bj][m][1];
;                 __builtin_nontemporal_store(x0, (f32x4*)(xout + p)); __builtin_nontemporal_store(x1, (f32x4*)(xout + p + 4));
;                 *(u32x4*)(xb + p) = EPI_PACK8(x0, x1);
;                 q += EPI_SQ8(x0, x1); }
;             q += __shfl_xor(q, 16); q += __shfl_xor(q, 32);
;             if (fq == 0) atomicAdd(ssout + row, q);
; #pragma unroll
;             for (int bj = 0; bj < 2; ++bj) { xc[bj][0] = xn[bj][0]; xc[bj][1] = xn[bj][1]; } }
	v_pk_add_f32 v[122:123], v[122:123], v[182:183]
	v_pk_add_f32 v[126:127], v[126:127], v[186:187]
	v_pk_add_f32 v[124:125], v[124:125], v[184:185]
	v_pk_add_f32 v[118:119], v[118:119], v[190:191]
	v_pk_add_f32 v[116:117], v[116:117], v[188:189]
	v_pk_add_f32 v[120:121], v[120:121], v[180:181]
	v_pk_add_f32 v[180:181], v[112:113], v[192:193]
	global_store_dwordx4 v[198:199], v[124:127], off nt
	global_store_dwordx4 v[198:199], v[120:123], off offset:16 nt
	v_cvt_pk_bf16_f32 v112, v124, v125
	v_cvt_pk_bf16_f32 v113, v126, v127
	v_mul_f32_e32 v185, v117, v117
	v_mul_f32_e32 v125, v125, v125
	v_mul_f32_e32 v127, v127, v127
	v_mul_f32_e32 v186, v119, v119
	v_pk_add_f32 v[182:183], v[114:115], v[194:195]
	v_cvt_pk_bf16_f32 v114, v120, v121
	v_cvt_pk_bf16_f32 v115, v122, v123
	v_mul_f32_e32 v121, v121, v121
	v_mul_f32_e32 v123, v123, v123
	v_mul_f32_e32 v187, v181, v181
	v_fmac_f32_e32 v125, v124, v124
	v_fmac_f32_e32 v127, v126, v126
	v_fmac_f32_e32 v185, v116, v116
	v_fmac_f32_e32 v186, v118, v118
	v_mul_f32_e32 v188, v183, v183
	v_fmac_f32_e32 v121, v120, v120
	v_fmac_f32_e32 v123, v122, v122
	v_fmac_f32_e32 v187, v180, v180
	v_add_f32_e32 v120, v125, v127
	v_add_f32_e32 v122, v185, v186
	v_fmac_f32_e32 v188, v182, v182
	v_add_f32_e32 v120, v120, v121
	v_add_f32_e32 v121, v122, v187
	v_add_f32_e32 v120, v123, v120
	v_add_f32_e32 v121, v188, v121
	v_add_f32_e32 v120, v120, v121
	ds_bpermute_b32 v121, v178, v120
	s_cmp_lg_u32 s99, 0
	s_cbranch_scc1 .Lwt457_10489
	global_store_dwordx4 v[196:197], v[112:115], off
	s_branch .Lwj457_10489
.Lwt457_10489:
	global_store_dwordx4 v[196:197], v[112:115], off sc1
.Lwj457_10489:
	global_store_dwordx4 v[200:201], v[116:119], off nt
	global_store_dwordx4 v[200:201], v[180:183], off offset:16 nt
	v_lshl_add_u64 v[114:115], v[168:169], 1, s[24:25]
	v_cvt_pk_bf16_f32 v184, v116, v117
	v_cvt_pk_bf16_f32 v185, v118, v119
	s_waitcnt lgkmcnt(0)
	v_add_f32_e32 v112, v120, v121
	ds_bpermute_b32 v113, v179, v112
	v_cvt_pk_bf16_f32 v186, v180, v181
	v_cvt_pk_bf16_f32 v187, v182, v183
	s_cmp_lg_u32 s99, 0
	s_cbranch_scc1 .Lwt457_10508
	global_store_dwordx4 v[114:115], v[184:187], off
	s_branch .Lwj457_10508
.Lwt457_10508:
	global_store_dwordx4 v[114:115], v[184:187], off sc1
.Lwj457_10508:
	s_and_saveexec_b64 s[0:1], vcc
	s_cbranch_execz .LBB0_462
	v_lshl_add_u64 v[114:115], v[164:165], 2, s[10:11]
	s_waitcnt lgkmcnt(0)
	v_add_f32_e32 v112, v112, v113
	global_atomic_add_f32 v[114:115], v112, off
.LBB0_462:
	s_or_b64 exec, exec, s[0:1]
	v_add_u32_e32 v168, 32, v164
	v_ashrrev_i32_e32 v169, 31, v168
	s_waitcnt lgkmcnt(0)
	v_lshlrev_b64 v[112:113], 12, v[168:169]
	v_lshl_add_u64 v[112:113], s[16:17], 0, v[112:113]
	v_lshl_add_u64 v[114:115], v[162:163], 2, v[112:113]
	v_lshl_add_u64 v[116:117], v[160:161], 2, v[112:113]
	global_load_dwordx4 v[120:123], v[114:115], off offset:16
	global_load_dwordx4 v[124:127], v[114:115], off
	s_nop 0
	global_load_dwordx4 v[112:115], v[116:117], off offset:16
	s_nop 0
	global_load_dwordx4 v[116:119], v[116:117], off
	v_lshlrev_b64 v[180:181], 10, v[166:167]
	v_lshl_add_u64 v[182:183], v[180:181], 0, v[162:163]
	v_pk_add_f32 v[110:111], v[110:111], v[142:143]
	v_pk_add_f32 v[108:109], v[108:109], v[140:141]
	v_pk_add_f32 v[104:105], v[104:105], v[136:137]
	v_lshl_add_u64 v[136:137], v[182:183], 2, s[48:49]
	v_pk_add_f32 v[106:107], v[106:107], v[138:139]
	global_store_dwordx4 v[136:137], v[108:111], off nt
	global_store_dwordx4 v[136:137], v[104:107], off offset:16 nt
	v_cvt_pk_bf16_f32 v136, v108, v109
	v_cvt_pk_bf16_f32 v138, v104, v105
	v_pk_add_f32 v[102:103], v[102:103], v[134:135]
	v_mul_f32_e32 v109, v109, v109
	v_fmac_f32_e32 v109, v108, v108
	v_mul_f32_e32 v108, v111, v111
	v_fmac_f32_e32 v108, v110, v110
	v_mul_f32_e32 v105, v105, v105
	v_add_f32_e32 v108, v109, v108
	v_fmac_f32_e32 v105, v104, v104
	v_add_f32_e32 v104, v108, v105
	v_mul_f32_e32 v105, v107, v107
	v_pk_add_f32 v[100:101], v[100:101], v[132:133]
	v_cvt_pk_bf16_f32 v139, v106, v107
	v_fmac_f32_e32 v105, v106, v106
	v_pk_add_f32 v[106:107], v[98:99], v[130:131]
	v_mul_f32_e32 v98, v101, v101
	v_mul_f32_e32 v99, v103, v103
	v_cvt_pk_bf16_f32 v137, v110, v111
	v_add_f32_e32 v110, v105, v104
	v_pk_add_f32 v[104:105], v[96:97], v[128:129]
	v_fmac_f32_e32 v98, v100, v100
	v_fmac_f32_e32 v99, v102, v102
	v_add_f32_e32 v98, v98, v99
	v_mul_f32_e32 v99, v105, v105
	v_fmac_f32_e32 v99, v104, v104
	v_add_f32_e32 v98, v98, v99
	v_mul_f32_e32 v99, v107, v107
	v_fmac_f32_e32 v99, v106, v106
	v_add_f32_e32 v98, v99, v98
	v_add_f32_e32 v110, v110, v98
	ds_bpermute_b32 v111, v178, v110
	v_lshl_add_u64 v[108:109], v[180:181], 0, v[160:161]
	v_lshl_add_u64 v[140:141], v[182:183], 1, s[24:25]
	v_lshl_add_u64 v[96:97], v[108:109], 2, s[48:49]
	s_cmp_lg_u32 s99, 0
	s_cbranch_scc1 .Lwt457_10583
	global_store_dwordx4 v[140:141], v[136:139], off
	s_branch .Lwj457_10583
.Lwt457_10583:
	global_store_dwordx4 v[140:141], v[136:139], off sc1
.Lwj457_10583:
	global_store_dwordx4 v[96:97], v[100:103], off nt
	global_store_dwordx4 v[96:97], v[104:107], off offset:16 nt
	s_waitcnt lgkmcnt(0)
	v_add_f32_e32 v96, v110, v111
	ds_bpermute_b32 v97, v179, v96
	v_cvt_pk_bf16_f32 v99, v102, v103
	v_lshl_add_u64 v[102:103], v[108:109], 1, s[24:25]
	v_cvt_pk_bf16_f32 v98, v100, v101
	v_cvt_pk_bf16_f32 v100, v104, v105
	v_cvt_pk_bf16_f32 v101, v106, v107
	s_cmp_lg_u32 s99, 0
	s_cbranch_scc1 .Lwt457_10602
	global_store_dwordx4 v[102:103], v[98:101], off
	s_branch .Lwj457_10602
.Lwt457_10602:
	global_store_dwordx4 v[102:103], v[98:101], off sc1
.Lwj457_10602:
	s_and_saveexec_b64 s[0:1], vcc
	s_cbranch_execz .LBB0_464
	v_lshl_add_u64 v[98:99], v[166:167], 2, s[10:11]
	s_waitcnt lgkmcnt(0)
	v_add_f32_e32 v96, v96, v97
	global_atomic_add_f32 v[98:99], v96, off
; #define EPI_IT_ROW(it) EPI_ROW((it) >> 2, (it) & 3)
; #define EPI_PACK8(v0, v1) (u32x4){pk2((v0)[0], (v0)[1]), pk2((v0)[2], (v0)[3]), pk2((v1)[0], (v1)[1]), pk2((v1)[2], (v1)[3])}
;     __device__ __forceinline__ void operator()(AccRef acc, const Unit& u, int wr, int wc, int fr, int fq) const {
;     ...
;         for (int it = 0; it < 8; ++it) { const int ai = it >> 2, m = it & 3, row = EPI_IT_ROW(it);
;             if (it + 1 < 8) {
; #pragma unroll
;                 for (int bj = 0; bj < 2; ++bj) { const size_t p = (size_t)EPI_IT_ROW(it + 1) * DM + EPI_COL(bj); xn[bj][0] = *(const f32x4*)(xin + p); xn[bj][1] = *(const f32x4*)(xin + p + 4); } }
;             float q = 0.f;
; #pragma unroll
;             for (int bj = 0; bj < 2; ++bj) { const size_t p = (size_t)row * DM + EPI_COL(bj);
;                 const f32x4 x0 = xc[bj][0] + acc[ai][bj][m][0], x1 = xc[bj][1] + acc[ai][bj][m][1];
;                 __builtin_nontemporal_store(x0, (f32x4*)(xout + p)); __builtin_nontemporal_store(x1, (f32x4*)(xout + p + 4));
;                 *(u32x4*)(xb + p) = EPI_PACK8(x0, x1);
;                 q += EPI_SQ8(x0, x1); }
;             q += __shfl_xor(q, 16); q += __shfl_xor(q, 32);
;             if (fq == 0) atomicAdd(ssout + row, q);
; #pragma unroll
;             for (int bj = 0; bj < 2; ++bj) { xc[bj][0] = xn[bj][0]; xc[bj][1] = xn[bj][1]; } }
.LBB0_464:
	s_or_b64 exec, exec, s[0:1]
	v_add_u32_e32 v128, 48, v164
	v_ashrrev_i32_e32 v129, 31, v128
	s_waitcnt lgkmcnt(0)
	v_lshlrev_b64 v[96:97], 12, v[128:129]
	v_lshl_add_u64 v[96:97], s[16:17], 0, v[96:97]
	v_lshl_add_u64 v[98:99], v[162:163], 2, v[96:97]
	v_lshl_add_u64 v[100:101], v[160:161], 2, v[96:97]
	global_load_dwordx4 v[104:107], v[98:99], off offset:16
	global_load_dwordx4 v[108:111], v[98:99], off
	s_nop 0
	global_load_dwordx4 v[96:99], v[100:101], off offset:16
	s_nop 0
	global_load_dwordx4 v[100:103], v[100:101], off
	v_lshlrev_b64 v[130:131], 10, v[168:169]
	v_lshl_add_u64 v[132:133], v[130:131], 0, v[162:163]
	s_waitcnt vmcnt(12)
	v_pk_add_f32 v[94:95], v[94:95], v[126:127]
	v_pk_add_f32 v[92:93], v[92:93], v[124:125]
	v_pk_add_f32 v[88:89], v[88:89], v[120:121]
	v_lshl_add_u64 v[120:121], v[132:133], 2, s[48:49]
	v_pk_add_f32 v[90:91], v[90:91], v[122:123]
	global_store_dwordx4 v[120:121], v[92:95], off nt
	global_store_dwordx4 v[120:121], v[88:91], off offset:16 nt
	v_cvt_pk_bf16_f32 v120, v92, v93
	v_cvt_pk_bf16_f32 v122, v88, v89
	s_waitcnt vmcnt(12)
	v_pk_add_f32 v[86:87], v[86:87], v[118:119]
	v_mul_f32_e32 v93, v93, v93
	v_fmac_f32_e32 v93, v92, v92
	v_mul_f32_e32 v92, v95, v95
	v_fmac_f32_e32 v92, v94, v94
	v_mul_f32_e32 v89, v89, v89
	v_add_f32_e32 v92, v93, v92
	v_fmac_f32_e32 v89, v88, v88
	v_add_f32_e32 v88, v92, v89
	v_mul_f32_e32 v89, v91, v91
	v_pk_add_f32 v[84:85], v[84:85], v[116:117]
	v_cvt_pk_bf16_f32 v123, v90, v91
	v_fmac_f32_e32 v89, v90, v90
	v_pk_add_f32 v[90:91], v[82:83], v[114:115]
	v_mul_f32_e32 v82, v85, v85
	v_mul_f32_e32 v83, v87, v87
	v_cvt_pk_bf16_f32 v121, v94, v95
	v_add_f32_e32 v94, v89, v88
	v_pk_add_f32 v[88:89], v[80:81], v[112:113]
	v_fmac_f32_e32 v82, v84, v84
	v_fmac_f32_e32 v83, v86, v86
	v_add_f32_e32 v82, v82, v83
	v_mul_f32_e32 v83, v89, v89
	v_fmac_f32_e32 v83, v88, v88
	v_add_f32_e32 v82, v82, v83
	v_mul_f32_e32 v83, v91, v91
	v_fmac_f32_e32 v83, v90, v90
	v_add_f32_e32 v82, v83, v82
	v_add_f32_e32 v94, v94, v82
	ds_bpermute_b32 v95, v178, v94
	v_lshl_add_u64 v[92:93], v[130:131], 0, v[160:161]
	v_lshl_add_u64 v[124:125], v[132:133], 1, s[24:25]
	v_lshl_add_u64 v[80:81], v[92:93], 2, s[48:49]
	s_cmp_lg_u32 s99, 0
	s_cbranch_scc1 .Lwt457_10679
	global_store_dwordx4 v[124:125], v[120:123], off
	s_branch .Lwj457_10679
.Lwt457_10679:
	global_store_dwordx4 v[124:125], v[120:123], off sc1
.Lwj457_10679:
	global_store_dwordx4 v[80:81], v[84:87], off nt
	global_store_dwordx4 v[80:81], v[88:91], off offset:16 nt
	s_waitcnt lgkmcnt(0)
	v_add_f32_e32 v80, v94, v95
	ds_bpermute_b32 v81, v179, v80
	v_cvt_pk_bf16_f32 v83, v86, v87
	v_lshl_add_u64 v[86:87], v[92:93], 1, s[24:25]
	v_cvt_pk_bf16_f32 v82, v84, v85
	v_cvt_pk_bf16_f32 v84, v88, v89
	v_cvt_pk_bf16_f32 v85, v90, v91
	s_cmp_lg_u32 s99, 0
	s_cbranch_scc1 .Lwt457_10698
	global_store_dwordx4 v[86:87], v[82:85], off
	s_branch .Lwj457_10698
.Lwt457_10698:
	global_store_dwordx4 v[86:87], v[82:85], off sc1
.Lwj457_10698:
	s_and_saveexec_b64 s[0:1], vcc
	s_cbranch_execz .LBB0_466
	v_lshl_add_u64 v[82:83], v[168:169], 2, s[10:11]
	s_waitcnt lgkmcnt(0)
	v_add_f32_e32 v80, v80, v81
	global_atomic_add_f32 v[82:83], v80, off
.LBB0_466:
	s_or_b64 exec, exec, s[0:1]
	v_add_u32_e32 v112, 0x80, v164
	v_ashrrev_i32_e32 v113, 31, v112
	s_waitcnt lgkmcnt(0)
	v_lshlrev_b64 v[80:81], 12, v[112:113]
	v_lshl_add_u64 v[80:81], s[16:17], 0, v[80:81]
	v_lshl_add_u64 v[82:83], v[162:163], 2, v[80:81]
	v_lshl_add_u64 v[84:85], v[160:161], 2, v[80:81]
	global_load_dwordx4 v[88:91], v[82:83], off offset:16
	global_load_dwordx4 v[92:95], v[82:83], off
	s_nop 0
	global_load_dwordx4 v[80:83], v[84:85], off offset:16
	s_nop 0
	global_load_dwordx4 v[84:87], v[84:85], off
	v_lshlrev_b64 v[114:115], 10, v[128:129]
	v_lshl_add_u64 v[116:117], v[114:115], 0, v[162:163]
	s_waitcnt vmcnt(12)
	v_pk_add_f32 v[78:79], v[78:79], v[110:111]
	v_pk_add_f32 v[76:77], v[76:77], v[108:109]
	v_pk_add_f32 v[72:73], v[72:73], v[104:105]
	v_lshl_add_u64 v[104:105], v[116:117], 2, s[48:49]
	v_pk_add_f32 v[74:75], v[74:75], v[106:107]
	global_store_dwordx4 v[104:105], v[76:79], off nt
	global_store_dwordx4 v[104:105], v[72:75], off offset:16 nt
	v_cvt_pk_bf16_f32 v104, v76, v77
	v_cvt_pk_bf16_f32 v106, v72, v73
	s_waitcnt vmcnt(12)
	v_pk_add_f32 v[70:71], v[70:71], v[102:103]
	v_mul_f32_e32 v77, v77, v77
	v_fmac_f32_e32 v77, v76, v76
	v_mul_f32_e32 v76, v79, v79
	v_fmac_f32_e32 v76, v78, v78
	v_mul_f32_e32 v73, v73, v73
	v_add_f32_e32 v76, v77, v76
	v_fmac_f32_e32 v73, v72, v72
	v_add_f32_e32 v72, v76, v73
	v_mul_f32_e32 v73, v75, v75
	v_pk_add_f32 v[68:69], v[68:69], v[100:101]
	v_cvt_pk_bf16_f32 v107, v74, v75
	v_fmac_f32_e32 v73, v74, v74
	v_pk_add_f32 v[74:75], v[66:67], v[98:99]
	v_mul_f32_e32 v66, v69, v69
	v_mul_f32_e32 v67, v71, v71
	v_cvt_pk_bf16_f32 v105, v78, v79
	v_add_f32_e32 v78, v73, v72
	v_pk_add_f32 v[72:73], v[64:65], v[96:97]
	v_fmac_f32_e32 v66, v68, v68
	v_fmac_f32_e32 v67, v70, v70
	v_add_f32_e32 v66, v66, v67
	v_mul_f32_e32 v67, v73, v73
	v_fmac_f32_e32 v67, v72, v72
	v_add_f32_e32 v66, v66, v67
	v_mul_f32_e32 v67, v75, v75
	v_fmac_f32_e32 v67, v74, v74
	v_add_f32_e32 v66, v67, v66
	v_add_f32_e32 v78, v78, v66
	ds_bpermute_b32 v79, v178, v78
	v_lshl_add_u64 v[76:77], v[114:115], 0, v[160:161]
	v_lshl_add_u64 v[108:109], v[116:117], 1, s[24:25]
	v_lshl_add_u64 v[64:65], v[76:77], 2, s[48:49]
	s_cmp_lg_u32 s99, 0
	s_cbranch_scc1 .Lwt457_10775
	global_store_dwordx4 v[108:109], v[104:107], off
	s_branch .Lwj457_10775
.Lwt457_10775:
	global_store_dwordx4 v[108:109], v[104:107], off sc1
; #define EPI_IT_ROW(it) EPI_ROW((it) >> 2, (it) & 3)
; #define EPI_PACK8(v0, v1) (u32x4){pk2((v0)[0], (v0)[1]), pk2((v0)[2], (v0)[3]), pk2((v1)[0], (v1)[1]), pk2((v1)[2], (v1)[3])}
;     __device__ __forceinline__ void operator()(AccRef acc, const Unit& u, int wr, int wc, int fr, int fq) const {
;     ...
;         for (int it = 0; it < 8; ++it) { const int ai = it >> 2, m = it & 3, row = EPI_IT_ROW(it);
;             if (it + 1 < 8) {
; #pragma unroll
;                 for (int bj = 0; bj < 2; ++bj) { const size_t p = (size_t)EPI_IT_ROW(it + 1) * DM + EPI_COL(bj); xn[bj][0] = *(const f32x4*)(xin + p); xn[bj][1] = *(const f32x4*)(xin + p + 4); } }
;             float q = 0.f;
; #pragma unroll
;             for (int bj = 0; bj < 2; ++bj) { const size_t p = (size_t)row * DM + EPI_COL(bj);
;                 const f32x4 x0 = xc[bj][0] + acc[ai][bj][m][0], x1 = xc[bj][1] + acc[ai][bj][m][1];
;                 __builtin_nontemporal_store(x0, (f32x4*)(xout + p)); __builtin_nontemporal_store(x1, (f32x4*)(xout + p + 4));
;                 *(u32x4*)(xb + p) = EPI_PACK8(x0, x1);
;                 q += EPI_SQ8(x0, x1); }
;             q += __shfl_xor(q, 16); q += __shfl_xor(q, 32);
;             if (fq == 0) atomicAdd(ssout + row, q);
; #pragma unroll
;             for (int bj = 0; bj < 2; ++bj) { xc[bj][0] = xn[bj][0]; xc[bj][1] = xn[bj][1]; } }
.Lwj457_10775:
	global_store_dwordx4 v[64:65], v[68:71], off nt
	global_store_dwordx4 v[64:65], v[72:75], off offset:16 nt
	s_waitcnt lgkmcnt(0)
	v_add_f32_e32 v64, v78, v79
	ds_bpermute_b32 v65, v179, v64
	v_cvt_pk_bf16_f32 v67, v70, v71
	v_lshl_add_u64 v[70:71], v[76:77], 1, s[24:25]
	v_cvt_pk_bf16_f32 v66, v68, v69
	v_cvt_pk_bf16_f32 v68, v72, v73
	v_cvt_pk_bf16_f32 v69, v74, v75
	s_cmp_lg_u32 s99, 0
	s_cbranch_scc1 .Lwt457_10794
	global_store_dwordx4 v[70:71], v[66:69], off
	s_branch .Lwj457_10794
.Lwt457_10794:
	global_store_dwordx4 v[70:71], v[66:69], off sc1
.Lwj457_10794:
	s_and_saveexec_b64 s[0:1], vcc
	s_cbranch_execz .LBB0_468
	v_lshl_add_u64 v[66:67], v[128:129], 2, s[10:11]
	s_waitcnt lgkmcnt(0)
	v_add_f32_e32 v64, v64, v65
	global_atomic_add_f32 v[66:67], v64, off
.LBB0_468:
	s_or_b64 exec, exec, s[0:1]
	v_add_u32_e32 v96, 0x90, v164
	v_ashrrev_i32_e32 v97, 31, v96
	s_waitcnt lgkmcnt(0)
	v_lshlrev_b64 v[64:65], 12, v[96:97]
	v_lshl_add_u64 v[64:65], s[16:17], 0, v[64:65]
	v_lshl_add_u64 v[66:67], v[162:163], 2, v[64:65]
	v_lshl_add_u64 v[68:69], v[160:161], 2, v[64:65]
	global_load_dwordx4 v[72:75], v[66:67], off offset:16
	global_load_dwordx4 v[76:79], v[66:67], off
	s_nop 0
	global_load_dwordx4 v[64:67], v[68:69], off offset:16
	s_nop 0
	global_load_dwordx4 v[68:71], v[68:69], off
	v_lshlrev_b64 v[98:99], 10, v[112:113]
	v_lshl_add_u64 v[100:101], v[98:99], 0, v[162:163]
	s_waitcnt vmcnt(12)
	v_pk_add_f32 v[62:63], v[62:63], v[94:95]
	v_pk_add_f32 v[60:61], v[60:61], v[92:93]
	v_pk_add_f32 v[56:57], v[56:57], v[88:89]
	v_lshl_add_u64 v[88:89], v[100:101], 2, s[48:49]
	v_pk_add_f32 v[58:59], v[58:59], v[90:91]
	global_store_dwordx4 v[88:89], v[60:63], off nt
	global_store_dwordx4 v[88:89], v[56:59], off offset:16 nt
	v_cvt_pk_bf16_f32 v88, v60, v61
	v_cvt_pk_bf16_f32 v90, v56, v57
	s_waitcnt vmcnt(12)
	v_pk_add_f32 v[54:55], v[54:55], v[86:87]
	v_mul_f32_e32 v61, v61, v61
	v_fmac_f32_e32 v61, v60, v60
	v_mul_f32_e32 v60, v63, v63
	v_fmac_f32_e32 v60, v62, v62
	v_mul_f32_e32 v57, v57, v57
	v_add_f32_e32 v60, v61, v60
	v_fmac_f32_e32 v57, v56, v56
	v_add_f32_e32 v56, v60, v57
	v_mul_f32_e32 v57, v59, v59
	v_pk_add_f32 v[52:53], v[52:53], v[84:85]
	v_cvt_pk_bf16_f32 v91, v58, v59
	v_fmac_f32_e32 v57, v58, v58
	v_pk_add_f32 v[58:59], v[50:51], v[82:83]
	v_mul_f32_e32 v50, v53, v53
	v_mul_f32_e32 v51, v55, v55
	v_cvt_pk_bf16_f32 v89, v62, v63
	v_add_f32_e32 v62, v57, v56
	v_pk_add_f32 v[56:57], v[48:49], v[80:81]
	v_fmac_f32_e32 v50, v52, v52
	v_fmac_f32_e32 v51, v54, v54
	v_add_f32_e32 v50, v50, v51
	v_mul_f32_e32 v51, v57, v57
	v_fmac_f32_e32 v51, v56, v56
	v_add_f32_e32 v50, v50, v51
	v_mul_f32_e32 v51, v59, v59
	v_fmac_f32_e32 v51, v58, v58
	v_add_f32_e32 v50, v51, v50
	v_add_f32_e32 v62, v62, v50
	ds_bpermute_b32 v63, v178, v62
	v_lshl_add_u64 v[60:61], v[98:99], 0, v[160:161]
	v_lshl_add_u64 v[92:93], v[100:101], 1, s[24:25]
	v_lshl_add_u64 v[48:49], v[60:61], 2, s[48:49]
	s_cmp_lg_u32 s99, 0
	s_cbranch_scc1 .Lwt457_10871
	global_store_dwordx4 v[92:93], v[88:91], off
	s_branch .Lwj457_10871
.Lwt457_10871:
	global_store_dwordx4 v[92:93], v[88:91], off sc1
.Lwj457_10871:
	global_store_dwordx4 v[48:49], v[52:55], off nt
	global_store_dwordx4 v[48:49], v[56:59], off offset:16 nt
	s_waitcnt lgkmcnt(0)
	v_add_f32_e32 v48, v62, v63
	ds_bpermute_b32 v49, v179, v48
	v_cvt_pk_bf16_f32 v51, v54, v55
	v_lshl_add_u64 v[54:55], v[60:61], 1, s[24:25]
	v_cvt_pk_bf16_f32 v50, v52, v53
	v_cvt_pk_bf16_f32 v52, v56, v57
	v_cvt_pk_bf16_f32 v53, v58, v59
	s_cmp_lg_u32 s99, 0
	s_cbranch_scc1 .Lwt457_10890
	global_store_dwordx4 v[54:55], v[50:53], off
	s_branch .Lwj457_10890
.Lwt457_10890:
	global_store_dwordx4 v[54:55], v[50:53], off sc1
.Lwj457_10890:
	s_and_saveexec_b64 s[0:1], vcc
	s_cbranch_execz .LBB0_470
	v_lshl_add_u64 v[50:51], v[112:113], 2, s[10:11]
	s_waitcnt lgkmcnt(0)
	v_add_f32_e32 v48, v48, v49
	global_atomic_add_f32 v[50:51], v48, off
.LBB0_470:
	s_or_b64 exec, exec, s[0:1]
	v_add_u32_e32 v80, 0xa0, v164
	v_ashrrev_i32_e32 v81, 31, v80
	s_waitcnt lgkmcnt(0)
	v_lshlrev_b64 v[48:49], 12, v[80:81]
	v_lshl_add_u64 v[48:49], s[16:17], 0, v[48:49]
	v_lshl_add_u64 v[50:51], v[162:163], 2, v[48:49]
	v_lshl_add_u64 v[52:53], v[160:161], 2, v[48:49]
	global_load_dwordx4 v[56:59], v[50:51], off offset:16
	global_load_dwordx4 v[60:63], v[50:51], off
	s_nop 0
	global_load_dwordx4 v[48:51], v[52:53], off offset:16
	s_nop 0
	global_load_dwordx4 v[52:55], v[52:53], off
	v_lshlrev_b64 v[82:83], 10, v[96:97]
	v_lshl_add_u64 v[84:85], v[82:83], 0, v[162:163]
	s_waitcnt vmcnt(12)
	v_pk_add_f32 v[46:47], v[46:47], v[78:79]
	v_pk_add_f32 v[44:45], v[44:45], v[76:77]
	v_pk_add_f32 v[40:41], v[40:41], v[72:73]
	v_lshl_add_u64 v[72:73], v[84:85], 2, s[48:49]
	v_pk_add_f32 v[42:43], v[42:43], v[74:75]
	global_store_dwordx4 v[72:73], v[44:47], off nt
	global_store_dwordx4 v[72:73], v[40:43], off offset:16 nt
	v_cvt_pk_bf16_f32 v72, v44, v45
	v_cvt_pk_bf16_f32 v74, v40, v41
	s_waitcnt vmcnt(12)
	v_pk_add_f32 v[38:39], v[38:39], v[70:71]
	v_mul_f32_e32 v45, v45, v45
	v_fmac_f32_e32 v45, v44, v44
	v_mul_f32_e32 v44, v47, v47
	v_fmac_f32_e32 v44, v46, v46
	v_mul_f32_e32 v41, v41, v41
	v_add_f32_e32 v44, v45, v44
	v_fmac_f32_e32 v41, v40, v40
	v_add_f32_e32 v40, v44, v41
	v_mul_f32_e32 v41, v43, v43
	v_pk_add_f32 v[36:37], v[36:37], v[68:69]
	v_cvt_pk_bf16_f32 v75, v42, v43
	v_fmac_f32_e32 v41, v42, v42
	v_pk_add_f32 v[42:43], v[34:35], v[66:67]
	v_mul_f32_e32 v34, v37, v37
	v_mul_f32_e32 v35, v39, v39
	v_cvt_pk_bf16_f32 v73, v46, v47
	v_add_f32_e32 v46, v41, v40
	v_pk_add_f32 v[40:41], v[32:33], v[64:65]
	v_fmac_f32_e32 v34, v36, v36
	v_fmac_f32_e32 v35, v38, v38
	v_add_f32_e32 v34, v34, v35
	v_mul_f32_e32 v35, v41, v41
	v_fmac_f32_e32 v35, v40, v40
	v_add_f32_e32 v34, v34, v35
	v_mul_f32_e32 v35, v43, v43
	v_fmac_f32_e32 v35, v42, v42
	v_add_f32_e32 v34, v35, v34
	v_add_f32_e32 v46, v46, v34
	ds_bpermute_b32 v47, v178, v46
	v_lshl_add_u64 v[44:45], v[82:83], 0, v[160:161]
	v_lshl_add_u64 v[76:77], v[84:85], 1, s[24:25]
	v_lshl_add_u64 v[32:33], v[44:45], 2, s[48:49]
	s_cmp_lg_u32 s99, 0
	s_cbranch_scc1 .Lwt457_10967
	global_store_dwordx4 v[76:77], v[72:75], off
	s_branch .Lwj457_10967
; #define EPI_IT_ROW(it) EPI_ROW((it) >> 2, (it) & 3)
; #define EPI_PACK8(v0, v1) (u32x4){pk2((v0)[0], (v0)[1]), pk2((v0)[2], (v0)[3]), pk2((v1)[0], (v1)[1]), pk2((v1)[2], (v1)[3])}
;     __device__ __forceinline__ void operator()(AccRef acc, const Unit& u, int wr, int wc, int fr, int fq) const {
;     ...
;         for (int it = 0; it < 8; ++it) { const int ai = it >> 2, m = it & 3, row = EPI_IT_ROW(it);
;             if (it + 1 < 8) {
; #pragma unroll
;                 for (int bj = 0; bj < 2; ++bj) { const size_t p = (size_t)EPI_IT_ROW(it + 1) * DM + EPI_COL(bj); xn[bj][0] = *(const f32x4*)(xin + p); xn[bj][1] = *(const f32x4*)(xin + p + 4); } }
;             float q = 0.f;
; #pragma unroll
;             for (int bj = 0; bj < 2; ++bj) { const size_t p = (size_t)row * DM + EPI_COL(bj);
;                 const f32x4 x0 = xc[bj][0] + acc[ai][bj][m][0], x1 = xc[bj][1] + acc[ai][bj][m][1];
;                 __builtin_nontemporal_store(x0, (f32x4*)(xout + p)); __builtin_nontemporal_store(x1, (f32x4*)(xout + p + 4));
;                 *(u32x4*)(xb + p) = EPI_PACK8(x0, x1);
;                 q += EPI_SQ8(x0, x1); }
;             q += __shfl_xor(q, 16); q += __shfl_xor(q, 32);
;             if (fq == 0) atomicAdd(ssout + row, q);
; #pragma unroll
;             for (int bj = 0; bj < 2; ++bj) { xc[bj][0] = xn[bj][0]; xc[bj][1] = xn[bj][1]; } }
.Lwt457_10967:
	global_store_dwordx4 v[76:77], v[72:75], off sc1
.Lwj457_10967:
	global_store_dwordx4 v[32:33], v[36:39], off nt
	global_store_dwordx4 v[32:33], v[40:43], off offset:16 nt
	s_waitcnt lgkmcnt(0)
	v_add_f32_e32 v32, v46, v47
	ds_bpermute_b32 v33, v179, v32
	v_cvt_pk_bf16_f32 v35, v38, v39
	v_lshl_add_u64 v[38:39], v[44:45], 1, s[24:25]
	v_cvt_pk_bf16_f32 v34, v36, v37
	v_cvt_pk_bf16_f32 v36, v40, v41
	v_cvt_pk_bf16_f32 v37, v42, v43
	s_cmp_lg_u32 s99, 0
	s_cbranch_scc1 .Lwt457_10986
	global_store_dwordx4 v[38:39], v[34:37], off
	s_branch .Lwj457_10986
.Lwt457_10986:
	global_store_dwordx4 v[38:39], v[34:37], off sc1
.Lwj457_10986:
	s_and_saveexec_b64 s[0:1], vcc
	s_cbranch_execz .LBB0_472
	v_lshl_add_u64 v[34:35], v[96:97], 2, s[10:11]
	s_waitcnt lgkmcnt(0)
	v_add_f32_e32 v32, v32, v33
	global_atomic_add_f32 v[34:35], v32, off
.LBB0_472:
	s_or_b64 exec, exec, s[0:1]
	v_add_u32_e32 v64, 0xb0, v164
	v_ashrrev_i32_e32 v65, 31, v64
	s_waitcnt lgkmcnt(0)
	v_lshlrev_b64 v[32:33], 12, v[64:65]
	v_lshl_add_u64 v[32:33], s[16:17], 0, v[32:33]
	v_lshl_add_u64 v[34:35], v[162:163], 2, v[32:33]
	v_lshl_add_u64 v[36:37], v[160:161], 2, v[32:33]
	global_load_dwordx4 v[40:43], v[34:35], off offset:16
	global_load_dwordx4 v[44:47], v[34:35], off
	s_nop 0
	global_load_dwordx4 v[32:35], v[36:37], off offset:16
	s_nop 0
	global_load_dwordx4 v[36:39], v[36:37], off
	v_lshlrev_b64 v[66:67], 10, v[80:81]
	v_lshl_add_u64 v[68:69], v[66:67], 0, v[162:163]
	s_waitcnt vmcnt(12)
	v_pk_add_f32 v[30:31], v[30:31], v[62:63]
	v_pk_add_f32 v[28:29], v[28:29], v[60:61]
	v_pk_add_f32 v[24:25], v[24:25], v[56:57]
	v_lshl_add_u64 v[56:57], v[68:69], 2, s[48:49]
	v_pk_add_f32 v[26:27], v[26:27], v[58:59]
	global_store_dwordx4 v[56:57], v[28:31], off nt
	global_store_dwordx4 v[56:57], v[24:27], off offset:16 nt
	v_cvt_pk_bf16_f32 v56, v28, v29
	v_cvt_pk_bf16_f32 v58, v24, v25
	s_waitcnt vmcnt(12)
	v_pk_add_f32 v[22:23], v[22:23], v[54:55]
	v_mul_f32_e32 v29, v29, v29
	v_fmac_f32_e32 v29, v28, v28
	v_mul_f32_e32 v28, v31, v31
	v_fmac_f32_e32 v28, v30, v30
	v_mul_f32_e32 v25, v25, v25
	v_add_f32_e32 v28, v29, v28
	v_fmac_f32_e32 v25, v24, v24
	v_add_f32_e32 v24, v28, v25
	v_mul_f32_e32 v25, v27, v27
	v_pk_add_f32 v[20:21], v[20:21], v[52:53]
	v_cvt_pk_bf16_f32 v59, v26, v27
	v_fmac_f32_e32 v25, v26, v26
	v_pk_add_f32 v[26:27], v[18:19], v[50:51]
	v_mul_f32_e32 v18, v21, v21
	v_mul_f32_e32 v19, v23, v23
	v_cvt_pk_bf16_f32 v57, v30, v31
	v_add_f32_e32 v30, v25, v24
	v_pk_add_f32 v[24:25], v[16:17], v[48:49]
	v_fmac_f32_e32 v18, v20, v20
	v_fmac_f32_e32 v19, v22, v22
	v_add_f32_e32 v18, v18, v19
	v_mul_f32_e32 v19, v25, v25
	v_fmac_f32_e32 v19, v24, v24
	v_add_f32_e32 v18, v18, v19
	v_mul_f32_e32 v19, v27, v27
	v_fmac_f32_e32 v19, v26, v26
	v_add_f32_e32 v18, v19, v18
	v_add_f32_e32 v30, v30, v18
	ds_bpermute_b32 v31, v178, v30
	v_lshl_add_u64 v[28:29], v[66:67], 0, v[160:161]
	v_lshl_add_u64 v[60:61], v[68:69], 1, s[24:25]
	v_lshl_add_u64 v[16:17], v[28:29], 2, s[48:49]
	s_cmp_lg_u32 s99, 0
	s_cbranch_scc1 .Lwt457_11063
	global_store_dwordx4 v[60:61], v[56:59], off
	s_branch .Lwj457_11063
.Lwt457_11063:
	global_store_dwordx4 v[60:61], v[56:59], off sc1
.Lwj457_11063:
	global_store_dwordx4 v[16:17], v[20:23], off nt
	global_store_dwordx4 v[16:17], v[24:27], off offset:16 nt
	s_waitcnt lgkmcnt(0)
	v_add_f32_e32 v16, v30, v31
	ds_bpermute_b32 v17, v179, v16
	v_cvt_pk_bf16_f32 v19, v22, v23
	v_lshl_add_u64 v[22:23], v[28:29], 1, s[24:25]
	v_cvt_pk_bf16_f32 v18, v20, v21
	v_cvt_pk_bf16_f32 v20, v24, v25
	v_cvt_pk_bf16_f32 v21, v26, v27
	s_cmp_lg_u32 s99, 0
	s_cbranch_scc1 .Lwt457_11082
	global_store_dwordx4 v[22:23], v[18:21], off
	s_branch .Lwj457_11082
.Lwt457_11082:
	global_store_dwordx4 v[22:23], v[18:21], off sc1
.Lwj457_11082:
	s_and_saveexec_b64 s[0:1], vcc
	s_cbranch_execz .LBB0_474
	v_lshl_add_u64 v[18:19], v[80:81], 2, s[10:11]
	s_waitcnt lgkmcnt(0)
	v_add_f32_e32 v16, v16, v17
	global_atomic_add_f32 v[18:19], v16, off
.LBB0_474:
	s_or_b64 exec, exec, s[0:1]
	v_lshlrev_b64 v[20:21], 10, v[64:65]
	v_lshl_add_u64 v[22:23], v[20:21], 0, v[162:163]
	s_waitcnt vmcnt(8)
	v_pk_add_f32 v[14:15], v[14:15], v[46:47]
	v_pk_add_f32 v[12:13], v[12:13], v[44:45]
	s_waitcnt lgkmcnt(0)
	v_lshl_add_u64 v[16:17], v[22:23], 2, s[48:49]
	v_pk_add_f32 v[10:11], v[10:11], v[42:43]
	v_pk_add_f32 v[8:9], v[8:9], v[40:41]
	global_store_dwordx4 v[16:17], v[12:15], off nt
	global_store_dwordx4 v[16:17], v[8:11], off offset:16 nt
	v_cvt_pk_bf16_f32 v16, v12, v13
	v_cvt_pk_bf16_f32 v18, v8, v9
	s_waitcnt vmcnt(8)
	v_pk_add_f32 v[6:7], v[6:7], v[38:39]
	v_mul_f32_e32 v13, v13, v13
	v_fmac_f32_e32 v13, v12, v12
	v_mul_f32_e32 v12, v15, v15
	v_fmac_f32_e32 v12, v14, v14
	v_mul_f32_e32 v9, v9, v9
	v_add_f32_e32 v12, v13, v12
	v_fmac_f32_e32 v9, v8, v8
	v_add_f32_e32 v8, v12, v9
	v_mul_f32_e32 v9, v11, v11
	v_pk_add_f32 v[4:5], v[4:5], v[36:37]
	v_cvt_pk_bf16_f32 v19, v10, v11
	v_fmac_f32_e32 v9, v10, v10
	v_pk_add_f32 v[10:11], v[2:3], v[34:35]
	v_mul_f32_e32 v2, v5, v5
	v_mul_f32_e32 v3, v7, v7
	v_cvt_pk_bf16_f32 v17, v14, v15
	v_add_f32_e32 v14, v9, v8
	v_pk_add_f32 v[8:9], v[0:1], v[32:33]
	v_fmac_f32_e32 v2, v4, v4
	v_fmac_f32_e32 v3, v6, v6
	v_add_f32_e32 v2, v2, v3
	v_mul_f32_e32 v3, v9, v9
	v_fmac_f32_e32 v3, v8, v8
	v_add_f32_e32 v2, v2, v3
	v_mul_f32_e32 v3, v11, v11
	v_fmac_f32_e32 v3, v10, v10
	v_add_f32_e32 v2, v3, v2
	v_add_f32_e32 v14, v14, v2
	ds_bpermute_b32 v15, v178, v14
	v_lshl_add_u64 v[12:13], v[20:21], 0, v[160:161]
	v_lshl_add_u64 v[22:23], v[22:23], 1, s[24:25]
	v_lshl_add_u64 v[0:1], v[12:13], 2, s[48:49]
	s_cmp_lg_u32 s99, 0
	s_cbranch_scc1 .Lwt457_11147
	global_store_dwordx4 v[22:23], v[16:19], off
	s_branch .Lwj457_11147
.Lwt457_11147:
	global_store_dwordx4 v[22:23], v[16:19], off sc1
.Lwj457_11147:
	global_store_dwordx4 v[0:1], v[4:7], off nt
	global_store_dwordx4 v[0:1], v[8:11], off offset:16 nt
	s_waitcnt lgkmcnt(0)
	v_add_f32_e32 v0, v14, v15
	ds_bpermute_b32 v1, v179, v0
	v_cvt_pk_bf16_f32 v3, v6, v7
	v_lshl_add_u64 v[6:7], v[12:13], 1, s[24:25]
	v_cvt_pk_bf16_f32 v2, v4, v5
	v_cvt_pk_bf16_f32 v4, v8, v9
	v_cvt_pk_bf16_f32 v5, v10, v11
	s_cmp_lg_u32 s99, 0
	s_cbranch_scc1 .Lwt457_11166
	global_store_dwordx4 v[6:7], v[2:5], off
	s_branch .Lwj457_11166
.Lwt457_11166:
	global_store_dwordx4 v[6:7], v[2:5], off sc1
.Lwj457_11166:
	s_and_saveexec_b64 s[0:1], vcc
	s_cbranch_execz .LBB0_476
	v_lshl_add_u64 v[2:3], v[64:65], 2, s[10:11]
	s_waitcnt lgkmcnt(0)
	v_add_f32_e32 v0, v0, v1
	global_atomic_add_f32 v[2:3], v0, off

; #define PG8_STAGE(bufoff, gbase, voff) do { _Pragma("unroll") for (int _i = 0; _i < 2; ++_i) \
;         __builtin_amdgcn_global_load_lds((const unsigned*)((const char*)(gbase) + (voff)[_i]), (LAS unsigned*)(lds + (bufoff) + ldsw + _i * 8192), 16, 0, 0); } while (0)
; #define PG8_LDA(dst, b, h) do { _Pragma("unroll") for (int m = 0; m < 4; ++m) _Pragma("unroll") for (int k = 0; k < 2; ++k) dst[m][k] = *(const LAS bf16x8*)(lds + PG8_SA(b, h) + aoff + m * 2048 + k * 1024); } while (0)
; #define PG8_LDB(dst, b, h) do { _Pragma("unroll") for (int n = 0; n < 2; ++n) _Pragma("unroll") for (int k = 0; k < 2; ++k) dst[n][k] = *(const LAS bf16x8*)(lds + PG8_SB(b, h) + boff + n * 2048 + k * 1024); } while (0)
; #define PG8_MMA(ai, bj, At, Bt) do { __builtin_amdgcn_s_setprio(1); _Pragma("unroll") for (int m = 0; m < 4; ++m) _Pragma("unroll") for (int n = 0; n < 2; ++n) _Pragma("unroll") for (int k = 0; k < 2; ++k) \
;         acc[ai][bj][m][n] = __builtin_amdgcn_mfma_f32_16x16x32_bf16(Bt[n][k], At[m][k], acc[ai][bj][m][n], 0, 0, 0); __builtin_amdgcn_s_setprio(0); } while (0)
; #define PG8_WAIT_V(n) asm volatile("s_waitcnt vmcnt(" #n ")" ::: "memory")
; #define PG8_WAIT_L(n) asm volatile("s_waitcnt lgkmcnt(" #n ")" ::: "memory")
; #define PG8_BAR __builtin_amdgcn_s_barrier()
; #define PG8_SCHED __builtin_amdgcn_sched_barrier(0)
; template <class Epi>
; __device__ __forceinline__ void gemm_phase(LAS unsigned char* lds, const Gemm g, const StaticOrder& S, const Epi& E) {
;     ...
;             PG8_LDB(B0, 0, 0); PG8_LDB(B1, 0, 1); PG8_SCHED; PG8_LDA(At, 0, 0); PG8_STAGE(PG8_SA(1, 1), a1 + hstepA, voffA);
;             PG8_WAIT_V(8); PG8_WAIT_L(0); PG8_BAR; PG8_MMA(0, 0, At, B0); PG8_MMA(0, 1, At, B1); PG8_BAR; PG8_SCHED;
;             PG8_LDA(At, 0, 1); PG8_STAGE(PG8_SB(0, 0), b2, voffB); PG8_STAGE(PG8_SB(0, 1), b2 + hstepB, voffB); PG8_STAGE(PG8_SA(0, 0), a2, voffA);
;             PG8_WAIT_V(8); PG8_WAIT_L(0); PG8_BAR; PG8_MMA(1, 0, At, B0); PG8_MMA(1, 1, At, B1); PG8_BAR; PG8_SCHED;
.LBB0_546:
	ds_read_b128 v[146:149], v162
	ds_read_b128 v[166:169], v162 offset:1024
	ds_read_b128 v[170:173], v162 offset:2048
	ds_read_b128 v[178:181], v162 offset:3072
	ds_read_b128 v[182:185], v163
	ds_read_b128 v[186:189], v163 offset:1024
	ds_read_b128 v[190:193], v163 offset:2048
	ds_read_b128 v[194:197], v163 offset:3072
	s_add_u32 s10, s8, 0xfffc0080
	s_addc_u32 s11, s9, -1
	s_cmp_eq_u32 s89, 12
	s_cselect_b32 s13, s1, s11
	s_cselect_b32 s12, s7, s10
	s_cselect_b32 s11, s69, s77
	s_cselect_b32 s10, s71, s76
	v_lshl_add_u64 v[174:175], s[8:9], 0, v[138:139]
	s_add_i32 m0, s43, 0xc000
	ds_read_b128 v[198:201], v164
	ds_read_b128 v[202:205], v164 offset:1024
	ds_read_b128 v[206:209], v164 offset:2048
	ds_read_b128 v[210:213], v164 offset:3072
	ds_read_b128 v[214:217], v164 offset:4096
	ds_read_b128 v[218:221], v164 offset:5120
	ds_read_b128 v[226:229], v164 offset:6144
	ds_read_b128 v[230:233], v164 offset:7168
	global_load_lds_dwordx4 v[174:175], off
	v_lshl_add_u64 v[174:175], s[8:9], 0, v[140:141]
	s_add_i32 m0, s43, 0xe000
	s_nop 0
	global_load_lds_dwordx4 v[174:175], off
	s_waitcnt vmcnt(8)
	s_waitcnt lgkmcnt(0)
	s_barrier
	s_setprio 1
	s_waitcnt lgkmcnt(0)
	v_mfma_f32_16x16x32_bf16 v[124:127], v[146:149], v[198:201], v[124:127]
	v_mfma_f32_16x16x32_bf16 v[120:123], v[170:173], v[198:201], v[120:123]
	v_mfma_f32_16x16x32_bf16 v[112:115], v[146:149], v[206:209], v[112:115]
	v_mfma_f32_16x16x32_bf16 v[104:107], v[170:173], v[206:209], v[104:107]
	v_mfma_f32_16x16x32_bf16 v[100:103], v[146:149], v[214:217], v[100:103]
	v_mfma_f32_16x16x32_bf16 v[92:95], v[170:173], v[214:217], v[92:95]
	v_mfma_f32_16x16x32_bf16 v[84:87], v[146:149], v[226:229], v[84:87]
	v_mfma_f32_16x16x32_bf16 v[76:79], v[170:173], v[226:229], v[76:79]
	v_mfma_f32_16x16x32_bf16 v[124:127], v[166:169], v[202:205], v[124:127]
	v_mfma_f32_16x16x32_bf16 v[120:123], v[178:181], v[202:205], v[120:123]
	v_mfma_f32_16x16x32_bf16 v[112:115], v[166:169], v[210:213], v[112:115]
	v_mfma_f32_16x16x32_bf16 v[104:107], v[178:181], v[210:213], v[104:107]
	v_mfma_f32_16x16x32_bf16 v[100:103], v[166:169], v[218:221], v[100:103]
	v_mfma_f32_16x16x32_bf16 v[92:95], v[178:181], v[218:221], v[92:95]
	v_mfma_f32_16x16x32_bf16 v[84:87], v[166:169], v[230:233], v[84:87]
	v_mfma_f32_16x16x32_bf16 v[76:79], v[178:181], v[230:233], v[76:79]
	s_setprio 0
	s_setprio 1
	v_mfma_f32_16x16x32_bf16 v[116:119], v[182:185], v[198:201], v[116:119]
	v_mfma_f32_16x16x32_bf16 v[108:111], v[190:193], v[198:201], v[108:111]
	v_mfma_f32_16x16x32_bf16 v[96:99], v[182:185], v[206:209], v[96:99]
	v_mfma_f32_16x16x32_bf16 v[88:91], v[190:193], v[206:209], v[88:91]
	v_mfma_f32_16x16x32_bf16 v[80:83], v[182:185], v[214:217], v[80:83]
	v_mfma_f32_16x16x32_bf16 v[72:75], v[190:193], v[214:217], v[72:75]
	v_mfma_f32_16x16x32_bf16 v[68:71], v[182:185], v[226:229], v[68:71]
	v_mfma_f32_16x16x32_bf16 v[64:67], v[190:193], v[226:229], v[64:67]
	v_mfma_f32_16x16x32_bf16 v[116:119], v[186:189], v[202:205], v[116:119]
	v_mfma_f32_16x16x32_bf16 v[108:111], v[194:197], v[202:205], v[108:111]
	v_mfma_f32_16x16x32_bf16 v[96:99], v[186:189], v[210:213], v[96:99]
	v_mfma_f32_16x16x32_bf16 v[88:91], v[194:197], v[210:213], v[88:91]
	v_mfma_f32_16x16x32_bf16 v[80:83], v[186:189], v[218:221], v[80:83]
	v_mfma_f32_16x16x32_bf16 v[72:75], v[194:197], v[218:221], v[72:75]
	v_mfma_f32_16x16x32_bf16 v[68:71], v[186:189], v[230:233], v[68:71]
	v_mfma_f32_16x16x32_bf16 v[64:67], v[194:197], v[230:233], v[64:67]
	s_setprio 0
	s_barrier
	s_add_i32 s90, s85, s39
	v_lshl_add_u64 v[174:175], s[10:11], 0, v[130:131]
	s_mov_b32 m0, s90
	ds_read_b128 v[198:201], v164 offset:16384
	ds_read_b128 v[202:205], v164 offset:17408
	ds_read_b128 v[206:209], v164 offset:18432
	ds_read_b128 v[210:213], v164 offset:19456
	ds_read_b128 v[214:217], v164 offset:20480
	ds_read_b128 v[218:221], v164 offset:21504
	ds_read_b128 v[226:229], v164 offset:22528
	ds_read_b128 v[230:233], v164 offset:23552
	global_load_lds_dwordx4 v[174:175], off
	s_add_i32 m0, s90, 0x2000
	s_add_u32 s90, s10, 0x40000
	v_lshl_add_u64 v[222:223], s[10:11], 0, v[134:135]
	s_addc_u32 s91, s11, 0
	s_add_i32 s92, s86, s39
	global_load_lds_dwordx4 v[222:223], off
	v_lshl_add_u64 v[234:235], s[90:91], 0, v[130:131]
	s_mov_b32 m0, s92
	v_lshl_add_u64 v[236:237], s[12:13], 0, v[132:133]
	global_load_lds_dwordx4 v[234:235], off
	v_lshl_add_u64 v[234:235], s[90:91], 0, v[134:135]
	s_add_i32 m0, s92, 0x2000
	s_nop 0
	global_load_lds_dwordx4 v[234:235], off
	v_lshl_add_u64 v[234:235], s[12:13], 0, v[128:129]
	s_mov_b32 m0, s43
	s_nop 0
	global_load_lds_dwordx4 v[234:235], off
	s_mov_b32 m0, s53
	s_nop 0
	global_load_lds_dwordx4 v[236:237], off
	s_waitcnt vmcnt(8)
	s_waitcnt lgkmcnt(0)
	s_barrier
; #define PG8_STAGE(bufoff, gbase, voff) do { _Pragma("unroll") for (int _i = 0; _i < 2; ++_i) \
;         __builtin_amdgcn_global_load_lds((const unsigned*)((const char*)(gbase) + (voff)[_i]), (LAS unsigned*)(lds + (bufoff) + ldsw + _i * 8192), 16, 0, 0); } while (0)
; #define PG8_LDA(dst, b, h) do { _Pragma("unroll") for (int m = 0; m < 4; ++m) _Pragma("unroll") for (int k = 0; k < 2; ++k) dst[m][k] = *(const LAS bf16x8*)(lds + PG8_SA(b, h) + aoff + m * 2048 + k * 1024); } while (0)
; #define PG8_LDB(dst, b, h) do { _Pragma("unroll") for (int n = 0; n < 2; ++n) _Pragma("unroll") for (int k = 0; k < 2; ++k) dst[n][k] = *(const LAS bf16x8*)(lds + PG8_SB(b, h) + boff + n * 2048 + k * 1024); } while (0)
; #define PG8_MMA(ai, bj, At, Bt) do { __builtin_amdgcn_s_setprio(1); _Pragma("unroll") for (int m = 0; m < 4; ++m) _Pragma("unroll") for (int n = 0; n < 2; ++n) _Pragma("unroll") for (int k = 0; k < 2; ++k) \
;         acc[ai][bj][m][n] = __builtin_amdgcn_mfma_f32_16x16x32_bf16(Bt[n][k], At[m][k], acc[ai][bj][m][n], 0, 0, 0); __builtin_amdgcn_s_setprio(0); } while (0)
; #define PG8_WAIT_V(n) asm volatile("s_waitcnt vmcnt(" #n ")" ::: "memory")
; #define PG8_WAIT_L(n) asm volatile("s_waitcnt lgkmcnt(" #n ")" ::: "memory")
; #define PG8_BAR __builtin_amdgcn_s_barrier()
; #define PG8_SCHED __builtin_amdgcn_sched_barrier(0)
; template <class Epi>
; __device__ __forceinline__ void gemm_phase(LAS unsigned char* lds, const Gemm g, const StaticOrder& S, const Epi& E) {
;     ...
;             PG8_WAIT_V(8); PG8_WAIT_L(0); PG8_BAR; PG8_MMA(1, 0, At, B0); PG8_MMA(1, 1, At, B1); PG8_BAR; PG8_SCHED;
;             PG8_LDB(B0, 1, 0); PG8_LDB(B1, 1, 1); PG8_SCHED; PG8_LDA(At, 1, 0); PG8_STAGE(PG8_SA(0, 1), a2 + hstepA, voffA);
;             PG8_WAIT_V(8); PG8_WAIT_L(0); PG8_BAR; PG8_MMA(0, 0, At, B0); PG8_MMA(0, 1, At, B1); PG8_BAR; PG8_SCHED;
	s_setprio 1
	s_waitcnt lgkmcnt(0)
	v_mfma_f32_16x16x32_bf16 v[60:63], v[146:149], v[198:201], v[60:63]
	v_mfma_f32_16x16x32_bf16 v[56:59], v[170:173], v[198:201], v[56:59]
	v_mfma_f32_16x16x32_bf16 v[52:55], v[146:149], v[206:209], v[52:55]
	v_mfma_f32_16x16x32_bf16 v[44:47], v[170:173], v[206:209], v[44:47]
	v_mfma_f32_16x16x32_bf16 v[36:39], v[146:149], v[214:217], v[36:39]
	v_mfma_f32_16x16x32_bf16 v[28:31], v[170:173], v[214:217], v[28:31]
	v_mfma_f32_16x16x32_bf16 v[20:23], v[146:149], v[226:229], v[20:23]
	v_mfma_f32_16x16x32_bf16 v[12:15], v[170:173], v[226:229], v[12:15]
	v_mfma_f32_16x16x32_bf16 v[60:63], v[166:169], v[202:205], v[60:63]
	v_mfma_f32_16x16x32_bf16 v[56:59], v[178:181], v[202:205], v[56:59]
	v_mfma_f32_16x16x32_bf16 v[52:55], v[166:169], v[210:213], v[52:55]
	v_mfma_f32_16x16x32_bf16 v[44:47], v[178:181], v[210:213], v[44:47]
	v_mfma_f32_16x16x32_bf16 v[36:39], v[166:169], v[218:221], v[36:39]
	v_mfma_f32_16x16x32_bf16 v[28:31], v[178:181], v[218:221], v[28:31]
	v_mfma_f32_16x16x32_bf16 v[20:23], v[166:169], v[230:233], v[20:23]
	v_mfma_f32_16x16x32_bf16 v[12:15], v[178:181], v[230:233], v[12:15]
	s_setprio 0
	s_setprio 1
	v_mfma_f32_16x16x32_bf16 v[48:51], v[182:185], v[198:201], v[48:51]
	v_mfma_f32_16x16x32_bf16 v[40:43], v[190:193], v[198:201], v[40:43]
	v_mfma_f32_16x16x32_bf16 v[32:35], v[182:185], v[206:209], v[32:35]
	v_mfma_f32_16x16x32_bf16 v[24:27], v[190:193], v[206:209], v[24:27]
	v_mfma_f32_16x16x32_bf16 v[16:19], v[182:185], v[214:217], v[16:19]
	v_mfma_f32_16x16x32_bf16 v[8:11], v[190:193], v[214:217], v[8:11]
	v_mfma_f32_16x16x32_bf16 v[4:7], v[182:185], v[226:229], v[4:7]
	v_mfma_f32_16x16x32_bf16 v[0:3], v[190:193], v[226:229], v[0:3]
	v_mfma_f32_16x16x32_bf16 v[48:51], v[186:189], v[202:205], v[48:51]
	v_mfma_f32_16x16x32_bf16 v[40:43], v[194:197], v[202:205], v[40:43]
	v_mfma_f32_16x16x32_bf16 v[32:35], v[186:189], v[210:213], v[32:35]
	v_mfma_f32_16x16x32_bf16 v[24:27], v[194:197], v[210:213], v[24:27]
	v_mfma_f32_16x16x32_bf16 v[16:19], v[186:189], v[218:221], v[16:19]
	v_mfma_f32_16x16x32_bf16 v[8:11], v[194:197], v[218:221], v[8:11]
	v_mfma_f32_16x16x32_bf16 v[4:7], v[186:189], v[230:233], v[4:7]
	v_mfma_f32_16x16x32_bf16 v[0:3], v[194:197], v[230:233], v[0:3]
	s_setprio 0
	s_barrier
	s_add_i32 s90, 0, 0x18000
	v_add_u32_e32 v136, s90, v161
	s_add_i32 s91, 0, 0x1c000
	ds_read_b128 v[146:149], v136
	ds_read_b128 v[166:169], v136 offset:1024
	ds_read_b128 v[170:173], v136 offset:2048
	ds_read_b128 v[178:181], v136 offset:3072
	v_add_u32_e32 v136, s91, v161
	ds_read_b128 v[182:185], v136
	ds_read_b128 v[186:189], v136 offset:1024
	ds_read_b128 v[190:193], v136 offset:2048
	ds_read_b128 v[194:197], v136 offset:3072
	s_add_u32 s12, s12, 0x40000
	s_addc_u32 s13, s13, 0
	s_mov_b32 m0, s55
	v_lshl_add_u64 v[238:239], s[12:13], 0, v[128:129]
	ds_read_b128 v[198:201], v164 offset:32768
	ds_read_b128 v[202:205], v164 offset:33792
	ds_read_b128 v[206:209], v164 offset:34816
	ds_read_b128 v[210:213], v164 offset:35840
	ds_read_b128 v[214:217], v164 offset:36864
	ds_read_b128 v[218:221], v164 offset:37888
	ds_read_b128 v[226:229], v164 offset:38912
	ds_read_b128 v[230:233], v164 offset:39936
	global_load_lds_dwordx4 v[238:239], off
	v_lshl_add_u64 v[238:239], s[12:13], 0, v[132:133]
	s_mov_b32 m0, s57
	s_nop 0
	global_load_lds_dwordx4 v[238:239], off
	s_waitcnt vmcnt(8)
	s_waitcnt lgkmcnt(0)
	s_barrier
	s_setprio 1
	s_waitcnt lgkmcnt(0)
	v_mfma_f32_16x16x32_bf16 v[124:127], v[146:149], v[198:201], v[124:127]
	v_mfma_f32_16x16x32_bf16 v[120:123], v[170:173], v[198:201], v[120:123]
	v_mfma_f32_16x16x32_bf16 v[112:115], v[146:149], v[206:209], v[112:115]
	v_mfma_f32_16x16x32_bf16 v[104:107], v[170:173], v[206:209], v[104:107]
	v_mfma_f32_16x16x32_bf16 v[100:103], v[146:149], v[214:217], v[100:103]
	v_mfma_f32_16x16x32_bf16 v[92:95], v[170:173], v[214:217], v[92:95]
	v_mfma_f32_16x16x32_bf16 v[84:87], v[146:149], v[226:229], v[84:87]
	v_mfma_f32_16x16x32_bf16 v[76:79], v[170:173], v[226:229], v[76:79]
	v_mfma_f32_16x16x32_bf16 v[124:127], v[166:169], v[202:205], v[124:127]
	v_mfma_f32_16x16x32_bf16 v[120:123], v[178:181], v[202:205], v[120:123]
	v_mfma_f32_16x16x32_bf16 v[112:115], v[166:169], v[210:213], v[112:115]
	v_mfma_f32_16x16x32_bf16 v[104:107], v[178:181], v[210:213], v[104:107]
	v_mfma_f32_16x16x32_bf16 v[100:103], v[166:169], v[218:221], v[100:103]
	v_mfma_f32_16x16x32_bf16 v[92:95], v[178:181], v[218:221], v[92:95]
	v_mfma_f32_16x16x32_bf16 v[84:87], v[166:169], v[230:233], v[84:87]
	v_mfma_f32_16x16x32_bf16 v[76:79], v[178:181], v[230:233], v[76:79]
	s_setprio 0
	s_setprio 1
	v_mfma_f32_16x16x32_bf16 v[116:119], v[182:185], v[198:201], v[116:119]
	v_mfma_f32_16x16x32_bf16 v[108:111], v[190:193], v[198:201], v[108:111]
	v_mfma_f32_16x16x32_bf16 v[96:99], v[182:185], v[206:209], v[96:99]
	v_mfma_f32_16x16x32_bf16 v[88:91], v[190:193], v[206:209], v[88:91]
	v_mfma_f32_16x16x32_bf16 v[80:83], v[182:185], v[214:217], v[80:83]
	v_mfma_f32_16x16x32_bf16 v[72:75], v[190:193], v[214:217], v[72:75]
	v_mfma_f32_16x16x32_bf16 v[68:71], v[182:185], v[226:229], v[68:71]
	v_mfma_f32_16x16x32_bf16 v[64:67], v[190:193], v[226:229], v[64:67]
	v_mfma_f32_16x16x32_bf16 v[116:119], v[186:189], v[202:205], v[116:119]
	v_mfma_f32_16x16x32_bf16 v[108:111], v[194:197], v[202:205], v[108:111]
	v_mfma_f32_16x16x32_bf16 v[96:99], v[186:189], v[210:213], v[96:99]
	v_mfma_f32_16x16x32_bf16 v[88:91], v[194:197], v[210:213], v[88:91]
	v_mfma_f32_16x16x32_bf16 v[80:83], v[186:189], v[218:221], v[80:83]
	v_mfma_f32_16x16x32_bf16 v[72:75], v[194:197], v[218:221], v[72:75]
	v_mfma_f32_16x16x32_bf16 v[68:71], v[186:189], v[230:233], v[68:71]
	v_mfma_f32_16x16x32_bf16 v[64:67], v[194:197], v[230:233], v[64:67]
	s_setprio 0
	s_barrier
; __device__ __forceinline__ u32x2 pack4(f32x4 v) { return (u32x2){pk2(v[0], v[1]), pk2(v[2], v[3])}; }
; #define PG8_STAGE(bufoff, gbase, voff) do { _Pragma("unroll") for (int _i = 0; _i < 2; ++_i) \
;         __builtin_amdgcn_global_load_lds((const unsigned*)((const char*)(gbase) + (voff)[_i]), (LAS unsigned*)(lds + (bufoff) + ldsw + _i * 8192), 16, 0, 0); } while (0)
; #define PG8_LDA(dst, b, h) do { _Pragma("unroll") for (int m = 0; m < 4; ++m) _Pragma("unroll") for (int k = 0; k < 2; ++k) dst[m][k] = *(const LAS bf16x8*)(lds + PG8_SA(b, h) + aoff + m * 2048 + k * 1024); } while (0)
; #define PG8_MMA(ai, bj, At, Bt) do { __builtin_amdgcn_s_setprio(1); _Pragma("unroll") for (int m = 0; m < 4; ++m) _Pragma("unroll") for (int n = 0; n < 2; ++n) _Pragma("unroll") for (int k = 0; k < 2; ++k) \
;         acc[ai][bj][m][n] = __builtin_amdgcn_mfma_f32_16x16x32_bf16(Bt[n][k], At[m][k], acc[ai][bj][m][n], 0, 0, 0); __builtin_amdgcn_s_setprio(0); } while (0)
; #define PG8_WAIT_V(n) asm volatile("s_waitcnt vmcnt(" #n ")" ::: "memory")
; #define PG8_WAIT_L(n) asm volatile("s_waitcnt lgkmcnt(" #n ")" ::: "memory")
; #define PG8_BAR __builtin_amdgcn_s_barrier()
; #define PG8_SCHED __builtin_amdgcn_sched_barrier(0)
; #define EPI_LOAD_RR(ssp) float rr[8]; _Pragma("unroll") for (int it = 0; it < 8; ++it) rr[it] = (ssp)[EPI_IT_ROW(it)]; _Pragma("unroll") for (int it = 0; it < 8; ++it) rr[it] = rms_r(rr[it])
; template <class Epi>
; __device__ __forceinline__ void gemm_phase(LAS unsigned char* lds, const Gemm g, const StaticOrder& S, const Epi& E) {
;     ...
;             PG8_LDA(At, 1, 1); PG8_STAGE(PG8_SB(1, 0), b3, voffB); PG8_STAGE(PG8_SB(1, 1), b3 + hstepB, voffB); PG8_STAGE(PG8_SA(1, 0), a3, voffA);
;             PG8_WAIT_V(8); PG8_WAIT_L(0); PG8_BAR; PG8_MMA(1, 0, At, B0); PG8_MMA(1, 1, At, B1); PG8_BAR; PG8_SCHED;
;         }
;         if (wr == 0) PG8_BAR;
;         E(acc, cur, wr, wc, fr, fq);
;         if (!has_next) break;
;     __device__ __forceinline__ void operator()(AccRef acc, const Unit& u, int wr, int wc, int fr, int fq) const {
;     ...
;         { EPI_LOAD_RR(ss);
; #pragma unroll
;           for (int it = 0; it < 8; ++it)
; #pragma unroll
;               for (int bj = 0; bj < 2; ++bj)
; #pragma unroll
;                   for (int n = 0; n < 2; ++n) pa[it >> 2][bj][it & 3][n] = pack4(acc[it >> 2][bj][it & 3][n] * rr[it]); }
	s_add_i32 s12, s90, s39
	v_lshl_add_u64 v[174:175], v[174:175], 0, s[30:31]
	s_mov_b32 m0, s12
	ds_read_b128 v[198:201], v164 offset:49152
	ds_read_b128 v[202:205], v164 offset:50176
	ds_read_b128 v[206:209], v164 offset:51200
	ds_read_b128 v[210:213], v164 offset:52224
	ds_read_b128 v[214:217], v164 offset:53248
	ds_read_b128 v[218:221], v164 offset:54272
	ds_read_b128 v[226:229], v164 offset:55296
	ds_read_b128 v[230:233], v164 offset:56320
	global_load_lds_dwordx4 v[174:175], off
	s_add_i32 m0, s12, 0x2000
	s_add_u32 s10, s10, 0x40080
	v_lshl_add_u64 v[174:175], v[222:223], 0, s[30:31]
	s_addc_u32 s11, s11, 0
	s_add_i32 s12, s91, s39
	global_load_lds_dwordx4 v[174:175], off
	v_lshl_add_u64 v[174:175], s[10:11], 0, v[130:131]
	s_mov_b32 m0, s12
	s_nop 0
	global_load_lds_dwordx4 v[174:175], off
	v_lshl_add_u64 v[174:175], s[10:11], 0, v[134:135]
	s_add_i32 m0, s12, 0x2000
	s_nop 0
	global_load_lds_dwordx4 v[174:175], off
	v_lshl_add_u64 v[174:175], v[234:235], 0, s[30:31]
	s_mov_b32 m0, s79
	s_nop 0
	global_load_lds_dwordx4 v[174:175], off
	v_lshl_add_u64 v[174:175], v[236:237], 0, s[30:31]
	s_mov_b32 m0, s80
	s_nop 0
	global_load_lds_dwordx4 v[174:175], off
	s_waitcnt vmcnt(8)
	s_waitcnt lgkmcnt(0)
	s_barrier
	s_setprio 1
	s_waitcnt lgkmcnt(0)
	v_mfma_f32_16x16x32_bf16 v[60:63], v[146:149], v[198:201], v[60:63]
	v_mfma_f32_16x16x32_bf16 v[56:59], v[170:173], v[198:201], v[56:59]
	v_mfma_f32_16x16x32_bf16 v[52:55], v[146:149], v[206:209], v[52:55]
	v_mfma_f32_16x16x32_bf16 v[44:47], v[170:173], v[206:209], v[44:47]
	v_mfma_f32_16x16x32_bf16 v[36:39], v[146:149], v[214:217], v[36:39]
	v_mfma_f32_16x16x32_bf16 v[28:31], v[170:173], v[214:217], v[28:31]
	v_mfma_f32_16x16x32_bf16 v[20:23], v[146:149], v[226:229], v[20:23]
	v_mfma_f32_16x16x32_bf16 v[12:15], v[170:173], v[226:229], v[12:15]
	v_mfma_f32_16x16x32_bf16 v[60:63], v[166:169], v[202:205], v[60:63]
	v_mfma_f32_16x16x32_bf16 v[56:59], v[178:181], v[202:205], v[56:59]
	v_mfma_f32_16x16x32_bf16 v[52:55], v[166:169], v[210:213], v[52:55]
	v_mfma_f32_16x16x32_bf16 v[44:47], v[178:181], v[210:213], v[44:47]
	v_mfma_f32_16x16x32_bf16 v[36:39], v[166:169], v[218:221], v[36:39]
	v_mfma_f32_16x16x32_bf16 v[28:31], v[178:181], v[218:221], v[28:31]
	v_mfma_f32_16x16x32_bf16 v[20:23], v[166:169], v[230:233], v[20:23]
	v_mfma_f32_16x16x32_bf16 v[12:15], v[178:181], v[230:233], v[12:15]
	s_setprio 0
	s_setprio 1
	v_mfma_f32_16x16x32_bf16 v[48:51], v[182:185], v[198:201], v[48:51]
	v_mfma_f32_16x16x32_bf16 v[40:43], v[190:193], v[198:201], v[40:43]
	v_mfma_f32_16x16x32_bf16 v[32:35], v[182:185], v[206:209], v[32:35]
	v_mfma_f32_16x16x32_bf16 v[24:27], v[190:193], v[206:209], v[24:27]
	v_mfma_f32_16x16x32_bf16 v[16:19], v[182:185], v[214:217], v[16:19]
	v_mfma_f32_16x16x32_bf16 v[8:11], v[190:193], v[214:217], v[8:11]
	v_mfma_f32_16x16x32_bf16 v[4:7], v[182:185], v[226:229], v[4:7]
	v_mfma_f32_16x16x32_bf16 v[0:3], v[190:193], v[226:229], v[0:3]
	v_mfma_f32_16x16x32_bf16 v[48:51], v[186:189], v[202:205], v[48:51]
	v_mfma_f32_16x16x32_bf16 v[40:43], v[194:197], v[202:205], v[40:43]
	v_mfma_f32_16x16x32_bf16 v[32:35], v[186:189], v[210:213], v[32:35]
	v_mfma_f32_16x16x32_bf16 v[24:27], v[194:197], v[210:213], v[24:27]
	v_mfma_f32_16x16x32_bf16 v[16:19], v[186:189], v[218:221], v[16:19]
	v_mfma_f32_16x16x32_bf16 v[8:11], v[194:197], v[218:221], v[8:11]
	v_mfma_f32_16x16x32_bf16 v[4:7], v[186:189], v[230:233], v[4:7]
	v_mfma_f32_16x16x32_bf16 v[0:3], v[194:197], v[230:233], v[0:3]
	s_setprio 0
	s_barrier
	s_add_i32 s89, s89, 2
	s_add_u32 s8, s8, 0x100
	s_addc_u32 s9, s9, 0
	s_add_u32 s76, s76, 0x100
	s_addc_u32 s77, s77, 0
	s_cmp_gt_u32 s89, 13
	s_cbranch_scc0 .LBB0_546
	s_cmp_eq_u64 s[4:5], 0
	s_cselect_b32 s99, 1, 0
	s_and_b64 vcc, exec, s[34:35]
	s_cbranch_vccz .LBB0_549
	s_barrier
.LBB0_549:
	s_lshl_b32 s69, s6, 8
	v_mov_b32_e32 v166, v151
	v_mov_b32_e32 v185, v153
	s_add_i32 s69, s69, s65
	s_lshl_b32 s0, s0, 7
	v_add_u32_e32 v146, s69, v166
	v_ashrrev_i32_e32 v147, 31, v146
	v_lshl_add_u64 v[148:149], v[146:147], 2, s[22:23]
	v_mov_b32_e32 v136, v240
	v_add_u32_e32 v148, 16, v146
	v_add_u32_e32 v170, 32, v146
	v_ashrrev_i32_e32 v149, 31, v148
	v_ashrrev_i32_e32 v171, 31, v170
	v_add_u32_e32 v172, 48, v146
	v_add_u32_e32 v174, 0x80, v146
	v_add_u32_e32 v178, 0x90, v146
	v_add_u32_e32 v180, 0xa0, v146
	v_add_u32_e32 v182, 0xb0, v146
	v_lshl_add_u64 v[168:169], v[148:149], 2, s[22:23]
	v_lshl_add_u64 v[170:171], v[170:171], 2, s[22:23]
	v_ashrrev_i32_e32 v173, 31, v172
	v_ashrrev_i32_e32 v175, 31, v174
	v_ashrrev_i32_e32 v179, 31, v178
	v_ashrrev_i32_e32 v181, 31, v180
	v_ashrrev_i32_e32 v183, 31, v182
	v_lshl_add_u64 v[172:173], v[172:173], 2, s[22:23]
	v_lshl_add_u64 v[174:175], v[174:175], 2, s[22:23]
	v_lshl_add_u64 v[178:179], v[178:179], 2, s[22:23]
	v_lshl_add_u64 v[180:181], v[180:181], 2, s[22:23]
	v_lshl_add_u64 v[182:183], v[182:183], 2, s[22:23]
	v_mov_b32_e32 v147, v241
	v_mov_b32_e32 v149, v242
	v_mov_b32_e32 v150, v243
	v_mov_b32_e32 v152, v244
	v_mov_b32_e32 v167, v245
	s_nop 0
	v_mov_b32_e32 v169, v246
	v_mov_b32_e32 v170, v247
	s_or_b32 s0, s0, s78
	s_nop 0
	v_fmamk_f32 v136, v136, 0x3a800000, v165
	v_rsq_f32_e32 v168, v136
	v_fmamk_f32 v136, v147, 0x3a800000, v165
	v_fmamk_f32 v147, v149, 0x3a800000, v165
	v_fmamk_f32 v149, v150, 0x3a800000, v165
	v_fmamk_f32 v150, v152, 0x3a800000, v165
	v_fmamk_f32 v152, v167, 0x3a800000, v165
	v_fmamk_f32 v167, v169, 0x3a800000, v165
	v_rsq_f32_e32 v172, v136
	v_fmamk_f32 v169, v170, 0x3a800000, v165
	v_rsq_f32_e32 v180, v147
	v_rsq_f32_e32 v184, v150
	v_rsq_f32_e32 v150, v167
	v_rsq_f32_e32 v182, v149
	v_rsq_f32_e32 v152, v152
; __device__ __forceinline__ u32x2 pack4(f32x4 v) { return (u32x2){pk2(v[0], v[1]), pk2(v[2], v[3])}; }
; #define EPI_LOAD_RR(ssp) float rr[8]; _Pragma("unroll") for (int it = 0; it < 8; ++it) rr[it] = (ssp)[EPI_IT_ROW(it)]; _Pragma("unroll") for (int it = 0; it < 8; ++it) rr[it] = rms_r(rr[it])
;     __device__ __forceinline__ void operator()(AccRef acc, const Unit& u, int wr, int wc, int fr, int fq) const {
;     ...
;         { EPI_LOAD_RR(ss);
; #pragma unroll
;           for (int it = 0; it < 8; ++it)
; #pragma unroll
;               for (int bj = 0; bj < 2; ++bj)
; #pragma unroll
;                   for (int n = 0; n < 2; ++n) pa[it >> 2][bj][it & 3][n] = pack4(acc[it >> 2][bj][it & 3][n] * rr[it]); }
	v_rsq_f32_e32 v136, v169
	v_pk_mul_f32 v[90:91], v[90:91], v[172:173] op_sel_hi:[1,0]
	v_pk_mul_f32 v[88:89], v[88:89], v[172:173] op_sel_hi:[1,0]
	v_pk_mul_f32 v[110:111], v[110:111], v[168:169] op_sel_hi:[1,0]
	v_pk_mul_f32 v[108:109], v[108:109], v[168:169] op_sel_hi:[1,0]
	v_pk_mul_f32 v[104:105], v[104:105], v[172:173] op_sel_hi:[1,0]
	v_pk_mul_f32 v[100:101], v[100:101], v[180:181] op_sel_hi:[1,0]
	v_cvt_pk_bf16_f32 v89, v88, v89
	v_cvt_pk_bf16_f32 v88, v90, v91
	v_pk_mul_f32 v[90:91], v[82:83], v[180:181] op_sel_hi:[1,0]
	v_pk_mul_f32 v[72:73], v[72:73], v[180:181] op_sel_hi:[1,0]
	v_pk_mul_f32 v[42:43], v[42:43], v[184:185] op_sel_hi:[1,0]
	v_pk_mul_f32 v[10:11], v[10:11], v[150:151] op_sel_hi:[1,0]
	v_pk_mul_f32 v[8:9], v[8:9], v[150:151] op_sel_hi:[1,0]
	v_cvt_pk_bf16_f32 v170, v108, v109
	v_cvt_pk_bf16_f32 v171, v110, v111
	v_pk_mul_f32 v[108:109], v[114:115], v[172:173] op_sel_hi:[1,0]
	v_pk_mul_f32 v[110:111], v[112:113], v[172:173] op_sel_hi:[1,0]
	v_pk_mul_f32 v[106:107], v[106:107], v[172:173] op_sel_hi:[1,0]
	v_pk_mul_f32 v[98:99], v[98:99], v[172:173] op_sel_hi:[1,0]
	v_pk_mul_f32 v[96:97], v[96:97], v[172:173] op_sel_hi:[1,0]
	v_pk_mul_f32 v[102:103], v[102:103], v[180:181] op_sel_hi:[1,0]
	v_cvt_pk_bf16_f32 v167, v104, v105
	v_cvt_pk_bf16_f32 v173, v100, v101
	v_pk_mul_f32 v[80:81], v[80:81], v[180:181] op_sel_hi:[1,0]
	v_cvt_pk_bf16_f32 v83, v90, v91
	v_pk_mul_f32 v[74:75], v[74:75], v[180:181] op_sel_hi:[1,0]
	v_cvt_pk_bf16_f32 v90, v72, v73
	v_pk_mul_f32 v[72:73], v[86:87], v[182:183] op_sel_hi:[1,0]
	v_pk_mul_f32 v[40:41], v[40:41], v[184:185] op_sel_hi:[1,0]
	v_cvt_pk_bf16_f32 v101, v42, v43
	v_pk_mul_f32 v[42:43], v[52:53], v[152:153] op_sel_hi:[1,0]
	v_pk_mul_f32 v[26:27], v[26:27], v[152:153] op_sel_hi:[1,0]
	v_pk_mul_f32 v[24:25], v[24:25], v[152:153] op_sel_hi:[1,0]
	v_cvt_pk_bf16_f32 v104, v8, v9
	v_cvt_pk_bf16_f32 v105, v10, v11
	v_pk_mul_f32 v[8:9], v[22:23], v[136:137] op_sel_hi:[1,0]
	v_pk_mul_f32 v[10:11], v[20:21], v[136:137] op_sel_hi:[1,0]
	v_pk_mul_f32 v[126:127], v[126:127], v[168:169] op_sel_hi:[1,0]
	v_pk_mul_f32 v[124:125], v[124:125], v[168:169] op_sel_hi:[1,0]
	v_pk_mul_f32 v[122:123], v[122:123], v[168:169] op_sel_hi:[1,0]
	v_pk_mul_f32 v[120:121], v[120:121], v[168:169] op_sel_hi:[1,0]
	v_pk_mul_f32 v[118:119], v[118:119], v[168:169] op_sel_hi:[1,0]
	v_pk_mul_f32 v[116:117], v[116:117], v[168:169] op_sel_hi:[1,0]
	v_pk_mul_f32 v[94:95], v[94:95], v[180:181] op_sel_hi:[1,0]
	v_pk_mul_f32 v[92:93], v[92:93], v[180:181] op_sel_hi:[1,0]
	v_cvt_pk_bf16_f32 v174, v108, v109
	v_cvt_pk_bf16_f32 v172, v102, v103
	v_cvt_pk_bf16_f32 v82, v80, v81
	v_cvt_pk_bf16_f32 v91, v74, v75
	v_pk_mul_f32 v[74:75], v[84:85], v[182:183] op_sel_hi:[1,0]
	v_cvt_pk_bf16_f32 v81, v72, v73
	v_pk_mul_f32 v[72:73], v[78:79], v[182:183] op_sel_hi:[1,0]
	v_pk_mul_f32 v[58:59], v[58:59], v[184:185] op_sel_hi:[1,0]
	v_pk_mul_f32 v[56:57], v[56:57], v[184:185] op_sel_hi:[1,0]
	v_cvt_pk_bf16_f32 v100, v40, v41
	v_pk_mul_f32 v[40:41], v[54:55], v[152:153] op_sel_hi:[1,0]
	v_cvt_pk_bf16_f32 v112, v42, v43
	v_pk_mul_f32 v[42:43], v[44:45], v[152:153] op_sel_hi:[1,0]
	v_cvt_pk_bf16_f32 v102, v24, v25
	v_cvt_pk_bf16_f32 v103, v26, v27
	v_pk_mul_f32 v[24:25], v[38:39], v[150:151] op_sel_hi:[1,0]
	v_pk_mul_f32 v[26:27], v[36:37], v[150:151] op_sel_hi:[1,0]
	v_cvt_pk_bf16_f32 v108, v10, v11
	v_cvt_pk_bf16_f32 v109, v8, v9
	v_pk_mul_f32 v[8:9], v[14:15], v[136:137] op_sel_hi:[1,0]
	v_pk_mul_f32 v[10:11], v[12:13], v[136:137] op_sel_hi:[1,0]
	v_pk_mul_f32 v[6:7], v[6:7], v[136:137] op_sel_hi:[1,0]
	v_pk_mul_f32 v[4:5], v[4:5], v[136:137] op_sel_hi:[1,0]
	v_pk_mul_f32 v[2:3], v[2:3], v[136:137] op_sel_hi:[1,0]
	v_pk_mul_f32 v[0:1], v[0:1], v[136:137] op_sel_hi:[1,0]
	v_lshl_add_u32 v44, v185, 3, s0
	v_cvt_pk_bf16_f32 v190, v124, v125
	v_cvt_pk_bf16_f32 v189, v126, v127
	v_cvt_pk_bf16_f32 v169, v120, v121
	v_cvt_pk_bf16_f32 v168, v122, v123
	v_cvt_pk_bf16_f32 v126, v116, v117
	v_cvt_pk_bf16_f32 v179, v118, v119
	v_cvt_pk_bf16_f32 v175, v110, v111
	v_cvt_pk_bf16_f32 v149, v106, v107
	v_cvt_pk_bf16_f32 v178, v96, v97
	v_cvt_pk_bf16_f32 v177, v98, v99
	v_cvt_pk_bf16_f32 v127, v92, v93
	v_cvt_pk_bf16_f32 v147, v94, v95
	v_cvt_pk_bf16_f32 v80, v74, v75
	v_pk_mul_f32 v[74:75], v[76:77], v[182:183] op_sel_hi:[1,0]
	v_cvt_pk_bf16_f32 v125, v72, v73
	v_pk_mul_f32 v[72:73], v[70:71], v[182:183] op_sel_hi:[1,0]
	v_cvt_pk_bf16_f32 v124, v74, v75
	v_pk_mul_f32 v[68:69], v[68:69], v[182:183] op_sel_hi:[1,0]
	v_cvt_pk_bf16_f32 v71, v72, v73
	v_pk_mul_f32 v[66:67], v[66:67], v[182:183] op_sel_hi:[1,0]
	v_cvt_pk_bf16_f32 v70, v68, v69
	v_pk_mul_f32 v[64:65], v[64:65], v[182:183] op_sel_hi:[1,0]
	v_cvt_pk_bf16_f32 v85, v66, v67
	v_pk_mul_f32 v[62:63], v[62:63], v[184:185] op_sel_hi:[1,0]
	v_cvt_pk_bf16_f32 v84, v64, v65
	v_pk_mul_f32 v[60:61], v[60:61], v[184:185] op_sel_hi:[1,0]
	v_cvt_pk_bf16_f32 v115, v62, v63
	v_cvt_pk_bf16_f32 v98, v56, v57
	v_cvt_pk_bf16_f32 v99, v58, v59
	v_pk_mul_f32 v[50:51], v[50:51], v[184:185] op_sel_hi:[1,0]
	v_cvt_pk_bf16_f32 v114, v60, v61
	v_pk_mul_f32 v[48:49], v[48:49], v[184:185] op_sel_hi:[1,0]
	v_cvt_pk_bf16_f32 v117, v50, v51
	v_cvt_pk_bf16_f32 v113, v40, v41
	v_pk_mul_f32 v[40:41], v[46:47], v[152:153] op_sel_hi:[1,0]
	v_cvt_pk_bf16_f32 v116, v48, v49
	v_cvt_pk_bf16_f32 v96, v42, v43
	v_pk_mul_f32 v[34:35], v[34:35], v[152:153] op_sel_hi:[1,0]
	v_cvt_pk_bf16_f32 v97, v40, v41
	v_pk_mul_f32 v[32:33], v[32:33], v[152:153] op_sel_hi:[1,0]
	v_cvt_pk_bf16_f32 v119, v34, v35
	v_cvt_pk_bf16_f32 v110, v26, v27
	v_cvt_pk_bf16_f32 v111, v24, v25
	v_pk_mul_f32 v[24:25], v[30:31], v[150:151] op_sel_hi:[1,0]
	v_cvt_pk_bf16_f32 v118, v32, v33
; __device__ __forceinline__ f32x4 ror1v(f32x4 v) { return (f32x4){dpp_ror1(v[0]), dpp_ror1(v[1]), dpp_ror1(v[2]), dpp_ror1(v[3])}; }
; __device__ __forceinline__ f32x4 ror2v(f32x4 v) { return (f32x4){dpp_ror2(v[0]), dpp_ror2(v[1]), dpp_ror2(v[2]), dpp_ror2(v[3])}; }
; __device__ __forceinline__ f32x4 unpack4(u32x2 w) { return (f32x4){bflo(w.x), bfhi(w.x), bflo(w.y), bfhi(w.y)}; }
;     __device__ __forceinline__ void operator()(AccRef acc, const Unit& u, int wr, int wc, int fr, int fq) const {
;     ...
;         for (int ai = 0; ai < 2; ++ai) {
;             const int rowg = u.pm * 256 + ai * 128 + wr * 64; const int grp = rowg >> 6;
; #pragma unroll
;             for (int n = 0; n < 2; ++n) { const unsigned jn = (unsigned)(j0 + 4 * n);
;                 f32x4 cu[4];
;                 {
;                     const f32x4 wu0 = *(const f32x4*)(cw + (DFF + jn)), wu1 = *(const f32x4*)(cw + (UPN + DFF + jn)), wu2 = *(const f32x4*)(cw + (2 * UPN + DFF + jn)), bu = *(const f32x4*)(cb + (DFF + jn));
;                     f32x4 pu1 = (f32x4){0.f, 0.f, 0.f, 0.f}, pu2 = pu1;
; #pragma unroll
;                     for (int m = 0; m < 4; ++m) {
;                         const f32x4 au = unpack4(pa[ai][1][m][n]);
;                         const f32x4 ru1 = ror1v(au), ru2 = ror2v(au);
;                         const f32x4 u1 = fr >= 1 ? ru1 : pu1, u2 = fr >= 2 ? ru2 : pu2;
;                         if (m == 0 && fr < 2) *(f32x4*)(edge + (unsigned)((grp * 4 + fr) * UPN + DFF + jn)) = au;
;                         if (m == 3 && fr >= 14) *(f32x4*)(edge + (unsigned)((grp * 4 + (fr - 12)) * UPN + DFF + jn)) = au;
;                         cu[m] = bu + wu0 * u2 + wu1 * u1 + wu2 * au;
;                         pu1 = ru1; pu2 = ru2; }
	v_pk_mul_f32 v[26:27], v[28:29], v[150:151] op_sel_hi:[1,0]
	v_cvt_pk_bf16_f32 v95, v24, v25
	v_pk_mul_f32 v[18:19], v[18:19], v[150:151] op_sel_hi:[1,0]
	v_cvt_pk_bf16_f32 v94, v26, v27
	v_pk_mul_f32 v[16:17], v[16:17], v[150:151] op_sel_hi:[1,0]
	v_cvt_pk_bf16_f32 v121, v18, v19
	v_cvt_pk_bf16_f32 v92, v10, v11
	v_cvt_pk_bf16_f32 v93, v8, v9
	v_cvt_pk_bf16_f32 v122, v4, v5
	v_cvt_pk_bf16_f32 v123, v6, v7
	s_nop 0
	v_cvt_pk_bf16_f32 v120, v16, v17
	v_cvt_pk_bf16_f32 v106, v0, v1
	v_cvt_pk_bf16_f32 v107, v2, v3
	v_add_u32_e32 v136, 0xb00, v44
	v_lshlrev_b64 v[12:13], 2, v[136:137]
	v_add_u32_e32 v136, 0x2100, v44
	v_lshl_add_u64 v[54:55], v[136:137], 2, s[66:67]
	v_add_u32_e32 v136, 0x3700, v44
	v_lshl_add_u64 v[52:53], s[66:67], 0, v[12:13]
	v_lshl_add_u64 v[56:57], v[136:137], 2, s[66:67]
	v_lshl_add_u64 v[58:59], s[36:37], 0, v[12:13]
	global_load_dwordx4 v[8:11], v[52:53], off
	global_load_dwordx4 v[0:3], v[54:55], off
	global_load_dwordx4 v[4:7], v[56:57], off
	global_load_dwordx4 v[12:15], v[58:59], off
	s_ashr_i32 s6, s69, 4
	v_add_u32_e32 v16, s6, v166
	v_mul_lo_u32 v152, v16, s87
	v_lshlrev_b32_e32 v36, 16, v126
	v_and_b32_e32 v37, 0xffff0000, v126
	v_lshlrev_b32_e32 v38, 16, v179
	v_and_b32_e32 v39, 0xffff0000, v179
	s_nop 1
	v_cmp_lt_i32_e64 s[10:11], 1, v166
	v_cmp_gt_i32_e64 s[12:13], 2, v166
	v_add_u32_e32 v78, 0xb00, v152
	v_mov_b32_dpp v191, v36 row_ror:1 row_mask:0xf bank_mask:0xf
	v_mov_b32_dpp v194, v37 row_ror:1 row_mask:0xf bank_mask:0xf
	v_mov_b32_dpp v192, v38 row_ror:1 row_mask:0xf bank_mask:0xf
	v_mov_b32_dpp v196, v39 row_ror:1 row_mask:0xf bank_mask:0xf
	v_mov_b32_dpp v193, v36 row_ror:2 row_mask:0xf bank_mask:0xf
	v_mov_b32_dpp v197, v37 row_ror:2 row_mask:0xf bank_mask:0xf
	v_mov_b32_dpp v201, v38 row_ror:2 row_mask:0xf bank_mask:0xf
	v_mov_b32_dpp v204, v39 row_ror:2 row_mask:0xf bank_mask:0xf
	s_and_saveexec_b64 s[0:1], s[12:13]
	s_cbranch_execz .LBB0_551
	v_add_u32_e32 v136, v78, v44
	v_lshl_add_u64 v[16:17], v[136:137], 2, s[28:29]
	s_cmp_lg_u32 s99, 0
	s_cbranch_scc1 .Lwt546_13088
	global_store_dwordx4 v[16:17], v[36:39], off
	s_branch .Lwj546_13088
.Lwt546_13088:
	global_store_dwordx4 v[16:17], v[36:39], off sc1
.Lwj546_13088:
.LBB0_551:
	s_or_b64 exec, exec, s[0:1]
	v_add_u32_e32 v126, -12, v166
	v_add_u32_e32 v16, s6, v126
	v_mul_lo_u32 v150, v16, s87
	v_lshlrev_b32_e32 v68, 16, v178
	v_and_b32_e32 v69, 0xffff0000, v178
	v_lshlrev_b32_e32 v66, 16, v177
	v_and_b32_e32 v67, 0xffff0000, v177
	s_nop 1
	v_lshlrev_b32_e32 v62, 16, v82
	v_and_b32_e32 v63, 0xffff0000, v82
	v_lshlrev_b32_e32 v50, 16, v83
	v_and_b32_e32 v51, 0xffff0000, v83
	s_nop 1
	v_lshlrev_b32_e32 v16, 16, v70
	v_and_b32_e32 v17, 0xffff0000, v70
	v_lshlrev_b32_e32 v18, 16, v71
	v_and_b32_e32 v19, 0xffff0000, v71
	s_nop 1
	v_cmp_lt_i32_e32 vcc, 13, v166
	v_add_u32_e32 v86, 0xb00, v150
	v_mov_b32_dpp v195, v68 row_ror:1 row_mask:0xf bank_mask:0xf
	v_mov_b32_dpp v200, v69 row_ror:1 row_mask:0xf bank_mask:0xf
	v_mov_b32_dpp v198, v66 row_ror:1 row_mask:0xf bank_mask:0xf
	v_mov_b32_dpp v202, v67 row_ror:1 row_mask:0xf bank_mask:0xf
	v_mov_b32_dpp v199, v68 row_ror:2 row_mask:0xf bank_mask:0xf
	v_mov_b32_dpp v203, v69 row_ror:2 row_mask:0xf bank_mask:0xf
	v_mov_b32_dpp v205, v66 row_ror:2 row_mask:0xf bank_mask:0xf
	v_mov_b32_dpp v206, v67 row_ror:2 row_mask:0xf bank_mask:0xf
	v_mov_b32_dpp v79, v62 row_ror:1 row_mask:0xf bank_mask:0xf
	v_mov_b32_dpp v87, v63 row_ror:1 row_mask:0xf bank_mask:0xf
	v_mov_b32_dpp v82, v50 row_ror:1 row_mask:0xf bank_mask:0xf
	v_mov_b32_dpp v177, v51 row_ror:1 row_mask:0xf bank_mask:0xf
	v_mov_b32_dpp v83, v62 row_ror:2 row_mask:0xf bank_mask:0xf
	v_mov_b32_dpp v178, v63 row_ror:2 row_mask:0xf bank_mask:0xf
	v_mov_b32_dpp v179, v50 row_ror:2 row_mask:0xf bank_mask:0xf
	v_mov_b32_dpp v180, v51 row_ror:2 row_mask:0xf bank_mask:0xf
	v_mov_b32_dpp v181, v16 row_ror:1 row_mask:0xf bank_mask:0xf
	v_mov_b32_dpp v184, v17 row_ror:1 row_mask:0xf bank_mask:0xf
	v_mov_b32_dpp v182, v18 row_ror:1 row_mask:0xf bank_mask:0xf
	v_mov_b32_dpp v185, v19 row_ror:1 row_mask:0xf bank_mask:0xf
	v_mov_b32_dpp v183, v16 row_ror:2 row_mask:0xf bank_mask:0xf
	v_mov_b32_dpp v186, v17 row_ror:2 row_mask:0xf bank_mask:0xf
	v_mov_b32_dpp v187, v18 row_ror:2 row_mask:0xf bank_mask:0xf
	v_mov_b32_dpp v188, v19 row_ror:2 row_mask:0xf bank_mask:0xf
	s_and_saveexec_b64 s[0:1], vcc
	s_cbranch_execz .LBB0_553
	v_add_u32_e32 v136, v86, v44
	v_lshl_add_u64 v[20:21], v[136:137], 2, s[28:29]
	s_cmp_lg_u32 s99, 0
	s_cbranch_scc1 .Lwt546_13140
	global_store_dwordx4 v[20:21], v[16:19], off
	s_branch .Lwj546_13140
.Lwt546_13140:
	global_store_dwordx4 v[20:21], v[16:19], off sc1
; __device__ __forceinline__ f32x2 gelu_pk(f32x2 v) {
;     const f32x2 av = __builtin_elementwise_abs(v), d = av * 0.2316418882f + 1.0f;
;     __device__ __forceinline__ void operator()(AccRef acc, const Unit& u, int wr, int wc, int fr, int fq) const {
;     ...
;             for (int n = 0; n < 2; ++n) { const unsigned jn = (unsigned)(j0 + 4 * n);
;                 f32x4 cu[4];
;                 {
;                     const f32x4 wu0 = *(const f32x4*)(cw + (DFF + jn)), wu1 = *(const f32x4*)(cw + (UPN + DFF + jn)), wu2 = *(const f32x4*)(cw + (2 * UPN + DFF + jn)), bu = *(const f32x4*)(cb + (DFF + jn));
;                     f32x4 pu1 = (f32x4){0.f, 0.f, 0.f, 0.f}, pu2 = pu1;
; #pragma unroll
;                     for (int m = 0; m < 4; ++m) {
;                         const f32x4 au = unpack4(pa[ai][1][m][n]);
;                         const f32x4 ru1 = ror1v(au), ru2 = ror2v(au);
;                         const f32x4 u1 = fr >= 1 ? ru1 : pu1, u2 = fr >= 2 ? ru2 : pu2;
;                         if (m == 0 && fr < 2) *(f32x4*)(edge + (unsigned)((grp * 4 + fr) * UPN + DFF + jn)) = au;
;                         if (m == 3 && fr >= 14) *(f32x4*)(edge + (unsigned)((grp * 4 + (fr - 12)) * UPN + DFF + jn)) = au;
;                         cu[m] = bu + wu0 * u2 + wu1 * u1 + wu2 * au;
;                         pu1 = ru1; pu2 = ru2; }
;                 }
;                 {
;                     const f32x4 wg0 = *(const f32x4*)(cw + jn), wg1 = *(const f32x4*)(cw + (UPN + jn)), wg2 = *(const f32x4*)(cw + (2 * UPN + jn)), bg = *(const f32x4*)(cb + jn);
;                     f32x4 pg1 = (f32x4){0.f, 0.f, 0.f, 0.f}, pg2 = pg1;
; #pragma unroll
;                     for (int m = 0; m < 4; ++m) { const int row = rowg + m * 16 + fr;
;                         const f32x4 ag = unpack4(pa[ai][0][m][n]);
;                         const f32x4 rg1 = ror1v(ag), rg2 = ror2v(ag);
;                         const f32x4 g1 = fr >= 1 ? rg1 : pg1, g2 = fr >= 2 ? rg2 : pg2;
;                         if (m == 0 && fr < 2) *(f32x4*)(edge + (unsigned)((grp * 4 + fr) * UPN + jn)) = ag;
;                         if (m == 3 && fr >= 14) *(f32x4*)(edge + (unsigned)((grp * 4 + (fr - 12)) * UPN + jn)) = ag;
;                         const f32x4 o = gelu4(bg + wg0 * g2 + wg1 * g1 + wg2 * ag) * cu[m];
;                         if (!(m == 0 && fr < 2)) *(u32x2*)(act + (unsigned)(row * DFF + jn)) = pack4(o);
.Lwj546_13140:
.LBB0_553:
	s_or_b64 exec, exec, s[0:1]
	v_mov_b32_e32 v45, v137
	v_add_u32_e32 v136, 0x1600, v44
	v_lshlrev_b64 v[32:33], 2, v[44:45]
	v_lshl_add_u64 v[60:61], v[136:137], 2, s[66:67]
	v_add_u32_e32 v136, 0x2c00, v44
	v_lshl_add_u64 v[46:47], s[66:67], 0, v[32:33]
	v_lshl_add_u64 v[64:65], v[136:137], 2, s[66:67]
	v_lshl_add_u64 v[48:49], s[36:37], 0, v[32:33]
	global_load_dwordx4 v[28:31], v[46:47], off
	global_load_dwordx4 v[20:23], v[60:61], off
	global_load_dwordx4 v[24:27], v[64:65], off
	global_load_dwordx4 v[32:35], v[48:49], off
	v_lshlrev_b32_e32 v40, 16, v190
	v_and_b32_e32 v41, 0xffff0000, v190
	v_lshlrev_b32_e32 v42, 16, v189
	v_and_b32_e32 v43, 0xffff0000, v189
	s_nop 1
	v_cmp_lt_i32_e64 s[8:9], 0, v166
	v_cmp_lt_i32_e64 s[6:7], 1, v166
	v_mov_b32_dpp v70, v40 row_ror:1 row_mask:0xf bank_mask:0xf
	v_mov_b32_dpp v71, v41 row_ror:1 row_mask:0xf bank_mask:0xf
	v_mov_b32_dpp v72, v42 row_ror:1 row_mask:0xf bank_mask:0xf
	v_mov_b32_dpp v73, v43 row_ror:1 row_mask:0xf bank_mask:0xf
	v_mov_b32_dpp v74, v40 row_ror:2 row_mask:0xf bank_mask:0xf
	v_mov_b32_dpp v75, v41 row_ror:2 row_mask:0xf bank_mask:0xf
	v_mov_b32_dpp v76, v42 row_ror:2 row_mask:0xf bank_mask:0xf
	v_mov_b32_dpp v77, v43 row_ror:2 row_mask:0xf bank_mask:0xf
	s_and_saveexec_b64 s[0:1], s[10:11]
	s_xor_b64 s[76:77], exec, s[0:1]
	s_cbranch_execz .LBB0_555
	v_cndmask_b32_e64 v213, 0, v204, s[6:7]
	v_cndmask_b32_e64 v212, 0, v201, s[6:7]
	v_cndmask_b32_e64 v211, 0, v196, s[8:9]
	v_cndmask_b32_e64 v210, 0, v192, s[8:9]
	s_waitcnt vmcnt(4)
	v_pk_fma_f32 v[212:213], v[10:11], v[212:213], v[14:15]
	v_cndmask_b32_e64 v215, 0, v197, s[6:7]
	v_pk_fma_f32 v[210:211], v[2:3], v[210:211], v[212:213]
	v_cndmask_b32_e64 v214, 0, v193, s[6:7]
	v_pk_fma_f32 v[38:39], v[6:7], v[38:39], v[210:211]
	s_waitcnt vmcnt(0)
	v_pk_fma_f32 v[210:211], v[28:29], v[74:75], v[32:33]
	v_cndmask_b32_e64 v209, 0, v194, s[8:9]
	v_pk_fma_f32 v[210:211], v[20:21], v[70:71], v[210:211]
	v_cndmask_b32_e64 v208, 0, v191, s[8:9]
	v_pk_fma_f32 v[40:41], v[24:25], v[40:41], v[210:211]
	v_pk_fma_f32 v[214:215], v[8:9], v[214:215], v[12:13]
	v_and_b32_e32 v213, 0x7fffffff, v41
	v_and_b32_e32 v212, 0x7fffffff, v40
	v_pk_fma_f32 v[212:213], v[212:213], s[42:43], 1.0 op_sel_hi:[1,0,0]
	v_pk_fma_f32 v[208:209], v[0:1], v[208:209], v[214:215]
	v_rcp_f32_e32 v212, v212
	v_rcp_f32_e32 v213, v213
	v_pk_mul_f32 v[210:211], v[40:41], v[40:41]
	v_mov_b64_e32 v[214:215], s[54:55]
	v_pk_mul_f32 v[210:211], v[210:211], s[38:39] op_sel_hi:[1,0]
	v_pk_fma_f32 v[216:217], v[212:213], s[52:53], v[214:215] op_sel_hi:[1,0,0]
	v_exp_f32_e32 v210, v210
	v_exp_f32_e32 v211, v211
	v_pk_fma_f32 v[216:217], v[212:213], v[216:217], s[56:57] op_sel_hi:[1,1,0]
	v_pk_fma_f32 v[36:37], v[4:5], v[36:37], v[208:209]
	v_pk_fma_f32 v[216:217], v[212:213], v[216:217], s[62:63] op_sel_hi:[1,1,0]
	v_pk_fma_f32 v[208:209], v[30:31], v[76:77], v[34:35]
	v_pk_fma_f32 v[216:217], v[212:213], v[216:217], s[64:65] op_sel_hi:[1,1,0]
	v_pk_fma_f32 v[208:209], v[22:23], v[72:73], v[208:209]
	v_pk_mul_f32 v[212:213], v[212:213], v[216:217]
	v_cmp_gt_f32_e64 s[0:1], 0, v40
	v_pk_mul_f32 v[210:211], v[210:211], v[212:213]
	v_pk_fma_f32 v[42:43], v[26:27], v[42:43], v[208:209]
	v_pk_mul_f32 v[212:213], v[40:41], v[210:211]
	v_pk_fma_f32 v[210:211], v[40:41], v[210:211], v[40:41] neg_lo:[1,0,0] neg_hi:[1,0,0]
	v_pk_mul_f32 v[208:209], v[42:43], v[42:43]
	v_cndmask_b32_e64 v40, v210, v212, s[0:1]
	v_cmp_gt_f32_e64 s[0:1], 0, v41
	v_and_b32_e32 v210, 0x7fffffff, v42
	v_pk_mul_f32 v[208:209], v[208:209], s[38:39] op_sel_hi:[1,0]
	v_cndmask_b32_e64 v41, v211, v213, s[0:1]
	v_and_b32_e32 v211, 0x7fffffff, v43
	v_pk_fma_f32 v[210:211], v[210:211], s[42:43], 1.0 op_sel_hi:[1,0,0]
	v_exp_f32_e32 v208, v208
	v_rcp_f32_e32 v210, v210
	v_rcp_f32_e32 v211, v211
	v_exp_f32_e32 v209, v209
	v_cmp_gt_f32_e64 s[0:1], 0, v42
	v_pk_mul_f32 v[36:37], v[36:37], v[40:41]
	v_pk_fma_f32 v[212:213], v[210:211], s[52:53], v[214:215] op_sel_hi:[1,0,0]
	v_cvt_pk_bf16_f32 v36, v36, v37
	s_nop 0
	v_pk_fma_f32 v[212:213], v[210:211], v[212:213], s[56:57] op_sel_hi:[1,1,0]
	s_nop 0
	v_pk_fma_f32 v[212:213], v[210:211], v[212:213], s[62:63] op_sel_hi:[1,1,0]
	s_nop 0
	v_pk_fma_f32 v[212:213], v[210:211], v[212:213], s[64:65] op_sel_hi:[1,1,0]
	s_nop 0
	v_pk_mul_f32 v[210:211], v[210:211], v[212:213]
	s_nop 0
	v_pk_mul_f32 v[208:209], v[208:209], v[210:211]
	s_nop 0
	v_pk_mul_f32 v[210:211], v[42:43], v[208:209]
	v_pk_fma_f32 v[208:209], v[42:43], v[208:209], v[42:43] neg_lo:[1,0,0] neg_hi:[1,0,0]
	s_nop 0
	v_cndmask_b32_e64 v42, v208, v210, s[0:1]
	v_cmp_gt_f32_e64 s[0:1], 0, v43
	s_nop 1
	v_cndmask_b32_e64 v43, v209, v211, s[0:1]
	v_pk_mul_f32 v[38:39], v[38:39], v[42:43]
	s_nop 0
	v_cvt_pk_bf16_f32 v37, v38, v39
	v_mad_u64_u32 v[38:39], s[0:1], v146, s88, v[44:45]
	v_mov_b32_e32 v39, v137
	v_lshl_add_u64 v[38:39], v[38:39], 1, s[26:27]
	s_cmp_lg_u32 s99, 0
	s_cbranch_scc1 .Lwt546_13260
	global_store_dwordx2 v[38:39], v[36:37], off
	s_branch .Lwj546_13260
.Lwt546_13260:
	global_store_dwordx2 v[38:39], v[36:37], off sc1
.Lwj546_13260:
.LBB0_555:
	s_andn2_saveexec_b64 s[0:1], s[76:77]
	s_cbranch_execz .LBB0_557
	v_add_u32_e32 v136, v44, v152
	v_lshl_add_u64 v[36:37], v[136:137], 2, s[28:29]
	s_cmp_lg_u32 s99, 0
	s_cbranch_scc1 .Lwt546_13267
	global_store_dwordx4 v[36:37], v[40:43], off
	s_branch .Lwj546_13267
; __device__ __forceinline__ f32x2 gelu_pk(f32x2 v) {
;     const f32x2 av = __builtin_elementwise_abs(v), d = av * 0.2316418882f + 1.0f;
;     __device__ __forceinline__ void operator()(AccRef acc, const Unit& u, int wr, int wc, int fr, int fq) const {
;     ...
;             for (int n = 0; n < 2; ++n) { const unsigned jn = (unsigned)(j0 + 4 * n);
;                 f32x4 cu[4];
;                 {
;                     const f32x4 wu0 = *(const f32x4*)(cw + (DFF + jn)), wu1 = *(const f32x4*)(cw + (UPN + DFF + jn)), wu2 = *(const f32x4*)(cw + (2 * UPN + DFF + jn)), bu = *(const f32x4*)(cb + (DFF + jn));
;                     f32x4 pu1 = (f32x4){0.f, 0.f, 0.f, 0.f}, pu2 = pu1;
; #pragma unroll
;                     for (int m = 0; m < 4; ++m) {
;                         const f32x4 au = unpack4(pa[ai][1][m][n]);
;                         const f32x4 ru1 = ror1v(au), ru2 = ror2v(au);
;                         const f32x4 u1 = fr >= 1 ? ru1 : pu1, u2 = fr >= 2 ? ru2 : pu2;
;                         if (m == 0 && fr < 2) *(f32x4*)(edge + (unsigned)((grp * 4 + fr) * UPN + DFF + jn)) = au;
;                         if (m == 3 && fr >= 14) *(f32x4*)(edge + (unsigned)((grp * 4 + (fr - 12)) * UPN + DFF + jn)) = au;
;                         cu[m] = bu + wu0 * u2 + wu1 * u1 + wu2 * au;
;                         pu1 = ru1; pu2 = ru2; }
;                 }
;                 {
;                     const f32x4 wg0 = *(const f32x4*)(cw + jn), wg1 = *(const f32x4*)(cw + (UPN + jn)), wg2 = *(const f32x4*)(cw + (2 * UPN + jn)), bg = *(const f32x4*)(cb + jn);
;                     f32x4 pg1 = (f32x4){0.f, 0.f, 0.f, 0.f}, pg2 = pg1;
; #pragma unroll
;                     for (int m = 0; m < 4; ++m) { const int row = rowg + m * 16 + fr;
;                         const f32x4 ag = unpack4(pa[ai][0][m][n]);
;                         const f32x4 rg1 = ror1v(ag), rg2 = ror2v(ag);
;                         const f32x4 g1 = fr >= 1 ? rg1 : pg1, g2 = fr >= 2 ? rg2 : pg2;
;                         if (m == 0 && fr < 2) *(f32x4*)(edge + (unsigned)((grp * 4 + fr) * UPN + jn)) = ag;
;                         if (m == 3 && fr >= 14) *(f32x4*)(edge + (unsigned)((grp * 4 + (fr - 12)) * UPN + jn)) = ag;
;                         const f32x4 o = gelu4(bg + wg0 * g2 + wg1 * g1 + wg2 * ag) * cu[m];
;                         if (!(m == 0 && fr < 2)) *(u32x2*)(act + (unsigned)(row * DFF + jn)) = pack4(o);
.Lwt546_13267:
	global_store_dwordx4 v[36:37], v[40:43], off sc1
.Lwj546_13267:
.LBB0_557:
	s_or_b64 exec, exec, s[0:1]
	s_nop 0
	v_cndmask_b32_e64 v43, v197, v203, s[6:7]
	v_cndmask_b32_e64 v42, v193, v199, s[6:7]
	v_cndmask_b32_e64 v37, v194, v200, s[8:9]
	v_cndmask_b32_e64 v36, v191, v195, s[8:9]
	v_cndmask_b32_e64 v41, v204, v206, s[6:7]
	v_cndmask_b32_e64 v40, v201, v205, s[6:7]
	s_waitcnt vmcnt(4)
	v_pk_fma_f32 v[42:43], v[8:9], v[42:43], v[12:13]
	v_cndmask_b32_e64 v39, v196, v202, s[8:9]
	v_cndmask_b32_e64 v38, v192, v198, s[8:9]
	v_pk_fma_f32 v[40:41], v[10:11], v[40:41], v[14:15]
	v_pk_fma_f32 v[36:37], v[0:1], v[36:37], v[42:43]
	v_pk_fma_f32 v[38:39], v[2:3], v[38:39], v[40:41]
	v_pk_fma_f32 v[36:37], v[4:5], v[68:69], v[36:37]
	v_cndmask_b32_e64 v69, v203, v178, s[6:7]
	v_cndmask_b32_e64 v68, v199, v83, s[6:7]
	v_pk_fma_f32 v[38:39], v[6:7], v[66:67], v[38:39]
	v_cndmask_b32_e64 v41, v200, v87, s[8:9]
	v_cndmask_b32_e64 v40, v195, v79, s[8:9]
	v_cndmask_b32_e64 v67, v206, v180, s[6:7]
	v_cndmask_b32_e64 v66, v205, v179, s[6:7]
	v_pk_fma_f32 v[68:69], v[8:9], v[68:69], v[12:13]
	v_cndmask_b32_e64 v43, v202, v177, s[8:9]
	v_cndmask_b32_e64 v42, v198, v82, s[8:9]
	v_pk_fma_f32 v[66:67], v[10:11], v[66:67], v[14:15]
	v_pk_fma_f32 v[40:41], v[0:1], v[40:41], v[68:69]
	v_pk_fma_f32 v[42:43], v[2:3], v[42:43], v[66:67]
	v_pk_fma_f32 v[68:69], v[4:5], v[62:63], v[40:41]
	v_lshlrev_b32_e32 v40, 16, v175
	v_and_b32_e32 v41, 0xffff0000, v175
	s_nop 1
	v_pk_fma_f32 v[190:191], v[6:7], v[50:51], v[42:43]
	v_lshlrev_b32_e32 v42, 16, v174
	v_and_b32_e32 v43, 0xffff0000, v174
	s_nop 1
	v_mov_b32_dpp v193, v40 row_ror:2 row_mask:0xf bank_mask:0xf
	v_mov_b32_dpp v194, v41 row_ror:2 row_mask:0xf bank_mask:0xf
	v_mov_b32_dpp v174, v40 row_ror:1 row_mask:0xf bank_mask:0xf
	v_mov_b32_dpp v175, v41 row_ror:1 row_mask:0xf bank_mask:0xf
	v_cndmask_b32_e64 v67, v75, v194, s[6:7]
	v_cndmask_b32_e64 v66, v74, v193, s[6:7]
	v_cndmask_b32_e64 v63, v71, v175, s[8:9]
	v_cndmask_b32_e64 v62, v70, v174, s[8:9]
	s_waitcnt vmcnt(2)
	v_pk_fma_f32 v[66:67], v[28:29], v[66:67], v[32:33]
	s_nop 1
	v_pk_fma_f32 v[62:63], v[20:21], v[62:63], v[66:67]
	s_nop 1
	v_pk_fma_f32 v[40:41], v[24:25], v[40:41], v[62:63]
	s_nop 1
	v_and_b32_e32 v67, 0x7fffffff, v41
	v_and_b32_e32 v66, 0x7fffffff, v40
	v_pk_fma_f32 v[66:67], v[66:67], s[42:43], 1.0 op_sel_hi:[1,0,0]
	s_nop 1
	v_mov_b32_dpp v195, v42 row_ror:2 row_mask:0xf bank_mask:0xf
	v_mov_b32_dpp v196, v43 row_ror:2 row_mask:0xf bank_mask:0xf
	v_rcp_f32_e32 v66, v66
	v_rcp_f32_e32 v67, v67
	v_mov_b32_dpp v189, v42 row_ror:1 row_mask:0xf bank_mask:0xf
	v_mov_b32_dpp v192, v43 row_ror:1 row_mask:0xf bank_mask:0xf
	v_cndmask_b32_e64 v71, v77, v196, s[6:7]
	v_cndmask_b32_e64 v70, v76, v195, s[6:7]
	v_cndmask_b32_e64 v51, v73, v192, s[8:9]
	v_cndmask_b32_e64 v50, v72, v189, s[8:9]
	v_pk_fma_f32 v[70:71], v[30:31], v[70:71], v[34:35]
	v_pk_mul_f32 v[62:63], v[40:41], v[40:41]
	v_pk_fma_f32 v[50:51], v[22:23], v[50:51], v[70:71]
	v_mov_b64_e32 v[70:71], s[54:55]
	v_pk_mul_f32 v[62:63], v[62:63], s[38:39] op_sel_hi:[1,0]
	v_pk_fma_f32 v[72:73], v[66:67], s[52:53], v[70:71] op_sel_hi:[1,0,0]
	v_exp_f32_e32 v62, v62
	v_exp_f32_e32 v63, v63
	v_pk_fma_f32 v[72:73], v[66:67], v[72:73], s[56:57] op_sel_hi:[1,1,0]
	v_cmp_gt_f32_e64 s[0:1], 0, v40
	v_pk_fma_f32 v[72:73], v[66:67], v[72:73], s[62:63] op_sel_hi:[1,1,0]
	v_pk_fma_f32 v[42:43], v[26:27], v[42:43], v[50:51]
	v_pk_fma_f32 v[72:73], v[66:67], v[72:73], s[64:65] op_sel_hi:[1,1,0]
	v_pk_mul_f32 v[50:51], v[42:43], v[42:43]
	v_pk_mul_f32 v[66:67], v[66:67], v[72:73]
	v_pk_mul_f32 v[50:51], v[50:51], s[38:39] op_sel_hi:[1,0]
	v_pk_mul_f32 v[62:63], v[62:63], v[66:67]
	v_exp_f32_e32 v50, v50
	v_pk_mul_f32 v[66:67], v[40:41], v[62:63]
	v_pk_fma_f32 v[62:63], v[40:41], v[62:63], v[40:41] neg_lo:[1,0,0] neg_hi:[1,0,0]
	v_exp_f32_e32 v51, v51
	v_cndmask_b32_e64 v40, v62, v66, s[0:1]
	v_cmp_gt_f32_e64 s[0:1], 0, v41
	v_and_b32_e32 v62, 0x7fffffff, v42
	v_mul_lo_u32 v45, v148, s88
	v_cndmask_b32_e64 v41, v63, v67, s[0:1]
	v_and_b32_e32 v63, 0x7fffffff, v43
	v_pk_fma_f32 v[62:63], v[62:63], s[42:43], 1.0 op_sel_hi:[1,0,0]
	v_cmp_gt_f32_e64 s[0:1], 0, v42
	v_rcp_f32_e32 v62, v62
	v_rcp_f32_e32 v63, v63
	v_pk_mul_f32 v[36:37], v[36:37], v[40:41]
	v_add_u32_e32 v136, v45, v44
	v_cvt_pk_bf16_f32 v36, v36, v37
	v_pk_fma_f32 v[66:67], v[62:63], s[52:53], v[70:71] op_sel_hi:[1,0,0]
	s_nop 1
	v_pk_fma_f32 v[66:67], v[62:63], v[66:67], s[56:57] op_sel_hi:[1,1,0]
	s_nop 1
	v_pk_fma_f32 v[66:67], v[62:63], v[66:67], s[62:63] op_sel_hi:[1,1,0]
	s_nop 0
	v_pk_fma_f32 v[66:67], v[62:63], v[66:67], s[64:65] op_sel_hi:[1,1,0]
	s_nop 0
	v_pk_mul_f32 v[62:63], v[62:63], v[66:67]
	s_nop 1
	v_pk_mul_f32 v[50:51], v[50:51], v[62:63]
	s_nop 1
	v_pk_mul_f32 v[62:63], v[42:43], v[50:51]
	v_pk_fma_f32 v[50:51], v[42:43], v[50:51], v[42:43] neg_lo:[1,0,0] neg_hi:[1,0,0]
	s_nop 0
	v_cndmask_b32_e64 v42, v50, v62, s[0:1]
	v_cmp_gt_f32_e64 s[0:1], 0, v43
	s_nop 1
	v_cndmask_b32_e64 v43, v51, v63, s[0:1]
	v_pk_mul_f32 v[38:39], v[38:39], v[42:43]
	s_nop 1
	v_cvt_pk_bf16_f32 v37, v38, v39
	v_lshl_add_u64 v[38:39], v[136:137], 1, s[26:27]
	s_cmp_lg_u32 s99, 0
	s_cbranch_scc1 .Lwt546_13396
	global_store_dwordx2 v[38:39], v[36:37], off
	s_branch .Lwj546_13396

; __device__ __forceinline__ f32x2 gelu_pk(f32x2 v) {
;     const f32x2 av = __builtin_elementwise_abs(v), d = av * 0.2316418882f + 1.0f;
;     __device__ __forceinline__ void operator()(AccRef acc, const Unit& u, int wr, int wc, int fr, int fq) const {
;     ...
;             for (int n = 0; n < 2; ++n) { const unsigned jn = (unsigned)(j0 + 4 * n);
;                 f32x4 cu[4];
;                 {
;                     const f32x4 wu0 = *(const f32x4*)(cw + (DFF + jn)), wu1 = *(const f32x4*)(cw + (UPN + DFF + jn)), wu2 = *(const f32x4*)(cw + (2 * UPN + DFF + jn)), bu = *(const f32x4*)(cb + (DFF + jn));
;                     f32x4 pu1 = (f32x4){0.f, 0.f, 0.f, 0.f}, pu2 = pu1;
; #pragma unroll
;                     for (int m = 0; m < 4; ++m) {
;                         const f32x4 au = unpack4(pa[ai][1][m][n]);
;                         const f32x4 ru1 = ror1v(au), ru2 = ror2v(au);
;                         const f32x4 u1 = fr >= 1 ? ru1 : pu1, u2 = fr >= 2 ? ru2 : pu2;
;                         if (m == 0 && fr < 2) *(f32x4*)(edge + (unsigned)((grp * 4 + fr) * UPN + DFF + jn)) = au;
;                         if (m == 3 && fr >= 14) *(f32x4*)(edge + (unsigned)((grp * 4 + (fr - 12)) * UPN + DFF + jn)) = au;
;                         cu[m] = bu + wu0 * u2 + wu1 * u1 + wu2 * au;
;                         pu1 = ru1; pu2 = ru2; }
;                 }
;                 {
;                     const f32x4 wg0 = *(const f32x4*)(cw + jn), wg1 = *(const f32x4*)(cw + (UPN + jn)), wg2 = *(const f32x4*)(cw + (2 * UPN + jn)), bg = *(const f32x4*)(cb + jn);
;                     f32x4 pg1 = (f32x4){0.f, 0.f, 0.f, 0.f}, pg2 = pg1;
; #pragma unroll
;                     for (int m = 0; m < 4; ++m) { const int row = rowg + m * 16 + fr;
;                         const f32x4 ag = unpack4(pa[ai][0][m][n]);
;                         const f32x4 rg1 = ror1v(ag), rg2 = ror2v(ag);
;                         const f32x4 g1 = fr >= 1 ? rg1 : pg1, g2 = fr >= 2 ? rg2 : pg2;
;                         if (m == 0 && fr < 2) *(f32x4*)(edge + (unsigned)((grp * 4 + fr) * UPN + jn)) = ag;
;                         if (m == 3 && fr >= 14) *(f32x4*)(edge + (unsigned)((grp * 4 + (fr - 12)) * UPN + jn)) = ag;
;                         const f32x4 o = gelu4(bg + wg0 * g2 + wg1 * g1 + wg2 * ag) * cu[m];
;                         if (!(m == 0 && fr < 2)) *(u32x2*)(act + (unsigned)(row * DFF + jn)) = pack4(o);
.Lwj546_13396:
	v_lshlrev_b32_e32 v36, 16, v173
	v_and_b32_e32 v37, 0xffff0000, v173
	s_nop 1
	v_mov_b32_dpp v43, v36 row_ror:2 row_mask:0xf bank_mask:0xf
	v_mov_b32_dpp v40, v36 row_ror:1 row_mask:0xf bank_mask:0xf
	v_mov_b32_dpp v63, v37 row_ror:2 row_mask:0xf bank_mask:0xf
	v_mov_b32_dpp v41, v37 row_ror:1 row_mask:0xf bank_mask:0xf
	v_cndmask_b32_e64 v77, v194, v63, s[6:7]
	v_cndmask_b32_e64 v76, v193, v43, s[6:7]
	v_cndmask_b32_e64 v75, v175, v41, s[8:9]
	v_cndmask_b32_e64 v74, v174, v40, s[8:9]
	v_pk_fma_f32 v[76:77], v[28:29], v[76:77], v[32:33]
	v_lshlrev_b32_e32 v38, 16, v172
	v_pk_fma_f32 v[74:75], v[20:21], v[74:75], v[76:77]
	v_and_b32_e32 v39, 0xffff0000, v172
	v_pk_fma_f32 v[36:37], v[24:25], v[36:37], v[74:75]
	s_nop 1
	v_and_b32_e32 v77, 0x7fffffff, v37
	v_and_b32_e32 v76, 0x7fffffff, v36
	v_pk_fma_f32 v[76:77], v[76:77], s[42:43], 1.0 op_sel_hi:[1,0,0]
	v_mov_b32_dpp v50, v38 row_ror:2 row_mask:0xf bank_mask:0xf
	v_rcp_f32_e32 v76, v76
	v_rcp_f32_e32 v77, v77
	v_mov_b32_dpp v66, v39 row_ror:2 row_mask:0xf bank_mask:0xf
	v_mov_b32_dpp v42, v38 row_ror:1 row_mask:0xf bank_mask:0xf
	v_mov_b32_dpp v62, v39 row_ror:1 row_mask:0xf bank_mask:0xf
	v_cndmask_b32_e64 v173, v196, v66, s[6:7]
	v_cndmask_b32_e64 v172, v195, v50, s[6:7]
	v_cndmask_b32_e64 v73, v192, v62, s[8:9]
	v_cndmask_b32_e64 v72, v189, v42, s[8:9]
	v_pk_fma_f32 v[172:173], v[30:31], v[172:173], v[34:35]
	v_pk_mul_f32 v[74:75], v[36:37], v[36:37]
	v_pk_fma_f32 v[72:73], v[22:23], v[72:73], v[172:173]
	v_pk_mul_f32 v[74:75], v[74:75], s[38:39] op_sel_hi:[1,0]
	v_pk_fma_f32 v[172:173], v[76:77], s[52:53], v[70:71] op_sel_hi:[1,0,0]
	v_exp_f32_e32 v74, v74
	v_exp_f32_e32 v75, v75
	v_pk_fma_f32 v[172:173], v[76:77], v[172:173], s[56:57] op_sel_hi:[1,1,0]
	v_cmp_gt_f32_e64 s[0:1], 0, v36
	v_pk_fma_f32 v[172:173], v[76:77], v[172:173], s[62:63] op_sel_hi:[1,1,0]
	v_pk_fma_f32 v[38:39], v[26:27], v[38:39], v[72:73]
	v_pk_fma_f32 v[172:173], v[76:77], v[172:173], s[64:65] op_sel_hi:[1,1,0]
	v_pk_mul_f32 v[72:73], v[38:39], v[38:39]
	v_pk_mul_f32 v[76:77], v[76:77], v[172:173]
	v_pk_mul_f32 v[72:73], v[72:73], s[38:39] op_sel_hi:[1,0]
	v_pk_mul_f32 v[74:75], v[74:75], v[76:77]
	v_exp_f32_e32 v72, v72
	v_pk_mul_f32 v[76:77], v[36:37], v[74:75]
	v_pk_fma_f32 v[74:75], v[36:37], v[74:75], v[36:37] neg_lo:[1,0,0] neg_hi:[1,0,0]
	v_exp_f32_e32 v73, v73
	v_cndmask_b32_e64 v36, v74, v76, s[0:1]
	v_cmp_gt_f32_e64 s[0:1], 0, v37
	v_and_b32_e32 v74, 0x7fffffff, v38
	v_add_u32_e32 v51, 0xb000, v45
	v_cndmask_b32_e64 v37, v75, v77, s[0:1]
	v_and_b32_e32 v75, 0x7fffffff, v39
	v_pk_fma_f32 v[74:75], v[74:75], s[42:43], 1.0 op_sel_hi:[1,0,0]
	v_cmp_gt_f32_e64 s[0:1], 0, v38
	v_rcp_f32_e32 v74, v74
	v_rcp_f32_e32 v75, v75
	v_pk_mul_f32 v[36:37], v[68:69], v[36:37]
	v_add_u32_e32 v136, v51, v44
	v_cvt_pk_bf16_f32 v36, v36, v37
	v_pk_fma_f32 v[70:71], v[74:75], s[52:53], v[70:71] op_sel_hi:[1,0,0]
	s_nop 1
	v_pk_fma_f32 v[70:71], v[74:75], v[70:71], s[56:57] op_sel_hi:[1,1,0]
	s_nop 1
	v_pk_fma_f32 v[70:71], v[74:75], v[70:71], s[62:63] op_sel_hi:[1,1,0]
	s_nop 0
	v_pk_fma_f32 v[70:71], v[74:75], v[70:71], s[64:65] op_sel_hi:[1,1,0]
	s_nop 0
	v_pk_mul_f32 v[70:71], v[74:75], v[70:71]
	s_nop 1
	v_pk_mul_f32 v[70:71], v[72:73], v[70:71]
	s_nop 0
	v_pk_mul_f32 v[72:73], v[38:39], v[70:71]
	v_pk_fma_f32 v[70:71], v[38:39], v[70:71], v[38:39] neg_lo:[1,0,0] neg_hi:[1,0,0]
	s_nop 0
	v_cndmask_b32_e64 v38, v70, v72, s[0:1]
	v_cmp_gt_f32_e64 s[0:1], 0, v39
	s_nop 1
	v_cndmask_b32_e64 v39, v71, v73, s[0:1]
	v_pk_mul_f32 v[38:39], v[190:191], v[38:39]
	s_nop 1
	v_cvt_pk_bf16_f32 v37, v38, v39
	v_lshl_add_u64 v[38:39], v[136:137], 1, s[26:27]
	s_cmp_lg_u32 s99, 0
	s_cbranch_scc1 .Lwt546_13487
	global_store_dwordx2 v[38:39], v[36:37], off
	s_branch .Lwj546_13487

; __device__ __forceinline__ f32x2 gelu_pk(f32x2 v) {
;     const f32x2 av = __builtin_elementwise_abs(v), d = av * 0.2316418882f + 1.0f;
;     __device__ __forceinline__ void operator()(AccRef acc, const Unit& u, int wr, int wc, int fr, int fq) const {
;     ...
;             for (int n = 0; n < 2; ++n) { const unsigned jn = (unsigned)(j0 + 4 * n);
;                 f32x4 cu[4];
;                 {
;                     const f32x4 wu0 = *(const f32x4*)(cw + (DFF + jn)), wu1 = *(const f32x4*)(cw + (UPN + DFF + jn)), wu2 = *(const f32x4*)(cw + (2 * UPN + DFF + jn)), bu = *(const f32x4*)(cb + (DFF + jn));
;                     f32x4 pu1 = (f32x4){0.f, 0.f, 0.f, 0.f}, pu2 = pu1;
; #pragma unroll
;                     for (int m = 0; m < 4; ++m) {
;                         const f32x4 au = unpack4(pa[ai][1][m][n]);
;                         const f32x4 ru1 = ror1v(au), ru2 = ror2v(au);
;                         const f32x4 u1 = fr >= 1 ? ru1 : pu1, u2 = fr >= 2 ? ru2 : pu2;
;                         if (m == 0 && fr < 2) *(f32x4*)(edge + (unsigned)((grp * 4 + fr) * UPN + DFF + jn)) = au;
;                         if (m == 3 && fr >= 14) *(f32x4*)(edge + (unsigned)((grp * 4 + (fr - 12)) * UPN + DFF + jn)) = au;
;                         cu[m] = bu + wu0 * u2 + wu1 * u1 + wu2 * au;
;                         pu1 = ru1; pu2 = ru2; }
;                 }
;                 {
;                     const f32x4 wg0 = *(const f32x4*)(cw + jn), wg1 = *(const f32x4*)(cw + (UPN + jn)), wg2 = *(const f32x4*)(cw + (2 * UPN + jn)), bg = *(const f32x4*)(cb + jn);
;                     f32x4 pg1 = (f32x4){0.f, 0.f, 0.f, 0.f}, pg2 = pg1;
; #pragma unroll
;                     for (int m = 0; m < 4; ++m) { const int row = rowg + m * 16 + fr;
;                         const f32x4 ag = unpack4(pa[ai][0][m][n]);
;                         const f32x4 rg1 = ror1v(ag), rg2 = ror2v(ag);
;                         const f32x4 g1 = fr >= 1 ? rg1 : pg1, g2 = fr >= 2 ? rg2 : pg2;
;                         if (m == 0 && fr < 2) *(f32x4*)(edge + (unsigned)((grp * 4 + fr) * UPN + jn)) = ag;
;                         if (m == 3 && fr >= 14) *(f32x4*)(edge + (unsigned)((grp * 4 + (fr - 12)) * UPN + jn)) = ag;
;                         const f32x4 o = gelu4(bg + wg0 * g2 + wg1 * g1 + wg2 * ag) * cu[m];
;                         if (!(m == 0 && fr < 2)) *(u32x2*)(act + (unsigned)(row * DFF + jn)) = pack4(o);
.Lwj546_13487:
	v_lshlrev_b32_e32 v36, 16, v80
	v_and_b32_e32 v37, 0xffff0000, v80
	v_lshlrev_b32_e32 v38, 16, v81
	v_and_b32_e32 v39, 0xffff0000, v81
	s_nop 1
	v_mov_b32_dpp v67, v36 row_ror:1 row_mask:0xf bank_mask:0xf
	v_mov_b32_dpp v68, v37 row_ror:1 row_mask:0xf bank_mask:0xf
	v_mov_b32_dpp v69, v38 row_ror:1 row_mask:0xf bank_mask:0xf
	v_mov_b32_dpp v72, v39 row_ror:1 row_mask:0xf bank_mask:0xf
	v_mov_b32_dpp v70, v36 row_ror:2 row_mask:0xf bank_mask:0xf
	v_mov_b32_dpp v73, v37 row_ror:2 row_mask:0xf bank_mask:0xf
	v_mov_b32_dpp v71, v38 row_ror:2 row_mask:0xf bank_mask:0xf
	v_mov_b32_dpp v74, v39 row_ror:2 row_mask:0xf bank_mask:0xf
	s_and_saveexec_b64 s[0:1], vcc
	s_cbranch_execz .LBB0_559
	v_add_u32_e32 v136, v150, v44
	v_lshl_add_u64 v[76:77], v[136:137], 2, s[28:29]
	s_cmp_lg_u32 s99, 0
	s_cbranch_scc1 .Lwt546_13506
	global_store_dwordx4 v[76:77], v[36:39], off
	s_branch .Lwj546_13506
.Lwt546_13506:
	global_store_dwordx4 v[76:77], v[36:39], off sc1
.Lwj546_13506:
.LBB0_559:
	s_or_b64 exec, exec, s[0:1]
	v_cndmask_b32_e64 v77, v62, v72, s[8:9]
	v_cndmask_b32_e64 v76, v42, v69, s[8:9]
	v_cndmask_b32_e64 v62, v43, v70, s[6:7]
	v_cndmask_b32_e64 v42, v50, v71, s[6:7]
	v_cndmask_b32_e64 v71, v180, v188, s[6:7]
	v_cndmask_b32_e64 v70, v179, v187, s[6:7]
	v_cndmask_b32_e64 v41, v41, v68, s[8:9]
	v_cndmask_b32_e64 v69, v177, v185, s[8:9]
	v_cndmask_b32_e64 v68, v82, v182, s[8:9]
	v_pk_fma_f32 v[10:11], v[10:11], v[70:71], v[14:15]
	v_cndmask_b32_e64 v63, v63, v73, s[6:7]
	v_pk_fma_f32 v[2:3], v[2:3], v[68:69], v[10:11]
	v_cndmask_b32_e64 v40, v40, v67, s[8:9]
	v_pk_fma_f32 v[2:3], v[6:7], v[18:19], v[2:3]
	v_pk_fma_f32 v[6:7], v[28:29], v[62:63], v[32:33]
	v_cndmask_b32_e64 v73, v178, v186, s[6:7]
	v_pk_fma_f32 v[6:7], v[20:21], v[40:41], v[6:7]
	v_cndmask_b32_e64 v72, v83, v183, s[6:7]
	v_pk_fma_f32 v[6:7], v[24:25], v[36:37], v[6:7]
	v_pk_fma_f32 v[8:9], v[8:9], v[72:73], v[12:13]
	v_and_b32_e32 v13, 0x7fffffff, v7
	v_and_b32_e32 v12, 0x7fffffff, v6
	v_pk_fma_f32 v[12:13], v[12:13], s[42:43], 1.0 op_sel_hi:[1,0,0]
	v_cndmask_b32_e64 v43, v66, v74, s[6:7]
	v_rcp_f32_e32 v12, v12
	v_rcp_f32_e32 v13, v13
	v_cndmask_b32_e64 v67, v87, v184, s[8:9]
	v_cndmask_b32_e64 v66, v79, v181, s[8:9]
	v_pk_fma_f32 v[0:1], v[0:1], v[66:67], v[8:9]
	v_pk_mul_f32 v[10:11], v[6:7], v[6:7]
	v_mov_b64_e32 v[14:15], s[54:55]
	v_pk_fma_f32 v[0:1], v[4:5], v[16:17], v[0:1]
	v_pk_mul_f32 v[10:11], v[10:11], s[38:39] op_sel_hi:[1,0]
	v_pk_fma_f32 v[16:17], v[12:13], s[52:53], v[14:15] op_sel_hi:[1,0,0]
	v_exp_f32_e32 v10, v10
	v_exp_f32_e32 v11, v11
	v_pk_fma_f32 v[16:17], v[12:13], v[16:17], s[56:57] op_sel_hi:[1,1,0]
	v_pk_fma_f32 v[4:5], v[30:31], v[42:43], v[34:35]
	v_pk_fma_f32 v[16:17], v[12:13], v[16:17], s[62:63] op_sel_hi:[1,1,0]
	v_pk_fma_f32 v[4:5], v[22:23], v[76:77], v[4:5]
	v_pk_fma_f32 v[16:17], v[12:13], v[16:17], s[64:65] op_sel_hi:[1,1,0]
	v_cmp_gt_f32_e64 s[0:1], 0, v6
	v_pk_mul_f32 v[12:13], v[12:13], v[16:17]
	v_pk_fma_f32 v[4:5], v[26:27], v[38:39], v[4:5]
	v_pk_mul_f32 v[10:11], v[10:11], v[12:13]
	v_pk_mul_f32 v[8:9], v[4:5], v[4:5]
	v_pk_mul_f32 v[12:13], v[6:7], v[10:11]
	v_pk_fma_f32 v[10:11], v[6:7], v[10:11], v[6:7] neg_lo:[1,0,0] neg_hi:[1,0,0]
	v_pk_mul_f32 v[8:9], v[8:9], s[38:39] op_sel_hi:[1,0]
	v_cndmask_b32_e64 v6, v10, v12, s[0:1]
	v_cmp_gt_f32_e64 s[0:1], 0, v7
	v_and_b32_e32 v10, 0x7fffffff, v4
	v_exp_f32_e32 v8, v8
	v_cndmask_b32_e64 v7, v11, v13, s[0:1]
	v_and_b32_e32 v11, 0x7fffffff, v5
	v_pk_fma_f32 v[10:11], v[10:11], s[42:43], 1.0 op_sel_hi:[1,0,0]
	v_exp_f32_e32 v9, v9
	v_rcp_f32_e32 v10, v10
	v_rcp_f32_e32 v11, v11
	v_cmp_gt_f32_e64 s[0:1], 0, v4
	v_add_u32_e32 v148, 0xb000, v51
	v_pk_mul_f32 v[0:1], v[0:1], v[6:7]
	v_pk_fma_f32 v[12:13], v[10:11], s[52:53], v[14:15] op_sel_hi:[1,0,0]
	v_add_u32_e32 v136, v148, v44
	v_pk_fma_f32 v[12:13], v[10:11], v[12:13], s[56:57] op_sel_hi:[1,1,0]
	v_cvt_pk_bf16_f32 v0, v0, v1
	v_lshlrev_b32_e32 v36, 16, v170
	v_pk_fma_f32 v[12:13], v[10:11], v[12:13], s[62:63] op_sel_hi:[1,1,0]
	v_and_b32_e32 v37, 0xffff0000, v170
	v_pk_fma_f32 v[12:13], v[10:11], v[12:13], s[64:65] op_sel_hi:[1,1,0]
	v_lshlrev_b32_e32 v38, 16, v171
	v_pk_mul_f32 v[10:11], v[10:11], v[12:13]
	v_and_b32_e32 v39, 0xffff0000, v171
	v_pk_mul_f32 v[8:9], v[8:9], v[10:11]
	s_nop 1
	v_pk_mul_f32 v[10:11], v[4:5], v[8:9]
	v_pk_fma_f32 v[8:9], v[4:5], v[8:9], v[4:5] neg_lo:[1,0,0] neg_hi:[1,0,0]
	s_nop 1
	v_cndmask_b32_e64 v4, v8, v10, s[0:1]
	v_cmp_gt_f32_e64 s[0:1], 0, v5
	s_nop 1
	v_cndmask_b32_e64 v5, v9, v11, s[0:1]
	v_pk_mul_f32 v[2:3], v[2:3], v[4:5]
	s_nop 1
	v_cvt_pk_bf16_f32 v1, v2, v3
	v_lshl_add_u64 v[2:3], v[136:137], 1, s[26:27]
	v_add_u32_e32 v136, 0xb04, v44
	v_lshlrev_b64 v[12:13], 2, v[136:137]
	v_add_u32_e32 v136, 0x2104, v44
	v_lshl_add_u64 v[66:67], v[136:137], 2, s[66:67]
	v_add_u32_e32 v136, 0x3704, v44
	s_cmp_lg_u32 s99, 0
	s_cbranch_scc1 .Lwt546_13604
	global_store_dwordx2 v[2:3], v[0:1], off
	s_branch .Lwj546_13604
.Lwt546_13604:
	global_store_dwordx2 v[2:3], v[0:1], off sc1
.Lwj546_13604:
	v_lshl_add_u64 v[62:63], s[66:67], 0, v[12:13]
	v_lshl_add_u64 v[68:69], v[136:137], 2, s[66:67]
	v_lshl_add_u64 v[70:71], s[36:37], 0, v[12:13]
	global_load_dwordx4 v[8:11], v[62:63], off
	global_load_dwordx4 v[0:3], v[66:67], off
	global_load_dwordx4 v[4:7], v[68:69], off
	global_load_dwordx4 v[12:15], v[70:71], off
	s_nop 1
	v_or_b32_e32 v50, 4, v44
	v_mov_b32_dpp v188, v36 row_ror:1 row_mask:0xf bank_mask:0xf
	v_mov_b32_dpp v194, v37 row_ror:1 row_mask:0xf bank_mask:0xf
	v_mov_b32_dpp v191, v38 row_ror:1 row_mask:0xf bank_mask:0xf
	v_mov_b32_dpp v197, v39 row_ror:1 row_mask:0xf bank_mask:0xf
	v_mov_b32_dpp v192, v36 row_ror:2 row_mask:0xf bank_mask:0xf
	v_mov_b32_dpp v198, v37 row_ror:2 row_mask:0xf bank_mask:0xf
	v_mov_b32_dpp v200, v38 row_ror:2 row_mask:0xf bank_mask:0xf
	v_mov_b32_dpp v202, v39 row_ror:2 row_mask:0xf bank_mask:0xf
	s_and_saveexec_b64 s[0:1], s[12:13]
	s_cbranch_execz .LBB0_561
	v_add_u32_e32 v136, v50, v78
	v_lshl_add_u64 v[16:17], v[136:137], 2, s[28:29]
	s_cmp_lg_u32 s99, 0
	s_cbranch_scc1 .Lwt546_13627
	global_store_dwordx4 v[16:17], v[36:39], off
	s_branch .Lwj546_13627

; __device__ __forceinline__ f32x4 ror1v(f32x4 v) { return (f32x4){dpp_ror1(v[0]), dpp_ror1(v[1]), dpp_ror1(v[2]), dpp_ror1(v[3])}; }
;     __device__ __forceinline__ void operator()(AccRef acc, const Unit& u, int wr, int wc, int fr, int fq) const {
;     ...
;             for (int n = 0; n < 2; ++n) { const unsigned jn = (unsigned)(j0 + 4 * n);
;                 f32x4 cu[4];
;                 {
;                     const f32x4 wu0 = *(const f32x4*)(cw + (DFF + jn)), wu1 = *(const f32x4*)(cw + (UPN + DFF + jn)), wu2 = *(const f32x4*)(cw + (2 * UPN + DFF + jn)), bu = *(const f32x4*)(cb + (DFF + jn));
;                     f32x4 pu1 = (f32x4){0.f, 0.f, 0.f, 0.f}, pu2 = pu1;
; #pragma unroll
;                     for (int m = 0; m < 4; ++m) {
;                         const f32x4 au = unpack4(pa[ai][1][m][n]);
;                         const f32x4 ru1 = ror1v(au), ru2 = ror2v(au);
;                         const f32x4 u1 = fr >= 1 ? ru1 : pu1, u2 = fr >= 2 ? ru2 : pu2;
;                         if (m == 0 && fr < 2) *(f32x4*)(edge + (unsigned)((grp * 4 + fr) * UPN + DFF + jn)) = au;
;                         if (m == 3 && fr >= 14) *(f32x4*)(edge + (unsigned)((grp * 4 + (fr - 12)) * UPN + DFF + jn)) = au;
;                         cu[m] = bu + wu0 * u2 + wu1 * u1 + wu2 * au;
;                         pu1 = ru1; pu2 = ru2; }
;                 }
;                 {
;                     const f32x4 wg0 = *(const f32x4*)(cw + jn), wg1 = *(const f32x4*)(cw + (UPN + jn)), wg2 = *(const f32x4*)(cw + (2 * UPN + jn)), bg = *(const f32x4*)(cb + jn);
;                     f32x4 pg1 = (f32x4){0.f, 0.f, 0.f, 0.f}, pg2 = pg1;
; #pragma unroll
;                     for (int m = 0; m < 4; ++m) { const int row = rowg + m * 16 + fr;
;                         const f32x4 ag = unpack4(pa[ai][0][m][n]);
;                         const f32x4 rg1 = ror1v(ag), rg2 = ror2v(ag);
;                         const f32x4 g1 = fr >= 1 ? rg1 : pg1, g2 = fr >= 2 ? rg2 : pg2;
;                         if (m == 0 && fr < 2) *(f32x4*)(edge + (unsigned)((grp * 4 + fr) * UPN + jn)) = ag;
;                         if (m == 3 && fr >= 14) *(f32x4*)(edge + (unsigned)((grp * 4 + (fr - 12)) * UPN + jn)) = ag;
;                         const f32x4 o = gelu4(bg + wg0 * g2 + wg1 * g1 + wg2 * ag) * cu[m];
;                         if (!(m == 0 && fr < 2)) *(u32x2*)(act + (unsigned)(row * DFF + jn)) = pack4(o);
.Lwj546_13627:
.LBB0_561:
	s_or_b64 exec, exec, s[0:1]
	v_lshlrev_b32_e32 v82, 16, v89
	v_and_b32_e32 v83, 0xffff0000, v89
	v_lshlrev_b32_e32 v80, 16, v88
	v_and_b32_e32 v81, 0xffff0000, v88
	s_nop 1
	v_lshlrev_b32_e32 v78, 16, v90
	v_and_b32_e32 v79, 0xffff0000, v90
	v_lshlrev_b32_e32 v76, 16, v91
	v_and_b32_e32 v77, 0xffff0000, v91
	s_nop 1
	v_lshlrev_b32_e32 v16, 16, v84
	v_and_b32_e32 v17, 0xffff0000, v84
	v_lshlrev_b32_e32 v18, 16, v85
	v_and_b32_e32 v19, 0xffff0000, v85
	s_nop 1
	v_mov_b32_dpp v187, v82 row_ror:1 row_mask:0xf bank_mask:0xf
	v_mov_b32_dpp v193, v83 row_ror:1 row_mask:0xf bank_mask:0xf
	v_mov_b32_dpp v189, v80 row_ror:1 row_mask:0xf bank_mask:0xf
	v_mov_b32_dpp v195, v81 row_ror:1 row_mask:0xf bank_mask:0xf
	v_mov_b32_dpp v190, v82 row_ror:2 row_mask:0xf bank_mask:0xf
	v_mov_b32_dpp v196, v83 row_ror:2 row_mask:0xf bank_mask:0xf
	v_mov_b32_dpp v199, v80 row_ror:2 row_mask:0xf bank_mask:0xf
	v_mov_b32_dpp v201, v81 row_ror:2 row_mask:0xf bank_mask:0xf
	v_mov_b32_dpp v170, v78 row_ror:1 row_mask:0xf bank_mask:0xf
	v_mov_b32_dpp v173, v79 row_ror:1 row_mask:0xf bank_mask:0xf
	v_mov_b32_dpp v171, v76 row_ror:1 row_mask:0xf bank_mask:0xf
	v_mov_b32_dpp v174, v77 row_ror:1 row_mask:0xf bank_mask:0xf
	v_mov_b32_dpp v172, v78 row_ror:2 row_mask:0xf bank_mask:0xf
	v_mov_b32_dpp v175, v79 row_ror:2 row_mask:0xf bank_mask:0xf
	v_mov_b32_dpp v177, v76 row_ror:2 row_mask:0xf bank_mask:0xf
	v_mov_b32_dpp v178, v77 row_ror:2 row_mask:0xf bank_mask:0xf
	v_mov_b32_dpp v179, v16 row_ror:1 row_mask:0xf bank_mask:0xf
	v_mov_b32_dpp v182, v17 row_ror:1 row_mask:0xf bank_mask:0xf
	v_mov_b32_dpp v180, v18 row_ror:1 row_mask:0xf bank_mask:0xf
	v_mov_b32_dpp v183, v19 row_ror:1 row_mask:0xf bank_mask:0xf
	v_mov_b32_dpp v181, v16 row_ror:2 row_mask:0xf bank_mask:0xf
	v_mov_b32_dpp v184, v17 row_ror:2 row_mask:0xf bank_mask:0xf
	v_mov_b32_dpp v185, v18 row_ror:2 row_mask:0xf bank_mask:0xf
	v_mov_b32_dpp v186, v19 row_ror:2 row_mask:0xf bank_mask:0xf
	s_and_saveexec_b64 s[0:1], vcc
	s_cbranch_execz .LBB0_563
	v_add_u32_e32 v136, v86, v50
	v_lshl_add_u64 v[20:21], v[136:137], 2, s[28:29]
	s_cmp_lg_u32 s99, 0
	s_cbranch_scc1 .Lwt546_13674
	global_store_dwordx4 v[20:21], v[16:19], off
	s_branch .Lwj546_13674

; __device__ __forceinline__ f32x4 gelu4(f32x4 v) { const f32x2 a = gelu_pk((f32x2){v[0], v[1]}), b = gelu_pk((f32x2){v[2], v[3]}); return (f32x4){a.x, a.y, b.x, b.y}; }
; __device__ __forceinline__ f32x4 ror1v(f32x4 v) { return (f32x4){dpp_ror1(v[0]), dpp_ror1(v[1]), dpp_ror1(v[2]), dpp_ror1(v[3])}; }
; __device__ __forceinline__ f32x4 ror2v(f32x4 v) { return (f32x4){dpp_ror2(v[0]), dpp_ror2(v[1]), dpp_ror2(v[2]), dpp_ror2(v[3])}; }
; __device__ __forceinline__ u32x2 pack4(f32x4 v) { return (u32x2){pk2(v[0], v[1]), pk2(v[2], v[3])}; }
; __device__ __forceinline__ f32x2 gelu_pk(f32x2 v) {
;     const f32x2 av = __builtin_elementwise_abs(v), d = av * 0.2316418882f + 1.0f;
;     f32x2 t; t.x = __builtin_amdgcn_rcpf(d.x); t.y = __builtin_amdgcn_rcpf(d.y);
;     f32x2 q = t * 0.5307027145f + (-0.7265760135f); q = q * t + 0.7107068705f; q = q * t + (-0.142248368f); q = q * t + 0.127414796f; q = q * t;
;     const f32x2 s = (v * v) * (-0.72134752044f);
;     f32x2 e; e.x = __builtin_amdgcn_exp2f(s.x); e.y = __builtin_amdgcn_exp2f(s.y);
;     const f32x2 m = v * (q * e), r = v - m;
;     f32x2 o; o.x = v.x < 0.f ? m.x : r.x; o.y = v.y < 0.f ? m.y : r.y; return o;
;     __device__ __forceinline__ void operator()(AccRef acc, const Unit& u, int wr, int wc, int fr, int fq) const {
;     ...
;                     const f32x4 wg0 = *(const f32x4*)(cw + jn), wg1 = *(const f32x4*)(cw + (UPN + jn)), wg2 = *(const f32x4*)(cw + (2 * UPN + jn)), bg = *(const f32x4*)(cb + jn);
;                     f32x4 pg1 = (f32x4){0.f, 0.f, 0.f, 0.f}, pg2 = pg1;
; #pragma unroll
;                     for (int m = 0; m < 4; ++m) { const int row = rowg + m * 16 + fr;
;                         const f32x4 ag = unpack4(pa[ai][0][m][n]);
;                         const f32x4 rg1 = ror1v(ag), rg2 = ror2v(ag);
;                         const f32x4 g1 = fr >= 1 ? rg1 : pg1, g2 = fr >= 2 ? rg2 : pg2;
;                         if (m == 0 && fr < 2) *(f32x4*)(edge + (unsigned)((grp * 4 + fr) * UPN + jn)) = ag;
;                         if (m == 3 && fr >= 14) *(f32x4*)(edge + (unsigned)((grp * 4 + (fr - 12)) * UPN + jn)) = ag;
;                         const f32x4 o = gelu4(bg + wg0 * g2 + wg1 * g1 + wg2 * ag) * cu[m];
;                         if (!(m == 0 && fr < 2)) *(u32x2*)(act + (unsigned)(row * DFF + jn)) = pack4(o);
.Lwj546_13674:
.LBB0_563:
	s_or_b64 exec, exec, s[0:1]
	v_add_u32_e32 v136, 0x1604, v44
	v_lshl_add_u64 v[72:73], v[136:137], 2, s[66:67]
	v_add_u32_e32 v136, 0x2c04, v44
	global_load_dwordx4 v[20:23], v[46:47], off offset:16
	v_lshl_add_u64 v[74:75], v[136:137], 2, s[66:67]
	global_load_dwordx4 v[28:31], v[72:73], off
	global_load_dwordx4 v[24:27], v[74:75], off
	global_load_dwordx4 v[32:35], v[48:49], off offset:16
	v_lshlrev_b32_e32 v40, 16, v169
	v_and_b32_e32 v41, 0xffff0000, v169
	v_lshlrev_b32_e32 v42, 16, v168
	v_and_b32_e32 v43, 0xffff0000, v168
	s_nop 1
	v_mov_b32_dpp v84, v40 row_ror:1 row_mask:0xf bank_mask:0xf
	v_mov_b32_dpp v85, v41 row_ror:1 row_mask:0xf bank_mask:0xf
	v_mov_b32_dpp v86, v42 row_ror:1 row_mask:0xf bank_mask:0xf
	v_mov_b32_dpp v87, v43 row_ror:1 row_mask:0xf bank_mask:0xf
	v_mov_b32_dpp v88, v40 row_ror:2 row_mask:0xf bank_mask:0xf
	v_mov_b32_dpp v89, v41 row_ror:2 row_mask:0xf bank_mask:0xf
	v_mov_b32_dpp v90, v42 row_ror:2 row_mask:0xf bank_mask:0xf
	v_mov_b32_dpp v91, v43 row_ror:2 row_mask:0xf bank_mask:0xf
	s_and_saveexec_b64 s[0:1], s[10:11]
	s_xor_b64 s[76:77], exec, s[0:1]
	s_cbranch_execz .LBB0_565
	v_cndmask_b32_e64 v207, 0, v202, s[6:7]
	v_cndmask_b32_e64 v206, 0, v200, s[6:7]
	v_cndmask_b32_e64 v205, 0, v197, s[8:9]
	v_cndmask_b32_e64 v204, 0, v191, s[8:9]
	s_waitcnt vmcnt(4)
	v_pk_fma_f32 v[206:207], v[10:11], v[206:207], v[14:15]
	v_cndmask_b32_e64 v209, 0, v198, s[6:7]
	v_pk_fma_f32 v[204:205], v[2:3], v[204:205], v[206:207]
	v_cndmask_b32_e64 v208, 0, v192, s[6:7]
	v_pk_fma_f32 v[38:39], v[6:7], v[38:39], v[204:205]
	s_waitcnt vmcnt(0)
	v_pk_fma_f32 v[204:205], v[20:21], v[88:89], v[32:33]
	v_cndmask_b32_e64 v169, 0, v194, s[8:9]
	v_pk_fma_f32 v[204:205], v[28:29], v[84:85], v[204:205]
	v_cndmask_b32_e64 v168, 0, v188, s[8:9]
	v_pk_fma_f32 v[40:41], v[24:25], v[40:41], v[204:205]
	v_pk_fma_f32 v[208:209], v[8:9], v[208:209], v[12:13]
	v_and_b32_e32 v207, 0x7fffffff, v41
	v_and_b32_e32 v206, 0x7fffffff, v40
	v_pk_fma_f32 v[206:207], v[206:207], s[42:43], 1.0 op_sel_hi:[1,0,0]
	v_pk_fma_f32 v[168:169], v[0:1], v[168:169], v[208:209]
	v_rcp_f32_e32 v206, v206
	v_rcp_f32_e32 v207, v207
	v_pk_mul_f32 v[204:205], v[40:41], v[40:41]
	v_mov_b64_e32 v[208:209], s[54:55]
	v_pk_mul_f32 v[204:205], v[204:205], s[38:39] op_sel_hi:[1,0]
	v_pk_fma_f32 v[210:211], v[206:207], s[52:53], v[208:209] op_sel_hi:[1,0,0]
	v_exp_f32_e32 v204, v204
	v_exp_f32_e32 v205, v205
	v_pk_fma_f32 v[210:211], v[206:207], v[210:211], s[56:57] op_sel_hi:[1,1,0]
	v_pk_fma_f32 v[36:37], v[4:5], v[36:37], v[168:169]
	v_pk_fma_f32 v[210:211], v[206:207], v[210:211], s[62:63] op_sel_hi:[1,1,0]
	v_pk_fma_f32 v[168:169], v[22:23], v[90:91], v[34:35]
	v_pk_fma_f32 v[210:211], v[206:207], v[210:211], s[64:65] op_sel_hi:[1,1,0]
	v_pk_fma_f32 v[168:169], v[30:31], v[86:87], v[168:169]
	v_pk_mul_f32 v[206:207], v[206:207], v[210:211]
	v_cmp_gt_f32_e64 s[0:1], 0, v40
	v_pk_mul_f32 v[204:205], v[204:205], v[206:207]
	v_pk_fma_f32 v[42:43], v[26:27], v[42:43], v[168:169]
	v_pk_mul_f32 v[206:207], v[40:41], v[204:205]
	v_pk_fma_f32 v[204:205], v[40:41], v[204:205], v[40:41] neg_lo:[1,0,0] neg_hi:[1,0,0]
	v_pk_mul_f32 v[168:169], v[42:43], v[42:43]
	v_cndmask_b32_e64 v40, v204, v206, s[0:1]
	v_cmp_gt_f32_e64 s[0:1], 0, v41
	v_and_b32_e32 v204, 0x7fffffff, v42
	v_pk_mul_f32 v[168:169], v[168:169], s[38:39] op_sel_hi:[1,0]
	v_cndmask_b32_e64 v41, v205, v207, s[0:1]
	v_and_b32_e32 v205, 0x7fffffff, v43
	v_pk_fma_f32 v[204:205], v[204:205], s[42:43], 1.0 op_sel_hi:[1,0,0]
	v_exp_f32_e32 v168, v168
	v_rcp_f32_e32 v204, v204
	v_rcp_f32_e32 v205, v205
	v_exp_f32_e32 v169, v169
	v_cmp_gt_f32_e64 s[0:1], 0, v42
	v_pk_mul_f32 v[36:37], v[36:37], v[40:41]
	v_pk_fma_f32 v[206:207], v[204:205], s[52:53], v[208:209] op_sel_hi:[1,0,0]
	v_cvt_pk_bf16_f32 v36, v36, v37
	s_nop 0
	v_pk_fma_f32 v[206:207], v[204:205], v[206:207], s[56:57] op_sel_hi:[1,1,0]
	s_nop 0
	v_pk_fma_f32 v[206:207], v[204:205], v[206:207], s[62:63] op_sel_hi:[1,1,0]
	s_nop 0
	v_pk_fma_f32 v[206:207], v[204:205], v[206:207], s[64:65] op_sel_hi:[1,1,0]
	s_nop 0
	v_pk_mul_f32 v[204:205], v[204:205], v[206:207]
	s_nop 0
	v_pk_mul_f32 v[168:169], v[168:169], v[204:205]
	s_nop 0
	v_pk_mul_f32 v[204:205], v[42:43], v[168:169]
	v_pk_fma_f32 v[168:169], v[42:43], v[168:169], v[42:43] neg_lo:[1,0,0] neg_hi:[1,0,0]
	s_nop 0
	v_cndmask_b32_e64 v42, v168, v204, s[0:1]
	v_cmp_gt_f32_e64 s[0:1], 0, v43
	s_nop 1
	v_cndmask_b32_e64 v43, v169, v205, s[0:1]
	v_pk_mul_f32 v[38:39], v[38:39], v[42:43]
	s_nop 0
	v_cvt_pk_bf16_f32 v37, v38, v39
	v_mad_u64_u32 v[38:39], s[0:1], v146, s88, v[50:51]
	v_mov_b32_e32 v39, v137
	v_lshl_add_u64 v[38:39], v[38:39], 1, s[26:27]
	s_cmp_lg_u32 s99, 0
	s_cbranch_scc1 .Lwt546_13789
	global_store_dwordx2 v[38:39], v[36:37], off
	s_branch .Lwj546_13789

;     __device__ __forceinline__ void operator()(AccRef acc, const Unit& u, int wr, int wc, int fr, int fq) const {
;     ...
;                         if (m == 0 && fr < 2) *(f32x4*)(edge + (unsigned)((grp * 4 + fr) * UPN + jn)) = ag;
.Lwj546_13789:
.LBB0_565:
	s_andn2_saveexec_b64 s[0:1], s[76:77]
	s_cbranch_execz .LBB0_567
	v_add_u32_e32 v136, v50, v152
	v_lshl_add_u64 v[36:37], v[136:137], 2, s[28:29]
	s_cmp_lg_u32 s99, 0
	s_cbranch_scc1 .Lwt546_13796
	global_store_dwordx4 v[36:37], v[40:43], off
	s_branch .Lwj546_13796

; __device__ __forceinline__ f32x4 gelu4(f32x4 v) { const f32x2 a = gelu_pk((f32x2){v[0], v[1]}), b = gelu_pk((f32x2){v[2], v[3]}); return (f32x4){a.x, a.y, b.x, b.y}; }
; __device__ __forceinline__ f32x4 ror1v(f32x4 v) { return (f32x4){dpp_ror1(v[0]), dpp_ror1(v[1]), dpp_ror1(v[2]), dpp_ror1(v[3])}; }
; __device__ __forceinline__ f32x4 ror2v(f32x4 v) { return (f32x4){dpp_ror2(v[0]), dpp_ror2(v[1]), dpp_ror2(v[2]), dpp_ror2(v[3])}; }
; __device__ __forceinline__ u32x2 pack4(f32x4 v) { return (u32x2){pk2(v[0], v[1]), pk2(v[2], v[3])}; }
; __device__ __forceinline__ f32x4 unpack4(u32x2 w) { return (f32x4){bflo(w.x), bfhi(w.x), bflo(w.y), bfhi(w.y)}; }
; __device__ __forceinline__ f32x2 gelu_pk(f32x2 v) {
;     const f32x2 av = __builtin_elementwise_abs(v), d = av * 0.2316418882f + 1.0f;
;     f32x2 t; t.x = __builtin_amdgcn_rcpf(d.x); t.y = __builtin_amdgcn_rcpf(d.y);
;     f32x2 q = t * 0.5307027145f + (-0.7265760135f); q = q * t + 0.7107068705f; q = q * t + (-0.142248368f); q = q * t + 0.127414796f; q = q * t;
;     const f32x2 s = (v * v) * (-0.72134752044f);
;     f32x2 e; e.x = __builtin_amdgcn_exp2f(s.x); e.y = __builtin_amdgcn_exp2f(s.y);
;     const f32x2 m = v * (q * e), r = v - m;
;     f32x2 o; o.x = v.x < 0.f ? m.x : r.x; o.y = v.y < 0.f ? m.y : r.y; return o;
;     __device__ __forceinline__ void operator()(AccRef acc, const Unit& u, int wr, int wc, int fr, int fq) const {
;     ...
;                     for (int m = 0; m < 4; ++m) { const int row = rowg + m * 16 + fr;
;                         const f32x4 ag = unpack4(pa[ai][0][m][n]);
;                         const f32x4 rg1 = ror1v(ag), rg2 = ror2v(ag);
;                         const f32x4 g1 = fr >= 1 ? rg1 : pg1, g2 = fr >= 2 ? rg2 : pg2;
;                         if (m == 0 && fr < 2) *(f32x4*)(edge + (unsigned)((grp * 4 + fr) * UPN + jn)) = ag;
;                         if (m == 3 && fr >= 14) *(f32x4*)(edge + (unsigned)((grp * 4 + (fr - 12)) * UPN + jn)) = ag;
;                         const f32x4 o = gelu4(bg + wg0 * g2 + wg1 * g1 + wg2 * ag) * cu[m];
;                         if (!(m == 0 && fr < 2)) *(u32x2*)(act + (unsigned)(row * DFF + jn)) = pack4(o);
.Lwj546_13796:
.LBB0_567:
	s_or_b64 exec, exec, s[0:1]
	s_nop 0
	v_cndmask_b32_e64 v41, v202, v201, s[6:7]
	v_cndmask_b32_e64 v40, v200, v199, s[6:7]
	v_cndmask_b32_e64 v43, v198, v196, s[6:7]
	v_cndmask_b32_e64 v42, v192, v190, s[6:7]
	v_cndmask_b32_e64 v37, v194, v193, s[8:9]
	v_cndmask_b32_e64 v36, v188, v187, s[8:9]
	v_cndmask_b32_e64 v39, v197, v195, s[8:9]
	v_cndmask_b32_e64 v38, v191, v189, s[8:9]
	s_waitcnt vmcnt(4)
	v_pk_fma_f32 v[42:43], v[8:9], v[42:43], v[12:13]
	v_pk_fma_f32 v[40:41], v[10:11], v[40:41], v[14:15]
	v_pk_fma_f32 v[36:37], v[0:1], v[36:37], v[42:43]
	v_pk_fma_f32 v[38:39], v[2:3], v[38:39], v[40:41]
	v_pk_fma_f32 v[36:37], v[4:5], v[82:83], v[36:37]
	v_pk_fma_f32 v[38:39], v[6:7], v[80:81], v[38:39]
	v_cndmask_b32_e64 v81, v201, v178, s[6:7]
	v_cndmask_b32_e64 v80, v199, v177, s[6:7]
	v_cndmask_b32_e64 v83, v196, v175, s[6:7]
	v_cndmask_b32_e64 v82, v190, v172, s[6:7]
	v_cndmask_b32_e64 v41, v193, v173, s[8:9]
	v_cndmask_b32_e64 v40, v187, v170, s[8:9]
	v_cndmask_b32_e64 v43, v195, v174, s[8:9]
	v_cndmask_b32_e64 v42, v189, v171, s[8:9]
	v_pk_fma_f32 v[82:83], v[8:9], v[82:83], v[12:13]
	v_pk_fma_f32 v[80:81], v[10:11], v[80:81], v[14:15]
	v_pk_fma_f32 v[40:41], v[0:1], v[40:41], v[82:83]
	v_pk_fma_f32 v[42:43], v[2:3], v[42:43], v[80:81]
	v_pk_fma_f32 v[80:81], v[4:5], v[78:79], v[40:41]
	v_pk_fma_f32 v[82:83], v[6:7], v[76:77], v[42:43]
	v_lshlrev_b32_e32 v40, 16, v167
	v_and_b32_e32 v41, 0xffff0000, v167
	v_lshlrev_b32_e32 v42, 16, v149
	v_and_b32_e32 v43, 0xffff0000, v149
	s_nop 1
	v_mov_b32_dpp v146, v40 row_ror:1 row_mask:0xf bank_mask:0xf
	v_mov_b32_dpp v149, v41 row_ror:1 row_mask:0xf bank_mask:0xf
	v_mov_b32_dpp v168, v40 row_ror:2 row_mask:0xf bank_mask:0xf
	v_mov_b32_dpp v169, v41 row_ror:2 row_mask:0xf bank_mask:0xf
	v_cndmask_b32_e64 v79, v85, v149, s[8:9]
	v_cndmask_b32_e64 v78, v84, v146, s[8:9]
	v_cndmask_b32_e64 v85, v89, v169, s[6:7]
	v_cndmask_b32_e64 v84, v88, v168, s[6:7]
	s_waitcnt vmcnt(2)
	v_pk_fma_f32 v[84:85], v[20:21], v[84:85], v[32:33]
	s_nop 1
	v_pk_fma_f32 v[78:79], v[28:29], v[78:79], v[84:85]
	s_nop 1
	v_pk_fma_f32 v[40:41], v[24:25], v[40:41], v[78:79]
	s_nop 1
	v_and_b32_e32 v85, 0x7fffffff, v41
	v_and_b32_e32 v84, 0x7fffffff, v40
	s_nop 1
	v_pk_fma_f32 v[84:85], v[84:85], s[42:43], 1.0 op_sel_hi:[1,0,0]
	v_mov_b32_dpp v152, v42 row_ror:1 row_mask:0xf bank_mask:0xf
	v_mov_b32_dpp v167, v43 row_ror:1 row_mask:0xf bank_mask:0xf
	v_mov_b32_dpp v187, v42 row_ror:2 row_mask:0xf bank_mask:0xf
	v_mov_b32_dpp v188, v43 row_ror:2 row_mask:0xf bank_mask:0xf
	v_rcp_f32_e32 v84, v84
	v_rcp_f32_e32 v85, v85
	v_cndmask_b32_e64 v77, v87, v167, s[8:9]
	v_cndmask_b32_e64 v76, v86, v152, s[8:9]
	v_cndmask_b32_e64 v87, v91, v188, s[6:7]
	v_cndmask_b32_e64 v86, v90, v187, s[6:7]
	v_pk_fma_f32 v[86:87], v[22:23], v[86:87], v[34:35]
	v_pk_mul_f32 v[78:79], v[40:41], v[40:41]
	v_pk_fma_f32 v[76:77], v[30:31], v[76:77], v[86:87]
	v_mov_b64_e32 v[86:87], s[54:55]
	v_pk_mul_f32 v[78:79], v[78:79], s[38:39] op_sel_hi:[1,0]
	v_pk_fma_f32 v[88:89], v[84:85], s[52:53], v[86:87] op_sel_hi:[1,0,0]
	v_exp_f32_e32 v78, v78
	v_exp_f32_e32 v79, v79
	v_pk_fma_f32 v[88:89], v[84:85], v[88:89], s[56:57] op_sel_hi:[1,1,0]
	v_cmp_gt_f32_e64 s[0:1], 0, v40
	v_pk_fma_f32 v[88:89], v[84:85], v[88:89], s[62:63] op_sel_hi:[1,1,0]
	v_pk_fma_f32 v[42:43], v[26:27], v[42:43], v[76:77]
	v_pk_fma_f32 v[88:89], v[84:85], v[88:89], s[64:65] op_sel_hi:[1,1,0]
	v_pk_mul_f32 v[76:77], v[42:43], v[42:43]
	v_pk_mul_f32 v[84:85], v[84:85], v[88:89]
	v_pk_mul_f32 v[76:77], v[76:77], s[38:39] op_sel_hi:[1,0]
	v_pk_mul_f32 v[78:79], v[78:79], v[84:85]
	v_exp_f32_e32 v76, v76
	v_pk_mul_f32 v[84:85], v[40:41], v[78:79]
	v_pk_fma_f32 v[78:79], v[40:41], v[78:79], v[40:41] neg_lo:[1,0,0] neg_hi:[1,0,0]
	v_exp_f32_e32 v77, v77
	v_cndmask_b32_e64 v40, v78, v84, s[0:1]
	v_cmp_gt_f32_e64 s[0:1], 0, v41
	v_and_b32_e32 v78, 0x7fffffff, v42
	v_add_u32_e32 v136, v45, v50
	v_cndmask_b32_e64 v41, v79, v85, s[0:1]
	v_and_b32_e32 v79, 0x7fffffff, v43
	v_pk_fma_f32 v[78:79], v[78:79], s[42:43], 1.0 op_sel_hi:[1,0,0]
	v_cmp_gt_f32_e64 s[0:1], 0, v42
	v_rcp_f32_e32 v78, v78
	v_rcp_f32_e32 v79, v79
	v_pk_mul_f32 v[36:37], v[36:37], v[40:41]
	s_nop 1
	v_cvt_pk_bf16_f32 v36, v36, v37
	v_pk_fma_f32 v[84:85], v[78:79], s[52:53], v[86:87] op_sel_hi:[1,0,0]
	s_nop 1
	v_pk_fma_f32 v[84:85], v[78:79], v[84:85], s[56:57] op_sel_hi:[1,1,0]
	s_nop 1
	v_pk_fma_f32 v[84:85], v[78:79], v[84:85], s[62:63] op_sel_hi:[1,1,0]
	s_nop 0
	v_pk_fma_f32 v[84:85], v[78:79], v[84:85], s[64:65] op_sel_hi:[1,1,0]
	s_nop 0
	v_pk_mul_f32 v[78:79], v[78:79], v[84:85]
	s_nop 0
	v_pk_mul_f32 v[76:77], v[76:77], v[78:79]
	s_nop 0
	v_pk_mul_f32 v[78:79], v[42:43], v[76:77]
	v_pk_fma_f32 v[76:77], v[42:43], v[76:77], v[42:43] neg_lo:[1,0,0] neg_hi:[1,0,0]
	s_nop 0
	v_cndmask_b32_e64 v42, v76, v78, s[0:1]
	v_cmp_gt_f32_e64 s[0:1], 0, v43
	s_nop 1
	v_cndmask_b32_e64 v43, v77, v79, s[0:1]
	v_pk_mul_f32 v[38:39], v[38:39], v[42:43]
	s_nop 1
	v_cvt_pk_bf16_f32 v37, v38, v39
	v_lshl_add_u64 v[38:39], v[136:137], 1, s[26:27]
	s_cmp_lg_u32 s99, 0
	s_cbranch_scc1 .Lwt546_13924
	global_store_dwordx2 v[38:39], v[36:37], off
	s_branch .Lwj546_13924

; __device__ __forceinline__ f32x4 gelu4(f32x4 v) { const f32x2 a = gelu_pk((f32x2){v[0], v[1]}), b = gelu_pk((f32x2){v[2], v[3]}); return (f32x4){a.x, a.y, b.x, b.y}; }
; __device__ __forceinline__ f32x4 ror1v(f32x4 v) { return (f32x4){dpp_ror1(v[0]), dpp_ror1(v[1]), dpp_ror1(v[2]), dpp_ror1(v[3])}; }
; __device__ __forceinline__ f32x4 ror2v(f32x4 v) { return (f32x4){dpp_ror2(v[0]), dpp_ror2(v[1]), dpp_ror2(v[2]), dpp_ror2(v[3])}; }
; __device__ __forceinline__ u32x2 pack4(f32x4 v) { return (u32x2){pk2(v[0], v[1]), pk2(v[2], v[3])}; }
; __device__ __forceinline__ f32x4 unpack4(u32x2 w) { return (f32x4){bflo(w.x), bfhi(w.x), bflo(w.y), bfhi(w.y)}; }
; __device__ __forceinline__ f32x2 gelu_pk(f32x2 v) {
;     const f32x2 av = __builtin_elementwise_abs(v), d = av * 0.2316418882f + 1.0f;
;     f32x2 t; t.x = __builtin_amdgcn_rcpf(d.x); t.y = __builtin_amdgcn_rcpf(d.y);
;     f32x2 q = t * 0.5307027145f + (-0.7265760135f); q = q * t + 0.7107068705f; q = q * t + (-0.142248368f); q = q * t + 0.127414796f; q = q * t;
;     const f32x2 s = (v * v) * (-0.72134752044f);
;     f32x2 e; e.x = __builtin_amdgcn_exp2f(s.x); e.y = __builtin_amdgcn_exp2f(s.y);
;     const f32x2 m = v * (q * e), r = v - m;
;     f32x2 o; o.x = v.x < 0.f ? m.x : r.x; o.y = v.y < 0.f ? m.y : r.y; return o;
;     __device__ __forceinline__ void operator()(AccRef acc, const Unit& u, int wr, int wc, int fr, int fq) const {
;     ...
;                     for (int m = 0; m < 4; ++m) { const int row = rowg + m * 16 + fr;
;                         const f32x4 ag = unpack4(pa[ai][0][m][n]);
;                         const f32x4 rg1 = ror1v(ag), rg2 = ror2v(ag);
;                         const f32x4 g1 = fr >= 1 ? rg1 : pg1, g2 = fr >= 2 ? rg2 : pg2;
;                         if (m == 0 && fr < 2) *(f32x4*)(edge + (unsigned)((grp * 4 + fr) * UPN + jn)) = ag;
;                         if (m == 3 && fr >= 14) *(f32x4*)(edge + (unsigned)((grp * 4 + (fr - 12)) * UPN + jn)) = ag;
;                         const f32x4 o = gelu4(bg + wg0 * g2 + wg1 * g1 + wg2 * ag) * cu[m];
;                         if (!(m == 0 && fr < 2)) *(u32x2*)(act + (unsigned)(row * DFF + jn)) = pack4(o);
.Lwj546_13924:
	v_lshlrev_b32_e32 v36, 16, v127
	v_and_b32_e32 v37, 0xffff0000, v127
	s_nop 1
	v_mov_b32_dpp v43, v36 row_ror:2 row_mask:0xf bank_mask:0xf
	v_mov_b32_dpp v40, v36 row_ror:1 row_mask:0xf bank_mask:0xf
	v_mov_b32_dpp v77, v37 row_ror:2 row_mask:0xf bank_mask:0xf
	v_mov_b32_dpp v41, v37 row_ror:1 row_mask:0xf bank_mask:0xf
	v_cndmask_b32_e64 v91, v169, v77, s[6:7]
	v_cndmask_b32_e64 v90, v168, v43, s[6:7]
	v_cndmask_b32_e64 v89, v149, v41, s[8:9]
	v_cndmask_b32_e64 v88, v146, v40, s[8:9]
	v_pk_fma_f32 v[90:91], v[20:21], v[90:91], v[32:33]
	v_lshlrev_b32_e32 v38, 16, v147
	v_pk_fma_f32 v[88:89], v[28:29], v[88:89], v[90:91]
	v_and_b32_e32 v39, 0xffff0000, v147
	v_pk_fma_f32 v[36:37], v[24:25], v[36:37], v[88:89]
	s_nop 1
	v_and_b32_e32 v91, 0x7fffffff, v37
	v_and_b32_e32 v90, 0x7fffffff, v36
	v_pk_fma_f32 v[90:91], v[90:91], s[42:43], 1.0 op_sel_hi:[1,0,0]
	v_mov_b32_dpp v45, v38 row_ror:2 row_mask:0xf bank_mask:0xf
	v_rcp_f32_e32 v90, v90
	v_rcp_f32_e32 v91, v91
	v_mov_b32_dpp v78, v39 row_ror:2 row_mask:0xf bank_mask:0xf
	v_mov_b32_dpp v42, v38 row_ror:1 row_mask:0xf bank_mask:0xf
	v_mov_b32_dpp v76, v39 row_ror:1 row_mask:0xf bank_mask:0xf
	v_cndmask_b32_e64 v147, v188, v78, s[6:7]
	v_cndmask_b32_e64 v146, v187, v45, s[6:7]
	v_cndmask_b32_e64 v85, v167, v76, s[8:9]
	v_cndmask_b32_e64 v84, v152, v42, s[8:9]
	v_pk_fma_f32 v[146:147], v[22:23], v[146:147], v[34:35]
	v_pk_mul_f32 v[88:89], v[36:37], v[36:37]
	v_pk_fma_f32 v[84:85], v[30:31], v[84:85], v[146:147]
	v_pk_mul_f32 v[88:89], v[88:89], s[38:39] op_sel_hi:[1,0]
	v_pk_fma_f32 v[146:147], v[90:91], s[52:53], v[86:87] op_sel_hi:[1,0,0]
	v_exp_f32_e32 v88, v88
	v_exp_f32_e32 v89, v89
	v_pk_fma_f32 v[146:147], v[90:91], v[146:147], s[56:57] op_sel_hi:[1,1,0]
	v_cmp_gt_f32_e64 s[0:1], 0, v36
	v_pk_fma_f32 v[146:147], v[90:91], v[146:147], s[62:63] op_sel_hi:[1,1,0]
	v_pk_fma_f32 v[38:39], v[26:27], v[38:39], v[84:85]
	v_pk_fma_f32 v[146:147], v[90:91], v[146:147], s[64:65] op_sel_hi:[1,1,0]
	v_pk_mul_f32 v[84:85], v[38:39], v[38:39]
	v_pk_mul_f32 v[90:91], v[90:91], v[146:147]
	v_pk_mul_f32 v[84:85], v[84:85], s[38:39] op_sel_hi:[1,0]
	v_pk_mul_f32 v[88:89], v[88:89], v[90:91]
	v_exp_f32_e32 v84, v84
	v_pk_mul_f32 v[90:91], v[36:37], v[88:89]
	v_pk_fma_f32 v[88:89], v[36:37], v[88:89], v[36:37] neg_lo:[1,0,0] neg_hi:[1,0,0]
	v_exp_f32_e32 v85, v85
	v_cndmask_b32_e64 v36, v88, v90, s[0:1]
	v_cmp_gt_f32_e64 s[0:1], 0, v37
	v_and_b32_e32 v88, 0x7fffffff, v38
	v_add_u32_e32 v136, v51, v50
	v_cndmask_b32_e64 v37, v89, v91, s[0:1]
	v_and_b32_e32 v89, 0x7fffffff, v39
	v_pk_fma_f32 v[88:89], v[88:89], s[42:43], 1.0 op_sel_hi:[1,0,0]
	v_cmp_gt_f32_e64 s[0:1], 0, v38
	v_rcp_f32_e32 v88, v88
	v_rcp_f32_e32 v89, v89
	v_pk_mul_f32 v[36:37], v[80:81], v[36:37]
	s_nop 1
	v_cvt_pk_bf16_f32 v36, v36, v37
	v_pk_fma_f32 v[86:87], v[88:89], s[52:53], v[86:87] op_sel_hi:[1,0,0]
	s_nop 1
	v_pk_fma_f32 v[86:87], v[88:89], v[86:87], s[56:57] op_sel_hi:[1,1,0]
	s_nop 1
	v_pk_fma_f32 v[86:87], v[88:89], v[86:87], s[62:63] op_sel_hi:[1,1,0]
	s_nop 1
	v_pk_fma_f32 v[86:87], v[88:89], v[86:87], s[64:65] op_sel_hi:[1,1,0]
	s_nop 0
	v_pk_mul_f32 v[86:87], v[88:89], v[86:87]
	s_nop 0
	v_pk_mul_f32 v[84:85], v[84:85], v[86:87]
	s_nop 0
	v_pk_mul_f32 v[86:87], v[38:39], v[84:85]
	v_pk_fma_f32 v[84:85], v[38:39], v[84:85], v[38:39] neg_lo:[1,0,0] neg_hi:[1,0,0]
	s_nop 0
	v_cndmask_b32_e64 v38, v84, v86, s[0:1]
	v_cmp_gt_f32_e64 s[0:1], 0, v39
	s_nop 1
	s_nop 0
	v_cndmask_b32_e64 v39, v85, v87, s[0:1]
	v_pk_mul_f32 v[38:39], v[82:83], v[38:39]
	s_nop 1
	v_cvt_pk_bf16_f32 v37, v38, v39
	v_lshl_add_u64 v[38:39], v[136:137], 1, s[26:27]
	s_cmp_lg_u32 s99, 0
	s_cbranch_scc1 .Lwt546_14016
	global_store_dwordx2 v[38:39], v[36:37], off
	s_branch .Lwj546_14016

; __device__ __forceinline__ f32x4 gelu4(f32x4 v) { const f32x2 a = gelu_pk((f32x2){v[0], v[1]}), b = gelu_pk((f32x2){v[2], v[3]}); return (f32x4){a.x, a.y, b.x, b.y}; }
; __device__ __forceinline__ f32x4 ror1v(f32x4 v) { return (f32x4){dpp_ror1(v[0]), dpp_ror1(v[1]), dpp_ror1(v[2]), dpp_ror1(v[3])}; }
; __device__ __forceinline__ f32x4 ror2v(f32x4 v) { return (f32x4){dpp_ror2(v[0]), dpp_ror2(v[1]), dpp_ror2(v[2]), dpp_ror2(v[3])}; }
; __device__ __forceinline__ u32x2 pack4(f32x4 v) { return (u32x2){pk2(v[0], v[1]), pk2(v[2], v[3])}; }
; __device__ __forceinline__ f32x4 unpack4(u32x2 w) { return (f32x4){bflo(w.x), bfhi(w.x), bflo(w.y), bfhi(w.y)}; }
;     __device__ __forceinline__ void operator()(AccRef acc, const Unit& u, int wr, int wc, int fr, int fq) const {
;     ...
;         for (int ai = 0; ai < 2; ++ai) {
;             const int rowg = u.pm * 256 + ai * 128 + wr * 64; const int grp = rowg >> 6;
;     ...
;                     for (int m = 0; m < 4; ++m) { const int row = rowg + m * 16 + fr;
;                         const f32x4 ag = unpack4(pa[ai][0][m][n]);
;                         const f32x4 rg1 = ror1v(ag), rg2 = ror2v(ag);
;                         const f32x4 g1 = fr >= 1 ? rg1 : pg1, g2 = fr >= 2 ? rg2 : pg2;
;                         if (m == 0 && fr < 2) *(f32x4*)(edge + (unsigned)((grp * 4 + fr) * UPN + jn)) = ag;
;                         if (m == 3 && fr >= 14) *(f32x4*)(edge + (unsigned)((grp * 4 + (fr - 12)) * UPN + jn)) = ag;
;                         const f32x4 o = gelu4(bg + wg0 * g2 + wg1 * g1 + wg2 * ag) * cu[m];
;                         if (!(m == 0 && fr < 2)) *(u32x2*)(act + (unsigned)(row * DFF + jn)) = pack4(o);
.Lwj546_14016:
	v_lshlrev_b32_e32 v36, 16, v124
	v_and_b32_e32 v37, 0xffff0000, v124
	v_lshlrev_b32_e32 v38, 16, v125
	v_and_b32_e32 v39, 0xffff0000, v125
	s_nop 1
	v_mov_b32_dpp v51, v36 row_ror:1 row_mask:0xf bank_mask:0xf
	v_mov_b32_dpp v79, v37 row_ror:1 row_mask:0xf bank_mask:0xf
	v_mov_b32_dpp v80, v38 row_ror:1 row_mask:0xf bank_mask:0xf
	v_mov_b32_dpp v83, v39 row_ror:1 row_mask:0xf bank_mask:0xf
	v_mov_b32_dpp v81, v36 row_ror:2 row_mask:0xf bank_mask:0xf
	v_mov_b32_dpp v84, v37 row_ror:2 row_mask:0xf bank_mask:0xf
	v_mov_b32_dpp v82, v38 row_ror:2 row_mask:0xf bank_mask:0xf
	v_mov_b32_dpp v85, v39 row_ror:2 row_mask:0xf bank_mask:0xf
	s_and_saveexec_b64 s[0:1], vcc
	s_cbranch_execz .LBB0_569
	v_add_u32_e32 v136, v50, v150
	v_lshl_add_u64 v[86:87], v[136:137], 2, s[28:29]
	s_cmp_lg_u32 s99, 0
	s_cbranch_scc1 .Lwt546_14035
	global_store_dwordx4 v[86:87], v[36:39], off
	s_branch .Lwj546_14035
.Lwt546_14035:
	global_store_dwordx4 v[86:87], v[36:39], off sc1
.Lwj546_14035:
.LBB0_569:
	s_or_b64 exec, exec, s[0:1]
	v_cndmask_b32_e64 v87, v76, v83, s[8:9]
	v_cndmask_b32_e64 v86, v42, v80, s[8:9]
	v_cndmask_b32_e64 v42, v45, v82, s[6:7]
	v_cndmask_b32_e64 v83, v178, v186, s[6:7]
	v_cndmask_b32_e64 v82, v177, v185, s[6:7]
	v_cndmask_b32_e64 v76, v43, v81, s[6:7]
	v_cndmask_b32_e64 v81, v174, v183, s[8:9]
	v_cndmask_b32_e64 v80, v171, v180, s[8:9]
	v_pk_fma_f32 v[10:11], v[10:11], v[82:83], v[14:15]
	v_cndmask_b32_e64 v77, v77, v84, s[6:7]
	v_pk_fma_f32 v[2:3], v[2:3], v[80:81], v[10:11]
	v_cndmask_b32_e64 v41, v41, v79, s[8:9]
	v_cndmask_b32_e64 v40, v40, v51, s[8:9]
	v_pk_fma_f32 v[2:3], v[6:7], v[18:19], v[2:3]
	v_pk_fma_f32 v[6:7], v[20:21], v[76:77], v[32:33]
	v_cndmask_b32_e64 v43, v78, v85, s[6:7]
	v_pk_fma_f32 v[6:7], v[28:29], v[40:41], v[6:7]
	v_cndmask_b32_e64 v85, v175, v184, s[6:7]
	v_cndmask_b32_e64 v84, v172, v181, s[6:7]
	v_pk_fma_f32 v[6:7], v[24:25], v[36:37], v[6:7]
	v_pk_fma_f32 v[8:9], v[8:9], v[84:85], v[12:13]
	v_and_b32_e32 v13, 0x7fffffff, v7
	v_and_b32_e32 v12, 0x7fffffff, v6
	v_pk_fma_f32 v[12:13], v[12:13], s[42:43], 1.0 op_sel_hi:[1,0,0]
	v_cndmask_b32_e64 v79, v173, v182, s[8:9]
	v_rcp_f32_e32 v12, v12
	v_rcp_f32_e32 v13, v13
	v_cndmask_b32_e64 v78, v170, v179, s[8:9]
	v_pk_fma_f32 v[0:1], v[0:1], v[78:79], v[8:9]
	v_pk_mul_f32 v[10:11], v[6:7], v[6:7]
	v_mov_b64_e32 v[14:15], s[54:55]
	v_pk_fma_f32 v[0:1], v[4:5], v[16:17], v[0:1]
	v_pk_mul_f32 v[10:11], v[10:11], s[38:39] op_sel_hi:[1,0]
	v_pk_fma_f32 v[16:17], v[12:13], s[52:53], v[14:15] op_sel_hi:[1,0,0]
	v_exp_f32_e32 v10, v10
	v_exp_f32_e32 v11, v11
	v_pk_fma_f32 v[16:17], v[12:13], v[16:17], s[56:57] op_sel_hi:[1,1,0]
	v_pk_fma_f32 v[4:5], v[22:23], v[42:43], v[34:35]
	v_pk_fma_f32 v[16:17], v[12:13], v[16:17], s[62:63] op_sel_hi:[1,1,0]
	v_pk_fma_f32 v[4:5], v[30:31], v[86:87], v[4:5]
	v_pk_fma_f32 v[16:17], v[12:13], v[16:17], s[64:65] op_sel_hi:[1,1,0]
	v_cmp_gt_f32_e64 s[0:1], 0, v6
	v_pk_mul_f32 v[12:13], v[12:13], v[16:17]
	v_pk_fma_f32 v[4:5], v[26:27], v[38:39], v[4:5]
	v_pk_mul_f32 v[10:11], v[10:11], v[12:13]
	v_pk_mul_f32 v[8:9], v[4:5], v[4:5]
	v_pk_mul_f32 v[12:13], v[6:7], v[10:11]
	v_pk_fma_f32 v[10:11], v[6:7], v[10:11], v[6:7] neg_lo:[1,0,0] neg_hi:[1,0,0]
	v_pk_mul_f32 v[8:9], v[8:9], s[38:39] op_sel_hi:[1,0]
	v_cndmask_b32_e64 v6, v10, v12, s[0:1]
	v_cmp_gt_f32_e64 s[0:1], 0, v7
	v_and_b32_e32 v10, 0x7fffffff, v4
	v_exp_f32_e32 v8, v8
	v_cndmask_b32_e64 v7, v11, v13, s[0:1]
	v_and_b32_e32 v11, 0x7fffffff, v5
	v_pk_fma_f32 v[10:11], v[10:11], s[42:43], 1.0 op_sel_hi:[1,0,0]
	v_exp_f32_e32 v9, v9
	v_rcp_f32_e32 v10, v10
	v_rcp_f32_e32 v11, v11
	v_cmp_gt_f32_e64 s[0:1], 0, v4
	v_pk_mul_f32 v[0:1], v[0:1], v[6:7]
	v_add_u32_e32 v136, v148, v50
	v_pk_fma_f32 v[12:13], v[10:11], s[52:53], v[14:15] op_sel_hi:[1,0,0]
	v_cvt_pk_bf16_f32 v0, v0, v1
	s_addk_i32 s69, 0x80
	v_pk_fma_f32 v[12:13], v[10:11], v[12:13], s[56:57] op_sel_hi:[1,1,0]
	s_ashr_i32 s71, s69, 4
	v_pk_fma_f32 v[12:13], v[10:11], v[12:13], s[62:63] op_sel_hi:[1,1,0]
	v_add_u32_e32 v16, s71, v166
	v_pk_fma_f32 v[12:13], v[10:11], v[12:13], s[64:65] op_sel_hi:[1,1,0]
	v_mul_lo_u32 v80, v16, s87
	v_pk_mul_f32 v[10:11], v[10:11], v[12:13]
	v_lshlrev_b32_e32 v36, 16, v116
	v_pk_mul_f32 v[8:9], v[8:9], v[10:11]
	v_and_b32_e32 v37, 0xffff0000, v116
	v_pk_mul_f32 v[10:11], v[4:5], v[8:9]
	v_pk_fma_f32 v[8:9], v[4:5], v[8:9], v[4:5] neg_lo:[1,0,0] neg_hi:[1,0,0]
	v_lshlrev_b32_e32 v38, 16, v117
	v_cndmask_b32_e64 v4, v8, v10, s[0:1]
	v_cmp_gt_f32_e64 s[0:1], 0, v5
	v_and_b32_e32 v39, 0xffff0000, v117
	s_nop 1
	v_cndmask_b32_e64 v5, v9, v11, s[0:1]
	v_pk_mul_f32 v[2:3], v[2:3], v[4:5]
	s_nop 1
	v_cvt_pk_bf16_f32 v1, v2, v3
	v_lshl_add_u64 v[2:3], v[136:137], 1, s[26:27]
	s_cmp_lg_u32 s99, 0
	s_cbranch_scc1 .Lwt546_14129
	global_store_dwordx2 v[2:3], v[0:1], off
	s_branch .Lwj546_14129

; __device__ __forceinline__ f32x4 ror1v(f32x4 v) { return (f32x4){dpp_ror1(v[0]), dpp_ror1(v[1]), dpp_ror1(v[2]), dpp_ror1(v[3])}; }
; __device__ __forceinline__ f32x4 ror2v(f32x4 v) { return (f32x4){dpp_ror2(v[0]), dpp_ror2(v[1]), dpp_ror2(v[2]), dpp_ror2(v[3])}; }
; __device__ __forceinline__ f32x4 unpack4(u32x2 w) { return (f32x4){bflo(w.x), bfhi(w.x), bflo(w.y), bfhi(w.y)}; }
;     __device__ __forceinline__ void operator()(AccRef acc, const Unit& u, int wr, int wc, int fr, int fq) const {
;     ...
;                     const f32x4 wu0 = *(const f32x4*)(cw + (DFF + jn)), wu1 = *(const f32x4*)(cw + (UPN + DFF + jn)), wu2 = *(const f32x4*)(cw + (2 * UPN + DFF + jn)), bu = *(const f32x4*)(cb + (DFF + jn));
;                     f32x4 pu1 = (f32x4){0.f, 0.f, 0.f, 0.f}, pu2 = pu1;
; #pragma unroll
;                     for (int m = 0; m < 4; ++m) {
;                         const f32x4 au = unpack4(pa[ai][1][m][n]);
;                         const f32x4 ru1 = ror1v(au), ru2 = ror2v(au);
;                         const f32x4 u1 = fr >= 1 ? ru1 : pu1, u2 = fr >= 2 ? ru2 : pu2;
;                         if (m == 0 && fr < 2) *(f32x4*)(edge + (unsigned)((grp * 4 + fr) * UPN + DFF + jn)) = au;
;                         if (m == 3 && fr >= 14) *(f32x4*)(edge + (unsigned)((grp * 4 + (fr - 12)) * UPN + DFF + jn)) = au;
.Lwj546_14129:
	global_load_dwordx4 v[8:11], v[52:53], off
	global_load_dwordx4 v[4:7], v[54:55], off
	s_nop 0
	global_load_dwordx4 v[0:3], v[56:57], off
	global_load_dwordx4 v[12:15], v[58:59], off
	s_nop 1
	v_add_u32_e32 v45, 0xb00, v80
	v_mov_b32_dpp v124, v36 row_ror:1 row_mask:0xf bank_mask:0xf
	v_mov_b32_dpp v146, v37 row_ror:1 row_mask:0xf bank_mask:0xf
	v_mov_b32_dpp v125, v38 row_ror:1 row_mask:0xf bank_mask:0xf
	v_mov_b32_dpp v149, v39 row_ror:1 row_mask:0xf bank_mask:0xf
	v_mov_b32_dpp v127, v36 row_ror:2 row_mask:0xf bank_mask:0xf
	v_mov_b32_dpp v150, v37 row_ror:2 row_mask:0xf bank_mask:0xf
	v_mov_b32_dpp v169, v38 row_ror:2 row_mask:0xf bank_mask:0xf
	v_mov_b32_dpp v171, v39 row_ror:2 row_mask:0xf bank_mask:0xf
	s_and_saveexec_b64 s[0:1], s[12:13]
	s_cbranch_execz .LBB0_571
	v_add_u32_e32 v136, v45, v44
	v_lshl_add_u64 v[16:17], v[136:137], 2, s[28:29]
	s_cmp_lg_u32 s99, 0
	s_cbranch_scc1 .Lwt546_14150
	global_store_dwordx4 v[16:17], v[36:39], off
	s_branch .Lwj546_14150

; __device__ __forceinline__ f32x4 ror1v(f32x4 v) { return (f32x4){dpp_ror1(v[0]), dpp_ror1(v[1]), dpp_ror1(v[2]), dpp_ror1(v[3])}; }
; __device__ __forceinline__ f32x4 ror2v(f32x4 v) { return (f32x4){dpp_ror2(v[0]), dpp_ror2(v[1]), dpp_ror2(v[2]), dpp_ror2(v[3])}; }
; __device__ __forceinline__ f32x4 unpack4(u32x2 w) { return (f32x4){bflo(w.x), bfhi(w.x), bflo(w.y), bfhi(w.y)}; }
;     __device__ __forceinline__ void operator()(AccRef acc, const Unit& u, int wr, int wc, int fr, int fq) const {
;     ...
;                     const f32x4 wu0 = *(const f32x4*)(cw + (DFF + jn)), wu1 = *(const f32x4*)(cw + (UPN + DFF + jn)), wu2 = *(const f32x4*)(cw + (2 * UPN + DFF + jn)), bu = *(const f32x4*)(cb + (DFF + jn));
;                     f32x4 pu1 = (f32x4){0.f, 0.f, 0.f, 0.f}, pu2 = pu1;
; #pragma unroll
;                     for (int m = 0; m < 4; ++m) {
;                         const f32x4 au = unpack4(pa[ai][1][m][n]);
;                         const f32x4 ru1 = ror1v(au), ru2 = ror2v(au);
;                         const f32x4 u1 = fr >= 1 ? ru1 : pu1, u2 = fr >= 2 ? ru2 : pu2;
;                         if (m == 0 && fr < 2) *(f32x4*)(edge + (unsigned)((grp * 4 + fr) * UPN + DFF + jn)) = au;
;                         if (m == 3 && fr >= 14) *(f32x4*)(edge + (unsigned)((grp * 4 + (fr - 12)) * UPN + DFF + jn)) = au;
;                         cu[m] = bu + wu0 * u2 + wu1 * u1 + wu2 * au;
;                         pu1 = ru1; pu2 = ru2; }
.Lwj546_14150:
.LBB0_571:
	s_or_b64 exec, exec, s[0:1]
	v_add_u32_e32 v16, s71, v126
	v_mul_lo_u32 v51, v16, s87
	v_lshlrev_b32_e32 v58, 16, v118
	v_and_b32_e32 v59, 0xffff0000, v118
	v_lshlrev_b32_e32 v56, 16, v119
	v_and_b32_e32 v57, 0xffff0000, v119
	s_nop 1
	v_lshlrev_b32_e32 v54, 16, v120
	v_and_b32_e32 v55, 0xffff0000, v120
	v_lshlrev_b32_e32 v52, 16, v121
	v_and_b32_e32 v53, 0xffff0000, v121
	s_nop 1
	v_lshlrev_b32_e32 v16, 16, v122
	v_and_b32_e32 v17, 0xffff0000, v122
	v_lshlrev_b32_e32 v18, 16, v123
	v_and_b32_e32 v19, 0xffff0000, v123
	s_nop 1
	v_add_u32_e32 v81, 0xb00, v51
	v_mov_b32_dpp v126, v58 row_ror:1 row_mask:0xf bank_mask:0xf
	v_mov_b32_dpp v152, v59 row_ror:1 row_mask:0xf bank_mask:0xf
	v_mov_b32_dpp v147, v56 row_ror:1 row_mask:0xf bank_mask:0xf
	v_mov_b32_dpp v167, v57 row_ror:1 row_mask:0xf bank_mask:0xf
	v_mov_b32_dpp v148, v58 row_ror:2 row_mask:0xf bank_mask:0xf
	v_mov_b32_dpp v168, v59 row_ror:2 row_mask:0xf bank_mask:0xf
	v_mov_b32_dpp v170, v56 row_ror:2 row_mask:0xf bank_mask:0xf
	v_mov_b32_dpp v172, v57 row_ror:2 row_mask:0xf bank_mask:0xf
	v_mov_b32_dpp v83, v54 row_ror:1 row_mask:0xf bank_mask:0xf
	v_mov_b32_dpp v86, v55 row_ror:1 row_mask:0xf bank_mask:0xf
	v_mov_b32_dpp v84, v52 row_ror:1 row_mask:0xf bank_mask:0xf
	v_mov_b32_dpp v87, v53 row_ror:1 row_mask:0xf bank_mask:0xf
	v_mov_b32_dpp v85, v54 row_ror:2 row_mask:0xf bank_mask:0xf
	v_mov_b32_dpp v88, v55 row_ror:2 row_mask:0xf bank_mask:0xf
	v_mov_b32_dpp v89, v52 row_ror:2 row_mask:0xf bank_mask:0xf
	v_mov_b32_dpp v90, v53 row_ror:2 row_mask:0xf bank_mask:0xf
	v_mov_b32_dpp v91, v16 row_ror:1 row_mask:0xf bank_mask:0xf
	v_mov_b32_dpp v118, v17 row_ror:1 row_mask:0xf bank_mask:0xf
	v_mov_b32_dpp v116, v18 row_ror:1 row_mask:0xf bank_mask:0xf
	v_mov_b32_dpp v119, v19 row_ror:1 row_mask:0xf bank_mask:0xf
	v_mov_b32_dpp v117, v16 row_ror:2 row_mask:0xf bank_mask:0xf
	v_mov_b32_dpp v120, v17 row_ror:2 row_mask:0xf bank_mask:0xf
	v_mov_b32_dpp v121, v18 row_ror:2 row_mask:0xf bank_mask:0xf
	v_mov_b32_dpp v122, v19 row_ror:2 row_mask:0xf bank_mask:0xf
	s_and_saveexec_b64 s[0:1], vcc
	s_cbranch_execz .LBB0_573
	v_add_u32_e32 v136, v81, v44
	v_lshl_add_u64 v[20:21], v[136:137], 2, s[28:29]
	s_cmp_lg_u32 s99, 0
	s_cbranch_scc1 .Lwt546_14200
	global_store_dwordx4 v[20:21], v[16:19], off
	s_branch .Lwj546_14200

; __device__ __forceinline__ f32x4 gelu4(f32x4 v) { const f32x2 a = gelu_pk((f32x2){v[0], v[1]}), b = gelu_pk((f32x2){v[2], v[3]}); return (f32x4){a.x, a.y, b.x, b.y}; }
; __device__ __forceinline__ f32x4 ror1v(f32x4 v) { return (f32x4){dpp_ror1(v[0]), dpp_ror1(v[1]), dpp_ror1(v[2]), dpp_ror1(v[3])}; }
; __device__ __forceinline__ f32x4 ror2v(f32x4 v) { return (f32x4){dpp_ror2(v[0]), dpp_ror2(v[1]), dpp_ror2(v[2]), dpp_ror2(v[3])}; }
; __device__ __forceinline__ u32x2 pack4(f32x4 v) { return (u32x2){pk2(v[0], v[1]), pk2(v[2], v[3])}; }
; __device__ __forceinline__ f32x2 gelu_pk(f32x2 v) {
;     const f32x2 av = __builtin_elementwise_abs(v), d = av * 0.2316418882f + 1.0f;
;     f32x2 t; t.x = __builtin_amdgcn_rcpf(d.x); t.y = __builtin_amdgcn_rcpf(d.y);
;     f32x2 q = t * 0.5307027145f + (-0.7265760135f); q = q * t + 0.7107068705f; q = q * t + (-0.142248368f); q = q * t + 0.127414796f; q = q * t;
;     const f32x2 s = (v * v) * (-0.72134752044f);
;     f32x2 e; e.x = __builtin_amdgcn_exp2f(s.x); e.y = __builtin_amdgcn_exp2f(s.y);
;     const f32x2 m = v * (q * e), r = v - m;
;     f32x2 o; o.x = v.x < 0.f ? m.x : r.x; o.y = v.y < 0.f ? m.y : r.y; return o;
;     __device__ __forceinline__ void operator()(AccRef acc, const Unit& u, int wr, int wc, int fr, int fq) const {
;     ...
;                     const f32x4 wg0 = *(const f32x4*)(cw + jn), wg1 = *(const f32x4*)(cw + (UPN + jn)), wg2 = *(const f32x4*)(cw + (2 * UPN + jn)), bg = *(const f32x4*)(cb + jn);
;                     f32x4 pg1 = (f32x4){0.f, 0.f, 0.f, 0.f}, pg2 = pg1;
; #pragma unroll
;                     for (int m = 0; m < 4; ++m) { const int row = rowg + m * 16 + fr;
;                         const f32x4 ag = unpack4(pa[ai][0][m][n]);
;                         const f32x4 rg1 = ror1v(ag), rg2 = ror2v(ag);
;                         const f32x4 g1 = fr >= 1 ? rg1 : pg1, g2 = fr >= 2 ? rg2 : pg2;
;                         if (m == 0 && fr < 2) *(f32x4*)(edge + (unsigned)((grp * 4 + fr) * UPN + jn)) = ag;
;                         if (m == 3 && fr >= 14) *(f32x4*)(edge + (unsigned)((grp * 4 + (fr - 12)) * UPN + jn)) = ag;
;                         const f32x4 o = gelu4(bg + wg0 * g2 + wg1 * g1 + wg2 * ag) * cu[m];
;                         if (!(m == 0 && fr < 2)) *(u32x2*)(act + (unsigned)(row * DFF + jn)) = pack4(o);
.Lwj546_14200:
.LBB0_573:
	s_or_b64 exec, exec, s[0:1]
	global_load_dwordx4 v[28:31], v[46:47], off
	global_load_dwordx4 v[24:27], v[60:61], off
	global_load_dwordx4 v[20:23], v[64:65], off
	global_load_dwordx4 v[32:35], v[48:49], off
	v_add_u32_e32 v123, s69, v166
	v_lshlrev_b32_e32 v40, 16, v114
	v_and_b32_e32 v41, 0xffff0000, v114
	v_lshlrev_b32_e32 v42, 16, v115
	v_and_b32_e32 v43, 0xffff0000, v115
	s_nop 1
	v_mov_b32_dpp v60, v40 row_ror:1 row_mask:0xf bank_mask:0xf
	v_mov_b32_dpp v61, v41 row_ror:1 row_mask:0xf bank_mask:0xf
	v_mov_b32_dpp v64, v42 row_ror:1 row_mask:0xf bank_mask:0xf
	v_mov_b32_dpp v65, v43 row_ror:1 row_mask:0xf bank_mask:0xf
	v_mov_b32_dpp v76, v40 row_ror:2 row_mask:0xf bank_mask:0xf
	v_mov_b32_dpp v77, v41 row_ror:2 row_mask:0xf bank_mask:0xf
	v_mov_b32_dpp v78, v42 row_ror:2 row_mask:0xf bank_mask:0xf
	v_mov_b32_dpp v79, v43 row_ror:2 row_mask:0xf bank_mask:0xf
	v_mul_lo_u32 v82, v123, s88
	s_and_saveexec_b64 s[0:1], s[10:11]
	s_xor_b64 s[76:77], exec, s[0:1]
	s_cbranch_execz .LBB0_575
	v_cndmask_b32_e64 v179, 0, v171, s[6:7]
	v_cndmask_b32_e64 v178, 0, v169, s[6:7]
	v_cndmask_b32_e64 v175, 0, v149, s[8:9]
	v_cndmask_b32_e64 v174, 0, v125, s[8:9]
	s_waitcnt vmcnt(4)
	v_pk_fma_f32 v[178:179], v[10:11], v[178:179], v[14:15]
	v_cndmask_b32_e64 v181, 0, v150, s[6:7]
	v_pk_fma_f32 v[174:175], v[6:7], v[174:175], v[178:179]
	v_cndmask_b32_e64 v180, 0, v127, s[6:7]
	v_pk_fma_f32 v[38:39], v[2:3], v[38:39], v[174:175]
	s_waitcnt vmcnt(0)
	v_pk_fma_f32 v[174:175], v[28:29], v[76:77], v[32:33]
	v_cndmask_b32_e64 v115, 0, v146, s[8:9]
	v_pk_fma_f32 v[174:175], v[24:25], v[60:61], v[174:175]
	v_cndmask_b32_e64 v114, 0, v124, s[8:9]
	v_pk_fma_f32 v[40:41], v[20:21], v[40:41], v[174:175]
	v_pk_fma_f32 v[180:181], v[8:9], v[180:181], v[12:13]
	v_and_b32_e32 v179, 0x7fffffff, v41
	v_and_b32_e32 v178, 0x7fffffff, v40
	v_pk_fma_f32 v[178:179], v[178:179], s[42:43], 1.0 op_sel_hi:[1,0,0]
	v_pk_fma_f32 v[114:115], v[4:5], v[114:115], v[180:181]
	v_rcp_f32_e32 v178, v178
	v_rcp_f32_e32 v179, v179
	v_pk_mul_f32 v[174:175], v[40:41], v[40:41]
	v_mov_b64_e32 v[180:181], s[54:55]
	v_pk_mul_f32 v[174:175], v[174:175], s[38:39] op_sel_hi:[1,0]
	v_pk_fma_f32 v[182:183], v[178:179], s[52:53], v[180:181] op_sel_hi:[1,0,0]
	v_exp_f32_e32 v174, v174
	v_exp_f32_e32 v175, v175
	v_pk_fma_f32 v[182:183], v[178:179], v[182:183], s[56:57] op_sel_hi:[1,1,0]
	v_pk_fma_f32 v[36:37], v[0:1], v[36:37], v[114:115]
	v_pk_fma_f32 v[182:183], v[178:179], v[182:183], s[62:63] op_sel_hi:[1,1,0]
	v_pk_fma_f32 v[114:115], v[30:31], v[78:79], v[34:35]
	v_pk_fma_f32 v[182:183], v[178:179], v[182:183], s[64:65] op_sel_hi:[1,1,0]
	v_pk_fma_f32 v[114:115], v[26:27], v[64:65], v[114:115]
	v_pk_mul_f32 v[178:179], v[178:179], v[182:183]
	v_cmp_gt_f32_e64 s[0:1], 0, v40
	v_pk_mul_f32 v[174:175], v[174:175], v[178:179]
	v_pk_fma_f32 v[42:43], v[22:23], v[42:43], v[114:115]
	v_pk_mul_f32 v[178:179], v[40:41], v[174:175]
	v_pk_fma_f32 v[174:175], v[40:41], v[174:175], v[40:41] neg_lo:[1,0,0] neg_hi:[1,0,0]
	v_pk_mul_f32 v[114:115], v[42:43], v[42:43]
	v_cndmask_b32_e64 v40, v174, v178, s[0:1]
	v_cmp_gt_f32_e64 s[0:1], 0, v41
	v_and_b32_e32 v174, 0x7fffffff, v42
	v_pk_mul_f32 v[114:115], v[114:115], s[38:39] op_sel_hi:[1,0]
	v_cndmask_b32_e64 v41, v175, v179, s[0:1]
	v_and_b32_e32 v175, 0x7fffffff, v43
	v_pk_fma_f32 v[174:175], v[174:175], s[42:43], 1.0 op_sel_hi:[1,0,0]
	v_exp_f32_e32 v114, v114
	v_rcp_f32_e32 v174, v174
	v_rcp_f32_e32 v175, v175
	v_exp_f32_e32 v115, v115
	v_cmp_gt_f32_e64 s[0:1], 0, v42
	v_mul_lo_u32 v82, v123, s88
	v_pk_fma_f32 v[178:179], v[174:175], s[52:53], v[180:181] op_sel_hi:[1,0,0]
	v_pk_mul_f32 v[36:37], v[36:37], v[40:41]
	v_pk_fma_f32 v[178:179], v[174:175], v[178:179], s[56:57] op_sel_hi:[1,1,0]
	v_add_u32_e32 v136, v82, v44
	v_pk_fma_f32 v[178:179], v[174:175], v[178:179], s[62:63] op_sel_hi:[1,1,0]
	v_cvt_pk_bf16_f32 v36, v36, v37
	s_nop 0
	v_pk_fma_f32 v[178:179], v[174:175], v[178:179], s[64:65] op_sel_hi:[1,1,0]
	s_nop 0
	v_pk_mul_f32 v[174:175], v[174:175], v[178:179]
	s_nop 0
	v_pk_mul_f32 v[114:115], v[114:115], v[174:175]
	s_nop 0
	v_pk_mul_f32 v[174:175], v[42:43], v[114:115]
	v_pk_fma_f32 v[114:115], v[42:43], v[114:115], v[42:43] neg_lo:[1,0,0] neg_hi:[1,0,0]
	s_nop 0
	v_cndmask_b32_e64 v42, v114, v174, s[0:1]
	v_cmp_gt_f32_e64 s[0:1], 0, v43
	s_nop 1
	v_cndmask_b32_e64 v43, v115, v175, s[0:1]
	v_pk_mul_f32 v[38:39], v[38:39], v[42:43]
	s_nop 0
	v_cvt_pk_bf16_f32 v37, v38, v39
	v_lshl_add_u64 v[38:39], v[136:137], 1, s[26:27]
	s_cmp_lg_u32 s99, 0
	s_cbranch_scc1 .Lwt546_14310
	global_store_dwordx2 v[38:39], v[36:37], off
	s_branch .Lwj546_14310

;     __device__ __forceinline__ void operator()(AccRef acc, const Unit& u, int wr, int wc, int fr, int fq) const {
;     ...
;                         if (m == 0 && fr < 2) *(f32x4*)(edge + (unsigned)((grp * 4 + fr) * UPN + jn)) = ag;
.Lwj546_14310:
.LBB0_575:
	s_andn2_saveexec_b64 s[0:1], s[76:77]
	s_cbranch_execz .LBB0_577
	v_add_u32_e32 v136, v44, v80
	v_lshl_add_u64 v[36:37], v[136:137], 2, s[28:29]
	s_cmp_lg_u32 s99, 0
	s_cbranch_scc1 .Lwt546_14317
	global_store_dwordx4 v[36:37], v[40:43], off
	s_branch .Lwj546_14317

; __device__ __forceinline__ f32x4 gelu4(f32x4 v) { const f32x2 a = gelu_pk((f32x2){v[0], v[1]}), b = gelu_pk((f32x2){v[2], v[3]}); return (f32x4){a.x, a.y, b.x, b.y}; }
; __device__ __forceinline__ f32x4 ror1v(f32x4 v) { return (f32x4){dpp_ror1(v[0]), dpp_ror1(v[1]), dpp_ror1(v[2]), dpp_ror1(v[3])}; }
; __device__ __forceinline__ f32x4 ror2v(f32x4 v) { return (f32x4){dpp_ror2(v[0]), dpp_ror2(v[1]), dpp_ror2(v[2]), dpp_ror2(v[3])}; }
; __device__ __forceinline__ u32x2 pack4(f32x4 v) { return (u32x2){pk2(v[0], v[1]), pk2(v[2], v[3])}; }
; __device__ __forceinline__ f32x4 unpack4(u32x2 w) { return (f32x4){bflo(w.x), bfhi(w.x), bflo(w.y), bfhi(w.y)}; }
; __device__ __forceinline__ f32x2 gelu_pk(f32x2 v) {
;     const f32x2 av = __builtin_elementwise_abs(v), d = av * 0.2316418882f + 1.0f;
;     f32x2 t; t.x = __builtin_amdgcn_rcpf(d.x); t.y = __builtin_amdgcn_rcpf(d.y);
;     f32x2 q = t * 0.5307027145f + (-0.7265760135f); q = q * t + 0.7107068705f; q = q * t + (-0.142248368f); q = q * t + 0.127414796f; q = q * t;
;     const f32x2 s = (v * v) * (-0.72134752044f);
;     f32x2 e; e.x = __builtin_amdgcn_exp2f(s.x); e.y = __builtin_amdgcn_exp2f(s.y);
;     const f32x2 m = v * (q * e), r = v - m;
;     f32x2 o; o.x = v.x < 0.f ? m.x : r.x; o.y = v.y < 0.f ? m.y : r.y; return o;
;     __device__ __forceinline__ void operator()(AccRef acc, const Unit& u, int wr, int wc, int fr, int fq) const {
;     ...
;                         cu[m] = bu + wu0 * u2 + wu1 * u1 + wu2 * au;
;     ...
;                     for (int m = 0; m < 4; ++m) { const int row = rowg + m * 16 + fr;
;                         const f32x4 ag = unpack4(pa[ai][0][m][n]);
;                         const f32x4 rg1 = ror1v(ag), rg2 = ror2v(ag);
;                         const f32x4 g1 = fr >= 1 ? rg1 : pg1, g2 = fr >= 2 ? rg2 : pg2;
;                         if (m == 0 && fr < 2) *(f32x4*)(edge + (unsigned)((grp * 4 + fr) * UPN + jn)) = ag;
;                         if (m == 3 && fr >= 14) *(f32x4*)(edge + (unsigned)((grp * 4 + (fr - 12)) * UPN + jn)) = ag;
;                         const f32x4 o = gelu4(bg + wg0 * g2 + wg1 * g1 + wg2 * ag) * cu[m];
;                         if (!(m == 0 && fr < 2)) *(u32x2*)(act + (unsigned)(row * DFF + jn)) = pack4(o);
.Lwj546_14317:
.LBB0_577:
	s_or_b64 exec, exec, s[0:1]
	s_nop 0
	v_cndmask_b32_e64 v41, v171, v172, s[6:7]
	v_cndmask_b32_e64 v40, v169, v170, s[6:7]
	v_cndmask_b32_e64 v43, v150, v168, s[6:7]
	v_cndmask_b32_e64 v42, v127, v148, s[6:7]
	v_cndmask_b32_e64 v37, v146, v152, s[8:9]
	v_cndmask_b32_e64 v36, v124, v126, s[8:9]
	v_cndmask_b32_e64 v39, v149, v167, s[8:9]
	v_cndmask_b32_e64 v38, v125, v147, s[8:9]
	s_waitcnt vmcnt(4)
	v_pk_fma_f32 v[42:43], v[8:9], v[42:43], v[12:13]
	v_pk_fma_f32 v[40:41], v[10:11], v[40:41], v[14:15]
	v_pk_fma_f32 v[36:37], v[4:5], v[36:37], v[42:43]
	v_pk_fma_f32 v[38:39], v[6:7], v[38:39], v[40:41]
	v_pk_fma_f32 v[36:37], v[0:1], v[58:59], v[36:37]
	v_pk_fma_f32 v[38:39], v[2:3], v[56:57], v[38:39]
	v_cndmask_b32_e64 v57, v172, v90, s[6:7]
	v_cndmask_b32_e64 v56, v170, v89, s[6:7]
	v_cndmask_b32_e64 v59, v168, v88, s[6:7]
	v_cndmask_b32_e64 v58, v148, v85, s[6:7]
	v_cndmask_b32_e64 v41, v152, v86, s[8:9]
	v_cndmask_b32_e64 v40, v126, v83, s[8:9]
	v_cndmask_b32_e64 v43, v167, v87, s[8:9]
	v_cndmask_b32_e64 v42, v147, v84, s[8:9]
	v_pk_fma_f32 v[58:59], v[8:9], v[58:59], v[12:13]
	v_pk_fma_f32 v[56:57], v[10:11], v[56:57], v[14:15]
	v_pk_fma_f32 v[40:41], v[4:5], v[40:41], v[58:59]
	v_pk_fma_f32 v[42:43], v[6:7], v[42:43], v[56:57]
	v_pk_fma_f32 v[56:57], v[0:1], v[54:55], v[40:41]
	v_pk_fma_f32 v[58:59], v[2:3], v[52:53], v[42:43]
	v_lshlrev_b32_e32 v40, 16, v112
	v_and_b32_e32 v41, 0xffff0000, v112
	v_lshlrev_b32_e32 v42, 16, v113
	v_and_b32_e32 v43, 0xffff0000, v113
	s_nop 1
	v_mov_b32_dpp v112, v40 row_ror:1 row_mask:0xf bank_mask:0xf
	v_mov_b32_dpp v113, v41 row_ror:1 row_mask:0xf bank_mask:0xf
	v_mov_b32_dpp v123, v40 row_ror:2 row_mask:0xf bank_mask:0xf
	v_mov_b32_dpp v124, v41 row_ror:2 row_mask:0xf bank_mask:0xf
	v_cndmask_b32_e64 v55, v61, v113, s[8:9]
	v_cndmask_b32_e64 v54, v60, v112, s[8:9]
	v_cndmask_b32_e64 v61, v77, v124, s[6:7]
	v_cndmask_b32_e64 v60, v76, v123, s[6:7]
	s_waitcnt vmcnt(2)
	v_pk_fma_f32 v[60:61], v[28:29], v[60:61], v[32:33]
	s_nop 1
	v_pk_fma_f32 v[54:55], v[24:25], v[54:55], v[60:61]
	s_nop 1
	v_pk_fma_f32 v[40:41], v[20:21], v[40:41], v[54:55]
	s_nop 1
	v_and_b32_e32 v61, 0x7fffffff, v41
	v_and_b32_e32 v60, 0x7fffffff, v40
	v_pk_fma_f32 v[60:61], v[60:61], s[42:43], 1.0 op_sel_hi:[1,0,0]
	s_nop 1
	v_rcp_f32_e32 v60, v60
	v_rcp_f32_e32 v61, v61
	v_mov_b32_dpp v114, v42 row_ror:1 row_mask:0xf bank_mask:0xf
	v_mov_b32_dpp v115, v43 row_ror:1 row_mask:0xf bank_mask:0xf
	v_mov_b32_dpp v125, v42 row_ror:2 row_mask:0xf bank_mask:0xf
	v_mov_b32_dpp v126, v43 row_ror:2 row_mask:0xf bank_mask:0xf
	v_cndmask_b32_e64 v53, v65, v115, s[8:9]
	v_cndmask_b32_e64 v52, v64, v114, s[8:9]
	v_cndmask_b32_e64 v65, v79, v126, s[6:7]
	v_cndmask_b32_e64 v64, v78, v125, s[6:7]
	v_pk_fma_f32 v[64:65], v[30:31], v[64:65], v[34:35]
	v_pk_mul_f32 v[54:55], v[40:41], v[40:41]
	v_mov_b64_e32 v[76:77], s[54:55]
	v_pk_fma_f32 v[52:53], v[26:27], v[52:53], v[64:65]
	v_pk_mul_f32 v[54:55], v[54:55], s[38:39] op_sel_hi:[1,0]
	v_pk_fma_f32 v[64:65], v[60:61], s[52:53], v[76:77] op_sel_hi:[1,0,0]
	v_exp_f32_e32 v54, v54
	v_exp_f32_e32 v55, v55
	v_pk_fma_f32 v[64:65], v[60:61], v[64:65], s[56:57] op_sel_hi:[1,1,0]
	v_cmp_gt_f32_e64 s[0:1], 0, v40
	v_pk_fma_f32 v[64:65], v[60:61], v[64:65], s[62:63] op_sel_hi:[1,1,0]
	v_pk_fma_f32 v[42:43], v[22:23], v[42:43], v[52:53]
	v_pk_fma_f32 v[64:65], v[60:61], v[64:65], s[64:65] op_sel_hi:[1,1,0]
	v_pk_mul_f32 v[52:53], v[42:43], v[42:43]
	v_pk_mul_f32 v[60:61], v[60:61], v[64:65]
	v_pk_mul_f32 v[52:53], v[52:53], s[38:39] op_sel_hi:[1,0]
	v_pk_mul_f32 v[54:55], v[54:55], v[60:61]
	v_exp_f32_e32 v52, v52
	v_pk_mul_f32 v[60:61], v[40:41], v[54:55]
	v_pk_fma_f32 v[54:55], v[40:41], v[54:55], v[40:41] neg_lo:[1,0,0] neg_hi:[1,0,0]
	v_exp_f32_e32 v53, v53
	v_cndmask_b32_e64 v40, v54, v60, s[0:1]
	v_cmp_gt_f32_e64 s[0:1], 0, v41
	v_and_b32_e32 v54, 0x7fffffff, v42
	v_add_u32_e32 v64, 0xb000, v82
	v_cndmask_b32_e64 v41, v55, v61, s[0:1]
	v_and_b32_e32 v55, 0x7fffffff, v43
	v_pk_fma_f32 v[54:55], v[54:55], s[42:43], 1.0 op_sel_hi:[1,0,0]
	v_cmp_gt_f32_e64 s[0:1], 0, v42
	v_rcp_f32_e32 v54, v54
	v_rcp_f32_e32 v55, v55
	v_pk_mul_f32 v[36:37], v[36:37], v[40:41]
	v_add_u32_e32 v136, v64, v44
	v_cvt_pk_bf16_f32 v36, v36, v37
	v_pk_fma_f32 v[60:61], v[54:55], s[52:53], v[76:77] op_sel_hi:[1,0,0]
	s_nop 1
	v_pk_fma_f32 v[60:61], v[54:55], v[60:61], s[56:57] op_sel_hi:[1,1,0]
	s_nop 1
	v_pk_fma_f32 v[60:61], v[54:55], v[60:61], s[62:63] op_sel_hi:[1,1,0]
	v_add_u32_e32 v65, 0x16000, v82
	v_pk_fma_f32 v[60:61], v[54:55], v[60:61], s[64:65] op_sel_hi:[1,1,0]
	s_nop 0
	v_pk_mul_f32 v[54:55], v[54:55], v[60:61]
	s_nop 0
	v_pk_mul_f32 v[52:53], v[52:53], v[54:55]
	s_nop 0
	v_pk_mul_f32 v[54:55], v[42:43], v[52:53]
	v_pk_fma_f32 v[52:53], v[42:43], v[52:53], v[42:43] neg_lo:[1,0,0] neg_hi:[1,0,0]
	s_nop 0
	v_cndmask_b32_e64 v42, v52, v54, s[0:1]
	v_cmp_gt_f32_e64 s[0:1], 0, v43
	s_nop 1
	v_cndmask_b32_e64 v43, v53, v55, s[0:1]
	v_pk_mul_f32 v[38:39], v[38:39], v[42:43]
	s_nop 1
	v_cvt_pk_bf16_f32 v37, v38, v39
	v_lshl_add_u64 v[38:39], v[136:137], 1, s[26:27]
	s_cmp_lg_u32 s99, 0
	s_cbranch_scc1 .Lwt546_14445
	global_store_dwordx2 v[38:39], v[36:37], off
	s_branch .Lwj546_14445

; __device__ __forceinline__ f32x4 gelu4(f32x4 v) { const f32x2 a = gelu_pk((f32x2){v[0], v[1]}), b = gelu_pk((f32x2){v[2], v[3]}); return (f32x4){a.x, a.y, b.x, b.y}; }
; __device__ __forceinline__ f32x4 ror1v(f32x4 v) { return (f32x4){dpp_ror1(v[0]), dpp_ror1(v[1]), dpp_ror1(v[2]), dpp_ror1(v[3])}; }
; __device__ __forceinline__ f32x4 ror2v(f32x4 v) { return (f32x4){dpp_ror2(v[0]), dpp_ror2(v[1]), dpp_ror2(v[2]), dpp_ror2(v[3])}; }
; __device__ __forceinline__ u32x2 pack4(f32x4 v) { return (u32x2){pk2(v[0], v[1]), pk2(v[2], v[3])}; }
; __device__ __forceinline__ f32x4 unpack4(u32x2 w) { return (f32x4){bflo(w.x), bfhi(w.x), bflo(w.y), bfhi(w.y)}; }
; __device__ __forceinline__ f32x2 gelu_pk(f32x2 v) {
;     const f32x2 av = __builtin_elementwise_abs(v), d = av * 0.2316418882f + 1.0f;
;     f32x2 t; t.x = __builtin_amdgcn_rcpf(d.x); t.y = __builtin_amdgcn_rcpf(d.y);
;     f32x2 q = t * 0.5307027145f + (-0.7265760135f); q = q * t + 0.7107068705f; q = q * t + (-0.142248368f); q = q * t + 0.127414796f; q = q * t;
;     const f32x2 s = (v * v) * (-0.72134752044f);
;     f32x2 e; e.x = __builtin_amdgcn_exp2f(s.x); e.y = __builtin_amdgcn_exp2f(s.y);
;     const f32x2 m = v * (q * e), r = v - m;
;     f32x2 o; o.x = v.x < 0.f ? m.x : r.x; o.y = v.y < 0.f ? m.y : r.y; return o;
;     __device__ __forceinline__ void operator()(AccRef acc, const Unit& u, int wr, int wc, int fr, int fq) const {
;     ...
;                     for (int m = 0; m < 4; ++m) { const int row = rowg + m * 16 + fr;
;                         const f32x4 ag = unpack4(pa[ai][0][m][n]);
;                         const f32x4 rg1 = ror1v(ag), rg2 = ror2v(ag);
;                         const f32x4 g1 = fr >= 1 ? rg1 : pg1, g2 = fr >= 2 ? rg2 : pg2;
;                         if (m == 0 && fr < 2) *(f32x4*)(edge + (unsigned)((grp * 4 + fr) * UPN + jn)) = ag;
;                         if (m == 3 && fr >= 14) *(f32x4*)(edge + (unsigned)((grp * 4 + (fr - 12)) * UPN + jn)) = ag;
;                         const f32x4 o = gelu4(bg + wg0 * g2 + wg1 * g1 + wg2 * ag) * cu[m];
;                         if (!(m == 0 && fr < 2)) *(u32x2*)(act + (unsigned)(row * DFF + jn)) = pack4(o);
.Lwj546_14445:
	v_lshlrev_b32_e32 v36, 16, v110
	v_and_b32_e32 v37, 0xffff0000, v110
	v_lshlrev_b32_e32 v38, 16, v111
	v_mov_b32_dpp v43, v36 row_ror:2 row_mask:0xf bank_mask:0xf
	v_mov_b32_dpp v54, v37 row_ror:2 row_mask:0xf bank_mask:0xf
	v_and_b32_e32 v39, 0xffff0000, v111
	v_mov_b32_dpp v40, v36 row_ror:1 row_mask:0xf bank_mask:0xf
	v_mov_b32_dpp v41, v37 row_ror:1 row_mask:0xf bank_mask:0xf
	v_cndmask_b32_e64 v111, v124, v54, s[6:7]
	v_cndmask_b32_e64 v110, v123, v43, s[6:7]
	v_cndmask_b32_e64 v79, v113, v41, s[8:9]
	v_cndmask_b32_e64 v78, v112, v40, s[8:9]
	v_pk_fma_f32 v[110:111], v[28:29], v[110:111], v[32:33]
	s_nop 1
	v_pk_fma_f32 v[78:79], v[24:25], v[78:79], v[110:111]
	s_nop 1
	v_pk_fma_f32 v[36:37], v[20:21], v[36:37], v[78:79]
	s_nop 1
	v_and_b32_e32 v111, 0x7fffffff, v37
	v_and_b32_e32 v110, 0x7fffffff, v36
	v_pk_fma_f32 v[110:111], v[110:111], s[42:43], 1.0 op_sel_hi:[1,0,0]
	v_mov_b32_dpp v52, v38 row_ror:2 row_mask:0xf bank_mask:0xf
	v_rcp_f32_e32 v110, v110
	v_rcp_f32_e32 v111, v111
	v_mov_b32_dpp v55, v39 row_ror:2 row_mask:0xf bank_mask:0xf
	v_mov_b32_dpp v42, v38 row_ror:1 row_mask:0xf bank_mask:0xf
	v_mov_b32_dpp v53, v39 row_ror:1 row_mask:0xf bank_mask:0xf
	v_cndmask_b32_e64 v113, v126, v55, s[6:7]
	v_cndmask_b32_e64 v112, v125, v52, s[6:7]
	v_cndmask_b32_e64 v61, v115, v53, s[8:9]
	v_cndmask_b32_e64 v60, v114, v42, s[8:9]
	v_pk_fma_f32 v[112:113], v[30:31], v[112:113], v[34:35]
	v_pk_mul_f32 v[78:79], v[36:37], v[36:37]
	v_pk_fma_f32 v[60:61], v[26:27], v[60:61], v[112:113]
	v_pk_mul_f32 v[78:79], v[78:79], s[38:39] op_sel_hi:[1,0]
	v_pk_fma_f32 v[112:113], v[110:111], s[52:53], v[76:77] op_sel_hi:[1,0,0]
	v_exp_f32_e32 v78, v78
	v_exp_f32_e32 v79, v79
	v_pk_fma_f32 v[112:113], v[110:111], v[112:113], s[56:57] op_sel_hi:[1,1,0]
	v_cmp_gt_f32_e64 s[0:1], 0, v36
	v_pk_fma_f32 v[112:113], v[110:111], v[112:113], s[62:63] op_sel_hi:[1,1,0]
	v_pk_fma_f32 v[38:39], v[22:23], v[38:39], v[60:61]
	v_pk_fma_f32 v[112:113], v[110:111], v[112:113], s[64:65] op_sel_hi:[1,1,0]
	v_pk_mul_f32 v[60:61], v[38:39], v[38:39]
	v_pk_mul_f32 v[110:111], v[110:111], v[112:113]
	v_pk_mul_f32 v[60:61], v[60:61], s[38:39] op_sel_hi:[1,0]
	v_pk_mul_f32 v[78:79], v[78:79], v[110:111]
	v_exp_f32_e32 v60, v60
	v_pk_mul_f32 v[110:111], v[36:37], v[78:79]
	v_pk_fma_f32 v[78:79], v[36:37], v[78:79], v[36:37] neg_lo:[1,0,0] neg_hi:[1,0,0]
	v_exp_f32_e32 v61, v61
	v_cndmask_b32_e64 v36, v78, v110, s[0:1]
	v_cmp_gt_f32_e64 s[0:1], 0, v37
	v_and_b32_e32 v78, 0x7fffffff, v38
	v_add_u32_e32 v136, v65, v44
	v_cndmask_b32_e64 v37, v79, v111, s[0:1]
	v_and_b32_e32 v79, 0x7fffffff, v39
	v_pk_fma_f32 v[78:79], v[78:79], s[42:43], 1.0 op_sel_hi:[1,0,0]
	v_cmp_gt_f32_e64 s[0:1], 0, v38
	v_rcp_f32_e32 v78, v78
	v_rcp_f32_e32 v79, v79
	v_pk_mul_f32 v[36:37], v[56:57], v[36:37]
	s_nop 1
	v_cvt_pk_bf16_f32 v36, v36, v37
	v_pk_fma_f32 v[76:77], v[78:79], s[52:53], v[76:77] op_sel_hi:[1,0,0]
	s_nop 1
	v_pk_fma_f32 v[76:77], v[78:79], v[76:77], s[56:57] op_sel_hi:[1,1,0]
	s_nop 0
	v_pk_fma_f32 v[76:77], v[78:79], v[76:77], s[62:63] op_sel_hi:[1,1,0]
	s_nop 0
	v_pk_fma_f32 v[76:77], v[78:79], v[76:77], s[64:65] op_sel_hi:[1,1,0]
	s_nop 0
	v_pk_mul_f32 v[76:77], v[78:79], v[76:77]
	s_nop 0
	v_pk_mul_f32 v[60:61], v[60:61], v[76:77]
	s_nop 0
	v_pk_mul_f32 v[76:77], v[38:39], v[60:61]
	v_pk_fma_f32 v[60:61], v[38:39], v[60:61], v[38:39] neg_lo:[1,0,0] neg_hi:[1,0,0]
	s_nop 0
	v_cndmask_b32_e64 v38, v60, v76, s[0:1]
	v_cmp_gt_f32_e64 s[0:1], 0, v39
	s_nop 1
	v_cndmask_b32_e64 v39, v61, v77, s[0:1]
	v_pk_mul_f32 v[38:39], v[58:59], v[38:39]
	s_nop 1
	v_cvt_pk_bf16_f32 v37, v38, v39
	v_lshl_add_u64 v[38:39], v[136:137], 1, s[26:27]
	s_cmp_lg_u32 s99, 0
	s_cbranch_scc1 .Lwt546_14537
	global_store_dwordx2 v[38:39], v[36:37], off
	s_branch .Lwj546_14537

; __device__ __forceinline__ f32x4 gelu4(f32x4 v) { const f32x2 a = gelu_pk((f32x2){v[0], v[1]}), b = gelu_pk((f32x2){v[2], v[3]}); return (f32x4){a.x, a.y, b.x, b.y}; }
; __device__ __forceinline__ f32x4 ror1v(f32x4 v) { return (f32x4){dpp_ror1(v[0]), dpp_ror1(v[1]), dpp_ror1(v[2]), dpp_ror1(v[3])}; }
; __device__ __forceinline__ f32x4 ror2v(f32x4 v) { return (f32x4){dpp_ror2(v[0]), dpp_ror2(v[1]), dpp_ror2(v[2]), dpp_ror2(v[3])}; }
;     __device__ __forceinline__ void operator()(AccRef acc, const Unit& u, int wr, int wc, int fr, int fq) const {
;     ...
;             for (int n = 0; n < 2; ++n) { const unsigned jn = (unsigned)(j0 + 4 * n);
;                 f32x4 cu[4];
;                 {
;                     const f32x4 wu0 = *(const f32x4*)(cw + (DFF + jn)), wu1 = *(const f32x4*)(cw + (UPN + DFF + jn)), wu2 = *(const f32x4*)(cw + (2 * UPN + DFF + jn)), bu = *(const f32x4*)(cb + (DFF + jn));
;                     f32x4 pu1 = (f32x4){0.f, 0.f, 0.f, 0.f}, pu2 = pu1;
; #pragma unroll
;                     for (int m = 0; m < 4; ++m) {
;                         const f32x4 au = unpack4(pa[ai][1][m][n]);
;                         const f32x4 ru1 = ror1v(au), ru2 = ror2v(au);
;                         const f32x4 u1 = fr >= 1 ? ru1 : pu1, u2 = fr >= 2 ? ru2 : pu2;
;                         if (m == 0 && fr < 2) *(f32x4*)(edge + (unsigned)((grp * 4 + fr) * UPN + DFF + jn)) = au;
;                         if (m == 3 && fr >= 14) *(f32x4*)(edge + (unsigned)((grp * 4 + (fr - 12)) * UPN + DFF + jn)) = au;
;                         cu[m] = bu + wu0 * u2 + wu1 * u1 + wu2 * au;
;     ...
;                     for (int m = 0; m < 4; ++m) { const int row = rowg + m * 16 + fr;
;                         const f32x4 ag = unpack4(pa[ai][0][m][n]);
;                         const f32x4 rg1 = ror1v(ag), rg2 = ror2v(ag);
;                         const f32x4 g1 = fr >= 1 ? rg1 : pg1, g2 = fr >= 2 ? rg2 : pg2;
;                         if (m == 0 && fr < 2) *(f32x4*)(edge + (unsigned)((grp * 4 + fr) * UPN + jn)) = ag;
;                         if (m == 3 && fr >= 14) *(f32x4*)(edge + (unsigned)((grp * 4 + (fr - 12)) * UPN + jn)) = ag;
;                         const f32x4 o = gelu4(bg + wg0 * g2 + wg1 * g1 + wg2 * ag) * cu[m];
;                         if (!(m == 0 && fr < 2)) *(u32x2*)(act + (unsigned)(row * DFF + jn)) = pack4(o);
.Lwj546_14537:
	v_lshlrev_b32_e32 v36, 16, v108
	v_and_b32_e32 v37, 0xffff0000, v108
	v_lshlrev_b32_e32 v38, 16, v109
	v_and_b32_e32 v39, 0xffff0000, v109
	s_nop 1
	v_mov_b32_dpp v56, v36 row_ror:1 row_mask:0xf bank_mask:0xf
	v_mov_b32_dpp v57, v37 row_ror:1 row_mask:0xf bank_mask:0xf
	v_mov_b32_dpp v58, v38 row_ror:1 row_mask:0xf bank_mask:0xf
	v_mov_b32_dpp v61, v39 row_ror:1 row_mask:0xf bank_mask:0xf
	v_mov_b32_dpp v59, v36 row_ror:2 row_mask:0xf bank_mask:0xf
	v_mov_b32_dpp v76, v37 row_ror:2 row_mask:0xf bank_mask:0xf
	v_mov_b32_dpp v60, v38 row_ror:2 row_mask:0xf bank_mask:0xf
	v_mov_b32_dpp v77, v39 row_ror:2 row_mask:0xf bank_mask:0xf
	s_and_saveexec_b64 s[0:1], vcc
	s_cbranch_execz .LBB0_579
	v_add_u32_e32 v136, v51, v44
	v_lshl_add_u64 v[78:79], v[136:137], 2, s[28:29]
	s_cmp_lg_u32 s99, 0
	s_cbranch_scc1 .Lwt546_14556
	global_store_dwordx4 v[78:79], v[36:39], off
	s_branch .Lwj546_14556
.Lwt546_14556:
	global_store_dwordx4 v[78:79], v[36:39], off sc1
.Lwj546_14556:
.LBB0_579:
	s_or_b64 exec, exec, s[0:1]
	v_cndmask_b32_e64 v78, v42, v58, s[8:9]
	v_cndmask_b32_e64 v40, v40, v56, s[8:9]
	v_cndmask_b32_e64 v56, v43, v59, s[6:7]
	v_cndmask_b32_e64 v59, v90, v122, s[6:7]
	v_cndmask_b32_e64 v58, v89, v121, s[6:7]
	v_cndmask_b32_e64 v41, v41, v57, s[8:9]
	v_cndmask_b32_e64 v57, v54, v76, s[6:7]
	v_cndmask_b32_e64 v43, v55, v77, s[6:7]
	v_cndmask_b32_e64 v55, v87, v119, s[8:9]
	v_cndmask_b32_e64 v54, v84, v116, s[8:9]
	v_pk_fma_f32 v[10:11], v[10:11], v[58:59], v[14:15]
	v_cndmask_b32_e64 v79, v53, v61, s[8:9]
	v_pk_fma_f32 v[6:7], v[6:7], v[54:55], v[10:11]
	v_cndmask_b32_e64 v42, v52, v60, s[6:7]
	v_pk_fma_f32 v[2:3], v[2:3], v[18:19], v[6:7]
	v_pk_fma_f32 v[6:7], v[28:29], v[56:57], v[32:33]
	v_cndmask_b32_e64 v61, v88, v120, s[6:7]
	v_pk_fma_f32 v[6:7], v[24:25], v[40:41], v[6:7]
	v_cndmask_b32_e64 v60, v85, v117, s[6:7]
	v_pk_fma_f32 v[6:7], v[20:21], v[36:37], v[6:7]
	v_pk_fma_f32 v[8:9], v[8:9], v[60:61], v[12:13]
	v_and_b32_e32 v13, 0x7fffffff, v7
	v_and_b32_e32 v12, 0x7fffffff, v6
	v_pk_fma_f32 v[12:13], v[12:13], s[42:43], 1.0 op_sel_hi:[1,0,0]
	v_cndmask_b32_e64 v53, v86, v118, s[8:9]
	v_rcp_f32_e32 v12, v12
	v_rcp_f32_e32 v13, v13
	v_cndmask_b32_e64 v52, v83, v91, s[8:9]
	v_pk_fma_f32 v[4:5], v[4:5], v[52:53], v[8:9]
	v_pk_mul_f32 v[10:11], v[6:7], v[6:7]
	v_mov_b64_e32 v[14:15], s[54:55]
	v_pk_fma_f32 v[0:1], v[0:1], v[16:17], v[4:5]
	v_pk_mul_f32 v[10:11], v[10:11], s[38:39] op_sel_hi:[1,0]
	v_pk_fma_f32 v[16:17], v[12:13], s[52:53], v[14:15] op_sel_hi:[1,0,0]
	v_exp_f32_e32 v10, v10
	v_exp_f32_e32 v11, v11
	v_pk_fma_f32 v[16:17], v[12:13], v[16:17], s[56:57] op_sel_hi:[1,1,0]
	v_pk_fma_f32 v[4:5], v[30:31], v[42:43], v[34:35]
	v_pk_fma_f32 v[16:17], v[12:13], v[16:17], s[62:63] op_sel_hi:[1,1,0]
	v_pk_fma_f32 v[4:5], v[26:27], v[78:79], v[4:5]
	v_pk_fma_f32 v[16:17], v[12:13], v[16:17], s[64:65] op_sel_hi:[1,1,0]
	v_cmp_gt_f32_e64 s[0:1], 0, v6
	v_pk_mul_f32 v[12:13], v[12:13], v[16:17]
	v_pk_fma_f32 v[4:5], v[22:23], v[38:39], v[4:5]
	v_pk_mul_f32 v[10:11], v[10:11], v[12:13]
	v_pk_mul_f32 v[8:9], v[4:5], v[4:5]
	v_pk_mul_f32 v[12:13], v[6:7], v[10:11]
	v_pk_fma_f32 v[10:11], v[6:7], v[10:11], v[6:7] neg_lo:[1,0,0] neg_hi:[1,0,0]
	v_pk_mul_f32 v[8:9], v[8:9], s[38:39] op_sel_hi:[1,0]
	v_cndmask_b32_e64 v6, v10, v12, s[0:1]
	v_cmp_gt_f32_e64 s[0:1], 0, v7
	v_and_b32_e32 v10, 0x7fffffff, v4
	v_exp_f32_e32 v8, v8
	v_cndmask_b32_e64 v7, v11, v13, s[0:1]
	v_and_b32_e32 v11, 0x7fffffff, v5
	v_pk_fma_f32 v[10:11], v[10:11], s[42:43], 1.0 op_sel_hi:[1,0,0]
	v_exp_f32_e32 v9, v9
	v_rcp_f32_e32 v10, v10
	v_rcp_f32_e32 v11, v11
	v_cmp_gt_f32_e64 s[0:1], 0, v4
	v_add_u32_e32 v76, 0x21000, v82
	v_pk_mul_f32 v[0:1], v[0:1], v[6:7]
	v_pk_fma_f32 v[12:13], v[10:11], s[52:53], v[14:15] op_sel_hi:[1,0,0]
	v_add_u32_e32 v136, v76, v44
	v_pk_fma_f32 v[12:13], v[10:11], v[12:13], s[56:57] op_sel_hi:[1,1,0]
	v_cvt_pk_bf16_f32 v0, v0, v1
	v_lshlrev_b32_e32 v36, 16, v100
	v_pk_fma_f32 v[12:13], v[10:11], v[12:13], s[62:63] op_sel_hi:[1,1,0]
	v_and_b32_e32 v37, 0xffff0000, v100
	v_pk_fma_f32 v[12:13], v[10:11], v[12:13], s[64:65] op_sel_hi:[1,1,0]
	v_lshlrev_b32_e32 v38, 16, v101
	v_pk_mul_f32 v[10:11], v[10:11], v[12:13]
	v_and_b32_e32 v39, 0xffff0000, v101
	v_pk_mul_f32 v[8:9], v[8:9], v[10:11]
	s_nop 1
	v_pk_mul_f32 v[10:11], v[4:5], v[8:9]
	v_pk_fma_f32 v[8:9], v[4:5], v[8:9], v[4:5] neg_lo:[1,0,0] neg_hi:[1,0,0]
	s_nop 1
	v_cndmask_b32_e64 v4, v8, v10, s[0:1]
	v_cmp_gt_f32_e64 s[0:1], 0, v5
	s_nop 1
	v_cndmask_b32_e64 v5, v9, v11, s[0:1]
	v_pk_mul_f32 v[2:3], v[2:3], v[4:5]
	s_nop 1
	v_cvt_pk_bf16_f32 v1, v2, v3
	v_lshl_add_u64 v[2:3], v[136:137], 1, s[26:27]
	s_cmp_lg_u32 s99, 0
	s_cbranch_scc1 .Lwt546_14649
	global_store_dwordx2 v[2:3], v[0:1], off
	s_branch .Lwj546_14649

; __device__ __forceinline__ f32x4 ror1v(f32x4 v) { return (f32x4){dpp_ror1(v[0]), dpp_ror1(v[1]), dpp_ror1(v[2]), dpp_ror1(v[3])}; }
; __device__ __forceinline__ f32x4 ror2v(f32x4 v) { return (f32x4){dpp_ror2(v[0]), dpp_ror2(v[1]), dpp_ror2(v[2]), dpp_ror2(v[3])}; }
; __device__ __forceinline__ f32x4 unpack4(u32x2 w) { return (f32x4){bflo(w.x), bfhi(w.x), bflo(w.y), bfhi(w.y)}; }
;     __device__ __forceinline__ void operator()(AccRef acc, const Unit& u, int wr, int wc, int fr, int fq) const {
;     ...
;             for (int n = 0; n < 2; ++n) { const unsigned jn = (unsigned)(j0 + 4 * n);
;                 f32x4 cu[4];
;                 {
;                     const f32x4 wu0 = *(const f32x4*)(cw + (DFF + jn)), wu1 = *(const f32x4*)(cw + (UPN + DFF + jn)), wu2 = *(const f32x4*)(cw + (2 * UPN + DFF + jn)), bu = *(const f32x4*)(cb + (DFF + jn));
;                     f32x4 pu1 = (f32x4){0.f, 0.f, 0.f, 0.f}, pu2 = pu1;
; #pragma unroll
;                     for (int m = 0; m < 4; ++m) {
;                         const f32x4 au = unpack4(pa[ai][1][m][n]);
;                         const f32x4 ru1 = ror1v(au), ru2 = ror2v(au);
;                         const f32x4 u1 = fr >= 1 ? ru1 : pu1, u2 = fr >= 2 ? ru2 : pu2;
;                         if (m == 0 && fr < 2) *(f32x4*)(edge + (unsigned)((grp * 4 + fr) * UPN + DFF + jn)) = au;
;                         if (m == 3 && fr >= 14) *(f32x4*)(edge + (unsigned)((grp * 4 + (fr - 12)) * UPN + DFF + jn)) = au;
.Lwj546_14649:
	global_load_dwordx4 v[8:11], v[62:63], off
	global_load_dwordx4 v[4:7], v[66:67], off
	s_nop 0
	global_load_dwordx4 v[0:3], v[68:69], off
	global_load_dwordx4 v[12:15], v[70:71], off
	s_nop 1
	v_mov_b32_dpp v89, v36 row_ror:1 row_mask:0xf bank_mask:0xf
	v_mov_b32_dpp v108, v37 row_ror:1 row_mask:0xf bank_mask:0xf
	v_mov_b32_dpp v100, v38 row_ror:1 row_mask:0xf bank_mask:0xf
	v_mov_b32_dpp v110, v39 row_ror:1 row_mask:0xf bank_mask:0xf
	v_mov_b32_dpp v101, v36 row_ror:2 row_mask:0xf bank_mask:0xf
	v_mov_b32_dpp v111, v37 row_ror:2 row_mask:0xf bank_mask:0xf
	v_mov_b32_dpp v113, v38 row_ror:2 row_mask:0xf bank_mask:0xf
	v_mov_b32_dpp v115, v39 row_ror:2 row_mask:0xf bank_mask:0xf
	s_and_saveexec_b64 s[0:1], s[12:13]
	s_cbranch_execz .LBB0_581
	v_add_u32_e32 v136, v50, v45
	v_lshl_add_u64 v[16:17], v[136:137], 2, s[28:29]
	s_cmp_lg_u32 s99, 0
	s_cbranch_scc1 .Lwt546_14669
	global_store_dwordx4 v[16:17], v[36:39], off
	s_branch .Lwj546_14669

; __device__ __forceinline__ f32x4 ror1v(f32x4 v) { return (f32x4){dpp_ror1(v[0]), dpp_ror1(v[1]), dpp_ror1(v[2]), dpp_ror1(v[3])}; }
; __device__ __forceinline__ f32x4 ror2v(f32x4 v) { return (f32x4){dpp_ror2(v[0]), dpp_ror2(v[1]), dpp_ror2(v[2]), dpp_ror2(v[3])}; }
; __device__ __forceinline__ f32x4 unpack4(u32x2 w) { return (f32x4){bflo(w.x), bfhi(w.x), bflo(w.y), bfhi(w.y)}; }
;     __device__ __forceinline__ void operator()(AccRef acc, const Unit& u, int wr, int wc, int fr, int fq) const {
;     ...
;                     for (int m = 0; m < 4; ++m) {
;                         const f32x4 au = unpack4(pa[ai][1][m][n]);
;                         const f32x4 ru1 = ror1v(au), ru2 = ror2v(au);
;                         const f32x4 u1 = fr >= 1 ? ru1 : pu1, u2 = fr >= 2 ? ru2 : pu2;
;                         if (m == 0 && fr < 2) *(f32x4*)(edge + (unsigned)((grp * 4 + fr) * UPN + DFF + jn)) = au;
;                         if (m == 3 && fr >= 14) *(f32x4*)(edge + (unsigned)((grp * 4 + (fr - 12)) * UPN + DFF + jn)) = au;
.Lwj546_14669:
.LBB0_581:
	s_or_b64 exec, exec, s[0:1]
	v_lshlrev_b32_e32 v56, 16, v102
	v_and_b32_e32 v57, 0xffff0000, v102
	v_lshlrev_b32_e32 v54, 16, v103
	v_and_b32_e32 v55, 0xffff0000, v103
	s_nop 1
	v_lshlrev_b32_e32 v52, 16, v104
	v_and_b32_e32 v53, 0xffff0000, v104
	v_lshlrev_b32_e32 v44, 16, v105
	v_and_b32_e32 v45, 0xffff0000, v105
	s_nop 1
	v_lshlrev_b32_e32 v16, 16, v106
	v_and_b32_e32 v17, 0xffff0000, v106
	v_lshlrev_b32_e32 v18, 16, v107
	v_and_b32_e32 v19, 0xffff0000, v107
	s_nop 1
	v_mov_b32_dpp v88, v56 row_ror:1 row_mask:0xf bank_mask:0xf
	v_mov_b32_dpp v102, v57 row_ror:1 row_mask:0xf bank_mask:0xf
	v_mov_b32_dpp v90, v54 row_ror:1 row_mask:0xf bank_mask:0xf
	v_mov_b32_dpp v103, v55 row_ror:1 row_mask:0xf bank_mask:0xf
	v_mov_b32_dpp v91, v56 row_ror:2 row_mask:0xf bank_mask:0xf
	v_mov_b32_dpp v109, v57 row_ror:2 row_mask:0xf bank_mask:0xf
	v_mov_b32_dpp v112, v54 row_ror:2 row_mask:0xf bank_mask:0xf
	v_mov_b32_dpp v114, v55 row_ror:2 row_mask:0xf bank_mask:0xf
	v_mov_b32_dpp v62, v52 row_ror:1 row_mask:0xf bank_mask:0xf
	v_mov_b32_dpp v67, v53 row_ror:1 row_mask:0xf bank_mask:0xf
	v_mov_b32_dpp v63, v44 row_ror:1 row_mask:0xf bank_mask:0xf
	v_mov_b32_dpp v68, v45 row_ror:1 row_mask:0xf bank_mask:0xf
	v_mov_b32_dpp v66, v52 row_ror:2 row_mask:0xf bank_mask:0xf
	v_mov_b32_dpp v69, v53 row_ror:2 row_mask:0xf bank_mask:0xf
	v_mov_b32_dpp v70, v44 row_ror:2 row_mask:0xf bank_mask:0xf
	v_mov_b32_dpp v71, v45 row_ror:2 row_mask:0xf bank_mask:0xf
	v_mov_b32_dpp v77, v16 row_ror:1 row_mask:0xf bank_mask:0xf
	v_mov_b32_dpp v83, v17 row_ror:1 row_mask:0xf bank_mask:0xf
	v_mov_b32_dpp v78, v18 row_ror:1 row_mask:0xf bank_mask:0xf
	v_mov_b32_dpp v84, v19 row_ror:1 row_mask:0xf bank_mask:0xf
	v_mov_b32_dpp v79, v16 row_ror:2 row_mask:0xf bank_mask:0xf
	v_mov_b32_dpp v85, v17 row_ror:2 row_mask:0xf bank_mask:0xf
	v_mov_b32_dpp v86, v18 row_ror:2 row_mask:0xf bank_mask:0xf
	v_mov_b32_dpp v87, v19 row_ror:2 row_mask:0xf bank_mask:0xf
	s_and_saveexec_b64 s[0:1], vcc
	s_cbranch_execz .LBB0_583
	v_add_u32_e32 v136, v81, v50
	v_lshl_add_u64 v[20:21], v[136:137], 2, s[28:29]
	s_cmp_lg_u32 s99, 0
	s_cbranch_scc1 .Lwt546_14716
	global_store_dwordx4 v[20:21], v[16:19], off
	s_branch .Lwj546_14716

; __device__ __forceinline__ f32x4 gelu4(f32x4 v) { const f32x2 a = gelu_pk((f32x2){v[0], v[1]}), b = gelu_pk((f32x2){v[2], v[3]}); return (f32x4){a.x, a.y, b.x, b.y}; }
; __device__ __forceinline__ f32x4 ror1v(f32x4 v) { return (f32x4){dpp_ror1(v[0]), dpp_ror1(v[1]), dpp_ror1(v[2]), dpp_ror1(v[3])}; }
; __device__ __forceinline__ f32x4 ror2v(f32x4 v) { return (f32x4){dpp_ror2(v[0]), dpp_ror2(v[1]), dpp_ror2(v[2]), dpp_ror2(v[3])}; }
; __device__ __forceinline__ u32x2 pack4(f32x4 v) { return (u32x2){pk2(v[0], v[1]), pk2(v[2], v[3])}; }
; __device__ __forceinline__ f32x2 gelu_pk(f32x2 v) {
;     const f32x2 av = __builtin_elementwise_abs(v), d = av * 0.2316418882f + 1.0f;
;     f32x2 t; t.x = __builtin_amdgcn_rcpf(d.x); t.y = __builtin_amdgcn_rcpf(d.y);
;     f32x2 q = t * 0.5307027145f + (-0.7265760135f); q = q * t + 0.7107068705f; q = q * t + (-0.142248368f); q = q * t + 0.127414796f; q = q * t;
;     const f32x2 s = (v * v) * (-0.72134752044f);
;     f32x2 e; e.x = __builtin_amdgcn_exp2f(s.x); e.y = __builtin_amdgcn_exp2f(s.y);
;     const f32x2 m = v * (q * e), r = v - m;
;     f32x2 o; o.x = v.x < 0.f ? m.x : r.x; o.y = v.y < 0.f ? m.y : r.y; return o;
;     __device__ __forceinline__ void operator()(AccRef acc, const Unit& u, int wr, int wc, int fr, int fq) const {
;     ...
;                     const f32x4 wg0 = *(const f32x4*)(cw + jn), wg1 = *(const f32x4*)(cw + (UPN + jn)), wg2 = *(const f32x4*)(cw + (2 * UPN + jn)), bg = *(const f32x4*)(cb + jn);
;                     f32x4 pg1 = (f32x4){0.f, 0.f, 0.f, 0.f}, pg2 = pg1;
; #pragma unroll
;                     for (int m = 0; m < 4; ++m) { const int row = rowg + m * 16 + fr;
;                         const f32x4 ag = unpack4(pa[ai][0][m][n]);
;                         const f32x4 rg1 = ror1v(ag), rg2 = ror2v(ag);
;                         const f32x4 g1 = fr >= 1 ? rg1 : pg1, g2 = fr >= 2 ? rg2 : pg2;
;                         if (m == 0 && fr < 2) *(f32x4*)(edge + (unsigned)((grp * 4 + fr) * UPN + jn)) = ag;
;                         if (m == 3 && fr >= 14) *(f32x4*)(edge + (unsigned)((grp * 4 + (fr - 12)) * UPN + jn)) = ag;
;                         const f32x4 o = gelu4(bg + wg0 * g2 + wg1 * g1 + wg2 * ag) * cu[m];
;                         if (!(m == 0 && fr < 2)) *(u32x2*)(act + (unsigned)(row * DFF + jn)) = pack4(o);
.Lwj546_14716:
.LBB0_583:
	s_or_b64 exec, exec, s[0:1]
	global_load_dwordx4 v[28:31], v[46:47], off offset:16
	global_load_dwordx4 v[24:27], v[72:73], off
	global_load_dwordx4 v[20:23], v[74:75], off
	global_load_dwordx4 v[32:35], v[48:49], off offset:16
	v_lshlrev_b32_e32 v40, 16, v98
	v_and_b32_e32 v41, 0xffff0000, v98
	v_lshlrev_b32_e32 v42, 16, v99
	v_and_b32_e32 v43, 0xffff0000, v99
	s_nop 1
	v_mov_b32_dpp v46, v40 row_ror:1 row_mask:0xf bank_mask:0xf
	v_mov_b32_dpp v47, v41 row_ror:1 row_mask:0xf bank_mask:0xf
	v_mov_b32_dpp v48, v42 row_ror:1 row_mask:0xf bank_mask:0xf
	v_mov_b32_dpp v49, v43 row_ror:1 row_mask:0xf bank_mask:0xf
	v_mov_b32_dpp v58, v40 row_ror:2 row_mask:0xf bank_mask:0xf
	v_mov_b32_dpp v59, v41 row_ror:2 row_mask:0xf bank_mask:0xf
	v_mov_b32_dpp v60, v42 row_ror:2 row_mask:0xf bank_mask:0xf
	v_mov_b32_dpp v61, v43 row_ror:2 row_mask:0xf bank_mask:0xf
	s_and_saveexec_b64 s[0:1], s[10:11]
	s_xor_b64 s[10:11], exec, s[0:1]
	s_cbranch_execz .LBB0_585
	v_cndmask_b32_e64 v81, 0, v115, s[6:7]
	v_cndmask_b32_e64 v80, 0, v113, s[6:7]
	v_cndmask_b32_e64 v75, 0, v110, s[8:9]
	v_cndmask_b32_e64 v74, 0, v100, s[8:9]
	s_waitcnt vmcnt(4)
	v_pk_fma_f32 v[80:81], v[10:11], v[80:81], v[14:15]
	v_cndmask_b32_e64 v99, 0, v111, s[6:7]
	v_pk_fma_f32 v[74:75], v[6:7], v[74:75], v[80:81]
	v_cndmask_b32_e64 v98, 0, v101, s[6:7]
	v_pk_fma_f32 v[38:39], v[2:3], v[38:39], v[74:75]
	s_waitcnt vmcnt(0)
	v_pk_fma_f32 v[74:75], v[28:29], v[58:59], v[32:33]
	v_cndmask_b32_e64 v73, 0, v108, s[8:9]
	v_pk_fma_f32 v[74:75], v[24:25], v[46:47], v[74:75]
	v_cndmask_b32_e64 v72, 0, v89, s[8:9]
	v_pk_fma_f32 v[40:41], v[20:21], v[40:41], v[74:75]
	v_pk_fma_f32 v[98:99], v[8:9], v[98:99], v[12:13]
	v_and_b32_e32 v81, 0x7fffffff, v41
	v_and_b32_e32 v80, 0x7fffffff, v40
	v_pk_fma_f32 v[80:81], v[80:81], s[42:43], 1.0 op_sel_hi:[1,0,0]
	v_pk_fma_f32 v[72:73], v[4:5], v[72:73], v[98:99]
	v_rcp_f32_e32 v80, v80
	v_rcp_f32_e32 v81, v81
	v_pk_mul_f32 v[74:75], v[40:41], v[40:41]
	v_mov_b64_e32 v[98:99], s[54:55]
	v_pk_mul_f32 v[74:75], v[74:75], s[38:39] op_sel_hi:[1,0]
	v_pk_fma_f32 v[104:105], v[80:81], s[52:53], v[98:99] op_sel_hi:[1,0,0]
	v_exp_f32_e32 v74, v74
	v_exp_f32_e32 v75, v75
	v_pk_fma_f32 v[104:105], v[80:81], v[104:105], s[56:57] op_sel_hi:[1,1,0]
	v_pk_fma_f32 v[36:37], v[0:1], v[36:37], v[72:73]
	v_pk_fma_f32 v[104:105], v[80:81], v[104:105], s[62:63] op_sel_hi:[1,1,0]
	v_pk_fma_f32 v[72:73], v[30:31], v[60:61], v[34:35]
	v_pk_fma_f32 v[104:105], v[80:81], v[104:105], s[64:65] op_sel_hi:[1,1,0]
	v_pk_fma_f32 v[72:73], v[26:27], v[48:49], v[72:73]
	v_pk_mul_f32 v[80:81], v[80:81], v[104:105]
	v_cmp_gt_f32_e64 s[0:1], 0, v40
	v_pk_mul_f32 v[74:75], v[74:75], v[80:81]
	v_pk_fma_f32 v[42:43], v[22:23], v[42:43], v[72:73]
	v_pk_mul_f32 v[80:81], v[40:41], v[74:75]
	v_pk_fma_f32 v[74:75], v[40:41], v[74:75], v[40:41] neg_lo:[1,0,0] neg_hi:[1,0,0]
	v_pk_mul_f32 v[72:73], v[42:43], v[42:43]
	v_cndmask_b32_e64 v40, v74, v80, s[0:1]
	v_cmp_gt_f32_e64 s[0:1], 0, v41
	v_and_b32_e32 v74, 0x7fffffff, v42
	v_pk_mul_f32 v[72:73], v[72:73], s[38:39] op_sel_hi:[1,0]
	v_cndmask_b32_e64 v41, v75, v81, s[0:1]
	v_and_b32_e32 v75, 0x7fffffff, v43
	v_pk_fma_f32 v[74:75], v[74:75], s[42:43], 1.0 op_sel_hi:[1,0,0]
	v_exp_f32_e32 v72, v72
	v_rcp_f32_e32 v74, v74
	v_rcp_f32_e32 v75, v75
	v_exp_f32_e32 v73, v73
	v_cmp_gt_f32_e64 s[0:1], 0, v42
	v_pk_mul_f32 v[36:37], v[36:37], v[40:41]
	v_pk_fma_f32 v[80:81], v[74:75], s[52:53], v[98:99] op_sel_hi:[1,0,0]
	v_add_u32_e32 v136, v82, v50
	v_pk_fma_f32 v[80:81], v[74:75], v[80:81], s[56:57] op_sel_hi:[1,1,0]
	v_cvt_pk_bf16_f32 v36, v36, v37
	s_nop 0
	v_pk_fma_f32 v[80:81], v[74:75], v[80:81], s[62:63] op_sel_hi:[1,1,0]
	s_nop 0
	v_pk_fma_f32 v[80:81], v[74:75], v[80:81], s[64:65] op_sel_hi:[1,1,0]
	s_nop 0
	v_pk_mul_f32 v[74:75], v[74:75], v[80:81]
	s_nop 0
	v_pk_mul_f32 v[72:73], v[72:73], v[74:75]
	s_nop 0
	v_pk_mul_f32 v[74:75], v[42:43], v[72:73]
	v_pk_fma_f32 v[72:73], v[42:43], v[72:73], v[42:43] neg_lo:[1,0,0] neg_hi:[1,0,0]
	s_nop 0
	v_cndmask_b32_e64 v42, v72, v74, s[0:1]
	v_cmp_gt_f32_e64 s[0:1], 0, v43
	s_nop 1
	v_cndmask_b32_e64 v43, v73, v75, s[0:1]
	v_pk_mul_f32 v[38:39], v[38:39], v[42:43]
	s_nop 0
	v_cvt_pk_bf16_f32 v37, v38, v39
	v_lshl_add_u64 v[38:39], v[136:137], 1, s[26:27]
	s_cmp_lg_u32 s99, 0
	s_cbranch_scc1 .Lwt546_14825
	global_store_dwordx2 v[38:39], v[36:37], off
	s_branch .Lwj546_14825

;     __device__ __forceinline__ void operator()(AccRef acc, const Unit& u, int wr, int wc, int fr, int fq) const {
;     ...
;                         if (m == 0 && fr < 2) *(f32x4*)(edge + (unsigned)((grp * 4 + fr) * UPN + jn)) = ag;
.Lwj546_14825:
.LBB0_585:
	s_andn2_saveexec_b64 s[0:1], s[10:11]
	s_cbranch_execz .LBB0_587
	v_add_u32_e32 v136, v50, v80
	v_lshl_add_u64 v[36:37], v[136:137], 2, s[28:29]
	s_cmp_lg_u32 s99, 0
	s_cbranch_scc1 .Lwt546_14832
	global_store_dwordx4 v[36:37], v[40:43], off
	s_branch .Lwj546_14832

; __device__ __forceinline__ f32x4 gelu4(f32x4 v) { const f32x2 a = gelu_pk((f32x2){v[0], v[1]}), b = gelu_pk((f32x2){v[2], v[3]}); return (f32x4){a.x, a.y, b.x, b.y}; }
; __device__ __forceinline__ f32x4 ror1v(f32x4 v) { return (f32x4){dpp_ror1(v[0]), dpp_ror1(v[1]), dpp_ror1(v[2]), dpp_ror1(v[3])}; }
; __device__ __forceinline__ f32x4 ror2v(f32x4 v) { return (f32x4){dpp_ror2(v[0]), dpp_ror2(v[1]), dpp_ror2(v[2]), dpp_ror2(v[3])}; }
; __device__ __forceinline__ u32x2 pack4(f32x4 v) { return (u32x2){pk2(v[0], v[1]), pk2(v[2], v[3])}; }
; __device__ __forceinline__ f32x4 unpack4(u32x2 w) { return (f32x4){bflo(w.x), bfhi(w.x), bflo(w.y), bfhi(w.y)}; }
; __device__ __forceinline__ f32x2 gelu_pk(f32x2 v) {
;     const f32x2 av = __builtin_elementwise_abs(v), d = av * 0.2316418882f + 1.0f;
;     f32x2 t; t.x = __builtin_amdgcn_rcpf(d.x); t.y = __builtin_amdgcn_rcpf(d.y);
;     f32x2 q = t * 0.5307027145f + (-0.7265760135f); q = q * t + 0.7107068705f; q = q * t + (-0.142248368f); q = q * t + 0.127414796f; q = q * t;
;     const f32x2 s = (v * v) * (-0.72134752044f);
;     f32x2 e; e.x = __builtin_amdgcn_exp2f(s.x); e.y = __builtin_amdgcn_exp2f(s.y);
;     const f32x2 m = v * (q * e), r = v - m;
;     f32x2 o; o.x = v.x < 0.f ? m.x : r.x; o.y = v.y < 0.f ? m.y : r.y; return o;
;     __device__ __forceinline__ void operator()(AccRef acc, const Unit& u, int wr, int wc, int fr, int fq) const {
;     ...
;                         cu[m] = bu + wu0 * u2 + wu1 * u1 + wu2 * au;
;     ...
;                     for (int m = 0; m < 4; ++m) { const int row = rowg + m * 16 + fr;
;                         const f32x4 ag = unpack4(pa[ai][0][m][n]);
;                         const f32x4 rg1 = ror1v(ag), rg2 = ror2v(ag);
;                         const f32x4 g1 = fr >= 1 ? rg1 : pg1, g2 = fr >= 2 ? rg2 : pg2;
;                         if (m == 0 && fr < 2) *(f32x4*)(edge + (unsigned)((grp * 4 + fr) * UPN + jn)) = ag;
;                         if (m == 3 && fr >= 14) *(f32x4*)(edge + (unsigned)((grp * 4 + (fr - 12)) * UPN + jn)) = ag;
;                         const f32x4 o = gelu4(bg + wg0 * g2 + wg1 * g1 + wg2 * ag) * cu[m];
;                         if (!(m == 0 && fr < 2)) *(u32x2*)(act + (unsigned)(row * DFF + jn)) = pack4(o);
.Lwj546_14832:
.LBB0_587:
	s_or_b64 exec, exec, s[0:1]
	s_nop 0
	v_cndmask_b32_e64 v41, v115, v114, s[6:7]
	v_cndmask_b32_e64 v40, v113, v112, s[6:7]
	v_cndmask_b32_e64 v43, v111, v109, s[6:7]
	v_cndmask_b32_e64 v42, v101, v91, s[6:7]
	v_cndmask_b32_e64 v37, v108, v102, s[8:9]
	v_cndmask_b32_e64 v36, v89, v88, s[8:9]
	v_cndmask_b32_e64 v39, v110, v103, s[8:9]
	v_cndmask_b32_e64 v38, v100, v90, s[8:9]
	s_waitcnt vmcnt(4)
	v_pk_fma_f32 v[42:43], v[8:9], v[42:43], v[12:13]
	v_pk_fma_f32 v[40:41], v[10:11], v[40:41], v[14:15]
	v_pk_fma_f32 v[36:37], v[4:5], v[36:37], v[42:43]
	v_pk_fma_f32 v[38:39], v[6:7], v[38:39], v[40:41]
	v_pk_fma_f32 v[36:37], v[0:1], v[56:57], v[36:37]
	v_pk_fma_f32 v[38:39], v[2:3], v[54:55], v[38:39]
	v_cndmask_b32_e64 v55, v114, v71, s[6:7]
	v_cndmask_b32_e64 v54, v112, v70, s[6:7]
	v_cndmask_b32_e64 v57, v109, v69, s[6:7]
	v_cndmask_b32_e64 v56, v91, v66, s[6:7]
	v_cndmask_b32_e64 v41, v102, v67, s[8:9]
	v_cndmask_b32_e64 v40, v88, v62, s[8:9]
	v_cndmask_b32_e64 v43, v103, v68, s[8:9]
	v_cndmask_b32_e64 v42, v90, v63, s[8:9]
	v_pk_fma_f32 v[56:57], v[8:9], v[56:57], v[12:13]
	v_pk_fma_f32 v[54:55], v[10:11], v[54:55], v[14:15]
	v_pk_fma_f32 v[40:41], v[4:5], v[40:41], v[56:57]
	v_pk_fma_f32 v[42:43], v[6:7], v[42:43], v[54:55]
	v_pk_fma_f32 v[52:53], v[0:1], v[52:53], v[40:41]
	v_pk_fma_f32 v[54:55], v[2:3], v[44:45], v[42:43]
	v_lshlrev_b32_e32 v40, 16, v96
	v_and_b32_e32 v41, 0xffff0000, v96
	v_lshlrev_b32_e32 v42, 16, v97
	v_and_b32_e32 v43, 0xffff0000, v97
	s_nop 1
	v_mov_b32_dpp v74, v42 row_ror:1 row_mask:0xf bank_mask:0xf
	v_mov_b32_dpp v75, v43 row_ror:1 row_mask:0xf bank_mask:0xf
	v_mov_b32_dpp v80, v40 row_ror:2 row_mask:0xf bank_mask:0xf
	v_mov_b32_dpp v81, v41 row_ror:2 row_mask:0xf bank_mask:0xf
	v_mov_b32_dpp v72, v40 row_ror:1 row_mask:0xf bank_mask:0xf
	v_mov_b32_dpp v73, v41 row_ror:1 row_mask:0xf bank_mask:0xf
	v_cndmask_b32_e64 v45, v49, v75, s[8:9]
	v_cndmask_b32_e64 v44, v48, v74, s[8:9]
	v_cndmask_b32_e64 v49, v59, v81, s[6:7]
	v_cndmask_b32_e64 v48, v58, v80, s[6:7]
	v_cndmask_b32_e64 v47, v47, v73, s[8:9]
	v_cndmask_b32_e64 v46, v46, v72, s[8:9]
	s_waitcnt vmcnt(2)
	v_pk_fma_f32 v[48:49], v[28:29], v[48:49], v[32:33]
	s_nop 1
	v_pk_fma_f32 v[46:47], v[24:25], v[46:47], v[48:49]
	s_nop 1
	v_pk_fma_f32 v[40:41], v[20:21], v[40:41], v[46:47]
	v_mov_b32_dpp v82, v42 row_ror:2 row_mask:0xf bank_mask:0xf
	v_and_b32_e32 v49, 0x7fffffff, v41
	v_and_b32_e32 v48, 0x7fffffff, v40
	v_pk_fma_f32 v[48:49], v[48:49], s[42:43], 1.0 op_sel_hi:[1,0,0]
	v_mov_b32_dpp v88, v43 row_ror:2 row_mask:0xf bank_mask:0xf
	v_rcp_f32_e32 v48, v48
	v_rcp_f32_e32 v49, v49
	v_cndmask_b32_e64 v57, v61, v88, s[6:7]
	v_cndmask_b32_e64 v56, v60, v82, s[6:7]
	v_pk_fma_f32 v[56:57], v[30:31], v[56:57], v[34:35]
	v_pk_mul_f32 v[46:47], v[40:41], v[40:41]
	v_pk_fma_f32 v[44:45], v[26:27], v[44:45], v[56:57]
	v_mov_b64_e32 v[56:57], s[54:55]
	v_pk_mul_f32 v[46:47], v[46:47], s[38:39] op_sel_hi:[1,0]
	v_pk_fma_f32 v[58:59], v[48:49], s[52:53], v[56:57] op_sel_hi:[1,0,0]
	v_exp_f32_e32 v46, v46
	v_exp_f32_e32 v47, v47
	v_pk_fma_f32 v[58:59], v[48:49], v[58:59], s[56:57] op_sel_hi:[1,1,0]
	v_cmp_gt_f32_e64 s[0:1], 0, v40
	v_pk_fma_f32 v[58:59], v[48:49], v[58:59], s[62:63] op_sel_hi:[1,1,0]
	v_pk_fma_f32 v[42:43], v[22:23], v[42:43], v[44:45]
	v_pk_fma_f32 v[58:59], v[48:49], v[58:59], s[64:65] op_sel_hi:[1,1,0]
	v_pk_mul_f32 v[44:45], v[42:43], v[42:43]
	v_pk_mul_f32 v[48:49], v[48:49], v[58:59]
	v_pk_mul_f32 v[44:45], v[44:45], s[38:39] op_sel_hi:[1,0]
	v_pk_mul_f32 v[46:47], v[46:47], v[48:49]
	v_exp_f32_e32 v44, v44
	v_pk_mul_f32 v[48:49], v[40:41], v[46:47]
	v_pk_fma_f32 v[46:47], v[40:41], v[46:47], v[40:41] neg_lo:[1,0,0] neg_hi:[1,0,0]
	v_exp_f32_e32 v45, v45
	v_cndmask_b32_e64 v40, v46, v48, s[0:1]
	v_cmp_gt_f32_e64 s[0:1], 0, v41
	v_and_b32_e32 v46, 0x7fffffff, v42
	v_add_u32_e32 v136, v64, v50
	v_cndmask_b32_e64 v41, v47, v49, s[0:1]
	v_and_b32_e32 v47, 0x7fffffff, v43
	v_pk_fma_f32 v[46:47], v[46:47], s[42:43], 1.0 op_sel_hi:[1,0,0]
	v_cmp_gt_f32_e64 s[0:1], 0, v42
	v_rcp_f32_e32 v46, v46
	v_rcp_f32_e32 v47, v47
	v_pk_mul_f32 v[36:37], v[36:37], v[40:41]
	s_nop 1
	v_cvt_pk_bf16_f32 v36, v36, v37
	v_pk_fma_f32 v[48:49], v[46:47], s[52:53], v[56:57] op_sel_hi:[1,0,0]
	s_nop 1
	v_pk_fma_f32 v[48:49], v[46:47], v[48:49], s[56:57] op_sel_hi:[1,1,0]
	s_nop 0
	v_pk_fma_f32 v[48:49], v[46:47], v[48:49], s[62:63] op_sel_hi:[1,1,0]
	s_nop 0
	v_pk_fma_f32 v[48:49], v[46:47], v[48:49], s[64:65] op_sel_hi:[1,1,0]
	s_nop 0
	v_pk_mul_f32 v[46:47], v[46:47], v[48:49]
	s_nop 0
	v_pk_mul_f32 v[44:45], v[44:45], v[46:47]
	s_nop 0
	v_pk_mul_f32 v[46:47], v[42:43], v[44:45]
	v_pk_fma_f32 v[44:45], v[42:43], v[44:45], v[42:43] neg_lo:[1,0,0] neg_hi:[1,0,0]
	s_nop 0
	v_cndmask_b32_e64 v42, v44, v46, s[0:1]
	v_cmp_gt_f32_e64 s[0:1], 0, v43
	s_nop 1
	v_cndmask_b32_e64 v43, v45, v47, s[0:1]
	v_pk_mul_f32 v[38:39], v[38:39], v[42:43]
	s_nop 1
	v_cvt_pk_bf16_f32 v37, v38, v39
	v_lshl_add_u64 v[38:39], v[136:137], 1, s[26:27]
	s_cmp_lg_u32 s99, 0
	s_cbranch_scc1 .Lwt546_14958
	global_store_dwordx2 v[38:39], v[36:37], off
	s_branch .Lwj546_14958

; __device__ __forceinline__ f32x4 gelu4(f32x4 v) { const f32x2 a = gelu_pk((f32x2){v[0], v[1]}), b = gelu_pk((f32x2){v[2], v[3]}); return (f32x4){a.x, a.y, b.x, b.y}; }
; __device__ __forceinline__ f32x4 ror1v(f32x4 v) { return (f32x4){dpp_ror1(v[0]), dpp_ror1(v[1]), dpp_ror1(v[2]), dpp_ror1(v[3])}; }
; __device__ __forceinline__ f32x4 ror2v(f32x4 v) { return (f32x4){dpp_ror2(v[0]), dpp_ror2(v[1]), dpp_ror2(v[2]), dpp_ror2(v[3])}; }
; __device__ __forceinline__ u32x2 pack4(f32x4 v) { return (u32x2){pk2(v[0], v[1]), pk2(v[2], v[3])}; }
; __device__ __forceinline__ f32x4 unpack4(u32x2 w) { return (f32x4){bflo(w.x), bfhi(w.x), bflo(w.y), bfhi(w.y)}; }
; __device__ __forceinline__ f32x2 gelu_pk(f32x2 v) {
;     const f32x2 av = __builtin_elementwise_abs(v), d = av * 0.2316418882f + 1.0f;
;     f32x2 t; t.x = __builtin_amdgcn_rcpf(d.x); t.y = __builtin_amdgcn_rcpf(d.y);
;     f32x2 q = t * 0.5307027145f + (-0.7265760135f); q = q * t + 0.7107068705f; q = q * t + (-0.142248368f); q = q * t + 0.127414796f; q = q * t;
;     const f32x2 s = (v * v) * (-0.72134752044f);
;     f32x2 e; e.x = __builtin_amdgcn_exp2f(s.x); e.y = __builtin_amdgcn_exp2f(s.y);
;     const f32x2 m = v * (q * e), r = v - m;
;     f32x2 o; o.x = v.x < 0.f ? m.x : r.x; o.y = v.y < 0.f ? m.y : r.y; return o;
;     __device__ __forceinline__ void operator()(AccRef acc, const Unit& u, int wr, int wc, int fr, int fq) const {
;     ...
;                     for (int m = 0; m < 4; ++m) { const int row = rowg + m * 16 + fr;
;                         const f32x4 ag = unpack4(pa[ai][0][m][n]);
;                         const f32x4 rg1 = ror1v(ag), rg2 = ror2v(ag);
;                         const f32x4 g1 = fr >= 1 ? rg1 : pg1, g2 = fr >= 2 ? rg2 : pg2;
;                         if (m == 0 && fr < 2) *(f32x4*)(edge + (unsigned)((grp * 4 + fr) * UPN + jn)) = ag;
;                         if (m == 3 && fr >= 14) *(f32x4*)(edge + (unsigned)((grp * 4 + (fr - 12)) * UPN + jn)) = ag;
;                         const f32x4 o = gelu4(bg + wg0 * g2 + wg1 * g1 + wg2 * ag) * cu[m];
;                         if (!(m == 0 && fr < 2)) *(u32x2*)(act + (unsigned)(row * DFF + jn)) = pack4(o);
.Lwj546_14958:
	v_lshlrev_b32_e32 v36, 16, v94
	v_and_b32_e32 v37, 0xffff0000, v94
	v_lshlrev_b32_e32 v38, 16, v95
	v_mov_b32_dpp v44, v36 row_ror:2 row_mask:0xf bank_mask:0xf
	v_mov_b32_dpp v46, v37 row_ror:2 row_mask:0xf bank_mask:0xf
	v_mov_b32_dpp v40, v36 row_ror:1 row_mask:0xf bank_mask:0xf
	v_mov_b32_dpp v41, v37 row_ror:1 row_mask:0xf bank_mask:0xf
	v_cndmask_b32_e64 v61, v81, v46, s[6:7]
	v_cndmask_b32_e64 v60, v80, v44, s[6:7]
	v_cndmask_b32_e64 v59, v73, v41, s[8:9]
	v_cndmask_b32_e64 v58, v72, v40, s[8:9]
	v_pk_fma_f32 v[60:61], v[28:29], v[60:61], v[32:33]
	v_and_b32_e32 v39, 0xffff0000, v95
	v_pk_fma_f32 v[58:59], v[24:25], v[58:59], v[60:61]
	s_nop 1
	v_pk_fma_f32 v[36:37], v[20:21], v[36:37], v[58:59]
	s_nop 1
	v_and_b32_e32 v61, 0x7fffffff, v37
	v_and_b32_e32 v60, 0x7fffffff, v36
	v_pk_fma_f32 v[60:61], v[60:61], s[42:43], 1.0 op_sel_hi:[1,0,0]
	s_nop 1
	v_rcp_f32_e32 v60, v60
	v_rcp_f32_e32 v61, v61
	v_mov_b32_dpp v45, v38 row_ror:2 row_mask:0xf bank_mask:0xf
	v_mov_b32_dpp v47, v39 row_ror:2 row_mask:0xf bank_mask:0xf
	v_mov_b32_dpp v42, v38 row_ror:1 row_mask:0xf bank_mask:0xf
	v_mov_b32_dpp v43, v39 row_ror:1 row_mask:0xf bank_mask:0xf
	v_cndmask_b32_e64 v73, v88, v47, s[6:7]
	v_cndmask_b32_e64 v72, v82, v45, s[6:7]
	v_cndmask_b32_e64 v49, v75, v43, s[8:9]
	v_cndmask_b32_e64 v48, v74, v42, s[8:9]
	v_pk_fma_f32 v[72:73], v[30:31], v[72:73], v[34:35]
	v_pk_mul_f32 v[58:59], v[36:37], v[36:37]
	v_pk_fma_f32 v[48:49], v[26:27], v[48:49], v[72:73]
	v_pk_mul_f32 v[58:59], v[58:59], s[38:39] op_sel_hi:[1,0]
	v_pk_fma_f32 v[72:73], v[60:61], s[52:53], v[56:57] op_sel_hi:[1,0,0]
	v_exp_f32_e32 v58, v58
	v_exp_f32_e32 v59, v59
	v_pk_fma_f32 v[72:73], v[60:61], v[72:73], s[56:57] op_sel_hi:[1,1,0]
	v_cmp_gt_f32_e64 s[0:1], 0, v36
	v_pk_fma_f32 v[72:73], v[60:61], v[72:73], s[62:63] op_sel_hi:[1,1,0]
	v_pk_fma_f32 v[38:39], v[22:23], v[38:39], v[48:49]
	v_pk_fma_f32 v[72:73], v[60:61], v[72:73], s[64:65] op_sel_hi:[1,1,0]
	v_pk_mul_f32 v[48:49], v[38:39], v[38:39]
	v_pk_mul_f32 v[60:61], v[60:61], v[72:73]
	v_pk_mul_f32 v[48:49], v[48:49], s[38:39] op_sel_hi:[1,0]
	v_pk_mul_f32 v[58:59], v[58:59], v[60:61]
	v_exp_f32_e32 v48, v48
	v_pk_mul_f32 v[60:61], v[36:37], v[58:59]
	v_pk_fma_f32 v[58:59], v[36:37], v[58:59], v[36:37] neg_lo:[1,0,0] neg_hi:[1,0,0]
	v_exp_f32_e32 v49, v49
	v_cndmask_b32_e64 v36, v58, v60, s[0:1]
	v_cmp_gt_f32_e64 s[0:1], 0, v37
	v_and_b32_e32 v58, 0x7fffffff, v38
	v_add_u32_e32 v136, v65, v50
	v_cndmask_b32_e64 v37, v59, v61, s[0:1]
	v_and_b32_e32 v59, 0x7fffffff, v39
	v_pk_fma_f32 v[58:59], v[58:59], s[42:43], 1.0 op_sel_hi:[1,0,0]
	v_cmp_gt_f32_e64 s[0:1], 0, v38
	v_rcp_f32_e32 v58, v58
	v_rcp_f32_e32 v59, v59
	v_pk_mul_f32 v[36:37], v[52:53], v[36:37]
	s_nop 1
	v_cvt_pk_bf16_f32 v36, v36, v37
	v_pk_fma_f32 v[56:57], v[58:59], s[52:53], v[56:57] op_sel_hi:[1,0,0]
	s_nop 1
	v_pk_fma_f32 v[56:57], v[58:59], v[56:57], s[56:57] op_sel_hi:[1,1,0]
	s_nop 0
	v_pk_fma_f32 v[56:57], v[58:59], v[56:57], s[62:63] op_sel_hi:[1,1,0]
	s_nop 0
	v_pk_fma_f32 v[56:57], v[58:59], v[56:57], s[64:65] op_sel_hi:[1,1,0]
	s_nop 0
	v_pk_mul_f32 v[56:57], v[58:59], v[56:57]
	s_nop 0
	v_pk_mul_f32 v[48:49], v[48:49], v[56:57]
	s_nop 0
	v_pk_mul_f32 v[56:57], v[38:39], v[48:49]
	v_pk_fma_f32 v[48:49], v[38:39], v[48:49], v[38:39] neg_lo:[1,0,0] neg_hi:[1,0,0]
	s_nop 0
	v_cndmask_b32_e64 v38, v48, v56, s[0:1]
	v_cmp_gt_f32_e64 s[0:1], 0, v39
	s_nop 1
	v_cndmask_b32_e64 v39, v49, v57, s[0:1]
	v_pk_mul_f32 v[38:39], v[54:55], v[38:39]
	s_nop 1
	v_cvt_pk_bf16_f32 v37, v38, v39
	v_lshl_add_u64 v[38:39], v[136:137], 1, s[26:27]
	s_cmp_lg_u32 s99, 0
	s_cbranch_scc1 .Lwt546_15050
	global_store_dwordx2 v[38:39], v[36:37], off
	s_branch .Lwj546_15050

; __device__ __forceinline__ f32x4 gelu4(f32x4 v) { const f32x2 a = gelu_pk((f32x2){v[0], v[1]}), b = gelu_pk((f32x2){v[2], v[3]}); return (f32x4){a.x, a.y, b.x, b.y}; }
; __device__ __forceinline__ f32x4 ror1v(f32x4 v) { return (f32x4){dpp_ror1(v[0]), dpp_ror1(v[1]), dpp_ror1(v[2]), dpp_ror1(v[3])}; }
; __device__ __forceinline__ f32x4 ror2v(f32x4 v) { return (f32x4){dpp_ror2(v[0]), dpp_ror2(v[1]), dpp_ror2(v[2]), dpp_ror2(v[3])}; }
; __device__ __forceinline__ u32x2 pack4(f32x4 v) { return (u32x2){pk2(v[0], v[1]), pk2(v[2], v[3])}; }
; __device__ __forceinline__ f32x4 unpack4(u32x2 w) { return (f32x4){bflo(w.x), bfhi(w.x), bflo(w.y), bfhi(w.y)}; }
; #define PG8_BAR __builtin_amdgcn_s_barrier()
; template <class Epi>
; __device__ __forceinline__ void gemm_phase(LAS unsigned char* lds, const Gemm g, const StaticOrder& S, const Epi& E) {
;     ...
;         if (wr == 0) PG8_BAR;
;         E(acc, cur, wr, wc, fr, fq);
;         if (!has_next) break;
;     __device__ __forceinline__ void operator()(AccRef acc, const Unit& u, int wr, int wc, int fr, int fq) const {
;     ...
;                     for (int m = 0; m < 4; ++m) { const int row = rowg + m * 16 + fr;
;                         const f32x4 ag = unpack4(pa[ai][0][m][n]);
;                         const f32x4 rg1 = ror1v(ag), rg2 = ror2v(ag);
;                         const f32x4 g1 = fr >= 1 ? rg1 : pg1, g2 = fr >= 2 ? rg2 : pg2;
;                         if (m == 0 && fr < 2) *(f32x4*)(edge + (unsigned)((grp * 4 + fr) * UPN + jn)) = ag;
;                         if (m == 3 && fr >= 14) *(f32x4*)(edge + (unsigned)((grp * 4 + (fr - 12)) * UPN + jn)) = ag;
;                         const f32x4 o = gelu4(bg + wg0 * g2 + wg1 * g1 + wg2 * ag) * cu[m];
;                         if (!(m == 0 && fr < 2)) *(u32x2*)(act + (unsigned)(row * DFF + jn)) = pack4(o);
.Lwj546_15050:
	v_lshlrev_b32_e32 v36, 16, v92
	v_and_b32_e32 v37, 0xffff0000, v92
	v_lshlrev_b32_e32 v38, 16, v93
	v_and_b32_e32 v39, 0xffff0000, v93
	s_nop 1
	v_mov_b32_dpp v48, v36 row_ror:1 row_mask:0xf bank_mask:0xf
	v_mov_b32_dpp v49, v37 row_ror:1 row_mask:0xf bank_mask:0xf
	v_mov_b32_dpp v52, v38 row_ror:1 row_mask:0xf bank_mask:0xf
	v_mov_b32_dpp v53, v39 row_ror:1 row_mask:0xf bank_mask:0xf
	v_mov_b32_dpp v54, v36 row_ror:2 row_mask:0xf bank_mask:0xf
	v_mov_b32_dpp v56, v37 row_ror:2 row_mask:0xf bank_mask:0xf
	v_mov_b32_dpp v55, v38 row_ror:2 row_mask:0xf bank_mask:0xf
	v_mov_b32_dpp v57, v39 row_ror:2 row_mask:0xf bank_mask:0xf
	s_and_saveexec_b64 s[0:1], vcc
	s_cbranch_execz .LBB0_589
	v_add_u32_e32 v136, v50, v51
	v_lshl_add_u64 v[58:59], v[136:137], 2, s[28:29]
	s_cmp_lg_u32 s99, 0
	s_cbranch_scc1 .Lwt546_15069
	global_store_dwordx4 v[58:59], v[36:39], off
	s_branch .Lwj546_15069
.Lwt546_15069:
	global_store_dwordx4 v[58:59], v[36:39], off sc1
.Lwj546_15069:
.LBB0_589:
	s_or_b64 exec, exec, s[0:1]
	v_cndmask_b32_e64 v43, v43, v53, s[8:9]
	v_cndmask_b32_e64 v42, v42, v52, s[8:9]
	v_cndmask_b32_e64 v53, v71, v87, s[6:7]
	v_cndmask_b32_e64 v52, v70, v86, s[6:7]
	v_cndmask_b32_e64 v41, v41, v49, s[8:9]
	v_cndmask_b32_e64 v40, v40, v48, s[8:9]
	v_cndmask_b32_e64 v49, v68, v84, s[8:9]
	v_cndmask_b32_e64 v48, v63, v78, s[8:9]
	v_pk_fma_f32 v[10:11], v[10:11], v[52:53], v[14:15]
	v_cndmask_b32_e64 v59, v46, v56, s[6:7]
	v_cndmask_b32_e64 v58, v44, v54, s[6:7]
	v_pk_fma_f32 v[6:7], v[6:7], v[48:49], v[10:11]
	v_cndmask_b32_e64 v46, v45, v55, s[6:7]
	v_pk_fma_f32 v[2:3], v[2:3], v[18:19], v[6:7]
	v_pk_fma_f32 v[6:7], v[28:29], v[58:59], v[32:33]
	v_cndmask_b32_e64 v55, v69, v85, s[6:7]
	v_pk_fma_f32 v[6:7], v[24:25], v[40:41], v[6:7]
	v_cndmask_b32_e64 v54, v66, v79, s[6:7]
	v_pk_fma_f32 v[6:7], v[20:21], v[36:37], v[6:7]
	v_pk_fma_f32 v[8:9], v[8:9], v[54:55], v[12:13]
	v_and_b32_e32 v13, 0x7fffffff, v7
	v_and_b32_e32 v12, 0x7fffffff, v6
	v_pk_fma_f32 v[12:13], v[12:13], s[42:43], 1.0 op_sel_hi:[1,0,0]
	v_cndmask_b32_e64 v45, v67, v83, s[8:9]
	v_rcp_f32_e32 v12, v12
	v_rcp_f32_e32 v13, v13
	v_cndmask_b32_e64 v44, v62, v77, s[8:9]
	v_pk_fma_f32 v[4:5], v[4:5], v[44:45], v[8:9]
	v_pk_mul_f32 v[10:11], v[6:7], v[6:7]
	v_mov_b64_e32 v[14:15], s[54:55]
	v_pk_fma_f32 v[0:1], v[0:1], v[16:17], v[4:5]
	v_pk_mul_f32 v[10:11], v[10:11], s[38:39] op_sel_hi:[1,0]
	v_pk_fma_f32 v[16:17], v[12:13], s[52:53], v[14:15] op_sel_hi:[1,0,0]
	v_exp_f32_e32 v10, v10
	v_exp_f32_e32 v11, v11
	v_pk_fma_f32 v[16:17], v[12:13], v[16:17], s[56:57] op_sel_hi:[1,1,0]
	v_cndmask_b32_e64 v47, v47, v57, s[6:7]
	v_pk_fma_f32 v[16:17], v[12:13], v[16:17], s[62:63] op_sel_hi:[1,1,0]
	v_pk_fma_f32 v[4:5], v[30:31], v[46:47], v[34:35]
	v_pk_fma_f32 v[16:17], v[12:13], v[16:17], s[64:65] op_sel_hi:[1,1,0]
	v_pk_fma_f32 v[4:5], v[26:27], v[42:43], v[4:5]
	v_pk_mul_f32 v[12:13], v[12:13], v[16:17]
	v_cmp_gt_f32_e32 vcc, 0, v6
	v_pk_mul_f32 v[10:11], v[10:11], v[12:13]
	v_pk_fma_f32 v[4:5], v[22:23], v[38:39], v[4:5]
	v_pk_mul_f32 v[12:13], v[6:7], v[10:11]
	v_pk_fma_f32 v[10:11], v[6:7], v[10:11], v[6:7] neg_lo:[1,0,0] neg_hi:[1,0,0]
	v_pk_mul_f32 v[8:9], v[4:5], v[4:5]
	v_cndmask_b32_e32 v6, v10, v12, vcc
	v_cmp_gt_f32_e32 vcc, 0, v7
	v_and_b32_e32 v10, 0x7fffffff, v4
	v_pk_mul_f32 v[8:9], v[8:9], s[38:39] op_sel_hi:[1,0]
	v_cndmask_b32_e32 v7, v11, v13, vcc
	v_and_b32_e32 v11, 0x7fffffff, v5
	v_pk_fma_f32 v[10:11], v[10:11], s[42:43], 1.0 op_sel_hi:[1,0,0]
	v_exp_f32_e32 v8, v8
	v_rcp_f32_e32 v10, v10
	v_rcp_f32_e32 v11, v11
	v_exp_f32_e32 v9, v9
	v_cmp_gt_f32_e32 vcc, 0, v4
	v_pk_mul_f32 v[0:1], v[0:1], v[6:7]
	v_pk_fma_f32 v[12:13], v[10:11], s[52:53], v[14:15] op_sel_hi:[1,0,0]
	v_add_u32_e32 v136, v76, v50
	v_pk_fma_f32 v[12:13], v[10:11], v[12:13], s[56:57] op_sel_hi:[1,1,0]
	v_cvt_pk_bf16_f32 v0, v0, v1
	s_mov_b64 s[0:1], -1
	v_pk_fma_f32 v[12:13], v[10:11], v[12:13], s[62:63] op_sel_hi:[1,1,0]
	s_nop 0
	v_pk_fma_f32 v[12:13], v[10:11], v[12:13], s[64:65] op_sel_hi:[1,1,0]
	s_nop 0
	v_pk_mul_f32 v[10:11], v[10:11], v[12:13]
	s_nop 0
	v_pk_mul_f32 v[8:9], v[8:9], v[10:11]
	s_nop 0
	v_pk_mul_f32 v[10:11], v[4:5], v[8:9]
	v_pk_fma_f32 v[8:9], v[4:5], v[8:9], v[4:5] neg_lo:[1,0,0] neg_hi:[1,0,0]
	s_nop 0
	v_cndmask_b32_e32 v4, v8, v10, vcc
	v_cmp_gt_f32_e32 vcc, 0, v5
	s_nop 1
	v_cndmask_b32_e32 v5, v9, v11, vcc
	v_pk_mul_f32 v[2:3], v[2:3], v[4:5]
	s_andn2_b64 vcc, exec, s[4:5]
	v_cvt_pk_bf16_f32 v1, v2, v3
	v_lshl_add_u64 v[2:3], v[136:137], 1, s[26:27]
	s_cmp_lg_u32 s99, 0
	s_cbranch_scc1 .Lwt546_15161
	global_store_dwordx2 v[2:3], v[0:1], off
	s_branch .Lwj546_15161

; #define PG8_BAR __builtin_amdgcn_s_barrier()
; template <class Epi>
; __device__ __forceinline__ void gemm_phase(LAS unsigned char* lds, const Gemm g, const StaticOrder& S, const Epi& E) {
;     ...
;         if (!has_next) break;
; #pragma unroll
;         for (int a = 0; a < 2; ++a)
; #pragma unroll
;             for (int b = 0; b < 2; ++b)
; #pragma unroll
;                 for (int m = 0; m < 4; ++m)
; #pragma unroll
;                     for (int n = 0; n < 2; ++n) acc[a][b][m][n] = (f32x4){0.f, 0.f, 0.f, 0.f};
;         cur = nxt; cA = nA; cB = nB; ++ui;
;         if (wr == 1) PG8_BAR;
.Lwj546_15161:
	s_cbranch_vccnz .LBB0_542
	s_andn2_b64 vcc, exec, s[18:19]
	s_cbranch_vccnz .LBB0_541
	s_barrier
	s_branch .LBB0_541

; #define PG8_STAGE(bufoff, gbase, voff) do { _Pragma("unroll") for (int _i = 0; _i < 2; ++_i) \
;         __builtin_amdgcn_global_load_lds((const unsigned*)((const char*)(gbase) + (voff)[_i]), (LAS unsigned*)(lds + (bufoff) + ldsw + _i * 8192), 16, 0, 0); } while (0)
; #define PG8_LDA(dst, b, h) do { _Pragma("unroll") for (int m = 0; m < 4; ++m) _Pragma("unroll") for (int k = 0; k < 2; ++k) dst[m][k] = *(const LAS bf16x8*)(lds + PG8_SA(b, h) + aoff + m * 2048 + k * 1024); } while (0)
; #define PG8_LDB(dst, b, h) do { _Pragma("unroll") for (int n = 0; n < 2; ++n) _Pragma("unroll") for (int k = 0; k < 2; ++k) dst[n][k] = *(const LAS bf16x8*)(lds + PG8_SB(b, h) + boff + n * 2048 + k * 1024); } while (0)
; #define PG8_MMA(ai, bj, At, Bt) do { __builtin_amdgcn_s_setprio(1); _Pragma("unroll") for (int m = 0; m < 4; ++m) _Pragma("unroll") for (int n = 0; n < 2; ++n) _Pragma("unroll") for (int k = 0; k < 2; ++k) \
;         acc[ai][bj][m][n] = __builtin_amdgcn_mfma_f32_16x16x32_bf16(Bt[n][k], At[m][k], acc[ai][bj][m][n], 0, 0, 0); __builtin_amdgcn_s_setprio(0); } while (0)
; #define PG8_WAIT_V(n) asm volatile("s_waitcnt vmcnt(" #n ")" ::: "memory")
; #define PG8_WAIT_L(n) asm volatile("s_waitcnt lgkmcnt(" #n ")" ::: "memory")
; #define PG8_BAR __builtin_amdgcn_s_barrier()
; #define PG8_SCHED __builtin_amdgcn_sched_barrier(0)
; template <class Epi>
; __device__ __forceinline__ void gemm_phase(LAS unsigned char* lds, const Gemm g, const StaticOrder& S, const Epi& E) {
;     ...
;             PG8_LDB(B0, 0, 0); PG8_LDB(B1, 0, 1); PG8_SCHED; PG8_LDA(At, 0, 0); PG8_STAGE(PG8_SA(1, 1), a1 + hstepA, voffA);
;             PG8_WAIT_V(8); PG8_WAIT_L(0); PG8_BAR; PG8_MMA(0, 0, At, B0); PG8_MMA(0, 1, At, B1); PG8_BAR; PG8_SCHED;
;             PG8_LDA(At, 0, 1); PG8_STAGE(PG8_SB(0, 0), b2, voffB); PG8_STAGE(PG8_SB(0, 1), b2 + hstepB, voffB); PG8_STAGE(PG8_SA(0, 0), a2, voffA);
;             PG8_WAIT_V(8); PG8_WAIT_L(0); PG8_BAR; PG8_MMA(1, 0, At, B0); PG8_MMA(1, 1, At, B1); PG8_BAR; PG8_SCHED;
.LBB0_612:
	s_add_u32 s68, s42, s56
	s_addc_u32 s69, s43, s57
	s_add_u32 s64, s68, 0x100
	s_addc_u32 s65, s69, 0
	s_and_b64 s[62:63], s[54:55], exec
	s_cselect_b32 s63, s1, s65
	s_cselect_b32 s62, s19, s64
	s_add_u32 s56, s38, s56
	s_addc_u32 s57, s39, s57
	s_add_u32 s56, s56, 0x100
	s_addc_u32 s57, s57, 0
	s_and_b64 s[54:55], s[54:55], exec
	s_cselect_b32 s65, s13, s57
	s_cselect_b32 s64, s88, s56
	s_add_u32 s70, s68, 0x10080
	ds_read_b128 v[140:143], v145
	ds_read_b128 v[154:157], v145 offset:1024
	ds_read_b128 v[158:161], v145 offset:2048
	ds_read_b128 v[162:165], v145 offset:3072
	ds_read_b128 v[166:169], v146
	ds_read_b128 v[170:173], v146 offset:1024
	ds_read_b128 v[178:181], v146 offset:2048
	ds_read_b128 v[182:185], v146 offset:3072
	s_addc_u32 s71, s69, 0
	s_add_i32 vcc_lo, s86, s72
	s_add_i32 m0, s35, 0xc000
	s_add_i32 vcc_hi, s35, 0xe000
	s_add_i32 s95, vcc_lo, 0x2000
	s_add_u32 s68, s64, 0x10000
	s_addc_u32 s69, s65, 0
	s_add_i32 s97, s87, s72
	s_add_i32 s96, s97, 0x2000
	s_add_i32 s94, 0, 0x18000
	s_add_i32 s93, 0, 0x1c000
	s_add_u32 s56, s62, 0x10000
	s_addc_u32 s57, s63, 0
	s_add_i32 s92, s94, s72
	s_add_i32 s90, s92, 0x2000
	s_add_u32 s54, s64, 0x10080
	s_addc_u32 s55, s65, 0
	s_add_i32 s91, s93, s72
	s_add_i32 s89, s91, 0x2000
	v_lshl_add_u64 v[174:175], s[70:71], 0, v[128:129]
	ds_read_b128 v[186:189], v147
	ds_read_b128 v[190:193], v147 offset:1024
	ds_read_b128 v[194:197], v147 offset:2048
	ds_read_b128 v[198:201], v147 offset:3072
	ds_read_b128 v[202:205], v147 offset:4096
	ds_read_b128 v[206:209], v147 offset:5120
	ds_read_b128 v[210:213], v147 offset:6144
	ds_read_b128 v[214:217], v147 offset:7168
	global_load_lds_dwordx4 v[174:175], off
	v_lshl_add_u64 v[174:175], s[70:71], 0, v[132:133]
	s_mov_b32 m0, vcc_hi
	s_nop 0
	global_load_lds_dwordx4 v[174:175], off
	s_waitcnt vmcnt(8)
	s_waitcnt lgkmcnt(0)
	s_barrier
	s_setprio 1
	s_waitcnt lgkmcnt(0)
	v_mfma_f32_16x16x32_bf16 v[124:127], v[140:143], v[186:189], v[124:127]
	v_mfma_f32_16x16x32_bf16 v[120:123], v[158:161], v[186:189], v[120:123]
	v_mfma_f32_16x16x32_bf16 v[108:111], v[140:143], v[194:197], v[108:111]
	v_mfma_f32_16x16x32_bf16 v[104:107], v[158:161], v[194:197], v[104:107]
	v_mfma_f32_16x16x32_bf16 v[92:95], v[140:143], v[202:205], v[92:95]
	v_mfma_f32_16x16x32_bf16 v[88:91], v[158:161], v[202:205], v[88:91]
	v_mfma_f32_16x16x32_bf16 v[76:79], v[140:143], v[210:213], v[76:79]
	v_mfma_f32_16x16x32_bf16 v[72:75], v[158:161], v[210:213], v[72:75]
	v_mfma_f32_16x16x32_bf16 v[124:127], v[154:157], v[190:193], v[124:127]
	v_mfma_f32_16x16x32_bf16 v[120:123], v[162:165], v[190:193], v[120:123]
	v_mfma_f32_16x16x32_bf16 v[108:111], v[154:157], v[198:201], v[108:111]
	v_mfma_f32_16x16x32_bf16 v[104:107], v[162:165], v[198:201], v[104:107]
	v_mfma_f32_16x16x32_bf16 v[92:95], v[154:157], v[206:209], v[92:95]
	v_mfma_f32_16x16x32_bf16 v[88:91], v[162:165], v[206:209], v[88:91]
	v_mfma_f32_16x16x32_bf16 v[76:79], v[154:157], v[214:217], v[76:79]
	v_mfma_f32_16x16x32_bf16 v[72:75], v[162:165], v[214:217], v[72:75]
	s_setprio 0
	s_setprio 1
	v_mfma_f32_16x16x32_bf16 v[116:119], v[166:169], v[186:189], v[116:119]
	v_mfma_f32_16x16x32_bf16 v[112:115], v[178:181], v[186:189], v[112:115]
	v_mfma_f32_16x16x32_bf16 v[100:103], v[166:169], v[194:197], v[100:103]
	v_mfma_f32_16x16x32_bf16 v[96:99], v[178:181], v[194:197], v[96:99]
	v_mfma_f32_16x16x32_bf16 v[84:87], v[166:169], v[202:205], v[84:87]
	v_mfma_f32_16x16x32_bf16 v[80:83], v[178:181], v[202:205], v[80:83]
	v_mfma_f32_16x16x32_bf16 v[68:71], v[166:169], v[210:213], v[68:71]
	v_mfma_f32_16x16x32_bf16 v[64:67], v[178:181], v[210:213], v[64:67]
	v_mfma_f32_16x16x32_bf16 v[116:119], v[170:173], v[190:193], v[116:119]
	v_mfma_f32_16x16x32_bf16 v[112:115], v[182:185], v[190:193], v[112:115]
	v_mfma_f32_16x16x32_bf16 v[100:103], v[170:173], v[198:201], v[100:103]
	v_mfma_f32_16x16x32_bf16 v[96:99], v[182:185], v[198:201], v[96:99]
	v_mfma_f32_16x16x32_bf16 v[84:87], v[170:173], v[206:209], v[84:87]
	v_mfma_f32_16x16x32_bf16 v[80:83], v[182:185], v[206:209], v[80:83]
	v_mfma_f32_16x16x32_bf16 v[68:71], v[170:173], v[214:217], v[68:71]
	v_mfma_f32_16x16x32_bf16 v[64:67], v[182:185], v[214:217], v[64:67]
	s_setprio 0
	s_barrier
	s_mov_b32 m0, vcc_lo
	v_lshl_add_u64 v[174:175], s[64:65], 0, v[130:131]
	ds_read_b128 v[186:189], v147 offset:16384
	ds_read_b128 v[190:193], v147 offset:17408
	ds_read_b128 v[194:197], v147 offset:18432
	ds_read_b128 v[198:201], v147 offset:19456
	ds_read_b128 v[202:205], v147 offset:20480
	ds_read_b128 v[206:209], v147 offset:21504
	ds_read_b128 v[210:213], v147 offset:22528
	ds_read_b128 v[214:217], v147 offset:23552
	global_load_lds_dwordx4 v[174:175], off
	v_lshl_add_u64 v[218:219], s[64:65], 0, v[134:135]
	s_mov_b32 m0, s95
	v_lshl_add_u64 v[220:221], s[68:69], 0, v[130:131]
	global_load_lds_dwordx4 v[218:219], off
	s_mov_b32 m0, s97
	v_lshl_add_u64 v[222:223], s[62:63], 0, v[132:133]
	global_load_lds_dwordx4 v[220:221], off
	v_lshl_add_u64 v[220:221], s[68:69], 0, v[134:135]
	s_mov_b32 m0, s96
	s_nop 0
	global_load_lds_dwordx4 v[220:221], off
	v_lshl_add_u64 v[220:221], s[62:63], 0, v[128:129]
	s_mov_b32 m0, s35
	s_nop 0
	global_load_lds_dwordx4 v[220:221], off
	s_mov_b32 m0, s75
	s_nop 0
	global_load_lds_dwordx4 v[222:223], off
	s_waitcnt vmcnt(8)
	s_waitcnt lgkmcnt(0)
	s_barrier
; #define PG8_STAGE(bufoff, gbase, voff) do { _Pragma("unroll") for (int _i = 0; _i < 2; ++_i) \
;         __builtin_amdgcn_global_load_lds((const unsigned*)((const char*)(gbase) + (voff)[_i]), (LAS unsigned*)(lds + (bufoff) + ldsw + _i * 8192), 16, 0, 0); } while (0)
; #define PG8_LDA(dst, b, h) do { _Pragma("unroll") for (int m = 0; m < 4; ++m) _Pragma("unroll") for (int k = 0; k < 2; ++k) dst[m][k] = *(const LAS bf16x8*)(lds + PG8_SA(b, h) + aoff + m * 2048 + k * 1024); } while (0)
; #define PG8_LDB(dst, b, h) do { _Pragma("unroll") for (int n = 0; n < 2; ++n) _Pragma("unroll") for (int k = 0; k < 2; ++k) dst[n][k] = *(const LAS bf16x8*)(lds + PG8_SB(b, h) + boff + n * 2048 + k * 1024); } while (0)
; #define PG8_MMA(ai, bj, At, Bt) do { __builtin_amdgcn_s_setprio(1); _Pragma("unroll") for (int m = 0; m < 4; ++m) _Pragma("unroll") for (int n = 0; n < 2; ++n) _Pragma("unroll") for (int k = 0; k < 2; ++k) \
;         acc[ai][bj][m][n] = __builtin_amdgcn_mfma_f32_16x16x32_bf16(Bt[n][k], At[m][k], acc[ai][bj][m][n], 0, 0, 0); __builtin_amdgcn_s_setprio(0); } while (0)
; #define PG8_WAIT_V(n) asm volatile("s_waitcnt vmcnt(" #n ")" ::: "memory")
; #define PG8_WAIT_L(n) asm volatile("s_waitcnt lgkmcnt(" #n ")" ::: "memory")
; #define PG8_BAR __builtin_amdgcn_s_barrier()
; #define PG8_SCHED __builtin_amdgcn_sched_barrier(0)
; template <class Epi>
; __device__ __forceinline__ void gemm_phase(LAS unsigned char* lds, const Gemm g, const StaticOrder& S, const Epi& E) {
;     ...
;             PG8_WAIT_V(8); PG8_WAIT_L(0); PG8_BAR; PG8_MMA(1, 0, At, B0); PG8_MMA(1, 1, At, B1); PG8_BAR; PG8_SCHED;
;             PG8_LDB(B0, 1, 0); PG8_LDB(B1, 1, 1); PG8_SCHED; PG8_LDA(At, 1, 0); PG8_STAGE(PG8_SA(0, 1), a2 + hstepA, voffA);
;             PG8_WAIT_V(8); PG8_WAIT_L(0); PG8_BAR; PG8_MMA(0, 0, At, B0); PG8_MMA(0, 1, At, B1); PG8_BAR; PG8_SCHED;
;             PG8_LDA(At, 1, 1); PG8_STAGE(PG8_SB(1, 0), b3, voffB); PG8_STAGE(PG8_SB(1, 1), b3 + hstepB, voffB); PG8_STAGE(PG8_SA(1, 0), a3, voffA);
	s_setprio 1
	s_waitcnt lgkmcnt(0)
	v_mfma_f32_16x16x32_bf16 v[60:63], v[140:143], v[186:189], v[60:63]
	v_mfma_f32_16x16x32_bf16 v[56:59], v[158:161], v[186:189], v[56:59]
	v_mfma_f32_16x16x32_bf16 v[44:47], v[140:143], v[194:197], v[44:47]
	v_mfma_f32_16x16x32_bf16 v[40:43], v[158:161], v[194:197], v[40:43]
	v_mfma_f32_16x16x32_bf16 v[28:31], v[140:143], v[202:205], v[28:31]
	v_mfma_f32_16x16x32_bf16 v[24:27], v[158:161], v[202:205], v[24:27]
	v_mfma_f32_16x16x32_bf16 v[12:15], v[140:143], v[210:213], v[12:15]
	v_mfma_f32_16x16x32_bf16 v[8:11], v[158:161], v[210:213], v[8:11]
	v_mfma_f32_16x16x32_bf16 v[60:63], v[154:157], v[190:193], v[60:63]
	v_mfma_f32_16x16x32_bf16 v[56:59], v[162:165], v[190:193], v[56:59]
	v_mfma_f32_16x16x32_bf16 v[44:47], v[154:157], v[198:201], v[44:47]
	v_mfma_f32_16x16x32_bf16 v[40:43], v[162:165], v[198:201], v[40:43]
	v_mfma_f32_16x16x32_bf16 v[28:31], v[154:157], v[206:209], v[28:31]
	v_mfma_f32_16x16x32_bf16 v[24:27], v[162:165], v[206:209], v[24:27]
	v_mfma_f32_16x16x32_bf16 v[12:15], v[154:157], v[214:217], v[12:15]
	v_mfma_f32_16x16x32_bf16 v[8:11], v[162:165], v[214:217], v[8:11]
	s_setprio 0
	s_setprio 1
	v_mfma_f32_16x16x32_bf16 v[52:55], v[166:169], v[186:189], v[52:55]
	v_mfma_f32_16x16x32_bf16 v[48:51], v[178:181], v[186:189], v[48:51]
	v_mfma_f32_16x16x32_bf16 v[36:39], v[166:169], v[194:197], v[36:39]
	v_mfma_f32_16x16x32_bf16 v[32:35], v[178:181], v[194:197], v[32:35]
	v_mfma_f32_16x16x32_bf16 v[20:23], v[166:169], v[202:205], v[20:23]
	v_mfma_f32_16x16x32_bf16 v[16:19], v[178:181], v[202:205], v[16:19]
	v_mfma_f32_16x16x32_bf16 v[4:7], v[166:169], v[210:213], v[4:7]
	v_mfma_f32_16x16x32_bf16 v[0:3], v[178:181], v[210:213], v[0:3]
	v_mfma_f32_16x16x32_bf16 v[52:55], v[170:173], v[190:193], v[52:55]
	v_mfma_f32_16x16x32_bf16 v[48:51], v[182:185], v[190:193], v[48:51]
	v_mfma_f32_16x16x32_bf16 v[36:39], v[170:173], v[198:201], v[36:39]
	v_mfma_f32_16x16x32_bf16 v[32:35], v[182:185], v[198:201], v[32:35]
	v_mfma_f32_16x16x32_bf16 v[20:23], v[170:173], v[206:209], v[20:23]
	v_mfma_f32_16x16x32_bf16 v[16:19], v[182:185], v[206:209], v[16:19]
	v_mfma_f32_16x16x32_bf16 v[4:7], v[170:173], v[214:217], v[4:7]
	v_mfma_f32_16x16x32_bf16 v[0:3], v[182:185], v[214:217], v[0:3]
	s_setprio 0
	s_barrier
	v_add_u32_e32 v149, s94, v144
	ds_read_b128 v[140:143], v149
	ds_read_b128 v[154:157], v149 offset:1024
	ds_read_b128 v[158:161], v149 offset:2048
	ds_read_b128 v[162:165], v149 offset:3072
	v_add_u32_e32 v149, s93, v144
	ds_read_b128 v[166:169], v149
	ds_read_b128 v[170:173], v149 offset:1024
	ds_read_b128 v[178:181], v149 offset:2048
	ds_read_b128 v[182:185], v149 offset:3072
	s_mov_b32 m0, s76
	v_lshl_add_u64 v[226:227], s[56:57], 0, v[128:129]
	ds_read_b128 v[186:189], v147 offset:32768
	ds_read_b128 v[190:193], v147 offset:33792
	ds_read_b128 v[194:197], v147 offset:34816
	ds_read_b128 v[198:201], v147 offset:35840
	ds_read_b128 v[202:205], v147 offset:36864
	ds_read_b128 v[206:209], v147 offset:37888
	ds_read_b128 v[210:213], v147 offset:38912
	ds_read_b128 v[214:217], v147 offset:39936
	global_load_lds_dwordx4 v[226:227], off
	v_lshl_add_u64 v[226:227], s[56:57], 0, v[132:133]
	s_mov_b32 m0, s77
	s_nop 0
	global_load_lds_dwordx4 v[226:227], off
	s_waitcnt vmcnt(8)
	s_waitcnt lgkmcnt(0)
	s_barrier
	s_setprio 1
	s_waitcnt lgkmcnt(0)
	v_mfma_f32_16x16x32_bf16 v[124:127], v[140:143], v[186:189], v[124:127]
	v_mfma_f32_16x16x32_bf16 v[120:123], v[158:161], v[186:189], v[120:123]
	v_mfma_f32_16x16x32_bf16 v[108:111], v[140:143], v[194:197], v[108:111]
	v_mfma_f32_16x16x32_bf16 v[104:107], v[158:161], v[194:197], v[104:107]
	v_mfma_f32_16x16x32_bf16 v[92:95], v[140:143], v[202:205], v[92:95]
	v_mfma_f32_16x16x32_bf16 v[88:91], v[158:161], v[202:205], v[88:91]
	v_mfma_f32_16x16x32_bf16 v[76:79], v[140:143], v[210:213], v[76:79]
	v_mfma_f32_16x16x32_bf16 v[72:75], v[158:161], v[210:213], v[72:75]
	v_mfma_f32_16x16x32_bf16 v[124:127], v[154:157], v[190:193], v[124:127]
	v_mfma_f32_16x16x32_bf16 v[120:123], v[162:165], v[190:193], v[120:123]
	v_mfma_f32_16x16x32_bf16 v[108:111], v[154:157], v[198:201], v[108:111]
	v_mfma_f32_16x16x32_bf16 v[104:107], v[162:165], v[198:201], v[104:107]
	v_mfma_f32_16x16x32_bf16 v[92:95], v[154:157], v[206:209], v[92:95]
	v_mfma_f32_16x16x32_bf16 v[88:91], v[162:165], v[206:209], v[88:91]
	v_mfma_f32_16x16x32_bf16 v[76:79], v[154:157], v[214:217], v[76:79]
	v_mfma_f32_16x16x32_bf16 v[72:75], v[162:165], v[214:217], v[72:75]
	s_setprio 0
	s_setprio 1
	v_mfma_f32_16x16x32_bf16 v[116:119], v[166:169], v[186:189], v[116:119]
	v_mfma_f32_16x16x32_bf16 v[112:115], v[178:181], v[186:189], v[112:115]
	v_mfma_f32_16x16x32_bf16 v[100:103], v[166:169], v[194:197], v[100:103]
	v_mfma_f32_16x16x32_bf16 v[96:99], v[178:181], v[194:197], v[96:99]
	v_mfma_f32_16x16x32_bf16 v[84:87], v[166:169], v[202:205], v[84:87]
	v_mfma_f32_16x16x32_bf16 v[80:83], v[178:181], v[202:205], v[80:83]
	v_mfma_f32_16x16x32_bf16 v[68:71], v[166:169], v[210:213], v[68:71]
	v_mfma_f32_16x16x32_bf16 v[64:67], v[178:181], v[210:213], v[64:67]
	v_mfma_f32_16x16x32_bf16 v[116:119], v[170:173], v[190:193], v[116:119]
	v_mfma_f32_16x16x32_bf16 v[112:115], v[182:185], v[190:193], v[112:115]
	v_mfma_f32_16x16x32_bf16 v[100:103], v[170:173], v[198:201], v[100:103]
	v_mfma_f32_16x16x32_bf16 v[96:99], v[182:185], v[198:201], v[96:99]
	v_mfma_f32_16x16x32_bf16 v[84:87], v[170:173], v[206:209], v[84:87]
	v_mfma_f32_16x16x32_bf16 v[80:83], v[182:185], v[206:209], v[80:83]
	v_mfma_f32_16x16x32_bf16 v[68:71], v[170:173], v[214:217], v[68:71]
	v_mfma_f32_16x16x32_bf16 v[64:67], v[182:185], v[214:217], v[64:67]
	s_setprio 0
	s_barrier
; #define PG8_STAGE(bufoff, gbase, voff) do { _Pragma("unroll") for (int _i = 0; _i < 2; ++_i) \
;         __builtin_amdgcn_global_load_lds((const unsigned*)((const char*)(gbase) + (voff)[_i]), (LAS unsigned*)(lds + (bufoff) + ldsw + _i * 8192), 16, 0, 0); } while (0)
; #define PG8_LDA(dst, b, h) do { _Pragma("unroll") for (int m = 0; m < 4; ++m) _Pragma("unroll") for (int k = 0; k < 2; ++k) dst[m][k] = *(const LAS bf16x8*)(lds + PG8_SA(b, h) + aoff + m * 2048 + k * 1024); } while (0)
; #define PG8_MMA(ai, bj, At, Bt) do { __builtin_amdgcn_s_setprio(1); _Pragma("unroll") for (int m = 0; m < 4; ++m) _Pragma("unroll") for (int n = 0; n < 2; ++n) _Pragma("unroll") for (int k = 0; k < 2; ++k) \
;         acc[ai][bj][m][n] = __builtin_amdgcn_mfma_f32_16x16x32_bf16(Bt[n][k], At[m][k], acc[ai][bj][m][n], 0, 0, 0); __builtin_amdgcn_s_setprio(0); } while (0)
; #define PG8_WAIT_V(n) asm volatile("s_waitcnt vmcnt(" #n ")" ::: "memory")
; #define PG8_WAIT_L(n) asm volatile("s_waitcnt lgkmcnt(" #n ")" ::: "memory")
; #define PG8_BAR __builtin_amdgcn_s_barrier()
; #define PG8_SCHED __builtin_amdgcn_sched_barrier(0)
; #define EPI_IT_ROW(it) EPI_ROW((it) >> 2, (it) & 3)
; template <class Epi>
; __device__ __forceinline__ void gemm_phase(LAS unsigned char* lds, const Gemm g, const StaticOrder& S, const Epi& E) {
;     ...
;             PG8_LDA(At, 1, 1); PG8_STAGE(PG8_SB(1, 0), b3, voffB); PG8_STAGE(PG8_SB(1, 1), b3 + hstepB, voffB); PG8_STAGE(PG8_SA(1, 0), a3, voffA);
;             PG8_WAIT_V(8); PG8_WAIT_L(0); PG8_BAR; PG8_MMA(1, 0, At, B0); PG8_MMA(1, 1, At, B1); PG8_BAR; PG8_SCHED;
;         }
;         if (wr == 0) PG8_BAR;
;     __device__ __forceinline__ void operator()(AccRef acc, const Unit& u, int wr, int wc, int fr, int fq) const {
;         asm volatile("" : "+v"(fr), "+v"(fq));
; #pragma unroll
;         for (int it = 0; it < 8; ++it) { const int ai = it >> 2, m = it & 3, row = EPI_IT_ROW(it); float q = 0.f;
; #pragma unroll
;             for (int bj = 0; bj < 2; ++bj) { const f32x4 x0 = acc[ai][bj][m][0], x1 = acc[ai][bj][m][1];
;                 *(u32x4*)(O + (size_t)row * DM + EPI_COL(bj)) = EPI_PACK8(x0, x1);
;                 q += EPI_SQ8(x0, x1); }
;             q += __shfl_xor(q, 16); q += __shfl_xor(q, 32);
;             if (fq == 0) atomicAdd(ssout + row, q); }
	s_mov_b32 m0, s92
	v_lshl_add_u64 v[174:175], v[174:175], 0, s[8:9]
	ds_read_b128 v[186:189], v147 offset:49152
	ds_read_b128 v[190:193], v147 offset:50176
	ds_read_b128 v[194:197], v147 offset:51200
	ds_read_b128 v[198:201], v147 offset:52224
	ds_read_b128 v[202:205], v147 offset:53248
	ds_read_b128 v[206:209], v147 offset:54272
	ds_read_b128 v[210:213], v147 offset:55296
	ds_read_b128 v[214:217], v147 offset:56320
	global_load_lds_dwordx4 v[174:175], off
	v_lshl_add_u64 v[174:175], v[218:219], 0, s[8:9]
	s_mov_b32 m0, s90
	s_nop 0
	global_load_lds_dwordx4 v[174:175], off
	v_lshl_add_u64 v[174:175], s[54:55], 0, v[130:131]
	s_mov_b32 m0, s91
	s_nop 0
	global_load_lds_dwordx4 v[174:175], off
	v_lshl_add_u64 v[174:175], s[54:55], 0, v[134:135]
	s_mov_b32 m0, s89
	s_nop 0
	global_load_lds_dwordx4 v[174:175], off
	v_lshl_add_u64 v[174:175], v[220:221], 0, s[8:9]
	s_mov_b32 m0, s81
	s_nop 0
	global_load_lds_dwordx4 v[174:175], off
	v_lshl_add_u64 v[174:175], v[222:223], 0, s[8:9]
	s_mov_b32 m0, s82
	s_nop 0
	global_load_lds_dwordx4 v[174:175], off
	s_waitcnt vmcnt(8)
	s_waitcnt lgkmcnt(0)
	s_barrier
	s_setprio 1
	s_waitcnt lgkmcnt(0)
	v_mfma_f32_16x16x32_bf16 v[60:63], v[140:143], v[186:189], v[60:63]
	v_mfma_f32_16x16x32_bf16 v[56:59], v[158:161], v[186:189], v[56:59]
	v_mfma_f32_16x16x32_bf16 v[44:47], v[140:143], v[194:197], v[44:47]
	v_mfma_f32_16x16x32_bf16 v[40:43], v[158:161], v[194:197], v[40:43]
	v_mfma_f32_16x16x32_bf16 v[28:31], v[140:143], v[202:205], v[28:31]
	v_mfma_f32_16x16x32_bf16 v[24:27], v[158:161], v[202:205], v[24:27]
	v_mfma_f32_16x16x32_bf16 v[12:15], v[140:143], v[210:213], v[12:15]
	v_mfma_f32_16x16x32_bf16 v[8:11], v[158:161], v[210:213], v[8:11]
	v_mfma_f32_16x16x32_bf16 v[60:63], v[154:157], v[190:193], v[60:63]
	v_mfma_f32_16x16x32_bf16 v[56:59], v[162:165], v[190:193], v[56:59]
	v_mfma_f32_16x16x32_bf16 v[44:47], v[154:157], v[198:201], v[44:47]
	v_mfma_f32_16x16x32_bf16 v[40:43], v[162:165], v[198:201], v[40:43]
	v_mfma_f32_16x16x32_bf16 v[28:31], v[154:157], v[206:209], v[28:31]
	v_mfma_f32_16x16x32_bf16 v[24:27], v[162:165], v[206:209], v[24:27]
	v_mfma_f32_16x16x32_bf16 v[12:15], v[154:157], v[214:217], v[12:15]
	v_mfma_f32_16x16x32_bf16 v[8:11], v[162:165], v[214:217], v[8:11]
	s_setprio 0
	s_setprio 1
	v_mfma_f32_16x16x32_bf16 v[52:55], v[166:169], v[186:189], v[52:55]
	v_mfma_f32_16x16x32_bf16 v[48:51], v[178:181], v[186:189], v[48:51]
	v_mfma_f32_16x16x32_bf16 v[36:39], v[166:169], v[194:197], v[36:39]
	v_mfma_f32_16x16x32_bf16 v[32:35], v[178:181], v[194:197], v[32:35]
	v_mfma_f32_16x16x32_bf16 v[20:23], v[166:169], v[202:205], v[20:23]
	v_mfma_f32_16x16x32_bf16 v[16:19], v[178:181], v[202:205], v[16:19]
	v_mfma_f32_16x16x32_bf16 v[4:7], v[166:169], v[210:213], v[4:7]
	v_mfma_f32_16x16x32_bf16 v[0:3], v[178:181], v[210:213], v[0:3]
	v_mfma_f32_16x16x32_bf16 v[52:55], v[170:173], v[190:193], v[52:55]
	v_mfma_f32_16x16x32_bf16 v[48:51], v[182:185], v[190:193], v[48:51]
	v_mfma_f32_16x16x32_bf16 v[36:39], v[170:173], v[198:201], v[36:39]
	v_mfma_f32_16x16x32_bf16 v[32:35], v[182:185], v[198:201], v[32:35]
	v_mfma_f32_16x16x32_bf16 v[20:23], v[170:173], v[206:209], v[20:23]
	v_mfma_f32_16x16x32_bf16 v[16:19], v[182:185], v[206:209], v[16:19]
	v_mfma_f32_16x16x32_bf16 v[4:7], v[170:173], v[214:217], v[4:7]
	v_mfma_f32_16x16x32_bf16 v[0:3], v[182:185], v[214:217], v[0:3]
	s_setprio 0
	s_barrier
	s_andn2_b64 vcc, exec, s[52:53]
	s_mov_b64 s[54:55], -1
	s_mov_b64 s[52:53], 0
	s_mov_b64 s[56:57], 0x100
	s_cbranch_vccz .LBB0_612
	s_cmp_eq_u64 s[4:5], 0
	s_cselect_b32 s99, 1, 0
	s_and_b64 vcc, exec, s[10:11]
	s_cbranch_vccz .LBB0_615
	s_barrier
.LBB0_615:
	v_cvt_pk_bf16_f32 v154, v124, v125
	v_mul_f32_e32 v125, v125, v125
	v_fmac_f32_e32 v125, v124, v124
	v_mul_f32_e32 v124, v127, v127
	v_cvt_pk_bf16_f32 v156, v120, v121
	v_fmac_f32_e32 v124, v126, v126
	v_mul_f32_e32 v121, v121, v121
	v_add_f32_e32 v124, v125, v124
	v_fmac_f32_e32 v121, v120, v120
	v_add_f32_e32 v120, v124, v121
	v_mul_f32_e32 v121, v123, v123
	v_fmac_f32_e32 v121, v122, v122
	v_cvt_pk_bf16_f32 v157, v122, v123
	v_add_f32_e32 v120, v121, v120
	v_mul_f32_e32 v121, v117, v117
	v_mul_f32_e32 v122, v119, v119
	v_fmac_f32_e32 v121, v116, v116
	v_fmac_f32_e32 v122, v118, v118
	v_add_f32_e32 v121, v121, v122
	v_mul_f32_e32 v122, v113, v113
	v_fmac_f32_e32 v122, v112, v112
	v_add_f32_e32 v121, v121, v122
	v_mul_f32_e32 v122, v115, v115
	v_fmac_f32_e32 v122, v114, v114
	v_mov_b32_e32 v140, v151
	v_mov_b32_e32 v141, v153
	s_lshl_b32 s1, s34, 8
	s_lshl_b32 s0, s0, 8
	v_add_f32_e32 v121, v122, v121
	v_and_b32_e32 v122, 64, v148
	s_add_i32 s1, s1, s79
	s_or_b32 s0, s0, s80
	v_add_f32_e32 v121, v120, v121
	v_xor_b32_e32 v120, 16, v148
	v_add_u32_e32 v123, 64, v122
	v_add_u32_e32 v142, s1, v140
	v_lshl_add_u32 v140, v141, 3, s0
	v_cmp_lt_i32_e64 s[0:1], v120, v123
	v_cvt_pk_bf16_f32 v122, v116, v117
	v_xor_b32_e32 v116, 32, v148
	v_ashrrev_i32_e32 v143, 31, v142
	v_cndmask_b32_e64 v120, v148, v120, s[0:1]
	v_lshlrev_b32_e32 v120, 2, v120
	ds_bpermute_b32 v124, v120, v121
	v_cmp_lt_i32_e64 s[0:1], v116, v123
	v_lshlrev_b64 v[158:159], 11, v[142:143]
	v_cmp_eq_u32_e32 vcc, 0, v141
	v_cndmask_b32_e64 v116, v148, v116, s[0:1]
	s_waitcnt lgkmcnt(0)
	v_add_f32_e32 v117, v121, v124
	v_lshlrev_b32_e32 v116, 2, v116
	ds_bpermute_b32 v121, v116, v117
	v_lshl_add_u64 v[158:159], s[40:41], 0, v[158:159]
	v_ashrrev_i32_e32 v141, 31, v140
	v_cvt_pk_bf16_f32 v155, v126, v127
	v_lshl_add_u64 v[126:127], v[140:141], 1, v[158:159]
	s_cmp_lg_u32 s99, 0
	s_cbranch_scc1 .Lwt612_15983
	global_store_dwordx4 v[126:127], v[154:157], off
	s_branch .Lwj612_15983
; #define EPI_IT_ROW(it) EPI_ROW((it) >> 2, (it) & 3)
; #define EPI_PACK8(v0, v1) (u32x4){pk2((v0)[0], (v0)[1]), pk2((v0)[2], (v0)[3]), pk2((v1)[0], (v1)[1]), pk2((v1)[2], (v1)[3])}
;     __device__ __forceinline__ void operator()(AccRef acc, const Unit& u, int wr, int wc, int fr, int fq) const {
;         asm volatile("" : "+v"(fr), "+v"(fq));
; #pragma unroll
;         for (int it = 0; it < 8; ++it) { const int ai = it >> 2, m = it & 3, row = EPI_IT_ROW(it); float q = 0.f;
; #pragma unroll
;             for (int bj = 0; bj < 2; ++bj) { const f32x4 x0 = acc[ai][bj][m][0], x1 = acc[ai][bj][m][1];
;                 *(u32x4*)(O + (size_t)row * DM + EPI_COL(bj)) = EPI_PACK8(x0, x1);
;                 q += EPI_SQ8(x0, x1); }
;             q += __shfl_xor(q, 16); q += __shfl_xor(q, 32);
;             if (fq == 0) atomicAdd(ssout + row, q); }
.Lwt612_15983:
	global_store_dwordx4 v[126:127], v[154:157], off sc1
.Lwj612_15983:
	v_cvt_pk_bf16_f32 v123, v118, v119
	v_cvt_pk_bf16_f32 v124, v112, v113
	v_cvt_pk_bf16_f32 v125, v114, v115
	s_cmp_lg_u32 s99, 0
	s_cbranch_scc1 .Lwt612_15993
	global_store_dwordx4 v[126:127], v[122:125], off offset:256
	s_branch .Lwj612_15993
.Lwt612_15993:
	global_store_dwordx4 v[126:127], v[122:125], off offset:256 sc1
.Lwj612_15993:
	s_and_saveexec_b64 s[0:1], vcc
	s_cbranch_execz .LBB0_617
	s_waitcnt lgkmcnt(0)
	v_add_f32_e32 v114, v117, v121
	v_lshl_add_u64 v[112:113], v[142:143], 2, s[14:15]
	global_atomic_add_f32 v[112:113], v114, off
.LBB0_617:
	s_or_b64 exec, exec, s[0:1]
	v_cvt_pk_bf16_f32 v122, v108, v109
	v_mul_f32_e32 v109, v109, v109
	v_fmac_f32_e32 v109, v108, v108
	v_mul_f32_e32 v108, v111, v111
	v_cvt_pk_bf16_f32 v124, v104, v105
	v_fmac_f32_e32 v108, v110, v110
	v_mul_f32_e32 v105, v105, v105
	v_add_f32_e32 v108, v109, v108
	v_fmac_f32_e32 v105, v104, v104
	v_add_f32_e32 v104, v108, v105
	v_mul_f32_e32 v105, v107, v107
	v_fmac_f32_e32 v105, v106, v106
	v_cvt_pk_bf16_f32 v125, v106, v107
	v_add_f32_e32 v104, v105, v104
	v_mul_f32_e32 v105, v101, v101
	v_mul_f32_e32 v106, v103, v103
	v_fmac_f32_e32 v105, v100, v100
	v_fmac_f32_e32 v106, v102, v102
	v_add_f32_e32 v105, v105, v106
	v_mul_f32_e32 v106, v97, v97
	v_fmac_f32_e32 v106, v96, v96
	v_add_f32_e32 v105, v105, v106
	v_mul_f32_e32 v106, v99, v99
	v_fmac_f32_e32 v106, v98, v98
	v_add_f32_e32 v105, v106, v105
	v_add_f32_e32 v106, v104, v105
	ds_bpermute_b32 v107, v120, v106
	v_add_u32_e32 v112, 16, v142
	v_ashrrev_i32_e32 v113, 31, v112
	v_lshlrev_b64 v[114:115], 11, v[112:113]
	v_lshl_add_u64 v[104:105], s[40:41], 0, v[114:115]
	v_lshl_add_u64 v[108:109], v[140:141], 1, v[104:105]
	v_cvt_pk_bf16_f32 v104, v100, v101
	s_waitcnt lgkmcnt(0)
	v_add_f32_e32 v100, v106, v107
	ds_bpermute_b32 v101, v116, v100
	v_cvt_pk_bf16_f32 v123, v110, v111
	s_cmp_lg_u32 s99, 0
	s_cbranch_scc1 .Lwt612_16050
	global_store_dwordx4 v[108:109], v[122:125], off
	s_branch .Lwj612_16050
.Lwt612_16050:
	global_store_dwordx4 v[108:109], v[122:125], off sc1
.Lwj612_16050:
	v_cvt_pk_bf16_f32 v105, v102, v103
	v_cvt_pk_bf16_f32 v106, v96, v97
	v_cvt_pk_bf16_f32 v107, v98, v99
	s_cmp_lg_u32 s99, 0
	s_cbranch_scc1 .Lwt612_16060
	global_store_dwordx4 v[108:109], v[104:107], off offset:256
	s_branch .Lwj612_16060
.Lwt612_16060:
	global_store_dwordx4 v[108:109], v[104:107], off offset:256 sc1
.Lwj612_16060:
	s_and_saveexec_b64 s[0:1], vcc
	s_cbranch_execz .LBB0_619
	s_waitcnt lgkmcnt(0)
	v_add_f32_e32 v98, v100, v101
	v_lshl_add_u64 v[96:97], v[112:113], 2, s[14:15]
	global_atomic_add_f32 v[96:97], v98, off
.LBB0_619:
	s_or_b64 exec, exec, s[0:1]
	v_cvt_pk_bf16_f32 v98, v92, v93
	v_mul_f32_e32 v93, v93, v93
	v_fmac_f32_e32 v93, v92, v92
	v_mul_f32_e32 v92, v95, v95
	v_cvt_pk_bf16_f32 v100, v88, v89
	v_fmac_f32_e32 v92, v94, v94
	v_mul_f32_e32 v89, v89, v89
	v_add_f32_e32 v92, v93, v92
	v_fmac_f32_e32 v89, v88, v88
	v_add_f32_e32 v88, v92, v89
	v_mul_f32_e32 v89, v91, v91
	v_fmac_f32_e32 v89, v90, v90
	s_waitcnt lgkmcnt(0)
	v_cvt_pk_bf16_f32 v101, v90, v91
	v_add_f32_e32 v88, v89, v88
	v_mul_f32_e32 v89, v85, v85
	v_mul_f32_e32 v90, v87, v87
	v_fmac_f32_e32 v89, v84, v84
	v_fmac_f32_e32 v90, v86, v86
	v_add_f32_e32 v89, v89, v90
	v_mul_f32_e32 v90, v81, v81
	v_fmac_f32_e32 v90, v80, v80
	v_add_f32_e32 v89, v89, v90
	v_mul_f32_e32 v90, v83, v83
	v_fmac_f32_e32 v90, v82, v82
	v_add_f32_e32 v89, v90, v89
	v_add_f32_e32 v90, v88, v89
	ds_bpermute_b32 v91, v120, v90
	v_add_u32_e32 v96, 32, v142
	v_ashrrev_i32_e32 v97, 31, v96
	v_lshlrev_b64 v[102:103], 11, v[96:97]
	v_lshl_add_u64 v[88:89], s[40:41], 0, v[102:103]
	v_lshl_add_u64 v[92:93], v[140:141], 1, v[88:89]
	v_cvt_pk_bf16_f32 v88, v84, v85
	s_waitcnt lgkmcnt(0)
	v_add_f32_e32 v84, v90, v91
	ds_bpermute_b32 v85, v116, v84
	v_cvt_pk_bf16_f32 v99, v94, v95
	s_cmp_lg_u32 s99, 0
	s_cbranch_scc1 .Lwt612_16118
	global_store_dwordx4 v[92:93], v[98:101], off
	s_branch .Lwj612_16118
.Lwt612_16118:
	global_store_dwordx4 v[92:93], v[98:101], off sc1
.Lwj612_16118:
	v_cvt_pk_bf16_f32 v89, v86, v87
	v_cvt_pk_bf16_f32 v90, v80, v81
	v_cvt_pk_bf16_f32 v91, v82, v83
	s_cmp_lg_u32 s99, 0
	s_cbranch_scc1 .Lwt612_16128
	global_store_dwordx4 v[92:93], v[88:91], off offset:256
	s_branch .Lwj612_16128
.Lwt612_16128:
	global_store_dwordx4 v[92:93], v[88:91], off offset:256 sc1
.Lwj612_16128:
	s_and_saveexec_b64 s[0:1], vcc
	s_cbranch_execz .LBB0_621
	s_waitcnt lgkmcnt(0)
	v_add_f32_e32 v82, v84, v85
	v_lshl_add_u64 v[80:81], v[96:97], 2, s[14:15]
	global_atomic_add_f32 v[80:81], v82, off
.LBB0_621:
	s_or_b64 exec, exec, s[0:1]
	v_cvt_pk_bf16_f32 v82, v76, v77
	v_mul_f32_e32 v77, v77, v77
	v_fmac_f32_e32 v77, v76, v76
	v_mul_f32_e32 v76, v79, v79
	v_cvt_pk_bf16_f32 v84, v72, v73
	v_fmac_f32_e32 v76, v78, v78
	v_mul_f32_e32 v73, v73, v73
	v_add_f32_e32 v76, v77, v76
	v_fmac_f32_e32 v73, v72, v72
	v_add_f32_e32 v72, v76, v73
	v_mul_f32_e32 v73, v75, v75
	v_fmac_f32_e32 v73, v74, v74
	s_waitcnt lgkmcnt(0)
	v_cvt_pk_bf16_f32 v85, v74, v75
	v_add_f32_e32 v72, v73, v72
	v_mul_f32_e32 v73, v69, v69
	v_mul_f32_e32 v74, v71, v71
	v_fmac_f32_e32 v73, v68, v68
	v_fmac_f32_e32 v74, v70, v70
	v_add_f32_e32 v73, v73, v74
	v_mul_f32_e32 v74, v65, v65
	v_fmac_f32_e32 v74, v64, v64
	v_add_f32_e32 v73, v73, v74
	v_mul_f32_e32 v74, v67, v67
	v_fmac_f32_e32 v74, v66, v66
	v_add_f32_e32 v73, v74, v73
	v_add_f32_e32 v74, v72, v73
	ds_bpermute_b32 v75, v120, v74
	v_add_u32_e32 v80, 48, v142
	v_ashrrev_i32_e32 v81, 31, v80
	v_lshlrev_b64 v[86:87], 11, v[80:81]
	v_lshl_add_u64 v[72:73], s[40:41], 0, v[86:87]
	v_lshl_add_u64 v[76:77], v[140:141], 1, v[72:73]
	v_cvt_pk_bf16_f32 v72, v68, v69
	s_waitcnt lgkmcnt(0)
	v_add_f32_e32 v68, v74, v75
	ds_bpermute_b32 v69, v116, v68
	v_cvt_pk_bf16_f32 v83, v78, v79
	s_cmp_lg_u32 s99, 0
	s_cbranch_scc1 .Lwt612_16186
	global_store_dwordx4 v[76:77], v[82:85], off
	s_branch .Lwj612_16186
; #define EPI_IT_ROW(it) EPI_ROW((it) >> 2, (it) & 3)
; #define EPI_PACK8(v0, v1) (u32x4){pk2((v0)[0], (v0)[1]), pk2((v0)[2], (v0)[3]), pk2((v1)[0], (v1)[1]), pk2((v1)[2], (v1)[3])}
;     __device__ __forceinline__ void operator()(AccRef acc, const Unit& u, int wr, int wc, int fr, int fq) const {
;         asm volatile("" : "+v"(fr), "+v"(fq));
; #pragma unroll
;         for (int it = 0; it < 8; ++it) { const int ai = it >> 2, m = it & 3, row = EPI_IT_ROW(it); float q = 0.f;
; #pragma unroll
;             for (int bj = 0; bj < 2; ++bj) { const f32x4 x0 = acc[ai][bj][m][0], x1 = acc[ai][bj][m][1];
;                 *(u32x4*)(O + (size_t)row * DM + EPI_COL(bj)) = EPI_PACK8(x0, x1);
;                 q += EPI_SQ8(x0, x1); }
;             q += __shfl_xor(q, 16); q += __shfl_xor(q, 32);
;             if (fq == 0) atomicAdd(ssout + row, q); }
.Lwt612_16186:
	global_store_dwordx4 v[76:77], v[82:85], off sc1
.Lwj612_16186:
	v_cvt_pk_bf16_f32 v73, v70, v71
	v_cvt_pk_bf16_f32 v74, v64, v65
	v_cvt_pk_bf16_f32 v75, v66, v67
	s_cmp_lg_u32 s99, 0
	s_cbranch_scc1 .Lwt612_16196
	global_store_dwordx4 v[76:77], v[72:75], off offset:256
	s_branch .Lwj612_16196
.Lwt612_16196:
	global_store_dwordx4 v[76:77], v[72:75], off offset:256 sc1
.Lwj612_16196:
	s_and_saveexec_b64 s[0:1], vcc
	s_cbranch_execz .LBB0_623
	s_waitcnt lgkmcnt(0)
	v_add_f32_e32 v66, v68, v69
	v_lshl_add_u64 v[64:65], v[80:81], 2, s[14:15]
	global_atomic_add_f32 v[64:65], v66, off
.LBB0_623:
	s_or_b64 exec, exec, s[0:1]
	v_cvt_pk_bf16_f32 v66, v60, v61
	v_mul_f32_e32 v61, v61, v61
	v_fmac_f32_e32 v61, v60, v60
	v_mul_f32_e32 v60, v63, v63
	v_cvt_pk_bf16_f32 v68, v56, v57
	v_fmac_f32_e32 v60, v62, v62
	v_mul_f32_e32 v57, v57, v57
	v_add_f32_e32 v60, v61, v60
	v_fmac_f32_e32 v57, v56, v56
	v_add_f32_e32 v56, v60, v57
	v_mul_f32_e32 v57, v59, v59
	v_fmac_f32_e32 v57, v58, v58
	s_waitcnt lgkmcnt(0)
	v_cvt_pk_bf16_f32 v69, v58, v59
	v_add_f32_e32 v56, v57, v56
	v_mul_f32_e32 v57, v53, v53
	v_mul_f32_e32 v58, v55, v55
	v_fmac_f32_e32 v57, v52, v52
	v_fmac_f32_e32 v58, v54, v54
	v_add_f32_e32 v57, v57, v58
	v_mul_f32_e32 v58, v49, v49
	v_fmac_f32_e32 v58, v48, v48
	v_add_f32_e32 v57, v57, v58
	v_mul_f32_e32 v58, v51, v51
	v_fmac_f32_e32 v58, v50, v50
	v_add_f32_e32 v57, v58, v57
	v_add_f32_e32 v58, v56, v57
	ds_bpermute_b32 v59, v120, v58
	v_add_u32_e32 v64, 0x80, v142
	v_ashrrev_i32_e32 v65, 31, v64
	v_lshlrev_b64 v[70:71], 11, v[64:65]
	v_lshl_add_u64 v[56:57], s[40:41], 0, v[70:71]
	v_lshl_add_u64 v[60:61], v[140:141], 1, v[56:57]
	v_cvt_pk_bf16_f32 v56, v52, v53
	s_waitcnt lgkmcnt(0)
	v_add_f32_e32 v52, v58, v59
	ds_bpermute_b32 v53, v116, v52
	v_cvt_pk_bf16_f32 v67, v62, v63
	s_cmp_lg_u32 s99, 0
	s_cbranch_scc1 .Lwt612_16254
	global_store_dwordx4 v[60:61], v[66:69], off
	s_branch .Lwj612_16254
.Lwt612_16254:
	global_store_dwordx4 v[60:61], v[66:69], off sc1
.Lwj612_16254:
	v_cvt_pk_bf16_f32 v57, v54, v55
	v_cvt_pk_bf16_f32 v58, v48, v49
	v_cvt_pk_bf16_f32 v59, v50, v51
	s_cmp_lg_u32 s99, 0
	s_cbranch_scc1 .Lwt612_16264
	global_store_dwordx4 v[60:61], v[56:59], off offset:256
	s_branch .Lwj612_16264
.Lwt612_16264:
	global_store_dwordx4 v[60:61], v[56:59], off offset:256 sc1
.Lwj612_16264:
	s_and_saveexec_b64 s[0:1], vcc
	s_cbranch_execz .LBB0_625
	s_waitcnt lgkmcnt(0)
	v_add_f32_e32 v50, v52, v53
	v_lshl_add_u64 v[48:49], v[64:65], 2, s[14:15]
	global_atomic_add_f32 v[48:49], v50, off
.LBB0_625:
	s_or_b64 exec, exec, s[0:1]
	v_cvt_pk_bf16_f32 v50, v44, v45
	v_mul_f32_e32 v45, v45, v45
	v_fmac_f32_e32 v45, v44, v44
	v_mul_f32_e32 v44, v47, v47
	v_cvt_pk_bf16_f32 v52, v40, v41
	v_fmac_f32_e32 v44, v46, v46
	v_mul_f32_e32 v41, v41, v41
	v_add_f32_e32 v44, v45, v44
	v_fmac_f32_e32 v41, v40, v40
	v_add_f32_e32 v40, v44, v41
	v_mul_f32_e32 v41, v43, v43
	v_fmac_f32_e32 v41, v42, v42
	s_waitcnt lgkmcnt(0)
	v_cvt_pk_bf16_f32 v53, v42, v43
	v_add_f32_e32 v40, v41, v40
	v_mul_f32_e32 v41, v37, v37
	v_mul_f32_e32 v42, v39, v39
	v_fmac_f32_e32 v41, v36, v36
	v_fmac_f32_e32 v42, v38, v38
	v_add_f32_e32 v41, v41, v42
	v_mul_f32_e32 v42, v33, v33
	v_fmac_f32_e32 v42, v32, v32
	v_add_f32_e32 v41, v41, v42
	v_mul_f32_e32 v42, v35, v35
	v_fmac_f32_e32 v42, v34, v34
	v_add_f32_e32 v41, v42, v41
	v_add_f32_e32 v42, v40, v41
	ds_bpermute_b32 v43, v120, v42
	v_add_u32_e32 v48, 0x90, v142
	v_ashrrev_i32_e32 v49, 31, v48
	v_lshlrev_b64 v[54:55], 11, v[48:49]
	v_lshl_add_u64 v[40:41], s[40:41], 0, v[54:55]
	v_lshl_add_u64 v[44:45], v[140:141], 1, v[40:41]
	v_cvt_pk_bf16_f32 v40, v36, v37
	s_waitcnt lgkmcnt(0)
	v_add_f32_e32 v36, v42, v43
	ds_bpermute_b32 v37, v116, v36
	v_cvt_pk_bf16_f32 v51, v46, v47
	s_cmp_lg_u32 s99, 0
	s_cbranch_scc1 .Lwt612_16322
	global_store_dwordx4 v[44:45], v[50:53], off
	s_branch .Lwj612_16322
.Lwt612_16322:
	global_store_dwordx4 v[44:45], v[50:53], off sc1
.Lwj612_16322:
	v_cvt_pk_bf16_f32 v41, v38, v39
	v_cvt_pk_bf16_f32 v42, v32, v33
	v_cvt_pk_bf16_f32 v43, v34, v35
	s_cmp_lg_u32 s99, 0
	s_cbranch_scc1 .Lwt612_16332
	global_store_dwordx4 v[44:45], v[40:43], off offset:256
	s_branch .Lwj612_16332
; #define EPI_IT_ROW(it) EPI_ROW((it) >> 2, (it) & 3)
; #define EPI_PACK8(v0, v1) (u32x4){pk2((v0)[0], (v0)[1]), pk2((v0)[2], (v0)[3]), pk2((v1)[0], (v1)[1]), pk2((v1)[2], (v1)[3])}
;     __device__ __forceinline__ void operator()(AccRef acc, const Unit& u, int wr, int wc, int fr, int fq) const {
;         asm volatile("" : "+v"(fr), "+v"(fq));
; #pragma unroll
;         for (int it = 0; it < 8; ++it) { const int ai = it >> 2, m = it & 3, row = EPI_IT_ROW(it); float q = 0.f;
; #pragma unroll
;             for (int bj = 0; bj < 2; ++bj) { const f32x4 x0 = acc[ai][bj][m][0], x1 = acc[ai][bj][m][1];
;                 *(u32x4*)(O + (size_t)row * DM + EPI_COL(bj)) = EPI_PACK8(x0, x1);
;                 q += EPI_SQ8(x0, x1); }
;             q += __shfl_xor(q, 16); q += __shfl_xor(q, 32);
;             if (fq == 0) atomicAdd(ssout + row, q); }
.Lwt612_16332:
	global_store_dwordx4 v[44:45], v[40:43], off offset:256 sc1
.Lwj612_16332:
	s_and_saveexec_b64 s[0:1], vcc
	s_cbranch_execz .LBB0_627
	s_waitcnt lgkmcnt(0)
	v_add_f32_e32 v34, v36, v37
	v_lshl_add_u64 v[32:33], v[48:49], 2, s[14:15]
	global_atomic_add_f32 v[32:33], v34, off
.LBB0_627:
	s_or_b64 exec, exec, s[0:1]
	v_cvt_pk_bf16_f32 v34, v28, v29
	v_mul_f32_e32 v29, v29, v29
	v_fmac_f32_e32 v29, v28, v28
	v_mul_f32_e32 v28, v31, v31
	v_cvt_pk_bf16_f32 v36, v24, v25
	v_fmac_f32_e32 v28, v30, v30
	v_mul_f32_e32 v25, v25, v25
	v_add_f32_e32 v28, v29, v28
	v_fmac_f32_e32 v25, v24, v24
	v_add_f32_e32 v24, v28, v25
	v_mul_f32_e32 v25, v27, v27
	v_fmac_f32_e32 v25, v26, v26
	s_waitcnt lgkmcnt(0)
	v_cvt_pk_bf16_f32 v37, v26, v27
	v_add_f32_e32 v24, v25, v24
	v_mul_f32_e32 v25, v21, v21
	v_mul_f32_e32 v26, v23, v23
	v_fmac_f32_e32 v25, v20, v20
	v_fmac_f32_e32 v26, v22, v22
	v_add_f32_e32 v25, v25, v26
	v_mul_f32_e32 v26, v17, v17
	v_fmac_f32_e32 v26, v16, v16
	v_add_f32_e32 v25, v25, v26
	v_mul_f32_e32 v26, v19, v19
	v_fmac_f32_e32 v26, v18, v18
	v_add_f32_e32 v25, v26, v25
	v_add_f32_e32 v26, v24, v25
	ds_bpermute_b32 v27, v120, v26
	v_add_u32_e32 v32, 0xa0, v142
	v_ashrrev_i32_e32 v33, 31, v32
	v_lshlrev_b64 v[38:39], 11, v[32:33]
	v_lshl_add_u64 v[24:25], s[40:41], 0, v[38:39]
	v_lshl_add_u64 v[28:29], v[140:141], 1, v[24:25]
	v_cvt_pk_bf16_f32 v24, v20, v21
	s_waitcnt lgkmcnt(0)
	v_add_f32_e32 v20, v26, v27
	ds_bpermute_b32 v21, v116, v20
	v_cvt_pk_bf16_f32 v35, v30, v31
	s_cmp_lg_u32 s99, 0
	s_cbranch_scc1 .Lwt612_16390
	global_store_dwordx4 v[28:29], v[34:37], off
	s_branch .Lwj612_16390
.Lwt612_16390:
	global_store_dwordx4 v[28:29], v[34:37], off sc1
.Lwj612_16390:
	v_cvt_pk_bf16_f32 v25, v22, v23
	v_cvt_pk_bf16_f32 v26, v16, v17
	v_cvt_pk_bf16_f32 v27, v18, v19
	s_cmp_lg_u32 s99, 0
	s_cbranch_scc1 .Lwt612_16400
	global_store_dwordx4 v[28:29], v[24:27], off offset:256
	s_branch .Lwj612_16400
.Lwt612_16400:
	global_store_dwordx4 v[28:29], v[24:27], off offset:256 sc1
.Lwj612_16400:
	s_and_saveexec_b64 s[0:1], vcc
	s_cbranch_execz .LBB0_629
	s_waitcnt lgkmcnt(0)
	v_add_f32_e32 v18, v20, v21
	v_lshl_add_u64 v[16:17], v[32:33], 2, s[14:15]
	global_atomic_add_f32 v[16:17], v18, off
.LBB0_629:
	s_or_b64 exec, exec, s[0:1]
	v_cvt_pk_bf16_f32 v18, v12, v13
	v_mul_f32_e32 v13, v13, v13
	v_fmac_f32_e32 v13, v12, v12
	v_mul_f32_e32 v12, v15, v15
	v_cvt_pk_bf16_f32 v20, v8, v9
	v_fmac_f32_e32 v12, v14, v14
	v_mul_f32_e32 v9, v9, v9
	v_add_f32_e32 v12, v13, v12
	v_fmac_f32_e32 v9, v8, v8
	v_add_f32_e32 v8, v12, v9
	v_mul_f32_e32 v9, v11, v11
	v_fmac_f32_e32 v9, v10, v10
	s_waitcnt lgkmcnt(0)
	v_cvt_pk_bf16_f32 v21, v10, v11
	v_add_f32_e32 v8, v9, v8
	v_mul_f32_e32 v9, v5, v5
	v_mul_f32_e32 v10, v7, v7
	v_fmac_f32_e32 v9, v4, v4
	v_fmac_f32_e32 v10, v6, v6
	v_add_f32_e32 v9, v9, v10
	v_mul_f32_e32 v10, v1, v1
	v_fmac_f32_e32 v10, v0, v0
	v_add_f32_e32 v9, v9, v10
	v_mul_f32_e32 v10, v3, v3
	v_fmac_f32_e32 v10, v2, v2
	v_add_f32_e32 v9, v10, v9
	v_add_f32_e32 v10, v8, v9
	ds_bpermute_b32 v11, v120, v10
	v_add_u32_e32 v16, 0xb0, v142
	v_ashrrev_i32_e32 v17, 31, v16
	v_lshlrev_b64 v[22:23], 11, v[16:17]
	v_lshl_add_u64 v[8:9], s[40:41], 0, v[22:23]
	v_lshl_add_u64 v[12:13], v[140:141], 1, v[8:9]
	v_cvt_pk_bf16_f32 v8, v4, v5
	s_waitcnt lgkmcnt(0)
	v_add_f32_e32 v4, v10, v11
	ds_bpermute_b32 v5, v116, v4
	v_cvt_pk_bf16_f32 v19, v14, v15
	s_cmp_lg_u32 s99, 0
	s_cbranch_scc1 .Lwt612_16458
	global_store_dwordx4 v[12:13], v[18:21], off
	s_branch .Lwj612_16458
.Lwt612_16458:
	global_store_dwordx4 v[12:13], v[18:21], off sc1
.Lwj612_16458:
	v_cvt_pk_bf16_f32 v9, v6, v7
	v_cvt_pk_bf16_f32 v10, v0, v1
	v_cvt_pk_bf16_f32 v11, v2, v3
	s_cmp_lg_u32 s99, 0
	s_cbranch_scc1 .Lwt612_16468
	global_store_dwordx4 v[12:13], v[8:11], off offset:256
	s_branch .Lwj612_16468
.Lwt612_16468:
	global_store_dwordx4 v[12:13], v[8:11], off offset:256 sc1
.Lwj612_16468:
	s_and_saveexec_b64 s[0:1], vcc
	s_cbranch_execz .LBB0_631
	s_waitcnt lgkmcnt(0)
	v_add_f32_e32 v2, v4, v5
	v_lshl_add_u64 v[0:1], v[16:17], 2, s[14:15]
	global_atomic_add_f32 v[0:1], v2, off

; #define PG8_STAGE(bufoff, gbase, voff) do { _Pragma("unroll") for (int _i = 0; _i < 2; ++_i) \
;         __builtin_amdgcn_global_load_lds((const unsigned*)((const char*)(gbase) + (voff)[_i]), (LAS unsigned*)(lds + (bufoff) + ldsw + _i * 8192), 16, 0, 0); } while (0)
; #define PG8_LDA(dst, b, h) do { _Pragma("unroll") for (int m = 0; m < 4; ++m) _Pragma("unroll") for (int k = 0; k < 2; ++k) dst[m][k] = *(const LAS bf16x8*)(lds + PG8_SA(b, h) + aoff + m * 2048 + k * 1024); } while (0)
; #define PG8_LDB(dst, b, h) do { _Pragma("unroll") for (int n = 0; n < 2; ++n) _Pragma("unroll") for (int k = 0; k < 2; ++k) dst[n][k] = *(const LAS bf16x8*)(lds + PG8_SB(b, h) + boff + n * 2048 + k * 1024); } while (0)
; #define PG8_MMA(ai, bj, At, Bt) do { __builtin_amdgcn_s_setprio(1); _Pragma("unroll") for (int m = 0; m < 4; ++m) _Pragma("unroll") for (int n = 0; n < 2; ++n) _Pragma("unroll") for (int k = 0; k < 2; ++k) \
;         acc[ai][bj][m][n] = __builtin_amdgcn_mfma_f32_16x16x32_bf16(Bt[n][k], At[m][k], acc[ai][bj][m][n], 0, 0, 0); __builtin_amdgcn_s_setprio(0); } while (0)
; #define PG8_WAIT_V(n) asm volatile("s_waitcnt vmcnt(" #n ")" ::: "memory")
; #define PG8_WAIT_L(n) asm volatile("s_waitcnt lgkmcnt(" #n ")" ::: "memory")
; #define PG8_BAR __builtin_amdgcn_s_barrier()
; #define PG8_SCHED __builtin_amdgcn_sched_barrier(0)
; template <class Epi>
; __device__ __forceinline__ void gemm_phase(LAS unsigned char* lds, const Gemm g, const StaticOrder& S, const Epi& E) {
;     ...
;             PG8_LDB(B0, 0, 0); PG8_LDB(B1, 0, 1); PG8_SCHED; PG8_LDA(At, 0, 0); PG8_STAGE(PG8_SA(1, 1), a1 + hstepA, voffA);
;             PG8_WAIT_V(8); PG8_WAIT_L(0); PG8_BAR; PG8_MMA(0, 0, At, B0); PG8_MMA(0, 1, At, B1); PG8_BAR; PG8_SCHED;
;             PG8_LDA(At, 0, 1); PG8_STAGE(PG8_SB(0, 0), b2, voffB); PG8_STAGE(PG8_SB(0, 1), b2 + hstepB, voffB); PG8_STAGE(PG8_SA(0, 0), a2, voffA);
;             PG8_WAIT_V(8); PG8_WAIT_L(0); PG8_BAR; PG8_MMA(1, 0, At, B0); PG8_MMA(1, 1, At, B1); PG8_BAR; PG8_SCHED;
;             PG8_LDB(B0, 1, 0); PG8_LDB(B1, 1, 1); PG8_SCHED; PG8_LDA(At, 1, 0); PG8_STAGE(PG8_SA(0, 1), a2 + hstepA, voffA);
.LBB0_792:
	ds_read_b128 v[128:131], v182
	ds_read_b128 v[132:135], v182 offset:1024
	ds_read_b128 v[136:139], v182 offset:2048
	ds_read_b128 v[140:143], v182 offset:3072
	ds_read_b128 v[160:163], v183
	ds_read_b128 v[164:167], v183 offset:1024
	ds_read_b128 v[168:171], v183 offset:2048
	ds_read_b128 v[172:175], v183 offset:3072
	s_add_u32 s34, s0, 0xfff50080
	s_addc_u32 s35, s1, -1
	s_cmp_eq_u32 s77, 40
	s_cselect_b32 s39, s7, s35
	s_cselect_b32 s38, s6, s34
	s_cselect_b32 s35, s23, s76
	s_cselect_b32 s34, s22, s75
	v_lshl_add_u64 v[178:179], s[0:1], 0, v[152:153]
	s_add_i32 m0, s43, 0xc000
	ds_read_b128 v[186:189], v184
	ds_read_b128 v[190:193], v184 offset:1024
	ds_read_b128 v[194:197], v184 offset:2048
	ds_read_b128 v[198:201], v184 offset:3072
	ds_read_b128 v[202:205], v184 offset:4096
	ds_read_b128 v[206:209], v184 offset:5120
	ds_read_b128 v[210:213], v184 offset:6144
	ds_read_b128 v[214:217], v184 offset:7168
	global_load_lds_dwordx4 v[178:179], off
	v_lshl_add_u64 v[178:179], s[0:1], 0, v[154:155]
	s_add_i32 m0, s43, 0xe000
	s_nop 0
	global_load_lds_dwordx4 v[178:179], off
	s_waitcnt vmcnt(8)
	s_waitcnt lgkmcnt(0)
	s_barrier
	s_setprio 1
	s_waitcnt lgkmcnt(0)
	v_mfma_f32_16x16x32_bf16 v[124:127], v[128:131], v[186:189], v[124:127]
	v_mfma_f32_16x16x32_bf16 v[120:123], v[136:139], v[186:189], v[120:123]
	v_mfma_f32_16x16x32_bf16 v[108:111], v[128:131], v[194:197], v[108:111]
	v_mfma_f32_16x16x32_bf16 v[104:107], v[136:139], v[194:197], v[104:107]
	v_mfma_f32_16x16x32_bf16 v[92:95], v[128:131], v[202:205], v[92:95]
	v_mfma_f32_16x16x32_bf16 v[88:91], v[136:139], v[202:205], v[88:91]
	v_mfma_f32_16x16x32_bf16 v[76:79], v[128:131], v[210:213], v[76:79]
	v_mfma_f32_16x16x32_bf16 v[72:75], v[136:139], v[210:213], v[72:75]
	v_mfma_f32_16x16x32_bf16 v[124:127], v[132:135], v[190:193], v[124:127]
	v_mfma_f32_16x16x32_bf16 v[120:123], v[140:143], v[190:193], v[120:123]
	v_mfma_f32_16x16x32_bf16 v[108:111], v[132:135], v[198:201], v[108:111]
	v_mfma_f32_16x16x32_bf16 v[104:107], v[140:143], v[198:201], v[104:107]
	v_mfma_f32_16x16x32_bf16 v[92:95], v[132:135], v[206:209], v[92:95]
	v_mfma_f32_16x16x32_bf16 v[88:91], v[140:143], v[206:209], v[88:91]
	v_mfma_f32_16x16x32_bf16 v[76:79], v[132:135], v[214:217], v[76:79]
	v_mfma_f32_16x16x32_bf16 v[72:75], v[140:143], v[214:217], v[72:75]
	s_setprio 0
	s_setprio 1
	v_mfma_f32_16x16x32_bf16 v[116:119], v[160:163], v[186:189], v[116:119]
	v_mfma_f32_16x16x32_bf16 v[112:115], v[168:171], v[186:189], v[112:115]
	v_mfma_f32_16x16x32_bf16 v[100:103], v[160:163], v[194:197], v[100:103]
	v_mfma_f32_16x16x32_bf16 v[96:99], v[168:171], v[194:197], v[96:99]
	v_mfma_f32_16x16x32_bf16 v[84:87], v[160:163], v[202:205], v[84:87]
	v_mfma_f32_16x16x32_bf16 v[80:83], v[168:171], v[202:205], v[80:83]
	v_mfma_f32_16x16x32_bf16 v[68:71], v[160:163], v[210:213], v[68:71]
	v_mfma_f32_16x16x32_bf16 v[64:67], v[168:171], v[210:213], v[64:67]
	v_mfma_f32_16x16x32_bf16 v[116:119], v[164:167], v[190:193], v[116:119]
	v_mfma_f32_16x16x32_bf16 v[112:115], v[172:175], v[190:193], v[112:115]
	v_mfma_f32_16x16x32_bf16 v[100:103], v[164:167], v[198:201], v[100:103]
	v_mfma_f32_16x16x32_bf16 v[96:99], v[172:175], v[198:201], v[96:99]
	v_mfma_f32_16x16x32_bf16 v[84:87], v[164:167], v[206:209], v[84:87]
	v_mfma_f32_16x16x32_bf16 v[80:83], v[172:175], v[206:209], v[80:83]
	v_mfma_f32_16x16x32_bf16 v[68:71], v[164:167], v[214:217], v[68:71]
	v_mfma_f32_16x16x32_bf16 v[64:67], v[172:175], v[214:217], v[64:67]
	s_setprio 0
	s_barrier
	s_add_i32 s78, s69, s42
	v_lshl_add_u64 v[178:179], s[34:35], 0, v[146:147]
	s_mov_b32 m0, s78
	ds_read_b128 v[186:189], v184 offset:16384
	ds_read_b128 v[190:193], v184 offset:17408
	ds_read_b128 v[194:197], v184 offset:18432
	ds_read_b128 v[198:201], v184 offset:19456
	ds_read_b128 v[202:205], v184 offset:20480
	ds_read_b128 v[206:209], v184 offset:21504
	ds_read_b128 v[210:213], v184 offset:22528
	ds_read_b128 v[214:217], v184 offset:23552
	global_load_lds_dwordx4 v[178:179], off
	s_add_i32 m0, s78, 0x2000
	s_add_u32 s78, s34, 0xb0000
	v_lshl_add_u64 v[218:219], s[34:35], 0, v[150:151]
	s_addc_u32 s79, s35, 0
	s_add_i32 s80, s70, s42
	global_load_lds_dwordx4 v[218:219], off
	v_lshl_add_u64 v[220:221], s[78:79], 0, v[146:147]
	s_mov_b32 m0, s80
	v_lshl_add_u64 v[222:223], s[38:39], 0, v[148:149]
	global_load_lds_dwordx4 v[220:221], off
	v_lshl_add_u64 v[220:221], s[78:79], 0, v[150:151]
	s_add_i32 m0, s80, 0x2000
	s_nop 0
	global_load_lds_dwordx4 v[220:221], off
	v_lshl_add_u64 v[220:221], s[38:39], 0, v[144:145]
	s_mov_b32 m0, s43
	s_nop 0
	global_load_lds_dwordx4 v[220:221], off
	s_mov_b32 m0, s52
	s_nop 0
	global_load_lds_dwordx4 v[222:223], off
	s_waitcnt vmcnt(8)
	s_waitcnt lgkmcnt(0)
	s_barrier
; #define PG8_STAGE(bufoff, gbase, voff) do { _Pragma("unroll") for (int _i = 0; _i < 2; ++_i) \
;         __builtin_amdgcn_global_load_lds((const unsigned*)((const char*)(gbase) + (voff)[_i]), (LAS unsigned*)(lds + (bufoff) + ldsw + _i * 8192), 16, 0, 0); } while (0)
; #define PG8_LDA(dst, b, h) do { _Pragma("unroll") for (int m = 0; m < 4; ++m) _Pragma("unroll") for (int k = 0; k < 2; ++k) dst[m][k] = *(const LAS bf16x8*)(lds + PG8_SA(b, h) + aoff + m * 2048 + k * 1024); } while (0)
; #define PG8_LDB(dst, b, h) do { _Pragma("unroll") for (int n = 0; n < 2; ++n) _Pragma("unroll") for (int k = 0; k < 2; ++k) dst[n][k] = *(const LAS bf16x8*)(lds + PG8_SB(b, h) + boff + n * 2048 + k * 1024); } while (0)
; #define PG8_MMA(ai, bj, At, Bt) do { __builtin_amdgcn_s_setprio(1); _Pragma("unroll") for (int m = 0; m < 4; ++m) _Pragma("unroll") for (int n = 0; n < 2; ++n) _Pragma("unroll") for (int k = 0; k < 2; ++k) \
;         acc[ai][bj][m][n] = __builtin_amdgcn_mfma_f32_16x16x32_bf16(Bt[n][k], At[m][k], acc[ai][bj][m][n], 0, 0, 0); __builtin_amdgcn_s_setprio(0); } while (0)
; #define PG8_WAIT_V(n) asm volatile("s_waitcnt vmcnt(" #n ")" ::: "memory")
; #define PG8_BAR __builtin_amdgcn_s_barrier()
; template <class Epi>
; __device__ __forceinline__ void gemm_phase(LAS unsigned char* lds, const Gemm g, const StaticOrder& S, const Epi& E) {
;     ...
;             PG8_LDB(B0, 0, 0); PG8_LDB(B1, 0, 1); PG8_SCHED; PG8_LDA(At, 0, 0); PG8_STAGE(PG8_SA(1, 1), a1 + hstepA, voffA);
;             PG8_WAIT_V(8); PG8_WAIT_L(0); PG8_BAR; PG8_MMA(0, 0, At, B0); PG8_MMA(0, 1, At, B1); PG8_BAR; PG8_SCHED;
;             PG8_LDA(At, 0, 1); PG8_STAGE(PG8_SB(0, 0), b2, voffB); PG8_STAGE(PG8_SB(0, 1), b2 + hstepB, voffB); PG8_STAGE(PG8_SA(0, 0), a2, voffA);
;             PG8_WAIT_V(8); PG8_WAIT_L(0); PG8_BAR; PG8_MMA(1, 0, At, B0); PG8_MMA(1, 1, At, B1); PG8_BAR; PG8_SCHED;
;             PG8_LDB(B0, 1, 0); PG8_LDB(B1, 1, 1); PG8_SCHED; PG8_LDA(At, 1, 0); PG8_STAGE(PG8_SA(0, 1), a2 + hstepA, voffA);
;             PG8_WAIT_V(8); PG8_WAIT_L(0); PG8_BAR; PG8_MMA(0, 0, At, B0); PG8_MMA(0, 1, At, B1); PG8_BAR; PG8_SCHED;
;             PG8_LDA(At, 1, 1); PG8_STAGE(PG8_SB(1, 0), b3, voffB); PG8_STAGE(PG8_SB(1, 1), b3 + hstepB, voffB); PG8_STAGE(PG8_SA(1, 0), a3, voffA);
;             PG8_WAIT_V(8); PG8_WAIT_L(0); PG8_BAR; PG8_MMA(1, 0, At, B0); PG8_MMA(1, 1, At, B1); PG8_BAR; PG8_SCHED;
	s_setprio 1
	s_waitcnt lgkmcnt(0)
	v_mfma_f32_16x16x32_bf16 v[60:63], v[128:131], v[186:189], v[60:63]
	v_mfma_f32_16x16x32_bf16 v[56:59], v[136:139], v[186:189], v[56:59]
	v_mfma_f32_16x16x32_bf16 v[44:47], v[128:131], v[194:197], v[44:47]
	v_mfma_f32_16x16x32_bf16 v[40:43], v[136:139], v[194:197], v[40:43]
	v_mfma_f32_16x16x32_bf16 v[28:31], v[128:131], v[202:205], v[28:31]
	v_mfma_f32_16x16x32_bf16 v[24:27], v[136:139], v[202:205], v[24:27]
	v_mfma_f32_16x16x32_bf16 v[12:15], v[128:131], v[210:213], v[12:15]
	v_mfma_f32_16x16x32_bf16 v[8:11], v[136:139], v[210:213], v[8:11]
	v_mfma_f32_16x16x32_bf16 v[60:63], v[132:135], v[190:193], v[60:63]
	v_mfma_f32_16x16x32_bf16 v[56:59], v[140:143], v[190:193], v[56:59]
	v_mfma_f32_16x16x32_bf16 v[44:47], v[132:135], v[198:201], v[44:47]
	v_mfma_f32_16x16x32_bf16 v[40:43], v[140:143], v[198:201], v[40:43]
	v_mfma_f32_16x16x32_bf16 v[28:31], v[132:135], v[206:209], v[28:31]
	v_mfma_f32_16x16x32_bf16 v[24:27], v[140:143], v[206:209], v[24:27]
	v_mfma_f32_16x16x32_bf16 v[12:15], v[132:135], v[214:217], v[12:15]
	v_mfma_f32_16x16x32_bf16 v[8:11], v[140:143], v[214:217], v[8:11]
	s_setprio 0
	s_setprio 1
	v_mfma_f32_16x16x32_bf16 v[52:55], v[160:163], v[186:189], v[52:55]
	v_mfma_f32_16x16x32_bf16 v[48:51], v[168:171], v[186:189], v[48:51]
	v_mfma_f32_16x16x32_bf16 v[36:39], v[160:163], v[194:197], v[36:39]
	v_mfma_f32_16x16x32_bf16 v[32:35], v[168:171], v[194:197], v[32:35]
	v_mfma_f32_16x16x32_bf16 v[20:23], v[160:163], v[202:205], v[20:23]
	v_mfma_f32_16x16x32_bf16 v[16:19], v[168:171], v[202:205], v[16:19]
	v_mfma_f32_16x16x32_bf16 v[4:7], v[160:163], v[210:213], v[4:7]
	v_mfma_f32_16x16x32_bf16 v[0:3], v[168:171], v[210:213], v[0:3]
	v_mfma_f32_16x16x32_bf16 v[52:55], v[164:167], v[190:193], v[52:55]
	v_mfma_f32_16x16x32_bf16 v[48:51], v[172:175], v[190:193], v[48:51]
	v_mfma_f32_16x16x32_bf16 v[36:39], v[164:167], v[198:201], v[36:39]
	v_mfma_f32_16x16x32_bf16 v[32:35], v[172:175], v[198:201], v[32:35]
	v_mfma_f32_16x16x32_bf16 v[20:23], v[164:167], v[206:209], v[20:23]
	v_mfma_f32_16x16x32_bf16 v[16:19], v[172:175], v[206:209], v[16:19]
	v_mfma_f32_16x16x32_bf16 v[4:7], v[164:167], v[214:217], v[4:7]
	v_mfma_f32_16x16x32_bf16 v[0:3], v[172:175], v[214:217], v[0:3]
	s_setprio 0
	s_barrier
	s_add_i32 s78, 0, 0x18000
	s_add_i32 s79, 0, 0x1c000
	v_add_u32_e32 v140, s78, v181
	v_add_u32_e32 v172, s79, v181
	ds_read_b128 v[128:131], v140
	ds_read_b128 v[132:135], v140 offset:1024
	ds_read_b128 v[136:139], v140 offset:2048
	ds_read_b128 v[140:143], v140 offset:3072
	ds_read_b128 v[160:163], v172
	ds_read_b128 v[164:167], v172 offset:1024
	ds_read_b128 v[168:171], v172 offset:2048
	ds_read_b128 v[172:175], v172 offset:3072
	s_add_u32 s38, s38, 0xb0000
	s_addc_u32 s39, s39, 0
	s_mov_b32 m0, s53
	v_lshl_add_u64 v[226:227], s[38:39], 0, v[144:145]
	ds_read_b128 v[186:189], v184 offset:32768
	ds_read_b128 v[190:193], v184 offset:33792
	ds_read_b128 v[194:197], v184 offset:34816
	ds_read_b128 v[198:201], v184 offset:35840
	ds_read_b128 v[202:205], v184 offset:36864
	ds_read_b128 v[206:209], v184 offset:37888
	ds_read_b128 v[210:213], v184 offset:38912
	ds_read_b128 v[214:217], v184 offset:39936
	global_load_lds_dwordx4 v[226:227], off
	v_lshl_add_u64 v[226:227], s[38:39], 0, v[148:149]
	s_mov_b32 m0, s54
	s_nop 0
	global_load_lds_dwordx4 v[226:227], off
	s_waitcnt vmcnt(8)
	s_waitcnt lgkmcnt(0)
	s_barrier
	s_setprio 1
	s_waitcnt lgkmcnt(0)
	v_mfma_f32_16x16x32_bf16 v[124:127], v[128:131], v[186:189], v[124:127]
	v_mfma_f32_16x16x32_bf16 v[120:123], v[136:139], v[186:189], v[120:123]
	v_mfma_f32_16x16x32_bf16 v[108:111], v[128:131], v[194:197], v[108:111]
	v_mfma_f32_16x16x32_bf16 v[104:107], v[136:139], v[194:197], v[104:107]
	v_mfma_f32_16x16x32_bf16 v[92:95], v[128:131], v[202:205], v[92:95]
	v_mfma_f32_16x16x32_bf16 v[88:91], v[136:139], v[202:205], v[88:91]
	v_mfma_f32_16x16x32_bf16 v[76:79], v[128:131], v[210:213], v[76:79]
	v_mfma_f32_16x16x32_bf16 v[72:75], v[136:139], v[210:213], v[72:75]
	v_mfma_f32_16x16x32_bf16 v[124:127], v[132:135], v[190:193], v[124:127]
	v_mfma_f32_16x16x32_bf16 v[120:123], v[140:143], v[190:193], v[120:123]
	v_mfma_f32_16x16x32_bf16 v[108:111], v[132:135], v[198:201], v[108:111]
	v_mfma_f32_16x16x32_bf16 v[104:107], v[140:143], v[198:201], v[104:107]
	v_mfma_f32_16x16x32_bf16 v[92:95], v[132:135], v[206:209], v[92:95]
	v_mfma_f32_16x16x32_bf16 v[88:91], v[140:143], v[206:209], v[88:91]
	v_mfma_f32_16x16x32_bf16 v[76:79], v[132:135], v[214:217], v[76:79]
	v_mfma_f32_16x16x32_bf16 v[72:75], v[140:143], v[214:217], v[72:75]
	s_setprio 0
	s_setprio 1
	v_mfma_f32_16x16x32_bf16 v[116:119], v[160:163], v[186:189], v[116:119]
	v_mfma_f32_16x16x32_bf16 v[112:115], v[168:171], v[186:189], v[112:115]
	v_mfma_f32_16x16x32_bf16 v[100:103], v[160:163], v[194:197], v[100:103]
	v_mfma_f32_16x16x32_bf16 v[96:99], v[168:171], v[194:197], v[96:99]
	v_mfma_f32_16x16x32_bf16 v[84:87], v[160:163], v[202:205], v[84:87]
	v_mfma_f32_16x16x32_bf16 v[80:83], v[168:171], v[202:205], v[80:83]
	v_mfma_f32_16x16x32_bf16 v[68:71], v[160:163], v[210:213], v[68:71]
	v_mfma_f32_16x16x32_bf16 v[64:67], v[168:171], v[210:213], v[64:67]
	v_mfma_f32_16x16x32_bf16 v[116:119], v[164:167], v[190:193], v[116:119]
	v_mfma_f32_16x16x32_bf16 v[112:115], v[172:175], v[190:193], v[112:115]
	v_mfma_f32_16x16x32_bf16 v[100:103], v[164:167], v[198:201], v[100:103]
	v_mfma_f32_16x16x32_bf16 v[96:99], v[172:175], v[198:201], v[96:99]
	v_mfma_f32_16x16x32_bf16 v[84:87], v[164:167], v[206:209], v[84:87]
	v_mfma_f32_16x16x32_bf16 v[80:83], v[172:175], v[206:209], v[80:83]
	v_mfma_f32_16x16x32_bf16 v[68:71], v[164:167], v[214:217], v[68:71]
	v_mfma_f32_16x16x32_bf16 v[64:67], v[172:175], v[214:217], v[64:67]
	s_setprio 0
	s_barrier
; #define PG8_STAGE(bufoff, gbase, voff) do { _Pragma("unroll") for (int _i = 0; _i < 2; ++_i) \
;         __builtin_amdgcn_global_load_lds((const unsigned*)((const char*)(gbase) + (voff)[_i]), (LAS unsigned*)(lds + (bufoff) + ldsw + _i * 8192), 16, 0, 0); } while (0)
; #define PG8_LDA(dst, b, h) do { _Pragma("unroll") for (int m = 0; m < 4; ++m) _Pragma("unroll") for (int k = 0; k < 2; ++k) dst[m][k] = *(const LAS bf16x8*)(lds + PG8_SA(b, h) + aoff + m * 2048 + k * 1024); } while (0)
; #define PG8_LDB(dst, b, h) do { _Pragma("unroll") for (int n = 0; n < 2; ++n) _Pragma("unroll") for (int k = 0; k < 2; ++k) dst[n][k] = *(const LAS bf16x8*)(lds + PG8_SB(b, h) + boff + n * 2048 + k * 1024); } while (0)
; #define PG8_MMA(ai, bj, At, Bt) do { __builtin_amdgcn_s_setprio(1); _Pragma("unroll") for (int m = 0; m < 4; ++m) _Pragma("unroll") for (int n = 0; n < 2; ++n) _Pragma("unroll") for (int k = 0; k < 2; ++k) \
;         acc[ai][bj][m][n] = __builtin_amdgcn_mfma_f32_16x16x32_bf16(Bt[n][k], At[m][k], acc[ai][bj][m][n], 0, 0, 0); __builtin_amdgcn_s_setprio(0); } while (0)
; #define PG8_WAIT_V(n) asm volatile("s_waitcnt vmcnt(" #n ")" ::: "memory")
; #define PG8_WAIT_L(n) asm volatile("s_waitcnt lgkmcnt(" #n ")" ::: "memory")
; #define PG8_BAR __builtin_amdgcn_s_barrier()
; #define PG8_SCHED __builtin_amdgcn_sched_barrier(0)
; template <class Epi>
; __device__ __forceinline__ void gemm_phase(LAS unsigned char* lds, const Gemm g, const StaticOrder& S, const Epi& E) {
;     ...
;             PG8_LDB(B0, 1, 0); PG8_LDB(B1, 1, 1); PG8_SCHED; PG8_LDA(At, 1, 0); PG8_STAGE(PG8_SA(0, 1), a2 + hstepA, voffA);
;             PG8_WAIT_V(8); PG8_WAIT_L(0); PG8_BAR; PG8_MMA(0, 0, At, B0); PG8_MMA(0, 1, At, B1); PG8_BAR; PG8_SCHED;
;             PG8_LDA(At, 1, 1); PG8_STAGE(PG8_SB(1, 0), b3, voffB); PG8_STAGE(PG8_SB(1, 1), b3 + hstepB, voffB); PG8_STAGE(PG8_SA(1, 0), a3, voffA);
;             PG8_WAIT_V(8); PG8_WAIT_L(0); PG8_BAR; PG8_MMA(1, 0, At, B0); PG8_MMA(1, 1, At, B1); PG8_BAR; PG8_SCHED;
;         }
;         if (wr == 0) PG8_BAR;
	s_add_i32 s38, s78, s42
	v_lshl_add_u64 v[178:179], v[178:179], 0, s[16:17]
	s_mov_b32 m0, s38
	ds_read_b128 v[186:189], v184 offset:49152
	ds_read_b128 v[190:193], v184 offset:50176
	ds_read_b128 v[194:197], v184 offset:51200
	ds_read_b128 v[198:201], v184 offset:52224
	ds_read_b128 v[202:205], v184 offset:53248
	ds_read_b128 v[206:209], v184 offset:54272
	ds_read_b128 v[210:213], v184 offset:55296
	ds_read_b128 v[214:217], v184 offset:56320
	global_load_lds_dwordx4 v[178:179], off
	s_add_i32 m0, s38, 0x2000
	s_add_u32 s34, s34, 0xb0080
	v_lshl_add_u64 v[178:179], v[218:219], 0, s[16:17]
	s_addc_u32 s35, s35, 0
	s_add_i32 s38, s79, s42
	global_load_lds_dwordx4 v[178:179], off
	v_lshl_add_u64 v[178:179], s[34:35], 0, v[146:147]
	s_mov_b32 m0, s38
	s_nop 0
	global_load_lds_dwordx4 v[178:179], off
	v_lshl_add_u64 v[178:179], s[34:35], 0, v[150:151]
	s_add_i32 m0, s38, 0x2000
	s_nop 0
	global_load_lds_dwordx4 v[178:179], off
	v_lshl_add_u64 v[178:179], v[220:221], 0, s[16:17]
	s_mov_b32 m0, s62
	s_nop 0
	global_load_lds_dwordx4 v[178:179], off
	v_lshl_add_u64 v[178:179], v[222:223], 0, s[16:17]
	s_mov_b32 m0, s63
	s_nop 0
	global_load_lds_dwordx4 v[178:179], off
	s_waitcnt vmcnt(8)
	s_waitcnt lgkmcnt(0)
	s_barrier
	s_setprio 1
	s_waitcnt lgkmcnt(0)
	v_mfma_f32_16x16x32_bf16 v[60:63], v[128:131], v[186:189], v[60:63]
	v_mfma_f32_16x16x32_bf16 v[56:59], v[136:139], v[186:189], v[56:59]
	v_mfma_f32_16x16x32_bf16 v[44:47], v[128:131], v[194:197], v[44:47]
	v_mfma_f32_16x16x32_bf16 v[40:43], v[136:139], v[194:197], v[40:43]
	v_mfma_f32_16x16x32_bf16 v[28:31], v[128:131], v[202:205], v[28:31]
	v_mfma_f32_16x16x32_bf16 v[24:27], v[136:139], v[202:205], v[24:27]
	v_mfma_f32_16x16x32_bf16 v[12:15], v[128:131], v[210:213], v[12:15]
	v_mfma_f32_16x16x32_bf16 v[8:11], v[136:139], v[210:213], v[8:11]
	v_mfma_f32_16x16x32_bf16 v[60:63], v[132:135], v[190:193], v[60:63]
	v_mfma_f32_16x16x32_bf16 v[56:59], v[140:143], v[190:193], v[56:59]
	v_mfma_f32_16x16x32_bf16 v[44:47], v[132:135], v[198:201], v[44:47]
	v_mfma_f32_16x16x32_bf16 v[40:43], v[140:143], v[198:201], v[40:43]
	v_mfma_f32_16x16x32_bf16 v[28:31], v[132:135], v[206:209], v[28:31]
	v_mfma_f32_16x16x32_bf16 v[24:27], v[140:143], v[206:209], v[24:27]
	v_mfma_f32_16x16x32_bf16 v[12:15], v[132:135], v[214:217], v[12:15]
	v_mfma_f32_16x16x32_bf16 v[8:11], v[140:143], v[214:217], v[8:11]
	s_setprio 0
	s_setprio 1
	v_mfma_f32_16x16x32_bf16 v[52:55], v[160:163], v[186:189], v[52:55]
	v_mfma_f32_16x16x32_bf16 v[48:51], v[168:171], v[186:189], v[48:51]
	v_mfma_f32_16x16x32_bf16 v[36:39], v[160:163], v[194:197], v[36:39]
	v_mfma_f32_16x16x32_bf16 v[32:35], v[168:171], v[194:197], v[32:35]
	v_mfma_f32_16x16x32_bf16 v[20:23], v[160:163], v[202:205], v[20:23]
	v_mfma_f32_16x16x32_bf16 v[16:19], v[168:171], v[202:205], v[16:19]
	v_mfma_f32_16x16x32_bf16 v[4:7], v[160:163], v[210:213], v[4:7]
	v_mfma_f32_16x16x32_bf16 v[0:3], v[168:171], v[210:213], v[0:3]
	v_mfma_f32_16x16x32_bf16 v[52:55], v[164:167], v[190:193], v[52:55]
	v_mfma_f32_16x16x32_bf16 v[48:51], v[172:175], v[190:193], v[48:51]
	v_mfma_f32_16x16x32_bf16 v[36:39], v[164:167], v[198:201], v[36:39]
	v_mfma_f32_16x16x32_bf16 v[32:35], v[172:175], v[198:201], v[32:35]
	v_mfma_f32_16x16x32_bf16 v[20:23], v[164:167], v[206:209], v[20:23]
	v_mfma_f32_16x16x32_bf16 v[16:19], v[172:175], v[206:209], v[16:19]
	v_mfma_f32_16x16x32_bf16 v[4:7], v[164:167], v[214:217], v[4:7]
	v_mfma_f32_16x16x32_bf16 v[0:3], v[172:175], v[214:217], v[0:3]
	s_setprio 0
	s_barrier
	s_add_i32 s77, s77, 2
	s_add_u32 s0, s0, 0x100
	s_addc_u32 s1, s1, 0
	s_add_u32 s75, s75, 0x100
	s_addc_u32 s76, s76, 0
	s_cmp_gt_u32 s77, 41
	s_cbranch_scc0 .LBB0_792
	s_cmp_eq_u64 s[10:11], 0
	s_cselect_b32 s99, 1, 0
	s_and_b64 vcc, exec, s[18:19]
	s_cbranch_vccz .LBB0_795
	s_barrier
; #define EPI_IT_ROW(it) EPI_ROW((it) >> 2, (it) & 3)
; #define EPI_PACK8(v0, v1) (u32x4){pk2((v0)[0], (v0)[1]), pk2((v0)[2], (v0)[3]), pk2((v1)[0], (v1)[1]), pk2((v1)[2], (v1)[3])}
;     __device__ __forceinline__ void operator()(AccRef acc, const Unit& u, int wr, int wc, int fr, int fq) const {
;     ...
;         for (int bj = 0; bj < 2; ++bj) { const size_t p = (size_t)EPI_IT_ROW(0) * DM + EPI_COL(bj); xc[bj][0] = *(const f32x4*)(xin + p); xc[bj][1] = *(const f32x4*)(xin + p + 4); }
; #pragma unroll
;         for (int it = 0; it < 8; ++it) { const int ai = it >> 2, m = it & 3, row = EPI_IT_ROW(it);
;             if (it + 1 < 8) {
; #pragma unroll
;                 for (int bj = 0; bj < 2; ++bj) { const size_t p = (size_t)EPI_IT_ROW(it + 1) * DM + EPI_COL(bj); xn[bj][0] = *(const f32x4*)(xin + p); xn[bj][1] = *(const f32x4*)(xin + p + 4); } }
;             float q = 0.f;
; #pragma unroll
;             for (int bj = 0; bj < 2; ++bj) { const size_t p = (size_t)row * DM + EPI_COL(bj);
;                 const f32x4 x0 = xc[bj][0] + acc[ai][bj][m][0], x1 = xc[bj][1] + acc[ai][bj][m][1];
;                 __builtin_nontemporal_store(x0, (f32x4*)(xout + p)); __builtin_nontemporal_store(x1, (f32x4*)(xout + p + 4));
;                 *(u32x4*)(xb + p) = EPI_PACK8(x0, x1);
;                 q += EPI_SQ8(x0, x1); }
;             q += __shfl_xor(q, 16); q += __shfl_xor(q, 32);
;             if (fq == 0) atomicAdd(ssout + row, q);
.LBB0_795:
	s_lshl_b32 s0, s74, 8
	v_mov_b32_e32 v128, v180
	v_mov_b32_e32 v186, v177
	s_add_i32 s0, s0, s56
	v_and_b32_e32 v202, 64, v185
	v_add_u32_e32 v164, s0, v128
	s_lshl_b32 s0, s73, 8
	s_or_b32 s0, s0, s57
	v_ashrrev_i32_e32 v165, 31, v164
	v_lshl_add_u32 v162, v186, 3, s0
	v_lshlrev_b64 v[128:129], 12, v[164:165]
	v_ashrrev_i32_e32 v163, 31, v162
	v_add_u32_e32 v160, 0x80, v162
	v_lshl_add_u64 v[128:129], s[48:49], 0, v[128:129]
	v_lshlrev_b64 v[130:131], 2, v[162:163]
	v_ashrrev_i32_e32 v161, 31, v160
	v_lshl_add_u64 v[178:179], v[128:129], 0, v[130:131]
	v_lshlrev_b64 v[132:133], 2, v[160:161]
	global_load_dwordx4 v[170:173], v[178:179], off offset:16
	global_load_dwordx4 v[188:191], v[178:179], off
	v_lshl_add_u64 v[200:201], v[128:129], 0, v[132:133]
	global_load_dwordx4 v[192:195], v[200:201], off
	global_load_dwordx4 v[196:199], v[200:201], off offset:16
	v_add_u32_e32 v166, 16, v164
	v_ashrrev_i32_e32 v167, 31, v166
	v_lshlrev_b64 v[128:129], 12, v[166:167]
	v_lshl_add_u64 v[128:129], s[48:49], 0, v[128:129]
	v_lshl_add_u64 v[174:175], v[128:129], 0, v[130:131]
	v_lshl_add_u64 v[168:169], v[128:129], 0, v[132:133]
	global_load_dwordx4 v[136:139], v[174:175], off offset:16
	global_load_dwordx4 v[140:143], v[174:175], off
	global_load_dwordx4 v[128:131], v[168:169], off offset:16
	global_load_dwordx4 v[132:135], v[168:169], off
	v_xor_b32_e32 v187, 16, v185
	v_add_u32_e32 v202, 64, v202
	v_cmp_lt_i32_e64 s[0:1], v187, v202
	v_cmp_eq_u32_e32 vcc, 0, v186
	v_xor_b32_e32 v203, 32, v185
	v_cndmask_b32_e64 v186, v185, v187, s[0:1]
	v_lshlrev_b32_e32 v186, 2, v186
	v_cmp_lt_i32_e64 s[0:1], v203, v202
	s_waitcnt vmcnt(0)
	v_pk_add_f32 v[122:123], v[122:123], v[172:173]
	v_pk_add_f32 v[126:127], v[126:127], v[190:191]
	v_pk_add_f32 v[124:125], v[124:125], v[188:189]
	v_pk_add_f32 v[118:119], v[118:119], v[194:195]
	v_pk_add_f32 v[116:117], v[116:117], v[192:193]
	v_pk_add_f32 v[120:121], v[120:121], v[170:171]
	v_pk_add_f32 v[170:171], v[112:113], v[196:197]
	global_store_dwordx4 v[178:179], v[124:127], off nt
	global_store_dwordx4 v[178:179], v[120:123], off offset:16 nt
	v_cvt_pk_bf16_f32 v112, v124, v125
	v_cvt_pk_bf16_f32 v113, v126, v127
	v_mul_f32_e32 v178, v117, v117
	v_mul_f32_e32 v125, v125, v125
	v_mul_f32_e32 v127, v127, v127
	v_mul_f32_e32 v179, v119, v119
	v_pk_add_f32 v[172:173], v[114:115], v[198:199]
	v_cvt_pk_bf16_f32 v114, v120, v121
	v_cvt_pk_bf16_f32 v115, v122, v123
	v_mul_f32_e32 v121, v121, v121
	v_mul_f32_e32 v123, v123, v123
	v_mul_f32_e32 v189, v171, v171
	v_fmac_f32_e32 v125, v124, v124
	v_fmac_f32_e32 v127, v126, v126
	v_fmac_f32_e32 v178, v116, v116
	v_fmac_f32_e32 v179, v118, v118
	v_mul_f32_e32 v190, v173, v173
	v_fmac_f32_e32 v121, v120, v120
	v_fmac_f32_e32 v123, v122, v122
	v_fmac_f32_e32 v189, v170, v170
	v_add_f32_e32 v120, v125, v127
	v_add_f32_e32 v122, v178, v179
	v_fmac_f32_e32 v190, v172, v172
	v_add_f32_e32 v120, v120, v121
	v_add_f32_e32 v121, v122, v189
	v_add_f32_e32 v120, v123, v120
	v_add_f32_e32 v121, v190, v121
	v_add_f32_e32 v120, v120, v121
	ds_bpermute_b32 v121, v186, v120
	v_cndmask_b32_e64 v187, v185, v203, s[0:1]
	v_lshlrev_b64 v[202:203], 10, v[164:165]
	v_lshl_add_u64 v[204:205], v[202:203], 0, v[162:163]
	v_lshl_add_u64 v[204:205], v[204:205], 1, s[30:31]
	s_cmp_lg_u32 s99, 0
	s_cbranch_scc1 .Lwt792_19023
	global_store_dwordx4 v[204:205], v[112:115], off
	s_branch .Lwj792_19023
.Lwt792_19023:
	global_store_dwordx4 v[204:205], v[112:115], off sc1
.Lwj792_19023:
	global_store_dwordx4 v[200:201], v[116:119], off nt
	global_store_dwordx4 v[200:201], v[170:173], off offset:16 nt
	s_waitcnt lgkmcnt(0)
	v_add_f32_e32 v112, v120, v121
	v_lshlrev_b32_e32 v187, 2, v187
	ds_bpermute_b32 v113, v187, v112
	v_lshl_add_u64 v[202:203], v[202:203], 0, v[160:161]
	v_lshl_add_u64 v[114:115], v[202:203], 1, s[30:31]
	v_cvt_pk_bf16_f32 v188, v116, v117
	v_cvt_pk_bf16_f32 v189, v118, v119
	v_cvt_pk_bf16_f32 v190, v170, v171
	v_cvt_pk_bf16_f32 v191, v172, v173
	s_cmp_lg_u32 s99, 0
	s_cbranch_scc1 .Lwt792_19044
	global_store_dwordx4 v[114:115], v[188:191], off
	s_branch .Lwj792_19044
.Lwt792_19044:
	global_store_dwordx4 v[114:115], v[188:191], off sc1
.Lwj792_19044:
	s_and_saveexec_b64 s[0:1], vcc
	s_cbranch_execz .LBB0_797
	v_lshl_add_u64 v[114:115], v[164:165], 2, s[12:13]
	s_waitcnt lgkmcnt(0)
	v_add_f32_e32 v112, v112, v113
	global_atomic_add_f32 v[114:115], v112, off
.LBB0_797:
	s_or_b64 exec, exec, s[0:1]
	v_add_u32_e32 v170, 32, v164
	v_ashrrev_i32_e32 v171, 31, v170
	s_waitcnt lgkmcnt(0)
	v_lshlrev_b64 v[112:113], 12, v[170:171]
	v_lshl_add_u64 v[112:113], s[48:49], 0, v[112:113]
	v_lshl_add_u64 v[178:179], v[162:163], 2, v[112:113]
	v_lshl_add_u64 v[172:173], v[160:161], 2, v[112:113]
	global_load_dwordx4 v[120:123], v[178:179], off offset:16
	global_load_dwordx4 v[124:127], v[178:179], off
	global_load_dwordx4 v[112:115], v[172:173], off offset:16
	global_load_dwordx4 v[116:119], v[172:173], off
	v_pk_add_f32 v[110:111], v[110:111], v[142:143]
	v_pk_add_f32 v[108:109], v[108:109], v[140:141]
	v_pk_add_f32 v[106:107], v[106:107], v[138:139]
	v_pk_add_f32 v[104:105], v[104:105], v[136:137]
	global_store_dwordx4 v[174:175], v[108:111], off nt
	global_store_dwordx4 v[174:175], v[104:107], off offset:16 nt
	v_cvt_pk_bf16_f32 v136, v108, v109
	v_cvt_pk_bf16_f32 v138, v104, v105
	v_pk_add_f32 v[102:103], v[102:103], v[134:135]
	v_mul_f32_e32 v109, v109, v109
	v_fmac_f32_e32 v109, v108, v108
	v_mul_f32_e32 v108, v111, v111
	v_fmac_f32_e32 v108, v110, v110
	v_mul_f32_e32 v105, v105, v105
	v_add_f32_e32 v108, v109, v108
	v_fmac_f32_e32 v105, v104, v104
	v_add_f32_e32 v104, v108, v105
	v_mul_f32_e32 v105, v107, v107
	v_fmac_f32_e32 v105, v106, v106
	v_pk_add_f32 v[100:101], v[100:101], v[132:133]
	v_cvt_pk_bf16_f32 v137, v110, v111
	v_add_f32_e32 v110, v105, v104
	v_pk_add_f32 v[104:105], v[96:97], v[128:129]
	v_mul_f32_e32 v96, v101, v101
	v_mul_f32_e32 v97, v103, v103
	v_fmac_f32_e32 v96, v100, v100
	v_fmac_f32_e32 v97, v102, v102
	v_add_f32_e32 v96, v96, v97
	v_mul_f32_e32 v97, v105, v105
	v_cvt_pk_bf16_f32 v139, v106, v107
	v_pk_add_f32 v[106:107], v[98:99], v[130:131]
	v_fmac_f32_e32 v97, v104, v104
	v_add_f32_e32 v96, v96, v97
	v_mul_f32_e32 v97, v107, v107
	v_fmac_f32_e32 v97, v106, v106
	v_add_f32_e32 v96, v97, v96
	v_add_f32_e32 v96, v110, v96
	ds_bpermute_b32 v97, v186, v96
	v_lshlrev_b64 v[188:189], 10, v[166:167]
	v_lshl_add_u64 v[190:191], v[188:189], 0, v[162:163]
	v_lshl_add_u64 v[140:141], v[190:191], 1, s[30:31]
	v_lshl_add_u64 v[108:109], v[188:189], 0, v[160:161]
	s_waitcnt lgkmcnt(0)
	v_add_f32_e32 v96, v96, v97
	ds_bpermute_b32 v97, v187, v96
	s_cmp_lg_u32 s99, 0
	s_cbranch_scc1 .Lwt792_19118
	global_store_dwordx4 v[140:141], v[136:139], off
	s_branch .Lwj792_19118

; #define EPI_PACK8(v0, v1) (u32x4){pk2((v0)[0], (v0)[1]), pk2((v0)[2], (v0)[3]), pk2((v1)[0], (v1)[1]), pk2((v1)[2], (v1)[3])}
;     __device__ __forceinline__ void operator()(AccRef acc, const Unit& u, int wr, int wc, int fr, int fq) const {
;     ...
;             for (int bj = 0; bj < 2; ++bj) { const size_t p = (size_t)row * DM + EPI_COL(bj);
;                 const f32x4 x0 = xc[bj][0] + acc[ai][bj][m][0], x1 = xc[bj][1] + acc[ai][bj][m][1];
;                 __builtin_nontemporal_store(x0, (f32x4*)(xout + p)); __builtin_nontemporal_store(x1, (f32x4*)(xout + p + 4));
;                 *(u32x4*)(xb + p) = EPI_PACK8(x0, x1);
;                 q += EPI_SQ8(x0, x1); }
.Lwj792_19118:
	global_store_dwordx4 v[168:169], v[100:103], off nt
	global_store_dwordx4 v[168:169], v[104:107], off offset:16 nt
	v_cvt_pk_bf16_f32 v99, v102, v103
	v_cvt_pk_bf16_f32 v98, v100, v101
	s_nop 0
	v_lshl_add_u64 v[102:103], v[108:109], 1, s[30:31]
	v_cvt_pk_bf16_f32 v100, v104, v105
	v_cvt_pk_bf16_f32 v101, v106, v107
	s_cmp_lg_u32 s99, 0
	s_cbranch_scc1 .Lwt792_19135
	global_store_dwordx4 v[102:103], v[98:101], off
	s_branch .Lwj792_19135

; #define EPI_IT_ROW(it) EPI_ROW((it) >> 2, (it) & 3)
; #define EPI_PACK8(v0, v1) (u32x4){pk2((v0)[0], (v0)[1]), pk2((v0)[2], (v0)[3]), pk2((v1)[0], (v1)[1]), pk2((v1)[2], (v1)[3])}
;     __device__ __forceinline__ void operator()(AccRef acc, const Unit& u, int wr, int wc, int fr, int fq) const {
;     ...
;         for (int it = 0; it < 8; ++it) { const int ai = it >> 2, m = it & 3, row = EPI_IT_ROW(it);
;             if (it + 1 < 8) {
; #pragma unroll
;                 for (int bj = 0; bj < 2; ++bj) { const size_t p = (size_t)EPI_IT_ROW(it + 1) * DM + EPI_COL(bj); xn[bj][0] = *(const f32x4*)(xin + p); xn[bj][1] = *(const f32x4*)(xin + p + 4); } }
;             float q = 0.f;
; #pragma unroll
;             for (int bj = 0; bj < 2; ++bj) { const size_t p = (size_t)row * DM + EPI_COL(bj);
;                 const f32x4 x0 = xc[bj][0] + acc[ai][bj][m][0], x1 = xc[bj][1] + acc[ai][bj][m][1];
;                 __builtin_nontemporal_store(x0, (f32x4*)(xout + p)); __builtin_nontemporal_store(x1, (f32x4*)(xout + p + 4));
;                 *(u32x4*)(xb + p) = EPI_PACK8(x0, x1);
;                 q += EPI_SQ8(x0, x1); }
;             q += __shfl_xor(q, 16); q += __shfl_xor(q, 32);
;             if (fq == 0) atomicAdd(ssout + row, q);
.Lwj792_19135:
	s_and_saveexec_b64 s[0:1], vcc
	s_cbranch_execz .LBB0_799
	v_lshl_add_u64 v[98:99], v[166:167], 2, s[12:13]
	s_waitcnt lgkmcnt(0)
	v_add_f32_e32 v96, v96, v97
	global_atomic_add_f32 v[98:99], v96, off
.LBB0_799:
	s_or_b64 exec, exec, s[0:1]
	v_add_u32_e32 v128, 48, v164
	v_ashrrev_i32_e32 v129, 31, v128
	s_waitcnt lgkmcnt(0)
	v_lshlrev_b64 v[96:97], 12, v[128:129]
	v_lshl_add_u64 v[96:97], s[48:49], 0, v[96:97]
	v_lshl_add_u64 v[132:133], v[162:163], 2, v[96:97]
	v_lshl_add_u64 v[130:131], v[160:161], 2, v[96:97]
	global_load_dwordx4 v[104:107], v[132:133], off offset:16
	global_load_dwordx4 v[108:111], v[132:133], off
	global_load_dwordx4 v[96:99], v[130:131], off offset:16
	global_load_dwordx4 v[100:103], v[130:131], off
	s_waitcnt vmcnt(12)
	v_pk_add_f32 v[94:95], v[94:95], v[126:127]
	v_pk_add_f32 v[92:93], v[92:93], v[124:125]
	v_pk_add_f32 v[90:91], v[90:91], v[122:123]
	v_pk_add_f32 v[88:89], v[88:89], v[120:121]
	global_store_dwordx4 v[178:179], v[92:95], off nt
	global_store_dwordx4 v[178:179], v[88:91], off offset:16 nt
	v_cvt_pk_bf16_f32 v120, v92, v93
	v_cvt_pk_bf16_f32 v122, v88, v89
	s_waitcnt vmcnt(12)
	v_pk_add_f32 v[86:87], v[86:87], v[118:119]
	v_mul_f32_e32 v93, v93, v93
	v_fmac_f32_e32 v93, v92, v92
	v_mul_f32_e32 v92, v95, v95
	v_fmac_f32_e32 v92, v94, v94
	v_mul_f32_e32 v89, v89, v89
	v_add_f32_e32 v92, v93, v92
	v_fmac_f32_e32 v89, v88, v88
	v_add_f32_e32 v88, v92, v89
	v_mul_f32_e32 v89, v91, v91
	v_fmac_f32_e32 v89, v90, v90
	v_pk_add_f32 v[84:85], v[84:85], v[116:117]
	v_cvt_pk_bf16_f32 v121, v94, v95
	v_add_f32_e32 v94, v89, v88
	v_pk_add_f32 v[88:89], v[80:81], v[112:113]
	v_mul_f32_e32 v80, v85, v85
	v_mul_f32_e32 v81, v87, v87
	v_fmac_f32_e32 v80, v84, v84
	v_fmac_f32_e32 v81, v86, v86
	v_add_f32_e32 v80, v80, v81
	v_mul_f32_e32 v81, v89, v89
	v_cvt_pk_bf16_f32 v123, v90, v91
	v_pk_add_f32 v[90:91], v[82:83], v[114:115]
	v_fmac_f32_e32 v81, v88, v88
	v_add_f32_e32 v80, v80, v81
	v_mul_f32_e32 v81, v91, v91
	v_fmac_f32_e32 v81, v90, v90
	v_add_f32_e32 v80, v81, v80
	v_add_f32_e32 v80, v94, v80
	ds_bpermute_b32 v81, v186, v80
	v_lshlrev_b64 v[134:135], 10, v[170:171]
	v_lshl_add_u64 v[136:137], v[134:135], 0, v[162:163]
	v_lshl_add_u64 v[124:125], v[136:137], 1, s[30:31]
	v_lshl_add_u64 v[92:93], v[134:135], 0, v[160:161]
	s_waitcnt lgkmcnt(0)
	v_add_f32_e32 v80, v80, v81
	ds_bpermute_b32 v81, v187, v80
	s_cmp_lg_u32 s99, 0
	s_cbranch_scc1 .Lwt792_19211
	global_store_dwordx4 v[124:125], v[120:123], off
	s_branch .Lwj792_19211

; #define EPI_PACK8(v0, v1) (u32x4){pk2((v0)[0], (v0)[1]), pk2((v0)[2], (v0)[3]), pk2((v1)[0], (v1)[1]), pk2((v1)[2], (v1)[3])}
;     __device__ __forceinline__ void operator()(AccRef acc, const Unit& u, int wr, int wc, int fr, int fq) const {
;     ...
;             for (int bj = 0; bj < 2; ++bj) { const size_t p = (size_t)row * DM + EPI_COL(bj);
;                 const f32x4 x0 = xc[bj][0] + acc[ai][bj][m][0], x1 = xc[bj][1] + acc[ai][bj][m][1];
;                 __builtin_nontemporal_store(x0, (f32x4*)(xout + p)); __builtin_nontemporal_store(x1, (f32x4*)(xout + p + 4));
;                 *(u32x4*)(xb + p) = EPI_PACK8(x0, x1);
;                 q += EPI_SQ8(x0, x1); }
.Lwj792_19211:
	global_store_dwordx4 v[172:173], v[84:87], off nt
	global_store_dwordx4 v[172:173], v[88:91], off offset:16 nt
	v_cvt_pk_bf16_f32 v83, v86, v87
	v_cvt_pk_bf16_f32 v82, v84, v85
	s_nop 0
	v_lshl_add_u64 v[86:87], v[92:93], 1, s[30:31]
	v_cvt_pk_bf16_f32 v84, v88, v89
	v_cvt_pk_bf16_f32 v85, v90, v91
	s_cmp_lg_u32 s99, 0
	s_cbranch_scc1 .Lwt792_19228
	global_store_dwordx4 v[86:87], v[82:85], off
	s_branch .Lwj792_19228

; #define EPI_IT_ROW(it) EPI_ROW((it) >> 2, (it) & 3)
; #define EPI_PACK8(v0, v1) (u32x4){pk2((v0)[0], (v0)[1]), pk2((v0)[2], (v0)[3]), pk2((v1)[0], (v1)[1]), pk2((v1)[2], (v1)[3])}
;     __device__ __forceinline__ void operator()(AccRef acc, const Unit& u, int wr, int wc, int fr, int fq) const {
;     ...
;         for (int it = 0; it < 8; ++it) { const int ai = it >> 2, m = it & 3, row = EPI_IT_ROW(it);
;             if (it + 1 < 8) {
; #pragma unroll
;                 for (int bj = 0; bj < 2; ++bj) { const size_t p = (size_t)EPI_IT_ROW(it + 1) * DM + EPI_COL(bj); xn[bj][0] = *(const f32x4*)(xin + p); xn[bj][1] = *(const f32x4*)(xin + p + 4); } }
;             float q = 0.f;
; #pragma unroll
;             for (int bj = 0; bj < 2; ++bj) { const size_t p = (size_t)row * DM + EPI_COL(bj);
;                 const f32x4 x0 = xc[bj][0] + acc[ai][bj][m][0], x1 = xc[bj][1] + acc[ai][bj][m][1];
;                 __builtin_nontemporal_store(x0, (f32x4*)(xout + p)); __builtin_nontemporal_store(x1, (f32x4*)(xout + p + 4));
;                 *(u32x4*)(xb + p) = EPI_PACK8(x0, x1);
;                 q += EPI_SQ8(x0, x1); }
;             q += __shfl_xor(q, 16); q += __shfl_xor(q, 32);
;             if (fq == 0) atomicAdd(ssout + row, q);
.Lwj792_19228:
	s_and_saveexec_b64 s[0:1], vcc
	s_cbranch_execz .LBB0_801
	v_lshl_add_u64 v[82:83], v[170:171], 2, s[12:13]
	s_waitcnt lgkmcnt(0)
	v_add_f32_e32 v80, v80, v81
	global_atomic_add_f32 v[82:83], v80, off
.LBB0_801:
	s_or_b64 exec, exec, s[0:1]
	v_add_u32_e32 v112, 0x80, v164
	v_ashrrev_i32_e32 v113, 31, v112
	s_waitcnt lgkmcnt(0)
	v_lshlrev_b64 v[80:81], 12, v[112:113]
	v_lshl_add_u64 v[80:81], s[48:49], 0, v[80:81]
	v_lshl_add_u64 v[116:117], v[162:163], 2, v[80:81]
	v_lshl_add_u64 v[114:115], v[160:161], 2, v[80:81]
	global_load_dwordx4 v[88:91], v[116:117], off offset:16
	global_load_dwordx4 v[92:95], v[116:117], off
	global_load_dwordx4 v[80:83], v[114:115], off offset:16
	global_load_dwordx4 v[84:87], v[114:115], off
	s_waitcnt vmcnt(12)
	v_pk_add_f32 v[78:79], v[78:79], v[110:111]
	v_pk_add_f32 v[76:77], v[76:77], v[108:109]
	v_pk_add_f32 v[74:75], v[74:75], v[106:107]
	v_pk_add_f32 v[72:73], v[72:73], v[104:105]
	global_store_dwordx4 v[132:133], v[76:79], off nt
	global_store_dwordx4 v[132:133], v[72:75], off offset:16 nt
	v_cvt_pk_bf16_f32 v104, v76, v77
	v_cvt_pk_bf16_f32 v106, v72, v73
	s_waitcnt vmcnt(12)
	v_pk_add_f32 v[70:71], v[70:71], v[102:103]
	v_mul_f32_e32 v77, v77, v77
	v_fmac_f32_e32 v77, v76, v76
	v_mul_f32_e32 v76, v79, v79
	v_fmac_f32_e32 v76, v78, v78
	v_mul_f32_e32 v73, v73, v73
	v_add_f32_e32 v76, v77, v76
	v_fmac_f32_e32 v73, v72, v72
	v_add_f32_e32 v72, v76, v73
	v_mul_f32_e32 v73, v75, v75
	v_fmac_f32_e32 v73, v74, v74
	v_pk_add_f32 v[68:69], v[68:69], v[100:101]
	v_cvt_pk_bf16_f32 v105, v78, v79
	v_add_f32_e32 v78, v73, v72
	v_pk_add_f32 v[72:73], v[64:65], v[96:97]
	v_mul_f32_e32 v64, v69, v69
	v_mul_f32_e32 v65, v71, v71
	v_fmac_f32_e32 v64, v68, v68
	v_fmac_f32_e32 v65, v70, v70
	v_add_f32_e32 v64, v64, v65
	v_mul_f32_e32 v65, v73, v73
	v_cvt_pk_bf16_f32 v107, v74, v75
	v_pk_add_f32 v[74:75], v[66:67], v[98:99]
	v_fmac_f32_e32 v65, v72, v72
	v_add_f32_e32 v64, v64, v65
	v_mul_f32_e32 v65, v75, v75
	v_fmac_f32_e32 v65, v74, v74
	v_add_f32_e32 v64, v65, v64
	v_add_f32_e32 v64, v78, v64
	ds_bpermute_b32 v65, v186, v64
	v_lshlrev_b64 v[118:119], 10, v[128:129]
	v_lshl_add_u64 v[120:121], v[118:119], 0, v[162:163]
	v_lshl_add_u64 v[108:109], v[120:121], 1, s[30:31]
	v_lshl_add_u64 v[76:77], v[118:119], 0, v[160:161]
	s_waitcnt lgkmcnt(0)
	v_add_f32_e32 v64, v64, v65
	ds_bpermute_b32 v65, v187, v64
	s_cmp_lg_u32 s99, 0
	s_cbranch_scc1 .Lwt792_19304
	global_store_dwordx4 v[108:109], v[104:107], off
	s_branch .Lwj792_19304

; #define EPI_PACK8(v0, v1) (u32x4){pk2((v0)[0], (v0)[1]), pk2((v0)[2], (v0)[3]), pk2((v1)[0], (v1)[1]), pk2((v1)[2], (v1)[3])}
;     __device__ __forceinline__ void operator()(AccRef acc, const Unit& u, int wr, int wc, int fr, int fq) const {
;     ...
;             for (int bj = 0; bj < 2; ++bj) { const size_t p = (size_t)row * DM + EPI_COL(bj);
;                 const f32x4 x0 = xc[bj][0] + acc[ai][bj][m][0], x1 = xc[bj][1] + acc[ai][bj][m][1];
;                 __builtin_nontemporal_store(x0, (f32x4*)(xout + p)); __builtin_nontemporal_store(x1, (f32x4*)(xout + p + 4));
;                 *(u32x4*)(xb + p) = EPI_PACK8(x0, x1);
;                 q += EPI_SQ8(x0, x1); }
.Lwj792_19304:
	global_store_dwordx4 v[130:131], v[68:71], off nt
	global_store_dwordx4 v[130:131], v[72:75], off offset:16 nt
	v_cvt_pk_bf16_f32 v67, v70, v71
	v_cvt_pk_bf16_f32 v66, v68, v69
	s_nop 0
	v_lshl_add_u64 v[70:71], v[76:77], 1, s[30:31]
	v_cvt_pk_bf16_f32 v68, v72, v73
	v_cvt_pk_bf16_f32 v69, v74, v75
	s_cmp_lg_u32 s99, 0
	s_cbranch_scc1 .Lwt792_19321
	global_store_dwordx4 v[70:71], v[66:69], off
	s_branch .Lwj792_19321

; #define EPI_IT_ROW(it) EPI_ROW((it) >> 2, (it) & 3)
; #define EPI_PACK8(v0, v1) (u32x4){pk2((v0)[0], (v0)[1]), pk2((v0)[2], (v0)[3]), pk2((v1)[0], (v1)[1]), pk2((v1)[2], (v1)[3])}
;     __device__ __forceinline__ void operator()(AccRef acc, const Unit& u, int wr, int wc, int fr, int fq) const {
;     ...
;         for (int it = 0; it < 8; ++it) { const int ai = it >> 2, m = it & 3, row = EPI_IT_ROW(it);
;             if (it + 1 < 8) {
; #pragma unroll
;                 for (int bj = 0; bj < 2; ++bj) { const size_t p = (size_t)EPI_IT_ROW(it + 1) * DM + EPI_COL(bj); xn[bj][0] = *(const f32x4*)(xin + p); xn[bj][1] = *(const f32x4*)(xin + p + 4); } }
;             float q = 0.f;
; #pragma unroll
;             for (int bj = 0; bj < 2; ++bj) { const size_t p = (size_t)row * DM + EPI_COL(bj);
;                 const f32x4 x0 = xc[bj][0] + acc[ai][bj][m][0], x1 = xc[bj][1] + acc[ai][bj][m][1];
;                 __builtin_nontemporal_store(x0, (f32x4*)(xout + p)); __builtin_nontemporal_store(x1, (f32x4*)(xout + p + 4));
;                 *(u32x4*)(xb + p) = EPI_PACK8(x0, x1);
;                 q += EPI_SQ8(x0, x1); }
;             q += __shfl_xor(q, 16); q += __shfl_xor(q, 32);
;             if (fq == 0) atomicAdd(ssout + row, q);
.Lwj792_19321:
	s_and_saveexec_b64 s[0:1], vcc
	s_cbranch_execz .LBB0_803
	v_lshl_add_u64 v[66:67], v[128:129], 2, s[12:13]
	s_waitcnt lgkmcnt(0)
	v_add_f32_e32 v64, v64, v65
	global_atomic_add_f32 v[66:67], v64, off
.LBB0_803:
	s_or_b64 exec, exec, s[0:1]
	v_add_u32_e32 v96, 0x90, v164
	v_ashrrev_i32_e32 v97, 31, v96
	s_waitcnt lgkmcnt(0)
	v_lshlrev_b64 v[64:65], 12, v[96:97]
	v_lshl_add_u64 v[64:65], s[48:49], 0, v[64:65]
	v_lshl_add_u64 v[100:101], v[162:163], 2, v[64:65]
	v_lshl_add_u64 v[98:99], v[160:161], 2, v[64:65]
	global_load_dwordx4 v[72:75], v[100:101], off offset:16
	global_load_dwordx4 v[76:79], v[100:101], off
	global_load_dwordx4 v[64:67], v[98:99], off offset:16
	global_load_dwordx4 v[68:71], v[98:99], off
	s_waitcnt vmcnt(12)
	v_pk_add_f32 v[62:63], v[62:63], v[94:95]
	v_pk_add_f32 v[60:61], v[60:61], v[92:93]
	v_pk_add_f32 v[58:59], v[58:59], v[90:91]
	v_pk_add_f32 v[56:57], v[56:57], v[88:89]
	global_store_dwordx4 v[116:117], v[60:63], off nt
	global_store_dwordx4 v[116:117], v[56:59], off offset:16 nt
	v_cvt_pk_bf16_f32 v88, v60, v61
	v_cvt_pk_bf16_f32 v90, v56, v57
	s_waitcnt vmcnt(12)
	v_pk_add_f32 v[54:55], v[54:55], v[86:87]
	v_mul_f32_e32 v61, v61, v61
	v_fmac_f32_e32 v61, v60, v60
	v_mul_f32_e32 v60, v63, v63
	v_fmac_f32_e32 v60, v62, v62
	v_mul_f32_e32 v57, v57, v57
	v_add_f32_e32 v60, v61, v60
	v_fmac_f32_e32 v57, v56, v56
	v_add_f32_e32 v56, v60, v57
	v_mul_f32_e32 v57, v59, v59
	v_fmac_f32_e32 v57, v58, v58
	v_pk_add_f32 v[52:53], v[52:53], v[84:85]
	v_cvt_pk_bf16_f32 v89, v62, v63
	v_add_f32_e32 v62, v57, v56
	v_pk_add_f32 v[56:57], v[48:49], v[80:81]
	v_mul_f32_e32 v48, v53, v53
	v_mul_f32_e32 v49, v55, v55
	v_fmac_f32_e32 v48, v52, v52
	v_fmac_f32_e32 v49, v54, v54
	v_add_f32_e32 v48, v48, v49
	v_mul_f32_e32 v49, v57, v57
	v_cvt_pk_bf16_f32 v91, v58, v59
	v_pk_add_f32 v[58:59], v[50:51], v[82:83]
	v_fmac_f32_e32 v49, v56, v56
	v_add_f32_e32 v48, v48, v49
	v_mul_f32_e32 v49, v59, v59
	v_fmac_f32_e32 v49, v58, v58
	v_add_f32_e32 v48, v49, v48
	v_add_f32_e32 v48, v62, v48
	ds_bpermute_b32 v49, v186, v48
	v_lshlrev_b64 v[102:103], 10, v[112:113]
	v_lshl_add_u64 v[104:105], v[102:103], 0, v[162:163]
	v_lshl_add_u64 v[92:93], v[104:105], 1, s[30:31]
	v_lshl_add_u64 v[60:61], v[102:103], 0, v[160:161]
	s_waitcnt lgkmcnt(0)
	v_add_f32_e32 v48, v48, v49
	ds_bpermute_b32 v49, v187, v48
	s_cmp_lg_u32 s99, 0
	s_cbranch_scc1 .Lwt792_19397
	global_store_dwordx4 v[92:93], v[88:91], off
	s_branch .Lwj792_19397

; #define EPI_PACK8(v0, v1) (u32x4){pk2((v0)[0], (v0)[1]), pk2((v0)[2], (v0)[3]), pk2((v1)[0], (v1)[1]), pk2((v1)[2], (v1)[3])}
;     __device__ __forceinline__ void operator()(AccRef acc, const Unit& u, int wr, int wc, int fr, int fq) const {
;     ...
;             for (int bj = 0; bj < 2; ++bj) { const size_t p = (size_t)row * DM + EPI_COL(bj);
;                 const f32x4 x0 = xc[bj][0] + acc[ai][bj][m][0], x1 = xc[bj][1] + acc[ai][bj][m][1];
;                 __builtin_nontemporal_store(x0, (f32x4*)(xout + p)); __builtin_nontemporal_store(x1, (f32x4*)(xout + p + 4));
;                 *(u32x4*)(xb + p) = EPI_PACK8(x0, x1);
;                 q += EPI_SQ8(x0, x1); }
.Lwj792_19397:
	global_store_dwordx4 v[114:115], v[52:55], off nt
	global_store_dwordx4 v[114:115], v[56:59], off offset:16 nt
	v_cvt_pk_bf16_f32 v51, v54, v55
	v_cvt_pk_bf16_f32 v50, v52, v53
	s_nop 0
	v_lshl_add_u64 v[54:55], v[60:61], 1, s[30:31]
	v_cvt_pk_bf16_f32 v52, v56, v57
	v_cvt_pk_bf16_f32 v53, v58, v59
	s_cmp_lg_u32 s99, 0
	s_cbranch_scc1 .Lwt792_19414
	global_store_dwordx4 v[54:55], v[50:53], off
	s_branch .Lwj792_19414

; #define EPI_IT_ROW(it) EPI_ROW((it) >> 2, (it) & 3)
; #define EPI_PACK8(v0, v1) (u32x4){pk2((v0)[0], (v0)[1]), pk2((v0)[2], (v0)[3]), pk2((v1)[0], (v1)[1]), pk2((v1)[2], (v1)[3])}
;     __device__ __forceinline__ void operator()(AccRef acc, const Unit& u, int wr, int wc, int fr, int fq) const {
;     ...
;         for (int it = 0; it < 8; ++it) { const int ai = it >> 2, m = it & 3, row = EPI_IT_ROW(it);
;             if (it + 1 < 8) {
; #pragma unroll
;                 for (int bj = 0; bj < 2; ++bj) { const size_t p = (size_t)EPI_IT_ROW(it + 1) * DM + EPI_COL(bj); xn[bj][0] = *(const f32x4*)(xin + p); xn[bj][1] = *(const f32x4*)(xin + p + 4); } }
;             float q = 0.f;
; #pragma unroll
;             for (int bj = 0; bj < 2; ++bj) { const size_t p = (size_t)row * DM + EPI_COL(bj);
;                 const f32x4 x0 = xc[bj][0] + acc[ai][bj][m][0], x1 = xc[bj][1] + acc[ai][bj][m][1];
;                 __builtin_nontemporal_store(x0, (f32x4*)(xout + p)); __builtin_nontemporal_store(x1, (f32x4*)(xout + p + 4));
;                 *(u32x4*)(xb + p) = EPI_PACK8(x0, x1);
;                 q += EPI_SQ8(x0, x1); }
;             q += __shfl_xor(q, 16); q += __shfl_xor(q, 32);
;             if (fq == 0) atomicAdd(ssout + row, q);
.Lwj792_19414:
	s_and_saveexec_b64 s[0:1], vcc
	s_cbranch_execz .LBB0_805
	v_lshl_add_u64 v[50:51], v[112:113], 2, s[12:13]
	s_waitcnt lgkmcnt(0)
	v_add_f32_e32 v48, v48, v49
	global_atomic_add_f32 v[50:51], v48, off
.LBB0_805:
	s_or_b64 exec, exec, s[0:1]
	v_add_u32_e32 v80, 0xa0, v164
	v_ashrrev_i32_e32 v81, 31, v80
	s_waitcnt lgkmcnt(0)
	v_lshlrev_b64 v[48:49], 12, v[80:81]
	v_lshl_add_u64 v[48:49], s[48:49], 0, v[48:49]
	v_lshl_add_u64 v[84:85], v[162:163], 2, v[48:49]
	v_lshl_add_u64 v[82:83], v[160:161], 2, v[48:49]
	global_load_dwordx4 v[56:59], v[84:85], off offset:16
	global_load_dwordx4 v[60:63], v[84:85], off
	global_load_dwordx4 v[48:51], v[82:83], off offset:16
	global_load_dwordx4 v[52:55], v[82:83], off
	s_waitcnt vmcnt(12)
	v_pk_add_f32 v[46:47], v[46:47], v[78:79]
	v_pk_add_f32 v[44:45], v[44:45], v[76:77]
	v_pk_add_f32 v[42:43], v[42:43], v[74:75]
	v_pk_add_f32 v[40:41], v[40:41], v[72:73]
	global_store_dwordx4 v[100:101], v[44:47], off nt
	global_store_dwordx4 v[100:101], v[40:43], off offset:16 nt
	v_cvt_pk_bf16_f32 v72, v44, v45
	v_cvt_pk_bf16_f32 v74, v40, v41
	s_waitcnt vmcnt(12)
	v_pk_add_f32 v[38:39], v[38:39], v[70:71]
	v_mul_f32_e32 v45, v45, v45
	v_fmac_f32_e32 v45, v44, v44
	v_mul_f32_e32 v44, v47, v47
	v_fmac_f32_e32 v44, v46, v46
	v_mul_f32_e32 v41, v41, v41
	v_add_f32_e32 v44, v45, v44
	v_fmac_f32_e32 v41, v40, v40
	v_add_f32_e32 v40, v44, v41
	v_mul_f32_e32 v41, v43, v43
	v_fmac_f32_e32 v41, v42, v42
	v_pk_add_f32 v[36:37], v[36:37], v[68:69]
	v_cvt_pk_bf16_f32 v73, v46, v47
	v_add_f32_e32 v46, v41, v40
	v_pk_add_f32 v[40:41], v[32:33], v[64:65]
	v_mul_f32_e32 v32, v37, v37
	v_mul_f32_e32 v33, v39, v39
	v_fmac_f32_e32 v32, v36, v36
	v_fmac_f32_e32 v33, v38, v38
	v_add_f32_e32 v32, v32, v33
	v_mul_f32_e32 v33, v41, v41
	v_cvt_pk_bf16_f32 v75, v42, v43
	v_pk_add_f32 v[42:43], v[34:35], v[66:67]
	v_fmac_f32_e32 v33, v40, v40
	v_add_f32_e32 v32, v32, v33
	v_mul_f32_e32 v33, v43, v43
	v_fmac_f32_e32 v33, v42, v42
	v_add_f32_e32 v32, v33, v32
	v_add_f32_e32 v32, v46, v32
	ds_bpermute_b32 v33, v186, v32
	v_lshlrev_b64 v[86:87], 10, v[96:97]
	v_lshl_add_u64 v[88:89], v[86:87], 0, v[162:163]
	v_lshl_add_u64 v[76:77], v[88:89], 1, s[30:31]
	v_lshl_add_u64 v[44:45], v[86:87], 0, v[160:161]
	s_waitcnt lgkmcnt(0)
	v_add_f32_e32 v32, v32, v33
	ds_bpermute_b32 v33, v187, v32
	s_cmp_lg_u32 s99, 0
	s_cbranch_scc1 .Lwt792_19490
	global_store_dwordx4 v[76:77], v[72:75], off
	s_branch .Lwj792_19490

; #define EPI_PACK8(v0, v1) (u32x4){pk2((v0)[0], (v0)[1]), pk2((v0)[2], (v0)[3]), pk2((v1)[0], (v1)[1]), pk2((v1)[2], (v1)[3])}
;     __device__ __forceinline__ void operator()(AccRef acc, const Unit& u, int wr, int wc, int fr, int fq) const {
;     ...
;             for (int bj = 0; bj < 2; ++bj) { const size_t p = (size_t)row * DM + EPI_COL(bj);
;                 const f32x4 x0 = xc[bj][0] + acc[ai][bj][m][0], x1 = xc[bj][1] + acc[ai][bj][m][1];
;                 __builtin_nontemporal_store(x0, (f32x4*)(xout + p)); __builtin_nontemporal_store(x1, (f32x4*)(xout + p + 4));
;                 *(u32x4*)(xb + p) = EPI_PACK8(x0, x1);
;                 q += EPI_SQ8(x0, x1); }
.Lwj792_19490:
	global_store_dwordx4 v[98:99], v[36:39], off nt
	global_store_dwordx4 v[98:99], v[40:43], off offset:16 nt
	v_cvt_pk_bf16_f32 v35, v38, v39
	v_cvt_pk_bf16_f32 v34, v36, v37
	s_nop 0
	v_lshl_add_u64 v[38:39], v[44:45], 1, s[30:31]
	v_cvt_pk_bf16_f32 v36, v40, v41
	v_cvt_pk_bf16_f32 v37, v42, v43
	s_cmp_lg_u32 s99, 0
	s_cbranch_scc1 .Lwt792_19507
	global_store_dwordx4 v[38:39], v[34:37], off
	s_branch .Lwj792_19507

; #define EPI_IT_ROW(it) EPI_ROW((it) >> 2, (it) & 3)
; #define EPI_PACK8(v0, v1) (u32x4){pk2((v0)[0], (v0)[1]), pk2((v0)[2], (v0)[3]), pk2((v1)[0], (v1)[1]), pk2((v1)[2], (v1)[3])}
;     __device__ __forceinline__ void operator()(AccRef acc, const Unit& u, int wr, int wc, int fr, int fq) const {
;     ...
;         for (int it = 0; it < 8; ++it) { const int ai = it >> 2, m = it & 3, row = EPI_IT_ROW(it);
;             if (it + 1 < 8) {
; #pragma unroll
;                 for (int bj = 0; bj < 2; ++bj) { const size_t p = (size_t)EPI_IT_ROW(it + 1) * DM + EPI_COL(bj); xn[bj][0] = *(const f32x4*)(xin + p); xn[bj][1] = *(const f32x4*)(xin + p + 4); } }
;             float q = 0.f;
; #pragma unroll
;             for (int bj = 0; bj < 2; ++bj) { const size_t p = (size_t)row * DM + EPI_COL(bj);
;                 const f32x4 x0 = xc[bj][0] + acc[ai][bj][m][0], x1 = xc[bj][1] + acc[ai][bj][m][1];
;                 __builtin_nontemporal_store(x0, (f32x4*)(xout + p)); __builtin_nontemporal_store(x1, (f32x4*)(xout + p + 4));
;                 *(u32x4*)(xb + p) = EPI_PACK8(x0, x1);
;                 q += EPI_SQ8(x0, x1); }
;             q += __shfl_xor(q, 16); q += __shfl_xor(q, 32);
;             if (fq == 0) atomicAdd(ssout + row, q);
.Lwj792_19507:
	s_and_saveexec_b64 s[0:1], vcc
	s_cbranch_execz .LBB0_807
	v_lshl_add_u64 v[34:35], v[96:97], 2, s[12:13]
	s_waitcnt lgkmcnt(0)
	v_add_f32_e32 v32, v32, v33
	global_atomic_add_f32 v[34:35], v32, off
.LBB0_807:
	s_or_b64 exec, exec, s[0:1]
	v_add_u32_e32 v64, 0xb0, v164
	v_ashrrev_i32_e32 v65, 31, v64
	s_waitcnt lgkmcnt(0)
	v_lshlrev_b64 v[32:33], 12, v[64:65]
	v_lshl_add_u64 v[32:33], s[48:49], 0, v[32:33]
	v_lshl_add_u64 v[68:69], v[162:163], 2, v[32:33]
	v_lshl_add_u64 v[66:67], v[160:161], 2, v[32:33]
	global_load_dwordx4 v[40:43], v[68:69], off offset:16
	global_load_dwordx4 v[44:47], v[68:69], off
	global_load_dwordx4 v[32:35], v[66:67], off offset:16
	global_load_dwordx4 v[36:39], v[66:67], off
	s_waitcnt vmcnt(12)
	v_pk_add_f32 v[30:31], v[30:31], v[62:63]
	v_pk_add_f32 v[28:29], v[28:29], v[60:61]
	v_pk_add_f32 v[26:27], v[26:27], v[58:59]
	v_pk_add_f32 v[24:25], v[24:25], v[56:57]
	global_store_dwordx4 v[84:85], v[28:31], off nt
	global_store_dwordx4 v[84:85], v[24:27], off offset:16 nt
	v_cvt_pk_bf16_f32 v56, v28, v29
	v_cvt_pk_bf16_f32 v58, v24, v25
	s_waitcnt vmcnt(12)
	v_pk_add_f32 v[22:23], v[22:23], v[54:55]
	v_mul_f32_e32 v29, v29, v29
	v_fmac_f32_e32 v29, v28, v28
	v_mul_f32_e32 v28, v31, v31
	v_fmac_f32_e32 v28, v30, v30
	v_mul_f32_e32 v25, v25, v25
	v_add_f32_e32 v28, v29, v28
	v_fmac_f32_e32 v25, v24, v24
	v_add_f32_e32 v24, v28, v25
	v_mul_f32_e32 v25, v27, v27
	v_fmac_f32_e32 v25, v26, v26
	v_pk_add_f32 v[20:21], v[20:21], v[52:53]
	v_cvt_pk_bf16_f32 v57, v30, v31
	v_add_f32_e32 v30, v25, v24
	v_pk_add_f32 v[24:25], v[16:17], v[48:49]
	v_mul_f32_e32 v16, v21, v21
	v_mul_f32_e32 v17, v23, v23
	v_fmac_f32_e32 v16, v20, v20
	v_fmac_f32_e32 v17, v22, v22
	v_add_f32_e32 v16, v16, v17
	v_mul_f32_e32 v17, v25, v25
	v_cvt_pk_bf16_f32 v59, v26, v27
	v_pk_add_f32 v[26:27], v[18:19], v[50:51]
	v_fmac_f32_e32 v17, v24, v24
	v_add_f32_e32 v16, v16, v17
	v_mul_f32_e32 v17, v27, v27
	v_fmac_f32_e32 v17, v26, v26
	v_add_f32_e32 v16, v17, v16
	v_add_f32_e32 v16, v30, v16
	ds_bpermute_b32 v17, v186, v16
	v_lshlrev_b64 v[70:71], 10, v[80:81]
	v_lshl_add_u64 v[72:73], v[70:71], 0, v[162:163]
	v_lshl_add_u64 v[60:61], v[72:73], 1, s[30:31]
	v_lshl_add_u64 v[28:29], v[70:71], 0, v[160:161]
	s_waitcnt lgkmcnt(0)
	v_add_f32_e32 v16, v16, v17
	ds_bpermute_b32 v17, v187, v16
	s_cmp_lg_u32 s99, 0
	s_cbranch_scc1 .Lwt792_19583
	global_store_dwordx4 v[60:61], v[56:59], off
	s_branch .Lwj792_19583

; #define EPI_PACK8(v0, v1) (u32x4){pk2((v0)[0], (v0)[1]), pk2((v0)[2], (v0)[3]), pk2((v1)[0], (v1)[1]), pk2((v1)[2], (v1)[3])}
;     __device__ __forceinline__ void operator()(AccRef acc, const Unit& u, int wr, int wc, int fr, int fq) const {
;     ...
;             for (int bj = 0; bj < 2; ++bj) { const size_t p = (size_t)row * DM + EPI_COL(bj);
;                 const f32x4 x0 = xc[bj][0] + acc[ai][bj][m][0], x1 = xc[bj][1] + acc[ai][bj][m][1];
;                 __builtin_nontemporal_store(x0, (f32x4*)(xout + p)); __builtin_nontemporal_store(x1, (f32x4*)(xout + p + 4));
;                 *(u32x4*)(xb + p) = EPI_PACK8(x0, x1);
;                 q += EPI_SQ8(x0, x1); }
.Lwj792_19583:
	global_store_dwordx4 v[82:83], v[20:23], off nt
	global_store_dwordx4 v[82:83], v[24:27], off offset:16 nt
	v_cvt_pk_bf16_f32 v19, v22, v23
	v_cvt_pk_bf16_f32 v18, v20, v21
	s_nop 0
	v_lshl_add_u64 v[22:23], v[28:29], 1, s[30:31]
	v_cvt_pk_bf16_f32 v20, v24, v25
	v_cvt_pk_bf16_f32 v21, v26, v27
	s_cmp_lg_u32 s99, 0
	s_cbranch_scc1 .Lwt792_19600
	global_store_dwordx4 v[22:23], v[18:21], off
	s_branch .Lwj792_19600

; #define EPI_IT_ROW(it) EPI_ROW((it) >> 2, (it) & 3)
; #define EPI_PACK8(v0, v1) (u32x4){pk2((v0)[0], (v0)[1]), pk2((v0)[2], (v0)[3]), pk2((v1)[0], (v1)[1]), pk2((v1)[2], (v1)[3])}
;     __device__ __forceinline__ void operator()(AccRef acc, const Unit& u, int wr, int wc, int fr, int fq) const {
;     ...
;         for (int it = 0; it < 8; ++it) { const int ai = it >> 2, m = it & 3, row = EPI_IT_ROW(it);
;             if (it + 1 < 8) {
; #pragma unroll
;                 for (int bj = 0; bj < 2; ++bj) { const size_t p = (size_t)EPI_IT_ROW(it + 1) * DM + EPI_COL(bj); xn[bj][0] = *(const f32x4*)(xin + p); xn[bj][1] = *(const f32x4*)(xin + p + 4); } }
;             float q = 0.f;
; #pragma unroll
;             for (int bj = 0; bj < 2; ++bj) { const size_t p = (size_t)row * DM + EPI_COL(bj);
;                 const f32x4 x0 = xc[bj][0] + acc[ai][bj][m][0], x1 = xc[bj][1] + acc[ai][bj][m][1];
;                 __builtin_nontemporal_store(x0, (f32x4*)(xout + p)); __builtin_nontemporal_store(x1, (f32x4*)(xout + p + 4));
;                 *(u32x4*)(xb + p) = EPI_PACK8(x0, x1);
;                 q += EPI_SQ8(x0, x1); }
;             q += __shfl_xor(q, 16); q += __shfl_xor(q, 32);
;             if (fq == 0) atomicAdd(ssout + row, q);
.Lwj792_19600:
	s_and_saveexec_b64 s[0:1], vcc
	s_cbranch_execz .LBB0_809
	v_lshl_add_u64 v[18:19], v[80:81], 2, s[12:13]
	s_waitcnt lgkmcnt(0)
	v_add_f32_e32 v16, v16, v17
	global_atomic_add_f32 v[18:19], v16, off
.LBB0_809:
	s_or_b64 exec, exec, s[0:1]
	s_waitcnt vmcnt(8)
	v_pk_add_f32 v[14:15], v[14:15], v[46:47]
	v_pk_add_f32 v[12:13], v[12:13], v[44:45]
	v_pk_add_f32 v[10:11], v[10:11], v[42:43]
	v_pk_add_f32 v[8:9], v[8:9], v[40:41]
	global_store_dwordx4 v[68:69], v[12:15], off nt
	global_store_dwordx4 v[68:69], v[8:11], off offset:16 nt
	v_cvt_pk_bf16_f32 v16, v12, v13
	v_cvt_pk_bf16_f32 v18, v8, v9
	s_waitcnt vmcnt(8)
	v_pk_add_f32 v[6:7], v[6:7], v[38:39]
	v_mul_f32_e32 v13, v13, v13
	v_fmac_f32_e32 v13, v12, v12
	v_mul_f32_e32 v12, v15, v15
	v_fmac_f32_e32 v12, v14, v14
	v_mul_f32_e32 v9, v9, v9
	v_add_f32_e32 v12, v13, v12
	v_fmac_f32_e32 v9, v8, v8
	v_add_f32_e32 v8, v12, v9
	v_mul_f32_e32 v9, v11, v11
	v_fmac_f32_e32 v9, v10, v10
	v_pk_add_f32 v[4:5], v[4:5], v[36:37]
	s_waitcnt lgkmcnt(0)
	v_cvt_pk_bf16_f32 v17, v14, v15
	v_add_f32_e32 v14, v9, v8
	v_pk_add_f32 v[8:9], v[0:1], v[32:33]
	v_mul_f32_e32 v0, v5, v5
	v_mul_f32_e32 v1, v7, v7
	v_fmac_f32_e32 v0, v4, v4
	v_fmac_f32_e32 v1, v6, v6
	v_add_f32_e32 v0, v0, v1
	v_mul_f32_e32 v1, v9, v9
	v_cvt_pk_bf16_f32 v19, v10, v11
	v_pk_add_f32 v[10:11], v[2:3], v[34:35]
	v_fmac_f32_e32 v1, v8, v8
	v_add_f32_e32 v0, v0, v1
	v_mul_f32_e32 v1, v11, v11
	v_fmac_f32_e32 v1, v10, v10
	v_add_f32_e32 v0, v1, v0
	v_add_f32_e32 v0, v14, v0
	ds_bpermute_b32 v1, v186, v0
	v_lshlrev_b64 v[20:21], 10, v[64:65]
	v_lshl_add_u64 v[22:23], v[20:21], 0, v[162:163]
	v_lshl_add_u64 v[22:23], v[22:23], 1, s[30:31]
	v_lshl_add_u64 v[12:13], v[20:21], 0, v[160:161]
	s_waitcnt lgkmcnt(0)
	v_add_f32_e32 v0, v0, v1
	ds_bpermute_b32 v1, v187, v0
	s_cmp_lg_u32 s99, 0
	s_cbranch_scc1 .Lwt792_19666
	global_store_dwordx4 v[22:23], v[16:19], off
	s_branch .Lwj792_19666

; #define EPI_PACK8(v0, v1) (u32x4){pk2((v0)[0], (v0)[1]), pk2((v0)[2], (v0)[3]), pk2((v1)[0], (v1)[1]), pk2((v1)[2], (v1)[3])}
;     __device__ __forceinline__ void operator()(AccRef acc, const Unit& u, int wr, int wc, int fr, int fq) const {
;     ...
;             for (int bj = 0; bj < 2; ++bj) { const size_t p = (size_t)row * DM + EPI_COL(bj);
;                 const f32x4 x0 = xc[bj][0] + acc[ai][bj][m][0], x1 = xc[bj][1] + acc[ai][bj][m][1];
;                 __builtin_nontemporal_store(x0, (f32x4*)(xout + p)); __builtin_nontemporal_store(x1, (f32x4*)(xout + p + 4));
;                 *(u32x4*)(xb + p) = EPI_PACK8(x0, x1);
;                 q += EPI_SQ8(x0, x1); }
.Lwj792_19666:
	global_store_dwordx4 v[66:67], v[4:7], off nt
	global_store_dwordx4 v[66:67], v[8:11], off offset:16 nt
	v_cvt_pk_bf16_f32 v3, v6, v7
	v_cvt_pk_bf16_f32 v2, v4, v5
	s_nop 0
	v_lshl_add_u64 v[6:7], v[12:13], 1, s[30:31]
	v_cvt_pk_bf16_f32 v4, v8, v9
	v_cvt_pk_bf16_f32 v5, v10, v11
	s_cmp_lg_u32 s99, 0
	s_cbranch_scc1 .Lwt792_19683
	global_store_dwordx4 v[6:7], v[2:5], off
	s_branch .Lwj792_19683

;     __device__ __forceinline__ void operator()(AccRef acc, const Unit& u, int wr, int wc, int fr, int fq) const {
;     ...
;             q += __shfl_xor(q, 16); q += __shfl_xor(q, 32);
;             if (fq == 0) atomicAdd(ssout + row, q);
.Lwj792_19683:
	s_and_saveexec_b64 s[0:1], vcc
	s_cbranch_execz .LBB0_811
	v_lshl_add_u64 v[2:3], v[64:65], 2, s[12:13]
	s_waitcnt lgkmcnt(0)
	v_add_f32_e32 v0, v0, v1
	global_atomic_add_f32 v[2:3], v0, off

; #define PG8_STAGE(bufoff, gbase, voff) do { _Pragma("unroll") for (int _i = 0; _i < 2; ++_i) \
;         __builtin_amdgcn_global_load_lds((const unsigned*)((const char*)(gbase) + (voff)[_i]), (LAS unsigned*)(lds + (bufoff) + ldsw + _i * 8192), 16, 0, 0); } while (0)
; #define PG8_LDA(dst, b, h) do { _Pragma("unroll") for (int m = 0; m < 4; ++m) _Pragma("unroll") for (int k = 0; k < 2; ++k) dst[m][k] = *(const LAS bf16x8*)(lds + PG8_SA(b, h) + aoff + m * 2048 + k * 1024); } while (0)
; #define PG8_LDB(dst, b, h) do { _Pragma("unroll") for (int n = 0; n < 2; ++n) _Pragma("unroll") for (int k = 0; k < 2; ++k) dst[n][k] = *(const LAS bf16x8*)(lds + PG8_SB(b, h) + boff + n * 2048 + k * 1024); } while (0)
; #define PG8_MMA(ai, bj, At, Bt) do { __builtin_amdgcn_s_setprio(1); _Pragma("unroll") for (int m = 0; m < 4; ++m) _Pragma("unroll") for (int n = 0; n < 2; ++n) _Pragma("unroll") for (int k = 0; k < 2; ++k) \
;         acc[ai][bj][m][n] = __builtin_amdgcn_mfma_f32_16x16x32_bf16(Bt[n][k], At[m][k], acc[ai][bj][m][n], 0, 0, 0); __builtin_amdgcn_s_setprio(0); } while (0)
; #define PG8_WAIT_V(n) asm volatile("s_waitcnt vmcnt(" #n ")" ::: "memory")
; #define PG8_WAIT_L(n) asm volatile("s_waitcnt lgkmcnt(" #n ")" ::: "memory")
; #define PG8_BAR __builtin_amdgcn_s_barrier()
; #define PG8_SCHED __builtin_amdgcn_sched_barrier(0)
; template <class Epi>
; __device__ __forceinline__ void gemm_phase(LAS unsigned char* lds, const Gemm g, const StaticOrder& S, const Epi& E) {
;     ...
;             PG8_LDB(B0, 0, 0); PG8_LDB(B1, 0, 1); PG8_SCHED; PG8_LDA(At, 0, 0); PG8_STAGE(PG8_SA(1, 1), a1 + hstepA, voffA);
;             PG8_WAIT_V(8); PG8_WAIT_L(0); PG8_BAR; PG8_MMA(0, 0, At, B0); PG8_MMA(0, 1, At, B1); PG8_BAR; PG8_SCHED;
;             PG8_LDA(At, 0, 1); PG8_STAGE(PG8_SB(0, 0), b2, voffB); PG8_STAGE(PG8_SB(0, 1), b2 + hstepB, voffB); PG8_STAGE(PG8_SA(0, 0), a2, voffA);
;             PG8_WAIT_V(8); PG8_WAIT_L(0); PG8_BAR; PG8_MMA(1, 0, At, B0); PG8_MMA(1, 1, At, B1); PG8_BAR; PG8_SCHED;
.LBB0_889:
	ds_read_b128 v[40:43], v208
	ds_read_b128 v[44:47], v208 offset:1024
	ds_read_b128 v[56:59], v208 offset:2048
	ds_read_b128 v[60:63], v208 offset:3072
	ds_read_b128 v[144:147], v209
	ds_read_b128 v[148:151], v209 offset:1024
	ds_read_b128 v[152:155], v209 offset:2048
	ds_read_b128 v[156:159], v209 offset:3072
	s_add_u32 s62, s56, 0xfffc0080
	s_addc_u32 s63, s57, -1
	s_cmp_eq_u32 s85, 12
	s_cselect_b32 s65, s7, s63
	s_cselect_b32 s64, s9, s62
	s_cselect_b32 s63, s39, s84
	s_cselect_b32 s62, s43, s83
	v_lshl_add_u64 v[218:219], s[56:57], 0, v[178:179]
	s_add_i32 m0, s69, 0xc000
	ds_read_b128 v[160:163], v210
	ds_read_b128 v[164:167], v210 offset:1024
	ds_read_b128 v[186:189], v210 offset:2048
	ds_read_b128 v[190:193], v210 offset:3072
	ds_read_b128 v[194:197], v210 offset:4096
	ds_read_b128 v[198:201], v210 offset:5120
	ds_read_b128 v[202:205], v210 offset:6144
	ds_read_b128 v[214:217], v210 offset:7168
	global_load_lds_dwordx4 v[218:219], off
	v_lshl_add_u64 v[218:219], s[56:57], 0, v[180:181]
	s_add_i32 m0, s69, 0xe000
	s_nop 0
	global_load_lds_dwordx4 v[218:219], off
	s_waitcnt vmcnt(8)
	s_waitcnt lgkmcnt(0)
	s_barrier
	s_setprio 1
	s_waitcnt lgkmcnt(0)
	v_mfma_f32_16x16x32_bf16 v[140:143], v[40:43], v[160:163], v[140:143]
	v_mfma_f32_16x16x32_bf16 v[136:139], v[56:59], v[160:163], v[136:139]
	v_mfma_f32_16x16x32_bf16 v[124:127], v[40:43], v[186:189], v[124:127]
	v_mfma_f32_16x16x32_bf16 v[120:123], v[56:59], v[186:189], v[120:123]
	v_mfma_f32_16x16x32_bf16 v[108:111], v[40:43], v[194:197], v[108:111]
	v_mfma_f32_16x16x32_bf16 v[104:107], v[56:59], v[194:197], v[104:107]
	v_mfma_f32_16x16x32_bf16 v[92:95], v[40:43], v[202:205], v[92:95]
	v_mfma_f32_16x16x32_bf16 v[88:91], v[56:59], v[202:205], v[88:91]
	v_mfma_f32_16x16x32_bf16 v[140:143], v[44:47], v[164:167], v[140:143]
	v_mfma_f32_16x16x32_bf16 v[136:139], v[60:63], v[164:167], v[136:139]
	v_mfma_f32_16x16x32_bf16 v[124:127], v[44:47], v[190:193], v[124:127]
	v_mfma_f32_16x16x32_bf16 v[120:123], v[60:63], v[190:193], v[120:123]
	v_mfma_f32_16x16x32_bf16 v[108:111], v[44:47], v[198:201], v[108:111]
	v_mfma_f32_16x16x32_bf16 v[104:107], v[60:63], v[198:201], v[104:107]
	v_mfma_f32_16x16x32_bf16 v[92:95], v[44:47], v[214:217], v[92:95]
	v_mfma_f32_16x16x32_bf16 v[88:91], v[60:63], v[214:217], v[88:91]
	s_setprio 0
	s_setprio 1
	v_mfma_f32_16x16x32_bf16 v[132:135], v[144:147], v[160:163], v[132:135]
	v_mfma_f32_16x16x32_bf16 v[128:131], v[152:155], v[160:163], v[128:131]
	v_mfma_f32_16x16x32_bf16 v[116:119], v[144:147], v[186:189], v[116:119]
	v_mfma_f32_16x16x32_bf16 v[112:115], v[152:155], v[186:189], v[112:115]
	v_mfma_f32_16x16x32_bf16 v[100:103], v[144:147], v[194:197], v[100:103]
	v_mfma_f32_16x16x32_bf16 v[96:99], v[152:155], v[194:197], v[96:99]
	v_mfma_f32_16x16x32_bf16 v[84:87], v[144:147], v[202:205], v[84:87]
	v_mfma_f32_16x16x32_bf16 v[80:83], v[152:155], v[202:205], v[80:83]
	v_mfma_f32_16x16x32_bf16 v[132:135], v[148:151], v[164:167], v[132:135]
	v_mfma_f32_16x16x32_bf16 v[128:131], v[156:159], v[164:167], v[128:131]
	v_mfma_f32_16x16x32_bf16 v[116:119], v[148:151], v[190:193], v[116:119]
	v_mfma_f32_16x16x32_bf16 v[112:115], v[156:159], v[190:193], v[112:115]
	v_mfma_f32_16x16x32_bf16 v[100:103], v[148:151], v[198:201], v[100:103]
	v_mfma_f32_16x16x32_bf16 v[96:99], v[156:159], v[198:201], v[96:99]
	v_mfma_f32_16x16x32_bf16 v[84:87], v[148:151], v[214:217], v[84:87]
	v_mfma_f32_16x16x32_bf16 v[80:83], v[156:159], v[214:217], v[80:83]
	s_setprio 0
	s_barrier
	s_add_i32 s86, s81, s68
	v_lshl_add_u64 v[218:219], s[62:63], 0, v[170:171]
	s_mov_b32 m0, s86
	ds_read_b128 v[160:163], v210 offset:16384
	ds_read_b128 v[164:167], v210 offset:17408
	ds_read_b128 v[186:189], v210 offset:18432
	ds_read_b128 v[190:193], v210 offset:19456
	ds_read_b128 v[194:197], v210 offset:20480
	ds_read_b128 v[198:201], v210 offset:21504
	ds_read_b128 v[202:205], v210 offset:22528
	ds_read_b128 v[214:217], v210 offset:23552
	global_load_lds_dwordx4 v[218:219], off
	s_add_i32 m0, s86, 0x2000
	s_add_u32 s86, s62, 0x40000
	v_lshl_add_u64 v[220:221], s[62:63], 0, v[174:175]
	s_addc_u32 s87, s63, 0
	s_add_i32 s88, s82, s68
	global_load_lds_dwordx4 v[220:221], off
	v_lshl_add_u64 v[222:223], s[86:87], 0, v[170:171]
	s_mov_b32 m0, s88
	v_lshl_add_u64 v[226:227], s[64:65], 0, v[172:173]
	global_load_lds_dwordx4 v[222:223], off
	v_lshl_add_u64 v[222:223], s[86:87], 0, v[174:175]
	s_add_i32 m0, s88, 0x2000
	s_nop 0
	global_load_lds_dwordx4 v[222:223], off
	v_lshl_add_u64 v[222:223], s[64:65], 0, v[168:169]
	s_mov_b32 m0, s69
	s_nop 0
	global_load_lds_dwordx4 v[222:223], off
	s_mov_b32 m0, s70
	s_nop 0
	global_load_lds_dwordx4 v[226:227], off
	s_waitcnt vmcnt(8)
	s_waitcnt lgkmcnt(0)
	s_barrier
; #define PG8_STAGE(bufoff, gbase, voff) do { _Pragma("unroll") for (int _i = 0; _i < 2; ++_i) \
;         __builtin_amdgcn_global_load_lds((const unsigned*)((const char*)(gbase) + (voff)[_i]), (LAS unsigned*)(lds + (bufoff) + ldsw + _i * 8192), 16, 0, 0); } while (0)
; #define PG8_LDA(dst, b, h) do { _Pragma("unroll") for (int m = 0; m < 4; ++m) _Pragma("unroll") for (int k = 0; k < 2; ++k) dst[m][k] = *(const LAS bf16x8*)(lds + PG8_SA(b, h) + aoff + m * 2048 + k * 1024); } while (0)
; #define PG8_LDB(dst, b, h) do { _Pragma("unroll") for (int n = 0; n < 2; ++n) _Pragma("unroll") for (int k = 0; k < 2; ++k) dst[n][k] = *(const LAS bf16x8*)(lds + PG8_SB(b, h) + boff + n * 2048 + k * 1024); } while (0)
; #define PG8_MMA(ai, bj, At, Bt) do { __builtin_amdgcn_s_setprio(1); _Pragma("unroll") for (int m = 0; m < 4; ++m) _Pragma("unroll") for (int n = 0; n < 2; ++n) _Pragma("unroll") for (int k = 0; k < 2; ++k) \
;         acc[ai][bj][m][n] = __builtin_amdgcn_mfma_f32_16x16x32_bf16(Bt[n][k], At[m][k], acc[ai][bj][m][n], 0, 0, 0); __builtin_amdgcn_s_setprio(0); } while (0)
; #define PG8_WAIT_V(n) asm volatile("s_waitcnt vmcnt(" #n ")" ::: "memory")
; #define PG8_WAIT_L(n) asm volatile("s_waitcnt lgkmcnt(" #n ")" ::: "memory")
; #define PG8_BAR __builtin_amdgcn_s_barrier()
; #define PG8_SCHED __builtin_amdgcn_sched_barrier(0)
; template <class Epi>
; __device__ __forceinline__ void gemm_phase(LAS unsigned char* lds, const Gemm g, const StaticOrder& S, const Epi& E) {
;     ...
;             PG8_WAIT_V(8); PG8_WAIT_L(0); PG8_BAR; PG8_MMA(1, 0, At, B0); PG8_MMA(1, 1, At, B1); PG8_BAR; PG8_SCHED;
;             PG8_LDB(B0, 1, 0); PG8_LDB(B1, 1, 1); PG8_SCHED; PG8_LDA(At, 1, 0); PG8_STAGE(PG8_SA(0, 1), a2 + hstepA, voffA);
;             PG8_WAIT_V(8); PG8_WAIT_L(0); PG8_BAR; PG8_MMA(0, 0, At, B0); PG8_MMA(0, 1, At, B1); PG8_BAR; PG8_SCHED;
;             PG8_LDA(At, 1, 1); PG8_STAGE(PG8_SB(1, 0), b3, voffB); PG8_STAGE(PG8_SB(1, 1), b3 + hstepB, voffB); PG8_STAGE(PG8_SA(1, 0), a3, voffA);
;             PG8_WAIT_V(8); PG8_WAIT_L(0); PG8_BAR; PG8_MMA(1, 0, At, B0); PG8_MMA(1, 1, At, B1); PG8_BAR; PG8_SCHED;
	s_setprio 1
	s_waitcnt lgkmcnt(0)
	v_mfma_f32_16x16x32_bf16 v[76:79], v[40:43], v[160:163], v[76:79]
	v_mfma_f32_16x16x32_bf16 v[72:75], v[56:59], v[160:163], v[72:75]
	v_mfma_f32_16x16x32_bf16 v[52:55], v[40:43], v[186:189], v[52:55]
	v_mfma_f32_16x16x32_bf16 v[48:51], v[56:59], v[186:189], v[48:51]
	v_mfma_f32_16x16x32_bf16 v[28:31], v[40:43], v[194:197], v[28:31]
	v_mfma_f32_16x16x32_bf16 v[24:27], v[56:59], v[194:197], v[24:27]
	v_mfma_f32_16x16x32_bf16 v[12:15], v[40:43], v[202:205], v[12:15]
	v_mfma_f32_16x16x32_bf16 v[8:11], v[56:59], v[202:205], v[8:11]
	v_mfma_f32_16x16x32_bf16 v[76:79], v[44:47], v[164:167], v[76:79]
	v_mfma_f32_16x16x32_bf16 v[72:75], v[60:63], v[164:167], v[72:75]
	v_mfma_f32_16x16x32_bf16 v[52:55], v[44:47], v[190:193], v[52:55]
	v_mfma_f32_16x16x32_bf16 v[48:51], v[60:63], v[190:193], v[48:51]
	v_mfma_f32_16x16x32_bf16 v[28:31], v[44:47], v[198:201], v[28:31]
	v_mfma_f32_16x16x32_bf16 v[24:27], v[60:63], v[198:201], v[24:27]
	v_mfma_f32_16x16x32_bf16 v[12:15], v[44:47], v[214:217], v[12:15]
	v_mfma_f32_16x16x32_bf16 v[8:11], v[60:63], v[214:217], v[8:11]
	s_setprio 0
	s_setprio 1
	v_mfma_f32_16x16x32_bf16 v[36:39], v[144:147], v[186:189], v[36:39]
	v_mfma_f32_16x16x32_bf16 v[32:35], v[152:155], v[186:189], v[32:35]
	v_mfma_f32_16x16x32_bf16 v[20:23], v[144:147], v[194:197], v[20:23]
	v_mfma_f32_16x16x32_bf16 v[16:19], v[152:155], v[194:197], v[16:19]
	v_mfma_f32_16x16x32_bf16 v[4:7], v[144:147], v[202:205], v[4:7]
	v_mfma_f32_16x16x32_bf16 v[0:3], v[152:155], v[202:205], v[0:3]
	v_mfma_f32_16x16x32_bf16 v[40:43], v[144:147], v[160:163], v[68:71]
	v_mfma_f32_16x16x32_bf16 v[44:47], v[152:155], v[160:163], v[64:67]
	v_mfma_f32_16x16x32_bf16 v[36:39], v[148:151], v[190:193], v[36:39]
	v_mfma_f32_16x16x32_bf16 v[32:35], v[156:159], v[190:193], v[32:35]
	v_mfma_f32_16x16x32_bf16 v[20:23], v[148:151], v[198:201], v[20:23]
	v_mfma_f32_16x16x32_bf16 v[16:19], v[156:159], v[198:201], v[16:19]
	v_mfma_f32_16x16x32_bf16 v[4:7], v[148:151], v[214:217], v[4:7]
	v_mfma_f32_16x16x32_bf16 v[0:3], v[156:159], v[214:217], v[0:3]
	v_mfma_f32_16x16x32_bf16 v[40:43], v[148:151], v[164:167], v[40:43]
	v_mfma_f32_16x16x32_bf16 v[44:47], v[156:159], v[164:167], v[44:47]
	s_setprio 0
	s_barrier
	s_add_i32 s86, 0, 0x18000
	s_add_i32 s87, 0, 0x1c000
	v_add_u32_e32 v68, s86, v207
	v_add_u32_e32 v156, s87, v207
	ds_read_b128 v[56:59], v68
	ds_read_b128 v[60:63], v68 offset:1024
	ds_read_b128 v[64:67], v68 offset:2048
	ds_read_b128 v[68:71], v68 offset:3072
	ds_read_b128 v[144:147], v156
	ds_read_b128 v[148:151], v156 offset:1024
	ds_read_b128 v[152:155], v156 offset:2048
	ds_read_b128 v[156:159], v156 offset:3072
	s_add_u32 s64, s64, 0x40000
	s_addc_u32 s65, s65, 0
	s_mov_b32 m0, s71
	v_lshl_add_u64 v[228:229], s[64:65], 0, v[168:169]
	ds_read_b128 v[160:163], v210 offset:32768
	ds_read_b128 v[164:167], v210 offset:33792
	ds_read_b128 v[186:189], v210 offset:34816
	ds_read_b128 v[190:193], v210 offset:35840
	ds_read_b128 v[194:197], v210 offset:36864
	ds_read_b128 v[198:201], v210 offset:37888
	ds_read_b128 v[202:205], v210 offset:38912
	ds_read_b128 v[214:217], v210 offset:39936
	global_load_lds_dwordx4 v[228:229], off
	v_lshl_add_u64 v[228:229], s[64:65], 0, v[172:173]
	s_mov_b32 m0, s72
	s_nop 0
	global_load_lds_dwordx4 v[228:229], off
	s_waitcnt vmcnt(8)
	s_waitcnt lgkmcnt(0)
	s_barrier
	s_setprio 1
	s_waitcnt lgkmcnt(0)
	v_mfma_f32_16x16x32_bf16 v[140:143], v[56:59], v[160:163], v[140:143]
	v_mfma_f32_16x16x32_bf16 v[136:139], v[64:67], v[160:163], v[136:139]
	v_mfma_f32_16x16x32_bf16 v[124:127], v[56:59], v[186:189], v[124:127]
	v_mfma_f32_16x16x32_bf16 v[120:123], v[64:67], v[186:189], v[120:123]
	v_mfma_f32_16x16x32_bf16 v[108:111], v[56:59], v[194:197], v[108:111]
	v_mfma_f32_16x16x32_bf16 v[104:107], v[64:67], v[194:197], v[104:107]
	v_mfma_f32_16x16x32_bf16 v[92:95], v[56:59], v[202:205], v[92:95]
	v_mfma_f32_16x16x32_bf16 v[88:91], v[64:67], v[202:205], v[88:91]
	v_mfma_f32_16x16x32_bf16 v[140:143], v[60:63], v[164:167], v[140:143]
	v_mfma_f32_16x16x32_bf16 v[136:139], v[68:71], v[164:167], v[136:139]
	v_mfma_f32_16x16x32_bf16 v[124:127], v[60:63], v[190:193], v[124:127]
	v_mfma_f32_16x16x32_bf16 v[120:123], v[68:71], v[190:193], v[120:123]
	v_mfma_f32_16x16x32_bf16 v[108:111], v[60:63], v[198:201], v[108:111]
	v_mfma_f32_16x16x32_bf16 v[104:107], v[68:71], v[198:201], v[104:107]
	v_mfma_f32_16x16x32_bf16 v[92:95], v[60:63], v[214:217], v[92:95]
	v_mfma_f32_16x16x32_bf16 v[88:91], v[68:71], v[214:217], v[88:91]
	s_setprio 0
	s_setprio 1
	v_mfma_f32_16x16x32_bf16 v[132:135], v[144:147], v[160:163], v[132:135]
	v_mfma_f32_16x16x32_bf16 v[128:131], v[152:155], v[160:163], v[128:131]
	v_mfma_f32_16x16x32_bf16 v[116:119], v[144:147], v[186:189], v[116:119]
	v_mfma_f32_16x16x32_bf16 v[112:115], v[152:155], v[186:189], v[112:115]
	v_mfma_f32_16x16x32_bf16 v[100:103], v[144:147], v[194:197], v[100:103]
	v_mfma_f32_16x16x32_bf16 v[96:99], v[152:155], v[194:197], v[96:99]
	v_mfma_f32_16x16x32_bf16 v[84:87], v[144:147], v[202:205], v[84:87]
	v_mfma_f32_16x16x32_bf16 v[80:83], v[152:155], v[202:205], v[80:83]
	v_mfma_f32_16x16x32_bf16 v[132:135], v[148:151], v[164:167], v[132:135]
	v_mfma_f32_16x16x32_bf16 v[128:131], v[156:159], v[164:167], v[128:131]
	v_mfma_f32_16x16x32_bf16 v[116:119], v[148:151], v[190:193], v[116:119]
	v_mfma_f32_16x16x32_bf16 v[112:115], v[156:159], v[190:193], v[112:115]
	v_mfma_f32_16x16x32_bf16 v[100:103], v[148:151], v[198:201], v[100:103]
	v_mfma_f32_16x16x32_bf16 v[96:99], v[156:159], v[198:201], v[96:99]
	v_mfma_f32_16x16x32_bf16 v[84:87], v[148:151], v[214:217], v[84:87]
	v_mfma_f32_16x16x32_bf16 v[80:83], v[156:159], v[214:217], v[80:83]
	s_setprio 0
	s_barrier
; #define PG8_STAGE(bufoff, gbase, voff) do { _Pragma("unroll") for (int _i = 0; _i < 2; ++_i) \
;         __builtin_amdgcn_global_load_lds((const unsigned*)((const char*)(gbase) + (voff)[_i]), (LAS unsigned*)(lds + (bufoff) + ldsw + _i * 8192), 16, 0, 0); } while (0)
; #define PG8_LDA(dst, b, h) do { _Pragma("unroll") for (int m = 0; m < 4; ++m) _Pragma("unroll") for (int k = 0; k < 2; ++k) dst[m][k] = *(const LAS bf16x8*)(lds + PG8_SA(b, h) + aoff + m * 2048 + k * 1024); } while (0)
; #define PG8_MMA(ai, bj, At, Bt) do { __builtin_amdgcn_s_setprio(1); _Pragma("unroll") for (int m = 0; m < 4; ++m) _Pragma("unroll") for (int n = 0; n < 2; ++n) _Pragma("unroll") for (int k = 0; k < 2; ++k) \
;         acc[ai][bj][m][n] = __builtin_amdgcn_mfma_f32_16x16x32_bf16(Bt[n][k], At[m][k], acc[ai][bj][m][n], 0, 0, 0); __builtin_amdgcn_s_setprio(0); } while (0)
; #define PG8_WAIT_V(n) asm volatile("s_waitcnt vmcnt(" #n ")" ::: "memory")
; #define PG8_WAIT_L(n) asm volatile("s_waitcnt lgkmcnt(" #n ")" ::: "memory")
; #define PG8_BAR __builtin_amdgcn_s_barrier()
; #define PG8_SCHED __builtin_amdgcn_sched_barrier(0)
; template <class Epi>
; __device__ __forceinline__ void gemm_phase(LAS unsigned char* lds, const Gemm g, const StaticOrder& S, const Epi& E) {
;     ...
;             PG8_LDA(At, 1, 1); PG8_STAGE(PG8_SB(1, 0), b3, voffB); PG8_STAGE(PG8_SB(1, 1), b3 + hstepB, voffB); PG8_STAGE(PG8_SA(1, 0), a3, voffA);
;             PG8_WAIT_V(8); PG8_WAIT_L(0); PG8_BAR; PG8_MMA(1, 0, At, B0); PG8_MMA(1, 1, At, B1); PG8_BAR; PG8_SCHED;
;         }
;         if (wr == 0) PG8_BAR;
	s_add_i32 s64, s86, s68
	v_lshl_add_u64 v[218:219], v[218:219], 0, s[18:19]
	s_mov_b32 m0, s64
	ds_read_b128 v[160:163], v210 offset:49152
	ds_read_b128 v[164:167], v210 offset:50176
	ds_read_b128 v[186:189], v210 offset:51200
	ds_read_b128 v[190:193], v210 offset:52224
	ds_read_b128 v[194:197], v210 offset:53248
	ds_read_b128 v[198:201], v210 offset:54272
	ds_read_b128 v[202:205], v210 offset:55296
	ds_read_b128 v[214:217], v210 offset:56320
	global_load_lds_dwordx4 v[218:219], off
	s_add_i32 m0, s64, 0x2000
	s_add_u32 s62, s62, 0x40080
	v_lshl_add_u64 v[218:219], v[220:221], 0, s[18:19]
	s_addc_u32 s63, s63, 0
	s_add_i32 s64, s87, s68
	global_load_lds_dwordx4 v[218:219], off
	v_lshl_add_u64 v[218:219], s[62:63], 0, v[170:171]
	s_mov_b32 m0, s64
	s_nop 0
	global_load_lds_dwordx4 v[218:219], off
	v_lshl_add_u64 v[218:219], s[62:63], 0, v[174:175]
	s_add_i32 m0, s64, 0x2000
	s_nop 0
	global_load_lds_dwordx4 v[218:219], off
	v_lshl_add_u64 v[218:219], v[222:223], 0, s[18:19]
	s_mov_b32 m0, s76
	s_nop 0
	global_load_lds_dwordx4 v[218:219], off
	v_lshl_add_u64 v[218:219], v[226:227], 0, s[18:19]
	s_mov_b32 m0, s77
	s_nop 0
	global_load_lds_dwordx4 v[218:219], off
	s_waitcnt vmcnt(8)
	s_waitcnt lgkmcnt(0)
	s_barrier
	s_setprio 1
	s_waitcnt lgkmcnt(0)
	v_mfma_f32_16x16x32_bf16 v[76:79], v[56:59], v[160:163], v[76:79]
	v_mfma_f32_16x16x32_bf16 v[72:75], v[64:67], v[160:163], v[72:75]
	v_mfma_f32_16x16x32_bf16 v[52:55], v[56:59], v[186:189], v[52:55]
	v_mfma_f32_16x16x32_bf16 v[48:51], v[64:67], v[186:189], v[48:51]
	v_mfma_f32_16x16x32_bf16 v[28:31], v[56:59], v[194:197], v[28:31]
	v_mfma_f32_16x16x32_bf16 v[24:27], v[64:67], v[194:197], v[24:27]
	v_mfma_f32_16x16x32_bf16 v[12:15], v[56:59], v[202:205], v[12:15]
	v_mfma_f32_16x16x32_bf16 v[8:11], v[64:67], v[202:205], v[8:11]
	v_mfma_f32_16x16x32_bf16 v[76:79], v[60:63], v[164:167], v[76:79]
	v_mfma_f32_16x16x32_bf16 v[72:75], v[68:71], v[164:167], v[72:75]
	v_mfma_f32_16x16x32_bf16 v[52:55], v[60:63], v[190:193], v[52:55]
	v_mfma_f32_16x16x32_bf16 v[48:51], v[68:71], v[190:193], v[48:51]
	v_mfma_f32_16x16x32_bf16 v[28:31], v[60:63], v[198:201], v[28:31]
	v_mfma_f32_16x16x32_bf16 v[24:27], v[68:71], v[198:201], v[24:27]
	v_mfma_f32_16x16x32_bf16 v[12:15], v[60:63], v[214:217], v[12:15]
	v_mfma_f32_16x16x32_bf16 v[8:11], v[68:71], v[214:217], v[8:11]
	s_setprio 0
	s_setprio 1
	v_mfma_f32_16x16x32_bf16 v[40:43], v[144:147], v[160:163], v[40:43]
	v_mfma_f32_16x16x32_bf16 v[68:71], v[148:151], v[164:167], v[40:43]
	v_mfma_f32_16x16x32_bf16 v[40:43], v[152:155], v[160:163], v[44:47]
	v_mfma_f32_16x16x32_bf16 v[36:39], v[144:147], v[186:189], v[36:39]
	v_mfma_f32_16x16x32_bf16 v[32:35], v[152:155], v[186:189], v[32:35]
	v_mfma_f32_16x16x32_bf16 v[20:23], v[144:147], v[194:197], v[20:23]
	v_mfma_f32_16x16x32_bf16 v[16:19], v[152:155], v[194:197], v[16:19]
	v_mfma_f32_16x16x32_bf16 v[4:7], v[144:147], v[202:205], v[4:7]
	v_mfma_f32_16x16x32_bf16 v[0:3], v[152:155], v[202:205], v[0:3]
	v_mfma_f32_16x16x32_bf16 v[64:67], v[156:159], v[164:167], v[40:43]
	v_mfma_f32_16x16x32_bf16 v[36:39], v[148:151], v[190:193], v[36:39]
	v_mfma_f32_16x16x32_bf16 v[32:35], v[156:159], v[190:193], v[32:35]
	v_mfma_f32_16x16x32_bf16 v[20:23], v[148:151], v[198:201], v[20:23]
	v_mfma_f32_16x16x32_bf16 v[16:19], v[156:159], v[198:201], v[16:19]
	v_mfma_f32_16x16x32_bf16 v[4:7], v[148:151], v[214:217], v[4:7]
	v_mfma_f32_16x16x32_bf16 v[0:3], v[156:159], v[214:217], v[0:3]
	s_setprio 0
	s_barrier
	s_add_i32 s85, s85, 2
	s_add_u32 s56, s56, 0x100
	s_addc_u32 s57, s57, 0
	s_add_u32 s83, s83, 0x100
	s_addc_u32 s84, s84, 0
	s_cmp_gt_u32 s85, 13
	s_cbranch_scc0 .LBB0_889
	s_cmp_eq_u64 s[4:5], 0
	s_cselect_b32 s99, 1, 0
	s_and_b64 vcc, exec, s[22:23]
	s_cbranch_vccz .LBB0_892
	s_barrier

; #define EPI_PACK8(v0, v1) (u32x4){pk2((v0)[0], (v0)[1]), pk2((v0)[2], (v0)[3]), pk2((v1)[0], (v1)[1]), pk2((v1)[2], (v1)[3])}
;     __device__ __forceinline__ void operator()(AccRef acc, const Unit& u, int wr, int wc, int fr, int fq) const {
;     ...
;             *(u32x4*)(xb + p) = EPI_PACK8(x0, x1);
;             q += EPI_SQ8(x0, x1);
;             if (bj == 1) { q += __shfl_xor(q, 16); q += __shfl_xor(q, 32); if (fq == 0) atomicAdd(ssout + row, q); q = 0.f; sc = sn_; qc = qn; }
;             xc0 = xn0; xc1 = xn1; pc = pn; }
.LBB0_894:
	v_add_u32_e32 v192, 16, v190
	v_ashrrev_i32_e32 v193, 31, v192
	v_lshlrev_b64 v[202:203], 10, v[192:193]
	v_lshl_add_u64 v[140:141], v[152:153], 1, s[24:25]
	v_lshl_add_u64 v[196:197], v[202:203], 0, v[188:189]
	v_lshlrev_b64 v[154:155], 2, v[192:193]
	v_cvt_pk_bf16_f32 v136, v164, v165
	v_cvt_pk_bf16_f32 v137, v166, v167
	v_cvt_pk_bf16_f32 v138, v160, v161
	v_cvt_pk_bf16_f32 v139, v162, v163
	s_cmp_lg_u32 s99, 0
	s_cbranch_scc1 .Lwt889_21385
	global_store_dwordx4 v[140:141], v[136:139], off
	s_branch .Lwj889_21385

; __device__ __forceinline__ float sigmoid_f(float z) { return __builtin_amdgcn_rcpf(1.f + fexp(-z)); }
; __device__ __forceinline__ float rms_r(float ss) { return __builtin_amdgcn_rsqf(ss * (1.0f / DM) + RMS_EPS); }
; #define EPI_IT_ROW(it) EPI_ROW((it) >> 2, (it) & 3)
; #define EPI_PACK8(v0, v1) (u32x4){pk2((v0)[0], (v0)[1]), pk2((v0)[2], (v0)[3]), pk2((v1)[0], (v1)[1]), pk2((v1)[2], (v1)[3])}
;     __device__ __forceinline__ void operator()(AccRef acc, const Unit& u, int wr, int wc, int fr, int fq) const {
;     ...
;             if (st + 1 < 16) { const int it1 = (st + 1) >> 1, bj1 = (st + 1) & 1; const size_t p = (size_t)EPI_IT_ROW(it1) * DM + EPI_COL(bj1);
;                 xn0 = *(const f32x4*)(x + p); xn1 = *(const f32x4*)(x + p + 4); pn = *(const u32x4*)(pp + p);
;                 if (bj1 == 0) { sn_ = ssin[EPI_IT_ROW(it1)]; qn = ppss[EPI_IT_ROW(it1)]; } }
;             const float r = rms_r(sc), rp = rms_r(qc);
;             const size_t p = (size_t)row * DM + EPI_COL(bj);
;             const f32x4 p0 = (f32x4){bflo(pc.x), bfhi(pc.x), bflo(pc.y), bfhi(pc.y)}, p1 = (f32x4){bflo(pc.z), bfhi(pc.z), bflo(pc.w), bfhi(pc.w)};
;             const f32x4 z0 = acc[ai][bj][m][0] * r, z1 = acc[ai][bj][m][1] * r;
;             f32x4 g0, g1;
; #pragma unroll
;             for (int e = 0; e < 4; ++e) { g0[e] = sigmoid_f(z0[e]); g1[e] = sigmoid_f(z1[e]); }
;             const f32x4 x0 = xc0 + g0 * (p0 * rp) * pg[bj][0], x1 = xc1 + g1 * (p1 * rp) * pg[bj][1];
;             if (xo) { __builtin_nontemporal_store(x0, (f32x4*)(xo + p)); __builtin_nontemporal_store(x1, (f32x4*)(xo + p + 4)); }
;             *(u32x4*)(xb + p) = EPI_PACK8(x0, x1);
;             q += EPI_SQ8(x0, x1);
;             if (bj == 1) { q += __shfl_xor(q, 16); q += __shfl_xor(q, 32); if (fq == 0) atomicAdd(ssout + row, q); q = 0.f; sc = sn_; qc = qn; }
.Lwj889_21385:
	v_lshl_add_u64 v[198:199], v[196:197], 2, s[48:49]
	v_lshl_add_u64 v[152:153], v[196:197], 1, s[40:41]
	v_lshl_add_u64 v[214:215], s[12:13], 0, v[154:155]
	global_load_dwordx4 v[136:139], v[198:199], off offset:16
	global_load_dwordx4 v[140:143], v[198:199], off
	v_lshl_add_u64 v[218:219], s[14:15], 0, v[154:155]
	global_load_dwordx4 v[152:155], v[152:153], off
	s_nop 0
	global_load_dword v215, v[214:215], off
	s_nop 0
	global_load_dword v214, v[218:219], off
	v_mul_f32_e32 v132, v132, v216
	v_mul_f32_e32 v128, v128, v216
	v_mul_f32_e32 v132, 0xbfb8aa3b, v132
	v_mul_f32_e32 v128, 0xbfb8aa3b, v128
	v_exp_f32_e32 v132, v132
	v_exp_f32_e32 v217, v128
	v_mul_f32_e32 v133, v133, v216
	v_mul_f32_e32 v129, v129, v216
	v_mul_f32_e32 v133, 0xbfb8aa3b, v133
	v_mul_f32_e32 v129, 0xbfb8aa3b, v129
	v_add_f32_e32 v128, 1.0, v132
	v_add_f32_e32 v132, 1.0, v217
	v_exp_f32_e32 v133, v133
	v_exp_f32_e32 v217, v129
	v_mul_f32_e32 v134, v134, v216
	v_mul_f32_e32 v135, v135, v216
	v_mul_f32_e32 v134, 0xbfb8aa3b, v134
	v_mul_f32_e32 v135, 0xbfb8aa3b, v135
	v_exp_f32_e32 v134, v134
	v_mul_f32_e32 v130, v130, v216
	v_exp_f32_e32 v135, v135
	v_mul_f32_e32 v131, v131, v216
	v_mul_f32_e32 v130, 0xbfb8aa3b, v130
	v_mul_f32_e32 v131, 0xbfb8aa3b, v131
	v_add_f32_e32 v129, 1.0, v133
	v_add_f32_e32 v133, 1.0, v217
	v_exp_f32_e32 v217, v130
	v_exp_f32_e32 v216, v131
	v_add_f32_e32 v130, 1.0, v134
	v_add_f32_e32 v131, 1.0, v135
	v_rcp_f32_e32 v128, v128
	v_rcp_f32_e32 v129, v129
	v_rcp_f32_e32 v130, v130
	v_rcp_f32_e32 v131, v131
	v_add_f32_e32 v134, 1.0, v217
	v_add_f32_e32 v135, 1.0, v216
	v_mov_b32_e32 v205, v204
	v_lshlrev_b32_e32 v218, 16, v156
	v_and_b32_e32 v219, 0xffff0000, v156
	v_lshlrev_b32_e32 v156, 16, v157
	v_and_b32_e32 v157, 0xffff0000, v157
	v_rcp_f32_e32 v132, v132
	v_rcp_f32_e32 v133, v133
	v_rcp_f32_e32 v134, v134
	v_rcp_f32_e32 v135, v135
	v_mov_b32_e32 v216, v204
	v_mov_b32_e32 v217, v204
	v_pk_mul_f32 v[156:157], v[216:217], v[156:157]
	v_pk_mul_f32 v[218:219], v[204:205], v[218:219]
	v_lshlrev_b32_e32 v220, 16, v158
	v_and_b32_e32 v221, 0xffff0000, v158
	v_lshlrev_b32_e32 v158, 16, v159
	v_and_b32_e32 v159, 0xffff0000, v159
	v_pk_mul_f32 v[128:129], v[218:219], v[128:129]
	v_pk_mul_f32 v[130:131], v[156:157], v[130:131]
	v_pk_fma_f32 v[128:129], v[44:45], v[128:129], v[148:149]
	v_pk_fma_f32 v[130:131], v[46:47], v[130:131], v[150:151]
	v_pk_mul_f32 v[148:149], v[216:217], v[158:159]
	v_pk_mul_f32 v[150:151], v[204:205], v[220:221]
	v_pk_mul_f32 v[134:135], v[148:149], v[134:135]
	v_pk_mul_f32 v[132:133], v[150:151], v[132:133]
	v_pk_fma_f32 v[134:135], v[42:43], v[134:135], v[146:147]
	s_and_b64 vcc, exec, s[6:7]
	v_pk_fma_f32 v[132:133], v[40:41], v[132:133], v[144:145]
	s_cbranch_vccnz .LBB0_896
	global_store_dwordx4 v[200:201], v[128:131], off nt
	global_store_dwordx4 v[200:201], v[132:135], off offset:16 nt
.LBB0_896:
	v_mul_f32_e32 v144, v165, v165
	v_mul_f32_e32 v145, v167, v167
	v_fmac_f32_e32 v144, v164, v164
	v_fmac_f32_e32 v145, v166, v166
	v_add_f32_e32 v144, v144, v145
	v_mul_f32_e32 v145, v161, v161
	v_fmac_f32_e32 v145, v160, v160
	v_mul_f32_e32 v146, v129, v129
	v_mul_f32_e32 v147, v131, v131
	v_add_f32_e32 v144, v145, v144
	v_mul_f32_e32 v145, v163, v163
	v_fmac_f32_e32 v146, v128, v128
	v_fmac_f32_e32 v147, v130, v130
	v_fmac_f32_e32 v145, v162, v162
	v_add_f32_e32 v146, v146, v147
	v_mul_f32_e32 v147, v133, v133
	v_add_f32_e32 v144, v145, v144
	v_mul_f32_e32 v145, v135, v135
	v_fmac_f32_e32 v147, v132, v132
	v_fmac_f32_e32 v145, v134, v134
	v_add_f32_e32 v146, v147, v146
	v_add_f32_e32 v145, v145, v146
	v_add_f32_e32 v146, v144, v145
	v_and_b32_e32 v145, 64, v212
	v_xor_b32_e32 v144, 16, v212
	v_add_u32_e32 v147, 64, v145
	v_cmp_lt_i32_e32 vcc, v144, v147
	v_cmp_eq_u32_e64 s[8:9], 0, v213
	v_cvt_pk_bf16_f32 v145, v130, v131
	v_lshl_add_u64 v[130:131], v[194:195], 1, s[24:25]
	v_cndmask_b32_e32 v144, v212, v144, vcc
	v_lshlrev_b32_e32 v166, 2, v144
	ds_bpermute_b32 v148, v166, v146
	v_cvt_pk_bf16_f32 v144, v128, v129
	v_xor_b32_e32 v129, 32, v212
	v_cmp_lt_i32_e32 vcc, v129, v147
	v_cvt_pk_bf16_f32 v147, v134, v135
	s_waitcnt lgkmcnt(0)
	v_add_f32_e32 v128, v146, v148
	v_cvt_pk_bf16_f32 v146, v132, v133
	s_cmp_lg_u32 s99, 0
	s_cbranch_scc1 .Lwt889_21514
	global_store_dwordx4 v[130:131], v[144:147], off
	s_branch .Lwj889_21514
.Lwt889_21514:
	global_store_dwordx4 v[130:131], v[144:147], off sc1
.Lwj889_21514:
	v_cndmask_b32_e32 v129, v212, v129, vcc
	v_lshlrev_b32_e32 v167, 2, v129
	ds_bpermute_b32 v129, v167, v128
	s_and_saveexec_b64 s[56:57], s[8:9]
	s_cbranch_execz .LBB0_898
	v_lshl_add_u64 v[130:131], v[190:191], 2, s[16:17]
	s_waitcnt lgkmcnt(0)
	v_add_f32_e32 v128, v128, v129
	global_atomic_add_f32 v[130:131], v128, off

; #define EPI_PACK8(v0, v1) (u32x4){pk2((v0)[0], (v0)[1]), pk2((v0)[2], (v0)[3]), pk2((v1)[0], (v1)[1]), pk2((v1)[2], (v1)[3])}
;     __device__ __forceinline__ void operator()(AccRef acc, const Unit& u, int wr, int wc, int fr, int fq) const {
;     ...
;             *(u32x4*)(xb + p) = EPI_PACK8(x0, x1);
;             q += EPI_SQ8(x0, x1);
;             if (bj == 1) { q += __shfl_xor(q, 16); q += __shfl_xor(q, 32); if (fq == 0) atomicAdd(ssout + row, q); q = 0.f; sc = sn_; qc = qn; }
;             xc0 = xn0; xc1 = xn1; pc = pn; }
.LBB0_900:
	v_add_u32_e32 v152, 32, v190
	v_ashrrev_i32_e32 v153, 31, v152
	v_lshlrev_b64 v[162:163], 10, v[152:153]
	v_lshl_add_u64 v[124:125], v[196:197], 1, s[24:25]
	v_lshl_add_u64 v[154:155], v[162:163], 0, v[188:189]
	v_lshlrev_b64 v[138:139], 2, v[152:153]
	v_cvt_pk_bf16_f32 v120, v140, v141
	v_cvt_pk_bf16_f32 v121, v142, v143
	v_cvt_pk_bf16_f32 v122, v144, v145
	v_cvt_pk_bf16_f32 v123, v146, v147
	s_cmp_lg_u32 s99, 0
	s_cbranch_scc1 .Lwt889_21624
	global_store_dwordx4 v[124:125], v[120:123], off
	s_branch .Lwj889_21624

; __device__ __forceinline__ float sigmoid_f(float z) { return __builtin_amdgcn_rcpf(1.f + fexp(-z)); }
; __device__ __forceinline__ float rms_r(float ss) { return __builtin_amdgcn_rsqf(ss * (1.0f / DM) + RMS_EPS); }
; #define EPI_IT_ROW(it) EPI_ROW((it) >> 2, (it) & 3)
; #define EPI_PACK8(v0, v1) (u32x4){pk2((v0)[0], (v0)[1]), pk2((v0)[2], (v0)[3]), pk2((v1)[0], (v1)[1]), pk2((v1)[2], (v1)[3])}
;     __device__ __forceinline__ void operator()(AccRef acc, const Unit& u, int wr, int wc, int fr, int fq) const {
;     ...
;             if (st + 1 < 16) { const int it1 = (st + 1) >> 1, bj1 = (st + 1) & 1; const size_t p = (size_t)EPI_IT_ROW(it1) * DM + EPI_COL(bj1);
;                 xn0 = *(const f32x4*)(x + p); xn1 = *(const f32x4*)(x + p + 4); pn = *(const u32x4*)(pp + p);
;                 if (bj1 == 0) { sn_ = ssin[EPI_IT_ROW(it1)]; qn = ppss[EPI_IT_ROW(it1)]; } }
;             const float r = rms_r(sc), rp = rms_r(qc);
;             const size_t p = (size_t)row * DM + EPI_COL(bj);
;             const f32x4 p0 = (f32x4){bflo(pc.x), bfhi(pc.x), bflo(pc.y), bfhi(pc.y)}, p1 = (f32x4){bflo(pc.z), bfhi(pc.z), bflo(pc.w), bfhi(pc.w)};
;             const f32x4 z0 = acc[ai][bj][m][0] * r, z1 = acc[ai][bj][m][1] * r;
;             f32x4 g0, g1;
; #pragma unroll
;             for (int e = 0; e < 4; ++e) { g0[e] = sigmoid_f(z0[e]); g1[e] = sigmoid_f(z1[e]); }
;             const f32x4 x0 = xc0 + g0 * (p0 * rp) * pg[bj][0], x1 = xc1 + g1 * (p1 * rp) * pg[bj][1];
;             if (xo) { __builtin_nontemporal_store(x0, (f32x4*)(xo + p)); __builtin_nontemporal_store(x1, (f32x4*)(xo + p + 4)); }
;             *(u32x4*)(xb + p) = EPI_PACK8(x0, x1);
;             q += EPI_SQ8(x0, x1);
;             if (bj == 1) { q += __shfl_xor(q, 16); q += __shfl_xor(q, 32); if (fq == 0) atomicAdd(ssout + row, q); q = 0.f; sc = sn_; qc = qn; }
.Lwj889_21624:
	v_lshl_add_u64 v[158:159], v[154:155], 2, s[48:49]
	v_lshl_add_u64 v[136:137], v[154:155], 1, s[40:41]
	v_lshl_add_u64 v[194:195], s[12:13], 0, v[138:139]
	global_load_dwordx4 v[120:123], v[158:159], off offset:16
	global_load_dwordx4 v[124:127], v[158:159], off
	v_lshl_add_u64 v[196:197], s[14:15], 0, v[138:139]
	global_load_dwordx4 v[136:139], v[136:137], off
	s_nop 0
	global_load_dword v195, v[194:195], off
	s_nop 0
	global_load_dword v194, v[196:197], off
	v_mul_f32_e32 v116, v116, v191
	v_mul_f32_e32 v112, v112, v191
	v_mul_f32_e32 v116, 0xbfb8aa3b, v116
	v_mul_f32_e32 v112, 0xbfb8aa3b, v112
	v_exp_f32_e32 v116, v116
	v_exp_f32_e32 v200, v112
	v_mul_f32_e32 v117, v117, v191
	v_mul_f32_e32 v113, v113, v191
	v_mul_f32_e32 v117, 0xbfb8aa3b, v117
	v_mul_f32_e32 v113, 0xbfb8aa3b, v113
	v_add_f32_e32 v112, 1.0, v116
	v_add_f32_e32 v116, 1.0, v200
	v_exp_f32_e32 v117, v117
	v_exp_f32_e32 v200, v113
	v_mul_f32_e32 v118, v118, v191
	v_mul_f32_e32 v119, v119, v191
	v_mul_f32_e32 v118, 0xbfb8aa3b, v118
	v_mul_f32_e32 v119, 0xbfb8aa3b, v119
	v_exp_f32_e32 v118, v118
	v_mul_f32_e32 v114, v114, v191
	v_exp_f32_e32 v119, v119
	v_mul_f32_e32 v115, v115, v191
	v_mul_f32_e32 v114, 0xbfb8aa3b, v114
	v_mul_f32_e32 v115, 0xbfb8aa3b, v115
	v_add_f32_e32 v113, 1.0, v117
	v_add_f32_e32 v117, 1.0, v200
	v_exp_f32_e32 v200, v114
	v_exp_f32_e32 v191, v115
	v_add_f32_e32 v114, 1.0, v118
	v_add_f32_e32 v115, 1.0, v119
	v_rcp_f32_e32 v112, v112
	v_rcp_f32_e32 v113, v113
	v_rcp_f32_e32 v114, v114
	v_rcp_f32_e32 v115, v115
	v_add_f32_e32 v118, 1.0, v200
	v_add_f32_e32 v119, 1.0, v191
	v_mov_b32_e32 v165, v164
	s_waitcnt vmcnt(6)
	v_lshlrev_b32_e32 v196, 16, v148
	v_and_b32_e32 v197, 0xffff0000, v148
	v_lshlrev_b32_e32 v148, 16, v149
	v_and_b32_e32 v149, 0xffff0000, v149
	v_rcp_f32_e32 v116, v116
	v_rcp_f32_e32 v117, v117
	v_rcp_f32_e32 v118, v118
	v_rcp_f32_e32 v119, v119
	v_mov_b32_e32 v200, v164
	v_mov_b32_e32 v201, v164
	v_pk_mul_f32 v[148:149], v[200:201], v[148:149]
	v_pk_mul_f32 v[196:197], v[164:165], v[196:197]
	v_lshlrev_b32_e32 v198, 16, v150
	v_and_b32_e32 v199, 0xffff0000, v150
	v_lshlrev_b32_e32 v150, 16, v151
	v_and_b32_e32 v151, 0xffff0000, v151
	v_pk_mul_f32 v[112:113], v[112:113], v[196:197]
	v_pk_mul_f32 v[114:115], v[114:115], v[148:149]
	v_pk_fma_f32 v[112:113], v[44:45], v[112:113], v[132:133]
	v_pk_fma_f32 v[114:115], v[46:47], v[114:115], v[134:135]
	v_pk_mul_f32 v[132:133], v[200:201], v[150:151]
	v_pk_mul_f32 v[134:135], v[164:165], v[198:199]
	v_pk_mul_f32 v[118:119], v[118:119], v[132:133]
	v_pk_mul_f32 v[116:117], v[116:117], v[134:135]
	v_pk_fma_f32 v[118:119], v[42:43], v[118:119], v[130:131]
	s_and_b64 vcc, exec, s[6:7]
	v_pk_fma_f32 v[116:117], v[40:41], v[116:117], v[128:129]
	s_cbranch_vccnz .LBB0_902
	global_store_dwordx4 v[160:161], v[112:115], off nt
	global_store_dwordx4 v[160:161], v[116:119], off offset:16 nt
.LBB0_902:
	v_mul_f32_e32 v128, v141, v141
	v_mul_f32_e32 v129, v143, v143
	v_fmac_f32_e32 v128, v140, v140
	v_fmac_f32_e32 v129, v142, v142
	v_add_f32_e32 v128, v128, v129
	v_mul_f32_e32 v129, v145, v145
	v_fmac_f32_e32 v129, v144, v144
	v_mul_f32_e32 v130, v113, v113
	v_mul_f32_e32 v131, v115, v115
	v_add_f32_e32 v128, v129, v128
	v_mul_f32_e32 v129, v147, v147
	v_fmac_f32_e32 v130, v112, v112
	v_fmac_f32_e32 v131, v114, v114
	v_fmac_f32_e32 v129, v146, v146
	v_add_f32_e32 v130, v130, v131
	v_mul_f32_e32 v131, v117, v117
	v_add_f32_e32 v128, v129, v128
	v_mul_f32_e32 v129, v119, v119
	v_fmac_f32_e32 v131, v116, v116
	v_fmac_f32_e32 v129, v118, v118
	v_add_f32_e32 v130, v131, v130
	v_add_f32_e32 v129, v129, v130
	v_add_f32_e32 v130, v128, v129
	ds_bpermute_b32 v131, v166, v130
	v_cvt_pk_bf16_f32 v128, v112, v113
	v_cvt_pk_bf16_f32 v129, v114, v115
	v_lshl_add_u64 v[114:115], v[156:157], 1, s[24:25]
	s_waitcnt lgkmcnt(0)
	v_add_f32_e32 v112, v130, v131
	ds_bpermute_b32 v113, v167, v112
	v_cvt_pk_bf16_f32 v130, v116, v117
	v_cvt_pk_bf16_f32 v131, v118, v119
	s_cmp_lg_u32 s99, 0
	s_cbranch_scc1 .Lwt889_21746
	global_store_dwordx4 v[114:115], v[128:131], off
	s_branch .Lwj889_21746
.Lwt889_21746:
	global_store_dwordx4 v[114:115], v[128:131], off sc1
.Lwj889_21746:
	s_and_saveexec_b64 s[56:57], s[8:9]
	s_cbranch_execz .LBB0_904
	v_lshl_add_u64 v[114:115], v[192:193], 2, s[16:17]
	s_waitcnt lgkmcnt(0)
	v_add_f32_e32 v112, v112, v113
	global_atomic_add_f32 v[114:115], v112, off

; #define EPI_PACK8(v0, v1) (u32x4){pk2((v0)[0], (v0)[1]), pk2((v0)[2], (v0)[3]), pk2((v1)[0], (v1)[1]), pk2((v1)[2], (v1)[3])}
;     __device__ __forceinline__ void operator()(AccRef acc, const Unit& u, int wr, int wc, int fr, int fq) const {
;     ...
;             *(u32x4*)(xb + p) = EPI_PACK8(x0, x1);
;             q += EPI_SQ8(x0, x1);
;             if (bj == 1) { q += __shfl_xor(q, 16); q += __shfl_xor(q, 32); if (fq == 0) atomicAdd(ssout + row, q); q = 0.f; sc = sn_; qc = qn; }
;             xc0 = xn0; xc1 = xn1; pc = pn; }
.LBB0_906:
	v_add_u32_e32 v136, 48, v190
	v_ashrrev_i32_e32 v137, 31, v136
	v_lshlrev_b64 v[146:147], 10, v[136:137]
	v_lshl_add_u64 v[108:109], v[154:155], 1, s[24:25]
	v_lshl_add_u64 v[138:139], v[146:147], 0, v[188:189]
	v_lshlrev_b64 v[122:123], 2, v[136:137]
	v_cvt_pk_bf16_f32 v104, v124, v125
	v_cvt_pk_bf16_f32 v105, v126, v127
	v_cvt_pk_bf16_f32 v106, v128, v129
	v_cvt_pk_bf16_f32 v107, v130, v131
	s_cmp_lg_u32 s99, 0
	s_cbranch_scc1 .Lwt889_21853
	global_store_dwordx4 v[108:109], v[104:107], off
	s_branch .Lwj889_21853

; __device__ __forceinline__ float sigmoid_f(float z) { return __builtin_amdgcn_rcpf(1.f + fexp(-z)); }
; __device__ __forceinline__ float rms_r(float ss) { return __builtin_amdgcn_rsqf(ss * (1.0f / DM) + RMS_EPS); }
; #define EPI_IT_ROW(it) EPI_ROW((it) >> 2, (it) & 3)
; #define EPI_PACK8(v0, v1) (u32x4){pk2((v0)[0], (v0)[1]), pk2((v0)[2], (v0)[3]), pk2((v1)[0], (v1)[1]), pk2((v1)[2], (v1)[3])}
;     __device__ __forceinline__ void operator()(AccRef acc, const Unit& u, int wr, int wc, int fr, int fq) const {
;     ...
;             if (st + 1 < 16) { const int it1 = (st + 1) >> 1, bj1 = (st + 1) & 1; const size_t p = (size_t)EPI_IT_ROW(it1) * DM + EPI_COL(bj1);
;                 xn0 = *(const f32x4*)(x + p); xn1 = *(const f32x4*)(x + p + 4); pn = *(const u32x4*)(pp + p);
;                 if (bj1 == 0) { sn_ = ssin[EPI_IT_ROW(it1)]; qn = ppss[EPI_IT_ROW(it1)]; } }
;             const float r = rms_r(sc), rp = rms_r(qc);
;             const size_t p = (size_t)row * DM + EPI_COL(bj);
;             const f32x4 p0 = (f32x4){bflo(pc.x), bfhi(pc.x), bflo(pc.y), bfhi(pc.y)}, p1 = (f32x4){bflo(pc.z), bfhi(pc.z), bflo(pc.w), bfhi(pc.w)};
;             const f32x4 z0 = acc[ai][bj][m][0] * r, z1 = acc[ai][bj][m][1] * r;
;             f32x4 g0, g1;
; #pragma unroll
;             for (int e = 0; e < 4; ++e) { g0[e] = sigmoid_f(z0[e]); g1[e] = sigmoid_f(z1[e]); }
;             const f32x4 x0 = xc0 + g0 * (p0 * rp) * pg[bj][0], x1 = xc1 + g1 * (p1 * rp) * pg[bj][1];
;             if (xo) { __builtin_nontemporal_store(x0, (f32x4*)(xo + p)); __builtin_nontemporal_store(x1, (f32x4*)(xo + p + 4)); }
;             *(u32x4*)(xb + p) = EPI_PACK8(x0, x1);
;             q += EPI_SQ8(x0, x1);
;             if (bj == 1) { q += __shfl_xor(q, 16); q += __shfl_xor(q, 32); if (fq == 0) atomicAdd(ssout + row, q); q = 0.f; sc = sn_; qc = qn; }
.Lwj889_21853:
	v_lshl_add_u64 v[142:143], v[138:139], 2, s[48:49]
	v_lshl_add_u64 v[120:121], v[138:139], 1, s[40:41]
	v_lshl_add_u64 v[154:155], s[12:13], 0, v[122:123]
	global_load_dwordx4 v[104:107], v[142:143], off offset:16
	global_load_dwordx4 v[108:111], v[142:143], off
	v_lshl_add_u64 v[156:157], s[14:15], 0, v[122:123]
	global_load_dwordx4 v[120:123], v[120:121], off
	s_nop 0
	global_load_dword v154, v[154:155], off
	s_nop 0
	global_load_dword v151, v[156:157], off
	v_mul_f32_e32 v100, v100, v150
	v_mul_f32_e32 v96, v96, v150
	v_mul_f32_e32 v100, 0xbfb8aa3b, v100
	v_mul_f32_e32 v96, 0xbfb8aa3b, v96
	v_exp_f32_e32 v100, v100
	v_exp_f32_e32 v155, v96
	v_mul_f32_e32 v101, v101, v150
	v_mul_f32_e32 v97, v97, v150
	v_mul_f32_e32 v101, 0xbfb8aa3b, v101
	v_mul_f32_e32 v97, 0xbfb8aa3b, v97
	v_add_f32_e32 v96, 1.0, v100
	v_add_f32_e32 v100, 1.0, v155
	v_exp_f32_e32 v101, v101
	v_exp_f32_e32 v155, v97
	v_mul_f32_e32 v102, v102, v150
	v_mul_f32_e32 v103, v103, v150
	v_mul_f32_e32 v102, 0xbfb8aa3b, v102
	v_mul_f32_e32 v103, 0xbfb8aa3b, v103
	v_exp_f32_e32 v102, v102
	v_mul_f32_e32 v98, v98, v150
	v_exp_f32_e32 v103, v103
	v_mul_f32_e32 v99, v99, v150
	v_mul_f32_e32 v98, 0xbfb8aa3b, v98
	v_mul_f32_e32 v99, 0xbfb8aa3b, v99
	v_add_f32_e32 v97, 1.0, v101
	v_add_f32_e32 v101, 1.0, v155
	v_exp_f32_e32 v155, v98
	v_exp_f32_e32 v150, v99
	v_add_f32_e32 v98, 1.0, v102
	v_add_f32_e32 v99, 1.0, v103
	v_rcp_f32_e32 v96, v96
	v_rcp_f32_e32 v97, v97
	v_rcp_f32_e32 v98, v98
	v_rcp_f32_e32 v99, v99
	v_add_f32_e32 v102, 1.0, v155
	v_add_f32_e32 v103, 1.0, v150
	v_mov_b32_e32 v149, v148
	s_waitcnt vmcnt(6)
	v_lshlrev_b32_e32 v156, 16, v132
	v_and_b32_e32 v157, 0xffff0000, v132
	v_lshlrev_b32_e32 v132, 16, v133
	v_and_b32_e32 v133, 0xffff0000, v133
	v_rcp_f32_e32 v100, v100
	v_rcp_f32_e32 v101, v101
	v_rcp_f32_e32 v102, v102
	v_rcp_f32_e32 v103, v103
	v_mov_b32_e32 v160, v148
	v_mov_b32_e32 v161, v148
	v_pk_mul_f32 v[132:133], v[160:161], v[132:133]
	v_pk_mul_f32 v[156:157], v[148:149], v[156:157]
	v_lshlrev_b32_e32 v158, 16, v134
	v_and_b32_e32 v159, 0xffff0000, v134
	v_lshlrev_b32_e32 v134, 16, v135
	v_and_b32_e32 v135, 0xffff0000, v135
	v_pk_mul_f32 v[96:97], v[96:97], v[156:157]
	v_pk_mul_f32 v[98:99], v[98:99], v[132:133]
	v_pk_fma_f32 v[96:97], v[44:45], v[96:97], v[116:117]
	v_pk_fma_f32 v[98:99], v[46:47], v[98:99], v[118:119]
	v_pk_mul_f32 v[116:117], v[160:161], v[134:135]
	v_pk_mul_f32 v[118:119], v[148:149], v[158:159]
	v_pk_mul_f32 v[102:103], v[102:103], v[116:117]
	v_pk_mul_f32 v[100:101], v[100:101], v[118:119]
	v_pk_fma_f32 v[102:103], v[42:43], v[102:103], v[114:115]
	s_and_b64 vcc, exec, s[6:7]
	v_pk_fma_f32 v[100:101], v[40:41], v[100:101], v[112:113]
	s_cbranch_vccnz .LBB0_908
	global_store_dwordx4 v[144:145], v[96:99], off nt
	global_store_dwordx4 v[144:145], v[100:103], off offset:16 nt
.LBB0_908:
	v_mul_f32_e32 v112, v125, v125
	v_mul_f32_e32 v113, v127, v127
	v_fmac_f32_e32 v112, v124, v124
	v_fmac_f32_e32 v113, v126, v126
	v_add_f32_e32 v112, v112, v113
	v_mul_f32_e32 v113, v129, v129
	v_fmac_f32_e32 v113, v128, v128
	v_mul_f32_e32 v114, v97, v97
	v_mul_f32_e32 v115, v99, v99
	v_add_f32_e32 v112, v113, v112
	v_mul_f32_e32 v113, v131, v131
	v_fmac_f32_e32 v114, v96, v96
	v_fmac_f32_e32 v115, v98, v98
	v_fmac_f32_e32 v113, v130, v130
	v_add_f32_e32 v114, v114, v115
	v_mul_f32_e32 v115, v101, v101
	v_add_f32_e32 v112, v113, v112
	v_mul_f32_e32 v113, v103, v103
	v_fmac_f32_e32 v115, v100, v100
	v_fmac_f32_e32 v113, v102, v102
	v_add_f32_e32 v114, v115, v114
	v_add_f32_e32 v113, v113, v114
	v_add_f32_e32 v114, v112, v113
	ds_bpermute_b32 v115, v166, v114
	v_cvt_pk_bf16_f32 v112, v96, v97
	v_cvt_pk_bf16_f32 v113, v98, v99
	v_lshl_add_u64 v[98:99], v[140:141], 1, s[24:25]
	s_waitcnt lgkmcnt(0)
	v_add_f32_e32 v96, v114, v115
	ds_bpermute_b32 v97, v167, v96
	v_cvt_pk_bf16_f32 v114, v100, v101
	v_cvt_pk_bf16_f32 v115, v102, v103
	s_cmp_lg_u32 s99, 0
	s_cbranch_scc1 .Lwt889_21975
	global_store_dwordx4 v[98:99], v[112:115], off
	s_branch .Lwj889_21975
.Lwt889_21975:
	global_store_dwordx4 v[98:99], v[112:115], off sc1
.Lwj889_21975:
	s_and_saveexec_b64 s[56:57], s[8:9]
	s_cbranch_execz .LBB0_910
	v_lshl_add_u64 v[98:99], v[152:153], 2, s[16:17]
	s_waitcnt lgkmcnt(0)
	v_add_f32_e32 v96, v96, v97
	global_atomic_add_f32 v[98:99], v96, off

; #define EPI_PACK8(v0, v1) (u32x4){pk2((v0)[0], (v0)[1]), pk2((v0)[2], (v0)[3]), pk2((v1)[0], (v1)[1]), pk2((v1)[2], (v1)[3])}
;     __device__ __forceinline__ void operator()(AccRef acc, const Unit& u, int wr, int wc, int fr, int fq) const {
;     ...
;             *(u32x4*)(xb + p) = EPI_PACK8(x0, x1);
;             q += EPI_SQ8(x0, x1);
;             if (bj == 1) { q += __shfl_xor(q, 16); q += __shfl_xor(q, 32); if (fq == 0) atomicAdd(ssout + row, q); q = 0.f; sc = sn_; qc = qn; }
;             xc0 = xn0; xc1 = xn1; pc = pn; }
.LBB0_912:
	v_add_u32_e32 v120, 0x80, v190
	v_ashrrev_i32_e32 v121, 31, v120
	v_lshlrev_b64 v[130:131], 10, v[120:121]
	v_lshl_add_u64 v[92:93], v[138:139], 1, s[24:25]
	v_lshl_add_u64 v[122:123], v[130:131], 0, v[188:189]
	v_lshlrev_b64 v[106:107], 2, v[120:121]
	v_cvt_pk_bf16_f32 v88, v108, v109
	v_cvt_pk_bf16_f32 v89, v110, v111
	v_cvt_pk_bf16_f32 v90, v112, v113
	v_cvt_pk_bf16_f32 v91, v114, v115
	s_cmp_lg_u32 s99, 0
	s_cbranch_scc1 .Lwt889_22082
	global_store_dwordx4 v[92:93], v[88:91], off
	s_branch .Lwj889_22082

; __device__ __forceinline__ float sigmoid_f(float z) { return __builtin_amdgcn_rcpf(1.f + fexp(-z)); }
; __device__ __forceinline__ float rms_r(float ss) { return __builtin_amdgcn_rsqf(ss * (1.0f / DM) + RMS_EPS); }
; #define EPI_IT_ROW(it) EPI_ROW((it) >> 2, (it) & 3)
; #define EPI_PACK8(v0, v1) (u32x4){pk2((v0)[0], (v0)[1]), pk2((v0)[2], (v0)[3]), pk2((v1)[0], (v1)[1]), pk2((v1)[2], (v1)[3])}
;     __device__ __forceinline__ void operator()(AccRef acc, const Unit& u, int wr, int wc, int fr, int fq) const {
;     ...
;             if (st + 1 < 16) { const int it1 = (st + 1) >> 1, bj1 = (st + 1) & 1; const size_t p = (size_t)EPI_IT_ROW(it1) * DM + EPI_COL(bj1);
;                 xn0 = *(const f32x4*)(x + p); xn1 = *(const f32x4*)(x + p + 4); pn = *(const u32x4*)(pp + p);
;                 if (bj1 == 0) { sn_ = ssin[EPI_IT_ROW(it1)]; qn = ppss[EPI_IT_ROW(it1)]; } }
;             const float r = rms_r(sc), rp = rms_r(qc);
;             const size_t p = (size_t)row * DM + EPI_COL(bj);
;             const f32x4 p0 = (f32x4){bflo(pc.x), bfhi(pc.x), bflo(pc.y), bfhi(pc.y)}, p1 = (f32x4){bflo(pc.z), bfhi(pc.z), bflo(pc.w), bfhi(pc.w)};
;             const f32x4 z0 = acc[ai][bj][m][0] * r, z1 = acc[ai][bj][m][1] * r;
;             f32x4 g0, g1;
; #pragma unroll
;             for (int e = 0; e < 4; ++e) { g0[e] = sigmoid_f(z0[e]); g1[e] = sigmoid_f(z1[e]); }
;             const f32x4 x0 = xc0 + g0 * (p0 * rp) * pg[bj][0], x1 = xc1 + g1 * (p1 * rp) * pg[bj][1];
;             if (xo) { __builtin_nontemporal_store(x0, (f32x4*)(xo + p)); __builtin_nontemporal_store(x1, (f32x4*)(xo + p + 4)); }
;             *(u32x4*)(xb + p) = EPI_PACK8(x0, x1);
;             q += EPI_SQ8(x0, x1);
;             if (bj == 1) { q += __shfl_xor(q, 16); q += __shfl_xor(q, 32); if (fq == 0) atomicAdd(ssout + row, q); q = 0.f; sc = sn_; qc = qn; }
.Lwj889_22082:
	v_lshl_add_u64 v[126:127], v[122:123], 2, s[48:49]
	v_lshl_add_u64 v[104:105], v[122:123], 1, s[40:41]
	v_lshl_add_u64 v[138:139], s[12:13], 0, v[106:107]
	global_load_dwordx4 v[88:91], v[126:127], off offset:16
	global_load_dwordx4 v[92:95], v[126:127], off
	v_lshl_add_u64 v[140:141], s[14:15], 0, v[106:107]
	global_load_dwordx4 v[104:107], v[104:105], off
	s_nop 0
	global_load_dword v138, v[138:139], off
	s_nop 0
	global_load_dword v135, v[140:141], off
	v_mul_f32_e32 v84, v84, v134
	v_mul_f32_e32 v80, v80, v134
	v_mul_f32_e32 v84, 0xbfb8aa3b, v84
	v_mul_f32_e32 v80, 0xbfb8aa3b, v80
	v_exp_f32_e32 v84, v84
	v_exp_f32_e32 v139, v80
	v_mul_f32_e32 v85, v85, v134
	v_mul_f32_e32 v81, v81, v134
	v_mul_f32_e32 v85, 0xbfb8aa3b, v85
	v_mul_f32_e32 v81, 0xbfb8aa3b, v81
	v_add_f32_e32 v80, 1.0, v84
	v_add_f32_e32 v84, 1.0, v139
	v_exp_f32_e32 v85, v85
	v_exp_f32_e32 v139, v81
	v_mul_f32_e32 v86, v86, v134
	v_mul_f32_e32 v87, v87, v134
	v_mul_f32_e32 v86, 0xbfb8aa3b, v86
	v_mul_f32_e32 v87, 0xbfb8aa3b, v87
	v_exp_f32_e32 v86, v86
	v_mul_f32_e32 v82, v82, v134
	v_exp_f32_e32 v87, v87
	v_mul_f32_e32 v83, v83, v134
	v_mul_f32_e32 v82, 0xbfb8aa3b, v82
	v_mul_f32_e32 v83, 0xbfb8aa3b, v83
	v_add_f32_e32 v81, 1.0, v85
	v_add_f32_e32 v85, 1.0, v139
	v_exp_f32_e32 v139, v82
	v_exp_f32_e32 v134, v83
	v_add_f32_e32 v82, 1.0, v86
	v_add_f32_e32 v83, 1.0, v87
	v_rcp_f32_e32 v80, v80
	v_rcp_f32_e32 v81, v81
	v_rcp_f32_e32 v82, v82
	v_rcp_f32_e32 v83, v83
	v_add_f32_e32 v86, 1.0, v139
	v_add_f32_e32 v87, 1.0, v134
	v_mov_b32_e32 v133, v132
	s_waitcnt vmcnt(6)
	v_lshlrev_b32_e32 v140, 16, v116
	v_and_b32_e32 v141, 0xffff0000, v116
	v_lshlrev_b32_e32 v116, 16, v117
	v_and_b32_e32 v117, 0xffff0000, v117
	v_rcp_f32_e32 v84, v84
	v_rcp_f32_e32 v85, v85
	v_rcp_f32_e32 v86, v86
	v_rcp_f32_e32 v87, v87
	v_mov_b32_e32 v144, v132
	v_mov_b32_e32 v145, v132
	v_pk_mul_f32 v[116:117], v[144:145], v[116:117]
	v_pk_mul_f32 v[140:141], v[132:133], v[140:141]
	v_lshlrev_b32_e32 v142, 16, v118
	v_and_b32_e32 v143, 0xffff0000, v118
	v_lshlrev_b32_e32 v118, 16, v119
	v_and_b32_e32 v119, 0xffff0000, v119
	v_pk_mul_f32 v[80:81], v[80:81], v[140:141]
	v_pk_mul_f32 v[82:83], v[82:83], v[116:117]
	v_pk_fma_f32 v[80:81], v[44:45], v[80:81], v[100:101]
	v_pk_fma_f32 v[82:83], v[46:47], v[82:83], v[102:103]
	v_pk_mul_f32 v[100:101], v[144:145], v[118:119]
	v_pk_mul_f32 v[102:103], v[132:133], v[142:143]
	v_pk_mul_f32 v[86:87], v[86:87], v[100:101]
	v_pk_mul_f32 v[84:85], v[84:85], v[102:103]
	v_pk_fma_f32 v[86:87], v[42:43], v[86:87], v[98:99]
	s_and_b64 vcc, exec, s[6:7]
	v_pk_fma_f32 v[84:85], v[40:41], v[84:85], v[96:97]
	s_cbranch_vccnz .LBB0_914
	global_store_dwordx4 v[128:129], v[80:83], off nt
	global_store_dwordx4 v[128:129], v[84:87], off offset:16 nt
.LBB0_914:
	v_mul_f32_e32 v96, v109, v109
	v_mul_f32_e32 v97, v111, v111
	v_fmac_f32_e32 v96, v108, v108
	v_fmac_f32_e32 v97, v110, v110
	v_add_f32_e32 v96, v96, v97
	v_mul_f32_e32 v97, v113, v113
	v_fmac_f32_e32 v97, v112, v112
	v_mul_f32_e32 v98, v81, v81
	v_mul_f32_e32 v99, v83, v83
	v_add_f32_e32 v96, v97, v96
	v_mul_f32_e32 v97, v115, v115
	v_fmac_f32_e32 v98, v80, v80
	v_fmac_f32_e32 v99, v82, v82
	v_fmac_f32_e32 v97, v114, v114
	v_add_f32_e32 v98, v98, v99
	v_mul_f32_e32 v99, v85, v85
	v_add_f32_e32 v96, v97, v96
	v_mul_f32_e32 v97, v87, v87
	v_fmac_f32_e32 v99, v84, v84
	v_fmac_f32_e32 v97, v86, v86
	v_add_f32_e32 v98, v99, v98
	v_add_f32_e32 v97, v97, v98
	v_add_f32_e32 v98, v96, v97
	ds_bpermute_b32 v99, v166, v98
	v_cvt_pk_bf16_f32 v96, v80, v81
	v_cvt_pk_bf16_f32 v97, v82, v83
	v_lshl_add_u64 v[82:83], v[124:125], 1, s[24:25]
	s_waitcnt lgkmcnt(0)
	v_add_f32_e32 v80, v98, v99
	ds_bpermute_b32 v81, v167, v80
	v_cvt_pk_bf16_f32 v98, v84, v85
	v_cvt_pk_bf16_f32 v99, v86, v87
	s_cmp_lg_u32 s99, 0
	s_cbranch_scc1 .Lwt889_22204
	global_store_dwordx4 v[82:83], v[96:99], off
	s_branch .Lwj889_22204
.Lwt889_22204:
	global_store_dwordx4 v[82:83], v[96:99], off sc1
.Lwj889_22204:
	s_and_saveexec_b64 s[56:57], s[8:9]
	s_cbranch_execz .LBB0_916
	v_lshl_add_u64 v[82:83], v[136:137], 2, s[16:17]
	s_waitcnt lgkmcnt(0)
	v_add_f32_e32 v80, v80, v81
	global_atomic_add_f32 v[82:83], v80, off

; #define EPI_PACK8(v0, v1) (u32x4){pk2((v0)[0], (v0)[1]), pk2((v0)[2], (v0)[3]), pk2((v1)[0], (v1)[1]), pk2((v1)[2], (v1)[3])}
;     __device__ __forceinline__ void operator()(AccRef acc, const Unit& u, int wr, int wc, int fr, int fq) const {
;     ...
;             *(u32x4*)(xb + p) = EPI_PACK8(x0, x1);
;             q += EPI_SQ8(x0, x1);
;             if (bj == 1) { q += __shfl_xor(q, 16); q += __shfl_xor(q, 32); if (fq == 0) atomicAdd(ssout + row, q); q = 0.f; sc = sn_; qc = qn; }
;             xc0 = xn0; xc1 = xn1; pc = pn; }
.LBB0_918:
	v_add_u32_e32 v104, 0x90, v190
	v_ashrrev_i32_e32 v105, 31, v104
	v_lshlrev_b64 v[114:115], 10, v[104:105]
	v_lshl_add_u64 v[76:77], v[122:123], 1, s[24:25]
	v_lshl_add_u64 v[106:107], v[114:115], 0, v[188:189]
	v_lshlrev_b64 v[90:91], 2, v[104:105]
	v_cvt_pk_bf16_f32 v72, v92, v93
	v_cvt_pk_bf16_f32 v73, v94, v95
	v_cvt_pk_bf16_f32 v74, v96, v97
	v_cvt_pk_bf16_f32 v75, v98, v99
	s_cmp_lg_u32 s99, 0
	s_cbranch_scc1 .Lwt889_22311
	global_store_dwordx4 v[76:77], v[72:75], off
	s_branch .Lwj889_22311

; __device__ __forceinline__ float sigmoid_f(float z) { return __builtin_amdgcn_rcpf(1.f + fexp(-z)); }
; __device__ __forceinline__ float rms_r(float ss) { return __builtin_amdgcn_rsqf(ss * (1.0f / DM) + RMS_EPS); }
; #define EPI_IT_ROW(it) EPI_ROW((it) >> 2, (it) & 3)
; #define EPI_PACK8(v0, v1) (u32x4){pk2((v0)[0], (v0)[1]), pk2((v0)[2], (v0)[3]), pk2((v1)[0], (v1)[1]), pk2((v1)[2], (v1)[3])}
;     __device__ __forceinline__ void operator()(AccRef acc, const Unit& u, int wr, int wc, int fr, int fq) const {
;     ...
;             if (st + 1 < 16) { const int it1 = (st + 1) >> 1, bj1 = (st + 1) & 1; const size_t p = (size_t)EPI_IT_ROW(it1) * DM + EPI_COL(bj1);
;                 xn0 = *(const f32x4*)(x + p); xn1 = *(const f32x4*)(x + p + 4); pn = *(const u32x4*)(pp + p);
;                 if (bj1 == 0) { sn_ = ssin[EPI_IT_ROW(it1)]; qn = ppss[EPI_IT_ROW(it1)]; } }
;             const float r = rms_r(sc), rp = rms_r(qc);
;             const size_t p = (size_t)row * DM + EPI_COL(bj);
;             const f32x4 p0 = (f32x4){bflo(pc.x), bfhi(pc.x), bflo(pc.y), bfhi(pc.y)}, p1 = (f32x4){bflo(pc.z), bfhi(pc.z), bflo(pc.w), bfhi(pc.w)};
;             const f32x4 z0 = acc[ai][bj][m][0] * r, z1 = acc[ai][bj][m][1] * r;
;             f32x4 g0, g1;
; #pragma unroll
;             for (int e = 0; e < 4; ++e) { g0[e] = sigmoid_f(z0[e]); g1[e] = sigmoid_f(z1[e]); }
;             const f32x4 x0 = xc0 + g0 * (p0 * rp) * pg[bj][0], x1 = xc1 + g1 * (p1 * rp) * pg[bj][1];
;             if (xo) { __builtin_nontemporal_store(x0, (f32x4*)(xo + p)); __builtin_nontemporal_store(x1, (f32x4*)(xo + p + 4)); }
;             *(u32x4*)(xb + p) = EPI_PACK8(x0, x1);
;             q += EPI_SQ8(x0, x1);
;             if (bj == 1) { q += __shfl_xor(q, 16); q += __shfl_xor(q, 32); if (fq == 0) atomicAdd(ssout + row, q); q = 0.f; sc = sn_; qc = qn; }
.Lwj889_22311:
	v_lshl_add_u64 v[110:111], v[106:107], 2, s[48:49]
	v_lshl_add_u64 v[88:89], v[106:107], 1, s[40:41]
	v_lshl_add_u64 v[122:123], s[12:13], 0, v[90:91]
	global_load_dwordx4 v[72:75], v[110:111], off offset:16
	global_load_dwordx4 v[76:79], v[110:111], off
	v_lshl_add_u64 v[124:125], s[14:15], 0, v[90:91]
	global_load_dwordx4 v[88:91], v[88:89], off
	s_nop 0
	global_load_dword v122, v[122:123], off
	s_nop 0
	global_load_dword v119, v[124:125], off
	v_mul_f32_e32 v68, v68, v118
	v_mul_f32_e32 v64, v64, v118
	v_mul_f32_e32 v68, 0xbfb8aa3b, v68
	v_mul_f32_e32 v64, 0xbfb8aa3b, v64
	v_exp_f32_e32 v68, v68
	v_exp_f32_e32 v123, v64
	v_mul_f32_e32 v69, v69, v118
	v_mul_f32_e32 v65, v65, v118
	v_mul_f32_e32 v69, 0xbfb8aa3b, v69
	v_mul_f32_e32 v65, 0xbfb8aa3b, v65
	v_add_f32_e32 v64, 1.0, v68
	v_add_f32_e32 v68, 1.0, v123
	v_exp_f32_e32 v69, v69
	v_exp_f32_e32 v123, v65
	v_mul_f32_e32 v70, v70, v118
	v_mul_f32_e32 v71, v71, v118
	v_mul_f32_e32 v70, 0xbfb8aa3b, v70
	v_mul_f32_e32 v71, 0xbfb8aa3b, v71
	v_exp_f32_e32 v70, v70
	v_mul_f32_e32 v66, v66, v118
	v_exp_f32_e32 v71, v71
	v_mul_f32_e32 v67, v67, v118
	v_mul_f32_e32 v66, 0xbfb8aa3b, v66
	v_mul_f32_e32 v67, 0xbfb8aa3b, v67
	v_add_f32_e32 v65, 1.0, v69
	v_add_f32_e32 v69, 1.0, v123
	v_exp_f32_e32 v123, v66
	v_exp_f32_e32 v118, v67
	v_add_f32_e32 v66, 1.0, v70
	v_add_f32_e32 v67, 1.0, v71
	v_rcp_f32_e32 v64, v64
	v_rcp_f32_e32 v65, v65
	v_rcp_f32_e32 v66, v66
	v_rcp_f32_e32 v67, v67
	v_add_f32_e32 v70, 1.0, v123
	v_add_f32_e32 v71, 1.0, v118
	v_mov_b32_e32 v117, v116
	s_waitcnt vmcnt(6)
	v_lshlrev_b32_e32 v124, 16, v100
	v_and_b32_e32 v125, 0xffff0000, v100
	v_lshlrev_b32_e32 v100, 16, v101
	v_and_b32_e32 v101, 0xffff0000, v101
	v_rcp_f32_e32 v68, v68
	v_rcp_f32_e32 v69, v69
	v_rcp_f32_e32 v70, v70
	v_rcp_f32_e32 v71, v71
	v_mov_b32_e32 v128, v116
	v_mov_b32_e32 v129, v116
	v_pk_mul_f32 v[100:101], v[128:129], v[100:101]
	v_pk_mul_f32 v[124:125], v[116:117], v[124:125]
	v_lshlrev_b32_e32 v126, 16, v102
	v_and_b32_e32 v127, 0xffff0000, v102
	v_lshlrev_b32_e32 v102, 16, v103
	v_and_b32_e32 v103, 0xffff0000, v103
	v_pk_mul_f32 v[64:65], v[64:65], v[124:125]
	v_pk_mul_f32 v[66:67], v[66:67], v[100:101]
	v_pk_fma_f32 v[64:65], v[44:45], v[64:65], v[84:85]
	v_pk_fma_f32 v[66:67], v[46:47], v[66:67], v[86:87]
	v_pk_mul_f32 v[84:85], v[128:129], v[102:103]
	v_pk_mul_f32 v[86:87], v[116:117], v[126:127]
	v_pk_mul_f32 v[70:71], v[70:71], v[84:85]
	v_pk_mul_f32 v[68:69], v[68:69], v[86:87]
	v_pk_fma_f32 v[70:71], v[42:43], v[70:71], v[82:83]
	s_and_b64 vcc, exec, s[6:7]
	v_pk_fma_f32 v[68:69], v[40:41], v[68:69], v[80:81]
	s_cbranch_vccnz .LBB0_920
	global_store_dwordx4 v[112:113], v[64:67], off nt
	global_store_dwordx4 v[112:113], v[68:71], off offset:16 nt
.LBB0_920:
	v_mul_f32_e32 v80, v93, v93
	v_mul_f32_e32 v81, v95, v95
	v_fmac_f32_e32 v80, v92, v92
	v_fmac_f32_e32 v81, v94, v94
	v_add_f32_e32 v80, v80, v81
	v_mul_f32_e32 v81, v97, v97
	v_fmac_f32_e32 v81, v96, v96
	v_mul_f32_e32 v82, v65, v65
	v_mul_f32_e32 v83, v67, v67
	v_add_f32_e32 v80, v81, v80
	v_mul_f32_e32 v81, v99, v99
	v_fmac_f32_e32 v82, v64, v64
	v_fmac_f32_e32 v83, v66, v66
	v_fmac_f32_e32 v81, v98, v98
	v_add_f32_e32 v82, v82, v83
	v_mul_f32_e32 v83, v69, v69
	v_add_f32_e32 v80, v81, v80
	v_mul_f32_e32 v81, v71, v71
	v_fmac_f32_e32 v83, v68, v68
	v_fmac_f32_e32 v81, v70, v70
	v_add_f32_e32 v82, v83, v82
	v_add_f32_e32 v81, v81, v82
	v_add_f32_e32 v82, v80, v81
	ds_bpermute_b32 v83, v166, v82
	v_cvt_pk_bf16_f32 v80, v64, v65
	v_cvt_pk_bf16_f32 v81, v66, v67
	v_lshl_add_u64 v[66:67], v[108:109], 1, s[24:25]
	s_waitcnt lgkmcnt(0)
	v_add_f32_e32 v64, v82, v83
	ds_bpermute_b32 v65, v167, v64
	v_cvt_pk_bf16_f32 v82, v68, v69
	v_cvt_pk_bf16_f32 v83, v70, v71
	s_cmp_lg_u32 s99, 0
	s_cbranch_scc1 .Lwt889_22433
	global_store_dwordx4 v[66:67], v[80:83], off
	s_branch .Lwj889_22433
.Lwt889_22433:
	global_store_dwordx4 v[66:67], v[80:83], off sc1
.Lwj889_22433:
	s_and_saveexec_b64 s[56:57], s[8:9]
	s_cbranch_execz .LBB0_922
	v_lshl_add_u64 v[66:67], v[120:121], 2, s[16:17]
	s_waitcnt lgkmcnt(0)
	v_add_f32_e32 v64, v64, v65
	global_atomic_add_f32 v[66:67], v64, off

; __device__ __forceinline__ float sigmoid_f(float z) { return __builtin_amdgcn_rcpf(1.f + fexp(-z)); }
; __device__ __forceinline__ float rms_r(float ss) { return __builtin_amdgcn_rsqf(ss * (1.0f / DM) + RMS_EPS); }
; #define EPI_IT_ROW(it) EPI_ROW((it) >> 2, (it) & 3)
; #define EPI_PACK8(v0, v1) (u32x4){pk2((v0)[0], (v0)[1]), pk2((v0)[2], (v0)[3]), pk2((v1)[0], (v1)[1]), pk2((v1)[2], (v1)[3])}
;     __device__ __forceinline__ void operator()(AccRef acc, const Unit& u, int wr, int wc, int fr, int fq) const {
;     ...
;             if (st + 1 < 16) { const int it1 = (st + 1) >> 1, bj1 = (st + 1) & 1; const size_t p = (size_t)EPI_IT_ROW(it1) * DM + EPI_COL(bj1);
;                 xn0 = *(const f32x4*)(x + p); xn1 = *(const f32x4*)(x + p + 4); pn = *(const u32x4*)(pp + p);
;                 if (bj1 == 0) { sn_ = ssin[EPI_IT_ROW(it1)]; qn = ppss[EPI_IT_ROW(it1)]; } }
;             const float r = rms_r(sc), rp = rms_r(qc);
;             const size_t p = (size_t)row * DM + EPI_COL(bj);
;             const f32x4 p0 = (f32x4){bflo(pc.x), bfhi(pc.x), bflo(pc.y), bfhi(pc.y)}, p1 = (f32x4){bflo(pc.z), bfhi(pc.z), bflo(pc.w), bfhi(pc.w)};
;             const f32x4 z0 = acc[ai][bj][m][0] * r, z1 = acc[ai][bj][m][1] * r;
;             f32x4 g0, g1;
; #pragma unroll
;             for (int e = 0; e < 4; ++e) { g0[e] = sigmoid_f(z0[e]); g1[e] = sigmoid_f(z1[e]); }
;             const f32x4 x0 = xc0 + g0 * (p0 * rp) * pg[bj][0], x1 = xc1 + g1 * (p1 * rp) * pg[bj][1];
;             if (xo) { __builtin_nontemporal_store(x0, (f32x4*)(xo + p)); __builtin_nontemporal_store(x1, (f32x4*)(xo + p + 4)); }
;             *(u32x4*)(xb + p) = EPI_PACK8(x0, x1);
;             q += EPI_SQ8(x0, x1);
;             if (bj == 1) { q += __shfl_xor(q, 16); q += __shfl_xor(q, 32); if (fq == 0) atomicAdd(ssout + row, q); q = 0.f; sc = sn_; qc = qn; }
.LBB0_924:
	v_add_u32_e32 v88, 0xa0, v190
	v_ashrrev_i32_e32 v89, 31, v88
	v_lshlrev_b64 v[98:99], 10, v[88:89]
	v_lshl_add_u64 v[52:53], v[106:107], 1, s[24:25]
	v_lshl_add_u64 v[90:91], v[98:99], 0, v[188:189]
	v_lshlrev_b64 v[74:75], 2, v[88:89]
	v_cvt_pk_bf16_f32 v48, v76, v77
	v_cvt_pk_bf16_f32 v49, v78, v79
	v_cvt_pk_bf16_f32 v50, v80, v81
	v_cvt_pk_bf16_f32 v51, v82, v83
	s_cmp_lg_u32 s99, 0
	s_cbranch_scc1 .Lwt889_22540
	global_store_dwordx4 v[52:53], v[48:51], off
	s_branch .Lwj889_22540
.Lwt889_22540:
	global_store_dwordx4 v[52:53], v[48:51], off sc1
.Lwj889_22540:
	v_lshl_add_u64 v[94:95], v[90:91], 2, s[48:49]
	v_lshl_add_u64 v[72:73], v[90:91], 1, s[40:41]
	v_lshl_add_u64 v[106:107], s[12:13], 0, v[74:75]
	global_load_dwordx4 v[48:51], v[94:95], off offset:16
	global_load_dwordx4 v[52:55], v[94:95], off
	v_lshl_add_u64 v[108:109], s[14:15], 0, v[74:75]
	global_load_dwordx4 v[72:75], v[72:73], off
	s_nop 0
	global_load_dword v106, v[106:107], off
	s_nop 0
	global_load_dword v103, v[108:109], off
	v_mul_f32_e32 v36, v36, v102
	v_mul_f32_e32 v32, v32, v102
	v_mul_f32_e32 v36, 0xbfb8aa3b, v36
	v_mul_f32_e32 v32, 0xbfb8aa3b, v32
	v_exp_f32_e32 v36, v36
	v_exp_f32_e32 v107, v32
	v_mul_f32_e32 v37, v37, v102
	v_mul_f32_e32 v33, v33, v102
	v_mul_f32_e32 v37, 0xbfb8aa3b, v37
	v_mul_f32_e32 v33, 0xbfb8aa3b, v33
	v_add_f32_e32 v32, 1.0, v36
	v_add_f32_e32 v36, 1.0, v107
	v_exp_f32_e32 v37, v37
	v_exp_f32_e32 v107, v33
	v_mul_f32_e32 v38, v38, v102
	v_mul_f32_e32 v39, v39, v102
	v_mul_f32_e32 v38, 0xbfb8aa3b, v38
	v_mul_f32_e32 v39, 0xbfb8aa3b, v39
	v_exp_f32_e32 v38, v38
	v_mul_f32_e32 v34, v34, v102
	v_exp_f32_e32 v39, v39
	v_mul_f32_e32 v35, v35, v102
	v_mul_f32_e32 v34, 0xbfb8aa3b, v34
	v_mul_f32_e32 v35, 0xbfb8aa3b, v35
	v_add_f32_e32 v33, 1.0, v37
	v_add_f32_e32 v37, 1.0, v107
	v_exp_f32_e32 v107, v34
	v_exp_f32_e32 v102, v35
	v_add_f32_e32 v34, 1.0, v38
	v_add_f32_e32 v35, 1.0, v39
	v_rcp_f32_e32 v32, v32
	v_rcp_f32_e32 v33, v33
	v_rcp_f32_e32 v34, v34
	v_rcp_f32_e32 v35, v35
	v_add_f32_e32 v38, 1.0, v107
	v_add_f32_e32 v39, 1.0, v102
	v_mov_b32_e32 v101, v100
	s_waitcnt vmcnt(6)
	v_lshlrev_b32_e32 v108, 16, v84
	v_and_b32_e32 v109, 0xffff0000, v84
	v_lshlrev_b32_e32 v84, 16, v85
	v_and_b32_e32 v85, 0xffff0000, v85
	v_rcp_f32_e32 v36, v36
	v_rcp_f32_e32 v37, v37
	v_rcp_f32_e32 v38, v38
	v_rcp_f32_e32 v39, v39
	v_mov_b32_e32 v112, v100
	v_mov_b32_e32 v113, v100
	v_pk_mul_f32 v[84:85], v[112:113], v[84:85]
	v_pk_mul_f32 v[108:109], v[100:101], v[108:109]
	v_lshlrev_b32_e32 v110, 16, v86
	v_and_b32_e32 v111, 0xffff0000, v86
	v_lshlrev_b32_e32 v86, 16, v87
	v_and_b32_e32 v87, 0xffff0000, v87
	v_pk_mul_f32 v[32:33], v[32:33], v[108:109]
	v_pk_mul_f32 v[34:35], v[34:35], v[84:85]
	v_pk_fma_f32 v[32:33], v[44:45], v[32:33], v[68:69]
	v_pk_fma_f32 v[34:35], v[46:47], v[34:35], v[70:71]
	v_pk_mul_f32 v[68:69], v[112:113], v[86:87]
	v_pk_mul_f32 v[70:71], v[100:101], v[110:111]
	v_pk_mul_f32 v[38:39], v[38:39], v[68:69]
	v_pk_mul_f32 v[36:37], v[36:37], v[70:71]
	v_pk_fma_f32 v[38:39], v[42:43], v[38:39], v[66:67]
	s_and_b64 vcc, exec, s[6:7]
	v_pk_fma_f32 v[36:37], v[40:41], v[36:37], v[64:65]
	s_cbranch_vccnz .LBB0_926
	global_store_dwordx4 v[96:97], v[32:35], off nt
	global_store_dwordx4 v[96:97], v[36:39], off offset:16 nt
.LBB0_926:
	v_mul_f32_e32 v64, v77, v77
	v_mul_f32_e32 v65, v79, v79
	v_fmac_f32_e32 v64, v76, v76
	v_fmac_f32_e32 v65, v78, v78
	v_add_f32_e32 v64, v64, v65
	v_mul_f32_e32 v65, v81, v81
	v_fmac_f32_e32 v65, v80, v80
	v_mul_f32_e32 v66, v33, v33
	v_mul_f32_e32 v67, v35, v35
	v_add_f32_e32 v64, v65, v64
	v_mul_f32_e32 v65, v83, v83
	v_fmac_f32_e32 v66, v32, v32
	v_fmac_f32_e32 v67, v34, v34
	v_fmac_f32_e32 v65, v82, v82
	v_add_f32_e32 v66, v66, v67
	v_mul_f32_e32 v67, v37, v37
	v_add_f32_e32 v64, v65, v64
	v_mul_f32_e32 v65, v39, v39
	v_fmac_f32_e32 v67, v36, v36
	v_fmac_f32_e32 v65, v38, v38
	v_add_f32_e32 v66, v67, v66
	v_add_f32_e32 v65, v65, v66
	v_add_f32_e32 v66, v64, v65
	ds_bpermute_b32 v67, v166, v66
	v_cvt_pk_bf16_f32 v64, v32, v33
	v_cvt_pk_bf16_f32 v65, v34, v35
	v_lshl_add_u64 v[34:35], v[92:93], 1, s[24:25]
	s_waitcnt lgkmcnt(0)
	v_add_f32_e32 v32, v66, v67
	ds_bpermute_b32 v33, v167, v32
	v_cvt_pk_bf16_f32 v66, v36, v37
	v_cvt_pk_bf16_f32 v67, v38, v39
	s_cmp_lg_u32 s99, 0
	s_cbranch_scc1 .Lwt889_22662
	global_store_dwordx4 v[34:35], v[64:67], off
	s_branch .Lwj889_22662
.Lwt889_22662:
	global_store_dwordx4 v[34:35], v[64:67], off sc1
.Lwj889_22662:
	s_and_saveexec_b64 s[56:57], s[8:9]
	s_cbranch_execz .LBB0_928
	v_lshl_add_u64 v[34:35], v[104:105], 2, s[16:17]
	s_waitcnt lgkmcnt(0)
	v_add_f32_e32 v32, v32, v33
	global_atomic_add_f32 v[34:35], v32, off

; __device__ __forceinline__ float sigmoid_f(float z) { return __builtin_amdgcn_rcpf(1.f + fexp(-z)); }
; __device__ __forceinline__ float rms_r(float ss) { return __builtin_amdgcn_rsqf(ss * (1.0f / DM) + RMS_EPS); }
; #define EPI_IT_ROW(it) EPI_ROW((it) >> 2, (it) & 3)
; #define EPI_PACK8(v0, v1) (u32x4){pk2((v0)[0], (v0)[1]), pk2((v0)[2], (v0)[3]), pk2((v1)[0], (v1)[1]), pk2((v1)[2], (v1)[3])}
;     __device__ __forceinline__ void operator()(AccRef acc, const Unit& u, int wr, int wc, int fr, int fq) const {
;     ...
;             if (st + 1 < 16) { const int it1 = (st + 1) >> 1, bj1 = (st + 1) & 1; const size_t p = (size_t)EPI_IT_ROW(it1) * DM + EPI_COL(bj1);
;                 xn0 = *(const f32x4*)(x + p); xn1 = *(const f32x4*)(x + p + 4); pn = *(const u32x4*)(pp + p);
;                 if (bj1 == 0) { sn_ = ssin[EPI_IT_ROW(it1)]; qn = ppss[EPI_IT_ROW(it1)]; } }
;             const float r = rms_r(sc), rp = rms_r(qc);
;             const size_t p = (size_t)row * DM + EPI_COL(bj);
;             const f32x4 p0 = (f32x4){bflo(pc.x), bfhi(pc.x), bflo(pc.y), bfhi(pc.y)}, p1 = (f32x4){bflo(pc.z), bfhi(pc.z), bflo(pc.w), bfhi(pc.w)};
;             const f32x4 z0 = acc[ai][bj][m][0] * r, z1 = acc[ai][bj][m][1] * r;
;             f32x4 g0, g1;
; #pragma unroll
;             for (int e = 0; e < 4; ++e) { g0[e] = sigmoid_f(z0[e]); g1[e] = sigmoid_f(z1[e]); }
;             const f32x4 x0 = xc0 + g0 * (p0 * rp) * pg[bj][0], x1 = xc1 + g1 * (p1 * rp) * pg[bj][1];
;             if (xo) { __builtin_nontemporal_store(x0, (f32x4*)(xo + p)); __builtin_nontemporal_store(x1, (f32x4*)(xo + p + 4)); }
;             *(u32x4*)(xb + p) = EPI_PACK8(x0, x1);
;             q += EPI_SQ8(x0, x1);
;             if (bj == 1) { q += __shfl_xor(q, 16); q += __shfl_xor(q, 32); if (fq == 0) atomicAdd(ssout + row, q); q = 0.f; sc = sn_; qc = qn; }
.LBB0_930:
	v_add_u32_e32 v72, 0xb0, v190
	v_ashrrev_i32_e32 v73, 31, v72
	v_lshlrev_b64 v[82:83], 10, v[72:73]
	v_lshl_add_u64 v[28:29], v[90:91], 1, s[24:25]
	v_lshl_add_u64 v[74:75], v[82:83], 0, v[188:189]
	v_lshlrev_b64 v[50:51], 2, v[72:73]
	v_cvt_pk_bf16_f32 v24, v52, v53
	v_cvt_pk_bf16_f32 v25, v54, v55
	v_cvt_pk_bf16_f32 v26, v64, v65
	v_cvt_pk_bf16_f32 v27, v66, v67
	s_cmp_lg_u32 s99, 0
	s_cbranch_scc1 .Lwt889_22769
	global_store_dwordx4 v[28:29], v[24:27], off
	s_branch .Lwj889_22769
.Lwt889_22769:
	global_store_dwordx4 v[28:29], v[24:27], off sc1
.Lwj889_22769:
	v_lshl_add_u64 v[78:79], v[74:75], 2, s[48:49]
	v_lshl_add_u64 v[48:49], v[74:75], 1, s[40:41]
	v_lshl_add_u64 v[90:91], s[12:13], 0, v[50:51]
	global_load_dwordx4 v[24:27], v[78:79], off offset:16
	global_load_dwordx4 v[28:31], v[78:79], off
	v_lshl_add_u64 v[92:93], s[14:15], 0, v[50:51]
	global_load_dwordx4 v[48:51], v[48:49], off
	s_nop 0
	global_load_dword v90, v[90:91], off
	s_nop 0
	global_load_dword v87, v[92:93], off
	v_mul_f32_e32 v20, v20, v86
	v_mul_f32_e32 v16, v16, v86
	v_mul_f32_e32 v20, 0xbfb8aa3b, v20
	v_mul_f32_e32 v16, 0xbfb8aa3b, v16
	v_exp_f32_e32 v20, v20
	v_exp_f32_e32 v91, v16
	v_mul_f32_e32 v21, v21, v86
	v_mul_f32_e32 v17, v17, v86
	v_mul_f32_e32 v21, 0xbfb8aa3b, v21
	v_mul_f32_e32 v17, 0xbfb8aa3b, v17
	v_add_f32_e32 v16, 1.0, v20
	v_add_f32_e32 v20, 1.0, v91
	v_exp_f32_e32 v21, v21
	v_exp_f32_e32 v91, v17
	v_mul_f32_e32 v22, v22, v86
	v_mul_f32_e32 v23, v23, v86
	v_mul_f32_e32 v22, 0xbfb8aa3b, v22
	v_mul_f32_e32 v23, 0xbfb8aa3b, v23
	v_exp_f32_e32 v22, v22
	v_mul_f32_e32 v18, v18, v86
	v_exp_f32_e32 v23, v23
	v_mul_f32_e32 v19, v19, v86
	v_mul_f32_e32 v18, 0xbfb8aa3b, v18
	v_mul_f32_e32 v19, 0xbfb8aa3b, v19
	v_add_f32_e32 v17, 1.0, v21
	v_add_f32_e32 v21, 1.0, v91
	v_exp_f32_e32 v91, v18
	v_exp_f32_e32 v86, v19
	v_add_f32_e32 v18, 1.0, v22
	v_add_f32_e32 v19, 1.0, v23
	v_rcp_f32_e32 v16, v16
	v_rcp_f32_e32 v17, v17
	v_rcp_f32_e32 v18, v18
	v_rcp_f32_e32 v19, v19
	v_add_f32_e32 v22, 1.0, v91
	v_add_f32_e32 v23, 1.0, v86
	v_mov_b32_e32 v85, v84
	s_waitcnt vmcnt(6)
	v_lshlrev_b32_e32 v92, 16, v68
	v_and_b32_e32 v93, 0xffff0000, v68
	v_lshlrev_b32_e32 v68, 16, v69
	v_and_b32_e32 v69, 0xffff0000, v69
	v_rcp_f32_e32 v20, v20
	v_rcp_f32_e32 v21, v21
	v_rcp_f32_e32 v22, v22
	v_rcp_f32_e32 v23, v23
	v_mov_b32_e32 v96, v84
	v_mov_b32_e32 v97, v84
	v_pk_mul_f32 v[68:69], v[96:97], v[68:69]
	v_pk_mul_f32 v[92:93], v[84:85], v[92:93]
	v_lshlrev_b32_e32 v94, 16, v70
	v_and_b32_e32 v95, 0xffff0000, v70
	v_lshlrev_b32_e32 v70, 16, v71
	v_and_b32_e32 v71, 0xffff0000, v71
	v_pk_mul_f32 v[16:17], v[16:17], v[92:93]
	v_pk_mul_f32 v[18:19], v[18:19], v[68:69]
	v_pk_fma_f32 v[16:17], v[44:45], v[16:17], v[36:37]
	v_pk_fma_f32 v[18:19], v[46:47], v[18:19], v[38:39]
	v_pk_mul_f32 v[36:37], v[96:97], v[70:71]
	v_pk_mul_f32 v[38:39], v[84:85], v[94:95]
	v_pk_mul_f32 v[22:23], v[22:23], v[36:37]
	v_pk_mul_f32 v[20:21], v[20:21], v[38:39]
	v_pk_fma_f32 v[22:23], v[42:43], v[22:23], v[34:35]
	s_and_b64 vcc, exec, s[6:7]
	v_pk_fma_f32 v[20:21], v[40:41], v[20:21], v[32:33]
	s_cbranch_vccnz .LBB0_932
	global_store_dwordx4 v[80:81], v[16:19], off nt
	global_store_dwordx4 v[80:81], v[20:23], off offset:16 nt
.LBB0_932:
	v_mul_f32_e32 v32, v53, v53
	v_mul_f32_e32 v33, v55, v55
	v_fmac_f32_e32 v32, v52, v52
	v_fmac_f32_e32 v33, v54, v54
	v_add_f32_e32 v32, v32, v33
	v_mul_f32_e32 v33, v65, v65
	v_fmac_f32_e32 v33, v64, v64
	v_mul_f32_e32 v34, v17, v17
	v_mul_f32_e32 v35, v19, v19
	v_add_f32_e32 v32, v33, v32
	v_mul_f32_e32 v33, v67, v67
	v_fmac_f32_e32 v34, v16, v16
	v_fmac_f32_e32 v35, v18, v18
	v_fmac_f32_e32 v33, v66, v66
	v_add_f32_e32 v34, v34, v35
	v_mul_f32_e32 v35, v21, v21
	v_add_f32_e32 v32, v33, v32
	v_mul_f32_e32 v33, v23, v23
	v_fmac_f32_e32 v35, v20, v20
	v_fmac_f32_e32 v33, v22, v22
	v_add_f32_e32 v34, v35, v34
	v_add_f32_e32 v33, v33, v34
	v_add_f32_e32 v34, v32, v33
	ds_bpermute_b32 v35, v166, v34
	v_cvt_pk_bf16_f32 v32, v16, v17
	v_cvt_pk_bf16_f32 v33, v18, v19
	v_lshl_add_u64 v[18:19], v[76:77], 1, s[24:25]
	s_waitcnt lgkmcnt(0)
	v_add_f32_e32 v16, v34, v35
	ds_bpermute_b32 v17, v167, v16
	v_cvt_pk_bf16_f32 v34, v20, v21
	v_cvt_pk_bf16_f32 v35, v22, v23
	s_cmp_lg_u32 s99, 0
	s_cbranch_scc1 .Lwt889_22891
	global_store_dwordx4 v[18:19], v[32:35], off
	s_branch .Lwj889_22891
.Lwt889_22891:
	global_store_dwordx4 v[18:19], v[32:35], off sc1
.Lwj889_22891:
	s_and_saveexec_b64 s[56:57], s[8:9]
	s_cbranch_execz .LBB0_934
	v_lshl_add_u64 v[18:19], v[88:89], 2, s[16:17]
	s_waitcnt lgkmcnt(0)
	v_add_f32_e32 v16, v16, v17
	global_atomic_add_f32 v[18:19], v16, off

; #define EPI_PACK8(v0, v1) (u32x4){pk2((v0)[0], (v0)[1]), pk2((v0)[2], (v0)[3]), pk2((v1)[0], (v1)[1]), pk2((v1)[2], (v1)[3])}
;     __device__ __forceinline__ void operator()(AccRef acc, const Unit& u, int wr, int wc, int fr, int fq) const {
;     ...
;             *(u32x4*)(xb + p) = EPI_PACK8(x0, x1);
;             q += EPI_SQ8(x0, x1);
;             if (bj == 1) { q += __shfl_xor(q, 16); q += __shfl_xor(q, 32); if (fq == 0) atomicAdd(ssout + row, q); q = 0.f; sc = sn_; qc = qn; }
;             xc0 = xn0; xc1 = xn1; pc = pn; }
.LBB0_936:
	v_mul_f32_e32 v4, v4, v52
	v_mul_f32_e32 v0, v0, v52
	v_cvt_pk_bf16_f32 v24, v8, v9
	v_cvt_pk_bf16_f32 v25, v10, v11
	v_lshl_add_u64 v[28:29], v[74:75], 1, s[24:25]
	v_mul_f32_e32 v4, 0xbfb8aa3b, v4
	v_mul_f32_e32 v0, 0xbfb8aa3b, v0
	v_cvt_pk_bf16_f32 v26, v12, v13
	v_cvt_pk_bf16_f32 v27, v14, v15
	s_cmp_lg_u32 s99, 0
	s_cbranch_scc1 .Lwt889_22997
	global_store_dwordx4 v[28:29], v[24:27], off
	s_branch .Lwj889_22997

; __device__ __forceinline__ float sigmoid_f(float z) { return __builtin_amdgcn_rcpf(1.f + fexp(-z)); }
; __device__ __forceinline__ float rms_r(float ss) { return __builtin_amdgcn_rsqf(ss * (1.0f / DM) + RMS_EPS); }
; #define EPI_PACK8(v0, v1) (u32x4){pk2((v0)[0], (v0)[1]), pk2((v0)[2], (v0)[3]), pk2((v1)[0], (v1)[1]), pk2((v1)[2], (v1)[3])}
;     __device__ __forceinline__ void operator()(AccRef acc, const Unit& u, int wr, int wc, int fr, int fq) const {
;     ...
;             const float r = rms_r(sc), rp = rms_r(qc);
;             const size_t p = (size_t)row * DM + EPI_COL(bj);
;             const f32x4 p0 = (f32x4){bflo(pc.x), bfhi(pc.x), bflo(pc.y), bfhi(pc.y)}, p1 = (f32x4){bflo(pc.z), bfhi(pc.z), bflo(pc.w), bfhi(pc.w)};
;             const f32x4 z0 = acc[ai][bj][m][0] * r, z1 = acc[ai][bj][m][1] * r;
;             f32x4 g0, g1;
; #pragma unroll
;             for (int e = 0; e < 4; ++e) { g0[e] = sigmoid_f(z0[e]); g1[e] = sigmoid_f(z1[e]); }
;             const f32x4 x0 = xc0 + g0 * (p0 * rp) * pg[bj][0], x1 = xc1 + g1 * (p1 * rp) * pg[bj][1];
;             if (xo) { __builtin_nontemporal_store(x0, (f32x4*)(xo + p)); __builtin_nontemporal_store(x1, (f32x4*)(xo + p + 4)); }
;             *(u32x4*)(xb + p) = EPI_PACK8(x0, x1);
;             q += EPI_SQ8(x0, x1);
;             if (bj == 1) { q += __shfl_xor(q, 16); q += __shfl_xor(q, 32); if (fq == 0) atomicAdd(ssout + row, q); q = 0.f; sc = sn_; qc = qn; }
.Lwj889_22997:
	v_exp_f32_e32 v4, v4
	v_mul_f32_e32 v5, v5, v52
	s_waitcnt vmcnt(1)
	v_lshlrev_b32_e32 v24, 16, v32
	v_and_b32_e32 v25, 0xffff0000, v32
	v_exp_f32_e32 v32, v0
	v_mul_f32_e32 v1, v1, v52
	v_mul_f32_e32 v5, 0xbfb8aa3b, v5
	v_mul_f32_e32 v1, 0xbfb8aa3b, v1
	v_add_f32_e32 v0, 1.0, v4
	v_add_f32_e32 v4, 1.0, v32
	v_exp_f32_e32 v5, v5
	v_exp_f32_e32 v32, v1
	v_mul_f32_e32 v6, v6, v52
	v_mul_f32_e32 v2, v2, v52
	v_mul_f32_e32 v6, 0xbfb8aa3b, v6
	v_mul_f32_e32 v2, 0xbfb8aa3b, v2
	v_add_f32_e32 v1, 1.0, v5
	v_add_f32_e32 v5, 1.0, v32
	v_exp_f32_e32 v6, v6
	v_exp_f32_e32 v32, v2
	v_mul_f32_e32 v7, v7, v52
	v_mul_f32_e32 v7, 0xbfb8aa3b, v7
	v_exp_f32_e32 v7, v7
	v_mul_f32_e32 v3, v3, v52
	v_mul_f32_e32 v3, 0xbfb8aa3b, v3
	v_add_f32_e32 v2, 1.0, v6
	v_add_f32_e32 v6, 1.0, v32
	v_exp_f32_e32 v32, v3
	v_add_f32_e32 v3, 1.0, v7
	v_rcp_f32_e32 v0, v0
	v_rcp_f32_e32 v1, v1
	v_rcp_f32_e32 v2, v2
	v_rcp_f32_e32 v3, v3
	v_add_f32_e32 v7, 1.0, v32
	v_mov_b32_e32 v49, v48
	v_lshlrev_b32_e32 v26, 16, v33
	v_and_b32_e32 v27, 0xffff0000, v33
	v_rcp_f32_e32 v4, v4
	v_rcp_f32_e32 v5, v5
	v_rcp_f32_e32 v6, v6
	v_rcp_f32_e32 v7, v7
	v_mov_b32_e32 v32, v48
	v_mov_b32_e32 v33, v48
	v_pk_mul_f32 v[26:27], v[32:33], v[26:27]
	v_pk_mul_f32 v[24:25], v[48:49], v[24:25]
	v_lshlrev_b32_e32 v28, 16, v34
	v_and_b32_e32 v29, 0xffff0000, v34
	v_lshlrev_b32_e32 v30, 16, v35
	v_and_b32_e32 v31, 0xffff0000, v35
	v_pk_mul_f32 v[0:1], v[0:1], v[24:25]
	v_pk_mul_f32 v[2:3], v[2:3], v[26:27]
	v_pk_fma_f32 v[0:1], v[44:45], v[0:1], v[20:21]
	v_pk_fma_f32 v[2:3], v[46:47], v[2:3], v[22:23]
	v_pk_mul_f32 v[20:21], v[32:33], v[30:31]
	v_pk_mul_f32 v[22:23], v[48:49], v[28:29]
	v_pk_mul_f32 v[6:7], v[6:7], v[20:21]
	v_pk_mul_f32 v[4:5], v[4:5], v[22:23]
	v_pk_fma_f32 v[6:7], v[42:43], v[6:7], v[18:19]
	s_and_b64 vcc, exec, s[6:7]
	v_pk_fma_f32 v[4:5], v[40:41], v[4:5], v[16:17]
	s_cbranch_vccnz .LBB0_938
	global_store_dwordx4 v[38:39], v[0:3], off nt
	global_store_dwordx4 v[38:39], v[4:7], off offset:16 nt
.LBB0_938:
	v_mul_f32_e32 v9, v9, v9
	v_fmac_f32_e32 v9, v8, v8
	v_mul_f32_e32 v8, v11, v11
	v_fmac_f32_e32 v8, v10, v10
	v_add_f32_e32 v8, v9, v8
	v_mul_f32_e32 v9, v13, v13
	v_fmac_f32_e32 v9, v12, v12
	v_mul_f32_e32 v10, v1, v1
	v_mul_f32_e32 v11, v3, v3
	v_add_f32_e32 v8, v9, v8
	v_mul_f32_e32 v9, v15, v15
	v_fmac_f32_e32 v10, v0, v0
	v_fmac_f32_e32 v11, v2, v2
	v_fmac_f32_e32 v9, v14, v14
	v_add_f32_e32 v10, v10, v11
	v_mul_f32_e32 v11, v5, v5
	v_add_f32_e32 v8, v9, v8
	v_mul_f32_e32 v9, v7, v7
	v_fmac_f32_e32 v11, v4, v4
	v_fmac_f32_e32 v9, v6, v6
	v_add_f32_e32 v10, v11, v10
	v_add_f32_e32 v9, v9, v10
	v_add_f32_e32 v10, v8, v9
	ds_bpermute_b32 v11, v166, v10
	v_cvt_pk_bf16_f32 v8, v0, v1
	v_cvt_pk_bf16_f32 v9, v2, v3
	v_lshl_add_u64 v[2:3], v[36:37], 1, s[24:25]
	s_waitcnt lgkmcnt(0)
	v_add_f32_e32 v0, v10, v11
	ds_bpermute_b32 v1, v167, v0
	v_cvt_pk_bf16_f32 v10, v4, v5
	v_cvt_pk_bf16_f32 v11, v6, v7
	s_cmp_lg_u32 s99, 0
	s_cbranch_scc1 .Lwt889_23104
	global_store_dwordx4 v[2:3], v[8:11], off
	s_branch .Lwj889_23104
.Lwt889_23104:
	global_store_dwordx4 v[2:3], v[8:11], off sc1
.Lwj889_23104:
	s_and_saveexec_b64 s[6:7], s[8:9]
	s_cbranch_execz .LBB0_940
	v_lshl_add_u64 v[2:3], v[72:73], 2, s[16:17]
	s_waitcnt lgkmcnt(0)
	v_add_f32_e32 v0, v0, v1
	global_atomic_add_f32 v[2:3], v0, off

; #define PG8_STAGE(bufoff, gbase, voff) do { _Pragma("unroll") for (int _i = 0; _i < 2; ++_i) \
;         __builtin_amdgcn_global_load_lds((const unsigned*)((const char*)(gbase) + (voff)[_i]), (LAS unsigned*)(lds + (bufoff) + ldsw + _i * 8192), 16, 0, 0); } while (0)
; #define PG8_LDA(dst, b, h) do { _Pragma("unroll") for (int m = 0; m < 4; ++m) _Pragma("unroll") for (int k = 0; k < 2; ++k) dst[m][k] = *(const LAS bf16x8*)(lds + PG8_SA(b, h) + aoff + m * 2048 + k * 1024); } while (0)
; #define PG8_LDB(dst, b, h) do { _Pragma("unroll") for (int n = 0; n < 2; ++n) _Pragma("unroll") for (int k = 0; k < 2; ++k) dst[n][k] = *(const LAS bf16x8*)(lds + PG8_SB(b, h) + boff + n * 2048 + k * 1024); } while (0)
; #define PG8_MMA(ai, bj, At, Bt) do { __builtin_amdgcn_s_setprio(1); _Pragma("unroll") for (int m = 0; m < 4; ++m) _Pragma("unroll") for (int n = 0; n < 2; ++n) _Pragma("unroll") for (int k = 0; k < 2; ++k) \
;         acc[ai][bj][m][n] = __builtin_amdgcn_mfma_f32_16x16x32_bf16(Bt[n][k], At[m][k], acc[ai][bj][m][n], 0, 0, 0); __builtin_amdgcn_s_setprio(0); } while (0)
; #define PG8_WAIT_V(n) asm volatile("s_waitcnt vmcnt(" #n ")" ::: "memory")
; #define PG8_WAIT_L(n) asm volatile("s_waitcnt lgkmcnt(" #n ")" ::: "memory")
; #define PG8_BAR __builtin_amdgcn_s_barrier()
; #define PG8_SCHED __builtin_amdgcn_sched_barrier(0)
; template <class Epi>
; __device__ __forceinline__ void gemm_phase(LAS unsigned char* lds, const Gemm g, const StaticOrder& S, const Epi& E) {
;     ...
;             PG8_LDB(B0, 0, 0); PG8_LDB(B1, 0, 1); PG8_SCHED; PG8_LDA(At, 0, 0); PG8_STAGE(PG8_SA(1, 1), a1 + hstepA, voffA);
;             PG8_WAIT_V(8); PG8_WAIT_L(0); PG8_BAR; PG8_MMA(0, 0, At, B0); PG8_MMA(0, 1, At, B1); PG8_BAR; PG8_SCHED;
;             PG8_LDA(At, 0, 1); PG8_STAGE(PG8_SB(0, 0), b2, voffB); PG8_STAGE(PG8_SB(0, 1), b2 + hstepB, voffB); PG8_STAGE(PG8_SA(0, 0), a2, voffA);
;             PG8_WAIT_V(8); PG8_WAIT_L(0); PG8_BAR; PG8_MMA(1, 0, At, B0); PG8_MMA(1, 1, At, B1); PG8_BAR; PG8_SCHED;
.LBB0_1018:
	ds_read_b128 v[0:3], v230
	ds_read_b128 v[4:7], v230 offset:1024
	ds_read_b128 v[8:11], v230 offset:2048
	ds_read_b128 v[12:15], v230 offset:3072
	ds_read_b128 v[144:147], v231
	ds_read_b128 v[148:151], v231 offset:1024
	ds_read_b128 v[152:155], v231 offset:2048
	ds_read_b128 v[156:159], v231 offset:3072
	s_add_u32 s56, s54, 0xfffc0080
	s_addc_u32 s57, s55, -1
	s_cmp_eq_u32 s85, 12
	s_cselect_b32 s63, s7, s57
	s_cselect_b32 s62, s35, s56
	s_cselect_b32 s57, s23, s84
	s_cselect_b32 s56, s53, s83
	v_lshl_add_u64 v[212:213], s[54:55], 0, v[188:189]
	s_add_i32 m0, s68, 0xc000
	ds_read_b128 v[160:163], v232
	ds_read_b128 v[164:167], v232 offset:1024
	ds_read_b128 v[168:171], v232 offset:2048
	ds_read_b128 v[172:175], v232 offset:3072
	ds_read_b128 v[196:199], v232 offset:4096
	ds_read_b128 v[200:203], v232 offset:5120
	ds_read_b128 v[204:207], v232 offset:6144
	ds_read_b128 v[208:211], v232 offset:7168
	global_load_lds_dwordx4 v[212:213], off
	v_lshl_add_u64 v[212:213], s[54:55], 0, v[190:191]
	s_add_i32 m0, s68, 0xe000
	s_nop 0
	global_load_lds_dwordx4 v[212:213], off
	s_waitcnt vmcnt(8)
	s_waitcnt lgkmcnt(0)
	s_barrier
	s_setprio 1
	s_waitcnt lgkmcnt(0)
	v_mfma_f32_16x16x32_bf16 v[140:143], v[0:3], v[160:163], v[140:143]
	v_mfma_f32_16x16x32_bf16 v[132:135], v[8:11], v[160:163], v[132:135]
	v_mfma_f32_16x16x32_bf16 v[124:127], v[0:3], v[168:171], v[124:127]
	v_mfma_f32_16x16x32_bf16 v[120:123], v[8:11], v[168:171], v[120:123]
	v_mfma_f32_16x16x32_bf16 v[108:111], v[0:3], v[196:199], v[108:111]
	v_mfma_f32_16x16x32_bf16 v[104:107], v[8:11], v[196:199], v[104:107]
	v_mfma_f32_16x16x32_bf16 v[92:95], v[0:3], v[204:207], v[92:95]
	v_mfma_f32_16x16x32_bf16 v[88:91], v[8:11], v[204:207], v[88:91]
	v_mfma_f32_16x16x32_bf16 v[140:143], v[4:7], v[164:167], v[140:143]
	v_mfma_f32_16x16x32_bf16 v[132:135], v[12:15], v[164:167], v[132:135]
	v_mfma_f32_16x16x32_bf16 v[124:127], v[4:7], v[172:175], v[124:127]
	v_mfma_f32_16x16x32_bf16 v[120:123], v[12:15], v[172:175], v[120:123]
	v_mfma_f32_16x16x32_bf16 v[108:111], v[4:7], v[200:203], v[108:111]
	v_mfma_f32_16x16x32_bf16 v[104:107], v[12:15], v[200:203], v[104:107]
	v_mfma_f32_16x16x32_bf16 v[92:95], v[4:7], v[208:211], v[92:95]
	v_mfma_f32_16x16x32_bf16 v[88:91], v[12:15], v[208:211], v[88:91]
	s_setprio 0
	s_setprio 1
	v_mfma_f32_16x16x32_bf16 v[136:139], v[144:147], v[160:163], v[136:139]
	v_mfma_f32_16x16x32_bf16 v[128:131], v[152:155], v[160:163], v[128:131]
	v_mfma_f32_16x16x32_bf16 v[116:119], v[144:147], v[168:171], v[116:119]
	v_mfma_f32_16x16x32_bf16 v[112:115], v[152:155], v[168:171], v[112:115]
	v_mfma_f32_16x16x32_bf16 v[100:103], v[144:147], v[196:199], v[100:103]
	v_mfma_f32_16x16x32_bf16 v[96:99], v[152:155], v[196:199], v[96:99]
	v_mfma_f32_16x16x32_bf16 v[84:87], v[144:147], v[204:207], v[84:87]
	v_mfma_f32_16x16x32_bf16 v[80:83], v[152:155], v[204:207], v[80:83]
	v_mfma_f32_16x16x32_bf16 v[136:139], v[148:151], v[164:167], v[136:139]
	v_mfma_f32_16x16x32_bf16 v[128:131], v[156:159], v[164:167], v[128:131]
	v_mfma_f32_16x16x32_bf16 v[116:119], v[148:151], v[172:175], v[116:119]
	v_mfma_f32_16x16x32_bf16 v[112:115], v[156:159], v[172:175], v[112:115]
	v_mfma_f32_16x16x32_bf16 v[100:103], v[148:151], v[200:203], v[100:103]
	v_mfma_f32_16x16x32_bf16 v[96:99], v[156:159], v[200:203], v[96:99]
	v_mfma_f32_16x16x32_bf16 v[84:87], v[148:151], v[208:211], v[84:87]
	v_mfma_f32_16x16x32_bf16 v[80:83], v[156:159], v[208:211], v[80:83]
	s_setprio 0
	s_barrier
	s_add_i32 s86, s81, s65
	v_lshl_add_u64 v[212:213], s[56:57], 0, v[180:181]
	s_mov_b32 m0, s86
	ds_read_b128 v[160:163], v232 offset:16384
	ds_read_b128 v[164:167], v232 offset:17408
	ds_read_b128 v[168:171], v232 offset:18432
	ds_read_b128 v[172:175], v232 offset:19456
	ds_read_b128 v[196:199], v232 offset:20480
	ds_read_b128 v[200:203], v232 offset:21504
	ds_read_b128 v[204:207], v232 offset:22528
	ds_read_b128 v[208:211], v232 offset:23552
	global_load_lds_dwordx4 v[212:213], off
	s_add_i32 m0, s86, 0x2000
	s_add_u32 s86, s56, 0x40000
	v_lshl_add_u64 v[214:215], s[56:57], 0, v[184:185]
	s_addc_u32 s87, s57, 0
	s_add_i32 s88, s82, s65
	global_load_lds_dwordx4 v[214:215], off
	v_lshl_add_u64 v[216:217], s[86:87], 0, v[180:181]
	s_mov_b32 m0, s88
	v_lshl_add_u64 v[218:219], s[62:63], 0, v[182:183]
	global_load_lds_dwordx4 v[216:217], off
	v_lshl_add_u64 v[216:217], s[86:87], 0, v[184:185]
	s_add_i32 m0, s88, 0x2000
	s_nop 0
	global_load_lds_dwordx4 v[216:217], off
	v_lshl_add_u64 v[216:217], s[62:63], 0, v[178:179]
	s_mov_b32 m0, s68
	s_nop 0
	global_load_lds_dwordx4 v[216:217], off
	s_mov_b32 m0, s69
	s_nop 0
	global_load_lds_dwordx4 v[218:219], off
	s_waitcnt vmcnt(8)
	s_waitcnt lgkmcnt(0)
	s_barrier
; #define PG8_STAGE(bufoff, gbase, voff) do { _Pragma("unroll") for (int _i = 0; _i < 2; ++_i) \
;         __builtin_amdgcn_global_load_lds((const unsigned*)((const char*)(gbase) + (voff)[_i]), (LAS unsigned*)(lds + (bufoff) + ldsw + _i * 8192), 16, 0, 0); } while (0)
; #define PG8_LDA(dst, b, h) do { _Pragma("unroll") for (int m = 0; m < 4; ++m) _Pragma("unroll") for (int k = 0; k < 2; ++k) dst[m][k] = *(const LAS bf16x8*)(lds + PG8_SA(b, h) + aoff + m * 2048 + k * 1024); } while (0)
; #define PG8_LDB(dst, b, h) do { _Pragma("unroll") for (int n = 0; n < 2; ++n) _Pragma("unroll") for (int k = 0; k < 2; ++k) dst[n][k] = *(const LAS bf16x8*)(lds + PG8_SB(b, h) + boff + n * 2048 + k * 1024); } while (0)
; #define PG8_MMA(ai, bj, At, Bt) do { __builtin_amdgcn_s_setprio(1); _Pragma("unroll") for (int m = 0; m < 4; ++m) _Pragma("unroll") for (int n = 0; n < 2; ++n) _Pragma("unroll") for (int k = 0; k < 2; ++k) \
;         acc[ai][bj][m][n] = __builtin_amdgcn_mfma_f32_16x16x32_bf16(Bt[n][k], At[m][k], acc[ai][bj][m][n], 0, 0, 0); __builtin_amdgcn_s_setprio(0); } while (0)
; #define PG8_WAIT_V(n) asm volatile("s_waitcnt vmcnt(" #n ")" ::: "memory")
; #define PG8_WAIT_L(n) asm volatile("s_waitcnt lgkmcnt(" #n ")" ::: "memory")
; #define PG8_BAR __builtin_amdgcn_s_barrier()
; #define PG8_SCHED __builtin_amdgcn_sched_barrier(0)
; template <class Epi>
; __device__ __forceinline__ void gemm_phase(LAS unsigned char* lds, const Gemm g, const StaticOrder& S, const Epi& E) {
;     ...
;             PG8_WAIT_V(8); PG8_WAIT_L(0); PG8_BAR; PG8_MMA(1, 0, At, B0); PG8_MMA(1, 1, At, B1); PG8_BAR; PG8_SCHED;
;             PG8_LDB(B0, 1, 0); PG8_LDB(B1, 1, 1); PG8_SCHED; PG8_LDA(At, 1, 0); PG8_STAGE(PG8_SA(0, 1), a2 + hstepA, voffA);
;             PG8_WAIT_V(8); PG8_WAIT_L(0); PG8_BAR; PG8_MMA(0, 0, At, B0); PG8_MMA(0, 1, At, B1); PG8_BAR; PG8_SCHED;
;             PG8_LDA(At, 1, 1); PG8_STAGE(PG8_SB(1, 0), b3, voffB); PG8_STAGE(PG8_SB(1, 1), b3 + hstepB, voffB); PG8_STAGE(PG8_SA(1, 0), a3, voffA);
;             PG8_WAIT_V(8); PG8_WAIT_L(0); PG8_BAR; PG8_MMA(1, 0, At, B0); PG8_MMA(1, 1, At, B1); PG8_BAR; PG8_SCHED;
	s_setprio 1
	s_waitcnt lgkmcnt(0)
	v_mfma_f32_16x16x32_bf16 v[76:79], v[0:3], v[160:163], v[76:79]
	v_mfma_f32_16x16x32_bf16 v[72:75], v[8:11], v[160:163], v[72:75]
	v_mfma_f32_16x16x32_bf16 v[60:63], v[0:3], v[168:171], v[60:63]
	v_mfma_f32_16x16x32_bf16 v[56:59], v[8:11], v[168:171], v[56:59]
	v_mfma_f32_16x16x32_bf16 v[44:47], v[0:3], v[196:199], v[44:47]
	v_mfma_f32_16x16x32_bf16 v[40:43], v[8:11], v[196:199], v[40:43]
	v_mfma_f32_16x16x32_bf16 v[0:3], v[0:3], v[204:207], v[28:31]
	v_mfma_f32_16x16x32_bf16 v[76:79], v[4:7], v[164:167], v[76:79]
	v_mfma_f32_16x16x32_bf16 v[72:75], v[12:15], v[164:167], v[72:75]
	v_mfma_f32_16x16x32_bf16 v[60:63], v[4:7], v[172:175], v[60:63]
	v_mfma_f32_16x16x32_bf16 v[56:59], v[12:15], v[172:175], v[56:59]
	v_mfma_f32_16x16x32_bf16 v[44:47], v[4:7], v[200:203], v[44:47]
	v_mfma_f32_16x16x32_bf16 v[40:43], v[12:15], v[200:203], v[40:43]
	v_mfma_f32_16x16x32_bf16 v[0:3], v[4:7], v[208:211], v[0:3]
	v_mfma_f32_16x16x32_bf16 v[4:7], v[8:11], v[204:207], v[20:23]
	v_mfma_f32_16x16x32_bf16 v[4:7], v[12:15], v[208:211], v[4:7]
	s_setprio 0
	s_setprio 1
	v_mfma_f32_16x16x32_bf16 v[20:23], v[144:147], v[168:171], v[52:55]
	v_mfma_f32_16x16x32_bf16 v[52:55], v[148:151], v[172:175], v[20:23]
	v_mfma_f32_16x16x32_bf16 v[20:23], v[152:155], v[168:171], v[48:51]
	v_mfma_f32_16x16x32_bf16 v[48:51], v[156:159], v[172:175], v[20:23]
	v_mfma_f32_16x16x32_bf16 v[20:23], v[144:147], v[196:199], v[36:39]
	v_mfma_f32_16x16x32_bf16 v[36:39], v[148:151], v[200:203], v[20:23]
	v_mfma_f32_16x16x32_bf16 v[20:23], v[152:155], v[196:199], v[32:35]
	v_mfma_f32_16x16x32_bf16 v[32:35], v[156:159], v[200:203], v[20:23]
	v_mfma_f32_16x16x32_bf16 v[20:23], v[144:147], v[204:207], v[24:27]
	v_mfma_f32_16x16x32_bf16 v[16:19], v[152:155], v[204:207], v[16:19]
	v_mfma_f32_16x16x32_bf16 v[8:11], v[144:147], v[160:163], v[68:71]
	v_mfma_f32_16x16x32_bf16 v[12:15], v[152:155], v[160:163], v[64:67]
	v_mfma_f32_16x16x32_bf16 v[24:27], v[148:151], v[208:211], v[20:23]
	v_mfma_f32_16x16x32_bf16 v[16:19], v[156:159], v[208:211], v[16:19]
	v_mfma_f32_16x16x32_bf16 v[8:11], v[148:151], v[164:167], v[8:11]
	v_mfma_f32_16x16x32_bf16 v[12:15], v[156:159], v[164:167], v[12:15]
	s_setprio 0
	s_barrier
	s_add_i32 s86, 0, 0x18000
	s_add_i32 s87, 0, 0x1c000
	v_add_u32_e32 v68, s86, v229
	v_add_u32_e32 v156, s87, v229
	ds_read_b128 v[20:23], v68
	ds_read_b128 v[28:31], v68 offset:1024
	ds_read_b128 v[64:67], v68 offset:2048
	ds_read_b128 v[68:71], v68 offset:3072
	ds_read_b128 v[144:147], v156
	ds_read_b128 v[148:151], v156 offset:1024
	ds_read_b128 v[152:155], v156 offset:2048
	ds_read_b128 v[156:159], v156 offset:3072
	s_add_u32 s62, s62, 0x40000
	s_addc_u32 s63, s63, 0
	s_mov_b32 m0, s70
	v_lshl_add_u64 v[220:221], s[62:63], 0, v[178:179]
	ds_read_b128 v[160:163], v232 offset:32768
	ds_read_b128 v[164:167], v232 offset:33792
	ds_read_b128 v[168:171], v232 offset:34816
	ds_read_b128 v[172:175], v232 offset:35840
	ds_read_b128 v[196:199], v232 offset:36864
	ds_read_b128 v[200:203], v232 offset:37888
	ds_read_b128 v[204:207], v232 offset:38912
	ds_read_b128 v[208:211], v232 offset:39936
	global_load_lds_dwordx4 v[220:221], off
	v_lshl_add_u64 v[220:221], s[62:63], 0, v[182:183]
	s_mov_b32 m0, s71
	s_nop 0
	global_load_lds_dwordx4 v[220:221], off
	s_waitcnt vmcnt(8)
	s_waitcnt lgkmcnt(0)
	s_barrier
	s_setprio 1
	s_waitcnt lgkmcnt(0)
	v_mfma_f32_16x16x32_bf16 v[140:143], v[20:23], v[160:163], v[140:143]
	v_mfma_f32_16x16x32_bf16 v[132:135], v[64:67], v[160:163], v[132:135]
	v_mfma_f32_16x16x32_bf16 v[124:127], v[20:23], v[168:171], v[124:127]
	v_mfma_f32_16x16x32_bf16 v[120:123], v[64:67], v[168:171], v[120:123]
	v_mfma_f32_16x16x32_bf16 v[108:111], v[20:23], v[196:199], v[108:111]
	v_mfma_f32_16x16x32_bf16 v[104:107], v[64:67], v[196:199], v[104:107]
	v_mfma_f32_16x16x32_bf16 v[92:95], v[20:23], v[204:207], v[92:95]
	v_mfma_f32_16x16x32_bf16 v[88:91], v[64:67], v[204:207], v[88:91]
	v_mfma_f32_16x16x32_bf16 v[140:143], v[28:31], v[164:167], v[140:143]
	v_mfma_f32_16x16x32_bf16 v[132:135], v[68:71], v[164:167], v[132:135]
	v_mfma_f32_16x16x32_bf16 v[124:127], v[28:31], v[172:175], v[124:127]
	v_mfma_f32_16x16x32_bf16 v[120:123], v[68:71], v[172:175], v[120:123]
	v_mfma_f32_16x16x32_bf16 v[108:111], v[28:31], v[200:203], v[108:111]
	v_mfma_f32_16x16x32_bf16 v[104:107], v[68:71], v[200:203], v[104:107]
	v_mfma_f32_16x16x32_bf16 v[92:95], v[28:31], v[208:211], v[92:95]
	v_mfma_f32_16x16x32_bf16 v[88:91], v[68:71], v[208:211], v[88:91]
	s_setprio 0
	s_setprio 1
	v_mfma_f32_16x16x32_bf16 v[136:139], v[144:147], v[160:163], v[136:139]
	v_mfma_f32_16x16x32_bf16 v[128:131], v[152:155], v[160:163], v[128:131]
	v_mfma_f32_16x16x32_bf16 v[116:119], v[144:147], v[168:171], v[116:119]
	v_mfma_f32_16x16x32_bf16 v[112:115], v[152:155], v[168:171], v[112:115]
	v_mfma_f32_16x16x32_bf16 v[100:103], v[144:147], v[196:199], v[100:103]
	v_mfma_f32_16x16x32_bf16 v[96:99], v[152:155], v[196:199], v[96:99]
	v_mfma_f32_16x16x32_bf16 v[84:87], v[144:147], v[204:207], v[84:87]
	v_mfma_f32_16x16x32_bf16 v[80:83], v[152:155], v[204:207], v[80:83]
	v_mfma_f32_16x16x32_bf16 v[136:139], v[148:151], v[164:167], v[136:139]
	v_mfma_f32_16x16x32_bf16 v[128:131], v[156:159], v[164:167], v[128:131]
	v_mfma_f32_16x16x32_bf16 v[116:119], v[148:151], v[172:175], v[116:119]
	v_mfma_f32_16x16x32_bf16 v[112:115], v[156:159], v[172:175], v[112:115]
	v_mfma_f32_16x16x32_bf16 v[100:103], v[148:151], v[200:203], v[100:103]
	v_mfma_f32_16x16x32_bf16 v[96:99], v[156:159], v[200:203], v[96:99]
	v_mfma_f32_16x16x32_bf16 v[84:87], v[148:151], v[208:211], v[84:87]
	v_mfma_f32_16x16x32_bf16 v[80:83], v[156:159], v[208:211], v[80:83]
	s_setprio 0
	s_barrier
; #define PG8_STAGE(bufoff, gbase, voff) do { _Pragma("unroll") for (int _i = 0; _i < 2; ++_i) \
;         __builtin_amdgcn_global_load_lds((const unsigned*)((const char*)(gbase) + (voff)[_i]), (LAS unsigned*)(lds + (bufoff) + ldsw + _i * 8192), 16, 0, 0); } while (0)
; #define PG8_LDA(dst, b, h) do { _Pragma("unroll") for (int m = 0; m < 4; ++m) _Pragma("unroll") for (int k = 0; k < 2; ++k) dst[m][k] = *(const LAS bf16x8*)(lds + PG8_SA(b, h) + aoff + m * 2048 + k * 1024); } while (0)
; #define PG8_MMA(ai, bj, At, Bt) do { __builtin_amdgcn_s_setprio(1); _Pragma("unroll") for (int m = 0; m < 4; ++m) _Pragma("unroll") for (int n = 0; n < 2; ++n) _Pragma("unroll") for (int k = 0; k < 2; ++k) \
;         acc[ai][bj][m][n] = __builtin_amdgcn_mfma_f32_16x16x32_bf16(Bt[n][k], At[m][k], acc[ai][bj][m][n], 0, 0, 0); __builtin_amdgcn_s_setprio(0); } while (0)
; #define PG8_WAIT_V(n) asm volatile("s_waitcnt vmcnt(" #n ")" ::: "memory")
; #define PG8_WAIT_L(n) asm volatile("s_waitcnt lgkmcnt(" #n ")" ::: "memory")
; #define PG8_BAR __builtin_amdgcn_s_barrier()
; #define PG8_SCHED __builtin_amdgcn_sched_barrier(0)
; template <class Epi>
; __device__ __forceinline__ void gemm_phase(LAS unsigned char* lds, const Gemm g, const StaticOrder& S, const Epi& E) {
;     ...
;             PG8_LDA(At, 1, 1); PG8_STAGE(PG8_SB(1, 0), b3, voffB); PG8_STAGE(PG8_SB(1, 1), b3 + hstepB, voffB); PG8_STAGE(PG8_SA(1, 0), a3, voffA);
;             PG8_WAIT_V(8); PG8_WAIT_L(0); PG8_BAR; PG8_MMA(1, 0, At, B0); PG8_MMA(1, 1, At, B1); PG8_BAR; PG8_SCHED;
;         }
;         if (wr == 0) PG8_BAR;
	s_add_i32 s62, s86, s65
	v_lshl_add_u64 v[212:213], v[212:213], 0, s[16:17]
	s_mov_b32 m0, s62
	ds_read_b128 v[160:163], v232 offset:49152
	ds_read_b128 v[164:167], v232 offset:50176
	ds_read_b128 v[168:171], v232 offset:51200
	ds_read_b128 v[172:175], v232 offset:52224
	ds_read_b128 v[196:199], v232 offset:53248
	ds_read_b128 v[200:203], v232 offset:54272
	ds_read_b128 v[204:207], v232 offset:55296
	ds_read_b128 v[208:211], v232 offset:56320
	global_load_lds_dwordx4 v[212:213], off
	s_add_i32 m0, s62, 0x2000
	s_add_u32 s56, s56, 0x40080
	v_lshl_add_u64 v[212:213], v[214:215], 0, s[16:17]
	s_addc_u32 s57, s57, 0
	s_add_i32 s62, s87, s65
	global_load_lds_dwordx4 v[212:213], off
	v_lshl_add_u64 v[212:213], s[56:57], 0, v[180:181]
	s_mov_b32 m0, s62
	s_nop 0
	global_load_lds_dwordx4 v[212:213], off
	v_lshl_add_u64 v[212:213], s[56:57], 0, v[184:185]
	s_add_i32 m0, s62, 0x2000
	s_nop 0
	global_load_lds_dwordx4 v[212:213], off
	v_lshl_add_u64 v[212:213], v[216:217], 0, s[16:17]
	s_mov_b32 m0, s76
	s_nop 0
	global_load_lds_dwordx4 v[212:213], off
	v_lshl_add_u64 v[212:213], v[218:219], 0, s[16:17]
	s_mov_b32 m0, s77
	s_nop 0
	global_load_lds_dwordx4 v[212:213], off
	s_waitcnt vmcnt(8)
	s_waitcnt lgkmcnt(0)
	s_barrier
	s_setprio 1
	s_waitcnt lgkmcnt(0)
	v_mfma_f32_16x16x32_bf16 v[76:79], v[20:23], v[160:163], v[76:79]
	v_mfma_f32_16x16x32_bf16 v[60:63], v[20:23], v[168:171], v[60:63]
	v_mfma_f32_16x16x32_bf16 v[44:47], v[20:23], v[196:199], v[44:47]
	v_mfma_f32_16x16x32_bf16 v[0:3], v[20:23], v[204:207], v[0:3]
	v_mfma_f32_16x16x32_bf16 v[76:79], v[28:31], v[164:167], v[76:79]
	v_mfma_f32_16x16x32_bf16 v[72:75], v[64:67], v[160:163], v[72:75]
	v_mfma_f32_16x16x32_bf16 v[60:63], v[28:31], v[172:175], v[60:63]
	v_mfma_f32_16x16x32_bf16 v[56:59], v[64:67], v[168:171], v[56:59]
	v_mfma_f32_16x16x32_bf16 v[44:47], v[28:31], v[200:203], v[44:47]
	v_mfma_f32_16x16x32_bf16 v[40:43], v[64:67], v[196:199], v[40:43]
	v_mfma_f32_16x16x32_bf16 v[28:31], v[28:31], v[208:211], v[0:3]
	v_mfma_f32_16x16x32_bf16 v[0:3], v[64:67], v[204:207], v[4:7]
	v_mfma_f32_16x16x32_bf16 v[72:75], v[68:71], v[164:167], v[72:75]
	v_mfma_f32_16x16x32_bf16 v[56:59], v[68:71], v[172:175], v[56:59]
	v_mfma_f32_16x16x32_bf16 v[40:43], v[68:71], v[200:203], v[40:43]
	v_mfma_f32_16x16x32_bf16 v[20:23], v[68:71], v[208:211], v[0:3]
	s_setprio 0
	s_setprio 1
	v_mfma_f32_16x16x32_bf16 v[0:3], v[144:147], v[160:163], v[8:11]
	v_mfma_f32_16x16x32_bf16 v[68:71], v[148:151], v[164:167], v[0:3]
	v_mfma_f32_16x16x32_bf16 v[0:3], v[152:155], v[160:163], v[12:15]
	v_mfma_f32_16x16x32_bf16 v[64:67], v[156:159], v[164:167], v[0:3]
	v_mfma_f32_16x16x32_bf16 v[0:3], v[144:147], v[168:171], v[52:55]
	v_mfma_f32_16x16x32_bf16 v[52:55], v[148:151], v[172:175], v[0:3]
	v_mfma_f32_16x16x32_bf16 v[0:3], v[152:155], v[168:171], v[48:51]
	v_mfma_f32_16x16x32_bf16 v[48:51], v[156:159], v[172:175], v[0:3]
	v_mfma_f32_16x16x32_bf16 v[0:3], v[144:147], v[196:199], v[36:39]
	v_mfma_f32_16x16x32_bf16 v[36:39], v[148:151], v[200:203], v[0:3]
	v_mfma_f32_16x16x32_bf16 v[0:3], v[152:155], v[196:199], v[32:35]
	v_mfma_f32_16x16x32_bf16 v[32:35], v[156:159], v[200:203], v[0:3]
	v_mfma_f32_16x16x32_bf16 v[0:3], v[144:147], v[204:207], v[24:27]
	v_mfma_f32_16x16x32_bf16 v[24:27], v[148:151], v[208:211], v[0:3]
	v_mfma_f32_16x16x32_bf16 v[0:3], v[152:155], v[204:207], v[16:19]
	v_mfma_f32_16x16x32_bf16 v[16:19], v[156:159], v[208:211], v[0:3]
	s_setprio 0
	s_barrier
	s_add_i32 s85, s85, 2
	s_add_u32 s54, s54, 0x100
	s_addc_u32 s55, s55, 0
	s_add_u32 s83, s83, 0x100
	s_addc_u32 s84, s84, 0
	s_cmp_gt_u32 s85, 13
	s_cbranch_scc0 .LBB0_1018
	s_cmp_eq_u64 s[4:5], 0
	s_cselect_b32 s99, 1, 0
	s_and_b64 vcc, exec, s[18:19]
	s_cbranch_vccz .LBB0_1021
	s_barrier

; #define EPI_PACK8(v0, v1) (u32x4){pk2((v0)[0], (v0)[1]), pk2((v0)[2], (v0)[3]), pk2((v1)[0], (v1)[1]), pk2((v1)[2], (v1)[3])}
;     __device__ __forceinline__ void operator()(AccRef acc, const Unit& u, int wr, int wc, int fr, int fq) const {
;     ...
;             else {
; #pragma unroll
;                 for (int bj = 0; bj < 2; ++bj) { acc[ai][bj][m][0] = acc[ai][bj][m][0] * r; acc[ai][bj][m][1] = acc[ai][bj][m][1] * r; } }
; #pragma unroll
;             for (int bj = 0; bj < 2; ++bj) *(u32x4*)(O + (size_t)row * RET_QKV + EPI_COL(bj)) = EPI_PACK8(acc[ai][bj][m][0], acc[ai][bj][m][1]); }
.LBB0_1029:
	v_lshl_add_u32 v144, s52, 8, v222
	v_lshlrev_b64 v[132:133], 13, v[220:221]
	v_lshl_add_u64 v[132:133], s[26:27], 0, v[132:133]
	v_ashrrev_i32_e32 v145, 31, v144
	v_cvt_pk_bf16_f32 v128, v160, v161
	v_cvt_pk_bf16_f32 v129, v162, v163
	v_cvt_pk_bf16_f32 v130, v168, v169
	v_cvt_pk_bf16_f32 v131, v170, v171
	v_lshl_add_u64 v[132:133], v[144:145], 1, v[132:133]
	s_cmp_lg_u32 s99, 0
	s_cbranch_scc1 .Lwt1018_24933
	global_store_dwordx4 v[132:133], v[128:131], off
	s_branch .Lwj1018_24933
.Lwt1018_24933:
	global_store_dwordx4 v[132:133], v[128:131], off sc1
.Lwj1018_24933:
	s_and_b64 vcc, exec, s[6:7]
	s_mov_b64 s[52:53], -1
	v_cvt_pk_bf16_f32 v128, v164, v165
	v_cvt_pk_bf16_f32 v129, v166, v167
	v_cvt_pk_bf16_f32 v130, v172, v173
	v_cvt_pk_bf16_f32 v131, v174, v175
	s_cmp_lg_u32 s99, 0
	s_cbranch_scc1 .Lwt1018_24948
	global_store_dwordx4 v[132:133], v[128:131], off offset:256
	s_branch .Lwj1018_24948
.Lwt1018_24948:
	global_store_dwordx4 v[132:133], v[128:131], off offset:256 sc1
.Lwj1018_24948:
	s_cbranch_vccnz .LBB0_1031
	s_nop 0
	v_pk_mul_f32 v[128:129], v[124:125], v[218:219] op_sel:[0,1]
	v_pk_mul_f32 v[130:131], v[126:127], v[218:219] op_sel:[0,1]
	v_pk_mul_f32 v[136:137], v[120:121], v[218:219] op_sel:[0,1]
	v_pk_mul_f32 v[138:139], v[122:123], v[218:219] op_sel:[0,1]
	v_pk_mul_f32 v[132:133], v[116:117], v[218:219] op_sel:[0,1]
	v_pk_mul_f32 v[134:135], v[118:119], v[218:219] op_sel:[0,1]
	v_pk_mul_f32 v[140:141], v[112:113], v[218:219] op_sel:[0,1]
	v_pk_mul_f32 v[142:143], v[114:115], v[218:219] op_sel:[0,1]
	s_mov_b64 s[52:53], 0

; #define EPI_PACK8(v0, v1) (u32x4){pk2((v0)[0], (v0)[1]), pk2((v0)[2], (v0)[3]), pk2((v1)[0], (v1)[1]), pk2((v1)[2], (v1)[3])}
;     __device__ __forceinline__ void operator()(AccRef acc, const Unit& u, int wr, int wc, int fr, int fq) const {
;     ...
;             else {
; #pragma unroll
;                 for (int bj = 0; bj < 2; ++bj) { acc[ai][bj][m][0] = acc[ai][bj][m][0] * r; acc[ai][bj][m][1] = acc[ai][bj][m][1] * r; } }
; #pragma unroll
;             for (int bj = 0; bj < 2; ++bj) *(u32x4*)(O + (size_t)row * RET_QKV + EPI_COL(bj)) = EPI_PACK8(acc[ai][bj][m][0], acc[ai][bj][m][1]); }
.LBB0_1033:
	v_lshlrev_b64 v[116:117], 13, v[216:217]
	v_lshl_add_u64 v[116:117], s[26:27], 0, v[116:117]
	v_cvt_pk_bf16_f32 v112, v128, v129
	v_cvt_pk_bf16_f32 v113, v130, v131
	v_cvt_pk_bf16_f32 v114, v136, v137
	v_cvt_pk_bf16_f32 v115, v138, v139
	v_lshl_add_u64 v[116:117], v[144:145], 1, v[116:117]
	s_cmp_lg_u32 s99, 0
	s_cbranch_scc1 .Lwt1018_25030
	global_store_dwordx4 v[116:117], v[112:115], off
	s_branch .Lwj1018_25030
.Lwt1018_25030:
	global_store_dwordx4 v[116:117], v[112:115], off sc1
.Lwj1018_25030:
	s_and_b64 vcc, exec, s[6:7]
	s_mov_b64 s[52:53], -1
	v_cvt_pk_bf16_f32 v112, v132, v133
	v_cvt_pk_bf16_f32 v113, v134, v135
	v_cvt_pk_bf16_f32 v114, v140, v141
	v_cvt_pk_bf16_f32 v115, v142, v143
	s_cmp_lg_u32 s99, 0
	s_cbranch_scc1 .Lwt1018_25045
	global_store_dwordx4 v[116:117], v[112:115], off offset:256
	s_branch .Lwj1018_25045
.Lwt1018_25045:
	global_store_dwordx4 v[116:117], v[112:115], off offset:256 sc1
.Lwj1018_25045:
	s_cbranch_vccnz .LBB0_1035
	s_nop 0
	v_pk_mul_f32 v[114:115], v[110:111], v[212:213] op_sel_hi:[1,0]
	v_pk_mul_f32 v[112:113], v[108:109], v[212:213] op_sel_hi:[1,0]
	v_pk_mul_f32 v[122:123], v[106:107], v[212:213] op_sel_hi:[1,0]
	v_pk_mul_f32 v[120:121], v[104:105], v[212:213] op_sel_hi:[1,0]
	v_pk_mul_f32 v[118:119], v[102:103], v[212:213] op_sel_hi:[1,0]
	v_pk_mul_f32 v[116:117], v[100:101], v[212:213] op_sel_hi:[1,0]
	v_pk_mul_f32 v[126:127], v[98:99], v[212:213] op_sel_hi:[1,0]
	v_pk_mul_f32 v[124:125], v[96:97], v[212:213] op_sel_hi:[1,0]
	s_mov_b64 s[52:53], 0

; #define EPI_PACK8(v0, v1) (u32x4){pk2((v0)[0], (v0)[1]), pk2((v0)[2], (v0)[3]), pk2((v1)[0], (v1)[1]), pk2((v1)[2], (v1)[3])}
;     __device__ __forceinline__ void operator()(AccRef acc, const Unit& u, int wr, int wc, int fr, int fq) const {
;     ...
;             else {
; #pragma unroll
;                 for (int bj = 0; bj < 2; ++bj) { acc[ai][bj][m][0] = acc[ai][bj][m][0] * r; acc[ai][bj][m][1] = acc[ai][bj][m][1] * r; } }
; #pragma unroll
;             for (int bj = 0; bj < 2; ++bj) *(u32x4*)(O + (size_t)row * RET_QKV + EPI_COL(bj)) = EPI_PACK8(acc[ai][bj][m][0], acc[ai][bj][m][1]); }
.LBB0_1037:
	v_lshlrev_b64 v[100:101], 13, v[214:215]
	v_lshl_add_u64 v[100:101], s[26:27], 0, v[100:101]
	v_cvt_pk_bf16_f32 v96, v112, v113
	v_cvt_pk_bf16_f32 v97, v114, v115
	v_cvt_pk_bf16_f32 v98, v120, v121
	v_cvt_pk_bf16_f32 v99, v122, v123
	v_lshl_add_u64 v[100:101], v[144:145], 1, v[100:101]
	s_cmp_lg_u32 s99, 0
	s_cbranch_scc1 .Lwt1018_25127
	global_store_dwordx4 v[100:101], v[96:99], off
	s_branch .Lwj1018_25127
.Lwt1018_25127:
	global_store_dwordx4 v[100:101], v[96:99], off sc1
.Lwj1018_25127:
	s_and_b64 vcc, exec, s[6:7]
	s_mov_b64 s[52:53], -1
	v_cvt_pk_bf16_f32 v96, v116, v117
	v_cvt_pk_bf16_f32 v97, v118, v119
	v_cvt_pk_bf16_f32 v98, v124, v125
	v_cvt_pk_bf16_f32 v99, v126, v127
	s_cmp_lg_u32 s99, 0
	s_cbranch_scc1 .Lwt1018_25142
	global_store_dwordx4 v[100:101], v[96:99], off offset:256
	s_branch .Lwj1018_25142
.Lwt1018_25142:
	global_store_dwordx4 v[100:101], v[96:99], off offset:256 sc1
.Lwj1018_25142:
	s_cbranch_vccnz .LBB0_1039
	v_mov_b32_e32 v108, v213
	v_pk_mul_f32 v[98:99], v[94:95], v[108:109] op_sel_hi:[1,0]
	v_pk_mul_f32 v[96:97], v[92:93], v[108:109] op_sel_hi:[1,0]
	v_pk_mul_f32 v[106:107], v[90:91], v[108:109] op_sel_hi:[1,0]
	v_pk_mul_f32 v[104:105], v[88:89], v[108:109] op_sel_hi:[1,0]
	v_pk_mul_f32 v[102:103], v[86:87], v[108:109] op_sel_hi:[1,0]
	v_pk_mul_f32 v[100:101], v[84:85], v[108:109] op_sel_hi:[1,0]
	v_pk_mul_f32 v[110:111], v[82:83], v[108:109] op_sel_hi:[1,0]
	v_pk_mul_f32 v[108:109], v[80:81], v[108:109] op_sel_hi:[1,0]
	s_mov_b64 s[52:53], 0

; #define EPI_PACK8(v0, v1) (u32x4){pk2((v0)[0], (v0)[1]), pk2((v0)[2], (v0)[3]), pk2((v1)[0], (v1)[1]), pk2((v1)[2], (v1)[3])}
;     __device__ __forceinline__ void operator()(AccRef acc, const Unit& u, int wr, int wc, int fr, int fq) const {
;     ...
;             else {
; #pragma unroll
;                 for (int bj = 0; bj < 2; ++bj) { acc[ai][bj][m][0] = acc[ai][bj][m][0] * r; acc[ai][bj][m][1] = acc[ai][bj][m][1] * r; } }
; #pragma unroll
;             for (int bj = 0; bj < 2; ++bj) *(u32x4*)(O + (size_t)row * RET_QKV + EPI_COL(bj)) = EPI_PACK8(acc[ai][bj][m][0], acc[ai][bj][m][1]); }
.LBB0_1041:
	v_lshlrev_b64 v[84:85], 13, v[210:211]
	v_lshl_add_u64 v[84:85], s[26:27], 0, v[84:85]
	v_cvt_pk_bf16_f32 v80, v96, v97
	v_cvt_pk_bf16_f32 v81, v98, v99
	v_cvt_pk_bf16_f32 v82, v104, v105
	v_cvt_pk_bf16_f32 v83, v106, v107
	v_lshl_add_u64 v[84:85], v[144:145], 1, v[84:85]
	s_cmp_lg_u32 s99, 0
	s_cbranch_scc1 .Lwt1018_25225
	global_store_dwordx4 v[84:85], v[80:83], off
	s_branch .Lwj1018_25225
.Lwt1018_25225:
	global_store_dwordx4 v[84:85], v[80:83], off sc1
.Lwj1018_25225:
	s_and_b64 vcc, exec, s[6:7]
	s_mov_b64 s[52:53], -1
	v_cvt_pk_bf16_f32 v80, v100, v101
	v_cvt_pk_bf16_f32 v81, v102, v103
	v_cvt_pk_bf16_f32 v82, v108, v109
	v_cvt_pk_bf16_f32 v83, v110, v111
	s_cmp_lg_u32 s99, 0
	s_cbranch_scc1 .Lwt1018_25240
	global_store_dwordx4 v[84:85], v[80:83], off offset:256
	s_branch .Lwj1018_25240
.Lwt1018_25240:
	global_store_dwordx4 v[84:85], v[80:83], off offset:256 sc1
.Lwj1018_25240:
	s_cbranch_vccnz .LBB0_1043
	s_nop 0
	v_pk_mul_f32 v[82:83], v[78:79], v[204:205] op_sel_hi:[1,0]
	v_pk_mul_f32 v[80:81], v[76:77], v[204:205] op_sel_hi:[1,0]
	v_pk_mul_f32 v[90:91], v[74:75], v[204:205] op_sel_hi:[1,0]
	v_pk_mul_f32 v[88:89], v[72:73], v[204:205] op_sel_hi:[1,0]
	v_pk_mul_f32 v[86:87], v[70:71], v[204:205] op_sel_hi:[1,0]
	v_pk_mul_f32 v[84:85], v[68:69], v[204:205] op_sel_hi:[1,0]
	v_pk_mul_f32 v[94:95], v[66:67], v[204:205] op_sel_hi:[1,0]
	v_pk_mul_f32 v[92:93], v[64:65], v[204:205] op_sel_hi:[1,0]
	s_mov_b64 s[52:53], 0

; #define EPI_PACK8(v0, v1) (u32x4){pk2((v0)[0], (v0)[1]), pk2((v0)[2], (v0)[3]), pk2((v1)[0], (v1)[1]), pk2((v1)[2], (v1)[3])}
;     __device__ __forceinline__ void operator()(AccRef acc, const Unit& u, int wr, int wc, int fr, int fq) const {
;     ...
;             else {
; #pragma unroll
;                 for (int bj = 0; bj < 2; ++bj) { acc[ai][bj][m][0] = acc[ai][bj][m][0] * r; acc[ai][bj][m][1] = acc[ai][bj][m][1] * r; } }
; #pragma unroll
;             for (int bj = 0; bj < 2; ++bj) *(u32x4*)(O + (size_t)row * RET_QKV + EPI_COL(bj)) = EPI_PACK8(acc[ai][bj][m][0], acc[ai][bj][m][1]); }
.LBB0_1045:
	v_lshlrev_b64 v[68:69], 13, v[206:207]
	v_lshl_add_u64 v[68:69], s[26:27], 0, v[68:69]
	v_cvt_pk_bf16_f32 v64, v80, v81
	v_cvt_pk_bf16_f32 v65, v82, v83
	v_cvt_pk_bf16_f32 v66, v88, v89
	v_cvt_pk_bf16_f32 v67, v90, v91
	v_lshl_add_u64 v[68:69], v[144:145], 1, v[68:69]
	s_cmp_lg_u32 s99, 0
	s_cbranch_scc1 .Lwt1018_25322
	global_store_dwordx4 v[68:69], v[64:67], off
	s_branch .Lwj1018_25322
.Lwt1018_25322:
	global_store_dwordx4 v[68:69], v[64:67], off sc1
.Lwj1018_25322:
	s_and_b64 vcc, exec, s[6:7]
	s_mov_b64 s[52:53], -1
	v_cvt_pk_bf16_f32 v64, v84, v85
	v_cvt_pk_bf16_f32 v65, v86, v87
	v_cvt_pk_bf16_f32 v66, v92, v93
	v_cvt_pk_bf16_f32 v67, v94, v95
	s_cmp_lg_u32 s99, 0
	s_cbranch_scc1 .Lwt1018_25337
	global_store_dwordx4 v[68:69], v[64:67], off offset:256
	s_branch .Lwj1018_25337
.Lwt1018_25337:
	global_store_dwordx4 v[68:69], v[64:67], off offset:256 sc1
.Lwj1018_25337:
	s_cbranch_vccnz .LBB0_1047
	v_mov_b32_e32 v76, v205
	v_pk_mul_f32 v[66:67], v[62:63], v[76:77] op_sel_hi:[1,0]
	v_pk_mul_f32 v[64:65], v[60:61], v[76:77] op_sel_hi:[1,0]
	v_pk_mul_f32 v[74:75], v[58:59], v[76:77] op_sel_hi:[1,0]
	v_pk_mul_f32 v[72:73], v[56:57], v[76:77] op_sel_hi:[1,0]
	v_pk_mul_f32 v[70:71], v[54:55], v[76:77] op_sel_hi:[1,0]
	v_pk_mul_f32 v[68:69], v[52:53], v[76:77] op_sel_hi:[1,0]
	v_pk_mul_f32 v[78:79], v[50:51], v[76:77] op_sel_hi:[1,0]
	v_pk_mul_f32 v[76:77], v[48:49], v[76:77] op_sel_hi:[1,0]
	s_mov_b64 s[52:53], 0

; #define EPI_PACK8(v0, v1) (u32x4){pk2((v0)[0], (v0)[1]), pk2((v0)[2], (v0)[3]), pk2((v1)[0], (v1)[1]), pk2((v1)[2], (v1)[3])}
;     __device__ __forceinline__ void operator()(AccRef acc, const Unit& u, int wr, int wc, int fr, int fq) const {
;     ...
;             for (int bj = 0; bj < 2; ++bj) *(u32x4*)(O + (size_t)row * RET_QKV + EPI_COL(bj)) = EPI_PACK8(acc[ai][bj][m][0], acc[ai][bj][m][1]); }
.LBB0_1049:
	v_lshlrev_b64 v[52:53], 13, v[202:203]
	v_lshl_add_u64 v[52:53], s[26:27], 0, v[52:53]
	v_cvt_pk_bf16_f32 v48, v64, v65
	v_cvt_pk_bf16_f32 v49, v66, v67
	v_cvt_pk_bf16_f32 v50, v72, v73
	v_cvt_pk_bf16_f32 v51, v74, v75
	v_lshl_add_u64 v[52:53], v[144:145], 1, v[52:53]
	s_cmp_lg_u32 s99, 0
	s_cbranch_scc1 .Lwt1018_25420
	global_store_dwordx4 v[52:53], v[48:51], off
	s_branch .Lwj1018_25420

; #define EPI_PACK8(v0, v1) (u32x4){pk2((v0)[0], (v0)[1]), pk2((v0)[2], (v0)[3]), pk2((v1)[0], (v1)[1]), pk2((v1)[2], (v1)[3])}
;     __device__ __forceinline__ void operator()(AccRef acc, const Unit& u, int wr, int wc, int fr, int fq) const {
;     ...
;             else {
; #pragma unroll
;                 for (int bj = 0; bj < 2; ++bj) { acc[ai][bj][m][0] = acc[ai][bj][m][0] * r; acc[ai][bj][m][1] = acc[ai][bj][m][1] * r; } }
; #pragma unroll
;             for (int bj = 0; bj < 2; ++bj) *(u32x4*)(O + (size_t)row * RET_QKV + EPI_COL(bj)) = EPI_PACK8(acc[ai][bj][m][0], acc[ai][bj][m][1]); }
.Lwj1018_25420:
	s_and_b64 vcc, exec, s[6:7]
	s_mov_b64 s[52:53], -1
	v_cvt_pk_bf16_f32 v48, v68, v69
	v_cvt_pk_bf16_f32 v49, v70, v71
	v_cvt_pk_bf16_f32 v50, v76, v77
	v_cvt_pk_bf16_f32 v51, v78, v79
	s_cmp_lg_u32 s99, 0
	s_cbranch_scc1 .Lwt1018_25435
	global_store_dwordx4 v[52:53], v[48:51], off offset:256
	s_branch .Lwj1018_25435
.Lwt1018_25435:
	global_store_dwordx4 v[52:53], v[48:51], off offset:256 sc1
.Lwj1018_25435:
	s_cbranch_vccnz .LBB0_1051
	s_nop 0
	v_pk_mul_f32 v[50:51], v[46:47], v[198:199] op_sel_hi:[1,0]
	v_pk_mul_f32 v[48:49], v[44:45], v[198:199] op_sel_hi:[1,0]
	v_pk_mul_f32 v[58:59], v[42:43], v[198:199] op_sel_hi:[1,0]
	v_pk_mul_f32 v[56:57], v[40:41], v[198:199] op_sel_hi:[1,0]
	v_pk_mul_f32 v[54:55], v[38:39], v[198:199] op_sel_hi:[1,0]
	v_pk_mul_f32 v[52:53], v[36:37], v[198:199] op_sel_hi:[1,0]
	v_pk_mul_f32 v[62:63], v[34:35], v[198:199] op_sel_hi:[1,0]
	v_pk_mul_f32 v[60:61], v[32:33], v[198:199] op_sel_hi:[1,0]
	s_mov_b64 s[52:53], 0

; #define EPI_PACK8(v0, v1) (u32x4){pk2((v0)[0], (v0)[1]), pk2((v0)[2], (v0)[3]), pk2((v1)[0], (v1)[1]), pk2((v1)[2], (v1)[3])}
;     __device__ __forceinline__ void operator()(AccRef acc, const Unit& u, int wr, int wc, int fr, int fq) const {
;     ...
;             else {
; #pragma unroll
;                 for (int bj = 0; bj < 2; ++bj) { acc[ai][bj][m][0] = acc[ai][bj][m][0] * r; acc[ai][bj][m][1] = acc[ai][bj][m][1] * r; } }
; #pragma unroll
;             for (int bj = 0; bj < 2; ++bj) *(u32x4*)(O + (size_t)row * RET_QKV + EPI_COL(bj)) = EPI_PACK8(acc[ai][bj][m][0], acc[ai][bj][m][1]); }
.LBB0_1053:
	v_lshlrev_b64 v[36:37], 13, v[200:201]
	v_lshl_add_u64 v[36:37], s[26:27], 0, v[36:37]
	v_cvt_pk_bf16_f32 v32, v48, v49
	v_cvt_pk_bf16_f32 v33, v50, v51
	v_cvt_pk_bf16_f32 v34, v56, v57
	v_cvt_pk_bf16_f32 v35, v58, v59
	v_lshl_add_u64 v[36:37], v[144:145], 1, v[36:37]
	s_cmp_lg_u32 s99, 0
	s_cbranch_scc1 .Lwt1018_25517
	global_store_dwordx4 v[36:37], v[32:35], off
	s_branch .Lwj1018_25517
.Lwt1018_25517:
	global_store_dwordx4 v[36:37], v[32:35], off sc1
.Lwj1018_25517:
	v_mov_b32_e32 v48, v199
	v_mov_b32_e32 v49, v199
	v_cvt_pk_bf16_f32 v32, v52, v53
	v_cvt_pk_bf16_f32 v33, v54, v55
	v_cvt_pk_bf16_f32 v34, v60, v61
	v_cvt_pk_bf16_f32 v35, v62, v63
	s_and_b64 vcc, exec, s[6:7]
	s_mov_b64 s[6:7], -1
	s_cmp_lg_u32 s99, 0
	s_cbranch_scc1 .Lwt1018_25534
	global_store_dwordx4 v[36:37], v[32:35], off offset:256
	s_branch .Lwj1018_25534
.Lwt1018_25534:
	global_store_dwordx4 v[36:37], v[32:35], off offset:256 sc1
.Lwj1018_25534:
	s_cbranch_vccnz .LBB0_1055
	v_mov_b32_e32 v198, v199
	v_pk_mul_f32 v[34:35], v[30:31], v[198:199]
	v_pk_mul_f32 v[32:33], v[28:29], v[48:49]
	v_pk_mul_f32 v[42:43], v[22:23], v[198:199]
	v_pk_mul_f32 v[40:41], v[20:21], v[48:49]
	v_pk_mul_f32 v[38:39], v[26:27], v[198:199]
	v_pk_mul_f32 v[36:37], v[24:25], v[48:49]
	v_pk_mul_f32 v[46:47], v[18:19], v[198:199]
	v_pk_mul_f32 v[44:45], v[16:17], v[48:49]
	s_mov_b64 s[6:7], 0

; #define EPI_PACK8(v0, v1) (u32x4){pk2((v0)[0], (v0)[1]), pk2((v0)[2], (v0)[3]), pk2((v1)[0], (v1)[1]), pk2((v1)[2], (v1)[3])}
;     __device__ __forceinline__ void operator()(AccRef acc, const Unit& u, int wr, int wc, int fr, int fq) const {
;     ...
;             for (int bj = 0; bj < 2; ++bj) *(u32x4*)(O + (size_t)row * RET_QKV + EPI_COL(bj)) = EPI_PACK8(acc[ai][bj][m][0], acc[ai][bj][m][1]); }
.LBB0_1057:
	s_waitcnt vmcnt(17)
	v_lshlrev_b64 v[4:5], 13, v[196:197]
	v_lshl_add_u64 v[4:5], s[26:27], 0, v[4:5]
	s_waitcnt vmcnt(16)
	v_cvt_pk_bf16_f32 v0, v32, v33
	v_cvt_pk_bf16_f32 v1, v34, v35
	v_cvt_pk_bf16_f32 v2, v40, v41
	v_cvt_pk_bf16_f32 v3, v42, v43
	v_lshl_add_u64 v[4:5], v[144:145], 1, v[4:5]
	s_andn2_b64 vcc, exec, s[4:5]
	s_mov_b64 s[4:5], -1
	s_cmp_lg_u32 s99, 0
	s_cbranch_scc1 .Lwt1018_25602
	global_store_dwordx4 v[4:5], v[0:3], off
	s_branch .Lwj1018_25602
.Lwt1018_25602:
	global_store_dwordx4 v[4:5], v[0:3], off sc1
.Lwj1018_25602:
	s_nop 1
	v_cvt_pk_bf16_f32 v0, v36, v37
	v_cvt_pk_bf16_f32 v1, v38, v39
	v_cvt_pk_bf16_f32 v2, v44, v45
	v_cvt_pk_bf16_f32 v3, v46, v47
	s_cmp_lg_u32 s99, 0
	s_cbranch_scc1 .Lwt1018_25616
	global_store_dwordx4 v[4:5], v[0:3], off offset:256
	s_branch .Lwj1018_25616
.Lwt1018_25616:
	global_store_dwordx4 v[4:5], v[0:3], off offset:256 sc1

; #define PG8_STAGE(bufoff, gbase, voff) do { _Pragma("unroll") for (int _i = 0; _i < 2; ++_i) \
;         __builtin_amdgcn_global_load_lds((const unsigned*)((const char*)(gbase) + (voff)[_i]), (LAS unsigned*)(lds + (bufoff) + ldsw + _i * 8192), 16, 0, 0); } while (0)
; #define PG8_LDA(dst, b, h) do { _Pragma("unroll") for (int m = 0; m < 4; ++m) _Pragma("unroll") for (int k = 0; k < 2; ++k) dst[m][k] = *(const LAS bf16x8*)(lds + PG8_SA(b, h) + aoff + m * 2048 + k * 1024); } while (0)
; #define PG8_LDB(dst, b, h) do { _Pragma("unroll") for (int n = 0; n < 2; ++n) _Pragma("unroll") for (int k = 0; k < 2; ++k) dst[n][k] = *(const LAS bf16x8*)(lds + PG8_SB(b, h) + boff + n * 2048 + k * 1024); } while (0)
; #define PG8_MMA(ai, bj, At, Bt) do { __builtin_amdgcn_s_setprio(1); _Pragma("unroll") for (int m = 0; m < 4; ++m) _Pragma("unroll") for (int n = 0; n < 2; ++n) _Pragma("unroll") for (int k = 0; k < 2; ++k) \
;         acc[ai][bj][m][n] = __builtin_amdgcn_mfma_f32_16x16x32_bf16(Bt[n][k], At[m][k], acc[ai][bj][m][n], 0, 0, 0); __builtin_amdgcn_s_setprio(0); } while (0)
; #define PG8_WAIT_V(n) asm volatile("s_waitcnt vmcnt(" #n ")" ::: "memory")
; #define PG8_WAIT_L(n) asm volatile("s_waitcnt lgkmcnt(" #n ")" ::: "memory")
; #define PG8_BAR __builtin_amdgcn_s_barrier()
; #define PG8_SCHED __builtin_amdgcn_sched_barrier(0)
; template <class Epi>
; __device__ __forceinline__ void gemm_phase(LAS unsigned char* lds, const Gemm g, const StaticOrder& S, const Epi& E) {
;     ...
;             PG8_LDB(B0, 0, 0); PG8_LDB(B1, 0, 1); PG8_SCHED; PG8_LDA(At, 0, 0); PG8_STAGE(PG8_SA(1, 1), a1 + hstepA, voffA);
;             PG8_WAIT_V(8); PG8_WAIT_L(0); PG8_BAR; PG8_MMA(0, 0, At, B0); PG8_MMA(0, 1, At, B1); PG8_BAR; PG8_SCHED;
;             PG8_LDA(At, 0, 1); PG8_STAGE(PG8_SB(0, 0), b2, voffB); PG8_STAGE(PG8_SB(0, 1), b2 + hstepB, voffB); PG8_STAGE(PG8_SA(0, 0), a2, voffA);
;             PG8_WAIT_V(8); PG8_WAIT_L(0); PG8_BAR; PG8_MMA(1, 0, At, B0); PG8_MMA(1, 1, At, B1); PG8_BAR; PG8_SCHED;
.LBB0_1233:
	ds_read_b128 v[56:59], v189
	ds_read_b128 v[60:63], v189 offset:1024
	ds_read_b128 v[72:75], v189 offset:2048
	ds_read_b128 v[76:79], v189 offset:3072
	ds_read_b128 v[144:147], v195
	ds_read_b128 v[148:151], v195 offset:1024
	ds_read_b128 v[168:171], v195 offset:2048
	ds_read_b128 v[178:181], v195 offset:3072
	s_add_u32 s54, s52, 0xfffc0080
	s_addc_u32 s55, s53, -1
	s_cmp_eq_u32 s80, 12
	s_cselect_b32 s57, s23, s55
	s_cselect_b32 s56, s76, s54
	s_cselect_b32 s55, s21, s79
	s_cselect_b32 s54, s77, s78
	v_lshl_add_u64 v[174:175], s[52:53], 0, v[160:161]
	s_add_i32 m0, s43, 0xc000
	ds_read_b128 v[184:187], v201
	ds_read_b128 v[190:193], v201 offset:1024
	ds_read_b128 v[196:199], v201 offset:2048
	ds_read_b128 v[202:205], v201 offset:3072
	ds_read_b128 v[208:211], v201 offset:4096
	ds_read_b128 v[212:215], v201 offset:5120
	ds_read_b128 v[216:219], v201 offset:6144
	ds_read_b128 v[220:223], v201 offset:7168
	global_load_lds_dwordx4 v[174:175], off
	v_lshl_add_u64 v[174:175], s[52:53], 0, v[162:163]
	s_add_i32 m0, s43, 0xe000
	s_nop 0
	global_load_lds_dwordx4 v[174:175], off
	s_waitcnt vmcnt(8)
	s_waitcnt lgkmcnt(0)
	s_barrier
	s_setprio 1
	s_waitcnt lgkmcnt(0)
	v_mfma_f32_16x16x32_bf16 v[140:143], v[56:59], v[184:187], v[140:143]
	v_mfma_f32_16x16x32_bf16 v[136:139], v[72:75], v[184:187], v[136:139]
	v_mfma_f32_16x16x32_bf16 v[124:127], v[56:59], v[196:199], v[124:127]
	v_mfma_f32_16x16x32_bf16 v[120:123], v[72:75], v[196:199], v[120:123]
	v_mfma_f32_16x16x32_bf16 v[108:111], v[56:59], v[208:211], v[108:111]
	v_mfma_f32_16x16x32_bf16 v[104:107], v[72:75], v[208:211], v[104:107]
	v_mfma_f32_16x16x32_bf16 v[92:95], v[56:59], v[216:219], v[92:95]
	v_mfma_f32_16x16x32_bf16 v[88:91], v[72:75], v[216:219], v[88:91]
	v_mfma_f32_16x16x32_bf16 v[140:143], v[60:63], v[190:193], v[140:143]
	v_mfma_f32_16x16x32_bf16 v[136:139], v[76:79], v[190:193], v[136:139]
	v_mfma_f32_16x16x32_bf16 v[124:127], v[60:63], v[202:205], v[124:127]
	v_mfma_f32_16x16x32_bf16 v[120:123], v[76:79], v[202:205], v[120:123]
	v_mfma_f32_16x16x32_bf16 v[108:111], v[60:63], v[212:215], v[108:111]
	v_mfma_f32_16x16x32_bf16 v[104:107], v[76:79], v[212:215], v[104:107]
	v_mfma_f32_16x16x32_bf16 v[92:95], v[60:63], v[220:223], v[92:95]
	v_mfma_f32_16x16x32_bf16 v[88:91], v[76:79], v[220:223], v[88:91]
	s_setprio 0
	s_setprio 1
	v_mfma_f32_16x16x32_bf16 v[132:135], v[144:147], v[184:187], v[132:135]
	v_mfma_f32_16x16x32_bf16 v[128:131], v[168:171], v[184:187], v[128:131]
	v_mfma_f32_16x16x32_bf16 v[116:119], v[144:147], v[196:199], v[116:119]
	v_mfma_f32_16x16x32_bf16 v[112:115], v[168:171], v[196:199], v[112:115]
	v_mfma_f32_16x16x32_bf16 v[100:103], v[144:147], v[208:211], v[100:103]
	v_mfma_f32_16x16x32_bf16 v[96:99], v[168:171], v[208:211], v[96:99]
	v_mfma_f32_16x16x32_bf16 v[84:87], v[144:147], v[216:219], v[84:87]
	v_mfma_f32_16x16x32_bf16 v[80:83], v[168:171], v[216:219], v[80:83]
	v_mfma_f32_16x16x32_bf16 v[132:135], v[148:151], v[190:193], v[132:135]
	v_mfma_f32_16x16x32_bf16 v[128:131], v[178:181], v[190:193], v[128:131]
	v_mfma_f32_16x16x32_bf16 v[116:119], v[148:151], v[202:205], v[116:119]
	v_mfma_f32_16x16x32_bf16 v[112:115], v[178:181], v[202:205], v[112:115]
	v_mfma_f32_16x16x32_bf16 v[100:103], v[148:151], v[212:215], v[100:103]
	v_mfma_f32_16x16x32_bf16 v[96:99], v[178:181], v[212:215], v[96:99]
	v_mfma_f32_16x16x32_bf16 v[84:87], v[148:151], v[220:223], v[84:87]
	v_mfma_f32_16x16x32_bf16 v[80:83], v[178:181], v[220:223], v[80:83]
	s_setprio 0
	s_barrier
	s_add_i32 s81, s73, s58
	v_lshl_add_u64 v[174:175], s[54:55], 0, v[154:155]
	s_mov_b32 m0, s81
	ds_read_b128 v[184:187], v201 offset:16384
	ds_read_b128 v[190:193], v201 offset:17408
	ds_read_b128 v[196:199], v201 offset:18432
	ds_read_b128 v[202:205], v201 offset:19456
	ds_read_b128 v[208:211], v201 offset:20480
	ds_read_b128 v[212:215], v201 offset:21504
	ds_read_b128 v[216:219], v201 offset:22528
	ds_read_b128 v[220:223], v201 offset:23552
	global_load_lds_dwordx4 v[174:175], off
	s_add_i32 m0, s81, 0x2000
	s_add_u32 s82, s54, 0x40000
	v_lshl_add_u64 v[224:225], s[54:55], 0, v[158:159]
	s_addc_u32 s83, s55, 0
	s_add_i32 s81, s74, s58
	global_load_lds_dwordx4 v[224:225], off
	v_lshl_add_u64 v[226:227], s[82:83], 0, v[154:155]
	s_mov_b32 m0, s81
	v_lshl_add_u64 v[228:229], s[56:57], 0, v[156:157]
	global_load_lds_dwordx4 v[226:227], off
	v_lshl_add_u64 v[226:227], s[82:83], 0, v[158:159]
	s_add_i32 m0, s81, 0x2000
	s_nop 0
	global_load_lds_dwordx4 v[226:227], off
	v_lshl_add_u64 v[226:227], s[56:57], 0, v[152:153]
	s_mov_b32 m0, s43
	s_nop 0
	global_load_lds_dwordx4 v[226:227], off
	s_mov_b32 m0, s59
	s_nop 0
	global_load_lds_dwordx4 v[228:229], off
	s_waitcnt vmcnt(8)
	s_waitcnt lgkmcnt(0)
	s_barrier
; #define PG8_STAGE(bufoff, gbase, voff) do { _Pragma("unroll") for (int _i = 0; _i < 2; ++_i) \
;         __builtin_amdgcn_global_load_lds((const unsigned*)((const char*)(gbase) + (voff)[_i]), (LAS unsigned*)(lds + (bufoff) + ldsw + _i * 8192), 16, 0, 0); } while (0)
; #define PG8_LDA(dst, b, h) do { _Pragma("unroll") for (int m = 0; m < 4; ++m) _Pragma("unroll") for (int k = 0; k < 2; ++k) dst[m][k] = *(const LAS bf16x8*)(lds + PG8_SA(b, h) + aoff + m * 2048 + k * 1024); } while (0)
; #define PG8_LDB(dst, b, h) do { _Pragma("unroll") for (int n = 0; n < 2; ++n) _Pragma("unroll") for (int k = 0; k < 2; ++k) dst[n][k] = *(const LAS bf16x8*)(lds + PG8_SB(b, h) + boff + n * 2048 + k * 1024); } while (0)
; #define PG8_MMA(ai, bj, At, Bt) do { __builtin_amdgcn_s_setprio(1); _Pragma("unroll") for (int m = 0; m < 4; ++m) _Pragma("unroll") for (int n = 0; n < 2; ++n) _Pragma("unroll") for (int k = 0; k < 2; ++k) \
;         acc[ai][bj][m][n] = __builtin_amdgcn_mfma_f32_16x16x32_bf16(Bt[n][k], At[m][k], acc[ai][bj][m][n], 0, 0, 0); __builtin_amdgcn_s_setprio(0); } while (0)
; #define PG8_WAIT_V(n) asm volatile("s_waitcnt vmcnt(" #n ")" ::: "memory")
; #define PG8_WAIT_L(n) asm volatile("s_waitcnt lgkmcnt(" #n ")" ::: "memory")
; #define PG8_BAR __builtin_amdgcn_s_barrier()
; #define PG8_SCHED __builtin_amdgcn_sched_barrier(0)
; template <class Epi>
; __device__ __forceinline__ void gemm_phase(LAS unsigned char* lds, const Gemm g, const StaticOrder& S, const Epi& E) {
;     ...
;             PG8_WAIT_V(8); PG8_WAIT_L(0); PG8_BAR; PG8_MMA(1, 0, At, B0); PG8_MMA(1, 1, At, B1); PG8_BAR; PG8_SCHED;
;             PG8_LDB(B0, 1, 0); PG8_LDB(B1, 1, 1); PG8_SCHED; PG8_LDA(At, 1, 0); PG8_STAGE(PG8_SA(0, 1), a2 + hstepA, voffA);
;             PG8_WAIT_V(8); PG8_WAIT_L(0); PG8_BAR; PG8_MMA(0, 0, At, B0); PG8_MMA(0, 1, At, B1); PG8_BAR; PG8_SCHED;
;             PG8_LDA(At, 1, 1); PG8_STAGE(PG8_SB(1, 0), b3, voffB); PG8_STAGE(PG8_SB(1, 1), b3 + hstepB, voffB); PG8_STAGE(PG8_SA(1, 0), a3, voffA);
;             PG8_WAIT_V(8); PG8_WAIT_L(0); PG8_BAR; PG8_MMA(1, 0, At, B0); PG8_MMA(1, 1, At, B1); PG8_BAR; PG8_SCHED;
	s_setprio 1
	s_waitcnt lgkmcnt(0)
	v_mfma_f32_16x16x32_bf16 v[68:71], v[56:59], v[184:187], v[68:71]
	v_mfma_f32_16x16x32_bf16 v[64:67], v[72:75], v[184:187], v[64:67]
	v_mfma_f32_16x16x32_bf16 v[44:47], v[56:59], v[196:199], v[44:47]
	v_mfma_f32_16x16x32_bf16 v[40:43], v[72:75], v[196:199], v[40:43]
	v_mfma_f32_16x16x32_bf16 v[28:31], v[56:59], v[208:211], v[28:31]
	v_mfma_f32_16x16x32_bf16 v[24:27], v[72:75], v[208:211], v[24:27]
	v_mfma_f32_16x16x32_bf16 v[12:15], v[56:59], v[216:219], v[12:15]
	v_mfma_f32_16x16x32_bf16 v[8:11], v[72:75], v[216:219], v[8:11]
	v_mfma_f32_16x16x32_bf16 v[68:71], v[60:63], v[190:193], v[68:71]
	v_mfma_f32_16x16x32_bf16 v[64:67], v[76:79], v[190:193], v[64:67]
	v_mfma_f32_16x16x32_bf16 v[44:47], v[60:63], v[202:205], v[44:47]
	v_mfma_f32_16x16x32_bf16 v[40:43], v[76:79], v[202:205], v[40:43]
	v_mfma_f32_16x16x32_bf16 v[28:31], v[60:63], v[212:215], v[28:31]
	v_mfma_f32_16x16x32_bf16 v[24:27], v[76:79], v[212:215], v[24:27]
	v_mfma_f32_16x16x32_bf16 v[12:15], v[60:63], v[220:223], v[12:15]
	v_mfma_f32_16x16x32_bf16 v[8:11], v[76:79], v[220:223], v[8:11]
	s_setprio 0
	s_setprio 1
	v_mfma_f32_16x16x32_bf16 v[52:55], v[144:147], v[184:187], v[52:55]
	v_mfma_f32_16x16x32_bf16 v[48:51], v[168:171], v[184:187], v[48:51]
	v_mfma_f32_16x16x32_bf16 v[36:39], v[144:147], v[196:199], v[36:39]
	v_mfma_f32_16x16x32_bf16 v[32:35], v[168:171], v[196:199], v[32:35]
	v_mfma_f32_16x16x32_bf16 v[20:23], v[144:147], v[208:211], v[20:23]
	v_mfma_f32_16x16x32_bf16 v[16:19], v[168:171], v[208:211], v[16:19]
	v_mfma_f32_16x16x32_bf16 v[4:7], v[144:147], v[216:219], v[4:7]
	v_mfma_f32_16x16x32_bf16 v[0:3], v[168:171], v[216:219], v[0:3]
	v_mfma_f32_16x16x32_bf16 v[52:55], v[148:151], v[190:193], v[52:55]
	v_mfma_f32_16x16x32_bf16 v[48:51], v[178:181], v[190:193], v[48:51]
	v_mfma_f32_16x16x32_bf16 v[36:39], v[148:151], v[202:205], v[36:39]
	v_mfma_f32_16x16x32_bf16 v[32:35], v[178:181], v[202:205], v[32:35]
	v_mfma_f32_16x16x32_bf16 v[20:23], v[148:151], v[212:215], v[20:23]
	v_mfma_f32_16x16x32_bf16 v[16:19], v[178:181], v[212:215], v[16:19]
	v_mfma_f32_16x16x32_bf16 v[4:7], v[148:151], v[220:223], v[4:7]
	v_mfma_f32_16x16x32_bf16 v[0:3], v[178:181], v[220:223], v[0:3]
	s_setprio 0
	s_barrier
	s_add_i32 s81, 0, 0x18000
	s_add_i32 s82, 0, 0x1c000
	v_add_u32_e32 v76, s81, v183
	v_add_u32_e32 v172, s82, v183
	ds_read_b128 v[56:59], v76
	ds_read_b128 v[60:63], v76 offset:1024
	ds_read_b128 v[72:75], v76 offset:2048
	ds_read_b128 v[76:79], v76 offset:3072
	ds_read_b128 v[144:147], v172
	ds_read_b128 v[148:151], v172 offset:1024
	ds_read_b128 v[168:171], v172 offset:2048
	ds_read_b128 v[178:181], v172 offset:3072
	s_add_u32 s56, s56, 0x40000
	s_addc_u32 s57, s57, 0
	s_mov_b32 m0, s62
	v_lshl_add_u64 v[230:231], s[56:57], 0, v[152:153]
	ds_read_b128 v[184:187], v201 offset:32768
	ds_read_b128 v[190:193], v201 offset:33792
	ds_read_b128 v[196:199], v201 offset:34816
	ds_read_b128 v[202:205], v201 offset:35840
	ds_read_b128 v[208:211], v201 offset:36864
	ds_read_b128 v[212:215], v201 offset:37888
	ds_read_b128 v[216:219], v201 offset:38912
	ds_read_b128 v[220:223], v201 offset:39936
	global_load_lds_dwordx4 v[230:231], off
	v_lshl_add_u64 v[230:231], s[56:57], 0, v[156:157]
	s_mov_b32 m0, s63
	s_nop 0
	global_load_lds_dwordx4 v[230:231], off
	s_waitcnt vmcnt(8)
	s_waitcnt lgkmcnt(0)
	s_barrier
	s_setprio 1
	s_waitcnt lgkmcnt(0)
	v_mfma_f32_16x16x32_bf16 v[140:143], v[56:59], v[184:187], v[140:143]
	v_mfma_f32_16x16x32_bf16 v[136:139], v[72:75], v[184:187], v[136:139]
	v_mfma_f32_16x16x32_bf16 v[124:127], v[56:59], v[196:199], v[124:127]
	v_mfma_f32_16x16x32_bf16 v[120:123], v[72:75], v[196:199], v[120:123]
	v_mfma_f32_16x16x32_bf16 v[108:111], v[56:59], v[208:211], v[108:111]
	v_mfma_f32_16x16x32_bf16 v[104:107], v[72:75], v[208:211], v[104:107]
	v_mfma_f32_16x16x32_bf16 v[92:95], v[56:59], v[216:219], v[92:95]
	v_mfma_f32_16x16x32_bf16 v[88:91], v[72:75], v[216:219], v[88:91]
	v_mfma_f32_16x16x32_bf16 v[140:143], v[60:63], v[190:193], v[140:143]
	v_mfma_f32_16x16x32_bf16 v[136:139], v[76:79], v[190:193], v[136:139]
	v_mfma_f32_16x16x32_bf16 v[124:127], v[60:63], v[202:205], v[124:127]
	v_mfma_f32_16x16x32_bf16 v[120:123], v[76:79], v[202:205], v[120:123]
	v_mfma_f32_16x16x32_bf16 v[108:111], v[60:63], v[212:215], v[108:111]
	v_mfma_f32_16x16x32_bf16 v[104:107], v[76:79], v[212:215], v[104:107]
	v_mfma_f32_16x16x32_bf16 v[92:95], v[60:63], v[220:223], v[92:95]
	v_mfma_f32_16x16x32_bf16 v[88:91], v[76:79], v[220:223], v[88:91]
	s_setprio 0
	s_setprio 1
	v_mfma_f32_16x16x32_bf16 v[132:135], v[144:147], v[184:187], v[132:135]
	v_mfma_f32_16x16x32_bf16 v[128:131], v[168:171], v[184:187], v[128:131]
	v_mfma_f32_16x16x32_bf16 v[116:119], v[144:147], v[196:199], v[116:119]
	v_mfma_f32_16x16x32_bf16 v[112:115], v[168:171], v[196:199], v[112:115]
	v_mfma_f32_16x16x32_bf16 v[100:103], v[144:147], v[208:211], v[100:103]
	v_mfma_f32_16x16x32_bf16 v[96:99], v[168:171], v[208:211], v[96:99]
	v_mfma_f32_16x16x32_bf16 v[84:87], v[144:147], v[216:219], v[84:87]
	v_mfma_f32_16x16x32_bf16 v[80:83], v[168:171], v[216:219], v[80:83]
	v_mfma_f32_16x16x32_bf16 v[132:135], v[148:151], v[190:193], v[132:135]
	v_mfma_f32_16x16x32_bf16 v[128:131], v[178:181], v[190:193], v[128:131]
	v_mfma_f32_16x16x32_bf16 v[116:119], v[148:151], v[202:205], v[116:119]
	v_mfma_f32_16x16x32_bf16 v[112:115], v[178:181], v[202:205], v[112:115]
	v_mfma_f32_16x16x32_bf16 v[100:103], v[148:151], v[212:215], v[100:103]
	v_mfma_f32_16x16x32_bf16 v[96:99], v[178:181], v[212:215], v[96:99]
	v_mfma_f32_16x16x32_bf16 v[84:87], v[148:151], v[220:223], v[84:87]
	v_mfma_f32_16x16x32_bf16 v[80:83], v[178:181], v[220:223], v[80:83]
	s_setprio 0
	s_barrier
; #define PG8_STAGE(bufoff, gbase, voff) do { _Pragma("unroll") for (int _i = 0; _i < 2; ++_i) \
;         __builtin_amdgcn_global_load_lds((const unsigned*)((const char*)(gbase) + (voff)[_i]), (LAS unsigned*)(lds + (bufoff) + ldsw + _i * 8192), 16, 0, 0); } while (0)
; #define PG8_LDA(dst, b, h) do { _Pragma("unroll") for (int m = 0; m < 4; ++m) _Pragma("unroll") for (int k = 0; k < 2; ++k) dst[m][k] = *(const LAS bf16x8*)(lds + PG8_SA(b, h) + aoff + m * 2048 + k * 1024); } while (0)
; #define PG8_MMA(ai, bj, At, Bt) do { __builtin_amdgcn_s_setprio(1); _Pragma("unroll") for (int m = 0; m < 4; ++m) _Pragma("unroll") for (int n = 0; n < 2; ++n) _Pragma("unroll") for (int k = 0; k < 2; ++k) \
;         acc[ai][bj][m][n] = __builtin_amdgcn_mfma_f32_16x16x32_bf16(Bt[n][k], At[m][k], acc[ai][bj][m][n], 0, 0, 0); __builtin_amdgcn_s_setprio(0); } while (0)
; #define PG8_WAIT_V(n) asm volatile("s_waitcnt vmcnt(" #n ")" ::: "memory")
; #define PG8_WAIT_L(n) asm volatile("s_waitcnt lgkmcnt(" #n ")" ::: "memory")
; #define PG8_BAR __builtin_amdgcn_s_barrier()
; #define PG8_SCHED __builtin_amdgcn_sched_barrier(0)
; #define EPI_IT_ROW(it) EPI_ROW((it) >> 2, (it) & 3)
; template <class Epi>
; __device__ __forceinline__ void gemm_phase(LAS unsigned char* lds, const Gemm g, const StaticOrder& S, const Epi& E) {
;     ...
;             PG8_LDA(At, 1, 1); PG8_STAGE(PG8_SB(1, 0), b3, voffB); PG8_STAGE(PG8_SB(1, 1), b3 + hstepB, voffB); PG8_STAGE(PG8_SA(1, 0), a3, voffA);
;             PG8_WAIT_V(8); PG8_WAIT_L(0); PG8_BAR; PG8_MMA(1, 0, At, B0); PG8_MMA(1, 1, At, B1); PG8_BAR; PG8_SCHED;
;         }
;         if (wr == 0) PG8_BAR;
;     __device__ __forceinline__ void operator()(AccRef acc, const Unit& u, int wr, int wc, int fr, int fq) const {
;         asm volatile("" : "+v"(fr), "+v"(fq));
;         const int h = u.pn >> 1;
;         f32x4 gg[2][2];
; #pragma unroll
;         for (int bj = 0; bj < 2; ++bj) { gg[bj][0] = *(const f32x4*)(gng + EPI_COL(bj)); gg[bj][1] = *(const f32x4*)(gng + EPI_COL(bj) + 4); }
;         EPI_LOAD_RR(ss);
;         f32x2 sts[8];
; #pragma unroll
;         for (int it = 0; it < 8; ++it) sts[it] = *(const f32x2*)(gn + ((size_t)EPI_IT_ROW(it) * 4 + h) * 2);
;         u32x4 oc[2], on[2];
; #pragma unroll
;         for (int bj = 0; bj < 2; ++bj) oc[bj] = *(const u32x4*)(QKV + (size_t)EPI_IT_ROW(0) * RET_QKV + 2048 + EPI_COL(bj));
	s_add_i32 s56, s81, s58
	v_lshl_add_u64 v[174:175], v[174:175], 0, s[12:13]
	s_mov_b32 m0, s56
	ds_read_b128 v[184:187], v201 offset:49152
	ds_read_b128 v[190:193], v201 offset:50176
	ds_read_b128 v[196:199], v201 offset:51200
	ds_read_b128 v[202:205], v201 offset:52224
	ds_read_b128 v[208:211], v201 offset:53248
	ds_read_b128 v[212:215], v201 offset:54272
	ds_read_b128 v[216:219], v201 offset:55296
	ds_read_b128 v[220:223], v201 offset:56320
	global_load_lds_dwordx4 v[174:175], off
	s_add_i32 m0, s56, 0x2000
	s_add_u32 s54, s54, 0x40080
	v_lshl_add_u64 v[174:175], v[224:225], 0, s[12:13]
	s_addc_u32 s55, s55, 0
	s_add_i32 s56, s82, s58
	global_load_lds_dwordx4 v[174:175], off
	v_lshl_add_u64 v[174:175], s[54:55], 0, v[154:155]
	s_mov_b32 m0, s56
	s_nop 0
	global_load_lds_dwordx4 v[174:175], off
	v_lshl_add_u64 v[174:175], s[54:55], 0, v[158:159]
	s_add_i32 m0, s56, 0x2000
	s_nop 0
	global_load_lds_dwordx4 v[174:175], off
	v_lshl_add_u64 v[174:175], v[226:227], 0, s[12:13]
	s_mov_b32 m0, s69
	s_nop 0
	global_load_lds_dwordx4 v[174:175], off
	v_lshl_add_u64 v[174:175], v[228:229], 0, s[12:13]
	s_mov_b32 m0, s70
	s_nop 0
	global_load_lds_dwordx4 v[174:175], off
	s_waitcnt vmcnt(8)
	s_waitcnt lgkmcnt(0)
	s_barrier
	s_setprio 1
	s_waitcnt lgkmcnt(0)
	v_mfma_f32_16x16x32_bf16 v[68:71], v[56:59], v[184:187], v[68:71]
	v_mfma_f32_16x16x32_bf16 v[64:67], v[72:75], v[184:187], v[64:67]
	v_mfma_f32_16x16x32_bf16 v[44:47], v[56:59], v[196:199], v[44:47]
	v_mfma_f32_16x16x32_bf16 v[40:43], v[72:75], v[196:199], v[40:43]
	v_mfma_f32_16x16x32_bf16 v[28:31], v[56:59], v[208:211], v[28:31]
	v_mfma_f32_16x16x32_bf16 v[24:27], v[72:75], v[208:211], v[24:27]
	v_mfma_f32_16x16x32_bf16 v[12:15], v[56:59], v[216:219], v[12:15]
	v_mfma_f32_16x16x32_bf16 v[8:11], v[72:75], v[216:219], v[8:11]
	v_mfma_f32_16x16x32_bf16 v[68:71], v[60:63], v[190:193], v[68:71]
	v_mfma_f32_16x16x32_bf16 v[64:67], v[76:79], v[190:193], v[64:67]
	v_mfma_f32_16x16x32_bf16 v[44:47], v[60:63], v[202:205], v[44:47]
	v_mfma_f32_16x16x32_bf16 v[40:43], v[76:79], v[202:205], v[40:43]
	v_mfma_f32_16x16x32_bf16 v[28:31], v[60:63], v[212:215], v[28:31]
	v_mfma_f32_16x16x32_bf16 v[24:27], v[76:79], v[212:215], v[24:27]
	v_mfma_f32_16x16x32_bf16 v[12:15], v[60:63], v[220:223], v[12:15]
	v_mfma_f32_16x16x32_bf16 v[8:11], v[76:79], v[220:223], v[8:11]
	s_setprio 0
	s_setprio 1
	v_mfma_f32_16x16x32_bf16 v[52:55], v[144:147], v[184:187], v[52:55]
	v_mfma_f32_16x16x32_bf16 v[48:51], v[168:171], v[184:187], v[48:51]
	v_mfma_f32_16x16x32_bf16 v[36:39], v[144:147], v[196:199], v[36:39]
	v_mfma_f32_16x16x32_bf16 v[32:35], v[168:171], v[196:199], v[32:35]
	v_mfma_f32_16x16x32_bf16 v[20:23], v[144:147], v[208:211], v[20:23]
	v_mfma_f32_16x16x32_bf16 v[16:19], v[168:171], v[208:211], v[16:19]
	v_mfma_f32_16x16x32_bf16 v[4:7], v[144:147], v[216:219], v[4:7]
	v_mfma_f32_16x16x32_bf16 v[0:3], v[168:171], v[216:219], v[0:3]
	v_mfma_f32_16x16x32_bf16 v[52:55], v[148:151], v[190:193], v[52:55]
	v_mfma_f32_16x16x32_bf16 v[48:51], v[178:181], v[190:193], v[48:51]
	v_mfma_f32_16x16x32_bf16 v[36:39], v[148:151], v[202:205], v[36:39]
	v_mfma_f32_16x16x32_bf16 v[32:35], v[178:181], v[202:205], v[32:35]
	v_mfma_f32_16x16x32_bf16 v[20:23], v[148:151], v[212:215], v[20:23]
	v_mfma_f32_16x16x32_bf16 v[16:19], v[178:181], v[212:215], v[16:19]
	v_mfma_f32_16x16x32_bf16 v[4:7], v[148:151], v[220:223], v[4:7]
	v_mfma_f32_16x16x32_bf16 v[0:3], v[178:181], v[220:223], v[0:3]
	s_setprio 0
	s_barrier
	s_add_i32 s80, s80, 2
	s_add_u32 s52, s52, 0x100
	s_addc_u32 s53, s53, 0
	s_add_u32 s78, s78, 0x100
	s_addc_u32 s79, s79, 0
	s_cmp_gt_u32 s80, 13
	s_cbranch_scc0 .LBB0_1233
	s_cmp_eq_u64 s[8:9], 0
	s_cselect_b32 s99, 1, 0
	s_and_b64 vcc, exec, s[14:15]
	s_cbranch_vccz .LBB0_1236
	s_barrier
.LBB0_1236:
	v_mov_b32_e32 v78, v177
	v_mov_b32_e32 v56, v173
	s_lshl_b32 s21, s42, 8
	s_add_i32 s21, s21, s65
	v_add_u32_e32 v56, s21, v56
	v_ashrrev_i32_e32 v57, 31, v56
	v_add_u32_e32 v144, 16, v56
	v_lshl_add_u64 v[58:59], v[56:57], 2, s[10:11]
	v_ashrrev_i32_e32 v145, 31, v144
	v_add_u32_e32 v208, 32, v56
	v_add_u32_e32 v202, 48, v56
	v_add_u32_e32 v196, 0x80, v56
	v_add_u32_e32 v190, 0x90, v56
	v_add_u32_e32 v184, 0xa0, v56
	global_load_dword v172, v[58:59], off
	v_lshl_add_u64 v[58:59], v[144:145], 2, s[10:11]
	v_ashrrev_i32_e32 v209, 31, v208
	v_ashrrev_i32_e32 v203, 31, v202
	v_ashrrev_i32_e32 v197, 31, v196
	v_ashrrev_i32_e32 v191, 31, v190
	v_ashrrev_i32_e32 v185, 31, v184
	v_lshl_add_u64 v[60:61], v[208:209], 2, s[10:11]
	v_lshl_add_u64 v[62:63], v[202:203], 2, s[10:11]
	v_lshl_add_u64 v[72:73], v[196:197], 2, s[10:11]
	v_lshl_add_u64 v[74:75], v[190:191], 2, s[10:11]
	v_lshl_add_u64 v[76:77], v[184:185], 2, s[10:11]
	global_load_dword v182, v[58:59], off
	global_load_dword v188, v[60:61], off
	global_load_dword v194, v[62:63], off
	global_load_dword v200, v[72:73], off
	global_load_dword v206, v[74:75], off
	global_load_dword v210, v[76:77], off
	s_ashr_i32 s52, s75, 1
	s_lshl_b32 s21, s75, 8
	s_ashr_i32 s53, s52, 31
	s_or_b32 s21, s21, s68
	s_lshl_b64 s[52:53], s[52:53], 3
	s_add_u32 s52, s0, s52
	s_addc_u32 s53, s1, s53
	v_lshlrev_b64 v[60:61], 5, v[56:57]
	v_lshl_add_u64 v[60:61], s[52:53], 0, v[60:61]
	v_lshl_add_u32 v58, v78, 3, s21
	global_load_dwordx2 v[224:225], v[60:61], off
	v_lshlrev_b64 v[60:61], 13, v[56:57]
	v_ashrrev_i32_e32 v59, 31, v58
	v_lshl_add_u64 v[226:227], s[26:27], 0, v[60:61]
	v_lshl_add_u64 v[146:147], v[226:227], 0, s[16:17]
	v_lshlrev_b64 v[168:169], 1, v[58:59]
	v_lshl_add_u64 v[60:61], v[146:147], 0, v[168:169]
	global_load_dwordx4 v[216:219], v[60:61], off
	v_lshl_add_u64 v[60:61], v[58:59], 2, s[60:61]
	v_add_u32_e32 v148, 0x80, v58
	v_add_u32_e32 v174, 0xb0, v56
	global_load_dwordx4 v[72:75], v[60:61], off offset:16
	global_load_dwordx4 v[76:79], v[60:61], off
	global_load_dwordx4 v[56:59], v[60:61], off offset:528
	s_nop 0
	global_load_dwordx4 v[60:63], v[60:61], off offset:512
	v_ashrrev_i32_e32 v175, 31, v174
	v_lshl_add_u64 v[150:151], v[174:175], 2, s[10:11]
	v_lshlrev_b64 v[170:171], 5, v[144:145]
	v_lshlrev_b64 v[178:179], 5, v[208:209]
	v_lshlrev_b64 v[180:181], 5, v[202:203]
	global_load_dword v214, v[150:151], off
	v_lshl_add_u64 v[150:151], s[52:53], 0, v[170:171]
	v_lshl_add_u64 v[170:171], s[52:53], 0, v[178:179]
	v_lshl_add_u64 v[178:179], s[52:53], 0, v[180:181]
	global_load_dwordx2 v[212:213], v[150:151], off
	global_load_dwordx2 v[204:205], v[170:171], off
	global_load_dwordx2 v[198:199], v[178:179], off
	v_lshlrev_b64 v[186:187], 5, v[196:197]
	v_ashrrev_i32_e32 v149, 31, v148
	v_lshlrev_b64 v[192:193], 5, v[190:191]
	v_lshl_add_u64 v[180:181], s[52:53], 0, v[186:187]
	v_lshlrev_b64 v[144:145], 13, v[144:145]
	s_andn2_b64 vcc, exec, s[4:5]
	s_mov_b64 s[4:5], -1
	s_waitcnt vmcnt(0)
; __device__ __forceinline__ float sigmoid_f(float z) { return __builtin_amdgcn_rcpf(1.f + fexp(-z)); }
; #define EPI_IT_ROW(it) EPI_ROW((it) >> 2, (it) & 3)
; #define EPI_PACK8(v0, v1) (u32x4){pk2((v0)[0], (v0)[1]), pk2((v0)[2], (v0)[3]), pk2((v1)[0], (v1)[1]), pk2((v1)[2], (v1)[3])}
;     __device__ __forceinline__ void operator()(AccRef acc, const Unit& u, int wr, int wc, int fr, int fq) const {
;     ...
;         for (int it = 0; it < 8; ++it) { const int ai = it >> 2, m = it & 3, row = EPI_IT_ROW(it); const float r = rr[it];
;             if (it + 1 < 8) {
; #pragma unroll
;                 for (int bj = 0; bj < 2; ++bj) on[bj] = *(const u32x4*)(QKV + (size_t)EPI_IT_ROW(it + 1) * RET_QKV + 2048 + EPI_COL(bj)); }
;             const float mean = sts[it].x * (1.f / 512.f), var = fmaxf(sts[it].y * (1.f / 512.f) - mean * mean, 0.f), rstd = __builtin_amdgcn_rsqf(var + LN_EPS);
; #pragma unroll
;             for (int bj = 0; bj < 2; ++bj) { const int col = EPI_COL(bj);
;                 const u32x4 ow = oc[bj];
;                 const f32x4 o0 = (f32x4){bflo(ow.x), bfhi(ow.x), bflo(ow.y), bfhi(ow.y)}, o1 = (f32x4){bflo(ow.z), bfhi(ow.z), bflo(ow.w), bfhi(ow.w)};
;                 const f32x4 z0 = acc[ai][bj][m][0] * r, z1 = acc[ai][bj][m][1] * r;
;                 f32x4 g0, g1;
; #pragma unroll
;                 for (int e = 0; e < 4; ++e) { g0[e] = z0[e] * sigmoid_f(z0[e]); g1[e] = z1[e] * sigmoid_f(z1[e]); }
;                 const f32x4 y0 = g0 * ((o0 - mean) * rstd) * gg[bj][0], y1 = g1 * ((o1 - mean) * rstd) * gg[bj][1];
;                 *(u32x4*)(QKV + (size_t)row * RET_QKV + col) = EPI_PACK8(y0, y1); }
	v_fmamk_f32 v150, v172, 0x3a800000, v207
	v_rsq_f32_e32 v228, v150
	v_fmamk_f32 v150, v182, 0x3a800000, v207
	v_fmamk_f32 v151, v188, 0x3a800000, v207
	v_fmamk_f32 v170, v194, 0x3a800000, v207
	v_fmamk_f32 v171, v200, 0x3a800000, v207
	v_fmamk_f32 v172, v206, 0x3a800000, v207
	v_fmamk_f32 v178, v210, 0x3a800000, v207
	v_rsq_f32_e32 v194, v170
	v_rsq_f32_e32 v188, v171
	v_lshlrev_b64 v[170:171], 5, v[184:185]
	v_rsq_f32_e32 v182, v172
	v_rsq_f32_e32 v172, v178
	v_lshl_add_u64 v[170:171], s[52:53], 0, v[170:171]
	v_lshlrev_b64 v[178:179], 5, v[174:175]
	v_rsq_f32_e32 v206, v150
	v_rsq_f32_e32 v200, v151
	v_lshl_add_u64 v[150:151], s[52:53], 0, v[192:193]
	v_lshl_add_u64 v[210:211], s[52:53], 0, v[178:179]
	global_load_dwordx2 v[192:193], v[180:181], off
	global_load_dwordx2 v[186:187], v[150:151], off
	global_load_dwordx2 v[178:179], v[170:171], off
	s_nop 0
	global_load_dwordx2 v[170:171], v[210:211], off
	v_lshlrev_b64 v[180:181], 1, v[148:149]
	v_lshl_add_u64 v[146:147], v[146:147], 0, v[180:181]
	global_load_dwordx4 v[220:223], v[146:147], off
	v_lshl_add_u64 v[210:211], s[26:27], 0, v[144:145]
	v_lshl_add_u64 v[144:145], v[210:211], 0, s[16:17]
	v_lshl_add_u64 v[146:147], v[144:145], 0, v[180:181]
	v_lshl_add_u64 v[148:149], v[144:145], 0, v[168:169]
	global_load_dwordx4 v[144:147], v[146:147], off
	s_nop 0
	global_load_dwordx4 v[148:151], v[148:149], off
	v_pk_mul_f32 v[224:225], v[224:225], s[18:19] op_sel_hi:[1,0]
	v_lshlrev_b32_e32 v229, 16, v217
	v_fma_f32 v215, -v224, v224, v225
	v_max_f32_e32 v215, 0, v215
	v_add_f32_e32 v215, 0x3727c5ac, v215
	v_pk_mul_f32 v[140:141], v[140:141], v[228:229] op_sel_hi:[1,0]
	v_pk_mul_f32 v[136:137], v[136:137], v[228:229] op_sel_hi:[1,0]
	v_rsq_f32_e32 v230, v215
	v_lshlrev_b32_e32 v215, 16, v216
	v_and_b32_e32 v225, 0xffff0000, v216
	v_and_b32_e32 v231, 0xffff0000, v217
	v_lshlrev_b32_e32 v236, 16, v218
	v_and_b32_e32 v237, 0xffff0000, v218
	v_lshlrev_b32_e32 v238, 16, v219
	v_mul_f32_e32 v216, 0xbfb8aa3b, v140
	v_mul_f32_e32 v217, 0xbfb8aa3b, v141
	v_and_b32_e32 v239, 0xffff0000, v219
	v_mul_f32_e32 v218, 0xbfb8aa3b, v136
	v_mul_f32_e32 v219, 0xbfb8aa3b, v137
	v_pk_mul_f32 v[142:143], v[142:143], v[228:229] op_sel_hi:[1,0]
	v_exp_f32_e32 v216, v216
	v_exp_f32_e32 v217, v217
	v_exp_f32_e32 v218, v218
	v_exp_f32_e32 v219, v219
	v_mul_f32_e32 v232, 0xbfb8aa3b, v142
	v_mul_f32_e32 v233, 0xbfb8aa3b, v143
	v_exp_f32_e32 v232, v232
	v_exp_f32_e32 v233, v233
	v_pk_mul_f32 v[138:139], v[138:139], v[228:229] op_sel_hi:[1,0]
	v_add_f32_e32 v216, 1.0, v216
	v_mul_f32_e32 v234, 0xbfb8aa3b, v138
	v_mul_f32_e32 v235, 0xbfb8aa3b, v139
	v_exp_f32_e32 v234, v234
	v_exp_f32_e32 v235, v235
	v_add_f32_e32 v217, 1.0, v217
	v_add_f32_e32 v218, 1.0, v218
	v_add_f32_e32 v219, 1.0, v219
	v_rcp_f32_e32 v216, v216
	v_rcp_f32_e32 v217, v217
	v_rcp_f32_e32 v218, v218
	v_rcp_f32_e32 v219, v219
	v_add_f32_e32 v232, 1.0, v232
	v_add_f32_e32 v233, 1.0, v233
	v_rcp_f32_e32 v232, v232
	v_rcp_f32_e32 v233, v233
	v_add_f32_e32 v234, 1.0, v234
	v_add_f32_e32 v235, 1.0, v235
	v_rcp_f32_e32 v234, v234
	v_rcp_f32_e32 v235, v235
	v_pk_mul_f32 v[140:141], v[140:141], v[216:217]
	v_pk_mul_f32 v[136:137], v[136:137], v[218:219]
	v_sub_f32_e32 v217, v225, v224
	v_sub_f32_e32 v216, v215, v224
	v_sub_f32_e32 v219, v231, v224
	v_sub_f32_e32 v218, v229, v224
	v_pk_mul_f32 v[142:143], v[142:143], v[232:233]
	v_pk_mul_f32 v[218:219], v[230:231], v[218:219] op_sel_hi:[0,1]
	v_pk_mul_f32 v[216:217], v[230:231], v[216:217] op_sel_hi:[0,1]
	v_pk_mul_f32 v[140:141], v[140:141], v[216:217]
	v_pk_mul_f32 v[142:143], v[142:143], v[218:219]
	v_sub_f32_e32 v217, v237, v224
	v_sub_f32_e32 v216, v236, v224
	v_sub_f32_e32 v219, v239, v224
	v_sub_f32_e32 v218, v238, v224
	v_pk_mul_f32 v[138:139], v[138:139], v[234:235]
	v_pk_mul_f32 v[218:219], v[230:231], v[218:219] op_sel_hi:[0,1]
	v_pk_mul_f32 v[216:217], v[230:231], v[216:217] op_sel_hi:[0,1]
	v_pk_mul_f32 v[136:137], v[136:137], v[216:217]
	v_pk_mul_f32 v[138:139], v[138:139], v[218:219]
	v_pk_mul_f32 v[140:141], v[76:77], v[140:141]
	v_pk_mul_f32 v[216:217], v[74:75], v[138:139]
	v_pk_mul_f32 v[138:139], v[72:73], v[136:137]
	v_pk_mul_f32 v[142:143], v[78:79], v[142:143]
	v_cvt_pk_bf16_f32 v136, v140, v141
	v_cvt_pk_bf16_f32 v138, v138, v139
	v_cvt_pk_bf16_f32 v139, v216, v217
	v_lshl_add_u64 v[140:141], v[226:227], 0, v[168:169]
	v_cvt_pk_bf16_f32 v137, v142, v143
	v_pk_mul_f32 v[132:133], v[132:133], v[228:229] op_sel_hi:[1,0]
	v_pk_mul_f32 v[128:129], v[128:129], v[228:229] op_sel_hi:[1,0]
	s_cmp_lg_u32 s99, 0
	s_cbranch_scc1 .Lwt1233_30091
	global_store_dwordx4 v[140:141], v[136:139], off
	s_branch .Lwj1233_30091

; __device__ __forceinline__ float sigmoid_f(float z) { return __builtin_amdgcn_rcpf(1.f + fexp(-z)); }
; #define EPI_IT_ROW(it) EPI_ROW((it) >> 2, (it) & 3)
; #define EPI_PACK8(v0, v1) (u32x4){pk2((v0)[0], (v0)[1]), pk2((v0)[2], (v0)[3]), pk2((v1)[0], (v1)[1]), pk2((v1)[2], (v1)[3])}
;     __device__ __forceinline__ void operator()(AccRef acc, const Unit& u, int wr, int wc, int fr, int fq) const {
;     ...
;         for (int it = 0; it < 8; ++it) { const int ai = it >> 2, m = it & 3, row = EPI_IT_ROW(it); const float r = rr[it];
;             if (it + 1 < 8) {
; #pragma unroll
;                 for (int bj = 0; bj < 2; ++bj) on[bj] = *(const u32x4*)(QKV + (size_t)EPI_IT_ROW(it + 1) * RET_QKV + 2048 + EPI_COL(bj)); }
;             const float mean = sts[it].x * (1.f / 512.f), var = fmaxf(sts[it].y * (1.f / 512.f) - mean * mean, 0.f), rstd = __builtin_amdgcn_rsqf(var + LN_EPS);
; #pragma unroll
;             for (int bj = 0; bj < 2; ++bj) { const int col = EPI_COL(bj);
;                 const u32x4 ow = oc[bj];
;                 const f32x4 o0 = (f32x4){bflo(ow.x), bfhi(ow.x), bflo(ow.y), bfhi(ow.y)}, o1 = (f32x4){bflo(ow.z), bfhi(ow.z), bflo(ow.w), bfhi(ow.w)};
;                 const f32x4 z0 = acc[ai][bj][m][0] * r, z1 = acc[ai][bj][m][1] * r;
;                 f32x4 g0, g1;
; #pragma unroll
;                 for (int e = 0; e < 4; ++e) { g0[e] = z0[e] * sigmoid_f(z0[e]); g1[e] = z1[e] * sigmoid_f(z1[e]); }
;                 const f32x4 y0 = g0 * ((o0 - mean) * rstd) * gg[bj][0], y1 = g1 * ((o1 - mean) * rstd) * gg[bj][1];
;                 *(u32x4*)(QKV + (size_t)row * RET_QKV + col) = EPI_PACK8(y0, y1); }
; #pragma unroll
;             for (int bj = 0; bj < 2; ++bj) oc[bj] = on[bj]; }
.Lwj1233_30091:
	v_pk_mul_f32 v[134:135], v[134:135], v[228:229] op_sel_hi:[1,0]
	v_pk_mul_f32 v[130:131], v[130:131], v[228:229] op_sel_hi:[1,0]
	v_mul_f32_e32 v136, 0xbfb8aa3b, v132
	v_mul_f32_e32 v137, 0xbfb8aa3b, v133
	v_mul_f32_e32 v138, 0xbfb8aa3b, v128
	v_mul_f32_e32 v139, 0xbfb8aa3b, v129
	v_exp_f32_e32 v136, v136
	v_exp_f32_e32 v137, v137
	v_exp_f32_e32 v138, v138
	v_exp_f32_e32 v139, v139
	v_mul_f32_e32 v142, 0xbfb8aa3b, v134
	v_mul_f32_e32 v143, 0xbfb8aa3b, v135
	v_exp_f32_e32 v142, v142
	v_exp_f32_e32 v143, v143
	v_mul_f32_e32 v216, 0xbfb8aa3b, v130
	v_mul_f32_e32 v217, 0xbfb8aa3b, v131
	v_exp_f32_e32 v216, v216
	v_exp_f32_e32 v217, v217
	v_add_f32_e32 v136, 1.0, v136
	v_add_f32_e32 v137, 1.0, v137
	v_add_f32_e32 v138, 1.0, v138
	v_add_f32_e32 v139, 1.0, v139
	v_rcp_f32_e32 v136, v136
	v_rcp_f32_e32 v137, v137
	v_rcp_f32_e32 v138, v138
	v_rcp_f32_e32 v139, v139
	v_add_f32_e32 v142, 1.0, v142
	v_add_f32_e32 v143, 1.0, v143
	v_rcp_f32_e32 v142, v142
	v_rcp_f32_e32 v143, v143
	v_add_f32_e32 v216, 1.0, v216
	v_add_f32_e32 v217, 1.0, v217
	s_waitcnt vmcnt(3)
	v_lshlrev_b32_e32 v215, 16, v220
	v_and_b32_e32 v218, 0xffff0000, v220
	v_lshlrev_b32_e32 v219, 16, v221
	v_and_b32_e32 v220, 0xffff0000, v221
	v_rcp_f32_e32 v216, v216
	v_rcp_f32_e32 v217, v217
	v_pk_mul_f32 v[132:133], v[132:133], v[136:137]
	v_pk_mul_f32 v[128:129], v[128:129], v[138:139]
	v_sub_f32_e32 v137, v218, v224
	v_sub_f32_e32 v136, v215, v224
	v_sub_f32_e32 v139, v220, v224
	v_sub_f32_e32 v138, v219, v224
	v_lshlrev_b32_e32 v221, 16, v222
	v_and_b32_e32 v222, 0xffff0000, v222
	v_lshlrev_b32_e32 v225, 16, v223
	v_and_b32_e32 v223, 0xffff0000, v223
	v_pk_mul_f32 v[134:135], v[134:135], v[142:143]
	v_pk_mul_f32 v[138:139], v[230:231], v[138:139] op_sel_hi:[0,1]
	v_pk_mul_f32 v[136:137], v[230:231], v[136:137] op_sel_hi:[0,1]
	v_pk_mul_f32 v[132:133], v[132:133], v[136:137]
	v_pk_mul_f32 v[134:135], v[134:135], v[138:139]
	v_sub_f32_e32 v137, v222, v224
	v_sub_f32_e32 v136, v221, v224
	v_sub_f32_e32 v139, v223, v224
	v_sub_f32_e32 v138, v225, v224
	v_pk_mul_f32 v[130:131], v[130:131], v[216:217]
	v_pk_mul_f32 v[138:139], v[230:231], v[138:139] op_sel_hi:[0,1]
	v_pk_mul_f32 v[136:137], v[230:231], v[136:137] op_sel_hi:[0,1]
	v_pk_mul_f32 v[128:129], v[128:129], v[136:137]
	v_pk_mul_f32 v[130:131], v[130:131], v[138:139]
	v_pk_mul_f32 v[134:135], v[62:63], v[134:135]
	v_pk_mul_f32 v[132:133], v[60:61], v[132:133]
	v_pk_mul_f32 v[136:137], v[58:59], v[130:131]
	v_pk_mul_f32 v[130:131], v[56:57], v[128:129]
	v_cvt_pk_bf16_f32 v128, v132, v133
	v_cvt_pk_bf16_f32 v129, v134, v135
	v_pk_mul_f32 v[138:139], v[212:213], s[18:19] op_sel_hi:[1,0]
	v_cvt_pk_bf16_f32 v130, v130, v131
	v_cvt_pk_bf16_f32 v131, v136, v137
	s_cmp_lg_u32 s99, 0
	s_cbranch_scc1 .Lwt1233_30172
	global_store_dwordx4 v[140:141], v[128:131], off offset:256
	s_branch .Lwj1233_30172
.Lwt1233_30172:
	global_store_dwordx4 v[140:141], v[128:131], off offset:256 sc1
.Lwj1233_30172:
	v_fma_f32 v139, -v138, v138, v139
	v_max_f32_e32 v139, 0, v139
	v_lshlrev_b64 v[128:129], 13, v[208:209]
	v_lshl_add_u64 v[136:137], s[26:27], 0, v[128:129]
	v_lshl_add_u64 v[128:129], v[136:137], 0, s[16:17]
	v_lshl_add_u64 v[130:131], v[128:129], 0, v[180:181]
	v_lshl_add_u64 v[132:133], v[128:129], 0, v[168:169]
	global_load_dwordx4 v[128:131], v[130:131], off
	s_nop 0
	global_load_dwordx4 v[132:135], v[132:133], off
	v_add_f32_e32 v139, 0x3727c5ac, v139
	v_pk_mul_f32 v[124:125], v[124:125], v[206:207] op_sel_hi:[1,0]
	v_pk_mul_f32 v[120:121], v[120:121], v[206:207] op_sel_hi:[1,0]
	v_rsq_f32_e32 v140, v139
	s_waitcnt vmcnt(4)
	v_lshlrev_b32_e32 v139, 16, v148
	v_and_b32_e32 v141, 0xffff0000, v148
	v_lshlrev_b32_e32 v212, 16, v149
	v_and_b32_e32 v213, 0xffff0000, v149
	v_mul_f32_e32 v142, 0xbfb8aa3b, v124
	v_mul_f32_e32 v143, 0xbfb8aa3b, v125
	v_mul_f32_e32 v148, 0xbfb8aa3b, v120
	v_mul_f32_e32 v149, 0xbfb8aa3b, v121
	v_pk_mul_f32 v[126:127], v[126:127], v[206:207] op_sel_hi:[1,0]
	v_lshlrev_b32_e32 v215, 16, v150
	v_and_b32_e32 v216, 0xffff0000, v150
	v_lshlrev_b32_e32 v217, 16, v151
	v_exp_f32_e32 v142, v142
	v_exp_f32_e32 v143, v143
	v_and_b32_e32 v218, 0xffff0000, v151
	v_exp_f32_e32 v148, v148
	v_exp_f32_e32 v149, v149
	v_mul_f32_e32 v150, 0xbfb8aa3b, v126
	v_mul_f32_e32 v151, 0xbfb8aa3b, v127
	v_exp_f32_e32 v150, v150
	v_exp_f32_e32 v151, v151
	v_pk_mul_f32 v[122:123], v[122:123], v[206:207] op_sel_hi:[1,0]
	v_add_f32_e32 v142, 1.0, v142
	v_mul_f32_e32 v208, 0xbfb8aa3b, v122
	v_mul_f32_e32 v209, 0xbfb8aa3b, v123
	v_exp_f32_e32 v208, v208
	v_exp_f32_e32 v209, v209
	v_add_f32_e32 v143, 1.0, v143
	v_add_f32_e32 v148, 1.0, v148
	v_add_f32_e32 v149, 1.0, v149
	v_rcp_f32_e32 v142, v142
	v_rcp_f32_e32 v143, v143
	v_rcp_f32_e32 v148, v148
	v_rcp_f32_e32 v149, v149
	v_add_f32_e32 v150, 1.0, v150
	v_add_f32_e32 v151, 1.0, v151
	v_rcp_f32_e32 v150, v150
	v_rcp_f32_e32 v151, v151
	v_add_f32_e32 v208, 1.0, v208
	v_add_f32_e32 v209, 1.0, v209
	v_rcp_f32_e32 v208, v208
	v_rcp_f32_e32 v209, v209
	v_pk_mul_f32 v[124:125], v[124:125], v[142:143]
	v_pk_mul_f32 v[120:121], v[120:121], v[148:149]
	v_sub_f32_e32 v143, v141, v138
	v_sub_f32_e32 v142, v139, v138
	v_sub_f32_e32 v149, v213, v138
	v_sub_f32_e32 v148, v212, v138
	v_pk_mul_f32 v[126:127], v[126:127], v[150:151]
	v_pk_mul_f32 v[148:149], v[140:141], v[148:149] op_sel_hi:[0,1]
	v_pk_mul_f32 v[142:143], v[140:141], v[142:143] op_sel_hi:[0,1]
	v_pk_mul_f32 v[124:125], v[124:125], v[142:143]
	v_pk_mul_f32 v[126:127], v[126:127], v[148:149]
	v_sub_f32_e32 v143, v216, v138
	v_sub_f32_e32 v142, v215, v138
	v_sub_f32_e32 v149, v218, v138
	v_sub_f32_e32 v148, v217, v138
	v_pk_mul_f32 v[122:123], v[122:123], v[208:209]
	v_pk_mul_f32 v[148:149], v[140:141], v[148:149] op_sel_hi:[0,1]
	v_pk_mul_f32 v[142:143], v[140:141], v[142:143] op_sel_hi:[0,1]
	v_pk_mul_f32 v[120:121], v[120:121], v[142:143]
	v_pk_mul_f32 v[122:123], v[122:123], v[148:149]
	v_pk_mul_f32 v[124:125], v[76:77], v[124:125]
	v_pk_mul_f32 v[142:143], v[74:75], v[122:123]
	v_pk_mul_f32 v[122:123], v[72:73], v[120:121]
	v_pk_mul_f32 v[126:127], v[78:79], v[126:127]
	v_cvt_pk_bf16_f32 v120, v124, v125
	v_cvt_pk_bf16_f32 v122, v122, v123
	v_cvt_pk_bf16_f32 v123, v142, v143
	v_lshl_add_u64 v[124:125], v[210:211], 0, v[168:169]
	v_cvt_pk_bf16_f32 v121, v126, v127
	v_pk_mul_f32 v[116:117], v[116:117], v[206:207] op_sel_hi:[1,0]
	v_pk_mul_f32 v[112:113], v[112:113], v[206:207] op_sel_hi:[1,0]
	s_cmp_lg_u32 s99, 0
	s_cbranch_scc1 .Lwt1233_30269
	global_store_dwordx4 v[124:125], v[120:123], off
	s_branch .Lwj1233_30269

; __device__ __forceinline__ float sigmoid_f(float z) { return __builtin_amdgcn_rcpf(1.f + fexp(-z)); }
; #define EPI_IT_ROW(it) EPI_ROW((it) >> 2, (it) & 3)
; #define EPI_PACK8(v0, v1) (u32x4){pk2((v0)[0], (v0)[1]), pk2((v0)[2], (v0)[3]), pk2((v1)[0], (v1)[1]), pk2((v1)[2], (v1)[3])}
;     __device__ __forceinline__ void operator()(AccRef acc, const Unit& u, int wr, int wc, int fr, int fq) const {
;     ...
;         for (int it = 0; it < 8; ++it) { const int ai = it >> 2, m = it & 3, row = EPI_IT_ROW(it); const float r = rr[it];
;             if (it + 1 < 8) {
; #pragma unroll
;                 for (int bj = 0; bj < 2; ++bj) on[bj] = *(const u32x4*)(QKV + (size_t)EPI_IT_ROW(it + 1) * RET_QKV + 2048 + EPI_COL(bj)); }
;             const float mean = sts[it].x * (1.f / 512.f), var = fmaxf(sts[it].y * (1.f / 512.f) - mean * mean, 0.f), rstd = __builtin_amdgcn_rsqf(var + LN_EPS);
; #pragma unroll
;             for (int bj = 0; bj < 2; ++bj) { const int col = EPI_COL(bj);
;                 const u32x4 ow = oc[bj];
;                 const f32x4 o0 = (f32x4){bflo(ow.x), bfhi(ow.x), bflo(ow.y), bfhi(ow.y)}, o1 = (f32x4){bflo(ow.z), bfhi(ow.z), bflo(ow.w), bfhi(ow.w)};
;                 const f32x4 z0 = acc[ai][bj][m][0] * r, z1 = acc[ai][bj][m][1] * r;
;                 f32x4 g0, g1;
; #pragma unroll
;                 for (int e = 0; e < 4; ++e) { g0[e] = z0[e] * sigmoid_f(z0[e]); g1[e] = z1[e] * sigmoid_f(z1[e]); }
;                 const f32x4 y0 = g0 * ((o0 - mean) * rstd) * gg[bj][0], y1 = g1 * ((o1 - mean) * rstd) * gg[bj][1];
;                 *(u32x4*)(QKV + (size_t)row * RET_QKV + col) = EPI_PACK8(y0, y1); }
; #pragma unroll
;             for (int bj = 0; bj < 2; ++bj) oc[bj] = on[bj]; }
.Lwj1233_30269:
	v_pk_mul_f32 v[118:119], v[118:119], v[206:207] op_sel_hi:[1,0]
	v_pk_mul_f32 v[114:115], v[114:115], v[206:207] op_sel_hi:[1,0]
	v_mul_f32_e32 v120, 0xbfb8aa3b, v116
	v_mul_f32_e32 v121, 0xbfb8aa3b, v117
	v_mul_f32_e32 v122, 0xbfb8aa3b, v112
	v_mul_f32_e32 v123, 0xbfb8aa3b, v113
	v_exp_f32_e32 v120, v120
	v_exp_f32_e32 v121, v121
	v_exp_f32_e32 v122, v122
	v_exp_f32_e32 v123, v123
	v_mul_f32_e32 v126, 0xbfb8aa3b, v118
	v_mul_f32_e32 v127, 0xbfb8aa3b, v119
	v_exp_f32_e32 v126, v126
	v_exp_f32_e32 v127, v127
	v_mul_f32_e32 v142, 0xbfb8aa3b, v114
	v_mul_f32_e32 v143, 0xbfb8aa3b, v115
	v_exp_f32_e32 v142, v142
	v_exp_f32_e32 v143, v143
	v_add_f32_e32 v120, 1.0, v120
	v_add_f32_e32 v121, 1.0, v121
	v_add_f32_e32 v122, 1.0, v122
	v_add_f32_e32 v123, 1.0, v123
	v_rcp_f32_e32 v120, v120
	v_rcp_f32_e32 v121, v121
	v_rcp_f32_e32 v122, v122
	v_rcp_f32_e32 v123, v123
	v_add_f32_e32 v126, 1.0, v126
	v_add_f32_e32 v127, 1.0, v127
	v_rcp_f32_e32 v126, v126
	v_rcp_f32_e32 v127, v127
	v_add_f32_e32 v142, 1.0, v142
	v_add_f32_e32 v143, 1.0, v143
	v_lshlrev_b32_e32 v139, 16, v144
	v_and_b32_e32 v141, 0xffff0000, v144
	v_lshlrev_b32_e32 v144, 16, v145
	v_and_b32_e32 v145, 0xffff0000, v145
	v_rcp_f32_e32 v142, v142
	v_rcp_f32_e32 v143, v143
	v_pk_mul_f32 v[116:117], v[116:117], v[120:121]
	v_pk_mul_f32 v[112:113], v[112:113], v[122:123]
	v_sub_f32_e32 v121, v141, v138
	v_sub_f32_e32 v120, v139, v138
	v_sub_f32_e32 v123, v145, v138
	v_sub_f32_e32 v122, v144, v138
	v_lshlrev_b32_e32 v148, 16, v146
	v_and_b32_e32 v146, 0xffff0000, v146
	v_lshlrev_b32_e32 v149, 16, v147
	v_and_b32_e32 v147, 0xffff0000, v147
	v_pk_mul_f32 v[118:119], v[118:119], v[126:127]
	v_pk_mul_f32 v[122:123], v[140:141], v[122:123] op_sel_hi:[0,1]
	v_pk_mul_f32 v[120:121], v[140:141], v[120:121] op_sel_hi:[0,1]
	v_pk_mul_f32 v[116:117], v[116:117], v[120:121]
	v_pk_mul_f32 v[118:119], v[118:119], v[122:123]
	v_sub_f32_e32 v121, v146, v138
	v_sub_f32_e32 v120, v148, v138
	v_sub_f32_e32 v123, v147, v138
	v_sub_f32_e32 v122, v149, v138
	v_pk_mul_f32 v[114:115], v[114:115], v[142:143]
	v_pk_mul_f32 v[122:123], v[140:141], v[122:123] op_sel_hi:[0,1]
	v_pk_mul_f32 v[120:121], v[140:141], v[120:121] op_sel_hi:[0,1]
	v_pk_mul_f32 v[112:113], v[112:113], v[120:121]
	v_pk_mul_f32 v[114:115], v[114:115], v[122:123]
	v_pk_mul_f32 v[118:119], v[62:63], v[118:119]
	v_pk_mul_f32 v[116:117], v[60:61], v[116:117]
	v_pk_mul_f32 v[120:121], v[58:59], v[114:115]
	v_pk_mul_f32 v[114:115], v[56:57], v[112:113]
	v_cvt_pk_bf16_f32 v112, v116, v117
	v_cvt_pk_bf16_f32 v113, v118, v119
	v_pk_mul_f32 v[122:123], v[204:205], s[18:19] op_sel_hi:[1,0]
	v_cvt_pk_bf16_f32 v114, v114, v115
	v_cvt_pk_bf16_f32 v115, v120, v121
	s_cmp_lg_u32 s99, 0
	s_cbranch_scc1 .Lwt1233_30349
	global_store_dwordx4 v[124:125], v[112:115], off offset:256
	s_branch .Lwj1233_30349
.Lwt1233_30349:
	global_store_dwordx4 v[124:125], v[112:115], off offset:256 sc1
.Lwj1233_30349:
	v_fma_f32 v123, -v122, v122, v123
	v_max_f32_e32 v123, 0, v123
	v_lshlrev_b64 v[112:113], 13, v[202:203]
	v_lshl_add_u64 v[120:121], s[26:27], 0, v[112:113]
	v_lshl_add_u64 v[112:113], v[120:121], 0, s[16:17]
	v_lshl_add_u64 v[114:115], v[112:113], 0, v[180:181]
	v_lshl_add_u64 v[116:117], v[112:113], 0, v[168:169]
	global_load_dwordx4 v[112:115], v[114:115], off
	s_nop 0
	global_load_dwordx4 v[116:119], v[116:117], off
	v_add_f32_e32 v123, 0x3727c5ac, v123
	v_pk_mul_f32 v[108:109], v[108:109], v[200:201] op_sel_hi:[1,0]
	v_pk_mul_f32 v[104:105], v[104:105], v[200:201] op_sel_hi:[1,0]
	v_rsq_f32_e32 v124, v123
	s_waitcnt vmcnt(4)
	v_lshlrev_b32_e32 v123, 16, v132
	v_and_b32_e32 v125, 0xffff0000, v132
	v_lshlrev_b32_e32 v140, 16, v133
	v_and_b32_e32 v141, 0xffff0000, v133
	v_mul_f32_e32 v126, 0xbfb8aa3b, v108
	v_mul_f32_e32 v127, 0xbfb8aa3b, v109
	v_mul_f32_e32 v132, 0xbfb8aa3b, v104
	v_mul_f32_e32 v133, 0xbfb8aa3b, v105
	v_pk_mul_f32 v[110:111], v[110:111], v[200:201] op_sel_hi:[1,0]
	v_lshlrev_b32_e32 v142, 16, v134
	v_and_b32_e32 v143, 0xffff0000, v134
	v_lshlrev_b32_e32 v144, 16, v135
	v_exp_f32_e32 v126, v126
	v_exp_f32_e32 v127, v127
	v_and_b32_e32 v145, 0xffff0000, v135
	v_exp_f32_e32 v132, v132
	v_exp_f32_e32 v133, v133
	v_mul_f32_e32 v134, 0xbfb8aa3b, v110
	v_mul_f32_e32 v135, 0xbfb8aa3b, v111
	v_exp_f32_e32 v134, v134
	v_exp_f32_e32 v135, v135
	v_pk_mul_f32 v[106:107], v[106:107], v[200:201] op_sel_hi:[1,0]
	v_add_f32_e32 v126, 1.0, v126
	v_mul_f32_e32 v138, 0xbfb8aa3b, v106
	v_mul_f32_e32 v139, 0xbfb8aa3b, v107
	v_exp_f32_e32 v138, v138
	v_exp_f32_e32 v139, v139
	v_add_f32_e32 v127, 1.0, v127
	v_add_f32_e32 v132, 1.0, v132
	v_add_f32_e32 v133, 1.0, v133
	v_rcp_f32_e32 v126, v126
	v_rcp_f32_e32 v127, v127
	v_rcp_f32_e32 v132, v132
	v_rcp_f32_e32 v133, v133
	v_add_f32_e32 v134, 1.0, v134
	v_add_f32_e32 v135, 1.0, v135
	v_rcp_f32_e32 v134, v134
	v_rcp_f32_e32 v135, v135
	v_add_f32_e32 v138, 1.0, v138
	v_add_f32_e32 v139, 1.0, v139
	v_rcp_f32_e32 v138, v138
	v_rcp_f32_e32 v139, v139
	v_pk_mul_f32 v[108:109], v[108:109], v[126:127]
	v_pk_mul_f32 v[104:105], v[104:105], v[132:133]
	v_sub_f32_e32 v127, v125, v122
	v_sub_f32_e32 v126, v123, v122
	v_sub_f32_e32 v133, v141, v122
	v_sub_f32_e32 v132, v140, v122
	v_pk_mul_f32 v[110:111], v[110:111], v[134:135]
	v_pk_mul_f32 v[132:133], v[124:125], v[132:133] op_sel_hi:[0,1]
	v_pk_mul_f32 v[126:127], v[124:125], v[126:127] op_sel_hi:[0,1]
	v_pk_mul_f32 v[108:109], v[108:109], v[126:127]
	v_pk_mul_f32 v[110:111], v[110:111], v[132:133]
	v_sub_f32_e32 v127, v143, v122
	v_sub_f32_e32 v126, v142, v122
	v_sub_f32_e32 v133, v145, v122
	v_sub_f32_e32 v132, v144, v122
	v_pk_mul_f32 v[106:107], v[106:107], v[138:139]
	v_pk_mul_f32 v[132:133], v[124:125], v[132:133] op_sel_hi:[0,1]
	v_pk_mul_f32 v[126:127], v[124:125], v[126:127] op_sel_hi:[0,1]
	v_pk_mul_f32 v[104:105], v[104:105], v[126:127]
	v_pk_mul_f32 v[106:107], v[106:107], v[132:133]
	v_pk_mul_f32 v[108:109], v[76:77], v[108:109]
	v_pk_mul_f32 v[126:127], v[74:75], v[106:107]
	v_pk_mul_f32 v[106:107], v[72:73], v[104:105]
	v_pk_mul_f32 v[110:111], v[78:79], v[110:111]
	v_cvt_pk_bf16_f32 v104, v108, v109
	v_cvt_pk_bf16_f32 v106, v106, v107
	v_cvt_pk_bf16_f32 v107, v126, v127
	v_lshl_add_u64 v[108:109], v[136:137], 0, v[168:169]
	v_cvt_pk_bf16_f32 v105, v110, v111
	v_pk_mul_f32 v[100:101], v[100:101], v[200:201] op_sel_hi:[1,0]
	v_pk_mul_f32 v[96:97], v[96:97], v[200:201] op_sel_hi:[1,0]
	s_cmp_lg_u32 s99, 0
	s_cbranch_scc1 .Lwt1233_30446
	global_store_dwordx4 v[108:109], v[104:107], off
	s_branch .Lwj1233_30446

; __device__ __forceinline__ float sigmoid_f(float z) { return __builtin_amdgcn_rcpf(1.f + fexp(-z)); }
; #define EPI_IT_ROW(it) EPI_ROW((it) >> 2, (it) & 3)
; #define EPI_PACK8(v0, v1) (u32x4){pk2((v0)[0], (v0)[1]), pk2((v0)[2], (v0)[3]), pk2((v1)[0], (v1)[1]), pk2((v1)[2], (v1)[3])}
;     __device__ __forceinline__ void operator()(AccRef acc, const Unit& u, int wr, int wc, int fr, int fq) const {
;     ...
;         for (int it = 0; it < 8; ++it) { const int ai = it >> 2, m = it & 3, row = EPI_IT_ROW(it); const float r = rr[it];
;             if (it + 1 < 8) {
; #pragma unroll
;                 for (int bj = 0; bj < 2; ++bj) on[bj] = *(const u32x4*)(QKV + (size_t)EPI_IT_ROW(it + 1) * RET_QKV + 2048 + EPI_COL(bj)); }
;             const float mean = sts[it].x * (1.f / 512.f), var = fmaxf(sts[it].y * (1.f / 512.f) - mean * mean, 0.f), rstd = __builtin_amdgcn_rsqf(var + LN_EPS);
; #pragma unroll
;             for (int bj = 0; bj < 2; ++bj) { const int col = EPI_COL(bj);
;                 const u32x4 ow = oc[bj];
;                 const f32x4 o0 = (f32x4){bflo(ow.x), bfhi(ow.x), bflo(ow.y), bfhi(ow.y)}, o1 = (f32x4){bflo(ow.z), bfhi(ow.z), bflo(ow.w), bfhi(ow.w)};
;                 const f32x4 z0 = acc[ai][bj][m][0] * r, z1 = acc[ai][bj][m][1] * r;
;                 f32x4 g0, g1;
; #pragma unroll
;                 for (int e = 0; e < 4; ++e) { g0[e] = z0[e] * sigmoid_f(z0[e]); g1[e] = z1[e] * sigmoid_f(z1[e]); }
;                 const f32x4 y0 = g0 * ((o0 - mean) * rstd) * gg[bj][0], y1 = g1 * ((o1 - mean) * rstd) * gg[bj][1];
;                 *(u32x4*)(QKV + (size_t)row * RET_QKV + col) = EPI_PACK8(y0, y1); }
; #pragma unroll
;             for (int bj = 0; bj < 2; ++bj) oc[bj] = on[bj]; }
.Lwj1233_30446:
	v_pk_mul_f32 v[102:103], v[102:103], v[200:201] op_sel_hi:[1,0]
	v_pk_mul_f32 v[98:99], v[98:99], v[200:201] op_sel_hi:[1,0]
	v_mul_f32_e32 v104, 0xbfb8aa3b, v100
	v_mul_f32_e32 v105, 0xbfb8aa3b, v101
	v_mul_f32_e32 v106, 0xbfb8aa3b, v96
	v_mul_f32_e32 v107, 0xbfb8aa3b, v97
	v_exp_f32_e32 v104, v104
	v_exp_f32_e32 v105, v105
	v_exp_f32_e32 v106, v106
	v_exp_f32_e32 v107, v107
	v_mul_f32_e32 v110, 0xbfb8aa3b, v102
	v_mul_f32_e32 v111, 0xbfb8aa3b, v103
	v_exp_f32_e32 v110, v110
	v_exp_f32_e32 v111, v111
	v_mul_f32_e32 v126, 0xbfb8aa3b, v98
	v_mul_f32_e32 v127, 0xbfb8aa3b, v99
	v_exp_f32_e32 v126, v126
	v_exp_f32_e32 v127, v127
	v_add_f32_e32 v104, 1.0, v104
	v_add_f32_e32 v105, 1.0, v105
	v_add_f32_e32 v106, 1.0, v106
	v_add_f32_e32 v107, 1.0, v107
	v_rcp_f32_e32 v104, v104
	v_rcp_f32_e32 v105, v105
	v_rcp_f32_e32 v106, v106
	v_rcp_f32_e32 v107, v107
	v_add_f32_e32 v110, 1.0, v110
	v_add_f32_e32 v111, 1.0, v111
	v_rcp_f32_e32 v110, v110
	v_rcp_f32_e32 v111, v111
	v_add_f32_e32 v126, 1.0, v126
	v_add_f32_e32 v127, 1.0, v127
	v_lshlrev_b32_e32 v123, 16, v128
	v_and_b32_e32 v125, 0xffff0000, v128
	v_lshlrev_b32_e32 v128, 16, v129
	v_and_b32_e32 v129, 0xffff0000, v129
	v_rcp_f32_e32 v126, v126
	v_rcp_f32_e32 v127, v127
	v_pk_mul_f32 v[100:101], v[100:101], v[104:105]
	v_pk_mul_f32 v[96:97], v[96:97], v[106:107]
	v_sub_f32_e32 v105, v125, v122
	v_sub_f32_e32 v104, v123, v122
	v_sub_f32_e32 v107, v129, v122
	v_sub_f32_e32 v106, v128, v122
	v_lshlrev_b32_e32 v132, 16, v130
	v_and_b32_e32 v130, 0xffff0000, v130
	v_lshlrev_b32_e32 v133, 16, v131
	v_and_b32_e32 v131, 0xffff0000, v131
	v_pk_mul_f32 v[102:103], v[102:103], v[110:111]
	v_pk_mul_f32 v[106:107], v[124:125], v[106:107] op_sel_hi:[0,1]
	v_pk_mul_f32 v[104:105], v[124:125], v[104:105] op_sel_hi:[0,1]
	v_pk_mul_f32 v[100:101], v[100:101], v[104:105]
	v_pk_mul_f32 v[102:103], v[102:103], v[106:107]
	v_sub_f32_e32 v105, v130, v122
	v_sub_f32_e32 v104, v132, v122
	v_sub_f32_e32 v107, v131, v122
	v_sub_f32_e32 v106, v133, v122
	v_pk_mul_f32 v[98:99], v[98:99], v[126:127]
	v_pk_mul_f32 v[106:107], v[124:125], v[106:107] op_sel_hi:[0,1]
	v_pk_mul_f32 v[104:105], v[124:125], v[104:105] op_sel_hi:[0,1]
	v_pk_mul_f32 v[96:97], v[96:97], v[104:105]
	v_pk_mul_f32 v[98:99], v[98:99], v[106:107]
	v_pk_mul_f32 v[102:103], v[62:63], v[102:103]
	v_pk_mul_f32 v[100:101], v[60:61], v[100:101]
	v_pk_mul_f32 v[104:105], v[58:59], v[98:99]
	v_pk_mul_f32 v[98:99], v[56:57], v[96:97]
	v_cvt_pk_bf16_f32 v96, v100, v101
	v_cvt_pk_bf16_f32 v97, v102, v103
	v_pk_mul_f32 v[106:107], v[198:199], s[18:19] op_sel_hi:[1,0]
	v_cvt_pk_bf16_f32 v98, v98, v99
	v_cvt_pk_bf16_f32 v99, v104, v105
	s_cmp_lg_u32 s99, 0
	s_cbranch_scc1 .Lwt1233_30526
	global_store_dwordx4 v[108:109], v[96:99], off offset:256
	s_branch .Lwj1233_30526
.Lwt1233_30526:
	global_store_dwordx4 v[108:109], v[96:99], off offset:256 sc1
.Lwj1233_30526:
	v_fma_f32 v107, -v106, v106, v107
	v_max_f32_e32 v107, 0, v107
	v_lshlrev_b64 v[96:97], 13, v[196:197]
	v_lshl_add_u64 v[104:105], s[26:27], 0, v[96:97]
	v_lshl_add_u64 v[96:97], v[104:105], 0, s[16:17]
	v_lshl_add_u64 v[98:99], v[96:97], 0, v[180:181]
	v_lshl_add_u64 v[100:101], v[96:97], 0, v[168:169]
	global_load_dwordx4 v[96:99], v[98:99], off
	s_nop 0
	global_load_dwordx4 v[100:103], v[100:101], off
	v_add_f32_e32 v107, 0x3727c5ac, v107
	v_pk_mul_f32 v[92:93], v[92:93], v[194:195] op_sel_hi:[1,0]
	v_pk_mul_f32 v[88:89], v[88:89], v[194:195] op_sel_hi:[1,0]
	v_rsq_f32_e32 v108, v107
	s_waitcnt vmcnt(4)
	v_lshlrev_b32_e32 v107, 16, v116
	v_and_b32_e32 v109, 0xffff0000, v116
	v_lshlrev_b32_e32 v124, 16, v117
	v_and_b32_e32 v125, 0xffff0000, v117
	v_mul_f32_e32 v110, 0xbfb8aa3b, v92
	v_mul_f32_e32 v111, 0xbfb8aa3b, v93
	v_mul_f32_e32 v116, 0xbfb8aa3b, v88
	v_mul_f32_e32 v117, 0xbfb8aa3b, v89
	v_pk_mul_f32 v[94:95], v[94:95], v[194:195] op_sel_hi:[1,0]
	v_lshlrev_b32_e32 v126, 16, v118
	v_and_b32_e32 v127, 0xffff0000, v118
	v_lshlrev_b32_e32 v128, 16, v119
	v_exp_f32_e32 v110, v110
	v_exp_f32_e32 v111, v111
	v_and_b32_e32 v129, 0xffff0000, v119
	v_exp_f32_e32 v116, v116
	v_exp_f32_e32 v117, v117
	v_mul_f32_e32 v118, 0xbfb8aa3b, v94
	v_mul_f32_e32 v119, 0xbfb8aa3b, v95
	v_exp_f32_e32 v118, v118
	v_exp_f32_e32 v119, v119
	v_pk_mul_f32 v[90:91], v[90:91], v[194:195] op_sel_hi:[1,0]
	v_add_f32_e32 v110, 1.0, v110
	v_mul_f32_e32 v122, 0xbfb8aa3b, v90
	v_mul_f32_e32 v123, 0xbfb8aa3b, v91
	v_exp_f32_e32 v122, v122
	v_exp_f32_e32 v123, v123
	v_add_f32_e32 v111, 1.0, v111
	v_add_f32_e32 v116, 1.0, v116
	v_add_f32_e32 v117, 1.0, v117
	v_rcp_f32_e32 v110, v110
	v_rcp_f32_e32 v111, v111
	v_rcp_f32_e32 v116, v116
	v_rcp_f32_e32 v117, v117
	v_add_f32_e32 v118, 1.0, v118
	v_add_f32_e32 v119, 1.0, v119
	v_rcp_f32_e32 v118, v118
	v_rcp_f32_e32 v119, v119
	v_add_f32_e32 v122, 1.0, v122
	v_add_f32_e32 v123, 1.0, v123
	v_rcp_f32_e32 v122, v122
	v_rcp_f32_e32 v123, v123
	v_pk_mul_f32 v[92:93], v[92:93], v[110:111]
	v_pk_mul_f32 v[88:89], v[88:89], v[116:117]
	v_sub_f32_e32 v111, v109, v106
	v_sub_f32_e32 v110, v107, v106
	v_sub_f32_e32 v117, v125, v106
	v_sub_f32_e32 v116, v124, v106
	v_pk_mul_f32 v[94:95], v[94:95], v[118:119]
	v_pk_mul_f32 v[116:117], v[108:109], v[116:117] op_sel_hi:[0,1]
	v_pk_mul_f32 v[110:111], v[108:109], v[110:111] op_sel_hi:[0,1]
	v_pk_mul_f32 v[92:93], v[92:93], v[110:111]
	v_pk_mul_f32 v[94:95], v[94:95], v[116:117]
	v_sub_f32_e32 v111, v127, v106
	v_sub_f32_e32 v110, v126, v106
	v_sub_f32_e32 v117, v129, v106
	v_sub_f32_e32 v116, v128, v106
	v_pk_mul_f32 v[90:91], v[90:91], v[122:123]
	v_pk_mul_f32 v[116:117], v[108:109], v[116:117] op_sel_hi:[0,1]
	v_pk_mul_f32 v[110:111], v[108:109], v[110:111] op_sel_hi:[0,1]
	v_pk_mul_f32 v[88:89], v[88:89], v[110:111]
	v_pk_mul_f32 v[90:91], v[90:91], v[116:117]
	v_pk_mul_f32 v[92:93], v[76:77], v[92:93]
	v_pk_mul_f32 v[110:111], v[74:75], v[90:91]
	v_pk_mul_f32 v[90:91], v[72:73], v[88:89]
	v_pk_mul_f32 v[94:95], v[78:79], v[94:95]
	v_cvt_pk_bf16_f32 v88, v92, v93
	v_cvt_pk_bf16_f32 v90, v90, v91
	v_cvt_pk_bf16_f32 v91, v110, v111
	v_lshl_add_u64 v[92:93], v[120:121], 0, v[168:169]
	v_cvt_pk_bf16_f32 v89, v94, v95
	v_pk_mul_f32 v[84:85], v[84:85], v[194:195] op_sel_hi:[1,0]
	v_pk_mul_f32 v[80:81], v[80:81], v[194:195] op_sel_hi:[1,0]
	s_cmp_lg_u32 s99, 0
	s_cbranch_scc1 .Lwt1233_30623
	global_store_dwordx4 v[92:93], v[88:91], off
	s_branch .Lwj1233_30623

; __device__ __forceinline__ float sigmoid_f(float z) { return __builtin_amdgcn_rcpf(1.f + fexp(-z)); }
; #define EPI_IT_ROW(it) EPI_ROW((it) >> 2, (it) & 3)
; #define EPI_PACK8(v0, v1) (u32x4){pk2((v0)[0], (v0)[1]), pk2((v0)[2], (v0)[3]), pk2((v1)[0], (v1)[1]), pk2((v1)[2], (v1)[3])}
;     __device__ __forceinline__ void operator()(AccRef acc, const Unit& u, int wr, int wc, int fr, int fq) const {
;     ...
;         for (int it = 0; it < 8; ++it) { const int ai = it >> 2, m = it & 3, row = EPI_IT_ROW(it); const float r = rr[it];
;             if (it + 1 < 8) {
; #pragma unroll
;                 for (int bj = 0; bj < 2; ++bj) on[bj] = *(const u32x4*)(QKV + (size_t)EPI_IT_ROW(it + 1) * RET_QKV + 2048 + EPI_COL(bj)); }
;             const float mean = sts[it].x * (1.f / 512.f), var = fmaxf(sts[it].y * (1.f / 512.f) - mean * mean, 0.f), rstd = __builtin_amdgcn_rsqf(var + LN_EPS);
; #pragma unroll
;             for (int bj = 0; bj < 2; ++bj) { const int col = EPI_COL(bj);
;                 const u32x4 ow = oc[bj];
;                 const f32x4 o0 = (f32x4){bflo(ow.x), bfhi(ow.x), bflo(ow.y), bfhi(ow.y)}, o1 = (f32x4){bflo(ow.z), bfhi(ow.z), bflo(ow.w), bfhi(ow.w)};
;                 const f32x4 z0 = acc[ai][bj][m][0] * r, z1 = acc[ai][bj][m][1] * r;
;                 f32x4 g0, g1;
; #pragma unroll
;                 for (int e = 0; e < 4; ++e) { g0[e] = z0[e] * sigmoid_f(z0[e]); g1[e] = z1[e] * sigmoid_f(z1[e]); }
;                 const f32x4 y0 = g0 * ((o0 - mean) * rstd) * gg[bj][0], y1 = g1 * ((o1 - mean) * rstd) * gg[bj][1];
;                 *(u32x4*)(QKV + (size_t)row * RET_QKV + col) = EPI_PACK8(y0, y1); }
; #pragma unroll
;             for (int bj = 0; bj < 2; ++bj) oc[bj] = on[bj]; }
.Lwj1233_30623:
	v_pk_mul_f32 v[86:87], v[86:87], v[194:195] op_sel_hi:[1,0]
	v_pk_mul_f32 v[82:83], v[82:83], v[194:195] op_sel_hi:[1,0]
	v_mul_f32_e32 v88, 0xbfb8aa3b, v84
	v_mul_f32_e32 v89, 0xbfb8aa3b, v85
	v_mul_f32_e32 v90, 0xbfb8aa3b, v80
	v_mul_f32_e32 v91, 0xbfb8aa3b, v81
	v_exp_f32_e32 v88, v88
	v_exp_f32_e32 v89, v89
	v_exp_f32_e32 v90, v90
	v_exp_f32_e32 v91, v91
	v_mul_f32_e32 v94, 0xbfb8aa3b, v86
	v_mul_f32_e32 v95, 0xbfb8aa3b, v87
	v_exp_f32_e32 v94, v94
	v_exp_f32_e32 v95, v95
	v_mul_f32_e32 v110, 0xbfb8aa3b, v82
	v_mul_f32_e32 v111, 0xbfb8aa3b, v83
	v_exp_f32_e32 v110, v110
	v_exp_f32_e32 v111, v111
	v_add_f32_e32 v88, 1.0, v88
	v_add_f32_e32 v89, 1.0, v89
	v_add_f32_e32 v90, 1.0, v90
	v_add_f32_e32 v91, 1.0, v91
	v_rcp_f32_e32 v88, v88
	v_rcp_f32_e32 v89, v89
	v_rcp_f32_e32 v90, v90
	v_rcp_f32_e32 v91, v91
	v_add_f32_e32 v94, 1.0, v94
	v_add_f32_e32 v95, 1.0, v95
	v_rcp_f32_e32 v94, v94
	v_rcp_f32_e32 v95, v95
	v_add_f32_e32 v110, 1.0, v110
	v_add_f32_e32 v111, 1.0, v111
	v_lshlrev_b32_e32 v107, 16, v112
	v_and_b32_e32 v109, 0xffff0000, v112
	v_lshlrev_b32_e32 v112, 16, v113
	v_and_b32_e32 v113, 0xffff0000, v113
	v_rcp_f32_e32 v110, v110
	v_rcp_f32_e32 v111, v111
	v_pk_mul_f32 v[84:85], v[84:85], v[88:89]
	v_pk_mul_f32 v[80:81], v[80:81], v[90:91]
	v_sub_f32_e32 v89, v109, v106
	v_sub_f32_e32 v88, v107, v106
	v_sub_f32_e32 v91, v113, v106
	v_sub_f32_e32 v90, v112, v106
	v_lshlrev_b32_e32 v116, 16, v114
	v_and_b32_e32 v114, 0xffff0000, v114
	v_lshlrev_b32_e32 v117, 16, v115
	v_and_b32_e32 v115, 0xffff0000, v115
	v_pk_mul_f32 v[86:87], v[86:87], v[94:95]
	v_pk_mul_f32 v[90:91], v[108:109], v[90:91] op_sel_hi:[0,1]
	v_pk_mul_f32 v[88:89], v[108:109], v[88:89] op_sel_hi:[0,1]
	v_pk_mul_f32 v[84:85], v[84:85], v[88:89]
	v_pk_mul_f32 v[86:87], v[86:87], v[90:91]
	v_sub_f32_e32 v89, v114, v106
	v_sub_f32_e32 v88, v116, v106
	v_sub_f32_e32 v91, v115, v106
	v_sub_f32_e32 v90, v117, v106
	v_pk_mul_f32 v[82:83], v[82:83], v[110:111]
	v_pk_mul_f32 v[90:91], v[108:109], v[90:91] op_sel_hi:[0,1]
	v_pk_mul_f32 v[88:89], v[108:109], v[88:89] op_sel_hi:[0,1]
	v_pk_mul_f32 v[80:81], v[80:81], v[88:89]
	v_pk_mul_f32 v[82:83], v[82:83], v[90:91]
	v_pk_mul_f32 v[86:87], v[62:63], v[86:87]
	v_pk_mul_f32 v[84:85], v[60:61], v[84:85]
	v_pk_mul_f32 v[88:89], v[58:59], v[82:83]
	v_pk_mul_f32 v[82:83], v[56:57], v[80:81]
	v_cvt_pk_bf16_f32 v80, v84, v85
	v_cvt_pk_bf16_f32 v81, v86, v87
	v_pk_mul_f32 v[90:91], v[192:193], s[18:19] op_sel_hi:[1,0]
	v_cvt_pk_bf16_f32 v82, v82, v83
	v_cvt_pk_bf16_f32 v83, v88, v89
	s_cmp_lg_u32 s99, 0
	s_cbranch_scc1 .Lwt1233_30703
	global_store_dwordx4 v[92:93], v[80:83], off offset:256
	s_branch .Lwj1233_30703
.Lwt1233_30703:
	global_store_dwordx4 v[92:93], v[80:83], off offset:256 sc1
.Lwj1233_30703:
	v_fma_f32 v91, -v90, v90, v91
	v_max_f32_e32 v91, 0, v91
	v_lshlrev_b64 v[80:81], 13, v[190:191]
	v_lshl_add_u64 v[88:89], s[26:27], 0, v[80:81]
	v_lshl_add_u64 v[80:81], v[88:89], 0, s[16:17]
	v_lshl_add_u64 v[82:83], v[80:81], 0, v[180:181]
	v_lshl_add_u64 v[84:85], v[80:81], 0, v[168:169]
	global_load_dwordx4 v[80:83], v[82:83], off
	s_nop 0
	global_load_dwordx4 v[84:87], v[84:85], off
	v_add_f32_e32 v91, 0x3727c5ac, v91
	v_pk_mul_f32 v[68:69], v[68:69], v[188:189] op_sel_hi:[1,0]
	v_pk_mul_f32 v[64:65], v[64:65], v[188:189] op_sel_hi:[1,0]
	v_rsq_f32_e32 v92, v91
	s_waitcnt vmcnt(4)
	v_lshlrev_b32_e32 v91, 16, v100
	v_and_b32_e32 v93, 0xffff0000, v100
	v_lshlrev_b32_e32 v108, 16, v101
	v_and_b32_e32 v109, 0xffff0000, v101
	v_mul_f32_e32 v94, 0xbfb8aa3b, v68
	v_mul_f32_e32 v95, 0xbfb8aa3b, v69
	v_mul_f32_e32 v100, 0xbfb8aa3b, v64
	v_mul_f32_e32 v101, 0xbfb8aa3b, v65
	v_pk_mul_f32 v[70:71], v[70:71], v[188:189] op_sel_hi:[1,0]
	v_lshlrev_b32_e32 v110, 16, v102
	v_and_b32_e32 v111, 0xffff0000, v102
	v_lshlrev_b32_e32 v112, 16, v103
	v_exp_f32_e32 v94, v94
	v_exp_f32_e32 v95, v95
	v_and_b32_e32 v113, 0xffff0000, v103
	v_exp_f32_e32 v100, v100
	v_exp_f32_e32 v101, v101
	v_mul_f32_e32 v102, 0xbfb8aa3b, v70
	v_mul_f32_e32 v103, 0xbfb8aa3b, v71
	v_exp_f32_e32 v102, v102
	v_exp_f32_e32 v103, v103
	v_pk_mul_f32 v[66:67], v[66:67], v[188:189] op_sel_hi:[1,0]
	v_add_f32_e32 v94, 1.0, v94
	v_mul_f32_e32 v106, 0xbfb8aa3b, v66
	v_mul_f32_e32 v107, 0xbfb8aa3b, v67
	v_exp_f32_e32 v106, v106
	v_exp_f32_e32 v107, v107
	v_add_f32_e32 v95, 1.0, v95
	v_add_f32_e32 v100, 1.0, v100
	v_add_f32_e32 v101, 1.0, v101
	v_rcp_f32_e32 v94, v94
	v_rcp_f32_e32 v95, v95
	v_rcp_f32_e32 v100, v100
	v_rcp_f32_e32 v101, v101
	v_add_f32_e32 v102, 1.0, v102
	v_add_f32_e32 v103, 1.0, v103
	v_rcp_f32_e32 v102, v102
	v_rcp_f32_e32 v103, v103
	v_add_f32_e32 v106, 1.0, v106
	v_add_f32_e32 v107, 1.0, v107
	v_rcp_f32_e32 v106, v106
	v_rcp_f32_e32 v107, v107
	v_pk_mul_f32 v[68:69], v[68:69], v[94:95]
	v_pk_mul_f32 v[64:65], v[64:65], v[100:101]
	v_sub_f32_e32 v95, v93, v90
	v_sub_f32_e32 v94, v91, v90
	v_sub_f32_e32 v101, v109, v90
	v_sub_f32_e32 v100, v108, v90
	v_pk_mul_f32 v[70:71], v[70:71], v[102:103]
	v_pk_mul_f32 v[100:101], v[92:93], v[100:101] op_sel_hi:[0,1]
	v_pk_mul_f32 v[94:95], v[92:93], v[94:95] op_sel_hi:[0,1]
	v_pk_mul_f32 v[68:69], v[68:69], v[94:95]
	v_pk_mul_f32 v[70:71], v[70:71], v[100:101]
	v_sub_f32_e32 v95, v111, v90
	v_sub_f32_e32 v94, v110, v90
	v_sub_f32_e32 v101, v113, v90
	v_sub_f32_e32 v100, v112, v90
	v_pk_mul_f32 v[66:67], v[66:67], v[106:107]
	v_pk_mul_f32 v[100:101], v[92:93], v[100:101] op_sel_hi:[0,1]
	v_pk_mul_f32 v[94:95], v[92:93], v[94:95] op_sel_hi:[0,1]
	v_pk_mul_f32 v[64:65], v[64:65], v[94:95]
	v_pk_mul_f32 v[66:67], v[66:67], v[100:101]
	v_pk_mul_f32 v[68:69], v[76:77], v[68:69]
	v_pk_mul_f32 v[94:95], v[74:75], v[66:67]
	v_pk_mul_f32 v[66:67], v[72:73], v[64:65]
	v_pk_mul_f32 v[70:71], v[78:79], v[70:71]
	v_cvt_pk_bf16_f32 v64, v68, v69
	v_cvt_pk_bf16_f32 v66, v66, v67
	v_cvt_pk_bf16_f32 v67, v94, v95
	v_lshl_add_u64 v[68:69], v[104:105], 0, v[168:169]
	v_cvt_pk_bf16_f32 v65, v70, v71
	v_pk_mul_f32 v[52:53], v[52:53], v[188:189] op_sel_hi:[1,0]
	v_pk_mul_f32 v[48:49], v[48:49], v[188:189] op_sel_hi:[1,0]
	s_cmp_lg_u32 s99, 0
	s_cbranch_scc1 .Lwt1233_30800
	global_store_dwordx4 v[68:69], v[64:67], off
	s_branch .Lwj1233_30800

; __device__ __forceinline__ float sigmoid_f(float z) { return __builtin_amdgcn_rcpf(1.f + fexp(-z)); }
; #define EPI_IT_ROW(it) EPI_ROW((it) >> 2, (it) & 3)
; #define EPI_PACK8(v0, v1) (u32x4){pk2((v0)[0], (v0)[1]), pk2((v0)[2], (v0)[3]), pk2((v1)[0], (v1)[1]), pk2((v1)[2], (v1)[3])}
;     __device__ __forceinline__ void operator()(AccRef acc, const Unit& u, int wr, int wc, int fr, int fq) const {
;     ...
;         for (int it = 0; it < 8; ++it) { const int ai = it >> 2, m = it & 3, row = EPI_IT_ROW(it); const float r = rr[it];
;             if (it + 1 < 8) {
; #pragma unroll
;                 for (int bj = 0; bj < 2; ++bj) on[bj] = *(const u32x4*)(QKV + (size_t)EPI_IT_ROW(it + 1) * RET_QKV + 2048 + EPI_COL(bj)); }
;             const float mean = sts[it].x * (1.f / 512.f), var = fmaxf(sts[it].y * (1.f / 512.f) - mean * mean, 0.f), rstd = __builtin_amdgcn_rsqf(var + LN_EPS);
; #pragma unroll
;             for (int bj = 0; bj < 2; ++bj) { const int col = EPI_COL(bj);
;                 const u32x4 ow = oc[bj];
;                 const f32x4 o0 = (f32x4){bflo(ow.x), bfhi(ow.x), bflo(ow.y), bfhi(ow.y)}, o1 = (f32x4){bflo(ow.z), bfhi(ow.z), bflo(ow.w), bfhi(ow.w)};
;                 const f32x4 z0 = acc[ai][bj][m][0] * r, z1 = acc[ai][bj][m][1] * r;
;                 f32x4 g0, g1;
; #pragma unroll
;                 for (int e = 0; e < 4; ++e) { g0[e] = z0[e] * sigmoid_f(z0[e]); g1[e] = z1[e] * sigmoid_f(z1[e]); }
;                 const f32x4 y0 = g0 * ((o0 - mean) * rstd) * gg[bj][0], y1 = g1 * ((o1 - mean) * rstd) * gg[bj][1];
;                 *(u32x4*)(QKV + (size_t)row * RET_QKV + col) = EPI_PACK8(y0, y1); }
; #pragma unroll
;             for (int bj = 0; bj < 2; ++bj) oc[bj] = on[bj]; }
.Lwj1233_30800:
	v_pk_mul_f32 v[54:55], v[54:55], v[188:189] op_sel_hi:[1,0]
	v_pk_mul_f32 v[50:51], v[50:51], v[188:189] op_sel_hi:[1,0]
	v_mul_f32_e32 v64, 0xbfb8aa3b, v52
	v_mul_f32_e32 v65, 0xbfb8aa3b, v53
	v_mul_f32_e32 v66, 0xbfb8aa3b, v48
	v_mul_f32_e32 v67, 0xbfb8aa3b, v49
	v_exp_f32_e32 v64, v64
	v_exp_f32_e32 v65, v65
	v_exp_f32_e32 v66, v66
	v_exp_f32_e32 v67, v67
	v_mul_f32_e32 v70, 0xbfb8aa3b, v54
	v_mul_f32_e32 v71, 0xbfb8aa3b, v55
	v_exp_f32_e32 v70, v70
	v_exp_f32_e32 v71, v71
	v_mul_f32_e32 v94, 0xbfb8aa3b, v50
	v_mul_f32_e32 v95, 0xbfb8aa3b, v51
	v_exp_f32_e32 v94, v94
	v_exp_f32_e32 v95, v95
	v_add_f32_e32 v64, 1.0, v64
	v_add_f32_e32 v65, 1.0, v65
	v_add_f32_e32 v66, 1.0, v66
	v_add_f32_e32 v67, 1.0, v67
	v_rcp_f32_e32 v64, v64
	v_rcp_f32_e32 v65, v65
	v_rcp_f32_e32 v66, v66
	v_rcp_f32_e32 v67, v67
	v_add_f32_e32 v70, 1.0, v70
	v_add_f32_e32 v71, 1.0, v71
	v_rcp_f32_e32 v70, v70
	v_rcp_f32_e32 v71, v71
	v_add_f32_e32 v94, 1.0, v94
	v_add_f32_e32 v95, 1.0, v95
	v_lshlrev_b32_e32 v91, 16, v96
	v_and_b32_e32 v93, 0xffff0000, v96
	v_lshlrev_b32_e32 v96, 16, v97
	v_and_b32_e32 v97, 0xffff0000, v97
	v_rcp_f32_e32 v94, v94
	v_rcp_f32_e32 v95, v95
	v_pk_mul_f32 v[52:53], v[52:53], v[64:65]
	v_pk_mul_f32 v[48:49], v[48:49], v[66:67]
	v_sub_f32_e32 v65, v93, v90
	v_sub_f32_e32 v64, v91, v90
	v_sub_f32_e32 v67, v97, v90
	v_sub_f32_e32 v66, v96, v90
	v_lshlrev_b32_e32 v100, 16, v98
	v_and_b32_e32 v98, 0xffff0000, v98
	v_lshlrev_b32_e32 v101, 16, v99
	v_and_b32_e32 v99, 0xffff0000, v99
	v_pk_mul_f32 v[54:55], v[54:55], v[70:71]
	v_pk_mul_f32 v[66:67], v[92:93], v[66:67] op_sel_hi:[0,1]
	v_pk_mul_f32 v[64:65], v[92:93], v[64:65] op_sel_hi:[0,1]
	v_pk_mul_f32 v[52:53], v[52:53], v[64:65]
	v_pk_mul_f32 v[54:55], v[54:55], v[66:67]
	v_sub_f32_e32 v65, v98, v90
	v_sub_f32_e32 v64, v100, v90
	v_sub_f32_e32 v67, v99, v90
	v_sub_f32_e32 v66, v101, v90
	v_pk_mul_f32 v[50:51], v[50:51], v[94:95]
	v_pk_mul_f32 v[66:67], v[92:93], v[66:67] op_sel_hi:[0,1]
	v_pk_mul_f32 v[64:65], v[92:93], v[64:65] op_sel_hi:[0,1]
	v_pk_mul_f32 v[48:49], v[48:49], v[64:65]
	v_pk_mul_f32 v[50:51], v[50:51], v[66:67]
	v_pk_mul_f32 v[54:55], v[62:63], v[54:55]
	v_pk_mul_f32 v[52:53], v[60:61], v[52:53]
	v_pk_mul_f32 v[64:65], v[58:59], v[50:51]
	v_pk_mul_f32 v[50:51], v[56:57], v[48:49]
	v_cvt_pk_bf16_f32 v48, v52, v53
	v_cvt_pk_bf16_f32 v49, v54, v55
	v_pk_mul_f32 v[66:67], v[186:187], s[18:19] op_sel_hi:[1,0]
	v_cvt_pk_bf16_f32 v50, v50, v51
	v_cvt_pk_bf16_f32 v51, v64, v65
	s_cmp_lg_u32 s99, 0
	s_cbranch_scc1 .Lwt1233_30880
	global_store_dwordx4 v[68:69], v[48:51], off offset:256
	s_branch .Lwj1233_30880
.Lwt1233_30880:
	global_store_dwordx4 v[68:69], v[48:51], off offset:256 sc1
.Lwj1233_30880:
	v_fma_f32 v67, -v66, v66, v67
	v_max_f32_e32 v67, 0, v67
	v_lshlrev_b64 v[48:49], 13, v[184:185]
	v_lshl_add_u64 v[64:65], s[26:27], 0, v[48:49]
	v_lshl_add_u64 v[48:49], v[64:65], 0, s[16:17]
	v_lshl_add_u64 v[50:51], v[48:49], 0, v[180:181]
	v_lshl_add_u64 v[52:53], v[48:49], 0, v[168:169]
	global_load_dwordx4 v[48:51], v[50:51], off
	s_nop 0
	global_load_dwordx4 v[52:55], v[52:53], off
	v_add_f32_e32 v67, 0x3727c5ac, v67
	v_pk_mul_f32 v[44:45], v[44:45], v[182:183] op_sel_hi:[1,0]
	v_pk_mul_f32 v[40:41], v[40:41], v[182:183] op_sel_hi:[1,0]
	v_rsq_f32_e32 v68, v67
	s_waitcnt vmcnt(4)
	v_lshlrev_b32_e32 v67, 16, v84
	v_and_b32_e32 v69, 0xffff0000, v84
	v_lshlrev_b32_e32 v92, 16, v85
	v_and_b32_e32 v93, 0xffff0000, v85
	v_mul_f32_e32 v70, 0xbfb8aa3b, v44
	v_mul_f32_e32 v71, 0xbfb8aa3b, v45
	v_mul_f32_e32 v84, 0xbfb8aa3b, v40
	v_mul_f32_e32 v85, 0xbfb8aa3b, v41
	v_pk_mul_f32 v[46:47], v[46:47], v[182:183] op_sel_hi:[1,0]
	v_lshlrev_b32_e32 v94, 16, v86
	v_and_b32_e32 v95, 0xffff0000, v86
	v_lshlrev_b32_e32 v96, 16, v87
	v_exp_f32_e32 v70, v70
	v_exp_f32_e32 v71, v71
	v_and_b32_e32 v97, 0xffff0000, v87
	v_exp_f32_e32 v84, v84
	v_exp_f32_e32 v85, v85
	v_mul_f32_e32 v86, 0xbfb8aa3b, v46
	v_mul_f32_e32 v87, 0xbfb8aa3b, v47
	v_exp_f32_e32 v86, v86
	v_exp_f32_e32 v87, v87
	v_pk_mul_f32 v[42:43], v[42:43], v[182:183] op_sel_hi:[1,0]
	v_add_f32_e32 v70, 1.0, v70
	v_mul_f32_e32 v90, 0xbfb8aa3b, v42
	v_mul_f32_e32 v91, 0xbfb8aa3b, v43
	v_exp_f32_e32 v90, v90
	v_exp_f32_e32 v91, v91
	v_add_f32_e32 v71, 1.0, v71
	v_add_f32_e32 v84, 1.0, v84
	v_add_f32_e32 v85, 1.0, v85
	v_rcp_f32_e32 v70, v70
	v_rcp_f32_e32 v71, v71
	v_rcp_f32_e32 v84, v84
	v_rcp_f32_e32 v85, v85
	v_add_f32_e32 v86, 1.0, v86
	v_add_f32_e32 v87, 1.0, v87
	v_rcp_f32_e32 v86, v86
	v_rcp_f32_e32 v87, v87
	v_add_f32_e32 v90, 1.0, v90
	v_add_f32_e32 v91, 1.0, v91
	v_rcp_f32_e32 v90, v90
	v_rcp_f32_e32 v91, v91
	v_pk_mul_f32 v[44:45], v[44:45], v[70:71]
	v_pk_mul_f32 v[40:41], v[40:41], v[84:85]
	v_sub_f32_e32 v71, v69, v66
	v_sub_f32_e32 v70, v67, v66
	v_sub_f32_e32 v85, v93, v66
	v_sub_f32_e32 v84, v92, v66
	v_pk_mul_f32 v[46:47], v[46:47], v[86:87]
	v_pk_mul_f32 v[84:85], v[68:69], v[84:85] op_sel_hi:[0,1]
	v_pk_mul_f32 v[70:71], v[68:69], v[70:71] op_sel_hi:[0,1]
	v_pk_mul_f32 v[44:45], v[44:45], v[70:71]
	v_pk_mul_f32 v[46:47], v[46:47], v[84:85]
	v_sub_f32_e32 v71, v95, v66
	v_sub_f32_e32 v70, v94, v66
	v_sub_f32_e32 v85, v97, v66
	v_sub_f32_e32 v84, v96, v66
	v_pk_mul_f32 v[42:43], v[42:43], v[90:91]
	v_pk_mul_f32 v[84:85], v[68:69], v[84:85] op_sel_hi:[0,1]
	v_pk_mul_f32 v[70:71], v[68:69], v[70:71] op_sel_hi:[0,1]
	v_pk_mul_f32 v[40:41], v[40:41], v[70:71]
	v_pk_mul_f32 v[42:43], v[42:43], v[84:85]
	v_pk_mul_f32 v[44:45], v[76:77], v[44:45]
	v_pk_mul_f32 v[70:71], v[74:75], v[42:43]
	v_pk_mul_f32 v[42:43], v[72:73], v[40:41]
	v_pk_mul_f32 v[46:47], v[78:79], v[46:47]
	v_cvt_pk_bf16_f32 v40, v44, v45
	v_cvt_pk_bf16_f32 v42, v42, v43
	v_cvt_pk_bf16_f32 v43, v70, v71
	v_lshl_add_u64 v[44:45], v[88:89], 0, v[168:169]
	v_cvt_pk_bf16_f32 v41, v46, v47
	v_pk_mul_f32 v[36:37], v[36:37], v[182:183] op_sel_hi:[1,0]
	v_pk_mul_f32 v[32:33], v[32:33], v[182:183] op_sel_hi:[1,0]
	s_cmp_lg_u32 s99, 0
	s_cbranch_scc1 .Lwt1233_30977
	global_store_dwordx4 v[44:45], v[40:43], off
	s_branch .Lwj1233_30977
; __device__ __forceinline__ float sigmoid_f(float z) { return __builtin_amdgcn_rcpf(1.f + fexp(-z)); }
; #define EPI_IT_ROW(it) EPI_ROW((it) >> 2, (it) & 3)
; #define EPI_PACK8(v0, v1) (u32x4){pk2((v0)[0], (v0)[1]), pk2((v0)[2], (v0)[3]), pk2((v1)[0], (v1)[1]), pk2((v1)[2], (v1)[3])}
;     __device__ __forceinline__ void operator()(AccRef acc, const Unit& u, int wr, int wc, int fr, int fq) const {
;     ...
;         for (int it = 0; it < 8; ++it) { const int ai = it >> 2, m = it & 3, row = EPI_IT_ROW(it); const float r = rr[it];
;             if (it + 1 < 8) {
; #pragma unroll
;                 for (int bj = 0; bj < 2; ++bj) on[bj] = *(const u32x4*)(QKV + (size_t)EPI_IT_ROW(it + 1) * RET_QKV + 2048 + EPI_COL(bj)); }
;             const float mean = sts[it].x * (1.f / 512.f), var = fmaxf(sts[it].y * (1.f / 512.f) - mean * mean, 0.f), rstd = __builtin_amdgcn_rsqf(var + LN_EPS);
; #pragma unroll
;             for (int bj = 0; bj < 2; ++bj) { const int col = EPI_COL(bj);
;                 const u32x4 ow = oc[bj];
;                 const f32x4 o0 = (f32x4){bflo(ow.x), bfhi(ow.x), bflo(ow.y), bfhi(ow.y)}, o1 = (f32x4){bflo(ow.z), bfhi(ow.z), bflo(ow.w), bfhi(ow.w)};
;                 const f32x4 z0 = acc[ai][bj][m][0] * r, z1 = acc[ai][bj][m][1] * r;
;                 f32x4 g0, g1;
; #pragma unroll
;                 for (int e = 0; e < 4; ++e) { g0[e] = z0[e] * sigmoid_f(z0[e]); g1[e] = z1[e] * sigmoid_f(z1[e]); }
;                 const f32x4 y0 = g0 * ((o0 - mean) * rstd) * gg[bj][0], y1 = g1 * ((o1 - mean) * rstd) * gg[bj][1];
;                 *(u32x4*)(QKV + (size_t)row * RET_QKV + col) = EPI_PACK8(y0, y1); }
; #pragma unroll
;             for (int bj = 0; bj < 2; ++bj) oc[bj] = on[bj]; }
.Lwt1233_30977:
	global_store_dwordx4 v[44:45], v[40:43], off sc1
.Lwj1233_30977:
	v_pk_mul_f32 v[38:39], v[38:39], v[182:183] op_sel_hi:[1,0]
	v_pk_mul_f32 v[34:35], v[34:35], v[182:183] op_sel_hi:[1,0]
	v_mul_f32_e32 v40, 0xbfb8aa3b, v36
	v_mul_f32_e32 v41, 0xbfb8aa3b, v37
	v_mul_f32_e32 v42, 0xbfb8aa3b, v32
	v_mul_f32_e32 v43, 0xbfb8aa3b, v33
	v_exp_f32_e32 v40, v40
	v_exp_f32_e32 v41, v41
	v_exp_f32_e32 v42, v42
	v_exp_f32_e32 v43, v43
	v_mul_f32_e32 v46, 0xbfb8aa3b, v38
	v_mul_f32_e32 v47, 0xbfb8aa3b, v39
	v_exp_f32_e32 v46, v46
	v_exp_f32_e32 v47, v47
	v_mul_f32_e32 v70, 0xbfb8aa3b, v34
	v_mul_f32_e32 v71, 0xbfb8aa3b, v35
	v_exp_f32_e32 v70, v70
	v_exp_f32_e32 v71, v71
	v_add_f32_e32 v40, 1.0, v40
	v_add_f32_e32 v41, 1.0, v41
	v_add_f32_e32 v42, 1.0, v42
	v_add_f32_e32 v43, 1.0, v43
	v_rcp_f32_e32 v40, v40
	v_rcp_f32_e32 v41, v41
	v_rcp_f32_e32 v42, v42
	v_rcp_f32_e32 v43, v43
	v_add_f32_e32 v46, 1.0, v46
	v_add_f32_e32 v47, 1.0, v47
	v_rcp_f32_e32 v46, v46
	v_rcp_f32_e32 v47, v47
	v_add_f32_e32 v70, 1.0, v70
	v_add_f32_e32 v71, 1.0, v71
	v_lshlrev_b32_e32 v67, 16, v80
	v_and_b32_e32 v69, 0xffff0000, v80
	v_lshlrev_b32_e32 v80, 16, v81
	v_and_b32_e32 v81, 0xffff0000, v81
	v_rcp_f32_e32 v70, v70
	v_rcp_f32_e32 v71, v71
	v_pk_mul_f32 v[36:37], v[36:37], v[40:41]
	v_pk_mul_f32 v[32:33], v[32:33], v[42:43]
	v_sub_f32_e32 v41, v69, v66
	v_sub_f32_e32 v40, v67, v66
	v_sub_f32_e32 v43, v81, v66
	v_sub_f32_e32 v42, v80, v66
	v_lshlrev_b32_e32 v84, 16, v82
	v_and_b32_e32 v82, 0xffff0000, v82
	v_lshlrev_b32_e32 v85, 16, v83
	v_and_b32_e32 v83, 0xffff0000, v83
	v_pk_mul_f32 v[38:39], v[38:39], v[46:47]
	v_pk_mul_f32 v[42:43], v[68:69], v[42:43] op_sel_hi:[0,1]
	v_pk_mul_f32 v[40:41], v[68:69], v[40:41] op_sel_hi:[0,1]
	v_pk_mul_f32 v[36:37], v[36:37], v[40:41]
	v_pk_mul_f32 v[38:39], v[38:39], v[42:43]
	v_sub_f32_e32 v41, v82, v66
	v_sub_f32_e32 v40, v84, v66
	v_sub_f32_e32 v43, v83, v66
	v_sub_f32_e32 v42, v85, v66
	v_pk_mul_f32 v[34:35], v[34:35], v[70:71]
	v_pk_mul_f32 v[42:43], v[68:69], v[42:43] op_sel_hi:[0,1]
	v_pk_mul_f32 v[40:41], v[68:69], v[40:41] op_sel_hi:[0,1]
	v_pk_mul_f32 v[32:33], v[32:33], v[40:41]
	v_pk_mul_f32 v[34:35], v[34:35], v[42:43]
	v_pk_mul_f32 v[38:39], v[62:63], v[38:39]
	v_pk_mul_f32 v[36:37], v[60:61], v[36:37]
	v_pk_mul_f32 v[40:41], v[58:59], v[34:35]
	v_pk_mul_f32 v[34:35], v[56:57], v[32:33]
	v_cvt_pk_bf16_f32 v32, v36, v37
	v_cvt_pk_bf16_f32 v33, v38, v39
	v_pk_mul_f32 v[42:43], v[178:179], s[18:19] op_sel_hi:[1,0]
	v_cvt_pk_bf16_f32 v34, v34, v35
	v_cvt_pk_bf16_f32 v35, v40, v41
	s_cmp_lg_u32 s99, 0
	s_cbranch_scc1 .Lwt1233_31057
	global_store_dwordx4 v[44:45], v[32:35], off offset:256
	s_branch .Lwj1233_31057
.Lwt1233_31057:
	global_store_dwordx4 v[44:45], v[32:35], off offset:256 sc1
.Lwj1233_31057:
	v_fma_f32 v43, -v42, v42, v43
	v_max_f32_e32 v43, 0, v43
	v_lshlrev_b64 v[32:33], 13, v[174:175]
	v_lshl_add_u64 v[40:41], s[26:27], 0, v[32:33]
	v_lshl_add_u64 v[32:33], v[40:41], 0, s[16:17]
	v_lshl_add_u64 v[34:35], v[32:33], 0, v[180:181]
	v_lshl_add_u64 v[36:37], v[32:33], 0, v[168:169]
	global_load_dwordx4 v[32:35], v[34:35], off
	s_nop 0
	global_load_dwordx4 v[36:39], v[36:37], off
	v_add_f32_e32 v43, 0x3727c5ac, v43
	v_pk_mul_f32 v[28:29], v[28:29], v[172:173] op_sel_hi:[1,0]
	v_pk_mul_f32 v[24:25], v[24:25], v[172:173] op_sel_hi:[1,0]
	v_rsq_f32_e32 v44, v43
	s_waitcnt vmcnt(4)
	v_lshlrev_b32_e32 v43, 16, v52
	v_and_b32_e32 v45, 0xffff0000, v52
	v_lshlrev_b32_e32 v68, 16, v53
	v_and_b32_e32 v69, 0xffff0000, v53
	v_mul_f32_e32 v46, 0xbfb8aa3b, v28
	v_mul_f32_e32 v47, 0xbfb8aa3b, v29
	v_mul_f32_e32 v52, 0xbfb8aa3b, v24
	v_mul_f32_e32 v53, 0xbfb8aa3b, v25
	v_pk_mul_f32 v[30:31], v[30:31], v[172:173] op_sel_hi:[1,0]
	v_lshlrev_b32_e32 v70, 16, v54
	v_and_b32_e32 v71, 0xffff0000, v54
	v_lshlrev_b32_e32 v80, 16, v55
	v_exp_f32_e32 v46, v46
	v_exp_f32_e32 v47, v47
	v_and_b32_e32 v81, 0xffff0000, v55
	v_exp_f32_e32 v52, v52
	v_exp_f32_e32 v53, v53
	v_mul_f32_e32 v54, 0xbfb8aa3b, v30
	v_mul_f32_e32 v55, 0xbfb8aa3b, v31
	v_exp_f32_e32 v54, v54
	v_exp_f32_e32 v55, v55
	v_pk_mul_f32 v[26:27], v[26:27], v[172:173] op_sel_hi:[1,0]
	v_add_f32_e32 v46, 1.0, v46
	v_mul_f32_e32 v66, 0xbfb8aa3b, v26
	v_mul_f32_e32 v67, 0xbfb8aa3b, v27
	v_exp_f32_e32 v66, v66
	v_exp_f32_e32 v67, v67
	v_add_f32_e32 v47, 1.0, v47
	v_add_f32_e32 v52, 1.0, v52
	v_add_f32_e32 v53, 1.0, v53
	v_rcp_f32_e32 v46, v46
	v_rcp_f32_e32 v47, v47
	v_rcp_f32_e32 v52, v52
	v_rcp_f32_e32 v53, v53
	v_add_f32_e32 v54, 1.0, v54
	v_add_f32_e32 v55, 1.0, v55
	v_rcp_f32_e32 v54, v54
	v_rcp_f32_e32 v55, v55
	v_add_f32_e32 v66, 1.0, v66
	v_add_f32_e32 v67, 1.0, v67
	v_rcp_f32_e32 v66, v66
	v_rcp_f32_e32 v67, v67
	v_pk_mul_f32 v[28:29], v[28:29], v[46:47]
	v_pk_mul_f32 v[24:25], v[24:25], v[52:53]
	v_sub_f32_e32 v47, v45, v42
	v_sub_f32_e32 v46, v43, v42
	v_sub_f32_e32 v53, v69, v42
	v_sub_f32_e32 v52, v68, v42
	v_pk_mul_f32 v[30:31], v[30:31], v[54:55]
	v_pk_mul_f32 v[52:53], v[44:45], v[52:53] op_sel_hi:[0,1]
	v_pk_mul_f32 v[46:47], v[44:45], v[46:47] op_sel_hi:[0,1]
	v_pk_mul_f32 v[28:29], v[28:29], v[46:47]
	v_pk_mul_f32 v[30:31], v[30:31], v[52:53]
	v_sub_f32_e32 v47, v71, v42
	v_sub_f32_e32 v46, v70, v42
	v_sub_f32_e32 v53, v81, v42
	v_sub_f32_e32 v52, v80, v42
	v_pk_mul_f32 v[26:27], v[26:27], v[66:67]
	v_pk_mul_f32 v[52:53], v[44:45], v[52:53] op_sel_hi:[0,1]
	v_pk_mul_f32 v[46:47], v[44:45], v[46:47] op_sel_hi:[0,1]
	v_pk_mul_f32 v[24:25], v[24:25], v[46:47]
	v_pk_mul_f32 v[26:27], v[26:27], v[52:53]
	v_pk_mul_f32 v[28:29], v[76:77], v[28:29]
	v_pk_mul_f32 v[46:47], v[74:75], v[26:27]
	v_pk_mul_f32 v[26:27], v[72:73], v[24:25]
	v_pk_mul_f32 v[30:31], v[78:79], v[30:31]
	v_cvt_pk_bf16_f32 v24, v28, v29
	v_cvt_pk_bf16_f32 v26, v26, v27
	v_cvt_pk_bf16_f32 v27, v46, v47
	v_lshl_add_u64 v[28:29], v[64:65], 0, v[168:169]
	v_cvt_pk_bf16_f32 v25, v30, v31
	v_pk_mul_f32 v[20:21], v[20:21], v[172:173] op_sel_hi:[1,0]
	v_pk_mul_f32 v[16:17], v[16:17], v[172:173] op_sel_hi:[1,0]
	s_cmp_lg_u32 s99, 0
	s_cbranch_scc1 .Lwt1233_31154
	global_store_dwordx4 v[28:29], v[24:27], off
	s_branch .Lwj1233_31154

; __device__ __forceinline__ float sigmoid_f(float z) { return __builtin_amdgcn_rcpf(1.f + fexp(-z)); }
; #define EPI_IT_ROW(it) EPI_ROW((it) >> 2, (it) & 3)
; #define EPI_PACK8(v0, v1) (u32x4){pk2((v0)[0], (v0)[1]), pk2((v0)[2], (v0)[3]), pk2((v1)[0], (v1)[1]), pk2((v1)[2], (v1)[3])}
;     __device__ __forceinline__ void operator()(AccRef acc, const Unit& u, int wr, int wc, int fr, int fq) const {
;     ...
;         for (int it = 0; it < 8; ++it) { const int ai = it >> 2, m = it & 3, row = EPI_IT_ROW(it); const float r = rr[it];
;             if (it + 1 < 8) {
; #pragma unroll
;                 for (int bj = 0; bj < 2; ++bj) on[bj] = *(const u32x4*)(QKV + (size_t)EPI_IT_ROW(it + 1) * RET_QKV + 2048 + EPI_COL(bj)); }
;             const float mean = sts[it].x * (1.f / 512.f), var = fmaxf(sts[it].y * (1.f / 512.f) - mean * mean, 0.f), rstd = __builtin_amdgcn_rsqf(var + LN_EPS);
; #pragma unroll
;             for (int bj = 0; bj < 2; ++bj) { const int col = EPI_COL(bj);
;                 const u32x4 ow = oc[bj];
;                 const f32x4 o0 = (f32x4){bflo(ow.x), bfhi(ow.x), bflo(ow.y), bfhi(ow.y)}, o1 = (f32x4){bflo(ow.z), bfhi(ow.z), bflo(ow.w), bfhi(ow.w)};
;                 const f32x4 z0 = acc[ai][bj][m][0] * r, z1 = acc[ai][bj][m][1] * r;
;                 f32x4 g0, g1;
; #pragma unroll
;                 for (int e = 0; e < 4; ++e) { g0[e] = z0[e] * sigmoid_f(z0[e]); g1[e] = z1[e] * sigmoid_f(z1[e]); }
;                 const f32x4 y0 = g0 * ((o0 - mean) * rstd) * gg[bj][0], y1 = g1 * ((o1 - mean) * rstd) * gg[bj][1];
;                 *(u32x4*)(QKV + (size_t)row * RET_QKV + col) = EPI_PACK8(y0, y1); }
; #pragma unroll
;             for (int bj = 0; bj < 2; ++bj) oc[bj] = on[bj]; }
.Lwj1233_31154:
	v_pk_mul_f32 v[22:23], v[22:23], v[172:173] op_sel_hi:[1,0]
	v_pk_mul_f32 v[18:19], v[18:19], v[172:173] op_sel_hi:[1,0]
	v_mul_f32_e32 v24, 0xbfb8aa3b, v20
	v_mul_f32_e32 v25, 0xbfb8aa3b, v21
	v_mul_f32_e32 v26, 0xbfb8aa3b, v16
	v_mul_f32_e32 v27, 0xbfb8aa3b, v17
	v_exp_f32_e32 v24, v24
	v_exp_f32_e32 v25, v25
	v_exp_f32_e32 v26, v26
	v_exp_f32_e32 v27, v27
	v_mul_f32_e32 v30, 0xbfb8aa3b, v22
	v_mul_f32_e32 v31, 0xbfb8aa3b, v23
	v_exp_f32_e32 v30, v30
	v_exp_f32_e32 v31, v31
	v_mul_f32_e32 v46, 0xbfb8aa3b, v18
	v_mul_f32_e32 v47, 0xbfb8aa3b, v19
	v_exp_f32_e32 v46, v46
	v_exp_f32_e32 v47, v47
	v_add_f32_e32 v24, 1.0, v24
	v_add_f32_e32 v25, 1.0, v25
	v_add_f32_e32 v26, 1.0, v26
	v_add_f32_e32 v27, 1.0, v27
	v_rcp_f32_e32 v24, v24
	v_rcp_f32_e32 v25, v25
	v_rcp_f32_e32 v26, v26
	v_rcp_f32_e32 v27, v27
	v_add_f32_e32 v30, 1.0, v30
	v_add_f32_e32 v31, 1.0, v31
	v_rcp_f32_e32 v30, v30
	v_rcp_f32_e32 v31, v31
	v_add_f32_e32 v46, 1.0, v46
	v_add_f32_e32 v47, 1.0, v47
	v_lshlrev_b32_e32 v43, 16, v48
	v_and_b32_e32 v45, 0xffff0000, v48
	v_lshlrev_b32_e32 v48, 16, v49
	v_and_b32_e32 v49, 0xffff0000, v49
	v_rcp_f32_e32 v46, v46
	v_rcp_f32_e32 v47, v47
	v_pk_mul_f32 v[20:21], v[20:21], v[24:25]
	v_pk_mul_f32 v[16:17], v[16:17], v[26:27]
	v_sub_f32_e32 v25, v45, v42
	v_sub_f32_e32 v24, v43, v42
	v_sub_f32_e32 v27, v49, v42
	v_sub_f32_e32 v26, v48, v42
	v_lshlrev_b32_e32 v52, 16, v50
	v_and_b32_e32 v50, 0xffff0000, v50
	v_lshlrev_b32_e32 v53, 16, v51
	v_and_b32_e32 v51, 0xffff0000, v51
	v_pk_mul_f32 v[22:23], v[22:23], v[30:31]
	v_pk_mul_f32 v[26:27], v[44:45], v[26:27] op_sel_hi:[0,1]
	v_pk_mul_f32 v[24:25], v[44:45], v[24:25] op_sel_hi:[0,1]
	v_pk_mul_f32 v[20:21], v[20:21], v[24:25]
	v_pk_mul_f32 v[22:23], v[22:23], v[26:27]
	v_sub_f32_e32 v25, v50, v42
	v_sub_f32_e32 v24, v52, v42
	v_sub_f32_e32 v27, v51, v42
	v_sub_f32_e32 v26, v53, v42
	v_pk_mul_f32 v[18:19], v[18:19], v[46:47]
	v_pk_mul_f32 v[26:27], v[44:45], v[26:27] op_sel_hi:[0,1]
	v_pk_mul_f32 v[24:25], v[44:45], v[24:25] op_sel_hi:[0,1]
	v_pk_mul_f32 v[16:17], v[16:17], v[24:25]
	v_pk_mul_f32 v[18:19], v[18:19], v[26:27]
	v_pk_mul_f32 v[20:21], v[60:61], v[20:21]
	v_pk_mul_f32 v[24:25], v[58:59], v[18:19]
	v_pk_mul_f32 v[18:19], v[56:57], v[16:17]
	v_cvt_pk_bf16_f32 v16, v20, v21
	v_pk_mul_f32 v[22:23], v[62:63], v[22:23]
	v_cvt_pk_bf16_f32 v18, v18, v19
	v_cvt_pk_bf16_f32 v19, v24, v25
	s_waitcnt vmcnt(1)
	v_lshlrev_b32_e32 v21, 16, v37
	v_cvt_pk_bf16_f32 v17, v22, v23
	s_cmp_lg_u32 s99, 0
	s_cbranch_scc1 .Lwt1233_31235
	global_store_dwordx4 v[28:29], v[16:19], off offset:256
	s_branch .Lwj1233_31235
.Lwt1233_31235:
	global_store_dwordx4 v[28:29], v[16:19], off offset:256 sc1
; __device__ __forceinline__ float sigmoid_f(float z) { return __builtin_amdgcn_rcpf(1.f + fexp(-z)); }
; #define EPI_IT_ROW(it) EPI_ROW((it) >> 2, (it) & 3)
; #define EPI_PACK8(v0, v1) (u32x4){pk2((v0)[0], (v0)[1]), pk2((v0)[2], (v0)[3]), pk2((v1)[0], (v1)[1]), pk2((v1)[2], (v1)[3])}
;     __device__ __forceinline__ void operator()(AccRef acc, const Unit& u, int wr, int wc, int fr, int fq) const {
;     ...
;         for (int it = 0; it < 8; ++it) { const int ai = it >> 2, m = it & 3, row = EPI_IT_ROW(it); const float r = rr[it];
;             if (it + 1 < 8) {
; #pragma unroll
;                 for (int bj = 0; bj < 2; ++bj) on[bj] = *(const u32x4*)(QKV + (size_t)EPI_IT_ROW(it + 1) * RET_QKV + 2048 + EPI_COL(bj)); }
;             const float mean = sts[it].x * (1.f / 512.f), var = fmaxf(sts[it].y * (1.f / 512.f) - mean * mean, 0.f), rstd = __builtin_amdgcn_rsqf(var + LN_EPS);
; #pragma unroll
;             for (int bj = 0; bj < 2; ++bj) { const int col = EPI_COL(bj);
;                 const u32x4 ow = oc[bj];
;                 const f32x4 o0 = (f32x4){bflo(ow.x), bfhi(ow.x), bflo(ow.y), bfhi(ow.y)}, o1 = (f32x4){bflo(ow.z), bfhi(ow.z), bflo(ow.w), bfhi(ow.w)};
;                 const f32x4 z0 = acc[ai][bj][m][0] * r, z1 = acc[ai][bj][m][1] * r;
;                 f32x4 g0, g1;
; #pragma unroll
;                 for (int e = 0; e < 4; ++e) { g0[e] = z0[e] * sigmoid_f(z0[e]); g1[e] = z1[e] * sigmoid_f(z1[e]); }
;                 const f32x4 y0 = g0 * ((o0 - mean) * rstd) * gg[bj][0], y1 = g1 * ((o1 - mean) * rstd) * gg[bj][1];
;                 *(u32x4*)(QKV + (size_t)row * RET_QKV + col) = EPI_PACK8(y0, y1); }
; #pragma unroll
;             for (int bj = 0; bj < 2; ++bj) oc[bj] = on[bj]; }
.Lwj1233_31235:
	v_and_b32_e32 v30, 0xffff0000, v37
	v_lshlrev_b32_e32 v31, 16, v38
	v_fmamk_f32 v16, v214, 0x3a800000, v207
	v_pk_mul_f32 v[18:19], v[170:171], s[18:19] op_sel_hi:[1,0]
	v_rsq_f32_e32 v16, v16
	v_fma_f32 v17, -v18, v18, v19
	v_max_f32_e32 v17, 0, v17
	v_add_f32_e32 v17, 0x3727c5ac, v17
	v_rsq_f32_e32 v20, v17
	v_lshlrev_b32_e32 v17, 16, v36
	v_pk_mul_f32 v[12:13], v[12:13], v[16:17] op_sel_hi:[1,0]
	v_pk_mul_f32 v[8:9], v[8:9], v[16:17] op_sel_hi:[1,0]
	v_mul_f32_e32 v22, 0xbfb8aa3b, v12
	v_mul_f32_e32 v23, 0xbfb8aa3b, v13
	v_mul_f32_e32 v24, 0xbfb8aa3b, v8
	v_mul_f32_e32 v25, 0xbfb8aa3b, v9
	v_pk_mul_f32 v[14:15], v[14:15], v[16:17] op_sel_hi:[1,0]
	v_exp_f32_e32 v22, v22
	v_exp_f32_e32 v23, v23
	v_exp_f32_e32 v24, v24
	v_exp_f32_e32 v25, v25
	v_mul_f32_e32 v26, 0xbfb8aa3b, v14
	v_mul_f32_e32 v27, 0xbfb8aa3b, v15
	v_exp_f32_e32 v26, v26
	v_exp_f32_e32 v27, v27
	v_pk_mul_f32 v[10:11], v[10:11], v[16:17] op_sel_hi:[1,0]
	v_add_f32_e32 v22, 1.0, v22
	v_mul_f32_e32 v28, 0xbfb8aa3b, v10
	v_mul_f32_e32 v29, 0xbfb8aa3b, v11
	v_exp_f32_e32 v28, v28
	v_exp_f32_e32 v29, v29
	v_add_f32_e32 v23, 1.0, v23
	v_add_f32_e32 v24, 1.0, v24
	v_add_f32_e32 v25, 1.0, v25
	v_rcp_f32_e32 v22, v22
	v_rcp_f32_e32 v23, v23
	v_rcp_f32_e32 v24, v24
	v_rcp_f32_e32 v25, v25
	v_add_f32_e32 v26, 1.0, v26
	v_add_f32_e32 v27, 1.0, v27
	v_rcp_f32_e32 v26, v26
	v_rcp_f32_e32 v27, v27
	v_add_f32_e32 v28, 1.0, v28
	v_add_f32_e32 v29, 1.0, v29
	v_and_b32_e32 v19, 0xffff0000, v36
	v_rcp_f32_e32 v28, v28
	v_rcp_f32_e32 v29, v29
	v_pk_mul_f32 v[12:13], v[12:13], v[22:23]
	v_pk_mul_f32 v[8:9], v[8:9], v[24:25]
	v_sub_f32_e32 v23, v19, v18
	v_sub_f32_e32 v22, v17, v18
	v_sub_f32_e32 v25, v30, v18
	v_sub_f32_e32 v24, v21, v18
	v_and_b32_e32 v36, 0xffff0000, v38
	v_lshlrev_b32_e32 v37, 16, v39
	v_and_b32_e32 v38, 0xffff0000, v39
	v_pk_mul_f32 v[14:15], v[14:15], v[26:27]
	v_pk_mul_f32 v[24:25], v[20:21], v[24:25] op_sel_hi:[0,1]
	v_pk_mul_f32 v[22:23], v[20:21], v[22:23] op_sel_hi:[0,1]
	v_pk_mul_f32 v[12:13], v[12:13], v[22:23]
	v_pk_mul_f32 v[14:15], v[14:15], v[24:25]
	v_sub_f32_e32 v23, v36, v18
	v_sub_f32_e32 v22, v31, v18
	v_sub_f32_e32 v25, v38, v18
	v_sub_f32_e32 v24, v37, v18
	v_pk_mul_f32 v[10:11], v[10:11], v[28:29]
	v_pk_mul_f32 v[24:25], v[20:21], v[24:25] op_sel_hi:[0,1]
	v_pk_mul_f32 v[22:23], v[20:21], v[22:23] op_sel_hi:[0,1]
	v_pk_mul_f32 v[8:9], v[8:9], v[22:23]
	v_pk_mul_f32 v[10:11], v[10:11], v[24:25]
	v_pk_mul_f32 v[12:13], v[76:77], v[12:13]
	v_pk_mul_f32 v[22:23], v[74:75], v[10:11]
	v_pk_mul_f32 v[10:11], v[72:73], v[8:9]
	v_pk_mul_f32 v[14:15], v[78:79], v[14:15]
	v_cvt_pk_bf16_f32 v8, v12, v13
	v_cvt_pk_bf16_f32 v10, v10, v11
	v_cvt_pk_bf16_f32 v11, v22, v23
	v_lshl_add_u64 v[12:13], v[40:41], 0, v[168:169]
	v_cvt_pk_bf16_f32 v9, v14, v15
	v_pk_mul_f32 v[4:5], v[4:5], v[16:17] op_sel_hi:[1,0]
	v_pk_mul_f32 v[0:1], v[0:1], v[16:17] op_sel_hi:[1,0]
	s_cmp_lg_u32 s99, 0
	s_cbranch_scc1 .Lwt1233_31325
	global_store_dwordx4 v[12:13], v[8:11], off
	s_branch .Lwj1233_31325
.Lwt1233_31325:
	global_store_dwordx4 v[12:13], v[8:11], off sc1
.Lwj1233_31325:
	v_pk_mul_f32 v[6:7], v[6:7], v[16:17] op_sel_hi:[1,0]
	v_pk_mul_f32 v[2:3], v[2:3], v[16:17] op_sel_hi:[1,0]
	v_mul_f32_e32 v8, 0xbfb8aa3b, v4
	v_mul_f32_e32 v9, 0xbfb8aa3b, v5
	v_mul_f32_e32 v10, 0xbfb8aa3b, v0
	v_mul_f32_e32 v11, 0xbfb8aa3b, v1
	v_exp_f32_e32 v8, v8
	v_exp_f32_e32 v9, v9
	v_exp_f32_e32 v10, v10
	v_exp_f32_e32 v11, v11
	v_mul_f32_e32 v14, 0xbfb8aa3b, v6
	v_mul_f32_e32 v15, 0xbfb8aa3b, v7
	v_exp_f32_e32 v14, v14
	v_exp_f32_e32 v15, v15
	v_mul_f32_e32 v16, 0xbfb8aa3b, v2
	v_mul_f32_e32 v17, 0xbfb8aa3b, v3
	v_exp_f32_e32 v16, v16
	v_exp_f32_e32 v17, v17
	v_add_f32_e32 v8, 1.0, v8
	v_add_f32_e32 v9, 1.0, v9
	v_add_f32_e32 v10, 1.0, v10
	v_add_f32_e32 v11, 1.0, v11
	v_rcp_f32_e32 v8, v8
	v_rcp_f32_e32 v9, v9
	v_rcp_f32_e32 v10, v10
	v_rcp_f32_e32 v11, v11
	v_add_f32_e32 v14, 1.0, v14
	v_add_f32_e32 v15, 1.0, v15
	v_rcp_f32_e32 v14, v14
	v_rcp_f32_e32 v15, v15
	v_add_f32_e32 v16, 1.0, v16
	v_add_f32_e32 v17, 1.0, v17
	v_lshlrev_b32_e32 v19, 16, v32
	v_and_b32_e32 v21, 0xffff0000, v32
	v_lshlrev_b32_e32 v22, 16, v33
	v_and_b32_e32 v23, 0xffff0000, v33
	v_rcp_f32_e32 v16, v16
	v_rcp_f32_e32 v17, v17
	v_pk_mul_f32 v[4:5], v[4:5], v[8:9]
	v_pk_mul_f32 v[0:1], v[0:1], v[10:11]
	v_sub_f32_e32 v9, v21, v18
	v_sub_f32_e32 v8, v19, v18
	v_sub_f32_e32 v11, v23, v18
	v_sub_f32_e32 v10, v22, v18
	v_lshlrev_b32_e32 v24, 16, v34
	v_and_b32_e32 v25, 0xffff0000, v34
	v_lshlrev_b32_e32 v26, 16, v35
	v_and_b32_e32 v27, 0xffff0000, v35
	v_pk_mul_f32 v[6:7], v[6:7], v[14:15]
	v_pk_mul_f32 v[10:11], v[20:21], v[10:11] op_sel_hi:[0,1]
	v_pk_mul_f32 v[8:9], v[20:21], v[8:9] op_sel_hi:[0,1]
	v_pk_mul_f32 v[4:5], v[4:5], v[8:9]
	v_pk_mul_f32 v[6:7], v[6:7], v[10:11]
	v_sub_f32_e32 v9, v25, v18
	v_sub_f32_e32 v8, v24, v18
	v_sub_f32_e32 v11, v27, v18
	v_sub_f32_e32 v10, v26, v18
	v_pk_mul_f32 v[2:3], v[2:3], v[16:17]
	v_pk_mul_f32 v[10:11], v[20:21], v[10:11] op_sel_hi:[0,1]
	v_pk_mul_f32 v[8:9], v[20:21], v[8:9] op_sel_hi:[0,1]
	v_pk_mul_f32 v[0:1], v[0:1], v[8:9]
	v_pk_mul_f32 v[2:3], v[2:3], v[10:11]
	v_pk_mul_f32 v[6:7], v[62:63], v[6:7]
	v_pk_mul_f32 v[8:9], v[58:59], v[2:3]
	v_pk_mul_f32 v[2:3], v[56:57], v[0:1]
	v_pk_mul_f32 v[4:5], v[60:61], v[4:5]
	v_cvt_pk_bf16_f32 v1, v6, v7
	v_cvt_pk_bf16_f32 v2, v2, v3
	v_cvt_pk_bf16_f32 v3, v8, v9
	s_nop 0
	v_cvt_pk_bf16_f32 v0, v4, v5
	s_cmp_lg_u32 s99, 0
	s_cbranch_scc1 .Lwt1233_31405
	global_store_dwordx4 v[12:13], v[0:3], off offset:256
	s_branch .Lwj1233_31405
.Lwt1233_31405:
	global_store_dwordx4 v[12:13], v[0:3], off offset:256 sc1

; #define PG8_STAGE(bufoff, gbase, voff) do { _Pragma("unroll") for (int _i = 0; _i < 2; ++_i) \
;         __builtin_amdgcn_global_load_lds((const unsigned*)((const char*)(gbase) + (voff)[_i]), (LAS unsigned*)(lds + (bufoff) + ldsw + _i * 8192), 16, 0, 0); } while (0)
; #define PG8_LDA(dst, b, h) do { _Pragma("unroll") for (int m = 0; m < 4; ++m) _Pragma("unroll") for (int k = 0; k < 2; ++k) dst[m][k] = *(const LAS bf16x8*)(lds + PG8_SA(b, h) + aoff + m * 2048 + k * 1024); } while (0)
; #define PG8_LDB(dst, b, h) do { _Pragma("unroll") for (int n = 0; n < 2; ++n) _Pragma("unroll") for (int k = 0; k < 2; ++k) dst[n][k] = *(const LAS bf16x8*)(lds + PG8_SB(b, h) + boff + n * 2048 + k * 1024); } while (0)
; #define PG8_MMA(ai, bj, At, Bt) do { __builtin_amdgcn_s_setprio(1); _Pragma("unroll") for (int m = 0; m < 4; ++m) _Pragma("unroll") for (int n = 0; n < 2; ++n) _Pragma("unroll") for (int k = 0; k < 2; ++k) \
;         acc[ai][bj][m][n] = __builtin_amdgcn_mfma_f32_16x16x32_bf16(Bt[n][k], At[m][k], acc[ai][bj][m][n], 0, 0, 0); __builtin_amdgcn_s_setprio(0); } while (0)
; #define PG8_WAIT_V(n) asm volatile("s_waitcnt vmcnt(" #n ")" ::: "memory")
; #define PG8_WAIT_L(n) asm volatile("s_waitcnt lgkmcnt(" #n ")" ::: "memory")
; #define PG8_BAR __builtin_amdgcn_s_barrier()
; #define PG8_SCHED __builtin_amdgcn_sched_barrier(0)
; template <class Epi>
; __device__ __forceinline__ void gemm_phase(LAS unsigned char* lds, const Gemm g, const StaticOrder& S, const Epi& E) {
;     ...
;             PG8_LDB(B0, 0, 0); PG8_LDB(B1, 0, 1); PG8_SCHED; PG8_LDA(At, 0, 0); PG8_STAGE(PG8_SA(1, 1), a1 + hstepA, voffA);
;             PG8_WAIT_V(8); PG8_WAIT_L(0); PG8_BAR; PG8_MMA(0, 0, At, B0); PG8_MMA(0, 1, At, B1); PG8_BAR; PG8_SCHED;
;             PG8_LDA(At, 0, 1); PG8_STAGE(PG8_SB(0, 0), b2, voffB); PG8_STAGE(PG8_SB(0, 1), b2 + hstepB, voffB); PG8_STAGE(PG8_SA(0, 0), a2, voffA);
;             PG8_WAIT_V(8); PG8_WAIT_L(0); PG8_BAR; PG8_MMA(1, 0, At, B0); PG8_MMA(1, 1, At, B1); PG8_BAR; PG8_SCHED;
;             PG8_LDB(B0, 1, 0); PG8_LDB(B1, 1, 1); PG8_SCHED; PG8_LDA(At, 1, 0); PG8_STAGE(PG8_SA(0, 1), a2 + hstepA, voffA);
;             PG8_WAIT_V(8); PG8_WAIT_L(0); PG8_BAR; PG8_MMA(0, 0, At, B0); PG8_MMA(0, 1, At, B1); PG8_BAR; PG8_SCHED;
.LBB0_1314:
	ds_read_b128 v[128:131], v182
	ds_read_b128 v[132:135], v182 offset:1024
	ds_read_b128 v[136:139], v182 offset:2048
	ds_read_b128 v[140:143], v182 offset:3072
	ds_read_b128 v[160:163], v183
	ds_read_b128 v[164:167], v183 offset:1024
	ds_read_b128 v[168:171], v183 offset:2048
	ds_read_b128 v[172:175], v183 offset:3072
	s_add_u32 s42, s38, 0xfff00080
	s_addc_u32 s43, s39, -1
	s_cmp_eq_u32 s73, 28
	s_cselect_b32 s53, s1, s43
	s_cselect_b32 s52, s19, s42
	s_cselect_b32 s43, s17, s72
	s_cselect_b32 s42, s70, s71
	v_lshl_add_u64 v[178:179], s[38:39], 0, v[152:153]
	s_add_i32 m0, s35, 0xc000
	ds_read_b128 v[186:189], v184
	ds_read_b128 v[190:193], v184 offset:1024
	ds_read_b128 v[194:197], v184 offset:2048
	ds_read_b128 v[198:201], v184 offset:3072
	ds_read_b128 v[202:205], v184 offset:4096
	ds_read_b128 v[206:209], v184 offset:5120
	ds_read_b128 v[210:213], v184 offset:6144
	ds_read_b128 v[214:217], v184 offset:7168
	global_load_lds_dwordx4 v[178:179], off
	v_lshl_add_u64 v[178:179], s[38:39], 0, v[154:155]
	s_add_i32 m0, s35, 0xe000
	s_nop 0
	global_load_lds_dwordx4 v[178:179], off
	s_waitcnt vmcnt(8)
	s_waitcnt lgkmcnt(0)
	s_barrier
	s_setprio 1
	s_waitcnt lgkmcnt(0)
	v_mfma_f32_16x16x32_bf16 v[124:127], v[128:131], v[186:189], v[124:127]
	v_mfma_f32_16x16x32_bf16 v[120:123], v[136:139], v[186:189], v[120:123]
	v_mfma_f32_16x16x32_bf16 v[108:111], v[128:131], v[194:197], v[108:111]
	v_mfma_f32_16x16x32_bf16 v[104:107], v[136:139], v[194:197], v[104:107]
	v_mfma_f32_16x16x32_bf16 v[92:95], v[128:131], v[202:205], v[92:95]
	v_mfma_f32_16x16x32_bf16 v[88:91], v[136:139], v[202:205], v[88:91]
	v_mfma_f32_16x16x32_bf16 v[76:79], v[128:131], v[210:213], v[76:79]
	v_mfma_f32_16x16x32_bf16 v[72:75], v[136:139], v[210:213], v[72:75]
	v_mfma_f32_16x16x32_bf16 v[124:127], v[132:135], v[190:193], v[124:127]
	v_mfma_f32_16x16x32_bf16 v[120:123], v[140:143], v[190:193], v[120:123]
	v_mfma_f32_16x16x32_bf16 v[108:111], v[132:135], v[198:201], v[108:111]
	v_mfma_f32_16x16x32_bf16 v[104:107], v[140:143], v[198:201], v[104:107]
	v_mfma_f32_16x16x32_bf16 v[92:95], v[132:135], v[206:209], v[92:95]
	v_mfma_f32_16x16x32_bf16 v[88:91], v[140:143], v[206:209], v[88:91]
	v_mfma_f32_16x16x32_bf16 v[76:79], v[132:135], v[214:217], v[76:79]
	v_mfma_f32_16x16x32_bf16 v[72:75], v[140:143], v[214:217], v[72:75]
	s_setprio 0
	s_setprio 1
	v_mfma_f32_16x16x32_bf16 v[116:119], v[160:163], v[186:189], v[116:119]
	v_mfma_f32_16x16x32_bf16 v[112:115], v[168:171], v[186:189], v[112:115]
	v_mfma_f32_16x16x32_bf16 v[100:103], v[160:163], v[194:197], v[100:103]
	v_mfma_f32_16x16x32_bf16 v[96:99], v[168:171], v[194:197], v[96:99]
	v_mfma_f32_16x16x32_bf16 v[84:87], v[160:163], v[202:205], v[84:87]
	v_mfma_f32_16x16x32_bf16 v[80:83], v[168:171], v[202:205], v[80:83]
	v_mfma_f32_16x16x32_bf16 v[68:71], v[160:163], v[210:213], v[68:71]
	v_mfma_f32_16x16x32_bf16 v[64:67], v[168:171], v[210:213], v[64:67]
	v_mfma_f32_16x16x32_bf16 v[116:119], v[164:167], v[190:193], v[116:119]
	v_mfma_f32_16x16x32_bf16 v[112:115], v[172:175], v[190:193], v[112:115]
	v_mfma_f32_16x16x32_bf16 v[100:103], v[164:167], v[198:201], v[100:103]
	v_mfma_f32_16x16x32_bf16 v[96:99], v[172:175], v[198:201], v[96:99]
	v_mfma_f32_16x16x32_bf16 v[84:87], v[164:167], v[206:209], v[84:87]
	v_mfma_f32_16x16x32_bf16 v[80:83], v[172:175], v[206:209], v[80:83]
	v_mfma_f32_16x16x32_bf16 v[68:71], v[164:167], v[214:217], v[68:71]
	v_mfma_f32_16x16x32_bf16 v[64:67], v[172:175], v[214:217], v[64:67]
	s_setprio 0
	s_barrier
	s_add_i32 s74, s68, s54
	v_lshl_add_u64 v[178:179], s[42:43], 0, v[146:147]
	s_mov_b32 m0, s74
	ds_read_b128 v[186:189], v184 offset:16384
	ds_read_b128 v[190:193], v184 offset:17408
	ds_read_b128 v[194:197], v184 offset:18432
	ds_read_b128 v[198:201], v184 offset:19456
	ds_read_b128 v[202:205], v184 offset:20480
	ds_read_b128 v[206:209], v184 offset:21504
	ds_read_b128 v[210:213], v184 offset:22528
	ds_read_b128 v[214:217], v184 offset:23552
	global_load_lds_dwordx4 v[178:179], off
	s_add_i32 m0, s74, 0x2000
	s_add_u32 s74, s42, 0x80000
	v_lshl_add_u64 v[218:219], s[42:43], 0, v[150:151]
	s_addc_u32 s75, s43, 0
	s_add_i32 s76, s69, s54
	global_load_lds_dwordx4 v[218:219], off
	v_lshl_add_u64 v[220:221], s[74:75], 0, v[146:147]
	s_mov_b32 m0, s76
	v_lshl_add_u64 v[222:223], s[52:53], 0, v[148:149]
	global_load_lds_dwordx4 v[220:221], off
	v_lshl_add_u64 v[220:221], s[74:75], 0, v[150:151]
	s_add_i32 m0, s76, 0x2000
	s_nop 0
	global_load_lds_dwordx4 v[220:221], off
	v_lshl_add_u64 v[220:221], s[52:53], 0, v[144:145]
	s_mov_b32 m0, s35
	s_nop 0
	global_load_lds_dwordx4 v[220:221], off
	s_mov_b32 m0, s55
	s_nop 0
	global_load_lds_dwordx4 v[222:223], off
	s_waitcnt vmcnt(8)
	s_waitcnt lgkmcnt(0)
	s_barrier
; #define PG8_STAGE(bufoff, gbase, voff) do { _Pragma("unroll") for (int _i = 0; _i < 2; ++_i) \
;         __builtin_amdgcn_global_load_lds((const unsigned*)((const char*)(gbase) + (voff)[_i]), (LAS unsigned*)(lds + (bufoff) + ldsw + _i * 8192), 16, 0, 0); } while (0)
; #define PG8_LDA(dst, b, h) do { _Pragma("unroll") for (int m = 0; m < 4; ++m) _Pragma("unroll") for (int k = 0; k < 2; ++k) dst[m][k] = *(const LAS bf16x8*)(lds + PG8_SA(b, h) + aoff + m * 2048 + k * 1024); } while (0)
; #define PG8_LDB(dst, b, h) do { _Pragma("unroll") for (int n = 0; n < 2; ++n) _Pragma("unroll") for (int k = 0; k < 2; ++k) dst[n][k] = *(const LAS bf16x8*)(lds + PG8_SB(b, h) + boff + n * 2048 + k * 1024); } while (0)
; #define PG8_MMA(ai, bj, At, Bt) do { __builtin_amdgcn_s_setprio(1); _Pragma("unroll") for (int m = 0; m < 4; ++m) _Pragma("unroll") for (int n = 0; n < 2; ++n) _Pragma("unroll") for (int k = 0; k < 2; ++k) \
;         acc[ai][bj][m][n] = __builtin_amdgcn_mfma_f32_16x16x32_bf16(Bt[n][k], At[m][k], acc[ai][bj][m][n], 0, 0, 0); __builtin_amdgcn_s_setprio(0); } while (0)
; #define PG8_WAIT_V(n) asm volatile("s_waitcnt vmcnt(" #n ")" ::: "memory")
; #define PG8_BAR __builtin_amdgcn_s_barrier()
; template <class Epi>
; __device__ __forceinline__ void gemm_phase(LAS unsigned char* lds, const Gemm g, const StaticOrder& S, const Epi& E) {
;     ...
;             PG8_LDB(B0, 0, 0); PG8_LDB(B1, 0, 1); PG8_SCHED; PG8_LDA(At, 0, 0); PG8_STAGE(PG8_SA(1, 1), a1 + hstepA, voffA);
;             PG8_WAIT_V(8); PG8_WAIT_L(0); PG8_BAR; PG8_MMA(0, 0, At, B0); PG8_MMA(0, 1, At, B1); PG8_BAR; PG8_SCHED;
;             PG8_LDA(At, 0, 1); PG8_STAGE(PG8_SB(0, 0), b2, voffB); PG8_STAGE(PG8_SB(0, 1), b2 + hstepB, voffB); PG8_STAGE(PG8_SA(0, 0), a2, voffA);
;             PG8_WAIT_V(8); PG8_WAIT_L(0); PG8_BAR; PG8_MMA(1, 0, At, B0); PG8_MMA(1, 1, At, B1); PG8_BAR; PG8_SCHED;
;             PG8_LDB(B0, 1, 0); PG8_LDB(B1, 1, 1); PG8_SCHED; PG8_LDA(At, 1, 0); PG8_STAGE(PG8_SA(0, 1), a2 + hstepA, voffA);
;             PG8_WAIT_V(8); PG8_WAIT_L(0); PG8_BAR; PG8_MMA(0, 0, At, B0); PG8_MMA(0, 1, At, B1); PG8_BAR; PG8_SCHED;
;             PG8_LDA(At, 1, 1); PG8_STAGE(PG8_SB(1, 0), b3, voffB); PG8_STAGE(PG8_SB(1, 1), b3 + hstepB, voffB); PG8_STAGE(PG8_SA(1, 0), a3, voffA);
;             PG8_WAIT_V(8); PG8_WAIT_L(0); PG8_BAR; PG8_MMA(1, 0, At, B0); PG8_MMA(1, 1, At, B1); PG8_BAR; PG8_SCHED;
	s_setprio 1
	s_waitcnt lgkmcnt(0)
	v_mfma_f32_16x16x32_bf16 v[60:63], v[128:131], v[186:189], v[60:63]
	v_mfma_f32_16x16x32_bf16 v[56:59], v[136:139], v[186:189], v[56:59]
	v_mfma_f32_16x16x32_bf16 v[44:47], v[128:131], v[194:197], v[44:47]
	v_mfma_f32_16x16x32_bf16 v[40:43], v[136:139], v[194:197], v[40:43]
	v_mfma_f32_16x16x32_bf16 v[28:31], v[128:131], v[202:205], v[28:31]
	v_mfma_f32_16x16x32_bf16 v[24:27], v[136:139], v[202:205], v[24:27]
	v_mfma_f32_16x16x32_bf16 v[12:15], v[128:131], v[210:213], v[12:15]
	v_mfma_f32_16x16x32_bf16 v[8:11], v[136:139], v[210:213], v[8:11]
	v_mfma_f32_16x16x32_bf16 v[60:63], v[132:135], v[190:193], v[60:63]
	v_mfma_f32_16x16x32_bf16 v[56:59], v[140:143], v[190:193], v[56:59]
	v_mfma_f32_16x16x32_bf16 v[44:47], v[132:135], v[198:201], v[44:47]
	v_mfma_f32_16x16x32_bf16 v[40:43], v[140:143], v[198:201], v[40:43]
	v_mfma_f32_16x16x32_bf16 v[28:31], v[132:135], v[206:209], v[28:31]
	v_mfma_f32_16x16x32_bf16 v[24:27], v[140:143], v[206:209], v[24:27]
	v_mfma_f32_16x16x32_bf16 v[12:15], v[132:135], v[214:217], v[12:15]
	v_mfma_f32_16x16x32_bf16 v[8:11], v[140:143], v[214:217], v[8:11]
	s_setprio 0
	s_setprio 1
	v_mfma_f32_16x16x32_bf16 v[52:55], v[160:163], v[186:189], v[52:55]
	v_mfma_f32_16x16x32_bf16 v[48:51], v[168:171], v[186:189], v[48:51]
	v_mfma_f32_16x16x32_bf16 v[36:39], v[160:163], v[194:197], v[36:39]
	v_mfma_f32_16x16x32_bf16 v[32:35], v[168:171], v[194:197], v[32:35]
	v_mfma_f32_16x16x32_bf16 v[20:23], v[160:163], v[202:205], v[20:23]
	v_mfma_f32_16x16x32_bf16 v[16:19], v[168:171], v[202:205], v[16:19]
	v_mfma_f32_16x16x32_bf16 v[4:7], v[160:163], v[210:213], v[4:7]
	v_mfma_f32_16x16x32_bf16 v[0:3], v[168:171], v[210:213], v[0:3]
	v_mfma_f32_16x16x32_bf16 v[52:55], v[164:167], v[190:193], v[52:55]
	v_mfma_f32_16x16x32_bf16 v[48:51], v[172:175], v[190:193], v[48:51]
	v_mfma_f32_16x16x32_bf16 v[36:39], v[164:167], v[198:201], v[36:39]
	v_mfma_f32_16x16x32_bf16 v[32:35], v[172:175], v[198:201], v[32:35]
	v_mfma_f32_16x16x32_bf16 v[20:23], v[164:167], v[206:209], v[20:23]
	v_mfma_f32_16x16x32_bf16 v[16:19], v[172:175], v[206:209], v[16:19]
	v_mfma_f32_16x16x32_bf16 v[4:7], v[164:167], v[214:217], v[4:7]
	v_mfma_f32_16x16x32_bf16 v[0:3], v[172:175], v[214:217], v[0:3]
	s_setprio 0
	s_barrier
	s_add_i32 s74, 0, 0x18000
	s_add_i32 s75, 0, 0x1c000
	v_add_u32_e32 v140, s74, v181
	v_add_u32_e32 v172, s75, v181
	ds_read_b128 v[128:131], v140
	ds_read_b128 v[132:135], v140 offset:1024
	ds_read_b128 v[136:139], v140 offset:2048
	ds_read_b128 v[140:143], v140 offset:3072
	ds_read_b128 v[160:163], v172
	ds_read_b128 v[164:167], v172 offset:1024
	ds_read_b128 v[168:171], v172 offset:2048
	ds_read_b128 v[172:175], v172 offset:3072
	s_add_u32 s52, s52, 0x100000
	s_addc_u32 s53, s53, 0
	s_mov_b32 m0, s56
	v_lshl_add_u64 v[224:225], s[52:53], 0, v[144:145]
	ds_read_b128 v[186:189], v184 offset:32768
	ds_read_b128 v[190:193], v184 offset:33792
	ds_read_b128 v[194:197], v184 offset:34816
	ds_read_b128 v[198:201], v184 offset:35840
	ds_read_b128 v[202:205], v184 offset:36864
	ds_read_b128 v[206:209], v184 offset:37888
	ds_read_b128 v[210:213], v184 offset:38912
	ds_read_b128 v[214:217], v184 offset:39936
	global_load_lds_dwordx4 v[224:225], off
	v_lshl_add_u64 v[224:225], s[52:53], 0, v[148:149]
	s_mov_b32 m0, s57
	s_nop 0
	global_load_lds_dwordx4 v[224:225], off
	s_waitcnt vmcnt(8)
	s_waitcnt lgkmcnt(0)
	s_barrier
	s_setprio 1
	s_waitcnt lgkmcnt(0)
	v_mfma_f32_16x16x32_bf16 v[124:127], v[128:131], v[186:189], v[124:127]
	v_mfma_f32_16x16x32_bf16 v[120:123], v[136:139], v[186:189], v[120:123]
	v_mfma_f32_16x16x32_bf16 v[108:111], v[128:131], v[194:197], v[108:111]
	v_mfma_f32_16x16x32_bf16 v[104:107], v[136:139], v[194:197], v[104:107]
	v_mfma_f32_16x16x32_bf16 v[92:95], v[128:131], v[202:205], v[92:95]
	v_mfma_f32_16x16x32_bf16 v[88:91], v[136:139], v[202:205], v[88:91]
	v_mfma_f32_16x16x32_bf16 v[76:79], v[128:131], v[210:213], v[76:79]
	v_mfma_f32_16x16x32_bf16 v[72:75], v[136:139], v[210:213], v[72:75]
	v_mfma_f32_16x16x32_bf16 v[124:127], v[132:135], v[190:193], v[124:127]
	v_mfma_f32_16x16x32_bf16 v[120:123], v[140:143], v[190:193], v[120:123]
	v_mfma_f32_16x16x32_bf16 v[108:111], v[132:135], v[198:201], v[108:111]
	v_mfma_f32_16x16x32_bf16 v[104:107], v[140:143], v[198:201], v[104:107]
	v_mfma_f32_16x16x32_bf16 v[92:95], v[132:135], v[206:209], v[92:95]
	v_mfma_f32_16x16x32_bf16 v[88:91], v[140:143], v[206:209], v[88:91]
	v_mfma_f32_16x16x32_bf16 v[76:79], v[132:135], v[214:217], v[76:79]
	v_mfma_f32_16x16x32_bf16 v[72:75], v[140:143], v[214:217], v[72:75]
	s_setprio 0
	s_setprio 1
	v_mfma_f32_16x16x32_bf16 v[116:119], v[160:163], v[186:189], v[116:119]
	v_mfma_f32_16x16x32_bf16 v[112:115], v[168:171], v[186:189], v[112:115]
	v_mfma_f32_16x16x32_bf16 v[100:103], v[160:163], v[194:197], v[100:103]
	v_mfma_f32_16x16x32_bf16 v[96:99], v[168:171], v[194:197], v[96:99]
	v_mfma_f32_16x16x32_bf16 v[84:87], v[160:163], v[202:205], v[84:87]
	v_mfma_f32_16x16x32_bf16 v[80:83], v[168:171], v[202:205], v[80:83]
	v_mfma_f32_16x16x32_bf16 v[68:71], v[160:163], v[210:213], v[68:71]
	v_mfma_f32_16x16x32_bf16 v[64:67], v[168:171], v[210:213], v[64:67]
	v_mfma_f32_16x16x32_bf16 v[116:119], v[164:167], v[190:193], v[116:119]
	v_mfma_f32_16x16x32_bf16 v[112:115], v[172:175], v[190:193], v[112:115]
	v_mfma_f32_16x16x32_bf16 v[100:103], v[164:167], v[198:201], v[100:103]
	v_mfma_f32_16x16x32_bf16 v[96:99], v[172:175], v[198:201], v[96:99]
	v_mfma_f32_16x16x32_bf16 v[84:87], v[164:167], v[206:209], v[84:87]
	v_mfma_f32_16x16x32_bf16 v[80:83], v[172:175], v[206:209], v[80:83]
	v_mfma_f32_16x16x32_bf16 v[68:71], v[164:167], v[214:217], v[68:71]
	v_mfma_f32_16x16x32_bf16 v[64:67], v[172:175], v[214:217], v[64:67]
	s_setprio 0
	s_barrier
; #define PG8_STAGE(bufoff, gbase, voff) do { _Pragma("unroll") for (int _i = 0; _i < 2; ++_i) \
;         __builtin_amdgcn_global_load_lds((const unsigned*)((const char*)(gbase) + (voff)[_i]), (LAS unsigned*)(lds + (bufoff) + ldsw + _i * 8192), 16, 0, 0); } while (0)
; #define PG8_LDA(dst, b, h) do { _Pragma("unroll") for (int m = 0; m < 4; ++m) _Pragma("unroll") for (int k = 0; k < 2; ++k) dst[m][k] = *(const LAS bf16x8*)(lds + PG8_SA(b, h) + aoff + m * 2048 + k * 1024); } while (0)
; #define PG8_MMA(ai, bj, At, Bt) do { __builtin_amdgcn_s_setprio(1); _Pragma("unroll") for (int m = 0; m < 4; ++m) _Pragma("unroll") for (int n = 0; n < 2; ++n) _Pragma("unroll") for (int k = 0; k < 2; ++k) \
;         acc[ai][bj][m][n] = __builtin_amdgcn_mfma_f32_16x16x32_bf16(Bt[n][k], At[m][k], acc[ai][bj][m][n], 0, 0, 0); __builtin_amdgcn_s_setprio(0); } while (0)
; #define PG8_WAIT_V(n) asm volatile("s_waitcnt vmcnt(" #n ")" ::: "memory")
; #define PG8_WAIT_L(n) asm volatile("s_waitcnt lgkmcnt(" #n ")" ::: "memory")
; #define PG8_BAR __builtin_amdgcn_s_barrier()
; #define PG8_SCHED __builtin_amdgcn_sched_barrier(0)
; template <class Epi>
; __device__ __forceinline__ void gemm_phase(LAS unsigned char* lds, const Gemm g, const StaticOrder& S, const Epi& E) {
;     ...
;             PG8_LDA(At, 1, 1); PG8_STAGE(PG8_SB(1, 0), b3, voffB); PG8_STAGE(PG8_SB(1, 1), b3 + hstepB, voffB); PG8_STAGE(PG8_SA(1, 0), a3, voffA);
;             PG8_WAIT_V(8); PG8_WAIT_L(0); PG8_BAR; PG8_MMA(1, 0, At, B0); PG8_MMA(1, 1, At, B1); PG8_BAR; PG8_SCHED;
;         }
;         if (wr == 0) PG8_BAR;
	s_add_i32 s52, s74, s54
	v_lshl_add_u64 v[178:179], v[178:179], 0, s[12:13]
	s_mov_b32 m0, s52
	ds_read_b128 v[186:189], v184 offset:49152
	ds_read_b128 v[190:193], v184 offset:50176
	ds_read_b128 v[194:197], v184 offset:51200
	ds_read_b128 v[198:201], v184 offset:52224
	ds_read_b128 v[202:205], v184 offset:53248
	ds_read_b128 v[206:209], v184 offset:54272
	ds_read_b128 v[210:213], v184 offset:55296
	ds_read_b128 v[214:217], v184 offset:56320
	global_load_lds_dwordx4 v[178:179], off
	s_add_i32 m0, s52, 0x2000
	s_add_u32 s42, s42, 0x80080
	v_lshl_add_u64 v[178:179], v[218:219], 0, s[12:13]
	s_addc_u32 s43, s43, 0
	s_add_i32 s52, s75, s54
	global_load_lds_dwordx4 v[178:179], off
	v_lshl_add_u64 v[178:179], s[42:43], 0, v[146:147]
	s_mov_b32 m0, s52
	s_nop 0
	global_load_lds_dwordx4 v[178:179], off
	v_lshl_add_u64 v[178:179], s[42:43], 0, v[150:151]
	s_add_i32 m0, s52, 0x2000
	s_nop 0
	global_load_lds_dwordx4 v[178:179], off
	v_lshl_add_u64 v[178:179], v[220:221], 0, s[12:13]
	s_mov_b32 m0, s61
	s_nop 0
	global_load_lds_dwordx4 v[178:179], off
	v_lshl_add_u64 v[178:179], v[222:223], 0, s[12:13]
	s_mov_b32 m0, s62
	s_nop 0
	global_load_lds_dwordx4 v[178:179], off
	s_waitcnt vmcnt(8)
	s_waitcnt lgkmcnt(0)
	s_barrier
	s_setprio 1
	s_waitcnt lgkmcnt(0)
	v_mfma_f32_16x16x32_bf16 v[60:63], v[128:131], v[186:189], v[60:63]
	v_mfma_f32_16x16x32_bf16 v[56:59], v[136:139], v[186:189], v[56:59]
	v_mfma_f32_16x16x32_bf16 v[44:47], v[128:131], v[194:197], v[44:47]
	v_mfma_f32_16x16x32_bf16 v[40:43], v[136:139], v[194:197], v[40:43]
	v_mfma_f32_16x16x32_bf16 v[28:31], v[128:131], v[202:205], v[28:31]
	v_mfma_f32_16x16x32_bf16 v[24:27], v[136:139], v[202:205], v[24:27]
	v_mfma_f32_16x16x32_bf16 v[12:15], v[128:131], v[210:213], v[12:15]
	v_mfma_f32_16x16x32_bf16 v[8:11], v[136:139], v[210:213], v[8:11]
	v_mfma_f32_16x16x32_bf16 v[60:63], v[132:135], v[190:193], v[60:63]
	v_mfma_f32_16x16x32_bf16 v[56:59], v[140:143], v[190:193], v[56:59]
	v_mfma_f32_16x16x32_bf16 v[44:47], v[132:135], v[198:201], v[44:47]
	v_mfma_f32_16x16x32_bf16 v[40:43], v[140:143], v[198:201], v[40:43]
	v_mfma_f32_16x16x32_bf16 v[28:31], v[132:135], v[206:209], v[28:31]
	v_mfma_f32_16x16x32_bf16 v[24:27], v[140:143], v[206:209], v[24:27]
	v_mfma_f32_16x16x32_bf16 v[12:15], v[132:135], v[214:217], v[12:15]
	v_mfma_f32_16x16x32_bf16 v[8:11], v[140:143], v[214:217], v[8:11]
	s_setprio 0
	s_setprio 1
	v_mfma_f32_16x16x32_bf16 v[52:55], v[160:163], v[186:189], v[52:55]
	v_mfma_f32_16x16x32_bf16 v[48:51], v[168:171], v[186:189], v[48:51]
	v_mfma_f32_16x16x32_bf16 v[36:39], v[160:163], v[194:197], v[36:39]
	v_mfma_f32_16x16x32_bf16 v[32:35], v[168:171], v[194:197], v[32:35]
	v_mfma_f32_16x16x32_bf16 v[20:23], v[160:163], v[202:205], v[20:23]
	v_mfma_f32_16x16x32_bf16 v[16:19], v[168:171], v[202:205], v[16:19]
	v_mfma_f32_16x16x32_bf16 v[4:7], v[160:163], v[210:213], v[4:7]
	v_mfma_f32_16x16x32_bf16 v[0:3], v[168:171], v[210:213], v[0:3]
	v_mfma_f32_16x16x32_bf16 v[52:55], v[164:167], v[190:193], v[52:55]
	v_mfma_f32_16x16x32_bf16 v[48:51], v[172:175], v[190:193], v[48:51]
	v_mfma_f32_16x16x32_bf16 v[36:39], v[164:167], v[198:201], v[36:39]
	v_mfma_f32_16x16x32_bf16 v[32:35], v[172:175], v[198:201], v[32:35]
	v_mfma_f32_16x16x32_bf16 v[20:23], v[164:167], v[206:209], v[20:23]
	v_mfma_f32_16x16x32_bf16 v[16:19], v[172:175], v[206:209], v[16:19]
	v_mfma_f32_16x16x32_bf16 v[4:7], v[164:167], v[214:217], v[4:7]
	v_mfma_f32_16x16x32_bf16 v[0:3], v[172:175], v[214:217], v[0:3]
	s_setprio 0
	s_barrier
	s_add_i32 s73, s73, 2
	s_add_u32 s38, s38, 0x100
	s_addc_u32 s39, s39, 0
	s_add_u32 s71, s71, 0x100
	s_addc_u32 s72, s72, 0
	s_cmp_gt_u32 s73, 29
	s_cbranch_scc0 .LBB0_1314
	s_cmp_eq_u64 s[4:5], 0
	s_cselect_b32 s99, 1, 0
	s_and_b64 vcc, exec, s[14:15]
	s_cbranch_vccz .LBB0_1317
	s_barrier
; #define EPI_IT_ROW(it) EPI_ROW((it) >> 2, (it) & 3)
; #define EPI_PACK8(v0, v1) (u32x4){pk2((v0)[0], (v0)[1]), pk2((v0)[2], (v0)[3]), pk2((v1)[0], (v1)[1]), pk2((v1)[2], (v1)[3])}
;     __device__ __forceinline__ void operator()(AccRef acc, const Unit& u, int wr, int wc, int fr, int fq) const {
;     ...
;         f32x4 xc[2][2], xn[2][2];
; #pragma unroll
;         for (int bj = 0; bj < 2; ++bj) { const size_t p = (size_t)EPI_IT_ROW(0) * DM + EPI_COL(bj); xc[bj][0] = *(const f32x4*)(xin + p); xc[bj][1] = *(const f32x4*)(xin + p + 4); }
; #pragma unroll
;         for (int it = 0; it < 8; ++it) { const int ai = it >> 2, m = it & 3, row = EPI_IT_ROW(it);
;             if (it + 1 < 8) {
; #pragma unroll
;                 for (int bj = 0; bj < 2; ++bj) { const size_t p = (size_t)EPI_IT_ROW(it + 1) * DM + EPI_COL(bj); xn[bj][0] = *(const f32x4*)(xin + p); xn[bj][1] = *(const f32x4*)(xin + p + 4); } }
;             float q = 0.f;
; #pragma unroll
;             for (int bj = 0; bj < 2; ++bj) { const size_t p = (size_t)row * DM + EPI_COL(bj);
;                 const f32x4 x0 = xc[bj][0] + acc[ai][bj][m][0], x1 = xc[bj][1] + acc[ai][bj][m][1];
;                 __builtin_nontemporal_store(x0, (f32x4*)(xout + p)); __builtin_nontemporal_store(x1, (f32x4*)(xout + p + 4));
;                 *(u32x4*)(xb + p) = EPI_PACK8(x0, x1);
;                 q += EPI_SQ8(x0, x1); }
;             q += __shfl_xor(q, 16); q += __shfl_xor(q, 32);
;             if (fq == 0) atomicAdd(ssout + row, q);
.LBB0_1317:
	s_lshl_b32 s1, s34, 8
	v_mov_b32_e32 v128, v180
	v_mov_b32_e32 v186, v177
	s_add_i32 s1, s1, s59
	s_lshl_b32 s0, s0, 8
	s_or_b32 s0, s0, s60
	v_add_u32_e32 v164, s1, v128
	v_ashrrev_i32_e32 v165, 31, v164
	v_lshl_add_u32 v162, v186, 3, s0
	v_lshlrev_b64 v[128:129], 12, v[164:165]
	v_ashrrev_i32_e32 v163, 31, v162
	v_add_u32_e32 v160, 0x80, v162
	v_lshl_add_u64 v[128:129], s[48:49], 0, v[128:129]
	v_lshlrev_b64 v[130:131], 2, v[162:163]
	v_ashrrev_i32_e32 v161, 31, v160
	v_lshl_add_u64 v[178:179], v[128:129], 0, v[130:131]
	v_lshlrev_b64 v[132:133], 2, v[160:161]
	global_load_dwordx4 v[170:173], v[178:179], off offset:16
	global_load_dwordx4 v[188:191], v[178:179], off
	v_lshl_add_u64 v[200:201], v[128:129], 0, v[132:133]
	global_load_dwordx4 v[192:195], v[200:201], off
	global_load_dwordx4 v[196:199], v[200:201], off offset:16
	v_add_u32_e32 v166, 16, v164
	v_ashrrev_i32_e32 v167, 31, v166
	v_lshlrev_b64 v[128:129], 12, v[166:167]
	v_lshl_add_u64 v[128:129], s[48:49], 0, v[128:129]
	v_lshl_add_u64 v[174:175], v[128:129], 0, v[130:131]
	v_lshl_add_u64 v[168:169], v[128:129], 0, v[132:133]
	global_load_dwordx4 v[136:139], v[174:175], off offset:16
	global_load_dwordx4 v[140:143], v[174:175], off
	global_load_dwordx4 v[128:131], v[168:169], off offset:16
	global_load_dwordx4 v[132:135], v[168:169], off
	v_and_b32_e32 v202, 64, v185
	v_xor_b32_e32 v187, 16, v185
	v_add_u32_e32 v202, 64, v202
	v_cmp_lt_i32_e64 s[0:1], v187, v202
	v_cmp_eq_u32_e32 vcc, 0, v186
	v_xor_b32_e32 v203, 32, v185
	v_cndmask_b32_e64 v186, v185, v187, s[0:1]
	v_lshlrev_b32_e32 v186, 2, v186
	v_cmp_lt_i32_e64 s[0:1], v203, v202
	s_waitcnt vmcnt(0)
	v_pk_add_f32 v[122:123], v[122:123], v[172:173]
	v_pk_add_f32 v[126:127], v[126:127], v[190:191]
	v_pk_add_f32 v[124:125], v[124:125], v[188:189]
	v_pk_add_f32 v[118:119], v[118:119], v[194:195]
	v_pk_add_f32 v[116:117], v[116:117], v[192:193]
	v_pk_add_f32 v[120:121], v[120:121], v[170:171]
	v_pk_add_f32 v[170:171], v[112:113], v[196:197]
	global_store_dwordx4 v[178:179], v[124:127], off nt
	global_store_dwordx4 v[178:179], v[120:123], off offset:16 nt
	v_cvt_pk_bf16_f32 v112, v124, v125
	v_cvt_pk_bf16_f32 v113, v126, v127
	v_mul_f32_e32 v178, v117, v117
	v_mul_f32_e32 v125, v125, v125
	v_mul_f32_e32 v127, v127, v127
	v_mul_f32_e32 v179, v119, v119
	v_pk_add_f32 v[172:173], v[114:115], v[198:199]
	v_cvt_pk_bf16_f32 v114, v120, v121
	v_cvt_pk_bf16_f32 v115, v122, v123
	v_mul_f32_e32 v121, v121, v121
	v_mul_f32_e32 v123, v123, v123
	v_mul_f32_e32 v189, v171, v171
	v_fmac_f32_e32 v125, v124, v124
	v_fmac_f32_e32 v127, v126, v126
	v_fmac_f32_e32 v178, v116, v116
	v_fmac_f32_e32 v179, v118, v118
	v_mul_f32_e32 v190, v173, v173
	v_fmac_f32_e32 v121, v120, v120
	v_fmac_f32_e32 v123, v122, v122
	v_fmac_f32_e32 v189, v170, v170
	v_add_f32_e32 v120, v125, v127
	v_add_f32_e32 v122, v178, v179
	v_fmac_f32_e32 v190, v172, v172
	v_add_f32_e32 v120, v120, v121
	v_add_f32_e32 v121, v122, v189
	v_add_f32_e32 v120, v123, v120
	v_add_f32_e32 v121, v190, v121
	v_add_f32_e32 v120, v120, v121
	ds_bpermute_b32 v121, v186, v120
	v_cndmask_b32_e64 v187, v185, v203, s[0:1]
	v_lshlrev_b64 v[202:203], 10, v[164:165]
	v_lshl_add_u64 v[204:205], v[202:203], 0, v[162:163]
	v_lshl_add_u64 v[204:205], v[204:205], 1, s[24:25]
	s_cmp_lg_u32 s99, 0
	s_cbranch_scc1 .Lwt1314_33048
	global_store_dwordx4 v[204:205], v[112:115], off
	s_branch .Lwj1314_33048

; #define EPI_PACK8(v0, v1) (u32x4){pk2((v0)[0], (v0)[1]), pk2((v0)[2], (v0)[3]), pk2((v1)[0], (v1)[1]), pk2((v1)[2], (v1)[3])}
;     __device__ __forceinline__ void operator()(AccRef acc, const Unit& u, int wr, int wc, int fr, int fq) const {
;     ...
;             for (int bj = 0; bj < 2; ++bj) { const size_t p = (size_t)row * DM + EPI_COL(bj);
;                 const f32x4 x0 = xc[bj][0] + acc[ai][bj][m][0], x1 = xc[bj][1] + acc[ai][bj][m][1];
;                 __builtin_nontemporal_store(x0, (f32x4*)(xout + p)); __builtin_nontemporal_store(x1, (f32x4*)(xout + p + 4));
;                 *(u32x4*)(xb + p) = EPI_PACK8(x0, x1);
;                 q += EPI_SQ8(x0, x1); }
;             q += __shfl_xor(q, 16); q += __shfl_xor(q, 32);
.Lwj1314_33048:
	global_store_dwordx4 v[200:201], v[116:119], off nt
	global_store_dwordx4 v[200:201], v[170:173], off offset:16 nt
	s_waitcnt lgkmcnt(0)
	v_add_f32_e32 v112, v120, v121
	v_lshlrev_b32_e32 v187, 2, v187
	ds_bpermute_b32 v113, v187, v112
	v_lshl_add_u64 v[202:203], v[202:203], 0, v[160:161]
	v_lshl_add_u64 v[114:115], v[202:203], 1, s[24:25]
	v_cvt_pk_bf16_f32 v188, v116, v117
	v_cvt_pk_bf16_f32 v189, v118, v119
	v_cvt_pk_bf16_f32 v190, v170, v171
	v_cvt_pk_bf16_f32 v191, v172, v173
	s_cmp_lg_u32 s99, 0
	s_cbranch_scc1 .Lwt1314_33069
	global_store_dwordx4 v[114:115], v[188:191], off
	s_branch .Lwj1314_33069

; #define EPI_IT_ROW(it) EPI_ROW((it) >> 2, (it) & 3)
; #define EPI_PACK8(v0, v1) (u32x4){pk2((v0)[0], (v0)[1]), pk2((v0)[2], (v0)[3]), pk2((v1)[0], (v1)[1]), pk2((v1)[2], (v1)[3])}
;     __device__ __forceinline__ void operator()(AccRef acc, const Unit& u, int wr, int wc, int fr, int fq) const {
;     ...
;         for (int it = 0; it < 8; ++it) { const int ai = it >> 2, m = it & 3, row = EPI_IT_ROW(it);
;             if (it + 1 < 8) {
; #pragma unroll
;                 for (int bj = 0; bj < 2; ++bj) { const size_t p = (size_t)EPI_IT_ROW(it + 1) * DM + EPI_COL(bj); xn[bj][0] = *(const f32x4*)(xin + p); xn[bj][1] = *(const f32x4*)(xin + p + 4); } }
;             float q = 0.f;
; #pragma unroll
;             for (int bj = 0; bj < 2; ++bj) { const size_t p = (size_t)row * DM + EPI_COL(bj);
;                 const f32x4 x0 = xc[bj][0] + acc[ai][bj][m][0], x1 = xc[bj][1] + acc[ai][bj][m][1];
;                 __builtin_nontemporal_store(x0, (f32x4*)(xout + p)); __builtin_nontemporal_store(x1, (f32x4*)(xout + p + 4));
;                 *(u32x4*)(xb + p) = EPI_PACK8(x0, x1);
;                 q += EPI_SQ8(x0, x1); }
;             q += __shfl_xor(q, 16); q += __shfl_xor(q, 32);
;             if (fq == 0) atomicAdd(ssout + row, q);
; #pragma unroll
;             for (int bj = 0; bj < 2; ++bj) { xc[bj][0] = xn[bj][0]; xc[bj][1] = xn[bj][1]; } }
.Lwj1314_33069:
	s_and_saveexec_b64 s[0:1], vcc
	v_readlane_b32 s72, v254, 6
	v_readlane_b32 s73, v254, 7
	v_readlane_b32 s74, v254, 8
	v_readlane_b32 s75, v254, 9
	s_cbranch_execz .LBB0_1319
	v_lshl_add_u64 v[114:115], v[164:165], 2, s[10:11]
	s_waitcnt lgkmcnt(0)
	v_add_f32_e32 v112, v112, v113
	global_atomic_add_f32 v[114:115], v112, off
.LBB0_1319:
	s_or_b64 exec, exec, s[0:1]
	v_add_u32_e32 v170, 32, v164
	v_ashrrev_i32_e32 v171, 31, v170
	s_waitcnt lgkmcnt(0)
	v_lshlrev_b64 v[112:113], 12, v[170:171]
	v_lshl_add_u64 v[112:113], s[48:49], 0, v[112:113]
	v_lshl_add_u64 v[178:179], v[162:163], 2, v[112:113]
	v_lshl_add_u64 v[172:173], v[160:161], 2, v[112:113]
	global_load_dwordx4 v[120:123], v[178:179], off offset:16
	global_load_dwordx4 v[124:127], v[178:179], off
	global_load_dwordx4 v[112:115], v[172:173], off offset:16
	global_load_dwordx4 v[116:119], v[172:173], off
	v_pk_add_f32 v[110:111], v[110:111], v[142:143]
	v_pk_add_f32 v[108:109], v[108:109], v[140:141]
	v_pk_add_f32 v[106:107], v[106:107], v[138:139]
	v_pk_add_f32 v[104:105], v[104:105], v[136:137]
	global_store_dwordx4 v[174:175], v[108:111], off nt
	global_store_dwordx4 v[174:175], v[104:107], off offset:16 nt
	v_cvt_pk_bf16_f32 v136, v108, v109
	v_cvt_pk_bf16_f32 v138, v104, v105
	v_pk_add_f32 v[102:103], v[102:103], v[134:135]
	v_mul_f32_e32 v109, v109, v109
	v_fmac_f32_e32 v109, v108, v108
	v_mul_f32_e32 v108, v111, v111
	v_fmac_f32_e32 v108, v110, v110
	v_mul_f32_e32 v105, v105, v105
	v_add_f32_e32 v108, v109, v108
	v_fmac_f32_e32 v105, v104, v104
	v_add_f32_e32 v104, v108, v105
	v_mul_f32_e32 v105, v107, v107
	v_fmac_f32_e32 v105, v106, v106
	v_pk_add_f32 v[100:101], v[100:101], v[132:133]
	v_cvt_pk_bf16_f32 v137, v110, v111
	v_add_f32_e32 v110, v105, v104
	v_pk_add_f32 v[104:105], v[96:97], v[128:129]
	v_mul_f32_e32 v96, v101, v101
	v_mul_f32_e32 v97, v103, v103
	v_fmac_f32_e32 v96, v100, v100
	v_fmac_f32_e32 v97, v102, v102
	v_add_f32_e32 v96, v96, v97
	v_mul_f32_e32 v97, v105, v105
	v_cvt_pk_bf16_f32 v139, v106, v107
	v_pk_add_f32 v[106:107], v[98:99], v[130:131]
	v_fmac_f32_e32 v97, v104, v104
	v_add_f32_e32 v96, v96, v97
	v_mul_f32_e32 v97, v107, v107
	v_fmac_f32_e32 v97, v106, v106
	v_add_f32_e32 v96, v97, v96
	v_add_f32_e32 v96, v110, v96
	ds_bpermute_b32 v97, v186, v96
	v_lshlrev_b64 v[188:189], 10, v[166:167]
	v_lshl_add_u64 v[190:191], v[188:189], 0, v[162:163]
	v_lshl_add_u64 v[140:141], v[190:191], 1, s[24:25]
	v_lshl_add_u64 v[108:109], v[188:189], 0, v[160:161]
	s_waitcnt lgkmcnt(0)
	v_add_f32_e32 v96, v96, v97
	ds_bpermute_b32 v97, v187, v96
	s_cmp_lg_u32 s99, 0
	s_cbranch_scc1 .Lwt1314_33147
	global_store_dwordx4 v[140:141], v[136:139], off
	s_branch .Lwj1314_33147

; #define EPI_IT_ROW(it) EPI_ROW((it) >> 2, (it) & 3)
; #define EPI_PACK8(v0, v1) (u32x4){pk2((v0)[0], (v0)[1]), pk2((v0)[2], (v0)[3]), pk2((v1)[0], (v1)[1]), pk2((v1)[2], (v1)[3])}
;     __device__ __forceinline__ void operator()(AccRef acc, const Unit& u, int wr, int wc, int fr, int fq) const {
;     ...
;         for (int it = 0; it < 8; ++it) { const int ai = it >> 2, m = it & 3, row = EPI_IT_ROW(it);
;             if (it + 1 < 8) {
; #pragma unroll
;                 for (int bj = 0; bj < 2; ++bj) { const size_t p = (size_t)EPI_IT_ROW(it + 1) * DM + EPI_COL(bj); xn[bj][0] = *(const f32x4*)(xin + p); xn[bj][1] = *(const f32x4*)(xin + p + 4); } }
;             float q = 0.f;
; #pragma unroll
;             for (int bj = 0; bj < 2; ++bj) { const size_t p = (size_t)row * DM + EPI_COL(bj);
;                 const f32x4 x0 = xc[bj][0] + acc[ai][bj][m][0], x1 = xc[bj][1] + acc[ai][bj][m][1];
;                 __builtin_nontemporal_store(x0, (f32x4*)(xout + p)); __builtin_nontemporal_store(x1, (f32x4*)(xout + p + 4));
;                 *(u32x4*)(xb + p) = EPI_PACK8(x0, x1);
;                 q += EPI_SQ8(x0, x1); }
;             q += __shfl_xor(q, 16); q += __shfl_xor(q, 32);
;             if (fq == 0) atomicAdd(ssout + row, q);
; #pragma unroll
;             for (int bj = 0; bj < 2; ++bj) { xc[bj][0] = xn[bj][0]; xc[bj][1] = xn[bj][1]; } }
.Lwj1314_33147:
	global_store_dwordx4 v[168:169], v[100:103], off nt
	global_store_dwordx4 v[168:169], v[104:107], off offset:16 nt
	v_cvt_pk_bf16_f32 v99, v102, v103
	v_cvt_pk_bf16_f32 v98, v100, v101
	s_nop 0
	v_lshl_add_u64 v[102:103], v[108:109], 1, s[24:25]
	v_cvt_pk_bf16_f32 v100, v104, v105
	v_cvt_pk_bf16_f32 v101, v106, v107
	s_cmp_lg_u32 s99, 0
	s_cbranch_scc1 .Lwt1314_33164
	global_store_dwordx4 v[102:103], v[98:101], off
	s_branch .Lwj1314_33164

; #define EPI_IT_ROW(it) EPI_ROW((it) >> 2, (it) & 3)
; #define EPI_PACK8(v0, v1) (u32x4){pk2((v0)[0], (v0)[1]), pk2((v0)[2], (v0)[3]), pk2((v1)[0], (v1)[1]), pk2((v1)[2], (v1)[3])}
;     __device__ __forceinline__ void operator()(AccRef acc, const Unit& u, int wr, int wc, int fr, int fq) const {
;     ...
;         for (int it = 0; it < 8; ++it) { const int ai = it >> 2, m = it & 3, row = EPI_IT_ROW(it);
;             if (it + 1 < 8) {
; #pragma unroll
;                 for (int bj = 0; bj < 2; ++bj) { const size_t p = (size_t)EPI_IT_ROW(it + 1) * DM + EPI_COL(bj); xn[bj][0] = *(const f32x4*)(xin + p); xn[bj][1] = *(const f32x4*)(xin + p + 4); } }
;             float q = 0.f;
; #pragma unroll
;             for (int bj = 0; bj < 2; ++bj) { const size_t p = (size_t)row * DM + EPI_COL(bj);
;                 const f32x4 x0 = xc[bj][0] + acc[ai][bj][m][0], x1 = xc[bj][1] + acc[ai][bj][m][1];
;                 __builtin_nontemporal_store(x0, (f32x4*)(xout + p)); __builtin_nontemporal_store(x1, (f32x4*)(xout + p + 4));
;                 *(u32x4*)(xb + p) = EPI_PACK8(x0, x1);
;                 q += EPI_SQ8(x0, x1); }
;             q += __shfl_xor(q, 16); q += __shfl_xor(q, 32);
;             if (fq == 0) atomicAdd(ssout + row, q);
; #pragma unroll
;             for (int bj = 0; bj < 2; ++bj) { xc[bj][0] = xn[bj][0]; xc[bj][1] = xn[bj][1]; } }
.LBB0_1321:
	s_or_b64 exec, exec, s[0:1]
	v_add_u32_e32 v128, 48, v164
	v_ashrrev_i32_e32 v129, 31, v128
	s_waitcnt lgkmcnt(0)
	v_lshlrev_b64 v[96:97], 12, v[128:129]
	v_lshl_add_u64 v[96:97], s[48:49], 0, v[96:97]
	v_lshl_add_u64 v[132:133], v[162:163], 2, v[96:97]
	v_lshl_add_u64 v[130:131], v[160:161], 2, v[96:97]
	global_load_dwordx4 v[104:107], v[132:133], off offset:16
	global_load_dwordx4 v[108:111], v[132:133], off
	global_load_dwordx4 v[96:99], v[130:131], off offset:16
	global_load_dwordx4 v[100:103], v[130:131], off
	s_waitcnt vmcnt(12)
	v_pk_add_f32 v[94:95], v[94:95], v[126:127]
	v_pk_add_f32 v[92:93], v[92:93], v[124:125]
	v_pk_add_f32 v[90:91], v[90:91], v[122:123]
	v_pk_add_f32 v[88:89], v[88:89], v[120:121]
	global_store_dwordx4 v[178:179], v[92:95], off nt
	global_store_dwordx4 v[178:179], v[88:91], off offset:16 nt
	v_cvt_pk_bf16_f32 v120, v92, v93
	v_cvt_pk_bf16_f32 v122, v88, v89
	s_waitcnt vmcnt(12)
	v_pk_add_f32 v[86:87], v[86:87], v[118:119]
	v_mul_f32_e32 v93, v93, v93
	v_fmac_f32_e32 v93, v92, v92
	v_mul_f32_e32 v92, v95, v95
	v_fmac_f32_e32 v92, v94, v94
	v_mul_f32_e32 v89, v89, v89
	v_add_f32_e32 v92, v93, v92
	v_fmac_f32_e32 v89, v88, v88
	v_add_f32_e32 v88, v92, v89
	v_mul_f32_e32 v89, v91, v91
	v_fmac_f32_e32 v89, v90, v90
	v_pk_add_f32 v[84:85], v[84:85], v[116:117]
	v_cvt_pk_bf16_f32 v121, v94, v95
	v_add_f32_e32 v94, v89, v88
	v_pk_add_f32 v[88:89], v[80:81], v[112:113]
	v_mul_f32_e32 v80, v85, v85
	v_mul_f32_e32 v81, v87, v87
	v_fmac_f32_e32 v80, v84, v84
	v_fmac_f32_e32 v81, v86, v86
	v_add_f32_e32 v80, v80, v81
	v_mul_f32_e32 v81, v89, v89
	v_cvt_pk_bf16_f32 v123, v90, v91
	v_pk_add_f32 v[90:91], v[82:83], v[114:115]
	v_fmac_f32_e32 v81, v88, v88
	v_add_f32_e32 v80, v80, v81
	v_mul_f32_e32 v81, v91, v91
	v_fmac_f32_e32 v81, v90, v90
	v_add_f32_e32 v80, v81, v80
	v_add_f32_e32 v80, v94, v80
	ds_bpermute_b32 v81, v186, v80
	v_lshlrev_b64 v[134:135], 10, v[170:171]
	v_lshl_add_u64 v[136:137], v[134:135], 0, v[162:163]
	v_lshl_add_u64 v[124:125], v[136:137], 1, s[24:25]
	v_lshl_add_u64 v[92:93], v[134:135], 0, v[160:161]
	s_waitcnt lgkmcnt(0)
	v_add_f32_e32 v80, v80, v81
	ds_bpermute_b32 v81, v187, v80
	s_cmp_lg_u32 s99, 0
	s_cbranch_scc1 .Lwt1314_33240
	global_store_dwordx4 v[124:125], v[120:123], off
	s_branch .Lwj1314_33240

; #define EPI_IT_ROW(it) EPI_ROW((it) >> 2, (it) & 3)
; #define EPI_PACK8(v0, v1) (u32x4){pk2((v0)[0], (v0)[1]), pk2((v0)[2], (v0)[3]), pk2((v1)[0], (v1)[1]), pk2((v1)[2], (v1)[3])}
;     __device__ __forceinline__ void operator()(AccRef acc, const Unit& u, int wr, int wc, int fr, int fq) const {
;     ...
;         for (int it = 0; it < 8; ++it) { const int ai = it >> 2, m = it & 3, row = EPI_IT_ROW(it);
;             if (it + 1 < 8) {
; #pragma unroll
;                 for (int bj = 0; bj < 2; ++bj) { const size_t p = (size_t)EPI_IT_ROW(it + 1) * DM + EPI_COL(bj); xn[bj][0] = *(const f32x4*)(xin + p); xn[bj][1] = *(const f32x4*)(xin + p + 4); } }
;             float q = 0.f;
; #pragma unroll
;             for (int bj = 0; bj < 2; ++bj) { const size_t p = (size_t)row * DM + EPI_COL(bj);
;                 const f32x4 x0 = xc[bj][0] + acc[ai][bj][m][0], x1 = xc[bj][1] + acc[ai][bj][m][1];
;                 __builtin_nontemporal_store(x0, (f32x4*)(xout + p)); __builtin_nontemporal_store(x1, (f32x4*)(xout + p + 4));
;                 *(u32x4*)(xb + p) = EPI_PACK8(x0, x1);
;                 q += EPI_SQ8(x0, x1); }
;             q += __shfl_xor(q, 16); q += __shfl_xor(q, 32);
;             if (fq == 0) atomicAdd(ssout + row, q);
; #pragma unroll
;             for (int bj = 0; bj < 2; ++bj) { xc[bj][0] = xn[bj][0]; xc[bj][1] = xn[bj][1]; } }
.Lwj1314_33240:
	global_store_dwordx4 v[172:173], v[84:87], off nt
	global_store_dwordx4 v[172:173], v[88:91], off offset:16 nt
	v_cvt_pk_bf16_f32 v83, v86, v87
	v_cvt_pk_bf16_f32 v82, v84, v85
	s_nop 0
	v_lshl_add_u64 v[86:87], v[92:93], 1, s[24:25]
	v_cvt_pk_bf16_f32 v84, v88, v89
	v_cvt_pk_bf16_f32 v85, v90, v91
	s_cmp_lg_u32 s99, 0
	s_cbranch_scc1 .Lwt1314_33257
	global_store_dwordx4 v[86:87], v[82:85], off
	s_branch .Lwj1314_33257

; #define EPI_IT_ROW(it) EPI_ROW((it) >> 2, (it) & 3)
; #define EPI_PACK8(v0, v1) (u32x4){pk2((v0)[0], (v0)[1]), pk2((v0)[2], (v0)[3]), pk2((v1)[0], (v1)[1]), pk2((v1)[2], (v1)[3])}
;     __device__ __forceinline__ void operator()(AccRef acc, const Unit& u, int wr, int wc, int fr, int fq) const {
;     ...
;         for (int it = 0; it < 8; ++it) { const int ai = it >> 2, m = it & 3, row = EPI_IT_ROW(it);
;             if (it + 1 < 8) {
; #pragma unroll
;                 for (int bj = 0; bj < 2; ++bj) { const size_t p = (size_t)EPI_IT_ROW(it + 1) * DM + EPI_COL(bj); xn[bj][0] = *(const f32x4*)(xin + p); xn[bj][1] = *(const f32x4*)(xin + p + 4); } }
;             float q = 0.f;
; #pragma unroll
;             for (int bj = 0; bj < 2; ++bj) { const size_t p = (size_t)row * DM + EPI_COL(bj);
;                 const f32x4 x0 = xc[bj][0] + acc[ai][bj][m][0], x1 = xc[bj][1] + acc[ai][bj][m][1];
;                 __builtin_nontemporal_store(x0, (f32x4*)(xout + p)); __builtin_nontemporal_store(x1, (f32x4*)(xout + p + 4));
;                 *(u32x4*)(xb + p) = EPI_PACK8(x0, x1);
;                 q += EPI_SQ8(x0, x1); }
;             q += __shfl_xor(q, 16); q += __shfl_xor(q, 32);
;             if (fq == 0) atomicAdd(ssout + row, q);
; #pragma unroll
;             for (int bj = 0; bj < 2; ++bj) { xc[bj][0] = xn[bj][0]; xc[bj][1] = xn[bj][1]; } }
.Lwj1314_33257:
	s_and_saveexec_b64 s[0:1], vcc
	s_cbranch_execz .LBB0_1323
	v_lshl_add_u64 v[82:83], v[170:171], 2, s[10:11]
	s_waitcnt lgkmcnt(0)
	v_add_f32_e32 v80, v80, v81
	global_atomic_add_f32 v[82:83], v80, off
.LBB0_1323:
	s_or_b64 exec, exec, s[0:1]
	v_add_u32_e32 v112, 0x80, v164
	v_ashrrev_i32_e32 v113, 31, v112
	s_waitcnt lgkmcnt(0)
	v_lshlrev_b64 v[80:81], 12, v[112:113]
	v_lshl_add_u64 v[80:81], s[48:49], 0, v[80:81]
	v_lshl_add_u64 v[116:117], v[162:163], 2, v[80:81]
	v_lshl_add_u64 v[114:115], v[160:161], 2, v[80:81]
	global_load_dwordx4 v[88:91], v[116:117], off offset:16
	global_load_dwordx4 v[92:95], v[116:117], off
	global_load_dwordx4 v[80:83], v[114:115], off offset:16
	global_load_dwordx4 v[84:87], v[114:115], off
	s_waitcnt vmcnt(12)
	v_pk_add_f32 v[78:79], v[78:79], v[110:111]
	v_pk_add_f32 v[76:77], v[76:77], v[108:109]
	v_pk_add_f32 v[74:75], v[74:75], v[106:107]
	v_pk_add_f32 v[72:73], v[72:73], v[104:105]
	global_store_dwordx4 v[132:133], v[76:79], off nt
	global_store_dwordx4 v[132:133], v[72:75], off offset:16 nt
	v_cvt_pk_bf16_f32 v104, v76, v77
	v_cvt_pk_bf16_f32 v106, v72, v73
	s_waitcnt vmcnt(12)
	v_pk_add_f32 v[70:71], v[70:71], v[102:103]
	v_mul_f32_e32 v77, v77, v77
	v_fmac_f32_e32 v77, v76, v76
	v_mul_f32_e32 v76, v79, v79
	v_fmac_f32_e32 v76, v78, v78
	v_mul_f32_e32 v73, v73, v73
	v_add_f32_e32 v76, v77, v76
	v_fmac_f32_e32 v73, v72, v72
	v_add_f32_e32 v72, v76, v73
	v_mul_f32_e32 v73, v75, v75
	v_fmac_f32_e32 v73, v74, v74
	v_pk_add_f32 v[68:69], v[68:69], v[100:101]
	v_cvt_pk_bf16_f32 v105, v78, v79
	v_add_f32_e32 v78, v73, v72
	v_pk_add_f32 v[72:73], v[64:65], v[96:97]
	v_mul_f32_e32 v64, v69, v69
	v_mul_f32_e32 v65, v71, v71
	v_fmac_f32_e32 v64, v68, v68
	v_fmac_f32_e32 v65, v70, v70
	v_add_f32_e32 v64, v64, v65
	v_mul_f32_e32 v65, v73, v73
	v_cvt_pk_bf16_f32 v107, v74, v75
	v_pk_add_f32 v[74:75], v[66:67], v[98:99]
	v_fmac_f32_e32 v65, v72, v72
	v_add_f32_e32 v64, v64, v65
	v_mul_f32_e32 v65, v75, v75
	v_fmac_f32_e32 v65, v74, v74
	v_add_f32_e32 v64, v65, v64
	v_add_f32_e32 v64, v78, v64
	ds_bpermute_b32 v65, v186, v64
	v_lshlrev_b64 v[118:119], 10, v[128:129]
	v_lshl_add_u64 v[120:121], v[118:119], 0, v[162:163]
	v_lshl_add_u64 v[108:109], v[120:121], 1, s[24:25]
	v_lshl_add_u64 v[76:77], v[118:119], 0, v[160:161]
	s_waitcnt lgkmcnt(0)
	v_add_f32_e32 v64, v64, v65
	ds_bpermute_b32 v65, v187, v64
	s_cmp_lg_u32 s99, 0
	s_cbranch_scc1 .Lwt1314_33333
	global_store_dwordx4 v[108:109], v[104:107], off
	s_branch .Lwj1314_33333

; #define EPI_IT_ROW(it) EPI_ROW((it) >> 2, (it) & 3)
; #define EPI_PACK8(v0, v1) (u32x4){pk2((v0)[0], (v0)[1]), pk2((v0)[2], (v0)[3]), pk2((v1)[0], (v1)[1]), pk2((v1)[2], (v1)[3])}
;     __device__ __forceinline__ void operator()(AccRef acc, const Unit& u, int wr, int wc, int fr, int fq) const {
;     ...
;         for (int it = 0; it < 8; ++it) { const int ai = it >> 2, m = it & 3, row = EPI_IT_ROW(it);
;             if (it + 1 < 8) {
; #pragma unroll
;                 for (int bj = 0; bj < 2; ++bj) { const size_t p = (size_t)EPI_IT_ROW(it + 1) * DM + EPI_COL(bj); xn[bj][0] = *(const f32x4*)(xin + p); xn[bj][1] = *(const f32x4*)(xin + p + 4); } }
;             float q = 0.f;
; #pragma unroll
;             for (int bj = 0; bj < 2; ++bj) { const size_t p = (size_t)row * DM + EPI_COL(bj);
;                 const f32x4 x0 = xc[bj][0] + acc[ai][bj][m][0], x1 = xc[bj][1] + acc[ai][bj][m][1];
;                 __builtin_nontemporal_store(x0, (f32x4*)(xout + p)); __builtin_nontemporal_store(x1, (f32x4*)(xout + p + 4));
;                 *(u32x4*)(xb + p) = EPI_PACK8(x0, x1);
;                 q += EPI_SQ8(x0, x1); }
;             q += __shfl_xor(q, 16); q += __shfl_xor(q, 32);
;             if (fq == 0) atomicAdd(ssout + row, q);
; #pragma unroll
;             for (int bj = 0; bj < 2; ++bj) { xc[bj][0] = xn[bj][0]; xc[bj][1] = xn[bj][1]; } }
.Lwj1314_33333:
	global_store_dwordx4 v[130:131], v[68:71], off nt
	global_store_dwordx4 v[130:131], v[72:75], off offset:16 nt
	v_cvt_pk_bf16_f32 v67, v70, v71
	v_cvt_pk_bf16_f32 v66, v68, v69
	s_nop 0
	v_lshl_add_u64 v[70:71], v[76:77], 1, s[24:25]
	v_cvt_pk_bf16_f32 v68, v72, v73
	v_cvt_pk_bf16_f32 v69, v74, v75
	s_cmp_lg_u32 s99, 0
	s_cbranch_scc1 .Lwt1314_33350
	global_store_dwordx4 v[70:71], v[66:69], off
	s_branch .Lwj1314_33350

; #define EPI_IT_ROW(it) EPI_ROW((it) >> 2, (it) & 3)
; #define EPI_PACK8(v0, v1) (u32x4){pk2((v0)[0], (v0)[1]), pk2((v0)[2], (v0)[3]), pk2((v1)[0], (v1)[1]), pk2((v1)[2], (v1)[3])}
;     __device__ __forceinline__ void operator()(AccRef acc, const Unit& u, int wr, int wc, int fr, int fq) const {
;     ...
;         for (int it = 0; it < 8; ++it) { const int ai = it >> 2, m = it & 3, row = EPI_IT_ROW(it);
;             if (it + 1 < 8) {
; #pragma unroll
;                 for (int bj = 0; bj < 2; ++bj) { const size_t p = (size_t)EPI_IT_ROW(it + 1) * DM + EPI_COL(bj); xn[bj][0] = *(const f32x4*)(xin + p); xn[bj][1] = *(const f32x4*)(xin + p + 4); } }
;             float q = 0.f;
; #pragma unroll
;             for (int bj = 0; bj < 2; ++bj) { const size_t p = (size_t)row * DM + EPI_COL(bj);
;                 const f32x4 x0 = xc[bj][0] + acc[ai][bj][m][0], x1 = xc[bj][1] + acc[ai][bj][m][1];
;                 __builtin_nontemporal_store(x0, (f32x4*)(xout + p)); __builtin_nontemporal_store(x1, (f32x4*)(xout + p + 4));
;                 *(u32x4*)(xb + p) = EPI_PACK8(x0, x1);
;                 q += EPI_SQ8(x0, x1); }
;             q += __shfl_xor(q, 16); q += __shfl_xor(q, 32);
;             if (fq == 0) atomicAdd(ssout + row, q);
; #pragma unroll
;             for (int bj = 0; bj < 2; ++bj) { xc[bj][0] = xn[bj][0]; xc[bj][1] = xn[bj][1]; } }
.LBB0_1325:
	s_or_b64 exec, exec, s[0:1]
	v_add_u32_e32 v96, 0x90, v164
	v_ashrrev_i32_e32 v97, 31, v96
	s_waitcnt lgkmcnt(0)
	v_lshlrev_b64 v[64:65], 12, v[96:97]
	v_lshl_add_u64 v[64:65], s[48:49], 0, v[64:65]
	v_lshl_add_u64 v[100:101], v[162:163], 2, v[64:65]
	v_lshl_add_u64 v[98:99], v[160:161], 2, v[64:65]
	global_load_dwordx4 v[72:75], v[100:101], off offset:16
	global_load_dwordx4 v[76:79], v[100:101], off
	global_load_dwordx4 v[64:67], v[98:99], off offset:16
	global_load_dwordx4 v[68:71], v[98:99], off
	s_waitcnt vmcnt(12)
	v_pk_add_f32 v[62:63], v[62:63], v[94:95]
	v_pk_add_f32 v[60:61], v[60:61], v[92:93]
	v_pk_add_f32 v[58:59], v[58:59], v[90:91]
	v_pk_add_f32 v[56:57], v[56:57], v[88:89]
	global_store_dwordx4 v[116:117], v[60:63], off nt
	global_store_dwordx4 v[116:117], v[56:59], off offset:16 nt
	v_cvt_pk_bf16_f32 v88, v60, v61
	v_cvt_pk_bf16_f32 v90, v56, v57
	s_waitcnt vmcnt(12)
	v_pk_add_f32 v[54:55], v[54:55], v[86:87]
	v_mul_f32_e32 v61, v61, v61
	v_fmac_f32_e32 v61, v60, v60
	v_mul_f32_e32 v60, v63, v63
	v_fmac_f32_e32 v60, v62, v62
	v_mul_f32_e32 v57, v57, v57
	v_add_f32_e32 v60, v61, v60
	v_fmac_f32_e32 v57, v56, v56
	v_add_f32_e32 v56, v60, v57
	v_mul_f32_e32 v57, v59, v59
	v_fmac_f32_e32 v57, v58, v58
	v_pk_add_f32 v[52:53], v[52:53], v[84:85]
	v_cvt_pk_bf16_f32 v89, v62, v63
	v_add_f32_e32 v62, v57, v56
	v_pk_add_f32 v[56:57], v[48:49], v[80:81]
	v_mul_f32_e32 v48, v53, v53
	v_mul_f32_e32 v49, v55, v55
	v_fmac_f32_e32 v48, v52, v52
	v_fmac_f32_e32 v49, v54, v54
	v_add_f32_e32 v48, v48, v49
	v_mul_f32_e32 v49, v57, v57
	v_cvt_pk_bf16_f32 v91, v58, v59
	v_pk_add_f32 v[58:59], v[50:51], v[82:83]
	v_fmac_f32_e32 v49, v56, v56
	v_add_f32_e32 v48, v48, v49
	v_mul_f32_e32 v49, v59, v59
	v_fmac_f32_e32 v49, v58, v58
	v_add_f32_e32 v48, v49, v48
	v_add_f32_e32 v48, v62, v48
	ds_bpermute_b32 v49, v186, v48
	v_lshlrev_b64 v[102:103], 10, v[112:113]
	v_lshl_add_u64 v[104:105], v[102:103], 0, v[162:163]
	v_lshl_add_u64 v[92:93], v[104:105], 1, s[24:25]
	v_lshl_add_u64 v[60:61], v[102:103], 0, v[160:161]
	s_waitcnt lgkmcnt(0)
	v_add_f32_e32 v48, v48, v49
	ds_bpermute_b32 v49, v187, v48
	s_cmp_lg_u32 s99, 0
	s_cbranch_scc1 .Lwt1314_33426
	global_store_dwordx4 v[92:93], v[88:91], off
	s_branch .Lwj1314_33426

; #define EPI_IT_ROW(it) EPI_ROW((it) >> 2, (it) & 3)
; #define EPI_PACK8(v0, v1) (u32x4){pk2((v0)[0], (v0)[1]), pk2((v0)[2], (v0)[3]), pk2((v1)[0], (v1)[1]), pk2((v1)[2], (v1)[3])}
;     __device__ __forceinline__ void operator()(AccRef acc, const Unit& u, int wr, int wc, int fr, int fq) const {
;     ...
;         for (int it = 0; it < 8; ++it) { const int ai = it >> 2, m = it & 3, row = EPI_IT_ROW(it);
;             if (it + 1 < 8) {
; #pragma unroll
;                 for (int bj = 0; bj < 2; ++bj) { const size_t p = (size_t)EPI_IT_ROW(it + 1) * DM + EPI_COL(bj); xn[bj][0] = *(const f32x4*)(xin + p); xn[bj][1] = *(const f32x4*)(xin + p + 4); } }
;             float q = 0.f;
; #pragma unroll
;             for (int bj = 0; bj < 2; ++bj) { const size_t p = (size_t)row * DM + EPI_COL(bj);
;                 const f32x4 x0 = xc[bj][0] + acc[ai][bj][m][0], x1 = xc[bj][1] + acc[ai][bj][m][1];
;                 __builtin_nontemporal_store(x0, (f32x4*)(xout + p)); __builtin_nontemporal_store(x1, (f32x4*)(xout + p + 4));
;                 *(u32x4*)(xb + p) = EPI_PACK8(x0, x1);
;                 q += EPI_SQ8(x0, x1); }
;             q += __shfl_xor(q, 16); q += __shfl_xor(q, 32);
;             if (fq == 0) atomicAdd(ssout + row, q);
; #pragma unroll
;             for (int bj = 0; bj < 2; ++bj) { xc[bj][0] = xn[bj][0]; xc[bj][1] = xn[bj][1]; } }
.Lwj1314_33426:
	global_store_dwordx4 v[114:115], v[52:55], off nt
	global_store_dwordx4 v[114:115], v[56:59], off offset:16 nt
	v_cvt_pk_bf16_f32 v51, v54, v55
	v_cvt_pk_bf16_f32 v50, v52, v53
	s_nop 0
	v_lshl_add_u64 v[54:55], v[60:61], 1, s[24:25]
	v_cvt_pk_bf16_f32 v52, v56, v57
	v_cvt_pk_bf16_f32 v53, v58, v59
	s_cmp_lg_u32 s99, 0
	s_cbranch_scc1 .Lwt1314_33443
	global_store_dwordx4 v[54:55], v[50:53], off
	s_branch .Lwj1314_33443

; #define EPI_IT_ROW(it) EPI_ROW((it) >> 2, (it) & 3)
; #define EPI_PACK8(v0, v1) (u32x4){pk2((v0)[0], (v0)[1]), pk2((v0)[2], (v0)[3]), pk2((v1)[0], (v1)[1]), pk2((v1)[2], (v1)[3])}
;     __device__ __forceinline__ void operator()(AccRef acc, const Unit& u, int wr, int wc, int fr, int fq) const {
;     ...
;         for (int it = 0; it < 8; ++it) { const int ai = it >> 2, m = it & 3, row = EPI_IT_ROW(it);
;             if (it + 1 < 8) {
; #pragma unroll
;                 for (int bj = 0; bj < 2; ++bj) { const size_t p = (size_t)EPI_IT_ROW(it + 1) * DM + EPI_COL(bj); xn[bj][0] = *(const f32x4*)(xin + p); xn[bj][1] = *(const f32x4*)(xin + p + 4); } }
;             float q = 0.f;
; #pragma unroll
;             for (int bj = 0; bj < 2; ++bj) { const size_t p = (size_t)row * DM + EPI_COL(bj);
;                 const f32x4 x0 = xc[bj][0] + acc[ai][bj][m][0], x1 = xc[bj][1] + acc[ai][bj][m][1];
;                 __builtin_nontemporal_store(x0, (f32x4*)(xout + p)); __builtin_nontemporal_store(x1, (f32x4*)(xout + p + 4));
;                 *(u32x4*)(xb + p) = EPI_PACK8(x0, x1);
;                 q += EPI_SQ8(x0, x1); }
;             q += __shfl_xor(q, 16); q += __shfl_xor(q, 32);
;             if (fq == 0) atomicAdd(ssout + row, q);
; #pragma unroll
;             for (int bj = 0; bj < 2; ++bj) { xc[bj][0] = xn[bj][0]; xc[bj][1] = xn[bj][1]; } }
.LBB0_1327:
	s_or_b64 exec, exec, s[0:1]
	v_add_u32_e32 v80, 0xa0, v164
	v_ashrrev_i32_e32 v81, 31, v80
	s_waitcnt lgkmcnt(0)
	v_lshlrev_b64 v[48:49], 12, v[80:81]
	v_lshl_add_u64 v[48:49], s[48:49], 0, v[48:49]
	v_lshl_add_u64 v[84:85], v[162:163], 2, v[48:49]
	v_lshl_add_u64 v[82:83], v[160:161], 2, v[48:49]
	global_load_dwordx4 v[56:59], v[84:85], off offset:16
	global_load_dwordx4 v[60:63], v[84:85], off
	global_load_dwordx4 v[48:51], v[82:83], off offset:16
	global_load_dwordx4 v[52:55], v[82:83], off
	s_waitcnt vmcnt(12)
	v_pk_add_f32 v[46:47], v[46:47], v[78:79]
	v_pk_add_f32 v[44:45], v[44:45], v[76:77]
	v_pk_add_f32 v[42:43], v[42:43], v[74:75]
	v_pk_add_f32 v[40:41], v[40:41], v[72:73]
	global_store_dwordx4 v[100:101], v[44:47], off nt
	global_store_dwordx4 v[100:101], v[40:43], off offset:16 nt
	v_cvt_pk_bf16_f32 v72, v44, v45
	v_cvt_pk_bf16_f32 v74, v40, v41
	s_waitcnt vmcnt(12)
	v_pk_add_f32 v[38:39], v[38:39], v[70:71]
	v_mul_f32_e32 v45, v45, v45
	v_fmac_f32_e32 v45, v44, v44
	v_mul_f32_e32 v44, v47, v47
	v_fmac_f32_e32 v44, v46, v46
	v_mul_f32_e32 v41, v41, v41
	v_add_f32_e32 v44, v45, v44
	v_fmac_f32_e32 v41, v40, v40
	v_add_f32_e32 v40, v44, v41
	v_mul_f32_e32 v41, v43, v43
	v_fmac_f32_e32 v41, v42, v42
	v_pk_add_f32 v[36:37], v[36:37], v[68:69]
	v_cvt_pk_bf16_f32 v73, v46, v47
	v_add_f32_e32 v46, v41, v40
	v_pk_add_f32 v[40:41], v[32:33], v[64:65]
	v_mul_f32_e32 v32, v37, v37
	v_mul_f32_e32 v33, v39, v39
	v_fmac_f32_e32 v32, v36, v36
	v_fmac_f32_e32 v33, v38, v38
	v_add_f32_e32 v32, v32, v33
	v_mul_f32_e32 v33, v41, v41
	v_cvt_pk_bf16_f32 v75, v42, v43
	v_pk_add_f32 v[42:43], v[34:35], v[66:67]
	v_fmac_f32_e32 v33, v40, v40
	v_add_f32_e32 v32, v32, v33
	v_mul_f32_e32 v33, v43, v43
	v_fmac_f32_e32 v33, v42, v42
	v_add_f32_e32 v32, v33, v32
	v_add_f32_e32 v32, v46, v32
	ds_bpermute_b32 v33, v186, v32
	v_lshlrev_b64 v[86:87], 10, v[96:97]
	v_lshl_add_u64 v[88:89], v[86:87], 0, v[162:163]
	v_lshl_add_u64 v[76:77], v[88:89], 1, s[24:25]
	v_lshl_add_u64 v[44:45], v[86:87], 0, v[160:161]
	s_waitcnt lgkmcnt(0)
	v_add_f32_e32 v32, v32, v33
	ds_bpermute_b32 v33, v187, v32
	s_cmp_lg_u32 s99, 0
	s_cbranch_scc1 .Lwt1314_33519
	global_store_dwordx4 v[76:77], v[72:75], off
	s_branch .Lwj1314_33519

; #define EPI_IT_ROW(it) EPI_ROW((it) >> 2, (it) & 3)
; #define EPI_PACK8(v0, v1) (u32x4){pk2((v0)[0], (v0)[1]), pk2((v0)[2], (v0)[3]), pk2((v1)[0], (v1)[1]), pk2((v1)[2], (v1)[3])}
;     __device__ __forceinline__ void operator()(AccRef acc, const Unit& u, int wr, int wc, int fr, int fq) const {
;     ...
;         for (int it = 0; it < 8; ++it) { const int ai = it >> 2, m = it & 3, row = EPI_IT_ROW(it);
;             if (it + 1 < 8) {
; #pragma unroll
;                 for (int bj = 0; bj < 2; ++bj) { const size_t p = (size_t)EPI_IT_ROW(it + 1) * DM + EPI_COL(bj); xn[bj][0] = *(const f32x4*)(xin + p); xn[bj][1] = *(const f32x4*)(xin + p + 4); } }
;             float q = 0.f;
; #pragma unroll
;             for (int bj = 0; bj < 2; ++bj) { const size_t p = (size_t)row * DM + EPI_COL(bj);
;                 const f32x4 x0 = xc[bj][0] + acc[ai][bj][m][0], x1 = xc[bj][1] + acc[ai][bj][m][1];
;                 __builtin_nontemporal_store(x0, (f32x4*)(xout + p)); __builtin_nontemporal_store(x1, (f32x4*)(xout + p + 4));
;                 *(u32x4*)(xb + p) = EPI_PACK8(x0, x1);
;                 q += EPI_SQ8(x0, x1); }
;             q += __shfl_xor(q, 16); q += __shfl_xor(q, 32);
;             if (fq == 0) atomicAdd(ssout + row, q);
; #pragma unroll
;             for (int bj = 0; bj < 2; ++bj) { xc[bj][0] = xn[bj][0]; xc[bj][1] = xn[bj][1]; } }
.Lwj1314_33519:
	global_store_dwordx4 v[98:99], v[36:39], off nt
	global_store_dwordx4 v[98:99], v[40:43], off offset:16 nt
	v_cvt_pk_bf16_f32 v35, v38, v39
	v_cvt_pk_bf16_f32 v34, v36, v37
	s_nop 0
	v_lshl_add_u64 v[38:39], v[44:45], 1, s[24:25]
	v_cvt_pk_bf16_f32 v36, v40, v41
	v_cvt_pk_bf16_f32 v37, v42, v43
	s_cmp_lg_u32 s99, 0
	s_cbranch_scc1 .Lwt1314_33536
	global_store_dwordx4 v[38:39], v[34:37], off
	s_branch .Lwj1314_33536

; #define EPI_IT_ROW(it) EPI_ROW((it) >> 2, (it) & 3)
; #define EPI_PACK8(v0, v1) (u32x4){pk2((v0)[0], (v0)[1]), pk2((v0)[2], (v0)[3]), pk2((v1)[0], (v1)[1]), pk2((v1)[2], (v1)[3])}
;     __device__ __forceinline__ void operator()(AccRef acc, const Unit& u, int wr, int wc, int fr, int fq) const {
;     ...
;         for (int it = 0; it < 8; ++it) { const int ai = it >> 2, m = it & 3, row = EPI_IT_ROW(it);
;             if (it + 1 < 8) {
; #pragma unroll
;                 for (int bj = 0; bj < 2; ++bj) { const size_t p = (size_t)EPI_IT_ROW(it + 1) * DM + EPI_COL(bj); xn[bj][0] = *(const f32x4*)(xin + p); xn[bj][1] = *(const f32x4*)(xin + p + 4); } }
;             float q = 0.f;
; #pragma unroll
;             for (int bj = 0; bj < 2; ++bj) { const size_t p = (size_t)row * DM + EPI_COL(bj);
;                 const f32x4 x0 = xc[bj][0] + acc[ai][bj][m][0], x1 = xc[bj][1] + acc[ai][bj][m][1];
;                 __builtin_nontemporal_store(x0, (f32x4*)(xout + p)); __builtin_nontemporal_store(x1, (f32x4*)(xout + p + 4));
;                 *(u32x4*)(xb + p) = EPI_PACK8(x0, x1);
;                 q += EPI_SQ8(x0, x1); }
;             q += __shfl_xor(q, 16); q += __shfl_xor(q, 32);
;             if (fq == 0) atomicAdd(ssout + row, q);
; #pragma unroll
;             for (int bj = 0; bj < 2; ++bj) { xc[bj][0] = xn[bj][0]; xc[bj][1] = xn[bj][1]; } }
.LBB0_1329:
	s_or_b64 exec, exec, s[0:1]
	v_add_u32_e32 v64, 0xb0, v164
	v_ashrrev_i32_e32 v65, 31, v64
	s_waitcnt lgkmcnt(0)
	v_lshlrev_b64 v[32:33], 12, v[64:65]
	v_lshl_add_u64 v[32:33], s[48:49], 0, v[32:33]
	v_lshl_add_u64 v[68:69], v[162:163], 2, v[32:33]
	v_lshl_add_u64 v[66:67], v[160:161], 2, v[32:33]
	global_load_dwordx4 v[40:43], v[68:69], off offset:16
	global_load_dwordx4 v[44:47], v[68:69], off
	global_load_dwordx4 v[32:35], v[66:67], off offset:16
	global_load_dwordx4 v[36:39], v[66:67], off
	s_waitcnt vmcnt(12)
	v_pk_add_f32 v[30:31], v[30:31], v[62:63]
	v_pk_add_f32 v[28:29], v[28:29], v[60:61]
	v_pk_add_f32 v[26:27], v[26:27], v[58:59]
	v_pk_add_f32 v[24:25], v[24:25], v[56:57]
	global_store_dwordx4 v[84:85], v[28:31], off nt
	global_store_dwordx4 v[84:85], v[24:27], off offset:16 nt
	v_cvt_pk_bf16_f32 v56, v28, v29
	v_cvt_pk_bf16_f32 v58, v24, v25
	s_waitcnt vmcnt(12)
	v_pk_add_f32 v[22:23], v[22:23], v[54:55]
	v_mul_f32_e32 v29, v29, v29
	v_fmac_f32_e32 v29, v28, v28
	v_mul_f32_e32 v28, v31, v31
	v_fmac_f32_e32 v28, v30, v30
	v_mul_f32_e32 v25, v25, v25
	v_add_f32_e32 v28, v29, v28
	v_fmac_f32_e32 v25, v24, v24
	v_add_f32_e32 v24, v28, v25
	v_mul_f32_e32 v25, v27, v27
	v_fmac_f32_e32 v25, v26, v26
	v_pk_add_f32 v[20:21], v[20:21], v[52:53]
	v_cvt_pk_bf16_f32 v57, v30, v31
	v_add_f32_e32 v30, v25, v24
	v_pk_add_f32 v[24:25], v[16:17], v[48:49]
	v_mul_f32_e32 v16, v21, v21
	v_mul_f32_e32 v17, v23, v23
	v_fmac_f32_e32 v16, v20, v20
	v_fmac_f32_e32 v17, v22, v22
	v_add_f32_e32 v16, v16, v17
	v_mul_f32_e32 v17, v25, v25
	v_cvt_pk_bf16_f32 v59, v26, v27
	v_pk_add_f32 v[26:27], v[18:19], v[50:51]
	v_fmac_f32_e32 v17, v24, v24
	v_add_f32_e32 v16, v16, v17
	v_mul_f32_e32 v17, v27, v27
	v_fmac_f32_e32 v17, v26, v26
	v_add_f32_e32 v16, v17, v16
	v_add_f32_e32 v16, v30, v16
	ds_bpermute_b32 v17, v186, v16
	v_lshlrev_b64 v[70:71], 10, v[80:81]
	v_lshl_add_u64 v[72:73], v[70:71], 0, v[162:163]
	v_lshl_add_u64 v[60:61], v[72:73], 1, s[24:25]
	v_lshl_add_u64 v[28:29], v[70:71], 0, v[160:161]
	s_waitcnt lgkmcnt(0)
	v_add_f32_e32 v16, v16, v17
	ds_bpermute_b32 v17, v187, v16
	s_cmp_lg_u32 s99, 0
	s_cbranch_scc1 .Lwt1314_33612
	global_store_dwordx4 v[60:61], v[56:59], off
	s_branch .Lwj1314_33612

; #define EPI_IT_ROW(it) EPI_ROW((it) >> 2, (it) & 3)
; #define EPI_PACK8(v0, v1) (u32x4){pk2((v0)[0], (v0)[1]), pk2((v0)[2], (v0)[3]), pk2((v1)[0], (v1)[1]), pk2((v1)[2], (v1)[3])}
;     __device__ __forceinline__ void operator()(AccRef acc, const Unit& u, int wr, int wc, int fr, int fq) const {
;     ...
;         for (int it = 0; it < 8; ++it) { const int ai = it >> 2, m = it & 3, row = EPI_IT_ROW(it);
;             if (it + 1 < 8) {
; #pragma unroll
;                 for (int bj = 0; bj < 2; ++bj) { const size_t p = (size_t)EPI_IT_ROW(it + 1) * DM + EPI_COL(bj); xn[bj][0] = *(const f32x4*)(xin + p); xn[bj][1] = *(const f32x4*)(xin + p + 4); } }
;             float q = 0.f;
; #pragma unroll
;             for (int bj = 0; bj < 2; ++bj) { const size_t p = (size_t)row * DM + EPI_COL(bj);
;                 const f32x4 x0 = xc[bj][0] + acc[ai][bj][m][0], x1 = xc[bj][1] + acc[ai][bj][m][1];
;                 __builtin_nontemporal_store(x0, (f32x4*)(xout + p)); __builtin_nontemporal_store(x1, (f32x4*)(xout + p + 4));
;                 *(u32x4*)(xb + p) = EPI_PACK8(x0, x1);
;                 q += EPI_SQ8(x0, x1); }
;             q += __shfl_xor(q, 16); q += __shfl_xor(q, 32);
;             if (fq == 0) atomicAdd(ssout + row, q);
; #pragma unroll
;             for (int bj = 0; bj < 2; ++bj) { xc[bj][0] = xn[bj][0]; xc[bj][1] = xn[bj][1]; } }
.Lwj1314_33612:
	global_store_dwordx4 v[82:83], v[20:23], off nt
	global_store_dwordx4 v[82:83], v[24:27], off offset:16 nt
	v_cvt_pk_bf16_f32 v19, v22, v23
	v_cvt_pk_bf16_f32 v18, v20, v21
	s_nop 0
	v_lshl_add_u64 v[22:23], v[28:29], 1, s[24:25]
	v_cvt_pk_bf16_f32 v20, v24, v25
	v_cvt_pk_bf16_f32 v21, v26, v27
	s_cmp_lg_u32 s99, 0
	s_cbranch_scc1 .Lwt1314_33629
	global_store_dwordx4 v[22:23], v[18:21], off
	s_branch .Lwj1314_33629

; #define EPI_IT_ROW(it) EPI_ROW((it) >> 2, (it) & 3)
; #define EPI_PACK8(v0, v1) (u32x4){pk2((v0)[0], (v0)[1]), pk2((v0)[2], (v0)[3]), pk2((v1)[0], (v1)[1]), pk2((v1)[2], (v1)[3])}
;     __device__ __forceinline__ void operator()(AccRef acc, const Unit& u, int wr, int wc, int fr, int fq) const {
;     ...
;         for (int it = 0; it < 8; ++it) { const int ai = it >> 2, m = it & 3, row = EPI_IT_ROW(it);
;             if (it + 1 < 8) {
; #pragma unroll
;                 for (int bj = 0; bj < 2; ++bj) { const size_t p = (size_t)EPI_IT_ROW(it + 1) * DM + EPI_COL(bj); xn[bj][0] = *(const f32x4*)(xin + p); xn[bj][1] = *(const f32x4*)(xin + p + 4); } }
;             float q = 0.f;
; #pragma unroll
;             for (int bj = 0; bj < 2; ++bj) { const size_t p = (size_t)row * DM + EPI_COL(bj);
;                 const f32x4 x0 = xc[bj][0] + acc[ai][bj][m][0], x1 = xc[bj][1] + acc[ai][bj][m][1];
;                 __builtin_nontemporal_store(x0, (f32x4*)(xout + p)); __builtin_nontemporal_store(x1, (f32x4*)(xout + p + 4));
;                 *(u32x4*)(xb + p) = EPI_PACK8(x0, x1);
;                 q += EPI_SQ8(x0, x1); }
;             q += __shfl_xor(q, 16); q += __shfl_xor(q, 32);
;             if (fq == 0) atomicAdd(ssout + row, q);
; #pragma unroll
;             for (int bj = 0; bj < 2; ++bj) { xc[bj][0] = xn[bj][0]; xc[bj][1] = xn[bj][1]; } }
.LBB0_1331:
	s_or_b64 exec, exec, s[0:1]
	s_waitcnt vmcnt(8)
	v_pk_add_f32 v[14:15], v[14:15], v[46:47]
	v_pk_add_f32 v[12:13], v[12:13], v[44:45]
	v_pk_add_f32 v[10:11], v[10:11], v[42:43]
	v_pk_add_f32 v[8:9], v[8:9], v[40:41]
	global_store_dwordx4 v[68:69], v[12:15], off nt
	global_store_dwordx4 v[68:69], v[8:11], off offset:16 nt
	v_cvt_pk_bf16_f32 v16, v12, v13
	v_cvt_pk_bf16_f32 v18, v8, v9
	s_waitcnt vmcnt(8)
	v_pk_add_f32 v[6:7], v[6:7], v[38:39]
	v_mul_f32_e32 v13, v13, v13
	v_fmac_f32_e32 v13, v12, v12
	v_mul_f32_e32 v12, v15, v15
	v_fmac_f32_e32 v12, v14, v14
	v_mul_f32_e32 v9, v9, v9
	v_add_f32_e32 v12, v13, v12
	v_fmac_f32_e32 v9, v8, v8
	v_add_f32_e32 v8, v12, v9
	v_mul_f32_e32 v9, v11, v11
	v_fmac_f32_e32 v9, v10, v10
	v_pk_add_f32 v[4:5], v[4:5], v[36:37]
	s_waitcnt lgkmcnt(0)
	v_cvt_pk_bf16_f32 v17, v14, v15
	v_add_f32_e32 v14, v9, v8
	v_pk_add_f32 v[8:9], v[0:1], v[32:33]
	v_mul_f32_e32 v0, v5, v5
	v_mul_f32_e32 v1, v7, v7
	v_fmac_f32_e32 v0, v4, v4
	v_fmac_f32_e32 v1, v6, v6
	v_add_f32_e32 v0, v0, v1
	v_mul_f32_e32 v1, v9, v9
	v_cvt_pk_bf16_f32 v19, v10, v11
	v_pk_add_f32 v[10:11], v[2:3], v[34:35]
	v_fmac_f32_e32 v1, v8, v8
	v_add_f32_e32 v0, v0, v1
	v_mul_f32_e32 v1, v11, v11
	v_fmac_f32_e32 v1, v10, v10
	v_add_f32_e32 v0, v1, v0
	v_add_f32_e32 v0, v14, v0
	ds_bpermute_b32 v1, v186, v0
	v_lshlrev_b64 v[20:21], 10, v[64:65]
	v_lshl_add_u64 v[22:23], v[20:21], 0, v[162:163]
	v_lshl_add_u64 v[22:23], v[22:23], 1, s[24:25]
	v_lshl_add_u64 v[12:13], v[20:21], 0, v[160:161]
	s_waitcnt lgkmcnt(0)
	v_add_f32_e32 v0, v0, v1
	ds_bpermute_b32 v1, v187, v0
	s_cmp_lg_u32 s99, 0
	s_cbranch_scc1 .Lwt1314_33695
	global_store_dwordx4 v[22:23], v[16:19], off
	s_branch .Lwj1314_33695

; #define EPI_IT_ROW(it) EPI_ROW((it) >> 2, (it) & 3)
; #define EPI_PACK8(v0, v1) (u32x4){pk2((v0)[0], (v0)[1]), pk2((v0)[2], (v0)[3]), pk2((v1)[0], (v1)[1]), pk2((v1)[2], (v1)[3])}
;     __device__ __forceinline__ void operator()(AccRef acc, const Unit& u, int wr, int wc, int fr, int fq) const {
;     ...
;         for (int it = 0; it < 8; ++it) { const int ai = it >> 2, m = it & 3, row = EPI_IT_ROW(it);
;             if (it + 1 < 8) {
; #pragma unroll
;                 for (int bj = 0; bj < 2; ++bj) { const size_t p = (size_t)EPI_IT_ROW(it + 1) * DM + EPI_COL(bj); xn[bj][0] = *(const f32x4*)(xin + p); xn[bj][1] = *(const f32x4*)(xin + p + 4); } }
;             float q = 0.f;
; #pragma unroll
;             for (int bj = 0; bj < 2; ++bj) { const size_t p = (size_t)row * DM + EPI_COL(bj);
;                 const f32x4 x0 = xc[bj][0] + acc[ai][bj][m][0], x1 = xc[bj][1] + acc[ai][bj][m][1];
;                 __builtin_nontemporal_store(x0, (f32x4*)(xout + p)); __builtin_nontemporal_store(x1, (f32x4*)(xout + p + 4));
;                 *(u32x4*)(xb + p) = EPI_PACK8(x0, x1);
;                 q += EPI_SQ8(x0, x1); }
;             q += __shfl_xor(q, 16); q += __shfl_xor(q, 32);
;             if (fq == 0) atomicAdd(ssout + row, q);
; #pragma unroll
;             for (int bj = 0; bj < 2; ++bj) { xc[bj][0] = xn[bj][0]; xc[bj][1] = xn[bj][1]; } }
.Lwj1314_33695:
	global_store_dwordx4 v[66:67], v[4:7], off nt
	global_store_dwordx4 v[66:67], v[8:11], off offset:16 nt
	v_cvt_pk_bf16_f32 v3, v6, v7
	v_cvt_pk_bf16_f32 v2, v4, v5
	s_nop 0
	v_lshl_add_u64 v[6:7], v[12:13], 1, s[24:25]
	v_cvt_pk_bf16_f32 v4, v8, v9
	v_cvt_pk_bf16_f32 v5, v10, v11
	s_cmp_lg_u32 s99, 0
	s_cbranch_scc1 .Lwt1314_33712
	global_store_dwordx4 v[6:7], v[2:5], off
	s_branch .Lwj1314_33712

; #define PG8_STAGE(bufoff, gbase, voff) do { _Pragma("unroll") for (int _i = 0; _i < 2; ++_i) \
;         __builtin_amdgcn_global_load_lds((const unsigned*)((const char*)(gbase) + (voff)[_i]), (LAS unsigned*)(lds + (bufoff) + ldsw + _i * 8192), 16, 0, 0); } while (0)
; #define PG8_LDA(dst, b, h) do { _Pragma("unroll") for (int m = 0; m < 4; ++m) _Pragma("unroll") for (int k = 0; k < 2; ++k) dst[m][k] = *(const LAS bf16x8*)(lds + PG8_SA(b, h) + aoff + m * 2048 + k * 1024); } while (0)
; #define PG8_LDB(dst, b, h) do { _Pragma("unroll") for (int n = 0; n < 2; ++n) _Pragma("unroll") for (int k = 0; k < 2; ++k) dst[n][k] = *(const LAS bf16x8*)(lds + PG8_SB(b, h) + boff + n * 2048 + k * 1024); } while (0)
; #define PG8_MMA(ai, bj, At, Bt) do { __builtin_amdgcn_s_setprio(1); _Pragma("unroll") for (int m = 0; m < 4; ++m) _Pragma("unroll") for (int n = 0; n < 2; ++n) _Pragma("unroll") for (int k = 0; k < 2; ++k) \
;         acc[ai][bj][m][n] = __builtin_amdgcn_mfma_f32_16x16x32_bf16(Bt[n][k], At[m][k], acc[ai][bj][m][n], 0, 0, 0); __builtin_amdgcn_s_setprio(0); } while (0)
; #define PG8_WAIT_V(n) asm volatile("s_waitcnt vmcnt(" #n ")" ::: "memory")
; #define PG8_WAIT_L(n) asm volatile("s_waitcnt lgkmcnt(" #n ")" ::: "memory")
; #define PG8_BAR __builtin_amdgcn_s_barrier()
; #define PG8_SCHED __builtin_amdgcn_sched_barrier(0)
; template <class Epi>
; __device__ __forceinline__ void gemm_phase(LAS unsigned char* lds, const Gemm g, const StaticOrder& S, const Epi& E) {
;     ...
;             PG8_LDB(B0, 0, 0); PG8_LDB(B1, 0, 1); PG8_SCHED; PG8_LDA(At, 0, 0); PG8_STAGE(PG8_SA(1, 1), a1 + hstepA, voffA);
;             PG8_WAIT_V(8); PG8_WAIT_L(0); PG8_BAR; PG8_MMA(0, 0, At, B0); PG8_MMA(0, 1, At, B1); PG8_BAR; PG8_SCHED;
;             PG8_LDA(At, 0, 1); PG8_STAGE(PG8_SB(0, 0), b2, voffB); PG8_STAGE(PG8_SB(0, 1), b2 + hstepB, voffB); PG8_STAGE(PG8_SA(0, 0), a2, voffA);
;             PG8_WAIT_V(8); PG8_WAIT_L(0); PG8_BAR; PG8_MMA(1, 0, At, B0); PG8_MMA(1, 1, At, B1); PG8_BAR; PG8_SCHED;
;             PG8_LDB(B0, 1, 0); PG8_LDB(B1, 1, 1); PG8_SCHED; PG8_LDA(At, 1, 0); PG8_STAGE(PG8_SA(0, 1), a2 + hstepA, voffA);
;             PG8_WAIT_V(8); PG8_WAIT_L(0); PG8_BAR; PG8_MMA(0, 0, At, B0); PG8_MMA(0, 1, At, B1); PG8_BAR; PG8_SCHED;
.LBB0_1403:
	ds_read_b128 v[146:149], v162
	ds_read_b128 v[166:169], v162 offset:1024
	ds_read_b128 v[170:173], v162 offset:2048
	ds_read_b128 v[178:181], v162 offset:3072
	ds_read_b128 v[182:185], v163
	ds_read_b128 v[186:189], v163 offset:1024
	ds_read_b128 v[190:193], v163 offset:2048
	ds_read_b128 v[194:197], v163 offset:3072
	s_add_u32 s10, s8, 0xfffc0080
	s_addc_u32 s11, s9, -1
	s_cmp_eq_u32 s87, 12
	s_cselect_b32 s13, s1, s11
	s_cselect_b32 s12, s7, s10
	s_cselect_b32 s11, s65, s75
	s_cselect_b32 s10, s69, s74
	v_lshl_add_u64 v[174:175], s[8:9], 0, v[138:139]
	s_add_i32 m0, s53, 0xc000
	ds_read_b128 v[198:201], v164
	ds_read_b128 v[202:205], v164 offset:1024
	ds_read_b128 v[206:209], v164 offset:2048
	ds_read_b128 v[210:213], v164 offset:3072
	ds_read_b128 v[214:217], v164 offset:4096
	ds_read_b128 v[218:221], v164 offset:5120
	ds_read_b128 v[222:225], v164 offset:6144
	ds_read_b128 v[226:229], v164 offset:7168
	global_load_lds_dwordx4 v[174:175], off
	v_lshl_add_u64 v[174:175], s[8:9], 0, v[140:141]
	s_add_i32 m0, s53, 0xe000
	s_nop 0
	global_load_lds_dwordx4 v[174:175], off
	s_waitcnt vmcnt(8)
	s_waitcnt lgkmcnt(0)
	s_barrier
	s_setprio 1
	s_waitcnt lgkmcnt(0)
	v_mfma_f32_16x16x32_bf16 v[124:127], v[146:149], v[198:201], v[124:127]
	v_mfma_f32_16x16x32_bf16 v[120:123], v[170:173], v[198:201], v[120:123]
	v_mfma_f32_16x16x32_bf16 v[112:115], v[146:149], v[206:209], v[112:115]
	v_mfma_f32_16x16x32_bf16 v[104:107], v[170:173], v[206:209], v[104:107]
	v_mfma_f32_16x16x32_bf16 v[100:103], v[146:149], v[214:217], v[100:103]
	v_mfma_f32_16x16x32_bf16 v[92:95], v[170:173], v[214:217], v[92:95]
	v_mfma_f32_16x16x32_bf16 v[84:87], v[146:149], v[222:225], v[84:87]
	v_mfma_f32_16x16x32_bf16 v[76:79], v[170:173], v[222:225], v[76:79]
	v_mfma_f32_16x16x32_bf16 v[124:127], v[166:169], v[202:205], v[124:127]
	v_mfma_f32_16x16x32_bf16 v[120:123], v[178:181], v[202:205], v[120:123]
	v_mfma_f32_16x16x32_bf16 v[112:115], v[166:169], v[210:213], v[112:115]
	v_mfma_f32_16x16x32_bf16 v[104:107], v[178:181], v[210:213], v[104:107]
	v_mfma_f32_16x16x32_bf16 v[100:103], v[166:169], v[218:221], v[100:103]
	v_mfma_f32_16x16x32_bf16 v[92:95], v[178:181], v[218:221], v[92:95]
	v_mfma_f32_16x16x32_bf16 v[84:87], v[166:169], v[226:229], v[84:87]
	v_mfma_f32_16x16x32_bf16 v[76:79], v[178:181], v[226:229], v[76:79]
	s_setprio 0
	s_setprio 1
	v_mfma_f32_16x16x32_bf16 v[116:119], v[182:185], v[198:201], v[116:119]
	v_mfma_f32_16x16x32_bf16 v[108:111], v[190:193], v[198:201], v[108:111]
	v_mfma_f32_16x16x32_bf16 v[96:99], v[182:185], v[206:209], v[96:99]
	v_mfma_f32_16x16x32_bf16 v[88:91], v[190:193], v[206:209], v[88:91]
	v_mfma_f32_16x16x32_bf16 v[80:83], v[182:185], v[214:217], v[80:83]
	v_mfma_f32_16x16x32_bf16 v[72:75], v[190:193], v[214:217], v[72:75]
	v_mfma_f32_16x16x32_bf16 v[68:71], v[182:185], v[222:225], v[68:71]
	v_mfma_f32_16x16x32_bf16 v[64:67], v[190:193], v[222:225], v[64:67]
	v_mfma_f32_16x16x32_bf16 v[116:119], v[186:189], v[202:205], v[116:119]
	v_mfma_f32_16x16x32_bf16 v[108:111], v[194:197], v[202:205], v[108:111]
	v_mfma_f32_16x16x32_bf16 v[96:99], v[186:189], v[210:213], v[96:99]
	v_mfma_f32_16x16x32_bf16 v[88:91], v[194:197], v[210:213], v[88:91]
	v_mfma_f32_16x16x32_bf16 v[80:83], v[186:189], v[218:221], v[80:83]
	v_mfma_f32_16x16x32_bf16 v[72:75], v[194:197], v[218:221], v[72:75]
	v_mfma_f32_16x16x32_bf16 v[68:71], v[186:189], v[226:229], v[68:71]
	v_mfma_f32_16x16x32_bf16 v[64:67], v[194:197], v[226:229], v[64:67]
	s_setprio 0
	s_barrier
	s_add_i32 s88, s83, s43
	v_lshl_add_u64 v[174:175], s[10:11], 0, v[130:131]
	s_mov_b32 m0, s88
	ds_read_b128 v[198:201], v164 offset:16384
	ds_read_b128 v[202:205], v164 offset:17408
	ds_read_b128 v[206:209], v164 offset:18432
	ds_read_b128 v[210:213], v164 offset:19456
	ds_read_b128 v[214:217], v164 offset:20480
	ds_read_b128 v[218:221], v164 offset:21504
	ds_read_b128 v[222:225], v164 offset:22528
	ds_read_b128 v[226:229], v164 offset:23552
	global_load_lds_dwordx4 v[174:175], off
	s_add_i32 m0, s88, 0x2000
	s_add_u32 s88, s10, 0x40000
	v_lshl_add_u64 v[230:231], s[10:11], 0, v[134:135]
	s_addc_u32 s89, s11, 0
	s_add_i32 s90, s84, s43
	global_load_lds_dwordx4 v[230:231], off
	v_lshl_add_u64 v[232:233], s[88:89], 0, v[130:131]
	s_mov_b32 m0, s90
	v_lshl_add_u64 v[234:235], s[12:13], 0, v[132:133]
	global_load_lds_dwordx4 v[232:233], off
	v_lshl_add_u64 v[232:233], s[88:89], 0, v[134:135]
	s_add_i32 m0, s90, 0x2000
	s_nop 0
	global_load_lds_dwordx4 v[232:233], off
	v_lshl_add_u64 v[232:233], s[12:13], 0, v[128:129]
	s_mov_b32 m0, s53
	s_nop 0
	global_load_lds_dwordx4 v[232:233], off
	s_mov_b32 m0, s55
	s_nop 0
	global_load_lds_dwordx4 v[234:235], off
	s_waitcnt vmcnt(8)
	s_waitcnt lgkmcnt(0)
	s_barrier
; #define PG8_STAGE(bufoff, gbase, voff) do { _Pragma("unroll") for (int _i = 0; _i < 2; ++_i) \
;         __builtin_amdgcn_global_load_lds((const unsigned*)((const char*)(gbase) + (voff)[_i]), (LAS unsigned*)(lds + (bufoff) + ldsw + _i * 8192), 16, 0, 0); } while (0)
; #define PG8_LDA(dst, b, h) do { _Pragma("unroll") for (int m = 0; m < 4; ++m) _Pragma("unroll") for (int k = 0; k < 2; ++k) dst[m][k] = *(const LAS bf16x8*)(lds + PG8_SA(b, h) + aoff + m * 2048 + k * 1024); } while (0)
; #define PG8_LDB(dst, b, h) do { _Pragma("unroll") for (int n = 0; n < 2; ++n) _Pragma("unroll") for (int k = 0; k < 2; ++k) dst[n][k] = *(const LAS bf16x8*)(lds + PG8_SB(b, h) + boff + n * 2048 + k * 1024); } while (0)
; #define PG8_MMA(ai, bj, At, Bt) do { __builtin_amdgcn_s_setprio(1); _Pragma("unroll") for (int m = 0; m < 4; ++m) _Pragma("unroll") for (int n = 0; n < 2; ++n) _Pragma("unroll") for (int k = 0; k < 2; ++k) \
;         acc[ai][bj][m][n] = __builtin_amdgcn_mfma_f32_16x16x32_bf16(Bt[n][k], At[m][k], acc[ai][bj][m][n], 0, 0, 0); __builtin_amdgcn_s_setprio(0); } while (0)
; #define PG8_WAIT_V(n) asm volatile("s_waitcnt vmcnt(" #n ")" ::: "memory")
; #define PG8_BAR __builtin_amdgcn_s_barrier()
; template <class Epi>
; __device__ __forceinline__ void gemm_phase(LAS unsigned char* lds, const Gemm g, const StaticOrder& S, const Epi& E) {
;     ...
;             PG8_LDB(B0, 0, 0); PG8_LDB(B1, 0, 1); PG8_SCHED; PG8_LDA(At, 0, 0); PG8_STAGE(PG8_SA(1, 1), a1 + hstepA, voffA);
;             PG8_WAIT_V(8); PG8_WAIT_L(0); PG8_BAR; PG8_MMA(0, 0, At, B0); PG8_MMA(0, 1, At, B1); PG8_BAR; PG8_SCHED;
;             PG8_LDA(At, 0, 1); PG8_STAGE(PG8_SB(0, 0), b2, voffB); PG8_STAGE(PG8_SB(0, 1), b2 + hstepB, voffB); PG8_STAGE(PG8_SA(0, 0), a2, voffA);
;             PG8_WAIT_V(8); PG8_WAIT_L(0); PG8_BAR; PG8_MMA(1, 0, At, B0); PG8_MMA(1, 1, At, B1); PG8_BAR; PG8_SCHED;
;             PG8_LDB(B0, 1, 0); PG8_LDB(B1, 1, 1); PG8_SCHED; PG8_LDA(At, 1, 0); PG8_STAGE(PG8_SA(0, 1), a2 + hstepA, voffA);
;             PG8_WAIT_V(8); PG8_WAIT_L(0); PG8_BAR; PG8_MMA(0, 0, At, B0); PG8_MMA(0, 1, At, B1); PG8_BAR; PG8_SCHED;
;             PG8_LDA(At, 1, 1); PG8_STAGE(PG8_SB(1, 0), b3, voffB); PG8_STAGE(PG8_SB(1, 1), b3 + hstepB, voffB); PG8_STAGE(PG8_SA(1, 0), a3, voffA);
;             PG8_WAIT_V(8); PG8_WAIT_L(0); PG8_BAR; PG8_MMA(1, 0, At, B0); PG8_MMA(1, 1, At, B1); PG8_BAR; PG8_SCHED;
	s_setprio 1
	s_waitcnt lgkmcnt(0)
	v_mfma_f32_16x16x32_bf16 v[60:63], v[146:149], v[198:201], v[60:63]
	v_mfma_f32_16x16x32_bf16 v[56:59], v[170:173], v[198:201], v[56:59]
	v_mfma_f32_16x16x32_bf16 v[52:55], v[146:149], v[206:209], v[52:55]
	v_mfma_f32_16x16x32_bf16 v[44:47], v[170:173], v[206:209], v[44:47]
	v_mfma_f32_16x16x32_bf16 v[36:39], v[146:149], v[214:217], v[36:39]
	v_mfma_f32_16x16x32_bf16 v[28:31], v[170:173], v[214:217], v[28:31]
	v_mfma_f32_16x16x32_bf16 v[20:23], v[146:149], v[222:225], v[20:23]
	v_mfma_f32_16x16x32_bf16 v[12:15], v[170:173], v[222:225], v[12:15]
	v_mfma_f32_16x16x32_bf16 v[60:63], v[166:169], v[202:205], v[60:63]
	v_mfma_f32_16x16x32_bf16 v[56:59], v[178:181], v[202:205], v[56:59]
	v_mfma_f32_16x16x32_bf16 v[52:55], v[166:169], v[210:213], v[52:55]
	v_mfma_f32_16x16x32_bf16 v[44:47], v[178:181], v[210:213], v[44:47]
	v_mfma_f32_16x16x32_bf16 v[36:39], v[166:169], v[218:221], v[36:39]
	v_mfma_f32_16x16x32_bf16 v[28:31], v[178:181], v[218:221], v[28:31]
	v_mfma_f32_16x16x32_bf16 v[20:23], v[166:169], v[226:229], v[20:23]
	v_mfma_f32_16x16x32_bf16 v[12:15], v[178:181], v[226:229], v[12:15]
	s_setprio 0
	s_setprio 1
	v_mfma_f32_16x16x32_bf16 v[48:51], v[182:185], v[198:201], v[48:51]
	v_mfma_f32_16x16x32_bf16 v[40:43], v[190:193], v[198:201], v[40:43]
	v_mfma_f32_16x16x32_bf16 v[32:35], v[182:185], v[206:209], v[32:35]
	v_mfma_f32_16x16x32_bf16 v[24:27], v[190:193], v[206:209], v[24:27]
	v_mfma_f32_16x16x32_bf16 v[16:19], v[182:185], v[214:217], v[16:19]
	v_mfma_f32_16x16x32_bf16 v[8:11], v[190:193], v[214:217], v[8:11]
	v_mfma_f32_16x16x32_bf16 v[4:7], v[182:185], v[222:225], v[4:7]
	v_mfma_f32_16x16x32_bf16 v[0:3], v[190:193], v[222:225], v[0:3]
	v_mfma_f32_16x16x32_bf16 v[48:51], v[186:189], v[202:205], v[48:51]
	v_mfma_f32_16x16x32_bf16 v[40:43], v[194:197], v[202:205], v[40:43]
	v_mfma_f32_16x16x32_bf16 v[32:35], v[186:189], v[210:213], v[32:35]
	v_mfma_f32_16x16x32_bf16 v[24:27], v[194:197], v[210:213], v[24:27]
	v_mfma_f32_16x16x32_bf16 v[16:19], v[186:189], v[218:221], v[16:19]
	v_mfma_f32_16x16x32_bf16 v[8:11], v[194:197], v[218:221], v[8:11]
	v_mfma_f32_16x16x32_bf16 v[4:7], v[186:189], v[226:229], v[4:7]
	v_mfma_f32_16x16x32_bf16 v[0:3], v[194:197], v[226:229], v[0:3]
	s_setprio 0
	s_barrier
	s_add_i32 s88, 0, 0x18000
	v_add_u32_e32 v136, s88, v161
	s_add_i32 s89, 0, 0x1c000
	ds_read_b128 v[146:149], v136
	ds_read_b128 v[166:169], v136 offset:1024
	ds_read_b128 v[170:173], v136 offset:2048
	ds_read_b128 v[178:181], v136 offset:3072
	v_add_u32_e32 v136, s89, v161
	ds_read_b128 v[182:185], v136
	ds_read_b128 v[186:189], v136 offset:1024
	ds_read_b128 v[190:193], v136 offset:2048
	ds_read_b128 v[194:197], v136 offset:3072
	s_add_u32 s12, s12, 0x40000
	s_addc_u32 s13, s13, 0
	s_mov_b32 m0, s57
	v_lshl_add_u64 v[236:237], s[12:13], 0, v[128:129]
	ds_read_b128 v[198:201], v164 offset:32768
	ds_read_b128 v[202:205], v164 offset:33792
	ds_read_b128 v[206:209], v164 offset:34816
	ds_read_b128 v[210:213], v164 offset:35840
	ds_read_b128 v[214:217], v164 offset:36864
	ds_read_b128 v[218:221], v164 offset:37888
	ds_read_b128 v[222:225], v164 offset:38912
	ds_read_b128 v[226:229], v164 offset:39936
	global_load_lds_dwordx4 v[236:237], off
	v_lshl_add_u64 v[236:237], s[12:13], 0, v[132:133]
	s_mov_b32 m0, s59
	s_nop 0
	global_load_lds_dwordx4 v[236:237], off
	s_waitcnt vmcnt(8)
	s_waitcnt lgkmcnt(0)
	s_barrier
	s_setprio 1
	s_waitcnt lgkmcnt(0)
	v_mfma_f32_16x16x32_bf16 v[124:127], v[146:149], v[198:201], v[124:127]
	v_mfma_f32_16x16x32_bf16 v[120:123], v[170:173], v[198:201], v[120:123]
	v_mfma_f32_16x16x32_bf16 v[112:115], v[146:149], v[206:209], v[112:115]
	v_mfma_f32_16x16x32_bf16 v[104:107], v[170:173], v[206:209], v[104:107]
	v_mfma_f32_16x16x32_bf16 v[100:103], v[146:149], v[214:217], v[100:103]
	v_mfma_f32_16x16x32_bf16 v[92:95], v[170:173], v[214:217], v[92:95]
	v_mfma_f32_16x16x32_bf16 v[84:87], v[146:149], v[222:225], v[84:87]
	v_mfma_f32_16x16x32_bf16 v[76:79], v[170:173], v[222:225], v[76:79]
	v_mfma_f32_16x16x32_bf16 v[124:127], v[166:169], v[202:205], v[124:127]
	v_mfma_f32_16x16x32_bf16 v[120:123], v[178:181], v[202:205], v[120:123]
	v_mfma_f32_16x16x32_bf16 v[112:115], v[166:169], v[210:213], v[112:115]
	v_mfma_f32_16x16x32_bf16 v[104:107], v[178:181], v[210:213], v[104:107]
	v_mfma_f32_16x16x32_bf16 v[100:103], v[166:169], v[218:221], v[100:103]
	v_mfma_f32_16x16x32_bf16 v[92:95], v[178:181], v[218:221], v[92:95]
	v_mfma_f32_16x16x32_bf16 v[84:87], v[166:169], v[226:229], v[84:87]
	v_mfma_f32_16x16x32_bf16 v[76:79], v[178:181], v[226:229], v[76:79]
	s_setprio 0
	s_setprio 1
	v_mfma_f32_16x16x32_bf16 v[116:119], v[182:185], v[198:201], v[116:119]
	v_mfma_f32_16x16x32_bf16 v[108:111], v[190:193], v[198:201], v[108:111]
	v_mfma_f32_16x16x32_bf16 v[96:99], v[182:185], v[206:209], v[96:99]
	v_mfma_f32_16x16x32_bf16 v[88:91], v[190:193], v[206:209], v[88:91]
	v_mfma_f32_16x16x32_bf16 v[80:83], v[182:185], v[214:217], v[80:83]
	v_mfma_f32_16x16x32_bf16 v[72:75], v[190:193], v[214:217], v[72:75]
	v_mfma_f32_16x16x32_bf16 v[68:71], v[182:185], v[222:225], v[68:71]
	v_mfma_f32_16x16x32_bf16 v[64:67], v[190:193], v[222:225], v[64:67]
	v_mfma_f32_16x16x32_bf16 v[116:119], v[186:189], v[202:205], v[116:119]
	v_mfma_f32_16x16x32_bf16 v[108:111], v[194:197], v[202:205], v[108:111]
	v_mfma_f32_16x16x32_bf16 v[96:99], v[186:189], v[210:213], v[96:99]
	v_mfma_f32_16x16x32_bf16 v[88:91], v[194:197], v[210:213], v[88:91]
	v_mfma_f32_16x16x32_bf16 v[80:83], v[186:189], v[218:221], v[80:83]
	v_mfma_f32_16x16x32_bf16 v[72:75], v[194:197], v[218:221], v[72:75]
	v_mfma_f32_16x16x32_bf16 v[68:71], v[186:189], v[226:229], v[68:71]
	v_mfma_f32_16x16x32_bf16 v[64:67], v[194:197], v[226:229], v[64:67]
	s_setprio 0
	s_barrier
; #define PG8_STAGE(bufoff, gbase, voff) do { _Pragma("unroll") for (int _i = 0; _i < 2; ++_i) \
;         __builtin_amdgcn_global_load_lds((const unsigned*)((const char*)(gbase) + (voff)[_i]), (LAS unsigned*)(lds + (bufoff) + ldsw + _i * 8192), 16, 0, 0); } while (0)
; #define PG8_LDA(dst, b, h) do { _Pragma("unroll") for (int m = 0; m < 4; ++m) _Pragma("unroll") for (int k = 0; k < 2; ++k) dst[m][k] = *(const LAS bf16x8*)(lds + PG8_SA(b, h) + aoff + m * 2048 + k * 1024); } while (0)
; #define PG8_MMA(ai, bj, At, Bt) do { __builtin_amdgcn_s_setprio(1); _Pragma("unroll") for (int m = 0; m < 4; ++m) _Pragma("unroll") for (int n = 0; n < 2; ++n) _Pragma("unroll") for (int k = 0; k < 2; ++k) \
;         acc[ai][bj][m][n] = __builtin_amdgcn_mfma_f32_16x16x32_bf16(Bt[n][k], At[m][k], acc[ai][bj][m][n], 0, 0, 0); __builtin_amdgcn_s_setprio(0); } while (0)
; #define PG8_WAIT_V(n) asm volatile("s_waitcnt vmcnt(" #n ")" ::: "memory")
; #define PG8_WAIT_L(n) asm volatile("s_waitcnt lgkmcnt(" #n ")" ::: "memory")
; #define PG8_BAR __builtin_amdgcn_s_barrier()
; #define PG8_SCHED __builtin_amdgcn_sched_barrier(0)
; #define EPI_LOAD_RR(ssp) float rr[8]; _Pragma("unroll") for (int it = 0; it < 8; ++it) rr[it] = (ssp)[EPI_IT_ROW(it)]; _Pragma("unroll") for (int it = 0; it < 8; ++it) rr[it] = rms_r(rr[it])
; template <class Epi>
; __device__ __forceinline__ void gemm_phase(LAS unsigned char* lds, const Gemm g, const StaticOrder& S, const Epi& E) {
;     ...
;             PG8_LDA(At, 1, 1); PG8_STAGE(PG8_SB(1, 0), b3, voffB); PG8_STAGE(PG8_SB(1, 1), b3 + hstepB, voffB); PG8_STAGE(PG8_SA(1, 0), a3, voffA);
;             PG8_WAIT_V(8); PG8_WAIT_L(0); PG8_BAR; PG8_MMA(1, 0, At, B0); PG8_MMA(1, 1, At, B1); PG8_BAR; PG8_SCHED;
;         }
;         if (wr == 0) PG8_BAR;
;     __device__ __forceinline__ void operator()(AccRef acc, const Unit& u, int wr, int wc, int fr, int fq) const {
;         asm volatile("" : "+v"(fr), "+v"(fq));
;         const int j0 = u.pn * 128 + wc * 32 + 8 * fq;
;         u32x2 pa[2][2][4][2];
;         { EPI_LOAD_RR(ss);
	s_add_i32 s12, s88, s43
	v_lshl_add_u64 v[174:175], v[174:175], 0, s[34:35]
	s_mov_b32 m0, s12
	ds_read_b128 v[198:201], v164 offset:49152
	ds_read_b128 v[202:205], v164 offset:50176
	ds_read_b128 v[206:209], v164 offset:51200
	ds_read_b128 v[210:213], v164 offset:52224
	ds_read_b128 v[214:217], v164 offset:53248
	ds_read_b128 v[218:221], v164 offset:54272
	ds_read_b128 v[222:225], v164 offset:55296
	ds_read_b128 v[226:229], v164 offset:56320
	global_load_lds_dwordx4 v[174:175], off
	s_add_i32 m0, s12, 0x2000
	s_add_u32 s10, s10, 0x40080
	v_lshl_add_u64 v[174:175], v[230:231], 0, s[34:35]
	s_addc_u32 s11, s11, 0
	s_add_i32 s12, s89, s43
	global_load_lds_dwordx4 v[174:175], off
	v_lshl_add_u64 v[174:175], s[10:11], 0, v[130:131]
	s_mov_b32 m0, s12
	s_nop 0
	global_load_lds_dwordx4 v[174:175], off
	v_lshl_add_u64 v[174:175], s[10:11], 0, v[134:135]
	s_add_i32 m0, s12, 0x2000
	s_nop 0
	global_load_lds_dwordx4 v[174:175], off
	v_lshl_add_u64 v[174:175], v[232:233], 0, s[34:35]
	s_mov_b32 m0, s77
	s_nop 0
	global_load_lds_dwordx4 v[174:175], off
	v_lshl_add_u64 v[174:175], v[234:235], 0, s[34:35]
	s_mov_b32 m0, s78
	s_nop 0
	global_load_lds_dwordx4 v[174:175], off
	s_waitcnt vmcnt(8)
	s_waitcnt lgkmcnt(0)
	s_barrier
	s_setprio 1
	s_waitcnt lgkmcnt(0)
	v_mfma_f32_16x16x32_bf16 v[60:63], v[146:149], v[198:201], v[60:63]
	v_mfma_f32_16x16x32_bf16 v[56:59], v[170:173], v[198:201], v[56:59]
	v_mfma_f32_16x16x32_bf16 v[52:55], v[146:149], v[206:209], v[52:55]
	v_mfma_f32_16x16x32_bf16 v[44:47], v[170:173], v[206:209], v[44:47]
	v_mfma_f32_16x16x32_bf16 v[36:39], v[146:149], v[214:217], v[36:39]
	v_mfma_f32_16x16x32_bf16 v[28:31], v[170:173], v[214:217], v[28:31]
	v_mfma_f32_16x16x32_bf16 v[20:23], v[146:149], v[222:225], v[20:23]
	v_mfma_f32_16x16x32_bf16 v[12:15], v[170:173], v[222:225], v[12:15]
	v_mfma_f32_16x16x32_bf16 v[60:63], v[166:169], v[202:205], v[60:63]
	v_mfma_f32_16x16x32_bf16 v[56:59], v[178:181], v[202:205], v[56:59]
	v_mfma_f32_16x16x32_bf16 v[52:55], v[166:169], v[210:213], v[52:55]
	v_mfma_f32_16x16x32_bf16 v[44:47], v[178:181], v[210:213], v[44:47]
	v_mfma_f32_16x16x32_bf16 v[36:39], v[166:169], v[218:221], v[36:39]
	v_mfma_f32_16x16x32_bf16 v[28:31], v[178:181], v[218:221], v[28:31]
	v_mfma_f32_16x16x32_bf16 v[20:23], v[166:169], v[226:229], v[20:23]
	v_mfma_f32_16x16x32_bf16 v[12:15], v[178:181], v[226:229], v[12:15]
	s_setprio 0
	s_setprio 1
	v_mfma_f32_16x16x32_bf16 v[48:51], v[182:185], v[198:201], v[48:51]
	v_mfma_f32_16x16x32_bf16 v[40:43], v[190:193], v[198:201], v[40:43]
	v_mfma_f32_16x16x32_bf16 v[32:35], v[182:185], v[206:209], v[32:35]
	v_mfma_f32_16x16x32_bf16 v[24:27], v[190:193], v[206:209], v[24:27]
	v_mfma_f32_16x16x32_bf16 v[16:19], v[182:185], v[214:217], v[16:19]
	v_mfma_f32_16x16x32_bf16 v[8:11], v[190:193], v[214:217], v[8:11]
	v_mfma_f32_16x16x32_bf16 v[4:7], v[182:185], v[222:225], v[4:7]
	v_mfma_f32_16x16x32_bf16 v[0:3], v[190:193], v[222:225], v[0:3]
	v_mfma_f32_16x16x32_bf16 v[48:51], v[186:189], v[202:205], v[48:51]
	v_mfma_f32_16x16x32_bf16 v[40:43], v[194:197], v[202:205], v[40:43]
	v_mfma_f32_16x16x32_bf16 v[32:35], v[186:189], v[210:213], v[32:35]
	v_mfma_f32_16x16x32_bf16 v[24:27], v[194:197], v[210:213], v[24:27]
	v_mfma_f32_16x16x32_bf16 v[16:19], v[186:189], v[218:221], v[16:19]
	v_mfma_f32_16x16x32_bf16 v[8:11], v[194:197], v[218:221], v[8:11]
	v_mfma_f32_16x16x32_bf16 v[4:7], v[186:189], v[226:229], v[4:7]
	v_mfma_f32_16x16x32_bf16 v[0:3], v[194:197], v[226:229], v[0:3]
	s_setprio 0
	s_barrier
	s_add_i32 s87, s87, 2
	s_add_u32 s8, s8, 0x100
	s_addc_u32 s9, s9, 0
	s_add_u32 s74, s74, 0x100
	s_addc_u32 s75, s75, 0
	s_cmp_gt_u32 s87, 13
	s_cbranch_scc0 .LBB0_1403
	s_cmp_eq_u64 s[4:5], 0
	s_cselect_b32 s99, 1, 0
	s_and_b64 vcc, exec, s[38:39]
	s_cbranch_vccz .LBB0_1406
	s_barrier
.LBB0_1406:
	s_lshl_b32 s65, s6, 8
	v_mov_b32_e32 v166, v151
	v_mov_b32_e32 v185, v153
	s_add_i32 s65, s65, s63
	s_lshl_b32 s0, s0, 7
	v_add_u32_e32 v146, s65, v166
	v_ashrrev_i32_e32 v147, 31, v146
	v_lshl_add_u64 v[148:149], v[146:147], 2, s[18:19]
	v_mov_b32_e32 v136, v240
	v_add_u32_e32 v148, 16, v146
	v_add_u32_e32 v170, 32, v146
	v_ashrrev_i32_e32 v149, 31, v148
	v_ashrrev_i32_e32 v171, 31, v170
	v_add_u32_e32 v172, 48, v146
	v_add_u32_e32 v174, 0x80, v146
	v_add_u32_e32 v178, 0x90, v146
	v_add_u32_e32 v180, 0xa0, v146
	v_add_u32_e32 v182, 0xb0, v146
	v_lshl_add_u64 v[168:169], v[148:149], 2, s[18:19]
	v_lshl_add_u64 v[170:171], v[170:171], 2, s[18:19]
	v_ashrrev_i32_e32 v173, 31, v172
	v_ashrrev_i32_e32 v175, 31, v174
	v_ashrrev_i32_e32 v179, 31, v178
	v_ashrrev_i32_e32 v181, 31, v180
	v_ashrrev_i32_e32 v183, 31, v182
	v_lshl_add_u64 v[172:173], v[172:173], 2, s[18:19]
	v_lshl_add_u64 v[174:175], v[174:175], 2, s[18:19]
	v_lshl_add_u64 v[178:179], v[178:179], 2, s[18:19]
	v_lshl_add_u64 v[180:181], v[180:181], 2, s[18:19]
	v_lshl_add_u64 v[182:183], v[182:183], 2, s[18:19]
	v_mov_b32_e32 v147, v241
	v_mov_b32_e32 v149, v242
	v_mov_b32_e32 v150, v243
	v_mov_b32_e32 v152, v244
	v_mov_b32_e32 v167, v245
	s_nop 0
	v_mov_b32_e32 v169, v246
	v_mov_b32_e32 v170, v247
	s_or_b32 s0, s0, s76
	s_nop 0
	v_fmamk_f32 v136, v136, 0x3a800000, v165
	v_rsq_f32_e32 v168, v136
	v_fmamk_f32 v136, v147, 0x3a800000, v165
	v_fmamk_f32 v147, v149, 0x3a800000, v165
	v_fmamk_f32 v149, v150, 0x3a800000, v165
	v_fmamk_f32 v150, v152, 0x3a800000, v165
	v_fmamk_f32 v152, v167, 0x3a800000, v165
	v_fmamk_f32 v167, v169, 0x3a800000, v165
	v_fmamk_f32 v169, v170, 0x3a800000, v165
	v_rsq_f32_e32 v170, v136
	v_rsq_f32_e32 v180, v147
	v_rsq_f32_e32 v184, v150
	v_rsq_f32_e32 v150, v167
	v_rsq_f32_e32 v182, v149
	v_rsq_f32_e32 v152, v152
; __device__ __forceinline__ u32x2 pack4(f32x4 v) { return (u32x2){pk2(v[0], v[1]), pk2(v[2], v[3])}; }
; #define EPI_LOAD_RR(ssp) float rr[8]; _Pragma("unroll") for (int it = 0; it < 8; ++it) rr[it] = (ssp)[EPI_IT_ROW(it)]; _Pragma("unroll") for (int it = 0; it < 8; ++it) rr[it] = rms_r(rr[it])
;     __device__ __forceinline__ void operator()(AccRef acc, const Unit& u, int wr, int wc, int fr, int fq) const {
;     ...
;         { EPI_LOAD_RR(ss);
; #pragma unroll
;           for (int it = 0; it < 8; ++it)
; #pragma unroll
;               for (int bj = 0; bj < 2; ++bj)
; #pragma unroll
;                   for (int n = 0; n < 2; ++n) pa[it >> 2][bj][it & 3][n] = pack4(acc[it >> 2][bj][it & 3][n] * rr[it]); }
	v_rsq_f32_e32 v136, v169
	v_pk_mul_f32 v[108:109], v[108:109], v[168:169] op_sel_hi:[1,0]
	v_pk_mul_f32 v[122:123], v[122:123], v[168:169] op_sel_hi:[1,0]
	v_pk_mul_f32 v[116:117], v[116:117], v[168:169] op_sel_hi:[1,0]
	v_pk_mul_f32 v[110:111], v[110:111], v[168:169] op_sel_hi:[1,0]
	v_cvt_pk_bf16_f32 v171, v122, v123
	v_cvt_pk_bf16_f32 v181, v116, v117
	v_cvt_pk_bf16_f32 v173, v108, v109
	v_pk_mul_f32 v[42:43], v[42:43], v[184:185] op_sel_hi:[1,0]
	v_pk_mul_f32 v[108:109], v[114:115], v[170:171] op_sel_hi:[1,0]
	v_pk_mul_f32 v[104:105], v[104:105], v[170:171] op_sel_hi:[1,0]
	v_pk_mul_f32 v[80:81], v[80:81], v[180:181] op_sel_hi:[1,0]
	v_pk_mul_f32 v[72:73], v[72:73], v[180:181] op_sel_hi:[1,0]
	v_pk_mul_f32 v[10:11], v[10:11], v[150:151] op_sel_hi:[1,0]
	v_pk_mul_f32 v[8:9], v[8:9], v[150:151] op_sel_hi:[1,0]
	v_pk_mul_f32 v[118:119], v[118:119], v[168:169] op_sel_hi:[1,0]
	v_cvt_pk_bf16_f32 v174, v110, v111
	v_pk_mul_f32 v[110:111], v[112:113], v[170:171] op_sel_hi:[1,0]
	v_cvt_pk_bf16_f32 v183, v118, v119
	v_pk_mul_f32 v[106:107], v[106:107], v[170:171] op_sel_hi:[1,0]
	v_pk_mul_f32 v[98:99], v[98:99], v[170:171] op_sel_hi:[1,0]
	v_pk_mul_f32 v[96:97], v[96:97], v[170:171] op_sel_hi:[1,0]
	v_pk_mul_f32 v[90:91], v[90:91], v[170:171] op_sel_hi:[1,0]
	v_pk_mul_f32 v[88:89], v[88:89], v[170:171] op_sel_hi:[1,0]
	v_pk_mul_f32 v[112:113], v[94:95], v[180:181] op_sel_hi:[1,0]
	v_pk_mul_f32 v[114:115], v[92:93], v[180:181] op_sel_hi:[1,0]
	v_cvt_pk_bf16_f32 v93, v108, v109
	v_cvt_pk_bf16_f32 v170, v104, v105
	v_pk_mul_f32 v[82:83], v[82:83], v[180:181] op_sel_hi:[1,0]
	v_cvt_pk_bf16_f32 v95, v80, v81
	v_pk_mul_f32 v[74:75], v[74:75], v[180:181] op_sel_hi:[1,0]
	v_cvt_pk_bf16_f32 v80, v72, v73
	v_pk_mul_f32 v[72:73], v[86:87], v[182:183] op_sel_hi:[1,0]
	v_pk_mul_f32 v[40:41], v[40:41], v[184:185] op_sel_hi:[1,0]
	v_cvt_pk_bf16_f32 v105, v42, v43
	v_pk_mul_f32 v[42:43], v[52:53], v[152:153] op_sel_hi:[1,0]
	v_pk_mul_f32 v[26:27], v[26:27], v[152:153] op_sel_hi:[1,0]
	v_pk_mul_f32 v[24:25], v[24:25], v[152:153] op_sel_hi:[1,0]
	v_cvt_pk_bf16_f32 v108, v8, v9
	v_cvt_pk_bf16_f32 v109, v10, v11
	v_pk_mul_f32 v[8:9], v[22:23], v[136:137] op_sel_hi:[1,0]
	v_pk_mul_f32 v[10:11], v[20:21], v[136:137] op_sel_hi:[1,0]
	v_pk_mul_f32 v[126:127], v[126:127], v[168:169] op_sel_hi:[1,0]
	v_pk_mul_f32 v[124:125], v[124:125], v[168:169] op_sel_hi:[1,0]
	v_pk_mul_f32 v[120:121], v[120:121], v[168:169] op_sel_hi:[1,0]
	v_pk_mul_f32 v[102:103], v[102:103], v[180:181] op_sel_hi:[1,0]
	v_pk_mul_f32 v[100:101], v[100:101], v[180:181] op_sel_hi:[1,0]
	v_cvt_pk_bf16_f32 v169, v106, v107
	v_cvt_pk_bf16_f32 v168, v112, v113
	v_cvt_pk_bf16_f32 v178, v82, v83
	v_cvt_pk_bf16_f32 v81, v74, v75
	v_pk_mul_f32 v[74:75], v[84:85], v[182:183] op_sel_hi:[1,0]
	v_cvt_pk_bf16_f32 v83, v72, v73
	v_pk_mul_f32 v[72:73], v[78:79], v[182:183] op_sel_hi:[1,0]
	v_pk_mul_f32 v[50:51], v[50:51], v[184:185] op_sel_hi:[1,0]
	v_pk_mul_f32 v[48:49], v[48:49], v[184:185] op_sel_hi:[1,0]
	v_cvt_pk_bf16_f32 v104, v40, v41
	v_pk_mul_f32 v[40:41], v[54:55], v[152:153] op_sel_hi:[1,0]
	v_cvt_pk_bf16_f32 v116, v42, v43
	v_pk_mul_f32 v[42:43], v[44:45], v[152:153] op_sel_hi:[1,0]
	v_cvt_pk_bf16_f32 v106, v24, v25
	v_cvt_pk_bf16_f32 v107, v26, v27
	v_pk_mul_f32 v[24:25], v[38:39], v[150:151] op_sel_hi:[1,0]
	v_pk_mul_f32 v[26:27], v[36:37], v[150:151] op_sel_hi:[1,0]
	v_cvt_pk_bf16_f32 v112, v10, v11
	v_cvt_pk_bf16_f32 v113, v8, v9
	v_pk_mul_f32 v[8:9], v[14:15], v[136:137] op_sel_hi:[1,0]
	v_pk_mul_f32 v[10:11], v[12:13], v[136:137] op_sel_hi:[1,0]
	v_pk_mul_f32 v[6:7], v[6:7], v[136:137] op_sel_hi:[1,0]
	v_pk_mul_f32 v[4:5], v[4:5], v[136:137] op_sel_hi:[1,0]
	v_pk_mul_f32 v[2:3], v[2:3], v[136:137] op_sel_hi:[1,0]
	v_pk_mul_f32 v[0:1], v[0:1], v[136:137] op_sel_hi:[1,0]
	v_lshl_add_u32 v44, v185, 3, s0
	v_cvt_pk_bf16_f32 v190, v124, v125
	v_cvt_pk_bf16_f32 v189, v126, v127
; __device__ __forceinline__ f32x4 ror1v(f32x4 v) { return (f32x4){dpp_ror1(v[0]), dpp_ror1(v[1]), dpp_ror1(v[2]), dpp_ror1(v[3])}; }
; __device__ __forceinline__ f32x4 ror2v(f32x4 v) { return (f32x4){dpp_ror2(v[0]), dpp_ror2(v[1]), dpp_ror2(v[2]), dpp_ror2(v[3])}; }
; __device__ __forceinline__ u32x2 pack4(f32x4 v) { return (u32x2){pk2(v[0], v[1]), pk2(v[2], v[3])}; }
; __device__ __forceinline__ f32x4 unpack4(u32x2 w) { return (f32x4){bflo(w.x), bfhi(w.x), bflo(w.y), bfhi(w.y)}; }
;     __device__ __forceinline__ void operator()(AccRef acc, const Unit& u, int wr, int wc, int fr, int fq) const {
;     ...
;                   for (int n = 0; n < 2; ++n) pa[it >> 2][bj][it & 3][n] = pack4(acc[it >> 2][bj][it & 3][n] * rr[it]); }
;         __builtin_amdgcn_sched_barrier(0);
; #pragma unroll
;         for (int ai = 0; ai < 2; ++ai) {
;             const int rowg = u.pm * 256 + ai * 128 + wr * 64; const int grp = rowg >> 6;
; #pragma unroll
;             for (int n = 0; n < 2; ++n) { const unsigned jn = (unsigned)(j0 + 4 * n);
;                 f32x4 cu[4];
;                 {
;                     const f32x4 wu0 = *(const f32x4*)(cw + (DFF + jn)), wu1 = *(const f32x4*)(cw + (UPN + DFF + jn)), wu2 = *(const f32x4*)(cw + (2 * UPN + DFF + jn)), bu = *(const f32x4*)(cb + (DFF + jn));
;                     f32x4 pu1 = (f32x4){0.f, 0.f, 0.f, 0.f}, pu2 = pu1;
; #pragma unroll
;                     for (int m = 0; m < 4; ++m) {
;                         const f32x4 au = unpack4(pa[ai][1][m][n]);
;                         const f32x4 ru1 = ror1v(au), ru2 = ror2v(au);
;                         const f32x4 u1 = fr >= 1 ? ru1 : pu1, u2 = fr >= 2 ? ru2 : pu2;
;                         if (m == 0 && fr < 2) *(f32x4*)(edge + (unsigned)((grp * 4 + fr) * UPN + DFF + jn)) = au;
	v_cvt_pk_bf16_f32 v172, v120, v121
	v_cvt_pk_bf16_f32 v94, v110, v111
	v_cvt_pk_bf16_f32 v179, v96, v97
	v_cvt_pk_bf16_f32 v177, v98, v99
	v_cvt_pk_bf16_f32 v89, v88, v89
	v_cvt_pk_bf16_f32 v88, v90, v91
	v_cvt_pk_bf16_f32 v92, v100, v101
	v_cvt_pk_bf16_f32 v91, v102, v103
	v_cvt_pk_bf16_f32 v167, v114, v115
	v_cvt_pk_bf16_f32 v82, v74, v75
	v_pk_mul_f32 v[74:75], v[76:77], v[182:183] op_sel_hi:[1,0]
	v_cvt_pk_bf16_f32 v149, v72, v73
	v_pk_mul_f32 v[72:73], v[70:71], v[182:183] op_sel_hi:[1,0]
	v_cvt_pk_bf16_f32 v147, v74, v75
	v_pk_mul_f32 v[68:69], v[68:69], v[182:183] op_sel_hi:[1,0]
	v_cvt_pk_bf16_f32 v71, v72, v73
	v_pk_mul_f32 v[66:67], v[66:67], v[182:183] op_sel_hi:[1,0]
	v_cvt_pk_bf16_f32 v70, v68, v69
	v_pk_mul_f32 v[64:65], v[64:65], v[182:183] op_sel_hi:[1,0]
	v_cvt_pk_bf16_f32 v79, v66, v67
	v_pk_mul_f32 v[62:63], v[62:63], v[184:185] op_sel_hi:[1,0]
	v_cvt_pk_bf16_f32 v78, v64, v65
	v_pk_mul_f32 v[60:61], v[60:61], v[184:185] op_sel_hi:[1,0]
	v_cvt_pk_bf16_f32 v119, v62, v63
	v_pk_mul_f32 v[58:59], v[58:59], v[184:185] op_sel_hi:[1,0]
	v_cvt_pk_bf16_f32 v118, v60, v61
	v_pk_mul_f32 v[56:57], v[56:57], v[184:185] op_sel_hi:[1,0]
	v_cvt_pk_bf16_f32 v103, v58, v59
	v_cvt_pk_bf16_f32 v120, v48, v49
	v_cvt_pk_bf16_f32 v121, v50, v51
	v_cvt_pk_bf16_f32 v117, v40, v41
	v_pk_mul_f32 v[40:41], v[46:47], v[152:153] op_sel_hi:[1,0]
	v_cvt_pk_bf16_f32 v102, v56, v57
	v_cvt_pk_bf16_f32 v100, v42, v43
	v_pk_mul_f32 v[34:35], v[34:35], v[152:153] op_sel_hi:[1,0]
	v_cvt_pk_bf16_f32 v101, v40, v41
	v_pk_mul_f32 v[32:33], v[32:33], v[152:153] op_sel_hi:[1,0]
	v_cvt_pk_bf16_f32 v123, v34, v35
	v_cvt_pk_bf16_f32 v114, v26, v27
	v_cvt_pk_bf16_f32 v115, v24, v25
	v_pk_mul_f32 v[24:25], v[30:31], v[150:151] op_sel_hi:[1,0]
	v_cvt_pk_bf16_f32 v122, v32, v33
	v_pk_mul_f32 v[26:27], v[28:29], v[150:151] op_sel_hi:[1,0]
	v_cvt_pk_bf16_f32 v99, v24, v25
	v_pk_mul_f32 v[18:19], v[18:19], v[150:151] op_sel_hi:[1,0]
	v_cvt_pk_bf16_f32 v98, v26, v27
	v_pk_mul_f32 v[16:17], v[16:17], v[150:151] op_sel_hi:[1,0]
	v_cvt_pk_bf16_f32 v125, v18, v19
	v_cvt_pk_bf16_f32 v96, v10, v11
	v_cvt_pk_bf16_f32 v97, v8, v9
	v_cvt_pk_bf16_f32 v126, v4, v5
	v_cvt_pk_bf16_f32 v127, v6, v7
	s_nop 0
	v_cvt_pk_bf16_f32 v124, v16, v17
	v_cvt_pk_bf16_f32 v110, v0, v1
	v_cvt_pk_bf16_f32 v111, v2, v3
	v_add_u32_e32 v136, 0xb00, v44
	v_lshlrev_b64 v[12:13], 2, v[136:137]
	v_add_u32_e32 v136, 0x2100, v44
	v_lshl_add_u64 v[50:51], v[136:137], 2, s[20:21]
	v_add_u32_e32 v136, 0x3700, v44
	v_lshl_add_u64 v[48:49], s[20:21], 0, v[12:13]
	v_lshl_add_u64 v[52:53], v[136:137], 2, s[20:21]
	v_lshl_add_u64 v[54:55], s[22:23], 0, v[12:13]
	global_load_dwordx4 v[8:11], v[48:49], off
	global_load_dwordx4 v[0:3], v[50:51], off
	global_load_dwordx4 v[4:7], v[52:53], off
	global_load_dwordx4 v[12:15], v[54:55], off
	s_ashr_i32 s6, s65, 4
	v_add_u32_e32 v16, s6, v166
	v_mul_lo_u32 v175, v16, s85
	v_lshlrev_b32_e32 v36, 16, v181
	v_and_b32_e32 v37, 0xffff0000, v181
	v_lshlrev_b32_e32 v38, 16, v183
	v_and_b32_e32 v39, 0xffff0000, v183
	s_nop 1
	v_cmp_lt_i32_e64 s[10:11], 1, v166
	v_cmp_gt_i32_e64 s[12:13], 2, v166
	v_add_u32_e32 v84, 0xb00, v175
	v_mov_b32_dpp v191, v36 row_ror:1 row_mask:0xf bank_mask:0xf
	v_mov_b32_dpp v194, v37 row_ror:1 row_mask:0xf bank_mask:0xf
	v_mov_b32_dpp v192, v38 row_ror:1 row_mask:0xf bank_mask:0xf
	v_mov_b32_dpp v196, v39 row_ror:1 row_mask:0xf bank_mask:0xf
	v_mov_b32_dpp v193, v36 row_ror:2 row_mask:0xf bank_mask:0xf
	v_mov_b32_dpp v197, v37 row_ror:2 row_mask:0xf bank_mask:0xf
	v_mov_b32_dpp v201, v38 row_ror:2 row_mask:0xf bank_mask:0xf
	v_mov_b32_dpp v204, v39 row_ror:2 row_mask:0xf bank_mask:0xf
	s_and_saveexec_b64 s[0:1], s[12:13]
	s_cbranch_execz .LBB0_1408
	v_add_u32_e32 v136, v84, v44
	v_lshl_add_u64 v[16:17], v[136:137], 2, s[28:29]
	s_cmp_lg_u32 s99, 0
	s_cbranch_scc1 .Lwt1403_35630
	global_store_dwordx4 v[16:17], v[36:39], off
	s_branch .Lwj1403_35630

; __device__ __forceinline__ f32x4 ror1v(f32x4 v) { return (f32x4){dpp_ror1(v[0]), dpp_ror1(v[1]), dpp_ror1(v[2]), dpp_ror1(v[3])}; }
; __device__ __forceinline__ f32x4 ror2v(f32x4 v) { return (f32x4){dpp_ror2(v[0]), dpp_ror2(v[1]), dpp_ror2(v[2]), dpp_ror2(v[3])}; }
; __device__ __forceinline__ f32x4 unpack4(u32x2 w) { return (f32x4){bflo(w.x), bfhi(w.x), bflo(w.y), bfhi(w.y)}; }
;     __device__ __forceinline__ void operator()(AccRef acc, const Unit& u, int wr, int wc, int fr, int fq) const {
;     ...
;                     for (int m = 0; m < 4; ++m) {
;                         const f32x4 au = unpack4(pa[ai][1][m][n]);
;                         const f32x4 ru1 = ror1v(au), ru2 = ror2v(au);
;                         const f32x4 u1 = fr >= 1 ? ru1 : pu1, u2 = fr >= 2 ? ru2 : pu2;
;                         if (m == 0 && fr < 2) *(f32x4*)(edge + (unsigned)((grp * 4 + fr) * UPN + DFF + jn)) = au;
;                         if (m == 3 && fr >= 14) *(f32x4*)(edge + (unsigned)((grp * 4 + (fr - 12)) * UPN + DFF + jn)) = au;
;                         cu[m] = bu + wu0 * u2 + wu1 * u1 + wu2 * au;
;                         pu1 = ru1; pu2 = ru2; }
;                 }
;                 {
;                     const f32x4 wg0 = *(const f32x4*)(cw + jn), wg1 = *(const f32x4*)(cw + (UPN + jn)), wg2 = *(const f32x4*)(cw + (2 * UPN + jn)), bg = *(const f32x4*)(cb + jn);
;                     f32x4 pg1 = (f32x4){0.f, 0.f, 0.f, 0.f}, pg2 = pg1;
; #pragma unroll
;                     for (int m = 0; m < 4; ++m) { const int row = rowg + m * 16 + fr;
;                         const f32x4 ag = unpack4(pa[ai][0][m][n]);
;                         const f32x4 rg1 = ror1v(ag), rg2 = ror2v(ag);
;                         const f32x4 g1 = fr >= 1 ? rg1 : pg1, g2 = fr >= 2 ? rg2 : pg2;
;                         if (m == 0 && fr < 2) *(f32x4*)(edge + (unsigned)((grp * 4 + fr) * UPN + jn)) = ag;
;                         if (m == 3 && fr >= 14) *(f32x4*)(edge + (unsigned)((grp * 4 + (fr - 12)) * UPN + jn)) = ag;
.Lwj1403_35630:
.LBB0_1408:
	s_or_b64 exec, exec, s[0:1]
	v_add_u32_e32 v150, -12, v166
	v_add_u32_e32 v16, s6, v150
	v_mul_lo_u32 v152, v16, s85
	v_lshlrev_b32_e32 v68, 16, v179
	v_and_b32_e32 v69, 0xffff0000, v179
	v_lshlrev_b32_e32 v66, 16, v177
	v_and_b32_e32 v67, 0xffff0000, v177
	s_nop 1
	v_lshlrev_b32_e32 v60, 16, v95
	v_and_b32_e32 v61, 0xffff0000, v95
	v_lshlrev_b32_e32 v46, 16, v178
	v_and_b32_e32 v47, 0xffff0000, v178
	s_nop 1
	v_lshlrev_b32_e32 v16, 16, v70
	v_and_b32_e32 v17, 0xffff0000, v70
	v_lshlrev_b32_e32 v18, 16, v71
	v_and_b32_e32 v19, 0xffff0000, v71
	s_nop 1
	v_cmp_lt_i32_e32 vcc, 13, v166
	v_add_u32_e32 v90, 0xb00, v152
	v_mov_b32_dpp v195, v68 row_ror:1 row_mask:0xf bank_mask:0xf
	v_mov_b32_dpp v200, v69 row_ror:1 row_mask:0xf bank_mask:0xf
	v_mov_b32_dpp v198, v66 row_ror:1 row_mask:0xf bank_mask:0xf
	v_mov_b32_dpp v202, v67 row_ror:1 row_mask:0xf bank_mask:0xf
	v_mov_b32_dpp v199, v68 row_ror:2 row_mask:0xf bank_mask:0xf
	v_mov_b32_dpp v203, v69 row_ror:2 row_mask:0xf bank_mask:0xf
	v_mov_b32_dpp v205, v66 row_ror:2 row_mask:0xf bank_mask:0xf
	v_mov_b32_dpp v206, v67 row_ror:2 row_mask:0xf bank_mask:0xf
	v_mov_b32_dpp v85, v60 row_ror:1 row_mask:0xf bank_mask:0xf
	v_mov_b32_dpp v95, v61 row_ror:1 row_mask:0xf bank_mask:0xf
	v_mov_b32_dpp v86, v46 row_ror:1 row_mask:0xf bank_mask:0xf
	v_mov_b32_dpp v177, v47 row_ror:1 row_mask:0xf bank_mask:0xf
	v_mov_b32_dpp v87, v60 row_ror:2 row_mask:0xf bank_mask:0xf
	v_mov_b32_dpp v178, v61 row_ror:2 row_mask:0xf bank_mask:0xf
	v_mov_b32_dpp v179, v46 row_ror:2 row_mask:0xf bank_mask:0xf
	v_mov_b32_dpp v180, v47 row_ror:2 row_mask:0xf bank_mask:0xf
	v_mov_b32_dpp v181, v16 row_ror:1 row_mask:0xf bank_mask:0xf
	v_mov_b32_dpp v184, v17 row_ror:1 row_mask:0xf bank_mask:0xf
	v_mov_b32_dpp v182, v18 row_ror:1 row_mask:0xf bank_mask:0xf
	v_mov_b32_dpp v185, v19 row_ror:1 row_mask:0xf bank_mask:0xf
	v_mov_b32_dpp v183, v16 row_ror:2 row_mask:0xf bank_mask:0xf
	v_mov_b32_dpp v186, v17 row_ror:2 row_mask:0xf bank_mask:0xf
	v_mov_b32_dpp v187, v18 row_ror:2 row_mask:0xf bank_mask:0xf
	v_mov_b32_dpp v188, v19 row_ror:2 row_mask:0xf bank_mask:0xf
	s_and_saveexec_b64 s[0:1], vcc
	s_cbranch_execz .LBB0_1410
	v_add_u32_e32 v136, v90, v44
	v_lshl_add_u64 v[20:21], v[136:137], 2, s[28:29]
	s_cmp_lg_u32 s99, 0
	s_cbranch_scc1 .Lwt1403_35682
	global_store_dwordx4 v[20:21], v[16:19], off
	s_branch .Lwj1403_35682

; __device__ __forceinline__ f32x4 gelu4(f32x4 v) { const f32x2 a = gelu_pk((f32x2){v[0], v[1]}), b = gelu_pk((f32x2){v[2], v[3]}); return (f32x4){a.x, a.y, b.x, b.y}; }
; __device__ __forceinline__ f32x4 ror1v(f32x4 v) { return (f32x4){dpp_ror1(v[0]), dpp_ror1(v[1]), dpp_ror1(v[2]), dpp_ror1(v[3])}; }
; __device__ __forceinline__ f32x4 ror2v(f32x4 v) { return (f32x4){dpp_ror2(v[0]), dpp_ror2(v[1]), dpp_ror2(v[2]), dpp_ror2(v[3])}; }
; __device__ __forceinline__ u32x2 pack4(f32x4 v) { return (u32x2){pk2(v[0], v[1]), pk2(v[2], v[3])}; }
; __device__ __forceinline__ f32x4 unpack4(u32x2 w) { return (f32x4){bflo(w.x), bfhi(w.x), bflo(w.y), bfhi(w.y)}; }
;     __device__ __forceinline__ void operator()(AccRef acc, const Unit& u, int wr, int wc, int fr, int fq) const {
;     ...
;                 {
;                     const f32x4 wg0 = *(const f32x4*)(cw + jn), wg1 = *(const f32x4*)(cw + (UPN + jn)), wg2 = *(const f32x4*)(cw + (2 * UPN + jn)), bg = *(const f32x4*)(cb + jn);
;                     f32x4 pg1 = (f32x4){0.f, 0.f, 0.f, 0.f}, pg2 = pg1;
; #pragma unroll
;                     for (int m = 0; m < 4; ++m) { const int row = rowg + m * 16 + fr;
;                         const f32x4 ag = unpack4(pa[ai][0][m][n]);
;                         const f32x4 rg1 = ror1v(ag), rg2 = ror2v(ag);
;                         const f32x4 g1 = fr >= 1 ? rg1 : pg1, g2 = fr >= 2 ? rg2 : pg2;
;                         if (m == 0 && fr < 2) *(f32x4*)(edge + (unsigned)((grp * 4 + fr) * UPN + jn)) = ag;
;                         if (m == 3 && fr >= 14) *(f32x4*)(edge + (unsigned)((grp * 4 + (fr - 12)) * UPN + jn)) = ag;
;                         const f32x4 o = gelu4(bg + wg0 * g2 + wg1 * g1 + wg2 * ag) * cu[m];
;                         if (!(m == 0 && fr < 2)) *(u32x2*)(act + (unsigned)(row * DFF + jn)) = pack4(o);
;                         pg1 = rg1; pg2 = rg2; }
.Lwj1403_35682:
.LBB0_1410:
	s_or_b64 exec, exec, s[0:1]
	v_mov_b32_e32 v45, v137
	v_add_u32_e32 v136, 0x1600, v44
	v_lshlrev_b64 v[32:33], 2, v[44:45]
	v_lshl_add_u64 v[58:59], v[136:137], 2, s[20:21]
	v_add_u32_e32 v136, 0x2c00, v44
	v_lshl_add_u64 v[56:57], s[20:21], 0, v[32:33]
	v_lshl_add_u64 v[62:63], v[136:137], 2, s[20:21]
	v_lshl_add_u64 v[64:65], s[22:23], 0, v[32:33]
	global_load_dwordx4 v[28:31], v[56:57], off
	global_load_dwordx4 v[20:23], v[58:59], off
	global_load_dwordx4 v[24:27], v[62:63], off
	global_load_dwordx4 v[32:35], v[64:65], off
	v_lshlrev_b32_e32 v40, 16, v190
	v_and_b32_e32 v41, 0xffff0000, v190
	v_lshlrev_b32_e32 v42, 16, v189
	v_and_b32_e32 v43, 0xffff0000, v189
	s_nop 1
	v_cmp_lt_i32_e64 s[8:9], 0, v166
	v_cmp_lt_i32_e64 s[6:7], 1, v166
	v_mov_b32_dpp v70, v40 row_ror:1 row_mask:0xf bank_mask:0xf
	v_mov_b32_dpp v71, v41 row_ror:1 row_mask:0xf bank_mask:0xf
	v_mov_b32_dpp v72, v42 row_ror:1 row_mask:0xf bank_mask:0xf
	v_mov_b32_dpp v73, v43 row_ror:1 row_mask:0xf bank_mask:0xf
	v_mov_b32_dpp v74, v40 row_ror:2 row_mask:0xf bank_mask:0xf
	v_mov_b32_dpp v75, v41 row_ror:2 row_mask:0xf bank_mask:0xf
	v_mov_b32_dpp v76, v42 row_ror:2 row_mask:0xf bank_mask:0xf
	v_mov_b32_dpp v77, v43 row_ror:2 row_mask:0xf bank_mask:0xf
	s_and_saveexec_b64 s[0:1], s[10:11]
	s_xor_b64 s[74:75], exec, s[0:1]
	s_cbranch_execz .LBB0_1412
	v_cndmask_b32_e64 v213, 0, v204, s[6:7]
	v_cndmask_b32_e64 v212, 0, v201, s[6:7]
	v_cndmask_b32_e64 v211, 0, v196, s[8:9]
	v_cndmask_b32_e64 v210, 0, v192, s[8:9]
	s_waitcnt vmcnt(4)
	v_pk_fma_f32 v[212:213], v[10:11], v[212:213], v[14:15]
	v_cndmask_b32_e64 v215, 0, v197, s[6:7]
	v_pk_fma_f32 v[210:211], v[2:3], v[210:211], v[212:213]
	v_cndmask_b32_e64 v214, 0, v193, s[6:7]
	v_pk_fma_f32 v[38:39], v[6:7], v[38:39], v[210:211]
	s_waitcnt vmcnt(0)
	v_pk_fma_f32 v[210:211], v[28:29], v[74:75], v[32:33]
	v_cndmask_b32_e64 v209, 0, v194, s[8:9]
	v_pk_fma_f32 v[210:211], v[20:21], v[70:71], v[210:211]
	v_cndmask_b32_e64 v208, 0, v191, s[8:9]
	v_pk_fma_f32 v[40:41], v[24:25], v[40:41], v[210:211]
	v_pk_fma_f32 v[214:215], v[8:9], v[214:215], v[12:13]
	v_and_b32_e32 v213, 0x7fffffff, v41
	v_and_b32_e32 v212, 0x7fffffff, v40
	v_pk_fma_f32 v[212:213], v[212:213], s[52:53], 1.0 op_sel_hi:[1,0,0]
	v_pk_fma_f32 v[208:209], v[0:1], v[208:209], v[214:215]
	v_rcp_f32_e32 v212, v212
	v_rcp_f32_e32 v213, v213
	v_pk_mul_f32 v[210:211], v[40:41], v[40:41]
	v_mov_b64_e32 v[214:215], s[56:57]
	v_pk_mul_f32 v[210:211], v[210:211], s[42:43] op_sel_hi:[1,0]
	v_pk_fma_f32 v[216:217], v[212:213], s[54:55], v[214:215] op_sel_hi:[1,0,0]
	v_exp_f32_e32 v210, v210
	v_exp_f32_e32 v211, v211
	v_pk_fma_f32 v[216:217], v[212:213], v[216:217], s[58:59] op_sel_hi:[1,1,0]
	v_pk_fma_f32 v[36:37], v[4:5], v[36:37], v[208:209]
	v_pk_fma_f32 v[216:217], v[212:213], v[216:217], s[60:61] op_sel_hi:[1,1,0]
	v_pk_fma_f32 v[208:209], v[30:31], v[76:77], v[34:35]
	v_pk_fma_f32 v[216:217], v[212:213], v[216:217], s[62:63] op_sel_hi:[1,1,0]
	v_pk_fma_f32 v[208:209], v[22:23], v[72:73], v[208:209]
	v_pk_mul_f32 v[212:213], v[212:213], v[216:217]
	v_cmp_gt_f32_e64 s[0:1], 0, v40
	v_pk_mul_f32 v[210:211], v[210:211], v[212:213]
	v_pk_fma_f32 v[42:43], v[26:27], v[42:43], v[208:209]
	v_pk_mul_f32 v[212:213], v[40:41], v[210:211]
	v_pk_fma_f32 v[210:211], v[40:41], v[210:211], v[40:41] neg_lo:[1,0,0] neg_hi:[1,0,0]
	v_pk_mul_f32 v[208:209], v[42:43], v[42:43]
	v_cndmask_b32_e64 v40, v210, v212, s[0:1]
	v_cmp_gt_f32_e64 s[0:1], 0, v41
	v_and_b32_e32 v210, 0x7fffffff, v42
	v_pk_mul_f32 v[208:209], v[208:209], s[42:43] op_sel_hi:[1,0]
	v_cndmask_b32_e64 v41, v211, v213, s[0:1]
	v_and_b32_e32 v211, 0x7fffffff, v43
	v_pk_fma_f32 v[210:211], v[210:211], s[52:53], 1.0 op_sel_hi:[1,0,0]
	v_exp_f32_e32 v208, v208
	v_rcp_f32_e32 v210, v210
	v_rcp_f32_e32 v211, v211
	v_exp_f32_e32 v209, v209
	v_cmp_gt_f32_e64 s[0:1], 0, v42
	v_pk_mul_f32 v[36:37], v[36:37], v[40:41]
	v_pk_fma_f32 v[212:213], v[210:211], s[54:55], v[214:215] op_sel_hi:[1,0,0]
	v_cvt_pk_bf16_f32 v36, v36, v37
	s_nop 0
	v_pk_fma_f32 v[212:213], v[210:211], v[212:213], s[58:59] op_sel_hi:[1,1,0]
	s_nop 0
	v_pk_fma_f32 v[212:213], v[210:211], v[212:213], s[60:61] op_sel_hi:[1,1,0]
	s_nop 0
	v_pk_fma_f32 v[212:213], v[210:211], v[212:213], s[62:63] op_sel_hi:[1,1,0]
	s_nop 0
	v_pk_mul_f32 v[210:211], v[210:211], v[212:213]
	s_nop 0
	v_pk_mul_f32 v[208:209], v[208:209], v[210:211]
	s_nop 0
	v_pk_mul_f32 v[210:211], v[42:43], v[208:209]
	v_pk_fma_f32 v[208:209], v[42:43], v[208:209], v[42:43] neg_lo:[1,0,0] neg_hi:[1,0,0]
	s_nop 0
	v_cndmask_b32_e64 v42, v208, v210, s[0:1]
	v_cmp_gt_f32_e64 s[0:1], 0, v43
	s_nop 1
	v_cndmask_b32_e64 v43, v209, v211, s[0:1]
	v_pk_mul_f32 v[38:39], v[38:39], v[42:43]
	s_nop 0
	v_cvt_pk_bf16_f32 v37, v38, v39
	v_mad_u64_u32 v[38:39], s[0:1], v146, s86, v[44:45]
	v_mov_b32_e32 v39, v137
	v_lshl_add_u64 v[38:39], v[38:39], 1, s[26:27]
	s_cmp_lg_u32 s99, 0
	s_cbranch_scc1 .Lwt1403_35802
	global_store_dwordx2 v[38:39], v[36:37], off
	s_branch .Lwj1403_35802

; __device__ __forceinline__ f32x4 gelu4(f32x4 v) { const f32x2 a = gelu_pk((f32x2){v[0], v[1]}), b = gelu_pk((f32x2){v[2], v[3]}); return (f32x4){a.x, a.y, b.x, b.y}; }
; __device__ __forceinline__ u32x2 pack4(f32x4 v) { return (u32x2){pk2(v[0], v[1]), pk2(v[2], v[3])}; }
;     __device__ __forceinline__ void operator()(AccRef acc, const Unit& u, int wr, int wc, int fr, int fq) const {
;     ...
;                         if (m == 0 && fr < 2) *(f32x4*)(edge + (unsigned)((grp * 4 + fr) * UPN + jn)) = ag;
;                         if (m == 3 && fr >= 14) *(f32x4*)(edge + (unsigned)((grp * 4 + (fr - 12)) * UPN + jn)) = ag;
;                         const f32x4 o = gelu4(bg + wg0 * g2 + wg1 * g1 + wg2 * ag) * cu[m];
;                         if (!(m == 0 && fr < 2)) *(u32x2*)(act + (unsigned)(row * DFF + jn)) = pack4(o);
.Lwj1403_35802:
.LBB0_1412:
	s_andn2_saveexec_b64 s[0:1], s[74:75]
	s_cbranch_execz .LBB0_1414
	v_add_u32_e32 v136, v44, v175
	v_lshl_add_u64 v[36:37], v[136:137], 2, s[28:29]
	s_cmp_lg_u32 s99, 0
	s_cbranch_scc1 .Lwt1403_35809
	global_store_dwordx4 v[36:37], v[40:43], off
	s_branch .Lwj1403_35809

; __device__ __forceinline__ f32x4 gelu4(f32x4 v) { const f32x2 a = gelu_pk((f32x2){v[0], v[1]}), b = gelu_pk((f32x2){v[2], v[3]}); return (f32x4){a.x, a.y, b.x, b.y}; }
; __device__ __forceinline__ f32x4 ror1v(f32x4 v) { return (f32x4){dpp_ror1(v[0]), dpp_ror1(v[1]), dpp_ror1(v[2]), dpp_ror1(v[3])}; }
; __device__ __forceinline__ f32x4 ror2v(f32x4 v) { return (f32x4){dpp_ror2(v[0]), dpp_ror2(v[1]), dpp_ror2(v[2]), dpp_ror2(v[3])}; }
; __device__ __forceinline__ u32x2 pack4(f32x4 v) { return (u32x2){pk2(v[0], v[1]), pk2(v[2], v[3])}; }
; __device__ __forceinline__ f32x4 unpack4(u32x2 w) { return (f32x4){bflo(w.x), bfhi(w.x), bflo(w.y), bfhi(w.y)}; }
;     __device__ __forceinline__ void operator()(AccRef acc, const Unit& u, int wr, int wc, int fr, int fq) const {
;     ...
;                     for (int m = 0; m < 4; ++m) { const int row = rowg + m * 16 + fr;
;                         const f32x4 ag = unpack4(pa[ai][0][m][n]);
;                         const f32x4 rg1 = ror1v(ag), rg2 = ror2v(ag);
;                         const f32x4 g1 = fr >= 1 ? rg1 : pg1, g2 = fr >= 2 ? rg2 : pg2;
;                         if (m == 0 && fr < 2) *(f32x4*)(edge + (unsigned)((grp * 4 + fr) * UPN + jn)) = ag;
;                         if (m == 3 && fr >= 14) *(f32x4*)(edge + (unsigned)((grp * 4 + (fr - 12)) * UPN + jn)) = ag;
;                         const f32x4 o = gelu4(bg + wg0 * g2 + wg1 * g1 + wg2 * ag) * cu[m];
;                         if (!(m == 0 && fr < 2)) *(u32x2*)(act + (unsigned)(row * DFF + jn)) = pack4(o);
;                         pg1 = rg1; pg2 = rg2; }
.Lwj1403_35809:
.LBB0_1414:
	s_or_b64 exec, exec, s[0:1]
	s_nop 0
	v_cndmask_b32_e64 v41, v204, v206, s[6:7]
	v_cndmask_b32_e64 v40, v201, v205, s[6:7]
	v_cndmask_b32_e64 v43, v197, v203, s[6:7]
	v_cndmask_b32_e64 v42, v193, v199, s[6:7]
	v_cndmask_b32_e64 v37, v194, v200, s[8:9]
	v_cndmask_b32_e64 v36, v191, v195, s[8:9]
	v_cndmask_b32_e64 v39, v196, v202, s[8:9]
	v_cndmask_b32_e64 v38, v192, v198, s[8:9]
	s_waitcnt vmcnt(4)
	v_pk_fma_f32 v[42:43], v[8:9], v[42:43], v[12:13]
	v_pk_fma_f32 v[40:41], v[10:11], v[40:41], v[14:15]
	v_pk_fma_f32 v[36:37], v[0:1], v[36:37], v[42:43]
	v_pk_fma_f32 v[38:39], v[2:3], v[38:39], v[40:41]
	v_pk_fma_f32 v[36:37], v[4:5], v[68:69], v[36:37]
	v_pk_fma_f32 v[38:39], v[6:7], v[66:67], v[38:39]
	v_cndmask_b32_e64 v67, v206, v180, s[6:7]
	v_cndmask_b32_e64 v66, v205, v179, s[6:7]
	v_cndmask_b32_e64 v69, v203, v178, s[6:7]
	v_cndmask_b32_e64 v68, v199, v87, s[6:7]
	v_cndmask_b32_e64 v41, v200, v95, s[8:9]
	v_cndmask_b32_e64 v40, v195, v85, s[8:9]
	v_cndmask_b32_e64 v43, v202, v177, s[8:9]
	v_cndmask_b32_e64 v42, v198, v86, s[8:9]
	v_pk_fma_f32 v[68:69], v[8:9], v[68:69], v[12:13]
	v_pk_fma_f32 v[66:67], v[10:11], v[66:67], v[14:15]
	v_pk_fma_f32 v[40:41], v[0:1], v[40:41], v[68:69]
	v_pk_fma_f32 v[42:43], v[2:3], v[42:43], v[66:67]
	v_pk_fma_f32 v[66:67], v[4:5], v[60:61], v[40:41]
	v_pk_fma_f32 v[68:69], v[6:7], v[46:47], v[42:43]
	v_lshlrev_b32_e32 v40, 16, v94
	v_and_b32_e32 v41, 0xffff0000, v94
	v_lshlrev_b32_e32 v42, 16, v93
	v_and_b32_e32 v43, 0xffff0000, v93
	s_nop 1
	v_mov_b32_dpp v93, v40 row_ror:1 row_mask:0xf bank_mask:0xf
	v_mov_b32_dpp v94, v41 row_ror:1 row_mask:0xf bank_mask:0xf
	v_mov_b32_dpp v191, v40 row_ror:2 row_mask:0xf bank_mask:0xf
	v_mov_b32_dpp v192, v41 row_ror:2 row_mask:0xf bank_mask:0xf
	v_cndmask_b32_e64 v61, v71, v94, s[8:9]
	v_cndmask_b32_e64 v60, v70, v93, s[8:9]
	v_cndmask_b32_e64 v71, v75, v192, s[6:7]
	v_cndmask_b32_e64 v70, v74, v191, s[6:7]
	s_waitcnt vmcnt(2)
	v_pk_fma_f32 v[70:71], v[28:29], v[70:71], v[32:33]
	s_nop 1
	v_pk_fma_f32 v[60:61], v[20:21], v[60:61], v[70:71]
	s_nop 1
	v_pk_fma_f32 v[40:41], v[24:25], v[40:41], v[60:61]
	s_nop 1
	v_and_b32_e32 v71, 0x7fffffff, v41
	v_and_b32_e32 v70, 0x7fffffff, v40
	s_nop 1
	v_pk_fma_f32 v[70:71], v[70:71], s[52:53], 1.0 op_sel_hi:[1,0,0]
	v_mov_b32_dpp v189, v42 row_ror:1 row_mask:0xf bank_mask:0xf
	v_mov_b32_dpp v190, v43 row_ror:1 row_mask:0xf bank_mask:0xf
	v_mov_b32_dpp v193, v42 row_ror:2 row_mask:0xf bank_mask:0xf
	v_mov_b32_dpp v194, v43 row_ror:2 row_mask:0xf bank_mask:0xf
	v_rcp_f32_e32 v70, v70
	v_rcp_f32_e32 v71, v71
	v_cndmask_b32_e64 v47, v73, v190, s[8:9]
	v_cndmask_b32_e64 v46, v72, v189, s[8:9]
	v_cndmask_b32_e64 v73, v77, v194, s[6:7]
	v_cndmask_b32_e64 v72, v76, v193, s[6:7]
	v_pk_fma_f32 v[72:73], v[30:31], v[72:73], v[34:35]
	v_pk_mul_f32 v[60:61], v[40:41], v[40:41]
	v_pk_fma_f32 v[46:47], v[22:23], v[46:47], v[72:73]
	v_mov_b64_e32 v[72:73], s[56:57]
	v_pk_mul_f32 v[60:61], v[60:61], s[42:43] op_sel_hi:[1,0]
	v_pk_fma_f32 v[74:75], v[70:71], s[54:55], v[72:73] op_sel_hi:[1,0,0]
	v_exp_f32_e32 v60, v60
	v_exp_f32_e32 v61, v61
	v_pk_fma_f32 v[74:75], v[70:71], v[74:75], s[58:59] op_sel_hi:[1,1,0]
	v_cmp_gt_f32_e64 s[0:1], 0, v40
	v_pk_fma_f32 v[74:75], v[70:71], v[74:75], s[60:61] op_sel_hi:[1,1,0]
	v_pk_fma_f32 v[42:43], v[26:27], v[42:43], v[46:47]
	v_pk_fma_f32 v[74:75], v[70:71], v[74:75], s[62:63] op_sel_hi:[1,1,0]
	v_pk_mul_f32 v[46:47], v[42:43], v[42:43]
	v_pk_mul_f32 v[70:71], v[70:71], v[74:75]
	v_pk_mul_f32 v[46:47], v[46:47], s[42:43] op_sel_hi:[1,0]
	v_pk_mul_f32 v[60:61], v[60:61], v[70:71]
	v_exp_f32_e32 v46, v46
	v_pk_mul_f32 v[70:71], v[40:41], v[60:61]
	v_pk_fma_f32 v[60:61], v[40:41], v[60:61], v[40:41] neg_lo:[1,0,0] neg_hi:[1,0,0]
	v_exp_f32_e32 v47, v47
	v_cndmask_b32_e64 v40, v60, v70, s[0:1]
	v_cmp_gt_f32_e64 s[0:1], 0, v41
	v_and_b32_e32 v60, 0x7fffffff, v42
	v_mul_lo_u32 v45, v148, s86
	v_cndmask_b32_e64 v41, v61, v71, s[0:1]
	v_and_b32_e32 v61, 0x7fffffff, v43
	v_pk_fma_f32 v[60:61], v[60:61], s[52:53], 1.0 op_sel_hi:[1,0,0]
	v_cmp_gt_f32_e64 s[0:1], 0, v42
	v_rcp_f32_e32 v60, v60
	v_rcp_f32_e32 v61, v61
	v_pk_mul_f32 v[36:37], v[36:37], v[40:41]
	v_add_u32_e32 v136, v45, v44
	v_cvt_pk_bf16_f32 v36, v36, v37
	v_pk_fma_f32 v[70:71], v[60:61], s[54:55], v[72:73] op_sel_hi:[1,0,0]
	s_nop 1
	v_pk_fma_f32 v[70:71], v[60:61], v[70:71], s[58:59] op_sel_hi:[1,1,0]
	s_nop 1
	v_pk_fma_f32 v[70:71], v[60:61], v[70:71], s[60:61] op_sel_hi:[1,1,0]
	v_add_u32_e32 v148, 0xb000, v45
	v_pk_fma_f32 v[70:71], v[60:61], v[70:71], s[62:63] op_sel_hi:[1,1,0]
	s_nop 0
	v_pk_mul_f32 v[60:61], v[60:61], v[70:71]
	s_nop 0
	v_pk_mul_f32 v[46:47], v[46:47], v[60:61]
	s_nop 0
	v_pk_mul_f32 v[60:61], v[42:43], v[46:47]
	v_pk_fma_f32 v[46:47], v[42:43], v[46:47], v[42:43] neg_lo:[1,0,0] neg_hi:[1,0,0]
	s_nop 0
	v_cndmask_b32_e64 v42, v46, v60, s[0:1]
	v_cmp_gt_f32_e64 s[0:1], 0, v43
	s_nop 1
	v_cndmask_b32_e64 v43, v47, v61, s[0:1]
	v_pk_mul_f32 v[38:39], v[38:39], v[42:43]
	s_nop 1
	v_cvt_pk_bf16_f32 v37, v38, v39
	v_lshl_add_u64 v[38:39], v[136:137], 1, s[26:27]
	s_cmp_lg_u32 s99, 0
	s_cbranch_scc1 .Lwt1403_35937
	global_store_dwordx2 v[38:39], v[36:37], off
	s_branch .Lwj1403_35937

; __device__ __forceinline__ f32x4 gelu4(f32x4 v) { const f32x2 a = gelu_pk((f32x2){v[0], v[1]}), b = gelu_pk((f32x2){v[2], v[3]}); return (f32x4){a.x, a.y, b.x, b.y}; }
; __device__ __forceinline__ f32x4 ror1v(f32x4 v) { return (f32x4){dpp_ror1(v[0]), dpp_ror1(v[1]), dpp_ror1(v[2]), dpp_ror1(v[3])}; }
; __device__ __forceinline__ f32x4 ror2v(f32x4 v) { return (f32x4){dpp_ror2(v[0]), dpp_ror2(v[1]), dpp_ror2(v[2]), dpp_ror2(v[3])}; }
; __device__ __forceinline__ u32x2 pack4(f32x4 v) { return (u32x2){pk2(v[0], v[1]), pk2(v[2], v[3])}; }
; __device__ __forceinline__ f32x4 unpack4(u32x2 w) { return (f32x4){bflo(w.x), bfhi(w.x), bflo(w.y), bfhi(w.y)}; }
;     __device__ __forceinline__ void operator()(AccRef acc, const Unit& u, int wr, int wc, int fr, int fq) const {
;     ...
;                     for (int m = 0; m < 4; ++m) { const int row = rowg + m * 16 + fr;
;                         const f32x4 ag = unpack4(pa[ai][0][m][n]);
;                         const f32x4 rg1 = ror1v(ag), rg2 = ror2v(ag);
;                         const f32x4 g1 = fr >= 1 ? rg1 : pg1, g2 = fr >= 2 ? rg2 : pg2;
;                         if (m == 0 && fr < 2) *(f32x4*)(edge + (unsigned)((grp * 4 + fr) * UPN + jn)) = ag;
;                         if (m == 3 && fr >= 14) *(f32x4*)(edge + (unsigned)((grp * 4 + (fr - 12)) * UPN + jn)) = ag;
;                         const f32x4 o = gelu4(bg + wg0 * g2 + wg1 * g1 + wg2 * ag) * cu[m];
;                         if (!(m == 0 && fr < 2)) *(u32x2*)(act + (unsigned)(row * DFF + jn)) = pack4(o);
;                         pg1 = rg1; pg2 = rg2; }
.Lwj1403_35937:
	v_lshlrev_b32_e32 v36, 16, v92
	v_and_b32_e32 v37, 0xffff0000, v92
	v_lshlrev_b32_e32 v38, 16, v91
	v_mov_b32_dpp v43, v36 row_ror:2 row_mask:0xf bank_mask:0xf
	v_mov_b32_dpp v60, v37 row_ror:2 row_mask:0xf bank_mask:0xf
	v_mov_b32_dpp v40, v36 row_ror:1 row_mask:0xf bank_mask:0xf
	v_mov_b32_dpp v41, v37 row_ror:1 row_mask:0xf bank_mask:0xf
	v_cndmask_b32_e64 v77, v192, v60, s[6:7]
	v_cndmask_b32_e64 v76, v191, v43, s[6:7]
	v_cndmask_b32_e64 v75, v94, v41, s[8:9]
	v_cndmask_b32_e64 v74, v93, v40, s[8:9]
	v_pk_fma_f32 v[76:77], v[28:29], v[76:77], v[32:33]
	v_and_b32_e32 v39, 0xffff0000, v91
	v_pk_fma_f32 v[74:75], v[20:21], v[74:75], v[76:77]
	s_nop 1
	v_pk_fma_f32 v[36:37], v[24:25], v[36:37], v[74:75]
	s_nop 1
	v_and_b32_e32 v77, 0x7fffffff, v37
	v_and_b32_e32 v76, 0x7fffffff, v36
	v_pk_fma_f32 v[76:77], v[76:77], s[52:53], 1.0 op_sel_hi:[1,0,0]
	s_nop 1
	v_rcp_f32_e32 v76, v76
	v_rcp_f32_e32 v77, v77
	v_mov_b32_dpp v46, v38 row_ror:2 row_mask:0xf bank_mask:0xf
	v_mov_b32_dpp v61, v39 row_ror:2 row_mask:0xf bank_mask:0xf
	v_mov_b32_dpp v42, v38 row_ror:1 row_mask:0xf bank_mask:0xf
	v_mov_b32_dpp v47, v39 row_ror:1 row_mask:0xf bank_mask:0xf
	v_cndmask_b32_e64 v93, v194, v61, s[6:7]
	v_cndmask_b32_e64 v92, v193, v46, s[6:7]
	v_cndmask_b32_e64 v71, v190, v47, s[8:9]
	v_cndmask_b32_e64 v70, v189, v42, s[8:9]
	v_pk_fma_f32 v[92:93], v[30:31], v[92:93], v[34:35]
	v_pk_mul_f32 v[74:75], v[36:37], v[36:37]
	v_pk_fma_f32 v[70:71], v[22:23], v[70:71], v[92:93]
	v_pk_mul_f32 v[74:75], v[74:75], s[42:43] op_sel_hi:[1,0]
	v_pk_fma_f32 v[92:93], v[76:77], s[54:55], v[72:73] op_sel_hi:[1,0,0]
	v_exp_f32_e32 v74, v74
	v_exp_f32_e32 v75, v75
	v_pk_fma_f32 v[92:93], v[76:77], v[92:93], s[58:59] op_sel_hi:[1,1,0]
	v_cmp_gt_f32_e64 s[0:1], 0, v36
	v_pk_fma_f32 v[92:93], v[76:77], v[92:93], s[60:61] op_sel_hi:[1,1,0]
	v_pk_fma_f32 v[38:39], v[26:27], v[38:39], v[70:71]
	v_pk_fma_f32 v[92:93], v[76:77], v[92:93], s[62:63] op_sel_hi:[1,1,0]
	v_pk_mul_f32 v[70:71], v[38:39], v[38:39]
	v_pk_mul_f32 v[76:77], v[76:77], v[92:93]
	v_pk_mul_f32 v[70:71], v[70:71], s[42:43] op_sel_hi:[1,0]
	v_pk_mul_f32 v[74:75], v[74:75], v[76:77]
	v_exp_f32_e32 v70, v70
	v_pk_mul_f32 v[76:77], v[36:37], v[74:75]
	v_pk_fma_f32 v[74:75], v[36:37], v[74:75], v[36:37] neg_lo:[1,0,0] neg_hi:[1,0,0]
	v_exp_f32_e32 v71, v71
	v_cndmask_b32_e64 v36, v74, v76, s[0:1]
	v_cmp_gt_f32_e64 s[0:1], 0, v37
	v_and_b32_e32 v74, 0x7fffffff, v38
	v_add_u32_e32 v136, v148, v44
	v_cndmask_b32_e64 v37, v75, v77, s[0:1]
	v_and_b32_e32 v75, 0x7fffffff, v39
	v_pk_fma_f32 v[74:75], v[74:75], s[52:53], 1.0 op_sel_hi:[1,0,0]
	v_cmp_gt_f32_e64 s[0:1], 0, v38
	v_rcp_f32_e32 v74, v74
	v_rcp_f32_e32 v75, v75
	v_pk_mul_f32 v[36:37], v[66:67], v[36:37]
	s_nop 1
	v_cvt_pk_bf16_f32 v36, v36, v37
	v_pk_fma_f32 v[72:73], v[74:75], s[54:55], v[72:73] op_sel_hi:[1,0,0]
	s_nop 1
	v_pk_fma_f32 v[72:73], v[74:75], v[72:73], s[58:59] op_sel_hi:[1,1,0]
	s_nop 0
	v_pk_fma_f32 v[72:73], v[74:75], v[72:73], s[60:61] op_sel_hi:[1,1,0]
	s_nop 0
	v_pk_fma_f32 v[72:73], v[74:75], v[72:73], s[62:63] op_sel_hi:[1,1,0]
	s_nop 0
	v_pk_mul_f32 v[72:73], v[74:75], v[72:73]
	s_nop 0
	v_pk_mul_f32 v[70:71], v[70:71], v[72:73]
	s_nop 0
	v_pk_mul_f32 v[72:73], v[38:39], v[70:71]
	v_pk_fma_f32 v[70:71], v[38:39], v[70:71], v[38:39] neg_lo:[1,0,0] neg_hi:[1,0,0]
	s_nop 0
	v_cndmask_b32_e64 v38, v70, v72, s[0:1]
	v_cmp_gt_f32_e64 s[0:1], 0, v39
	s_nop 1
	v_cndmask_b32_e64 v39, v71, v73, s[0:1]
	v_pk_mul_f32 v[38:39], v[68:69], v[38:39]
	s_nop 1
	v_cvt_pk_bf16_f32 v37, v38, v39
	v_lshl_add_u64 v[38:39], v[136:137], 1, s[26:27]
	s_cmp_lg_u32 s99, 0
	s_cbranch_scc1 .Lwt1403_36029
	global_store_dwordx2 v[38:39], v[36:37], off
	s_branch .Lwj1403_36029

; __device__ __forceinline__ f32x4 gelu4(f32x4 v) { const f32x2 a = gelu_pk((f32x2){v[0], v[1]}), b = gelu_pk((f32x2){v[2], v[3]}); return (f32x4){a.x, a.y, b.x, b.y}; }
; __device__ __forceinline__ f32x4 ror1v(f32x4 v) { return (f32x4){dpp_ror1(v[0]), dpp_ror1(v[1]), dpp_ror1(v[2]), dpp_ror1(v[3])}; }
; __device__ __forceinline__ f32x4 ror2v(f32x4 v) { return (f32x4){dpp_ror2(v[0]), dpp_ror2(v[1]), dpp_ror2(v[2]), dpp_ror2(v[3])}; }
; __device__ __forceinline__ u32x2 pack4(f32x4 v) { return (u32x2){pk2(v[0], v[1]), pk2(v[2], v[3])}; }
; __device__ __forceinline__ f32x4 unpack4(u32x2 w) { return (f32x4){bflo(w.x), bfhi(w.x), bflo(w.y), bfhi(w.y)}; }
;     __device__ __forceinline__ void operator()(AccRef acc, const Unit& u, int wr, int wc, int fr, int fq) const {
;     ...
;                     const f32x4 wu0 = *(const f32x4*)(cw + (DFF + jn)), wu1 = *(const f32x4*)(cw + (UPN + DFF + jn)), wu2 = *(const f32x4*)(cw + (2 * UPN + DFF + jn)), bu = *(const f32x4*)(cb + (DFF + jn));
;     ...
;                     const f32x4 wg0 = *(const f32x4*)(cw + jn), wg1 = *(const f32x4*)(cw + (UPN + jn)), wg2 = *(const f32x4*)(cw + (2 * UPN + jn)), bg = *(const f32x4*)(cb + jn);
;                     f32x4 pg1 = (f32x4){0.f, 0.f, 0.f, 0.f}, pg2 = pg1;
; #pragma unroll
;                     for (int m = 0; m < 4; ++m) { const int row = rowg + m * 16 + fr;
;                         const f32x4 ag = unpack4(pa[ai][0][m][n]);
;                         const f32x4 rg1 = ror1v(ag), rg2 = ror2v(ag);
;                         const f32x4 g1 = fr >= 1 ? rg1 : pg1, g2 = fr >= 2 ? rg2 : pg2;
;                         if (m == 0 && fr < 2) *(f32x4*)(edge + (unsigned)((grp * 4 + fr) * UPN + jn)) = ag;
;                         if (m == 3 && fr >= 14) *(f32x4*)(edge + (unsigned)((grp * 4 + (fr - 12)) * UPN + jn)) = ag;
;                         const f32x4 o = gelu4(bg + wg0 * g2 + wg1 * g1 + wg2 * ag) * cu[m];
;                         if (!(m == 0 && fr < 2)) *(u32x2*)(act + (unsigned)(row * DFF + jn)) = pack4(o);
;                         pg1 = rg1; pg2 = rg2; }
.Lwj1403_36029:
	v_lshlrev_b32_e32 v36, 16, v82
	v_and_b32_e32 v37, 0xffff0000, v82
	v_lshlrev_b32_e32 v38, 16, v83
	v_and_b32_e32 v39, 0xffff0000, v83
	s_nop 1
	v_mov_b32_dpp v66, v36 row_ror:1 row_mask:0xf bank_mask:0xf
	v_mov_b32_dpp v67, v37 row_ror:1 row_mask:0xf bank_mask:0xf
	v_mov_b32_dpp v68, v38 row_ror:1 row_mask:0xf bank_mask:0xf
	v_mov_b32_dpp v71, v39 row_ror:1 row_mask:0xf bank_mask:0xf
	v_mov_b32_dpp v69, v36 row_ror:2 row_mask:0xf bank_mask:0xf
	v_mov_b32_dpp v72, v37 row_ror:2 row_mask:0xf bank_mask:0xf
	v_mov_b32_dpp v70, v38 row_ror:2 row_mask:0xf bank_mask:0xf
	v_mov_b32_dpp v73, v39 row_ror:2 row_mask:0xf bank_mask:0xf
	s_and_saveexec_b64 s[0:1], vcc
	s_cbranch_execz .LBB0_1416
	v_add_u32_e32 v136, v152, v44
	v_lshl_add_u64 v[74:75], v[136:137], 2, s[28:29]
	s_cmp_lg_u32 s99, 0
	s_cbranch_scc1 .Lwt1403_36048
	global_store_dwordx4 v[74:75], v[36:39], off
	s_branch .Lwj1403_36048
.Lwt1403_36048:
	global_store_dwordx4 v[74:75], v[36:39], off sc1
.Lwj1403_36048:
.LBB0_1416:
	s_or_b64 exec, exec, s[0:1]
	v_cndmask_b32_e64 v74, v42, v68, s[8:9]
	v_cndmask_b32_e64 v40, v40, v66, s[8:9]
	v_cndmask_b32_e64 v66, v43, v69, s[6:7]
	v_cndmask_b32_e64 v69, v180, v188, s[6:7]
	v_cndmask_b32_e64 v68, v179, v187, s[6:7]
	v_cndmask_b32_e64 v41, v41, v67, s[8:9]
	v_cndmask_b32_e64 v67, v60, v72, s[6:7]
	v_cndmask_b32_e64 v43, v61, v73, s[6:7]
	v_cndmask_b32_e64 v61, v177, v185, s[8:9]
	v_cndmask_b32_e64 v60, v86, v182, s[8:9]
	v_pk_fma_f32 v[10:11], v[10:11], v[68:69], v[14:15]
	v_cndmask_b32_e64 v75, v47, v71, s[8:9]
	v_pk_fma_f32 v[2:3], v[2:3], v[60:61], v[10:11]
	v_cndmask_b32_e64 v42, v46, v70, s[6:7]
	v_pk_fma_f32 v[2:3], v[6:7], v[18:19], v[2:3]
	v_pk_fma_f32 v[6:7], v[28:29], v[66:67], v[32:33]
	v_cndmask_b32_e64 v71, v178, v186, s[6:7]
	v_pk_fma_f32 v[6:7], v[20:21], v[40:41], v[6:7]
	v_cndmask_b32_e64 v70, v87, v183, s[6:7]
	v_pk_fma_f32 v[6:7], v[24:25], v[36:37], v[6:7]
	v_pk_fma_f32 v[8:9], v[8:9], v[70:71], v[12:13]
	v_and_b32_e32 v13, 0x7fffffff, v7
	v_and_b32_e32 v12, 0x7fffffff, v6
	v_pk_fma_f32 v[12:13], v[12:13], s[52:53], 1.0 op_sel_hi:[1,0,0]
	v_cndmask_b32_e64 v47, v95, v184, s[8:9]
	v_rcp_f32_e32 v12, v12
	v_rcp_f32_e32 v13, v13
	v_cndmask_b32_e64 v46, v85, v181, s[8:9]
	v_pk_fma_f32 v[0:1], v[0:1], v[46:47], v[8:9]
	v_pk_mul_f32 v[10:11], v[6:7], v[6:7]
	v_mov_b64_e32 v[14:15], s[56:57]
	v_pk_fma_f32 v[0:1], v[4:5], v[16:17], v[0:1]
	v_pk_mul_f32 v[10:11], v[10:11], s[42:43] op_sel_hi:[1,0]
	v_pk_fma_f32 v[16:17], v[12:13], s[54:55], v[14:15] op_sel_hi:[1,0,0]
	v_exp_f32_e32 v10, v10
	v_exp_f32_e32 v11, v11
	v_pk_fma_f32 v[16:17], v[12:13], v[16:17], s[58:59] op_sel_hi:[1,1,0]
	v_pk_fma_f32 v[4:5], v[30:31], v[42:43], v[34:35]
	v_pk_fma_f32 v[16:17], v[12:13], v[16:17], s[60:61] op_sel_hi:[1,1,0]
	v_pk_fma_f32 v[4:5], v[22:23], v[74:75], v[4:5]
	v_pk_fma_f32 v[16:17], v[12:13], v[16:17], s[62:63] op_sel_hi:[1,1,0]
	v_cmp_gt_f32_e64 s[0:1], 0, v6
	v_pk_mul_f32 v[12:13], v[12:13], v[16:17]
	v_pk_fma_f32 v[4:5], v[26:27], v[38:39], v[4:5]
	v_pk_mul_f32 v[10:11], v[10:11], v[12:13]
	v_pk_mul_f32 v[8:9], v[4:5], v[4:5]
	v_pk_mul_f32 v[12:13], v[6:7], v[10:11]
	v_pk_fma_f32 v[10:11], v[6:7], v[10:11], v[6:7] neg_lo:[1,0,0] neg_hi:[1,0,0]
	v_pk_mul_f32 v[8:9], v[8:9], s[42:43] op_sel_hi:[1,0]
	v_cndmask_b32_e64 v6, v10, v12, s[0:1]
	v_cmp_gt_f32_e64 s[0:1], 0, v7
	v_and_b32_e32 v10, 0x7fffffff, v4
	v_exp_f32_e32 v8, v8
	v_cndmask_b32_e64 v7, v11, v13, s[0:1]
	v_and_b32_e32 v11, 0x7fffffff, v5
	v_pk_fma_f32 v[10:11], v[10:11], s[52:53], 1.0 op_sel_hi:[1,0,0]
	v_exp_f32_e32 v9, v9
	v_rcp_f32_e32 v10, v10
	v_rcp_f32_e32 v11, v11
	v_cmp_gt_f32_e64 s[0:1], 0, v4
	v_add_u32_e32 v177, 0xb000, v148
	v_pk_mul_f32 v[0:1], v[0:1], v[6:7]
	v_pk_fma_f32 v[12:13], v[10:11], s[54:55], v[14:15] op_sel_hi:[1,0,0]
	v_add_u32_e32 v136, v177, v44
	v_pk_fma_f32 v[12:13], v[10:11], v[12:13], s[58:59] op_sel_hi:[1,1,0]
	v_cvt_pk_bf16_f32 v0, v0, v1
	v_lshlrev_b32_e32 v36, 16, v173
	v_pk_fma_f32 v[12:13], v[10:11], v[12:13], s[60:61] op_sel_hi:[1,1,0]
	v_and_b32_e32 v37, 0xffff0000, v173
	v_pk_fma_f32 v[12:13], v[10:11], v[12:13], s[62:63] op_sel_hi:[1,1,0]
	v_lshlrev_b32_e32 v38, 16, v174
	v_pk_mul_f32 v[10:11], v[10:11], v[12:13]
	v_and_b32_e32 v39, 0xffff0000, v174
	v_pk_mul_f32 v[8:9], v[8:9], v[10:11]
	s_nop 1
	v_pk_mul_f32 v[10:11], v[4:5], v[8:9]
	v_pk_fma_f32 v[8:9], v[4:5], v[8:9], v[4:5] neg_lo:[1,0,0] neg_hi:[1,0,0]
	s_nop 1
	v_cndmask_b32_e64 v4, v8, v10, s[0:1]
	v_cmp_gt_f32_e64 s[0:1], 0, v5
	s_nop 1
	v_cndmask_b32_e64 v5, v9, v11, s[0:1]
	v_pk_mul_f32 v[2:3], v[2:3], v[4:5]
	s_nop 1
	v_cvt_pk_bf16_f32 v1, v2, v3
	v_lshl_add_u64 v[2:3], v[136:137], 1, s[26:27]
	v_add_u32_e32 v136, 0xb04, v44
	v_lshlrev_b64 v[12:13], 2, v[136:137]
	v_add_u32_e32 v136, 0x2104, v44
	v_lshl_add_u64 v[66:67], v[136:137], 2, s[20:21]
	v_add_u32_e32 v136, 0x3704, v44
	s_cmp_lg_u32 s99, 0
	s_cbranch_scc1 .Lwt1403_36146
	global_store_dwordx2 v[2:3], v[0:1], off
	s_branch .Lwj1403_36146

; __device__ __forceinline__ f32x4 ror1v(f32x4 v) { return (f32x4){dpp_ror1(v[0]), dpp_ror1(v[1]), dpp_ror1(v[2]), dpp_ror1(v[3])}; }
; __device__ __forceinline__ f32x4 ror2v(f32x4 v) { return (f32x4){dpp_ror2(v[0]), dpp_ror2(v[1]), dpp_ror2(v[2]), dpp_ror2(v[3])}; }
; __device__ __forceinline__ f32x4 unpack4(u32x2 w) { return (f32x4){bflo(w.x), bfhi(w.x), bflo(w.y), bfhi(w.y)}; }
;     __device__ __forceinline__ void operator()(AccRef acc, const Unit& u, int wr, int wc, int fr, int fq) const {
;     ...
;             for (int n = 0; n < 2; ++n) { const unsigned jn = (unsigned)(j0 + 4 * n);
;                 f32x4 cu[4];
;                 {
;                     const f32x4 wu0 = *(const f32x4*)(cw + (DFF + jn)), wu1 = *(const f32x4*)(cw + (UPN + DFF + jn)), wu2 = *(const f32x4*)(cw + (2 * UPN + DFF + jn)), bu = *(const f32x4*)(cb + (DFF + jn));
;                     f32x4 pu1 = (f32x4){0.f, 0.f, 0.f, 0.f}, pu2 = pu1;
; #pragma unroll
;                     for (int m = 0; m < 4; ++m) {
;                         const f32x4 au = unpack4(pa[ai][1][m][n]);
;                         const f32x4 ru1 = ror1v(au), ru2 = ror2v(au);
;                         const f32x4 u1 = fr >= 1 ? ru1 : pu1, u2 = fr >= 2 ? ru2 : pu2;
;                         if (m == 0 && fr < 2) *(f32x4*)(edge + (unsigned)((grp * 4 + fr) * UPN + DFF + jn)) = au;
;                         if (m == 3 && fr >= 14) *(f32x4*)(edge + (unsigned)((grp * 4 + (fr - 12)) * UPN + DFF + jn)) = au;
;                         cu[m] = bu + wu0 * u2 + wu1 * u1 + wu2 * au;
.Lwj1403_36146:
	v_lshl_add_u64 v[60:61], s[20:21], 0, v[12:13]
	v_lshl_add_u64 v[68:69], v[136:137], 2, s[20:21]
	v_lshl_add_u64 v[70:71], s[22:23], 0, v[12:13]
	global_load_dwordx4 v[8:11], v[60:61], off
	global_load_dwordx4 v[0:3], v[66:67], off
	global_load_dwordx4 v[4:7], v[68:69], off
	global_load_dwordx4 v[12:15], v[70:71], off
	s_nop 1
	v_or_b32_e32 v46, 4, v44
	v_mov_b32_dpp v193, v36 row_ror:1 row_mask:0xf bank_mask:0xf
	v_mov_b32_dpp v199, v37 row_ror:1 row_mask:0xf bank_mask:0xf
	v_mov_b32_dpp v196, v38 row_ror:1 row_mask:0xf bank_mask:0xf
	v_mov_b32_dpp v202, v39 row_ror:1 row_mask:0xf bank_mask:0xf
	v_mov_b32_dpp v197, v36 row_ror:2 row_mask:0xf bank_mask:0xf
	v_mov_b32_dpp v203, v37 row_ror:2 row_mask:0xf bank_mask:0xf
	v_mov_b32_dpp v205, v38 row_ror:2 row_mask:0xf bank_mask:0xf
	v_mov_b32_dpp v207, v39 row_ror:2 row_mask:0xf bank_mask:0xf
	s_and_saveexec_b64 s[0:1], s[12:13]
	s_cbranch_execz .LBB0_1418
	v_add_u32_e32 v136, v46, v84
	v_lshl_add_u64 v[16:17], v[136:137], 2, s[28:29]
	s_cmp_lg_u32 s99, 0
	s_cbranch_scc1 .Lwt1403_36169
	global_store_dwordx4 v[16:17], v[36:39], off
	s_branch .Lwj1403_36169

; __device__ __forceinline__ f32x4 ror1v(f32x4 v) { return (f32x4){dpp_ror1(v[0]), dpp_ror1(v[1]), dpp_ror1(v[2]), dpp_ror1(v[3])}; }
; __device__ __forceinline__ f32x4 ror2v(f32x4 v) { return (f32x4){dpp_ror2(v[0]), dpp_ror2(v[1]), dpp_ror2(v[2]), dpp_ror2(v[3])}; }
; __device__ __forceinline__ f32x4 unpack4(u32x2 w) { return (f32x4){bflo(w.x), bfhi(w.x), bflo(w.y), bfhi(w.y)}; }
;     __device__ __forceinline__ void operator()(AccRef acc, const Unit& u, int wr, int wc, int fr, int fq) const {
;     ...
; #pragma unroll
;                     for (int m = 0; m < 4; ++m) {
;                         const f32x4 au = unpack4(pa[ai][1][m][n]);
;                         const f32x4 ru1 = ror1v(au), ru2 = ror2v(au);
;                         const f32x4 u1 = fr >= 1 ? ru1 : pu1, u2 = fr >= 2 ? ru2 : pu2;
;                         if (m == 0 && fr < 2) *(f32x4*)(edge + (unsigned)((grp * 4 + fr) * UPN + DFF + jn)) = au;
;                         if (m == 3 && fr >= 14) *(f32x4*)(edge + (unsigned)((grp * 4 + (fr - 12)) * UPN + DFF + jn)) = au;
;                         cu[m] = bu + wu0 * u2 + wu1 * u1 + wu2 * au;
;                         pu1 = ru1; pu2 = ru2; }
.Lwj1403_36169:
.LBB0_1418:
	s_or_b64 exec, exec, s[0:1]
	v_lshlrev_b32_e32 v86, 16, v89
	v_and_b32_e32 v87, 0xffff0000, v89
	v_lshlrev_b32_e32 v84, 16, v88
	v_and_b32_e32 v85, 0xffff0000, v88
	s_nop 1
	v_lshlrev_b32_e32 v82, 16, v80
	v_and_b32_e32 v83, 0xffff0000, v80
	v_lshlrev_b32_e32 v80, 16, v81
	v_and_b32_e32 v81, 0xffff0000, v81
	s_nop 1
	v_lshlrev_b32_e32 v16, 16, v78
	v_and_b32_e32 v17, 0xffff0000, v78
	v_lshlrev_b32_e32 v18, 16, v79
	v_and_b32_e32 v19, 0xffff0000, v79
	s_nop 1
	v_mov_b32_dpp v192, v86 row_ror:1 row_mask:0xf bank_mask:0xf
	v_mov_b32_dpp v198, v87 row_ror:1 row_mask:0xf bank_mask:0xf
	v_mov_b32_dpp v194, v84 row_ror:1 row_mask:0xf bank_mask:0xf
	v_mov_b32_dpp v200, v85 row_ror:1 row_mask:0xf bank_mask:0xf
	v_mov_b32_dpp v195, v86 row_ror:2 row_mask:0xf bank_mask:0xf
	v_mov_b32_dpp v201, v87 row_ror:2 row_mask:0xf bank_mask:0xf
	v_mov_b32_dpp v204, v84 row_ror:2 row_mask:0xf bank_mask:0xf
	v_mov_b32_dpp v206, v85 row_ror:2 row_mask:0xf bank_mask:0xf
	v_mov_b32_dpp v173, v82 row_ror:1 row_mask:0xf bank_mask:0xf
	v_mov_b32_dpp v179, v83 row_ror:1 row_mask:0xf bank_mask:0xf
	v_mov_b32_dpp v174, v80 row_ror:1 row_mask:0xf bank_mask:0xf
	v_mov_b32_dpp v180, v81 row_ror:1 row_mask:0xf bank_mask:0xf
	v_mov_b32_dpp v178, v82 row_ror:2 row_mask:0xf bank_mask:0xf
	v_mov_b32_dpp v181, v83 row_ror:2 row_mask:0xf bank_mask:0xf
	v_mov_b32_dpp v182, v80 row_ror:2 row_mask:0xf bank_mask:0xf
	v_mov_b32_dpp v183, v81 row_ror:2 row_mask:0xf bank_mask:0xf
	v_mov_b32_dpp v184, v16 row_ror:1 row_mask:0xf bank_mask:0xf
	v_mov_b32_dpp v187, v17 row_ror:1 row_mask:0xf bank_mask:0xf
	v_mov_b32_dpp v185, v18 row_ror:1 row_mask:0xf bank_mask:0xf
	v_mov_b32_dpp v188, v19 row_ror:1 row_mask:0xf bank_mask:0xf
	v_mov_b32_dpp v186, v16 row_ror:2 row_mask:0xf bank_mask:0xf
	v_mov_b32_dpp v189, v17 row_ror:2 row_mask:0xf bank_mask:0xf
	v_mov_b32_dpp v190, v18 row_ror:2 row_mask:0xf bank_mask:0xf
	v_mov_b32_dpp v191, v19 row_ror:2 row_mask:0xf bank_mask:0xf
	s_and_saveexec_b64 s[0:1], vcc
	s_cbranch_execz .LBB0_1420
	v_add_u32_e32 v136, v90, v46
	v_lshl_add_u64 v[20:21], v[136:137], 2, s[28:29]
	s_cmp_lg_u32 s99, 0
	s_cbranch_scc1 .Lwt1403_36216
	global_store_dwordx4 v[20:21], v[16:19], off
	s_branch .Lwj1403_36216

; __device__ __forceinline__ f32x4 gelu4(f32x4 v) { const f32x2 a = gelu_pk((f32x2){v[0], v[1]}), b = gelu_pk((f32x2){v[2], v[3]}); return (f32x4){a.x, a.y, b.x, b.y}; }
; __device__ __forceinline__ f32x4 ror1v(f32x4 v) { return (f32x4){dpp_ror1(v[0]), dpp_ror1(v[1]), dpp_ror1(v[2]), dpp_ror1(v[3])}; }
; __device__ __forceinline__ f32x4 ror2v(f32x4 v) { return (f32x4){dpp_ror2(v[0]), dpp_ror2(v[1]), dpp_ror2(v[2]), dpp_ror2(v[3])}; }
; __device__ __forceinline__ u32x2 pack4(f32x4 v) { return (u32x2){pk2(v[0], v[1]), pk2(v[2], v[3])}; }
; __device__ __forceinline__ f32x4 unpack4(u32x2 w) { return (f32x4){bflo(w.x), bfhi(w.x), bflo(w.y), bfhi(w.y)}; }
;     __device__ __forceinline__ void operator()(AccRef acc, const Unit& u, int wr, int wc, int fr, int fq) const {
;     ...
;                 {
;                     const f32x4 wg0 = *(const f32x4*)(cw + jn), wg1 = *(const f32x4*)(cw + (UPN + jn)), wg2 = *(const f32x4*)(cw + (2 * UPN + jn)), bg = *(const f32x4*)(cb + jn);
;                     f32x4 pg1 = (f32x4){0.f, 0.f, 0.f, 0.f}, pg2 = pg1;
; #pragma unroll
;                     for (int m = 0; m < 4; ++m) { const int row = rowg + m * 16 + fr;
;                         const f32x4 ag = unpack4(pa[ai][0][m][n]);
;                         const f32x4 rg1 = ror1v(ag), rg2 = ror2v(ag);
;                         const f32x4 g1 = fr >= 1 ? rg1 : pg1, g2 = fr >= 2 ? rg2 : pg2;
;                         if (m == 0 && fr < 2) *(f32x4*)(edge + (unsigned)((grp * 4 + fr) * UPN + jn)) = ag;
;                         if (m == 3 && fr >= 14) *(f32x4*)(edge + (unsigned)((grp * 4 + (fr - 12)) * UPN + jn)) = ag;
;                         const f32x4 o = gelu4(bg + wg0 * g2 + wg1 * g1 + wg2 * ag) * cu[m];
;                         if (!(m == 0 && fr < 2)) *(u32x2*)(act + (unsigned)(row * DFF + jn)) = pack4(o);
;                         pg1 = rg1; pg2 = rg2; }
.Lwj1403_36216:
.LBB0_1420:
	s_or_b64 exec, exec, s[0:1]
	v_mov_b32_e32 v47, v137
	v_add_u32_e32 v136, 0x1604, v44
	v_lshlrev_b64 v[32:33], 2, v[46:47]
	v_lshl_add_u64 v[74:75], v[136:137], 2, s[20:21]
	v_add_u32_e32 v136, 0x2c04, v44
	v_lshl_add_u64 v[72:73], s[20:21], 0, v[32:33]
	v_lshl_add_u64 v[76:77], v[136:137], 2, s[20:21]
	v_lshl_add_u64 v[78:79], s[22:23], 0, v[32:33]
	global_load_dwordx4 v[28:31], v[72:73], off
	global_load_dwordx4 v[20:23], v[74:75], off
	global_load_dwordx4 v[24:27], v[76:77], off
	global_load_dwordx4 v[32:35], v[78:79], off
	v_lshlrev_b32_e32 v40, 16, v172
	v_and_b32_e32 v41, 0xffff0000, v172
	v_lshlrev_b32_e32 v42, 16, v171
	v_and_b32_e32 v43, 0xffff0000, v171
	s_nop 1
	v_mov_b32_dpp v88, v40 row_ror:1 row_mask:0xf bank_mask:0xf
	v_mov_b32_dpp v89, v41 row_ror:1 row_mask:0xf bank_mask:0xf
	v_mov_b32_dpp v90, v42 row_ror:1 row_mask:0xf bank_mask:0xf
	v_mov_b32_dpp v91, v43 row_ror:1 row_mask:0xf bank_mask:0xf
	v_mov_b32_dpp v92, v40 row_ror:2 row_mask:0xf bank_mask:0xf
	v_mov_b32_dpp v93, v41 row_ror:2 row_mask:0xf bank_mask:0xf
	v_mov_b32_dpp v94, v42 row_ror:2 row_mask:0xf bank_mask:0xf
	v_mov_b32_dpp v95, v43 row_ror:2 row_mask:0xf bank_mask:0xf
	s_and_saveexec_b64 s[0:1], s[10:11]
	s_xor_b64 s[74:75], exec, s[0:1]
	s_cbranch_execz .LBB0_1422
	v_cndmask_b32_e64 v213, 0, v207, s[6:7]
	v_cndmask_b32_e64 v212, 0, v205, s[6:7]
	v_cndmask_b32_e64 v211, 0, v202, s[8:9]
	v_cndmask_b32_e64 v210, 0, v196, s[8:9]
	s_waitcnt vmcnt(4)
	v_pk_fma_f32 v[212:213], v[10:11], v[212:213], v[14:15]
	v_cndmask_b32_e64 v215, 0, v203, s[6:7]
	v_pk_fma_f32 v[210:211], v[2:3], v[210:211], v[212:213]
	v_cndmask_b32_e64 v214, 0, v197, s[6:7]
	v_pk_fma_f32 v[38:39], v[6:7], v[38:39], v[210:211]
	s_waitcnt vmcnt(0)
	v_pk_fma_f32 v[210:211], v[28:29], v[92:93], v[32:33]
	v_cndmask_b32_e64 v209, 0, v199, s[8:9]
	v_pk_fma_f32 v[210:211], v[20:21], v[88:89], v[210:211]
	v_cndmask_b32_e64 v208, 0, v193, s[8:9]
	v_pk_fma_f32 v[40:41], v[24:25], v[40:41], v[210:211]
	v_pk_fma_f32 v[214:215], v[8:9], v[214:215], v[12:13]
	v_and_b32_e32 v213, 0x7fffffff, v41
	v_and_b32_e32 v212, 0x7fffffff, v40
	v_pk_fma_f32 v[212:213], v[212:213], s[52:53], 1.0 op_sel_hi:[1,0,0]
	v_pk_fma_f32 v[208:209], v[0:1], v[208:209], v[214:215]
	v_rcp_f32_e32 v212, v212
	v_rcp_f32_e32 v213, v213
	v_pk_mul_f32 v[210:211], v[40:41], v[40:41]
	v_mov_b64_e32 v[214:215], s[56:57]
	v_pk_mul_f32 v[210:211], v[210:211], s[42:43] op_sel_hi:[1,0]
	v_pk_fma_f32 v[216:217], v[212:213], s[54:55], v[214:215] op_sel_hi:[1,0,0]
	v_exp_f32_e32 v210, v210
	v_exp_f32_e32 v211, v211
	v_pk_fma_f32 v[216:217], v[212:213], v[216:217], s[58:59] op_sel_hi:[1,1,0]
	v_pk_fma_f32 v[36:37], v[4:5], v[36:37], v[208:209]
	v_pk_fma_f32 v[216:217], v[212:213], v[216:217], s[60:61] op_sel_hi:[1,1,0]
	v_pk_fma_f32 v[208:209], v[30:31], v[94:95], v[34:35]
	v_pk_fma_f32 v[216:217], v[212:213], v[216:217], s[62:63] op_sel_hi:[1,1,0]
	v_pk_fma_f32 v[208:209], v[22:23], v[90:91], v[208:209]
	v_pk_mul_f32 v[212:213], v[212:213], v[216:217]
	v_cmp_gt_f32_e64 s[0:1], 0, v40
	v_pk_mul_f32 v[210:211], v[210:211], v[212:213]
	v_pk_fma_f32 v[42:43], v[26:27], v[42:43], v[208:209]
	v_pk_mul_f32 v[212:213], v[40:41], v[210:211]
	v_pk_fma_f32 v[210:211], v[40:41], v[210:211], v[40:41] neg_lo:[1,0,0] neg_hi:[1,0,0]
	v_pk_mul_f32 v[208:209], v[42:43], v[42:43]
	v_cndmask_b32_e64 v40, v210, v212, s[0:1]
	v_cmp_gt_f32_e64 s[0:1], 0, v41
	v_and_b32_e32 v210, 0x7fffffff, v42
	v_pk_mul_f32 v[208:209], v[208:209], s[42:43] op_sel_hi:[1,0]
	v_cndmask_b32_e64 v41, v211, v213, s[0:1]
	v_and_b32_e32 v211, 0x7fffffff, v43
	v_pk_fma_f32 v[210:211], v[210:211], s[52:53], 1.0 op_sel_hi:[1,0,0]
	v_exp_f32_e32 v208, v208
	v_rcp_f32_e32 v210, v210
	v_rcp_f32_e32 v211, v211
	v_exp_f32_e32 v209, v209
	v_cmp_gt_f32_e64 s[0:1], 0, v42
	v_pk_mul_f32 v[36:37], v[36:37], v[40:41]
	v_pk_fma_f32 v[212:213], v[210:211], s[54:55], v[214:215] op_sel_hi:[1,0,0]
	v_cvt_pk_bf16_f32 v36, v36, v37
	s_nop 0
	v_pk_fma_f32 v[212:213], v[210:211], v[212:213], s[58:59] op_sel_hi:[1,1,0]
	s_nop 0
	v_pk_fma_f32 v[212:213], v[210:211], v[212:213], s[60:61] op_sel_hi:[1,1,0]
	s_nop 0
	v_pk_fma_f32 v[212:213], v[210:211], v[212:213], s[62:63] op_sel_hi:[1,1,0]
	s_nop 0
	v_pk_mul_f32 v[210:211], v[210:211], v[212:213]
	s_nop 0
	v_pk_mul_f32 v[208:209], v[208:209], v[210:211]
	s_nop 0
	v_pk_mul_f32 v[210:211], v[42:43], v[208:209]
	v_pk_fma_f32 v[208:209], v[42:43], v[208:209], v[42:43] neg_lo:[1,0,0] neg_hi:[1,0,0]
	s_nop 0
	v_cndmask_b32_e64 v42, v208, v210, s[0:1]
	v_cmp_gt_f32_e64 s[0:1], 0, v43
	s_nop 1
	v_cndmask_b32_e64 v43, v209, v211, s[0:1]
	v_pk_mul_f32 v[38:39], v[38:39], v[42:43]
	s_nop 0
	v_cvt_pk_bf16_f32 v37, v38, v39
	v_mad_u64_u32 v[38:39], s[0:1], v146, s86, v[46:47]
	v_mov_b32_e32 v39, v137
	v_lshl_add_u64 v[38:39], v[38:39], 1, s[26:27]
	s_cmp_lg_u32 s99, 0
	s_cbranch_scc1 .Lwt1403_36335
	global_store_dwordx2 v[38:39], v[36:37], off
	s_branch .Lwj1403_36335

; __device__ __forceinline__ f32x4 gelu4(f32x4 v) { const f32x2 a = gelu_pk((f32x2){v[0], v[1]}), b = gelu_pk((f32x2){v[2], v[3]}); return (f32x4){a.x, a.y, b.x, b.y}; }
; __device__ __forceinline__ u32x2 pack4(f32x4 v) { return (u32x2){pk2(v[0], v[1]), pk2(v[2], v[3])}; }
;     __device__ __forceinline__ void operator()(AccRef acc, const Unit& u, int wr, int wc, int fr, int fq) const {
;     ...
;                         if (m == 0 && fr < 2) *(f32x4*)(edge + (unsigned)((grp * 4 + fr) * UPN + jn)) = ag;
;                         if (m == 3 && fr >= 14) *(f32x4*)(edge + (unsigned)((grp * 4 + (fr - 12)) * UPN + jn)) = ag;
;                         const f32x4 o = gelu4(bg + wg0 * g2 + wg1 * g1 + wg2 * ag) * cu[m];
;                         if (!(m == 0 && fr < 2)) *(u32x2*)(act + (unsigned)(row * DFF + jn)) = pack4(o);
.Lwj1403_36335:
.LBB0_1422:
	s_andn2_saveexec_b64 s[0:1], s[74:75]
	s_cbranch_execz .LBB0_1424
	v_add_u32_e32 v136, v46, v175
	v_lshl_add_u64 v[36:37], v[136:137], 2, s[28:29]
	s_cmp_lg_u32 s99, 0
	s_cbranch_scc1 .Lwt1403_36342
	global_store_dwordx4 v[36:37], v[40:43], off
	s_branch .Lwj1403_36342

; __device__ __forceinline__ f32x4 gelu4(f32x4 v) { const f32x2 a = gelu_pk((f32x2){v[0], v[1]}), b = gelu_pk((f32x2){v[2], v[3]}); return (f32x4){a.x, a.y, b.x, b.y}; }
; __device__ __forceinline__ f32x4 ror1v(f32x4 v) { return (f32x4){dpp_ror1(v[0]), dpp_ror1(v[1]), dpp_ror1(v[2]), dpp_ror1(v[3])}; }
; __device__ __forceinline__ f32x4 ror2v(f32x4 v) { return (f32x4){dpp_ror2(v[0]), dpp_ror2(v[1]), dpp_ror2(v[2]), dpp_ror2(v[3])}; }
; __device__ __forceinline__ u32x2 pack4(f32x4 v) { return (u32x2){pk2(v[0], v[1]), pk2(v[2], v[3])}; }
; __device__ __forceinline__ f32x4 unpack4(u32x2 w) { return (f32x4){bflo(w.x), bfhi(w.x), bflo(w.y), bfhi(w.y)}; }
;     __device__ __forceinline__ void operator()(AccRef acc, const Unit& u, int wr, int wc, int fr, int fq) const {
;     ...
;                     for (int m = 0; m < 4; ++m) { const int row = rowg + m * 16 + fr;
;                         const f32x4 ag = unpack4(pa[ai][0][m][n]);
;                         const f32x4 rg1 = ror1v(ag), rg2 = ror2v(ag);
;                         const f32x4 g1 = fr >= 1 ? rg1 : pg1, g2 = fr >= 2 ? rg2 : pg2;
;                         if (m == 0 && fr < 2) *(f32x4*)(edge + (unsigned)((grp * 4 + fr) * UPN + jn)) = ag;
;                         if (m == 3 && fr >= 14) *(f32x4*)(edge + (unsigned)((grp * 4 + (fr - 12)) * UPN + jn)) = ag;
;                         const f32x4 o = gelu4(bg + wg0 * g2 + wg1 * g1 + wg2 * ag) * cu[m];
;                         if (!(m == 0 && fr < 2)) *(u32x2*)(act + (unsigned)(row * DFF + jn)) = pack4(o);
;                         pg1 = rg1; pg2 = rg2; }
.Lwj1403_36342:
.LBB0_1424:
	s_or_b64 exec, exec, s[0:1]
	s_nop 0
	v_cndmask_b32_e64 v41, v207, v206, s[6:7]
	v_cndmask_b32_e64 v40, v205, v204, s[6:7]
	v_cndmask_b32_e64 v43, v203, v201, s[6:7]
	v_cndmask_b32_e64 v42, v197, v195, s[6:7]
	v_cndmask_b32_e64 v37, v199, v198, s[8:9]
	v_cndmask_b32_e64 v36, v193, v192, s[8:9]
	v_cndmask_b32_e64 v39, v202, v200, s[8:9]
	v_cndmask_b32_e64 v38, v196, v194, s[8:9]
	s_waitcnt vmcnt(4)
	v_pk_fma_f32 v[42:43], v[8:9], v[42:43], v[12:13]
	v_pk_fma_f32 v[40:41], v[10:11], v[40:41], v[14:15]
	v_pk_fma_f32 v[36:37], v[0:1], v[36:37], v[42:43]
	v_pk_fma_f32 v[38:39], v[2:3], v[38:39], v[40:41]
	v_pk_fma_f32 v[36:37], v[4:5], v[86:87], v[36:37]
	v_pk_fma_f32 v[38:39], v[6:7], v[84:85], v[38:39]
	v_cndmask_b32_e64 v85, v206, v183, s[6:7]
	v_cndmask_b32_e64 v84, v204, v182, s[6:7]
	v_cndmask_b32_e64 v87, v201, v181, s[6:7]
	v_cndmask_b32_e64 v86, v195, v178, s[6:7]
	v_cndmask_b32_e64 v41, v198, v179, s[8:9]
	v_cndmask_b32_e64 v40, v192, v173, s[8:9]
	v_cndmask_b32_e64 v43, v200, v180, s[8:9]
	v_cndmask_b32_e64 v42, v194, v174, s[8:9]
	v_pk_fma_f32 v[86:87], v[8:9], v[86:87], v[12:13]
	v_pk_fma_f32 v[84:85], v[10:11], v[84:85], v[14:15]
	v_pk_fma_f32 v[40:41], v[0:1], v[40:41], v[86:87]
	v_pk_fma_f32 v[42:43], v[2:3], v[42:43], v[84:85]
	v_pk_fma_f32 v[82:83], v[4:5], v[82:83], v[40:41]
	v_pk_fma_f32 v[84:85], v[6:7], v[80:81], v[42:43]
	v_lshlrev_b32_e32 v40, 16, v170
	v_and_b32_e32 v41, 0xffff0000, v170
	v_lshlrev_b32_e32 v42, 16, v169
	v_and_b32_e32 v43, 0xffff0000, v169
	s_nop 1
	v_mov_b32_dpp v146, v40 row_ror:1 row_mask:0xf bank_mask:0xf
	v_mov_b32_dpp v169, v41 row_ror:1 row_mask:0xf bank_mask:0xf
	v_mov_b32_dpp v172, v40 row_ror:2 row_mask:0xf bank_mask:0xf
	v_mov_b32_dpp v175, v41 row_ror:2 row_mask:0xf bank_mask:0xf
	v_cndmask_b32_e64 v87, v89, v169, s[8:9]
	v_cndmask_b32_e64 v86, v88, v146, s[8:9]
	v_cndmask_b32_e64 v89, v93, v175, s[6:7]
	v_cndmask_b32_e64 v88, v92, v172, s[6:7]
	s_waitcnt vmcnt(2)
	v_pk_fma_f32 v[88:89], v[28:29], v[88:89], v[32:33]
	s_nop 1
	v_pk_fma_f32 v[86:87], v[20:21], v[86:87], v[88:89]
	s_nop 1
	v_pk_fma_f32 v[40:41], v[24:25], v[40:41], v[86:87]
	s_nop 1
	v_and_b32_e32 v89, 0x7fffffff, v41
	v_and_b32_e32 v88, 0x7fffffff, v40
	s_nop 1
	v_pk_fma_f32 v[88:89], v[88:89], s[52:53], 1.0 op_sel_hi:[1,0,0]
	v_mov_b32_dpp v170, v42 row_ror:1 row_mask:0xf bank_mask:0xf
	v_mov_b32_dpp v171, v43 row_ror:1 row_mask:0xf bank_mask:0xf
	v_mov_b32_dpp v192, v42 row_ror:2 row_mask:0xf bank_mask:0xf
	v_mov_b32_dpp v193, v43 row_ror:2 row_mask:0xf bank_mask:0xf
	v_rcp_f32_e32 v88, v88
	v_rcp_f32_e32 v89, v89
	v_cndmask_b32_e64 v81, v91, v171, s[8:9]
	v_cndmask_b32_e64 v80, v90, v170, s[8:9]
	v_cndmask_b32_e64 v91, v95, v193, s[6:7]
	v_cndmask_b32_e64 v90, v94, v192, s[6:7]
	v_pk_fma_f32 v[90:91], v[30:31], v[90:91], v[34:35]
	v_pk_mul_f32 v[86:87], v[40:41], v[40:41]
	v_pk_fma_f32 v[80:81], v[22:23], v[80:81], v[90:91]
	v_mov_b64_e32 v[90:91], s[56:57]
	v_pk_mul_f32 v[86:87], v[86:87], s[42:43] op_sel_hi:[1,0]
	v_pk_fma_f32 v[92:93], v[88:89], s[54:55], v[90:91] op_sel_hi:[1,0,0]
	v_exp_f32_e32 v86, v86
	v_exp_f32_e32 v87, v87
	v_pk_fma_f32 v[92:93], v[88:89], v[92:93], s[58:59] op_sel_hi:[1,1,0]
	v_cmp_gt_f32_e64 s[0:1], 0, v40
	v_pk_fma_f32 v[92:93], v[88:89], v[92:93], s[60:61] op_sel_hi:[1,1,0]
	v_pk_fma_f32 v[42:43], v[26:27], v[42:43], v[80:81]
	v_pk_fma_f32 v[92:93], v[88:89], v[92:93], s[62:63] op_sel_hi:[1,1,0]
	v_pk_mul_f32 v[80:81], v[42:43], v[42:43]
	v_pk_mul_f32 v[88:89], v[88:89], v[92:93]
	v_pk_mul_f32 v[80:81], v[80:81], s[42:43] op_sel_hi:[1,0]
	v_pk_mul_f32 v[86:87], v[86:87], v[88:89]
	v_exp_f32_e32 v80, v80
	v_pk_mul_f32 v[88:89], v[40:41], v[86:87]
	v_pk_fma_f32 v[86:87], v[40:41], v[86:87], v[40:41] neg_lo:[1,0,0] neg_hi:[1,0,0]
	v_exp_f32_e32 v81, v81
	v_cndmask_b32_e64 v40, v86, v88, s[0:1]
	v_cmp_gt_f32_e64 s[0:1], 0, v41
	v_and_b32_e32 v86, 0x7fffffff, v42
	v_add_u32_e32 v136, v45, v46
	v_cndmask_b32_e64 v41, v87, v89, s[0:1]
	v_and_b32_e32 v87, 0x7fffffff, v43
	v_pk_fma_f32 v[86:87], v[86:87], s[52:53], 1.0 op_sel_hi:[1,0,0]
	v_cmp_gt_f32_e64 s[0:1], 0, v42
	v_rcp_f32_e32 v86, v86
	v_rcp_f32_e32 v87, v87
	v_pk_mul_f32 v[36:37], v[36:37], v[40:41]
	s_nop 1
	v_cvt_pk_bf16_f32 v36, v36, v37
	v_pk_fma_f32 v[88:89], v[86:87], s[54:55], v[90:91] op_sel_hi:[1,0,0]
	s_nop 1
	v_pk_fma_f32 v[88:89], v[86:87], v[88:89], s[58:59] op_sel_hi:[1,1,0]
	s_nop 1
	v_pk_fma_f32 v[88:89], v[86:87], v[88:89], s[60:61] op_sel_hi:[1,1,0]
	s_nop 1
	v_pk_fma_f32 v[88:89], v[86:87], v[88:89], s[62:63] op_sel_hi:[1,1,0]
	s_nop 0
	v_pk_mul_f32 v[86:87], v[86:87], v[88:89]
	s_nop 0
	v_pk_mul_f32 v[80:81], v[80:81], v[86:87]
	s_nop 0
	v_pk_mul_f32 v[86:87], v[42:43], v[80:81]
	v_pk_fma_f32 v[80:81], v[42:43], v[80:81], v[42:43] neg_lo:[1,0,0] neg_hi:[1,0,0]
	s_nop 0
	v_cndmask_b32_e64 v42, v80, v86, s[0:1]
	v_cmp_gt_f32_e64 s[0:1], 0, v43
	s_nop 1
	s_nop 0
	v_cndmask_b32_e64 v43, v81, v87, s[0:1]
	v_pk_mul_f32 v[38:39], v[38:39], v[42:43]
	s_nop 1
	v_cvt_pk_bf16_f32 v37, v38, v39
	v_lshl_add_u64 v[38:39], v[136:137], 1, s[26:27]
	s_cmp_lg_u32 s99, 0
	s_cbranch_scc1 .Lwt1403_36471
	global_store_dwordx2 v[38:39], v[36:37], off
	s_branch .Lwj1403_36471

; __device__ __forceinline__ f32x4 gelu4(f32x4 v) { const f32x2 a = gelu_pk((f32x2){v[0], v[1]}), b = gelu_pk((f32x2){v[2], v[3]}); return (f32x4){a.x, a.y, b.x, b.y}; }
; __device__ __forceinline__ f32x4 ror1v(f32x4 v) { return (f32x4){dpp_ror1(v[0]), dpp_ror1(v[1]), dpp_ror1(v[2]), dpp_ror1(v[3])}; }
; __device__ __forceinline__ f32x4 ror2v(f32x4 v) { return (f32x4){dpp_ror2(v[0]), dpp_ror2(v[1]), dpp_ror2(v[2]), dpp_ror2(v[3])}; }
; __device__ __forceinline__ u32x2 pack4(f32x4 v) { return (u32x2){pk2(v[0], v[1]), pk2(v[2], v[3])}; }
; __device__ __forceinline__ f32x4 unpack4(u32x2 w) { return (f32x4){bflo(w.x), bfhi(w.x), bflo(w.y), bfhi(w.y)}; }
;     __device__ __forceinline__ void operator()(AccRef acc, const Unit& u, int wr, int wc, int fr, int fq) const {
;     ...
;                     for (int m = 0; m < 4; ++m) { const int row = rowg + m * 16 + fr;
;                         const f32x4 ag = unpack4(pa[ai][0][m][n]);
;                         const f32x4 rg1 = ror1v(ag), rg2 = ror2v(ag);
;                         const f32x4 g1 = fr >= 1 ? rg1 : pg1, g2 = fr >= 2 ? rg2 : pg2;
;                         if (m == 0 && fr < 2) *(f32x4*)(edge + (unsigned)((grp * 4 + fr) * UPN + jn)) = ag;
;                         if (m == 3 && fr >= 14) *(f32x4*)(edge + (unsigned)((grp * 4 + (fr - 12)) * UPN + jn)) = ag;
;                         const f32x4 o = gelu4(bg + wg0 * g2 + wg1 * g1 + wg2 * ag) * cu[m];
;                         if (!(m == 0 && fr < 2)) *(u32x2*)(act + (unsigned)(row * DFF + jn)) = pack4(o);
;                         pg1 = rg1; pg2 = rg2; }
.Lwj1403_36471:
	v_lshlrev_b32_e32 v36, 16, v167
	v_and_b32_e32 v37, 0xffff0000, v167
	v_lshlrev_b32_e32 v38, 16, v168
	v_mov_b32_dpp v43, v36 row_ror:2 row_mask:0xf bank_mask:0xf
	v_mov_b32_dpp v80, v37 row_ror:2 row_mask:0xf bank_mask:0xf
	v_mov_b32_dpp v40, v36 row_ror:1 row_mask:0xf bank_mask:0xf
	v_mov_b32_dpp v41, v37 row_ror:1 row_mask:0xf bank_mask:0xf
	v_cndmask_b32_e64 v93, v175, v80, s[6:7]
	v_cndmask_b32_e64 v92, v172, v43, s[6:7]
	v_cndmask_b32_e64 v89, v169, v41, s[8:9]
	v_cndmask_b32_e64 v88, v146, v40, s[8:9]
	v_pk_fma_f32 v[92:93], v[28:29], v[92:93], v[32:33]
	v_and_b32_e32 v39, 0xffff0000, v168
	v_pk_fma_f32 v[88:89], v[20:21], v[88:89], v[92:93]
	s_nop 1
	v_pk_fma_f32 v[36:37], v[24:25], v[36:37], v[88:89]
	s_nop 1
	v_and_b32_e32 v93, 0x7fffffff, v37
	v_and_b32_e32 v92, 0x7fffffff, v36
	v_pk_fma_f32 v[92:93], v[92:93], s[52:53], 1.0 op_sel_hi:[1,0,0]
	v_mov_b32_dpp v45, v38 row_ror:2 row_mask:0xf bank_mask:0xf
	v_rcp_f32_e32 v92, v92
	v_rcp_f32_e32 v93, v93
	v_mov_b32_dpp v81, v39 row_ror:2 row_mask:0xf bank_mask:0xf
	v_mov_b32_dpp v42, v38 row_ror:1 row_mask:0xf bank_mask:0xf
	v_mov_b32_dpp v47, v39 row_ror:1 row_mask:0xf bank_mask:0xf
	v_cndmask_b32_e64 v95, v193, v81, s[6:7]
	v_cndmask_b32_e64 v94, v192, v45, s[6:7]
	v_cndmask_b32_e64 v87, v171, v47, s[8:9]
	v_cndmask_b32_e64 v86, v170, v42, s[8:9]
	v_pk_fma_f32 v[94:95], v[30:31], v[94:95], v[34:35]
	v_pk_mul_f32 v[88:89], v[36:37], v[36:37]
	v_pk_fma_f32 v[86:87], v[22:23], v[86:87], v[94:95]
	v_pk_mul_f32 v[88:89], v[88:89], s[42:43] op_sel_hi:[1,0]
	v_pk_fma_f32 v[94:95], v[92:93], s[54:55], v[90:91] op_sel_hi:[1,0,0]
	v_exp_f32_e32 v88, v88
	v_exp_f32_e32 v89, v89
	v_pk_fma_f32 v[94:95], v[92:93], v[94:95], s[58:59] op_sel_hi:[1,1,0]
	v_cmp_gt_f32_e64 s[0:1], 0, v36
	v_pk_fma_f32 v[94:95], v[92:93], v[94:95], s[60:61] op_sel_hi:[1,1,0]
	v_pk_fma_f32 v[38:39], v[26:27], v[38:39], v[86:87]
	v_pk_fma_f32 v[94:95], v[92:93], v[94:95], s[62:63] op_sel_hi:[1,1,0]
	v_pk_mul_f32 v[86:87], v[38:39], v[38:39]
	v_pk_mul_f32 v[92:93], v[92:93], v[94:95]
	v_pk_mul_f32 v[86:87], v[86:87], s[42:43] op_sel_hi:[1,0]
	v_pk_mul_f32 v[88:89], v[88:89], v[92:93]
	v_exp_f32_e32 v86, v86
	v_pk_mul_f32 v[92:93], v[36:37], v[88:89]
	v_pk_fma_f32 v[88:89], v[36:37], v[88:89], v[36:37] neg_lo:[1,0,0] neg_hi:[1,0,0]
	v_exp_f32_e32 v87, v87
	v_cndmask_b32_e64 v36, v88, v92, s[0:1]
	v_cmp_gt_f32_e64 s[0:1], 0, v37
	v_and_b32_e32 v88, 0x7fffffff, v38
	v_add_u32_e32 v136, v148, v46
	v_cndmask_b32_e64 v37, v89, v93, s[0:1]
	v_and_b32_e32 v89, 0x7fffffff, v39
	v_pk_fma_f32 v[88:89], v[88:89], s[52:53], 1.0 op_sel_hi:[1,0,0]
	v_cmp_gt_f32_e64 s[0:1], 0, v38
	v_rcp_f32_e32 v88, v88
	v_rcp_f32_e32 v89, v89
	v_pk_mul_f32 v[36:37], v[82:83], v[36:37]
	s_nop 1
	v_cvt_pk_bf16_f32 v36, v36, v37
	v_pk_fma_f32 v[90:91], v[88:89], s[54:55], v[90:91] op_sel_hi:[1,0,0]
	s_nop 1
	v_pk_fma_f32 v[90:91], v[88:89], v[90:91], s[58:59] op_sel_hi:[1,1,0]
	s_nop 0
	v_pk_fma_f32 v[90:91], v[88:89], v[90:91], s[60:61] op_sel_hi:[1,1,0]
	s_nop 0
	v_pk_fma_f32 v[90:91], v[88:89], v[90:91], s[62:63] op_sel_hi:[1,1,0]
	s_nop 0
	v_pk_mul_f32 v[88:89], v[88:89], v[90:91]
	s_nop 0
	v_pk_mul_f32 v[86:87], v[86:87], v[88:89]
	s_nop 0
	v_pk_mul_f32 v[88:89], v[38:39], v[86:87]
	v_pk_fma_f32 v[86:87], v[38:39], v[86:87], v[38:39] neg_lo:[1,0,0] neg_hi:[1,0,0]
	s_nop 0
	v_cndmask_b32_e64 v38, v86, v88, s[0:1]
	v_cmp_gt_f32_e64 s[0:1], 0, v39
	s_nop 1
	v_cndmask_b32_e64 v39, v87, v89, s[0:1]
	v_pk_mul_f32 v[38:39], v[84:85], v[38:39]
	s_nop 1
	v_cvt_pk_bf16_f32 v37, v38, v39
	v_lshl_add_u64 v[38:39], v[136:137], 1, s[26:27]
	s_cmp_lg_u32 s99, 0
	s_cbranch_scc1 .Lwt1403_36562
	global_store_dwordx2 v[38:39], v[36:37], off
	s_branch .Lwj1403_36562

;     __device__ __forceinline__ void operator()(AccRef acc, const Unit& u, int wr, int wc, int fr, int fq) const {
;     ...
;         for (int ai = 0; ai < 2; ++ai) {
;             const int rowg = u.pm * 256 + ai * 128 + wr * 64; const int grp = rowg >> 6;
; #pragma unroll
;             for (int n = 0; n < 2; ++n) { const unsigned jn = (unsigned)(j0 + 4 * n);
;                 f32x4 cu[4];
;                 {
;                     const f32x4 wu0 = *(const f32x4*)(cw + (DFF + jn)), wu1 = *(const f32x4*)(cw + (UPN + DFF + jn)), wu2 = *(const f32x4*)(cw + (2 * UPN + DFF + jn)), bu = *(const f32x4*)(cb + (DFF + jn));
;                     f32x4 pu1 = (f32x4){0.f, 0.f, 0.f, 0.f}, pu2 = pu1;
; #pragma unroll
;                     for (int m = 0; m < 4; ++m) {
;                         const f32x4 au = unpack4(pa[ai][1][m][n]);
;                         const f32x4 ru1 = ror1v(au), ru2 = ror2v(au);
;                         const f32x4 u1 = fr >= 1 ? ru1 : pu1, u2 = fr >= 2 ? ru2 : pu2;
;                         if (m == 0 && fr < 2) *(f32x4*)(edge + (unsigned)((grp * 4 + fr) * UPN + DFF + jn)) = au;
;                         if (m == 3 && fr >= 14) *(f32x4*)(edge + (unsigned)((grp * 4 + (fr - 12)) * UPN + DFF + jn)) = au;
;                         cu[m] = bu + wu0 * u2 + wu1 * u1 + wu2 * au;
;                         pu1 = ru1; pu2 = ru2; }
;                 }
;                 {
;                     const f32x4 wg0 = *(const f32x4*)(cw + jn), wg1 = *(const f32x4*)(cw + (UPN + jn)), wg2 = *(const f32x4*)(cw + (2 * UPN + jn)), bg = *(const f32x4*)(cb + jn);
;                     f32x4 pg1 = (f32x4){0.f, 0.f, 0.f, 0.f}, pg2 = pg1;
; #pragma unroll
;                     for (int m = 0; m < 4; ++m) { const int row = rowg + m * 16 + fr;
;                         const f32x4 ag = unpack4(pa[ai][0][m][n]);
;                         const f32x4 rg1 = ror1v(ag), rg2 = ror2v(ag);
;                         const f32x4 g1 = fr >= 1 ? rg1 : pg1, g2 = fr >= 2 ? rg2 : pg2;
;                         if (m == 0 && fr < 2) *(f32x4*)(edge + (unsigned)((grp * 4 + fr) * UPN + jn)) = ag;
;                         if (m == 3 && fr >= 14) *(f32x4*)(edge + (unsigned)((grp * 4 + (fr - 12)) * UPN + jn)) = ag;
;                         const f32x4 o = gelu4(bg + wg0 * g2 + wg1 * g1 + wg2 * ag) * cu[m];
.Lwj1403_36562:
	v_lshlrev_b32_e32 v36, 16, v147
	v_and_b32_e32 v37, 0xffff0000, v147
	v_lshlrev_b32_e32 v38, 16, v149
	v_and_b32_e32 v39, 0xffff0000, v149
	s_nop 1
	v_mov_b32_dpp v82, v36 row_ror:1 row_mask:0xf bank_mask:0xf
	v_mov_b32_dpp v83, v37 row_ror:1 row_mask:0xf bank_mask:0xf
	v_mov_b32_dpp v84, v38 row_ror:1 row_mask:0xf bank_mask:0xf
	v_mov_b32_dpp v87, v39 row_ror:1 row_mask:0xf bank_mask:0xf
	v_mov_b32_dpp v85, v36 row_ror:2 row_mask:0xf bank_mask:0xf
	v_mov_b32_dpp v88, v37 row_ror:2 row_mask:0xf bank_mask:0xf
	v_mov_b32_dpp v86, v38 row_ror:2 row_mask:0xf bank_mask:0xf
	v_mov_b32_dpp v89, v39 row_ror:2 row_mask:0xf bank_mask:0xf
	s_and_saveexec_b64 s[0:1], vcc
	s_cbranch_execz .LBB0_1426
	v_add_u32_e32 v136, v46, v152
	v_lshl_add_u64 v[90:91], v[136:137], 2, s[28:29]
	s_cmp_lg_u32 s99, 0
	s_cbranch_scc1 .Lwt1403_36581
	global_store_dwordx4 v[90:91], v[36:39], off
	s_branch .Lwj1403_36581
.Lwt1403_36581:
	global_store_dwordx4 v[90:91], v[36:39], off sc1
.Lwj1403_36581:
.LBB0_1426:
	s_or_b64 exec, exec, s[0:1]
	v_cndmask_b32_e64 v91, v47, v87, s[8:9]
	v_cndmask_b32_e64 v90, v42, v84, s[8:9]
	v_cndmask_b32_e64 v42, v45, v86, s[6:7]
	v_cndmask_b32_e64 v87, v183, v191, s[6:7]
	v_cndmask_b32_e64 v86, v182, v190, s[6:7]
	v_cndmask_b32_e64 v40, v40, v82, s[8:9]
	v_cndmask_b32_e64 v82, v43, v85, s[6:7]
	v_cndmask_b32_e64 v85, v180, v188, s[8:9]
	v_cndmask_b32_e64 v84, v174, v185, s[8:9]
	v_pk_fma_f32 v[10:11], v[10:11], v[86:87], v[14:15]
	v_cndmask_b32_e64 v41, v41, v83, s[8:9]
	v_cndmask_b32_e64 v83, v80, v88, s[6:7]
	v_pk_fma_f32 v[2:3], v[2:3], v[84:85], v[10:11]
	v_cndmask_b32_e64 v43, v81, v89, s[6:7]
	v_pk_fma_f32 v[2:3], v[6:7], v[18:19], v[2:3]
	v_pk_fma_f32 v[6:7], v[28:29], v[82:83], v[32:33]
	v_cndmask_b32_e64 v89, v181, v189, s[6:7]
	v_pk_fma_f32 v[6:7], v[20:21], v[40:41], v[6:7]
	v_cndmask_b32_e64 v88, v178, v186, s[6:7]
	v_pk_fma_f32 v[6:7], v[24:25], v[36:37], v[6:7]
	v_pk_fma_f32 v[8:9], v[8:9], v[88:89], v[12:13]
	v_and_b32_e32 v13, 0x7fffffff, v7
	v_and_b32_e32 v12, 0x7fffffff, v6
	v_pk_fma_f32 v[12:13], v[12:13], s[52:53], 1.0 op_sel_hi:[1,0,0]
	v_cndmask_b32_e64 v81, v179, v187, s[8:9]
	v_rcp_f32_e32 v12, v12
	v_rcp_f32_e32 v13, v13
	v_cndmask_b32_e64 v80, v173, v184, s[8:9]
	v_pk_fma_f32 v[0:1], v[0:1], v[80:81], v[8:9]
	v_pk_mul_f32 v[10:11], v[6:7], v[6:7]
	v_mov_b64_e32 v[14:15], s[56:57]
	v_pk_fma_f32 v[0:1], v[4:5], v[16:17], v[0:1]
	v_pk_mul_f32 v[10:11], v[10:11], s[42:43] op_sel_hi:[1,0]
	v_pk_fma_f32 v[16:17], v[12:13], s[54:55], v[14:15] op_sel_hi:[1,0,0]
	v_exp_f32_e32 v10, v10
	v_exp_f32_e32 v11, v11
	v_pk_fma_f32 v[16:17], v[12:13], v[16:17], s[58:59] op_sel_hi:[1,1,0]
	v_pk_fma_f32 v[4:5], v[30:31], v[42:43], v[34:35]
	v_pk_fma_f32 v[16:17], v[12:13], v[16:17], s[60:61] op_sel_hi:[1,1,0]
	v_pk_fma_f32 v[4:5], v[22:23], v[90:91], v[4:5]
	v_pk_fma_f32 v[16:17], v[12:13], v[16:17], s[62:63] op_sel_hi:[1,1,0]
	v_cmp_gt_f32_e64 s[0:1], 0, v6
	v_pk_mul_f32 v[12:13], v[12:13], v[16:17]
	v_pk_fma_f32 v[4:5], v[26:27], v[38:39], v[4:5]
	v_pk_mul_f32 v[10:11], v[10:11], v[12:13]
	v_pk_mul_f32 v[8:9], v[4:5], v[4:5]
	v_pk_mul_f32 v[12:13], v[6:7], v[10:11]
	v_pk_fma_f32 v[10:11], v[6:7], v[10:11], v[6:7] neg_lo:[1,0,0] neg_hi:[1,0,0]
	v_pk_mul_f32 v[8:9], v[8:9], s[42:43] op_sel_hi:[1,0]
	v_cndmask_b32_e64 v6, v10, v12, s[0:1]
	v_cmp_gt_f32_e64 s[0:1], 0, v7
	v_and_b32_e32 v10, 0x7fffffff, v4
	v_exp_f32_e32 v8, v8
	v_cndmask_b32_e64 v7, v11, v13, s[0:1]
	v_and_b32_e32 v11, 0x7fffffff, v5
	v_pk_fma_f32 v[10:11], v[10:11], s[52:53], 1.0 op_sel_hi:[1,0,0]
	v_exp_f32_e32 v9, v9
	v_rcp_f32_e32 v10, v10
	v_rcp_f32_e32 v11, v11
	v_cmp_gt_f32_e64 s[0:1], 0, v4
	v_pk_mul_f32 v[0:1], v[0:1], v[6:7]
	v_add_u32_e32 v136, v177, v46
	v_pk_fma_f32 v[12:13], v[10:11], s[54:55], v[14:15] op_sel_hi:[1,0,0]
	v_cvt_pk_bf16_f32 v0, v0, v1
	s_addk_i32 s65, 0x80
	v_pk_fma_f32 v[12:13], v[10:11], v[12:13], s[58:59] op_sel_hi:[1,1,0]
	s_ashr_i32 s69, s65, 4
	v_pk_fma_f32 v[12:13], v[10:11], v[12:13], s[60:61] op_sel_hi:[1,1,0]
	v_add_u32_e32 v16, s69, v166
	v_pk_fma_f32 v[12:13], v[10:11], v[12:13], s[62:63] op_sel_hi:[1,1,0]
	v_mul_lo_u32 v80, v16, s85
	v_pk_mul_f32 v[10:11], v[10:11], v[12:13]
	v_lshlrev_b32_e32 v36, 16, v120
	v_pk_mul_f32 v[8:9], v[8:9], v[10:11]
	v_and_b32_e32 v37, 0xffff0000, v120
	v_pk_mul_f32 v[10:11], v[4:5], v[8:9]
	v_pk_fma_f32 v[8:9], v[4:5], v[8:9], v[4:5] neg_lo:[1,0,0] neg_hi:[1,0,0]
	v_lshlrev_b32_e32 v38, 16, v121
	v_cndmask_b32_e64 v4, v8, v10, s[0:1]
	v_cmp_gt_f32_e64 s[0:1], 0, v5
	v_and_b32_e32 v39, 0xffff0000, v121
	s_nop 1
	v_cndmask_b32_e64 v5, v9, v11, s[0:1]
	v_pk_mul_f32 v[2:3], v[2:3], v[4:5]
	s_nop 1
	v_cvt_pk_bf16_f32 v1, v2, v3
	v_lshl_add_u64 v[2:3], v[136:137], 1, s[26:27]
	s_cmp_lg_u32 s99, 0
	s_cbranch_scc1 .Lwt1403_36675
	global_store_dwordx2 v[2:3], v[0:1], off
	s_branch .Lwj1403_36675

; __device__ __forceinline__ f32x4 ror1v(f32x4 v) { return (f32x4){dpp_ror1(v[0]), dpp_ror1(v[1]), dpp_ror1(v[2]), dpp_ror1(v[3])}; }
; __device__ __forceinline__ f32x4 ror2v(f32x4 v) { return (f32x4){dpp_ror2(v[0]), dpp_ror2(v[1]), dpp_ror2(v[2]), dpp_ror2(v[3])}; }
; __device__ __forceinline__ f32x4 unpack4(u32x2 w) { return (f32x4){bflo(w.x), bfhi(w.x), bflo(w.y), bfhi(w.y)}; }
;     __device__ __forceinline__ void operator()(AccRef acc, const Unit& u, int wr, int wc, int fr, int fq) const {
;     ...
;         for (int ai = 0; ai < 2; ++ai) {
;             const int rowg = u.pm * 256 + ai * 128 + wr * 64; const int grp = rowg >> 6;
; #pragma unroll
;             for (int n = 0; n < 2; ++n) { const unsigned jn = (unsigned)(j0 + 4 * n);
;                 f32x4 cu[4];
;                 {
;                     const f32x4 wu0 = *(const f32x4*)(cw + (DFF + jn)), wu1 = *(const f32x4*)(cw + (UPN + DFF + jn)), wu2 = *(const f32x4*)(cw + (2 * UPN + DFF + jn)), bu = *(const f32x4*)(cb + (DFF + jn));
;                     f32x4 pu1 = (f32x4){0.f, 0.f, 0.f, 0.f}, pu2 = pu1;
; #pragma unroll
;                     for (int m = 0; m < 4; ++m) {
;                         const f32x4 au = unpack4(pa[ai][1][m][n]);
;                         const f32x4 ru1 = ror1v(au), ru2 = ror2v(au);
;                         const f32x4 u1 = fr >= 1 ? ru1 : pu1, u2 = fr >= 2 ? ru2 : pu2;
;                         if (m == 0 && fr < 2) *(f32x4*)(edge + (unsigned)((grp * 4 + fr) * UPN + DFF + jn)) = au;
;                         if (m == 3 && fr >= 14) *(f32x4*)(edge + (unsigned)((grp * 4 + (fr - 12)) * UPN + DFF + jn)) = au;
;                         cu[m] = bu + wu0 * u2 + wu1 * u1 + wu2 * au;
.Lwj1403_36675:
	global_load_dwordx4 v[8:11], v[48:49], off
	global_load_dwordx4 v[4:7], v[50:51], off
	s_nop 0
	global_load_dwordx4 v[0:3], v[52:53], off
	global_load_dwordx4 v[12:15], v[54:55], off
	s_nop 1
	v_add_u32_e32 v45, 0xb00, v80
	v_mov_b32_dpp v146, v36 row_ror:1 row_mask:0xf bank_mask:0xf
	v_mov_b32_dpp v149, v37 row_ror:1 row_mask:0xf bank_mask:0xf
	v_mov_b32_dpp v147, v38 row_ror:1 row_mask:0xf bank_mask:0xf
	v_mov_b32_dpp v167, v39 row_ror:1 row_mask:0xf bank_mask:0xf
	v_mov_b32_dpp v148, v36 row_ror:2 row_mask:0xf bank_mask:0xf
	v_mov_b32_dpp v168, v37 row_ror:2 row_mask:0xf bank_mask:0xf
	v_mov_b32_dpp v172, v38 row_ror:2 row_mask:0xf bank_mask:0xf
	v_mov_b32_dpp v174, v39 row_ror:2 row_mask:0xf bank_mask:0xf
	s_and_saveexec_b64 s[0:1], s[12:13]
	s_cbranch_execz .LBB0_1428
	v_add_u32_e32 v136, v45, v44
	v_lshl_add_u64 v[16:17], v[136:137], 2, s[28:29]
	s_cmp_lg_u32 s99, 0
	s_cbranch_scc1 .Lwt1403_36696
	global_store_dwordx4 v[16:17], v[36:39], off
	s_branch .Lwj1403_36696

; __device__ __forceinline__ f32x4 ror1v(f32x4 v) { return (f32x4){dpp_ror1(v[0]), dpp_ror1(v[1]), dpp_ror1(v[2]), dpp_ror1(v[3])}; }
; __device__ __forceinline__ f32x4 ror2v(f32x4 v) { return (f32x4){dpp_ror2(v[0]), dpp_ror2(v[1]), dpp_ror2(v[2]), dpp_ror2(v[3])}; }
; __device__ __forceinline__ f32x4 unpack4(u32x2 w) { return (f32x4){bflo(w.x), bfhi(w.x), bflo(w.y), bfhi(w.y)}; }
;     __device__ __forceinline__ void operator()(AccRef acc, const Unit& u, int wr, int wc, int fr, int fq) const {
;     ...
; #pragma unroll
;                     for (int m = 0; m < 4; ++m) {
;                         const f32x4 au = unpack4(pa[ai][1][m][n]);
;                         const f32x4 ru1 = ror1v(au), ru2 = ror2v(au);
;                         const f32x4 u1 = fr >= 1 ? ru1 : pu1, u2 = fr >= 2 ? ru2 : pu2;
;                         if (m == 0 && fr < 2) *(f32x4*)(edge + (unsigned)((grp * 4 + fr) * UPN + DFF + jn)) = au;
;                         if (m == 3 && fr >= 14) *(f32x4*)(edge + (unsigned)((grp * 4 + (fr - 12)) * UPN + DFF + jn)) = au;
;                         cu[m] = bu + wu0 * u2 + wu1 * u1 + wu2 * au;
;                         pu1 = ru1; pu2 = ru2; }
.Lwj1403_36696:
.LBB0_1428:
	s_or_b64 exec, exec, s[0:1]
	v_add_u32_e32 v16, s69, v150
	v_mul_lo_u32 v47, v16, s85
	v_lshlrev_b32_e32 v54, 16, v122
	v_and_b32_e32 v55, 0xffff0000, v122
	v_lshlrev_b32_e32 v52, 16, v123
	v_and_b32_e32 v53, 0xffff0000, v123
	s_nop 1
	v_lshlrev_b32_e32 v50, 16, v124
	v_and_b32_e32 v51, 0xffff0000, v124
	v_lshlrev_b32_e32 v48, 16, v125
	v_and_b32_e32 v49, 0xffff0000, v125
	s_nop 1
	v_lshlrev_b32_e32 v16, 16, v126
	v_and_b32_e32 v17, 0xffff0000, v126
	v_lshlrev_b32_e32 v18, 16, v127
	v_and_b32_e32 v19, 0xffff0000, v127
	s_nop 1
	v_add_u32_e32 v81, 0xb00, v47
	v_mov_b32_dpp v123, v54 row_ror:1 row_mask:0xf bank_mask:0xf
	v_mov_b32_dpp v169, v55 row_ror:1 row_mask:0xf bank_mask:0xf
	v_mov_b32_dpp v150, v52 row_ror:1 row_mask:0xf bank_mask:0xf
	v_mov_b32_dpp v170, v53 row_ror:1 row_mask:0xf bank_mask:0xf
	v_mov_b32_dpp v152, v54 row_ror:2 row_mask:0xf bank_mask:0xf
	v_mov_b32_dpp v171, v55 row_ror:2 row_mask:0xf bank_mask:0xf
	v_mov_b32_dpp v173, v52 row_ror:2 row_mask:0xf bank_mask:0xf
	v_mov_b32_dpp v175, v53 row_ror:2 row_mask:0xf bank_mask:0xf
	v_mov_b32_dpp v83, v50 row_ror:1 row_mask:0xf bank_mask:0xf
	v_mov_b32_dpp v86, v51 row_ror:1 row_mask:0xf bank_mask:0xf
	v_mov_b32_dpp v84, v48 row_ror:1 row_mask:0xf bank_mask:0xf
	v_mov_b32_dpp v87, v49 row_ror:1 row_mask:0xf bank_mask:0xf
	v_mov_b32_dpp v85, v50 row_ror:2 row_mask:0xf bank_mask:0xf
	v_mov_b32_dpp v88, v51 row_ror:2 row_mask:0xf bank_mask:0xf
	v_mov_b32_dpp v89, v48 row_ror:2 row_mask:0xf bank_mask:0xf
	v_mov_b32_dpp v90, v49 row_ror:2 row_mask:0xf bank_mask:0xf
	v_mov_b32_dpp v91, v16 row_ror:1 row_mask:0xf bank_mask:0xf
	v_mov_b32_dpp v94, v17 row_ror:1 row_mask:0xf bank_mask:0xf
	v_mov_b32_dpp v92, v18 row_ror:1 row_mask:0xf bank_mask:0xf
	v_mov_b32_dpp v95, v19 row_ror:1 row_mask:0xf bank_mask:0xf
	v_mov_b32_dpp v93, v16 row_ror:2 row_mask:0xf bank_mask:0xf
	v_mov_b32_dpp v120, v17 row_ror:2 row_mask:0xf bank_mask:0xf
	v_mov_b32_dpp v121, v18 row_ror:2 row_mask:0xf bank_mask:0xf
	v_mov_b32_dpp v122, v19 row_ror:2 row_mask:0xf bank_mask:0xf
	s_and_saveexec_b64 s[0:1], vcc
	s_cbranch_execz .LBB0_1430
	v_add_u32_e32 v136, v81, v44
	v_lshl_add_u64 v[20:21], v[136:137], 2, s[28:29]
	s_cmp_lg_u32 s99, 0
	s_cbranch_scc1 .Lwt1403_36746
	global_store_dwordx4 v[20:21], v[16:19], off
	s_branch .Lwj1403_36746

; __device__ __forceinline__ f32x4 gelu4(f32x4 v) { const f32x2 a = gelu_pk((f32x2){v[0], v[1]}), b = gelu_pk((f32x2){v[2], v[3]}); return (f32x4){a.x, a.y, b.x, b.y}; }
; __device__ __forceinline__ f32x4 ror1v(f32x4 v) { return (f32x4){dpp_ror1(v[0]), dpp_ror1(v[1]), dpp_ror1(v[2]), dpp_ror1(v[3])}; }
; __device__ __forceinline__ f32x4 ror2v(f32x4 v) { return (f32x4){dpp_ror2(v[0]), dpp_ror2(v[1]), dpp_ror2(v[2]), dpp_ror2(v[3])}; }
; __device__ __forceinline__ u32x2 pack4(f32x4 v) { return (u32x2){pk2(v[0], v[1]), pk2(v[2], v[3])}; }
; __device__ __forceinline__ f32x4 unpack4(u32x2 w) { return (f32x4){bflo(w.x), bfhi(w.x), bflo(w.y), bfhi(w.y)}; }
;     __device__ __forceinline__ void operator()(AccRef acc, const Unit& u, int wr, int wc, int fr, int fq) const {
;     ...
;                 {
;                     const f32x4 wg0 = *(const f32x4*)(cw + jn), wg1 = *(const f32x4*)(cw + (UPN + jn)), wg2 = *(const f32x4*)(cw + (2 * UPN + jn)), bg = *(const f32x4*)(cb + jn);
;                     f32x4 pg1 = (f32x4){0.f, 0.f, 0.f, 0.f}, pg2 = pg1;
; #pragma unroll
;                     for (int m = 0; m < 4; ++m) { const int row = rowg + m * 16 + fr;
;                         const f32x4 ag = unpack4(pa[ai][0][m][n]);
;                         const f32x4 rg1 = ror1v(ag), rg2 = ror2v(ag);
;                         const f32x4 g1 = fr >= 1 ? rg1 : pg1, g2 = fr >= 2 ? rg2 : pg2;
;                         if (m == 0 && fr < 2) *(f32x4*)(edge + (unsigned)((grp * 4 + fr) * UPN + jn)) = ag;
;                         if (m == 3 && fr >= 14) *(f32x4*)(edge + (unsigned)((grp * 4 + (fr - 12)) * UPN + jn)) = ag;
;                         const f32x4 o = gelu4(bg + wg0 * g2 + wg1 * g1 + wg2 * ag) * cu[m];
;                         if (!(m == 0 && fr < 2)) *(u32x2*)(act + (unsigned)(row * DFF + jn)) = pack4(o);
;                         pg1 = rg1; pg2 = rg2; }
.Lwj1403_36746:
.LBB0_1430:
	s_or_b64 exec, exec, s[0:1]
	global_load_dwordx4 v[28:31], v[56:57], off
	global_load_dwordx4 v[24:27], v[58:59], off
	global_load_dwordx4 v[20:23], v[62:63], off
	global_load_dwordx4 v[32:35], v[64:65], off
	v_add_u32_e32 v124, s65, v166
	v_lshlrev_b32_e32 v40, 16, v118
	v_and_b32_e32 v41, 0xffff0000, v118
	v_lshlrev_b32_e32 v42, 16, v119
	v_and_b32_e32 v43, 0xffff0000, v119
	s_nop 1
	v_mov_b32_dpp v56, v40 row_ror:1 row_mask:0xf bank_mask:0xf
	v_mov_b32_dpp v57, v41 row_ror:1 row_mask:0xf bank_mask:0xf
	v_mov_b32_dpp v58, v42 row_ror:1 row_mask:0xf bank_mask:0xf
	v_mov_b32_dpp v59, v43 row_ror:1 row_mask:0xf bank_mask:0xf
	v_mov_b32_dpp v62, v40 row_ror:2 row_mask:0xf bank_mask:0xf
	v_mov_b32_dpp v63, v41 row_ror:2 row_mask:0xf bank_mask:0xf
	v_mov_b32_dpp v64, v42 row_ror:2 row_mask:0xf bank_mask:0xf
	v_mov_b32_dpp v65, v43 row_ror:2 row_mask:0xf bank_mask:0xf
	v_mul_lo_u32 v82, v124, s86
	s_and_saveexec_b64 s[0:1], s[10:11]
	s_xor_b64 s[74:75], exec, s[0:1]
	s_cbranch_execz .LBB0_1432
	v_cndmask_b32_e64 v179, 0, v174, s[6:7]
	v_cndmask_b32_e64 v178, 0, v172, s[6:7]
	v_cndmask_b32_e64 v127, 0, v167, s[8:9]
	v_cndmask_b32_e64 v126, 0, v147, s[8:9]
	s_waitcnt vmcnt(4)
	v_pk_fma_f32 v[178:179], v[10:11], v[178:179], v[14:15]
	v_cndmask_b32_e64 v181, 0, v168, s[6:7]
	v_pk_fma_f32 v[126:127], v[6:7], v[126:127], v[178:179]
	v_cndmask_b32_e64 v180, 0, v148, s[6:7]
	v_pk_fma_f32 v[38:39], v[2:3], v[38:39], v[126:127]
	s_waitcnt vmcnt(0)
	v_pk_fma_f32 v[126:127], v[28:29], v[62:63], v[32:33]
	v_cndmask_b32_e64 v119, 0, v149, s[8:9]
	v_pk_fma_f32 v[126:127], v[24:25], v[56:57], v[126:127]
	v_cndmask_b32_e64 v118, 0, v146, s[8:9]
	v_pk_fma_f32 v[40:41], v[20:21], v[40:41], v[126:127]
	v_pk_fma_f32 v[180:181], v[8:9], v[180:181], v[12:13]
	v_and_b32_e32 v179, 0x7fffffff, v41
	v_and_b32_e32 v178, 0x7fffffff, v40
	v_pk_fma_f32 v[178:179], v[178:179], s[52:53], 1.0 op_sel_hi:[1,0,0]
	v_pk_fma_f32 v[118:119], v[4:5], v[118:119], v[180:181]
	v_rcp_f32_e32 v178, v178
	v_rcp_f32_e32 v179, v179
	v_pk_mul_f32 v[126:127], v[40:41], v[40:41]
	v_mov_b64_e32 v[180:181], s[56:57]
	v_pk_mul_f32 v[126:127], v[126:127], s[42:43] op_sel_hi:[1,0]
	v_pk_fma_f32 v[182:183], v[178:179], s[54:55], v[180:181] op_sel_hi:[1,0,0]
	v_exp_f32_e32 v126, v126
	v_exp_f32_e32 v127, v127
	v_pk_fma_f32 v[182:183], v[178:179], v[182:183], s[58:59] op_sel_hi:[1,1,0]
	v_pk_fma_f32 v[36:37], v[0:1], v[36:37], v[118:119]
	v_pk_fma_f32 v[182:183], v[178:179], v[182:183], s[60:61] op_sel_hi:[1,1,0]
	v_pk_fma_f32 v[118:119], v[30:31], v[64:65], v[34:35]
	v_pk_fma_f32 v[182:183], v[178:179], v[182:183], s[62:63] op_sel_hi:[1,1,0]
	v_pk_fma_f32 v[118:119], v[26:27], v[58:59], v[118:119]
	v_pk_mul_f32 v[178:179], v[178:179], v[182:183]
	v_cmp_gt_f32_e64 s[0:1], 0, v40
	v_pk_mul_f32 v[126:127], v[126:127], v[178:179]
	v_pk_fma_f32 v[42:43], v[22:23], v[42:43], v[118:119]
	v_pk_mul_f32 v[178:179], v[40:41], v[126:127]
	v_pk_fma_f32 v[126:127], v[40:41], v[126:127], v[40:41] neg_lo:[1,0,0] neg_hi:[1,0,0]
	v_pk_mul_f32 v[118:119], v[42:43], v[42:43]
	v_cndmask_b32_e64 v40, v126, v178, s[0:1]
	v_cmp_gt_f32_e64 s[0:1], 0, v41
	v_and_b32_e32 v126, 0x7fffffff, v42
	v_pk_mul_f32 v[118:119], v[118:119], s[42:43] op_sel_hi:[1,0]
	v_cndmask_b32_e64 v41, v127, v179, s[0:1]
	v_and_b32_e32 v127, 0x7fffffff, v43
	v_pk_fma_f32 v[126:127], v[126:127], s[52:53], 1.0 op_sel_hi:[1,0,0]
	v_exp_f32_e32 v118, v118
	v_rcp_f32_e32 v126, v126
	v_rcp_f32_e32 v127, v127
	v_exp_f32_e32 v119, v119
	v_cmp_gt_f32_e64 s[0:1], 0, v42
	v_mul_lo_u32 v82, v124, s86
	v_pk_fma_f32 v[178:179], v[126:127], s[54:55], v[180:181] op_sel_hi:[1,0,0]
	v_pk_mul_f32 v[36:37], v[36:37], v[40:41]
	v_pk_fma_f32 v[178:179], v[126:127], v[178:179], s[58:59] op_sel_hi:[1,1,0]
	v_add_u32_e32 v136, v82, v44
	v_pk_fma_f32 v[178:179], v[126:127], v[178:179], s[60:61] op_sel_hi:[1,1,0]
	v_cvt_pk_bf16_f32 v36, v36, v37
	s_nop 0
	v_pk_fma_f32 v[178:179], v[126:127], v[178:179], s[62:63] op_sel_hi:[1,1,0]
	s_nop 0
	v_pk_mul_f32 v[126:127], v[126:127], v[178:179]
	s_nop 0
	v_pk_mul_f32 v[118:119], v[118:119], v[126:127]
	s_nop 0
	v_pk_mul_f32 v[126:127], v[42:43], v[118:119]
	v_pk_fma_f32 v[118:119], v[42:43], v[118:119], v[42:43] neg_lo:[1,0,0] neg_hi:[1,0,0]
	s_nop 0
	v_cndmask_b32_e64 v42, v118, v126, s[0:1]
	v_cmp_gt_f32_e64 s[0:1], 0, v43
	s_nop 1
	v_cndmask_b32_e64 v43, v119, v127, s[0:1]
	v_pk_mul_f32 v[38:39], v[38:39], v[42:43]
	s_nop 0
	v_cvt_pk_bf16_f32 v37, v38, v39
	v_lshl_add_u64 v[38:39], v[136:137], 1, s[26:27]
	s_cmp_lg_u32 s99, 0
	s_cbranch_scc1 .Lwt1403_36856
	global_store_dwordx2 v[38:39], v[36:37], off
	s_branch .Lwj1403_36856

; __device__ __forceinline__ f32x4 gelu4(f32x4 v) { const f32x2 a = gelu_pk((f32x2){v[0], v[1]}), b = gelu_pk((f32x2){v[2], v[3]}); return (f32x4){a.x, a.y, b.x, b.y}; }
; __device__ __forceinline__ u32x2 pack4(f32x4 v) { return (u32x2){pk2(v[0], v[1]), pk2(v[2], v[3])}; }
;     __device__ __forceinline__ void operator()(AccRef acc, const Unit& u, int wr, int wc, int fr, int fq) const {
;     ...
;                         if (m == 0 && fr < 2) *(f32x4*)(edge + (unsigned)((grp * 4 + fr) * UPN + jn)) = ag;
;                         if (m == 3 && fr >= 14) *(f32x4*)(edge + (unsigned)((grp * 4 + (fr - 12)) * UPN + jn)) = ag;
;                         const f32x4 o = gelu4(bg + wg0 * g2 + wg1 * g1 + wg2 * ag) * cu[m];
;                         if (!(m == 0 && fr < 2)) *(u32x2*)(act + (unsigned)(row * DFF + jn)) = pack4(o);
.Lwj1403_36856:
.LBB0_1432:
	s_andn2_saveexec_b64 s[0:1], s[74:75]
	s_cbranch_execz .LBB0_1434
	v_add_u32_e32 v136, v44, v80
	v_lshl_add_u64 v[36:37], v[136:137], 2, s[28:29]
	s_cmp_lg_u32 s99, 0
	s_cbranch_scc1 .Lwt1403_36863
	global_store_dwordx4 v[36:37], v[40:43], off
	s_branch .Lwj1403_36863

; __device__ __forceinline__ f32x4 gelu4(f32x4 v) { const f32x2 a = gelu_pk((f32x2){v[0], v[1]}), b = gelu_pk((f32x2){v[2], v[3]}); return (f32x4){a.x, a.y, b.x, b.y}; }
; __device__ __forceinline__ f32x4 ror1v(f32x4 v) { return (f32x4){dpp_ror1(v[0]), dpp_ror1(v[1]), dpp_ror1(v[2]), dpp_ror1(v[3])}; }
; __device__ __forceinline__ f32x4 ror2v(f32x4 v) { return (f32x4){dpp_ror2(v[0]), dpp_ror2(v[1]), dpp_ror2(v[2]), dpp_ror2(v[3])}; }
; __device__ __forceinline__ u32x2 pack4(f32x4 v) { return (u32x2){pk2(v[0], v[1]), pk2(v[2], v[3])}; }
; __device__ __forceinline__ f32x4 unpack4(u32x2 w) { return (f32x4){bflo(w.x), bfhi(w.x), bflo(w.y), bfhi(w.y)}; }
;     __device__ __forceinline__ void operator()(AccRef acc, const Unit& u, int wr, int wc, int fr, int fq) const {
;     ...
;                     for (int m = 0; m < 4; ++m) { const int row = rowg + m * 16 + fr;
;                         const f32x4 ag = unpack4(pa[ai][0][m][n]);
;                         const f32x4 rg1 = ror1v(ag), rg2 = ror2v(ag);
;                         const f32x4 g1 = fr >= 1 ? rg1 : pg1, g2 = fr >= 2 ? rg2 : pg2;
;                         if (m == 0 && fr < 2) *(f32x4*)(edge + (unsigned)((grp * 4 + fr) * UPN + jn)) = ag;
;                         if (m == 3 && fr >= 14) *(f32x4*)(edge + (unsigned)((grp * 4 + (fr - 12)) * UPN + jn)) = ag;
;                         const f32x4 o = gelu4(bg + wg0 * g2 + wg1 * g1 + wg2 * ag) * cu[m];
;                         if (!(m == 0 && fr < 2)) *(u32x2*)(act + (unsigned)(row * DFF + jn)) = pack4(o);
;                         pg1 = rg1; pg2 = rg2; }
.Lwj1403_36863:
.LBB0_1434:
	s_or_b64 exec, exec, s[0:1]
	s_nop 0
	v_cndmask_b32_e64 v41, v174, v175, s[6:7]
	v_cndmask_b32_e64 v40, v172, v173, s[6:7]
	v_cndmask_b32_e64 v43, v168, v171, s[6:7]
	v_cndmask_b32_e64 v42, v148, v152, s[6:7]
	v_cndmask_b32_e64 v37, v149, v169, s[8:9]
	v_cndmask_b32_e64 v36, v146, v123, s[8:9]
	v_cndmask_b32_e64 v39, v167, v170, s[8:9]
	v_cndmask_b32_e64 v38, v147, v150, s[8:9]
	s_waitcnt vmcnt(4)
	v_pk_fma_f32 v[42:43], v[8:9], v[42:43], v[12:13]
	v_pk_fma_f32 v[40:41], v[10:11], v[40:41], v[14:15]
	v_pk_fma_f32 v[36:37], v[4:5], v[36:37], v[42:43]
	v_pk_fma_f32 v[38:39], v[6:7], v[38:39], v[40:41]
	v_pk_fma_f32 v[36:37], v[0:1], v[54:55], v[36:37]
	v_pk_fma_f32 v[38:39], v[2:3], v[52:53], v[38:39]
	v_cndmask_b32_e64 v53, v175, v90, s[6:7]
	v_cndmask_b32_e64 v52, v173, v89, s[6:7]
	v_cndmask_b32_e64 v55, v171, v88, s[6:7]
	v_cndmask_b32_e64 v54, v152, v85, s[6:7]
	v_cndmask_b32_e64 v41, v169, v86, s[8:9]
	v_cndmask_b32_e64 v40, v123, v83, s[8:9]
	v_cndmask_b32_e64 v43, v170, v87, s[8:9]
	v_cndmask_b32_e64 v42, v150, v84, s[8:9]
	v_pk_fma_f32 v[54:55], v[8:9], v[54:55], v[12:13]
	v_pk_fma_f32 v[52:53], v[10:11], v[52:53], v[14:15]
	v_pk_fma_f32 v[40:41], v[4:5], v[40:41], v[54:55]
	v_pk_fma_f32 v[42:43], v[6:7], v[42:43], v[52:53]
	v_pk_fma_f32 v[52:53], v[0:1], v[50:51], v[40:41]
	v_pk_fma_f32 v[54:55], v[2:3], v[48:49], v[42:43]
	v_lshlrev_b32_e32 v40, 16, v116
	v_and_b32_e32 v41, 0xffff0000, v116
	v_lshlrev_b32_e32 v42, 16, v117
	v_and_b32_e32 v43, 0xffff0000, v117
	s_nop 1
	v_mov_b32_dpp v116, v40 row_ror:1 row_mask:0xf bank_mask:0xf
	v_mov_b32_dpp v117, v41 row_ror:1 row_mask:0xf bank_mask:0xf
	v_mov_b32_dpp v123, v40 row_ror:2 row_mask:0xf bank_mask:0xf
	v_mov_b32_dpp v124, v41 row_ror:2 row_mask:0xf bank_mask:0xf
	v_cndmask_b32_e64 v51, v57, v117, s[8:9]
	v_cndmask_b32_e64 v50, v56, v116, s[8:9]
	v_cndmask_b32_e64 v57, v63, v124, s[6:7]
	v_cndmask_b32_e64 v56, v62, v123, s[6:7]
	s_waitcnt vmcnt(2)
	v_pk_fma_f32 v[56:57], v[28:29], v[56:57], v[32:33]
	s_nop 1
	v_pk_fma_f32 v[50:51], v[24:25], v[50:51], v[56:57]
	s_nop 1
	v_pk_fma_f32 v[40:41], v[20:21], v[40:41], v[50:51]
	s_nop 1
	v_and_b32_e32 v57, 0x7fffffff, v41
	v_and_b32_e32 v56, 0x7fffffff, v40
	s_nop 1
	v_pk_fma_f32 v[56:57], v[56:57], s[52:53], 1.0 op_sel_hi:[1,0,0]
	v_mov_b32_dpp v118, v42 row_ror:1 row_mask:0xf bank_mask:0xf
	v_mov_b32_dpp v119, v43 row_ror:1 row_mask:0xf bank_mask:0xf
	v_mov_b32_dpp v125, v42 row_ror:2 row_mask:0xf bank_mask:0xf
	v_mov_b32_dpp v126, v43 row_ror:2 row_mask:0xf bank_mask:0xf
	v_rcp_f32_e32 v56, v56
	v_rcp_f32_e32 v57, v57
	v_cndmask_b32_e64 v49, v59, v119, s[8:9]
	v_cndmask_b32_e64 v48, v58, v118, s[8:9]
	v_cndmask_b32_e64 v59, v65, v126, s[6:7]
	v_cndmask_b32_e64 v58, v64, v125, s[6:7]
	v_pk_fma_f32 v[58:59], v[30:31], v[58:59], v[34:35]
	v_pk_mul_f32 v[50:51], v[40:41], v[40:41]
	v_pk_fma_f32 v[48:49], v[26:27], v[48:49], v[58:59]
	v_mov_b64_e32 v[58:59], s[56:57]
	v_pk_mul_f32 v[50:51], v[50:51], s[42:43] op_sel_hi:[1,0]
	v_pk_fma_f32 v[62:63], v[56:57], s[54:55], v[58:59] op_sel_hi:[1,0,0]
	v_exp_f32_e32 v50, v50
	v_exp_f32_e32 v51, v51
	v_pk_fma_f32 v[62:63], v[56:57], v[62:63], s[58:59] op_sel_hi:[1,1,0]
	v_cmp_gt_f32_e64 s[0:1], 0, v40
	v_pk_fma_f32 v[62:63], v[56:57], v[62:63], s[60:61] op_sel_hi:[1,1,0]
	v_pk_fma_f32 v[42:43], v[22:23], v[42:43], v[48:49]
	v_pk_fma_f32 v[62:63], v[56:57], v[62:63], s[62:63] op_sel_hi:[1,1,0]
	v_pk_mul_f32 v[48:49], v[42:43], v[42:43]
	v_pk_mul_f32 v[56:57], v[56:57], v[62:63]
	v_pk_mul_f32 v[48:49], v[48:49], s[42:43] op_sel_hi:[1,0]
	v_pk_mul_f32 v[50:51], v[50:51], v[56:57]
	v_exp_f32_e32 v48, v48
	v_pk_mul_f32 v[56:57], v[40:41], v[50:51]
	v_pk_fma_f32 v[50:51], v[40:41], v[50:51], v[40:41] neg_lo:[1,0,0] neg_hi:[1,0,0]
	v_exp_f32_e32 v49, v49
	v_cndmask_b32_e64 v40, v50, v56, s[0:1]
	v_cmp_gt_f32_e64 s[0:1], 0, v41
	v_and_b32_e32 v50, 0x7fffffff, v42
	v_add_u32_e32 v62, 0xb000, v82
	v_cndmask_b32_e64 v41, v51, v57, s[0:1]
	v_and_b32_e32 v51, 0x7fffffff, v43
	v_pk_fma_f32 v[50:51], v[50:51], s[52:53], 1.0 op_sel_hi:[1,0,0]
	v_cmp_gt_f32_e64 s[0:1], 0, v42
	v_rcp_f32_e32 v50, v50
	v_rcp_f32_e32 v51, v51
	v_pk_mul_f32 v[36:37], v[36:37], v[40:41]
	v_add_u32_e32 v136, v62, v44
	v_cvt_pk_bf16_f32 v36, v36, v37
	v_pk_fma_f32 v[56:57], v[50:51], s[54:55], v[58:59] op_sel_hi:[1,0,0]
	s_nop 1
	v_pk_fma_f32 v[56:57], v[50:51], v[56:57], s[58:59] op_sel_hi:[1,1,0]
	s_nop 1
	v_pk_fma_f32 v[56:57], v[50:51], v[56:57], s[60:61] op_sel_hi:[1,1,0]
	v_add_u32_e32 v63, 0x16000, v82
	v_pk_fma_f32 v[56:57], v[50:51], v[56:57], s[62:63] op_sel_hi:[1,1,0]
	s_nop 0
	v_pk_mul_f32 v[50:51], v[50:51], v[56:57]
	s_nop 0
	v_pk_mul_f32 v[48:49], v[48:49], v[50:51]
	s_nop 0
	v_pk_mul_f32 v[50:51], v[42:43], v[48:49]
	v_pk_fma_f32 v[48:49], v[42:43], v[48:49], v[42:43] neg_lo:[1,0,0] neg_hi:[1,0,0]
	s_nop 0
	v_cndmask_b32_e64 v42, v48, v50, s[0:1]
	v_cmp_gt_f32_e64 s[0:1], 0, v43
	s_nop 1
	v_cndmask_b32_e64 v43, v49, v51, s[0:1]
	v_pk_mul_f32 v[38:39], v[38:39], v[42:43]
	s_nop 1
	v_cvt_pk_bf16_f32 v37, v38, v39
	v_lshl_add_u64 v[38:39], v[136:137], 1, s[26:27]
	s_cmp_lg_u32 s99, 0
	s_cbranch_scc1 .Lwt1403_36991
	global_store_dwordx2 v[38:39], v[36:37], off
	s_branch .Lwj1403_36991

; __device__ __forceinline__ f32x4 gelu4(f32x4 v) { const f32x2 a = gelu_pk((f32x2){v[0], v[1]}), b = gelu_pk((f32x2){v[2], v[3]}); return (f32x4){a.x, a.y, b.x, b.y}; }
; __device__ __forceinline__ f32x4 ror1v(f32x4 v) { return (f32x4){dpp_ror1(v[0]), dpp_ror1(v[1]), dpp_ror1(v[2]), dpp_ror1(v[3])}; }
; __device__ __forceinline__ f32x4 ror2v(f32x4 v) { return (f32x4){dpp_ror2(v[0]), dpp_ror2(v[1]), dpp_ror2(v[2]), dpp_ror2(v[3])}; }
; __device__ __forceinline__ u32x2 pack4(f32x4 v) { return (u32x2){pk2(v[0], v[1]), pk2(v[2], v[3])}; }
; __device__ __forceinline__ f32x4 unpack4(u32x2 w) { return (f32x4){bflo(w.x), bfhi(w.x), bflo(w.y), bfhi(w.y)}; }
;     __device__ __forceinline__ void operator()(AccRef acc, const Unit& u, int wr, int wc, int fr, int fq) const {
;     ...
;                     for (int m = 0; m < 4; ++m) { const int row = rowg + m * 16 + fr;
;                         const f32x4 ag = unpack4(pa[ai][0][m][n]);
;                         const f32x4 rg1 = ror1v(ag), rg2 = ror2v(ag);
;                         const f32x4 g1 = fr >= 1 ? rg1 : pg1, g2 = fr >= 2 ? rg2 : pg2;
;                         if (m == 0 && fr < 2) *(f32x4*)(edge + (unsigned)((grp * 4 + fr) * UPN + jn)) = ag;
;                         if (m == 3 && fr >= 14) *(f32x4*)(edge + (unsigned)((grp * 4 + (fr - 12)) * UPN + jn)) = ag;
;                         const f32x4 o = gelu4(bg + wg0 * g2 + wg1 * g1 + wg2 * ag) * cu[m];
;                         if (!(m == 0 && fr < 2)) *(u32x2*)(act + (unsigned)(row * DFF + jn)) = pack4(o);
;                         pg1 = rg1; pg2 = rg2; }
.Lwj1403_36991:
	v_lshlrev_b32_e32 v36, 16, v114
	v_and_b32_e32 v37, 0xffff0000, v114
	v_lshlrev_b32_e32 v38, 16, v115
	v_mov_b32_dpp v43, v36 row_ror:2 row_mask:0xf bank_mask:0xf
	v_mov_b32_dpp v50, v37 row_ror:2 row_mask:0xf bank_mask:0xf
	v_and_b32_e32 v39, 0xffff0000, v115
	v_mov_b32_dpp v40, v36 row_ror:1 row_mask:0xf bank_mask:0xf
	v_mov_b32_dpp v41, v37 row_ror:1 row_mask:0xf bank_mask:0xf
	v_cndmask_b32_e64 v115, v124, v50, s[6:7]
	v_cndmask_b32_e64 v114, v123, v43, s[6:7]
	v_cndmask_b32_e64 v65, v117, v41, s[8:9]
	v_cndmask_b32_e64 v64, v116, v40, s[8:9]
	v_pk_fma_f32 v[114:115], v[28:29], v[114:115], v[32:33]
	s_nop 1
	v_pk_fma_f32 v[64:65], v[24:25], v[64:65], v[114:115]
	s_nop 1
	v_pk_fma_f32 v[36:37], v[20:21], v[36:37], v[64:65]
	s_nop 1
	v_and_b32_e32 v115, 0x7fffffff, v37
	v_and_b32_e32 v114, 0x7fffffff, v36
	v_pk_fma_f32 v[114:115], v[114:115], s[52:53], 1.0 op_sel_hi:[1,0,0]
	v_mov_b32_dpp v48, v38 row_ror:2 row_mask:0xf bank_mask:0xf
	v_rcp_f32_e32 v114, v114
	v_rcp_f32_e32 v115, v115
	v_mov_b32_dpp v51, v39 row_ror:2 row_mask:0xf bank_mask:0xf
	v_mov_b32_dpp v42, v38 row_ror:1 row_mask:0xf bank_mask:0xf
	v_mov_b32_dpp v49, v39 row_ror:1 row_mask:0xf bank_mask:0xf
	v_cndmask_b32_e64 v117, v126, v51, s[6:7]
	v_cndmask_b32_e64 v116, v125, v48, s[6:7]
	v_cndmask_b32_e64 v57, v119, v49, s[8:9]
	v_cndmask_b32_e64 v56, v118, v42, s[8:9]
	v_pk_fma_f32 v[116:117], v[30:31], v[116:117], v[34:35]
	v_pk_mul_f32 v[64:65], v[36:37], v[36:37]
	v_pk_fma_f32 v[56:57], v[26:27], v[56:57], v[116:117]
	v_pk_mul_f32 v[64:65], v[64:65], s[42:43] op_sel_hi:[1,0]
	v_pk_fma_f32 v[116:117], v[114:115], s[54:55], v[58:59] op_sel_hi:[1,0,0]
	v_exp_f32_e32 v64, v64
	v_exp_f32_e32 v65, v65
	v_pk_fma_f32 v[116:117], v[114:115], v[116:117], s[58:59] op_sel_hi:[1,1,0]
	v_cmp_gt_f32_e64 s[0:1], 0, v36
	v_pk_fma_f32 v[116:117], v[114:115], v[116:117], s[60:61] op_sel_hi:[1,1,0]
	v_pk_fma_f32 v[38:39], v[22:23], v[38:39], v[56:57]
	v_pk_fma_f32 v[116:117], v[114:115], v[116:117], s[62:63] op_sel_hi:[1,1,0]
	v_pk_mul_f32 v[56:57], v[38:39], v[38:39]
	v_pk_mul_f32 v[114:115], v[114:115], v[116:117]
	v_pk_mul_f32 v[56:57], v[56:57], s[42:43] op_sel_hi:[1,0]
	v_pk_mul_f32 v[64:65], v[64:65], v[114:115]
	v_exp_f32_e32 v56, v56
	v_pk_mul_f32 v[114:115], v[36:37], v[64:65]
	v_pk_fma_f32 v[64:65], v[36:37], v[64:65], v[36:37] neg_lo:[1,0,0] neg_hi:[1,0,0]
	v_exp_f32_e32 v57, v57
	v_cndmask_b32_e64 v36, v64, v114, s[0:1]
	v_cmp_gt_f32_e64 s[0:1], 0, v37
	v_and_b32_e32 v64, 0x7fffffff, v38
	v_add_u32_e32 v136, v63, v44
	v_cndmask_b32_e64 v37, v65, v115, s[0:1]
	v_and_b32_e32 v65, 0x7fffffff, v39
	v_pk_fma_f32 v[64:65], v[64:65], s[52:53], 1.0 op_sel_hi:[1,0,0]
	v_cmp_gt_f32_e64 s[0:1], 0, v38
	v_rcp_f32_e32 v64, v64
	v_rcp_f32_e32 v65, v65
	v_pk_mul_f32 v[36:37], v[52:53], v[36:37]
	s_nop 1
	v_cvt_pk_bf16_f32 v36, v36, v37
	v_pk_fma_f32 v[58:59], v[64:65], s[54:55], v[58:59] op_sel_hi:[1,0,0]
	s_nop 1
	v_pk_fma_f32 v[58:59], v[64:65], v[58:59], s[58:59] op_sel_hi:[1,1,0]
	s_nop 0
	v_pk_fma_f32 v[58:59], v[64:65], v[58:59], s[60:61] op_sel_hi:[1,1,0]
	s_nop 0
	v_pk_fma_f32 v[58:59], v[64:65], v[58:59], s[62:63] op_sel_hi:[1,1,0]
	s_nop 0
	v_pk_mul_f32 v[58:59], v[64:65], v[58:59]
	s_nop 0
	v_pk_mul_f32 v[56:57], v[56:57], v[58:59]
	s_nop 0
	v_pk_mul_f32 v[58:59], v[38:39], v[56:57]
	v_pk_fma_f32 v[56:57], v[38:39], v[56:57], v[38:39] neg_lo:[1,0,0] neg_hi:[1,0,0]
	s_nop 0
	v_cndmask_b32_e64 v38, v56, v58, s[0:1]
	v_cmp_gt_f32_e64 s[0:1], 0, v39
	s_nop 1
	v_cndmask_b32_e64 v39, v57, v59, s[0:1]
	v_pk_mul_f32 v[38:39], v[54:55], v[38:39]
	s_nop 1
	v_cvt_pk_bf16_f32 v37, v38, v39
	v_lshl_add_u64 v[38:39], v[136:137], 1, s[26:27]
	s_cmp_lg_u32 s99, 0
	s_cbranch_scc1 .Lwt1403_37083
	global_store_dwordx2 v[38:39], v[36:37], off
	s_branch .Lwj1403_37083

; __device__ __forceinline__ f32x4 gelu4(f32x4 v) { const f32x2 a = gelu_pk((f32x2){v[0], v[1]}), b = gelu_pk((f32x2){v[2], v[3]}); return (f32x4){a.x, a.y, b.x, b.y}; }
; __device__ __forceinline__ f32x4 ror1v(f32x4 v) { return (f32x4){dpp_ror1(v[0]), dpp_ror1(v[1]), dpp_ror1(v[2]), dpp_ror1(v[3])}; }
; __device__ __forceinline__ f32x4 ror2v(f32x4 v) { return (f32x4){dpp_ror2(v[0]), dpp_ror2(v[1]), dpp_ror2(v[2]), dpp_ror2(v[3])}; }
; __device__ __forceinline__ u32x2 pack4(f32x4 v) { return (u32x2){pk2(v[0], v[1]), pk2(v[2], v[3])}; }
; __device__ __forceinline__ f32x4 unpack4(u32x2 w) { return (f32x4){bflo(w.x), bfhi(w.x), bflo(w.y), bfhi(w.y)}; }
;     __device__ __forceinline__ void operator()(AccRef acc, const Unit& u, int wr, int wc, int fr, int fq) const {
;     ...
;                     const f32x4 wu0 = *(const f32x4*)(cw + (DFF + jn)), wu1 = *(const f32x4*)(cw + (UPN + DFF + jn)), wu2 = *(const f32x4*)(cw + (2 * UPN + DFF + jn)), bu = *(const f32x4*)(cb + (DFF + jn));
;     ...
;                     const f32x4 wg0 = *(const f32x4*)(cw + jn), wg1 = *(const f32x4*)(cw + (UPN + jn)), wg2 = *(const f32x4*)(cw + (2 * UPN + jn)), bg = *(const f32x4*)(cb + jn);
;                     f32x4 pg1 = (f32x4){0.f, 0.f, 0.f, 0.f}, pg2 = pg1;
; #pragma unroll
;                     for (int m = 0; m < 4; ++m) { const int row = rowg + m * 16 + fr;
;                         const f32x4 ag = unpack4(pa[ai][0][m][n]);
;                         const f32x4 rg1 = ror1v(ag), rg2 = ror2v(ag);
;                         const f32x4 g1 = fr >= 1 ? rg1 : pg1, g2 = fr >= 2 ? rg2 : pg2;
;                         if (m == 0 && fr < 2) *(f32x4*)(edge + (unsigned)((grp * 4 + fr) * UPN + jn)) = ag;
;                         if (m == 3 && fr >= 14) *(f32x4*)(edge + (unsigned)((grp * 4 + (fr - 12)) * UPN + jn)) = ag;
;                         const f32x4 o = gelu4(bg + wg0 * g2 + wg1 * g1 + wg2 * ag) * cu[m];
;                         if (!(m == 0 && fr < 2)) *(u32x2*)(act + (unsigned)(row * DFF + jn)) = pack4(o);
;                         pg1 = rg1; pg2 = rg2; }
.Lwj1403_37083:
	v_lshlrev_b32_e32 v36, 16, v112
	v_and_b32_e32 v37, 0xffff0000, v112
	v_lshlrev_b32_e32 v38, 16, v113
	v_and_b32_e32 v39, 0xffff0000, v113
	s_nop 1
	v_mov_b32_dpp v52, v36 row_ror:1 row_mask:0xf bank_mask:0xf
	v_mov_b32_dpp v53, v37 row_ror:1 row_mask:0xf bank_mask:0xf
	v_mov_b32_dpp v54, v38 row_ror:1 row_mask:0xf bank_mask:0xf
	v_mov_b32_dpp v57, v39 row_ror:1 row_mask:0xf bank_mask:0xf
	v_mov_b32_dpp v55, v36 row_ror:2 row_mask:0xf bank_mask:0xf
	v_mov_b32_dpp v58, v37 row_ror:2 row_mask:0xf bank_mask:0xf
	v_mov_b32_dpp v56, v38 row_ror:2 row_mask:0xf bank_mask:0xf
	v_mov_b32_dpp v59, v39 row_ror:2 row_mask:0xf bank_mask:0xf
	s_and_saveexec_b64 s[0:1], vcc
	s_cbranch_execz .LBB0_1436
	v_add_u32_e32 v136, v47, v44
	v_lshl_add_u64 v[64:65], v[136:137], 2, s[28:29]
	s_cmp_lg_u32 s99, 0
	s_cbranch_scc1 .Lwt1403_37102
	global_store_dwordx4 v[64:65], v[36:39], off
	s_branch .Lwj1403_37102
.Lwt1403_37102:
	global_store_dwordx4 v[64:65], v[36:39], off sc1
.Lwj1403_37102:
.LBB0_1436:
	s_or_b64 exec, exec, s[0:1]
	v_cndmask_b32_e64 v64, v42, v54, s[8:9]
	v_cndmask_b32_e64 v40, v40, v52, s[8:9]
	v_cndmask_b32_e64 v52, v43, v55, s[6:7]
	v_cndmask_b32_e64 v55, v90, v122, s[6:7]
	v_cndmask_b32_e64 v54, v89, v121, s[6:7]
	v_cndmask_b32_e64 v41, v41, v53, s[8:9]
	v_cndmask_b32_e64 v53, v50, v58, s[6:7]
	v_cndmask_b32_e64 v43, v51, v59, s[6:7]
	v_cndmask_b32_e64 v51, v87, v95, s[8:9]
	v_cndmask_b32_e64 v50, v84, v92, s[8:9]
	v_pk_fma_f32 v[10:11], v[10:11], v[54:55], v[14:15]
	v_cndmask_b32_e64 v65, v49, v57, s[8:9]
	v_pk_fma_f32 v[6:7], v[6:7], v[50:51], v[10:11]
	v_cndmask_b32_e64 v42, v48, v56, s[6:7]
	v_pk_fma_f32 v[2:3], v[2:3], v[18:19], v[6:7]
	v_pk_fma_f32 v[6:7], v[28:29], v[52:53], v[32:33]
	v_cndmask_b32_e64 v57, v88, v120, s[6:7]
	v_pk_fma_f32 v[6:7], v[24:25], v[40:41], v[6:7]
	v_cndmask_b32_e64 v56, v85, v93, s[6:7]
	v_pk_fma_f32 v[6:7], v[20:21], v[36:37], v[6:7]
	v_pk_fma_f32 v[8:9], v[8:9], v[56:57], v[12:13]
	v_and_b32_e32 v13, 0x7fffffff, v7
	v_and_b32_e32 v12, 0x7fffffff, v6
	v_pk_fma_f32 v[12:13], v[12:13], s[52:53], 1.0 op_sel_hi:[1,0,0]
	v_cndmask_b32_e64 v49, v86, v94, s[8:9]
	v_rcp_f32_e32 v12, v12
	v_rcp_f32_e32 v13, v13
	v_cndmask_b32_e64 v48, v83, v91, s[8:9]
	v_pk_fma_f32 v[4:5], v[4:5], v[48:49], v[8:9]
	v_pk_mul_f32 v[10:11], v[6:7], v[6:7]
	v_mov_b64_e32 v[14:15], s[56:57]
	v_pk_fma_f32 v[0:1], v[0:1], v[16:17], v[4:5]
	v_pk_mul_f32 v[10:11], v[10:11], s[42:43] op_sel_hi:[1,0]
	v_pk_fma_f32 v[16:17], v[12:13], s[54:55], v[14:15] op_sel_hi:[1,0,0]
	v_exp_f32_e32 v10, v10
	v_exp_f32_e32 v11, v11
	v_pk_fma_f32 v[16:17], v[12:13], v[16:17], s[58:59] op_sel_hi:[1,1,0]
	v_pk_fma_f32 v[4:5], v[30:31], v[42:43], v[34:35]
	v_pk_fma_f32 v[16:17], v[12:13], v[16:17], s[60:61] op_sel_hi:[1,1,0]
	v_pk_fma_f32 v[4:5], v[26:27], v[64:65], v[4:5]
	v_pk_fma_f32 v[16:17], v[12:13], v[16:17], s[62:63] op_sel_hi:[1,1,0]
	v_cmp_gt_f32_e64 s[0:1], 0, v6
	v_pk_mul_f32 v[12:13], v[12:13], v[16:17]
	v_pk_fma_f32 v[4:5], v[22:23], v[38:39], v[4:5]
	v_pk_mul_f32 v[10:11], v[10:11], v[12:13]
	v_pk_mul_f32 v[8:9], v[4:5], v[4:5]
	v_pk_mul_f32 v[12:13], v[6:7], v[10:11]
	v_pk_fma_f32 v[10:11], v[6:7], v[10:11], v[6:7] neg_lo:[1,0,0] neg_hi:[1,0,0]
	v_pk_mul_f32 v[8:9], v[8:9], s[42:43] op_sel_hi:[1,0]
	v_cndmask_b32_e64 v6, v10, v12, s[0:1]
	v_cmp_gt_f32_e64 s[0:1], 0, v7
	v_and_b32_e32 v10, 0x7fffffff, v4
	v_exp_f32_e32 v8, v8
	v_cndmask_b32_e64 v7, v11, v13, s[0:1]
	v_and_b32_e32 v11, 0x7fffffff, v5
	v_pk_fma_f32 v[10:11], v[10:11], s[52:53], 1.0 op_sel_hi:[1,0,0]
	v_exp_f32_e32 v9, v9
	v_rcp_f32_e32 v10, v10
	v_rcp_f32_e32 v11, v11
	v_cmp_gt_f32_e64 s[0:1], 0, v4
	v_add_u32_e32 v64, 0x21000, v82
	v_pk_mul_f32 v[0:1], v[0:1], v[6:7]
	v_pk_fma_f32 v[12:13], v[10:11], s[54:55], v[14:15] op_sel_hi:[1,0,0]
	v_add_u32_e32 v136, v64, v44
	v_pk_fma_f32 v[12:13], v[10:11], v[12:13], s[58:59] op_sel_hi:[1,1,0]
	v_cvt_pk_bf16_f32 v0, v0, v1
	v_lshlrev_b32_e32 v36, 16, v104
	v_pk_fma_f32 v[12:13], v[10:11], v[12:13], s[60:61] op_sel_hi:[1,1,0]
	v_and_b32_e32 v37, 0xffff0000, v104
	v_pk_fma_f32 v[12:13], v[10:11], v[12:13], s[62:63] op_sel_hi:[1,1,0]
	v_lshlrev_b32_e32 v38, 16, v105
	v_pk_mul_f32 v[10:11], v[10:11], v[12:13]
	v_and_b32_e32 v39, 0xffff0000, v105
	v_pk_mul_f32 v[8:9], v[8:9], v[10:11]
	s_nop 1
	v_pk_mul_f32 v[10:11], v[4:5], v[8:9]
	v_pk_fma_f32 v[8:9], v[4:5], v[8:9], v[4:5] neg_lo:[1,0,0] neg_hi:[1,0,0]
	s_nop 1
	v_cndmask_b32_e64 v4, v8, v10, s[0:1]
	v_cmp_gt_f32_e64 s[0:1], 0, v5
	s_nop 1
	v_cndmask_b32_e64 v5, v9, v11, s[0:1]
	v_pk_mul_f32 v[2:3], v[2:3], v[4:5]
	s_nop 1
	v_cvt_pk_bf16_f32 v1, v2, v3
	v_lshl_add_u64 v[2:3], v[136:137], 1, s[26:27]
	s_cmp_lg_u32 s99, 0
	s_cbranch_scc1 .Lwt1403_37195
	global_store_dwordx2 v[2:3], v[0:1], off
	s_branch .Lwj1403_37195

; __device__ __forceinline__ f32x4 ror1v(f32x4 v) { return (f32x4){dpp_ror1(v[0]), dpp_ror1(v[1]), dpp_ror1(v[2]), dpp_ror1(v[3])}; }
; __device__ __forceinline__ f32x4 ror2v(f32x4 v) { return (f32x4){dpp_ror2(v[0]), dpp_ror2(v[1]), dpp_ror2(v[2]), dpp_ror2(v[3])}; }
; __device__ __forceinline__ f32x4 unpack4(u32x2 w) { return (f32x4){bflo(w.x), bfhi(w.x), bflo(w.y), bfhi(w.y)}; }
;     __device__ __forceinline__ void operator()(AccRef acc, const Unit& u, int wr, int wc, int fr, int fq) const {
;     ...
;             for (int n = 0; n < 2; ++n) { const unsigned jn = (unsigned)(j0 + 4 * n);
;                 f32x4 cu[4];
;                 {
;                     const f32x4 wu0 = *(const f32x4*)(cw + (DFF + jn)), wu1 = *(const f32x4*)(cw + (UPN + DFF + jn)), wu2 = *(const f32x4*)(cw + (2 * UPN + DFF + jn)), bu = *(const f32x4*)(cb + (DFF + jn));
;                     f32x4 pu1 = (f32x4){0.f, 0.f, 0.f, 0.f}, pu2 = pu1;
; #pragma unroll
;                     for (int m = 0; m < 4; ++m) {
;                         const f32x4 au = unpack4(pa[ai][1][m][n]);
;                         const f32x4 ru1 = ror1v(au), ru2 = ror2v(au);
;                         const f32x4 u1 = fr >= 1 ? ru1 : pu1, u2 = fr >= 2 ? ru2 : pu2;
;                         if (m == 0 && fr < 2) *(f32x4*)(edge + (unsigned)((grp * 4 + fr) * UPN + DFF + jn)) = au;
;                         if (m == 3 && fr >= 14) *(f32x4*)(edge + (unsigned)((grp * 4 + (fr - 12)) * UPN + DFF + jn)) = au;
;                         cu[m] = bu + wu0 * u2 + wu1 * u1 + wu2 * au;
.Lwj1403_37195:
	global_load_dwordx4 v[8:11], v[60:61], off
	global_load_dwordx4 v[4:7], v[66:67], off
	s_nop 0
	global_load_dwordx4 v[0:3], v[68:69], off
	global_load_dwordx4 v[12:15], v[70:71], off
	s_nop 1
	v_mov_b32_dpp v93, v36 row_ror:1 row_mask:0xf bank_mask:0xf
	v_mov_b32_dpp v112, v37 row_ror:1 row_mask:0xf bank_mask:0xf
	v_mov_b32_dpp v104, v38 row_ror:1 row_mask:0xf bank_mask:0xf
	v_mov_b32_dpp v114, v39 row_ror:1 row_mask:0xf bank_mask:0xf
	v_mov_b32_dpp v105, v36 row_ror:2 row_mask:0xf bank_mask:0xf
	v_mov_b32_dpp v115, v37 row_ror:2 row_mask:0xf bank_mask:0xf
	v_mov_b32_dpp v117, v38 row_ror:2 row_mask:0xf bank_mask:0xf
	v_mov_b32_dpp v119, v39 row_ror:2 row_mask:0xf bank_mask:0xf
	s_and_saveexec_b64 s[0:1], s[12:13]
	s_cbranch_execz .LBB0_1438
	v_add_u32_e32 v136, v46, v45
	v_lshl_add_u64 v[16:17], v[136:137], 2, s[28:29]
	s_cmp_lg_u32 s99, 0
	s_cbranch_scc1 .Lwt1403_37215
	global_store_dwordx4 v[16:17], v[36:39], off
	s_branch .Lwj1403_37215

; __device__ __forceinline__ f32x4 ror1v(f32x4 v) { return (f32x4){dpp_ror1(v[0]), dpp_ror1(v[1]), dpp_ror1(v[2]), dpp_ror1(v[3])}; }
; __device__ __forceinline__ f32x4 ror2v(f32x4 v) { return (f32x4){dpp_ror2(v[0]), dpp_ror2(v[1]), dpp_ror2(v[2]), dpp_ror2(v[3])}; }
; __device__ __forceinline__ f32x4 unpack4(u32x2 w) { return (f32x4){bflo(w.x), bfhi(w.x), bflo(w.y), bfhi(w.y)}; }
;     __device__ __forceinline__ void operator()(AccRef acc, const Unit& u, int wr, int wc, int fr, int fq) const {
;     ...
; #pragma unroll
;                     for (int m = 0; m < 4; ++m) {
;                         const f32x4 au = unpack4(pa[ai][1][m][n]);
;                         const f32x4 ru1 = ror1v(au), ru2 = ror2v(au);
;                         const f32x4 u1 = fr >= 1 ? ru1 : pu1, u2 = fr >= 2 ? ru2 : pu2;
;                         if (m == 0 && fr < 2) *(f32x4*)(edge + (unsigned)((grp * 4 + fr) * UPN + DFF + jn)) = au;
;                         if (m == 3 && fr >= 14) *(f32x4*)(edge + (unsigned)((grp * 4 + (fr - 12)) * UPN + DFF + jn)) = au;
;                         cu[m] = bu + wu0 * u2 + wu1 * u1 + wu2 * au;
;                         pu1 = ru1; pu2 = ru2; }
.Lwj1403_37215:
.LBB0_1438:
	s_or_b64 exec, exec, s[0:1]
	v_lshlrev_b32_e32 v52, 16, v106
	v_and_b32_e32 v53, 0xffff0000, v106
	v_lshlrev_b32_e32 v50, 16, v107
	v_and_b32_e32 v51, 0xffff0000, v107
	s_nop 1
	v_lshlrev_b32_e32 v48, 16, v108
	v_and_b32_e32 v49, 0xffff0000, v108
	v_lshlrev_b32_e32 v44, 16, v109
	v_and_b32_e32 v45, 0xffff0000, v109
	s_nop 1
	v_lshlrev_b32_e32 v16, 16, v110
	v_and_b32_e32 v17, 0xffff0000, v110
	v_lshlrev_b32_e32 v18, 16, v111
	v_and_b32_e32 v19, 0xffff0000, v111
	s_nop 1
	v_mov_b32_dpp v92, v52 row_ror:1 row_mask:0xf bank_mask:0xf
	v_mov_b32_dpp v106, v53 row_ror:1 row_mask:0xf bank_mask:0xf
	v_mov_b32_dpp v94, v50 row_ror:1 row_mask:0xf bank_mask:0xf
	v_mov_b32_dpp v107, v51 row_ror:1 row_mask:0xf bank_mask:0xf
	v_mov_b32_dpp v95, v52 row_ror:2 row_mask:0xf bank_mask:0xf
	v_mov_b32_dpp v113, v53 row_ror:2 row_mask:0xf bank_mask:0xf
	v_mov_b32_dpp v116, v50 row_ror:2 row_mask:0xf bank_mask:0xf
	v_mov_b32_dpp v118, v51 row_ror:2 row_mask:0xf bank_mask:0xf
	v_mov_b32_dpp v65, v48 row_ror:1 row_mask:0xf bank_mask:0xf
	v_mov_b32_dpp v68, v49 row_ror:1 row_mask:0xf bank_mask:0xf
	v_mov_b32_dpp v66, v44 row_ror:1 row_mask:0xf bank_mask:0xf
	v_mov_b32_dpp v69, v45 row_ror:1 row_mask:0xf bank_mask:0xf
	v_mov_b32_dpp v67, v48 row_ror:2 row_mask:0xf bank_mask:0xf
	v_mov_b32_dpp v70, v49 row_ror:2 row_mask:0xf bank_mask:0xf
	v_mov_b32_dpp v71, v44 row_ror:2 row_mask:0xf bank_mask:0xf
	v_mov_b32_dpp v83, v45 row_ror:2 row_mask:0xf bank_mask:0xf
	v_mov_b32_dpp v84, v16 row_ror:1 row_mask:0xf bank_mask:0xf
	v_mov_b32_dpp v87, v17 row_ror:1 row_mask:0xf bank_mask:0xf
	v_mov_b32_dpp v85, v18 row_ror:1 row_mask:0xf bank_mask:0xf
	v_mov_b32_dpp v88, v19 row_ror:1 row_mask:0xf bank_mask:0xf
	v_mov_b32_dpp v86, v16 row_ror:2 row_mask:0xf bank_mask:0xf
	v_mov_b32_dpp v89, v17 row_ror:2 row_mask:0xf bank_mask:0xf
	v_mov_b32_dpp v90, v18 row_ror:2 row_mask:0xf bank_mask:0xf
	v_mov_b32_dpp v91, v19 row_ror:2 row_mask:0xf bank_mask:0xf
	s_and_saveexec_b64 s[0:1], vcc
	s_cbranch_execz .LBB0_1440
	v_add_u32_e32 v136, v81, v46
	v_lshl_add_u64 v[20:21], v[136:137], 2, s[28:29]
	s_cmp_lg_u32 s99, 0
	s_cbranch_scc1 .Lwt1403_37262
	global_store_dwordx4 v[20:21], v[16:19], off
	s_branch .Lwj1403_37262

; __device__ __forceinline__ f32x4 gelu4(f32x4 v) { const f32x2 a = gelu_pk((f32x2){v[0], v[1]}), b = gelu_pk((f32x2){v[2], v[3]}); return (f32x4){a.x, a.y, b.x, b.y}; }
; __device__ __forceinline__ f32x4 ror1v(f32x4 v) { return (f32x4){dpp_ror1(v[0]), dpp_ror1(v[1]), dpp_ror1(v[2]), dpp_ror1(v[3])}; }
; __device__ __forceinline__ f32x4 ror2v(f32x4 v) { return (f32x4){dpp_ror2(v[0]), dpp_ror2(v[1]), dpp_ror2(v[2]), dpp_ror2(v[3])}; }
; __device__ __forceinline__ u32x2 pack4(f32x4 v) { return (u32x2){pk2(v[0], v[1]), pk2(v[2], v[3])}; }
; __device__ __forceinline__ f32x4 unpack4(u32x2 w) { return (f32x4){bflo(w.x), bfhi(w.x), bflo(w.y), bfhi(w.y)}; }
;     __device__ __forceinline__ void operator()(AccRef acc, const Unit& u, int wr, int wc, int fr, int fq) const {
;     ...
;                 {
;                     const f32x4 wg0 = *(const f32x4*)(cw + jn), wg1 = *(const f32x4*)(cw + (UPN + jn)), wg2 = *(const f32x4*)(cw + (2 * UPN + jn)), bg = *(const f32x4*)(cb + jn);
;                     f32x4 pg1 = (f32x4){0.f, 0.f, 0.f, 0.f}, pg2 = pg1;
; #pragma unroll
;                     for (int m = 0; m < 4; ++m) { const int row = rowg + m * 16 + fr;
;                         const f32x4 ag = unpack4(pa[ai][0][m][n]);
;                         const f32x4 rg1 = ror1v(ag), rg2 = ror2v(ag);
;                         const f32x4 g1 = fr >= 1 ? rg1 : pg1, g2 = fr >= 2 ? rg2 : pg2;
;                         if (m == 0 && fr < 2) *(f32x4*)(edge + (unsigned)((grp * 4 + fr) * UPN + jn)) = ag;
;                         if (m == 3 && fr >= 14) *(f32x4*)(edge + (unsigned)((grp * 4 + (fr - 12)) * UPN + jn)) = ag;
;                         const f32x4 o = gelu4(bg + wg0 * g2 + wg1 * g1 + wg2 * ag) * cu[m];
;                         if (!(m == 0 && fr < 2)) *(u32x2*)(act + (unsigned)(row * DFF + jn)) = pack4(o);
;                         pg1 = rg1; pg2 = rg2; }
.Lwj1403_37262:
.LBB0_1440:
	s_or_b64 exec, exec, s[0:1]
	global_load_dwordx4 v[28:31], v[72:73], off
	global_load_dwordx4 v[24:27], v[74:75], off
	global_load_dwordx4 v[20:23], v[76:77], off
	global_load_dwordx4 v[32:35], v[78:79], off
	v_lshlrev_b32_e32 v40, 16, v102
	v_and_b32_e32 v41, 0xffff0000, v102
	v_lshlrev_b32_e32 v42, 16, v103
	v_and_b32_e32 v43, 0xffff0000, v103
	s_nop 1
	v_mov_b32_dpp v54, v40 row_ror:1 row_mask:0xf bank_mask:0xf
	v_mov_b32_dpp v55, v41 row_ror:1 row_mask:0xf bank_mask:0xf
	v_mov_b32_dpp v56, v42 row_ror:1 row_mask:0xf bank_mask:0xf
	v_mov_b32_dpp v57, v43 row_ror:1 row_mask:0xf bank_mask:0xf
	v_mov_b32_dpp v58, v40 row_ror:2 row_mask:0xf bank_mask:0xf
	v_mov_b32_dpp v59, v41 row_ror:2 row_mask:0xf bank_mask:0xf
	v_mov_b32_dpp v60, v42 row_ror:2 row_mask:0xf bank_mask:0xf
	v_mov_b32_dpp v61, v43 row_ror:2 row_mask:0xf bank_mask:0xf
	s_and_saveexec_b64 s[0:1], s[10:11]
	s_xor_b64 s[10:11], exec, s[0:1]
	s_cbranch_execz .LBB0_1442
	v_cndmask_b32_e64 v77, 0, v119, s[6:7]
	v_cndmask_b32_e64 v76, 0, v117, s[6:7]
	v_cndmask_b32_e64 v75, 0, v114, s[8:9]
	v_cndmask_b32_e64 v74, 0, v104, s[8:9]
	s_waitcnt vmcnt(4)
	v_pk_fma_f32 v[76:77], v[10:11], v[76:77], v[14:15]
	v_cndmask_b32_e64 v79, 0, v115, s[6:7]
	v_pk_fma_f32 v[74:75], v[6:7], v[74:75], v[76:77]
	v_cndmask_b32_e64 v78, 0, v105, s[6:7]
	v_pk_fma_f32 v[38:39], v[2:3], v[38:39], v[74:75]
	s_waitcnt vmcnt(0)
	v_pk_fma_f32 v[74:75], v[28:29], v[58:59], v[32:33]
	v_cndmask_b32_e64 v73, 0, v112, s[8:9]
	v_pk_fma_f32 v[74:75], v[24:25], v[54:55], v[74:75]
	v_cndmask_b32_e64 v72, 0, v93, s[8:9]
	v_pk_fma_f32 v[40:41], v[20:21], v[40:41], v[74:75]
	v_pk_fma_f32 v[78:79], v[8:9], v[78:79], v[12:13]
	v_and_b32_e32 v77, 0x7fffffff, v41
	v_and_b32_e32 v76, 0x7fffffff, v40
	v_pk_fma_f32 v[76:77], v[76:77], s[52:53], 1.0 op_sel_hi:[1,0,0]
	v_pk_fma_f32 v[72:73], v[4:5], v[72:73], v[78:79]
	v_rcp_f32_e32 v76, v76
	v_rcp_f32_e32 v77, v77
	v_pk_mul_f32 v[74:75], v[40:41], v[40:41]
	v_mov_b64_e32 v[78:79], s[56:57]
	v_pk_mul_f32 v[74:75], v[74:75], s[42:43] op_sel_hi:[1,0]
	v_pk_fma_f32 v[80:81], v[76:77], s[54:55], v[78:79] op_sel_hi:[1,0,0]
	v_exp_f32_e32 v74, v74
	v_exp_f32_e32 v75, v75
	v_pk_fma_f32 v[80:81], v[76:77], v[80:81], s[58:59] op_sel_hi:[1,1,0]
	v_pk_fma_f32 v[36:37], v[0:1], v[36:37], v[72:73]
	v_pk_fma_f32 v[80:81], v[76:77], v[80:81], s[60:61] op_sel_hi:[1,1,0]
	v_pk_fma_f32 v[72:73], v[30:31], v[60:61], v[34:35]
	v_pk_fma_f32 v[80:81], v[76:77], v[80:81], s[62:63] op_sel_hi:[1,1,0]
	v_pk_fma_f32 v[72:73], v[26:27], v[56:57], v[72:73]
	v_pk_mul_f32 v[76:77], v[76:77], v[80:81]
	v_cmp_gt_f32_e64 s[0:1], 0, v40
	v_pk_mul_f32 v[74:75], v[74:75], v[76:77]
	v_pk_fma_f32 v[42:43], v[22:23], v[42:43], v[72:73]
	v_pk_mul_f32 v[76:77], v[40:41], v[74:75]
	v_pk_fma_f32 v[74:75], v[40:41], v[74:75], v[40:41] neg_lo:[1,0,0] neg_hi:[1,0,0]
	v_pk_mul_f32 v[72:73], v[42:43], v[42:43]
	v_cndmask_b32_e64 v40, v74, v76, s[0:1]
	v_cmp_gt_f32_e64 s[0:1], 0, v41
	v_and_b32_e32 v74, 0x7fffffff, v42
	v_pk_mul_f32 v[72:73], v[72:73], s[42:43] op_sel_hi:[1,0]
	v_cndmask_b32_e64 v41, v75, v77, s[0:1]
	v_and_b32_e32 v75, 0x7fffffff, v43
	v_pk_fma_f32 v[74:75], v[74:75], s[52:53], 1.0 op_sel_hi:[1,0,0]
	v_exp_f32_e32 v72, v72
	v_rcp_f32_e32 v74, v74
	v_rcp_f32_e32 v75, v75
	v_exp_f32_e32 v73, v73
	v_cmp_gt_f32_e64 s[0:1], 0, v42
	v_pk_mul_f32 v[36:37], v[36:37], v[40:41]
	v_pk_fma_f32 v[76:77], v[74:75], s[54:55], v[78:79] op_sel_hi:[1,0,0]
	v_add_u32_e32 v136, v82, v46
	v_pk_fma_f32 v[76:77], v[74:75], v[76:77], s[58:59] op_sel_hi:[1,1,0]
	v_cvt_pk_bf16_f32 v36, v36, v37
	s_nop 0
	v_pk_fma_f32 v[76:77], v[74:75], v[76:77], s[60:61] op_sel_hi:[1,1,0]
	s_nop 0
	v_pk_fma_f32 v[76:77], v[74:75], v[76:77], s[62:63] op_sel_hi:[1,1,0]
	s_nop 0
	v_pk_mul_f32 v[74:75], v[74:75], v[76:77]
	s_nop 0
	v_pk_mul_f32 v[72:73], v[72:73], v[74:75]
	s_nop 0
	v_pk_mul_f32 v[74:75], v[42:43], v[72:73]
	v_pk_fma_f32 v[72:73], v[42:43], v[72:73], v[42:43] neg_lo:[1,0,0] neg_hi:[1,0,0]
	s_nop 0
	v_cndmask_b32_e64 v42, v72, v74, s[0:1]
	v_cmp_gt_f32_e64 s[0:1], 0, v43
	s_nop 1
	v_cndmask_b32_e64 v43, v73, v75, s[0:1]
	v_pk_mul_f32 v[38:39], v[38:39], v[42:43]
	s_nop 0
	v_cvt_pk_bf16_f32 v37, v38, v39
	v_lshl_add_u64 v[38:39], v[136:137], 1, s[26:27]
	s_cmp_lg_u32 s99, 0
	s_cbranch_scc1 .Lwt1403_37371
	global_store_dwordx2 v[38:39], v[36:37], off
	s_branch .Lwj1403_37371

; __device__ __forceinline__ f32x4 gelu4(f32x4 v) { const f32x2 a = gelu_pk((f32x2){v[0], v[1]}), b = gelu_pk((f32x2){v[2], v[3]}); return (f32x4){a.x, a.y, b.x, b.y}; }
; __device__ __forceinline__ u32x2 pack4(f32x4 v) { return (u32x2){pk2(v[0], v[1]), pk2(v[2], v[3])}; }
;     __device__ __forceinline__ void operator()(AccRef acc, const Unit& u, int wr, int wc, int fr, int fq) const {
;     ...
;                         if (m == 0 && fr < 2) *(f32x4*)(edge + (unsigned)((grp * 4 + fr) * UPN + jn)) = ag;
;                         if (m == 3 && fr >= 14) *(f32x4*)(edge + (unsigned)((grp * 4 + (fr - 12)) * UPN + jn)) = ag;
;                         const f32x4 o = gelu4(bg + wg0 * g2 + wg1 * g1 + wg2 * ag) * cu[m];
;                         if (!(m == 0 && fr < 2)) *(u32x2*)(act + (unsigned)(row * DFF + jn)) = pack4(o);
.Lwj1403_37371:
.LBB0_1442:
	s_andn2_saveexec_b64 s[0:1], s[10:11]
	s_cbranch_execz .LBB0_1444
	v_add_u32_e32 v136, v46, v80
	v_lshl_add_u64 v[36:37], v[136:137], 2, s[28:29]
	s_cmp_lg_u32 s99, 0
	s_cbranch_scc1 .Lwt1403_37378
	global_store_dwordx4 v[36:37], v[40:43], off
	s_branch .Lwj1403_37378

; __device__ __forceinline__ f32x4 gelu4(f32x4 v) { const f32x2 a = gelu_pk((f32x2){v[0], v[1]}), b = gelu_pk((f32x2){v[2], v[3]}); return (f32x4){a.x, a.y, b.x, b.y}; }
; __device__ __forceinline__ f32x4 ror1v(f32x4 v) { return (f32x4){dpp_ror1(v[0]), dpp_ror1(v[1]), dpp_ror1(v[2]), dpp_ror1(v[3])}; }
; __device__ __forceinline__ f32x4 ror2v(f32x4 v) { return (f32x4){dpp_ror2(v[0]), dpp_ror2(v[1]), dpp_ror2(v[2]), dpp_ror2(v[3])}; }
; __device__ __forceinline__ u32x2 pack4(f32x4 v) { return (u32x2){pk2(v[0], v[1]), pk2(v[2], v[3])}; }
; __device__ __forceinline__ f32x4 unpack4(u32x2 w) { return (f32x4){bflo(w.x), bfhi(w.x), bflo(w.y), bfhi(w.y)}; }
;     __device__ __forceinline__ void operator()(AccRef acc, const Unit& u, int wr, int wc, int fr, int fq) const {
;     ...
;                     for (int m = 0; m < 4; ++m) { const int row = rowg + m * 16 + fr;
;                         const f32x4 ag = unpack4(pa[ai][0][m][n]);
;                         const f32x4 rg1 = ror1v(ag), rg2 = ror2v(ag);
;                         const f32x4 g1 = fr >= 1 ? rg1 : pg1, g2 = fr >= 2 ? rg2 : pg2;
;                         if (m == 0 && fr < 2) *(f32x4*)(edge + (unsigned)((grp * 4 + fr) * UPN + jn)) = ag;
;                         if (m == 3 && fr >= 14) *(f32x4*)(edge + (unsigned)((grp * 4 + (fr - 12)) * UPN + jn)) = ag;
;                         const f32x4 o = gelu4(bg + wg0 * g2 + wg1 * g1 + wg2 * ag) * cu[m];
;                         if (!(m == 0 && fr < 2)) *(u32x2*)(act + (unsigned)(row * DFF + jn)) = pack4(o);
;                         pg1 = rg1; pg2 = rg2; }
.Lwj1403_37378:
.LBB0_1444:
	s_or_b64 exec, exec, s[0:1]
	s_nop 0
	v_cndmask_b32_e64 v43, v115, v113, s[6:7]
	v_cndmask_b32_e64 v42, v105, v95, s[6:7]
	v_cndmask_b32_e64 v37, v112, v106, s[8:9]
	v_cndmask_b32_e64 v36, v93, v92, s[8:9]
	v_cndmask_b32_e64 v41, v119, v118, s[6:7]
	v_cndmask_b32_e64 v40, v117, v116, s[6:7]
	s_waitcnt vmcnt(4)
	v_pk_fma_f32 v[42:43], v[8:9], v[42:43], v[12:13]
	v_cndmask_b32_e64 v39, v114, v107, s[8:9]
	v_cndmask_b32_e64 v38, v104, v94, s[8:9]
	v_pk_fma_f32 v[40:41], v[10:11], v[40:41], v[14:15]
	v_pk_fma_f32 v[36:37], v[4:5], v[36:37], v[42:43]
	v_pk_fma_f32 v[38:39], v[6:7], v[38:39], v[40:41]
	v_pk_fma_f32 v[36:37], v[0:1], v[52:53], v[36:37]
	v_cndmask_b32_e64 v53, v113, v70, s[6:7]
	v_cndmask_b32_e64 v52, v95, v67, s[6:7]
	v_pk_fma_f32 v[38:39], v[2:3], v[50:51], v[38:39]
	v_cndmask_b32_e64 v41, v106, v68, s[8:9]
	v_cndmask_b32_e64 v40, v92, v65, s[8:9]
	v_cndmask_b32_e64 v51, v118, v83, s[6:7]
	v_cndmask_b32_e64 v50, v116, v71, s[6:7]
	v_pk_fma_f32 v[52:53], v[8:9], v[52:53], v[12:13]
	v_cndmask_b32_e64 v43, v107, v69, s[8:9]
	v_cndmask_b32_e64 v42, v94, v66, s[8:9]
	v_pk_fma_f32 v[50:51], v[10:11], v[50:51], v[14:15]
	v_pk_fma_f32 v[40:41], v[4:5], v[40:41], v[52:53]
	v_pk_fma_f32 v[42:43], v[6:7], v[42:43], v[50:51]
	v_pk_fma_f32 v[50:51], v[0:1], v[48:49], v[40:41]
	v_lshlrev_b32_e32 v40, 16, v100
	v_and_b32_e32 v41, 0xffff0000, v100
	s_nop 1
	v_mov_b32_dpp v72, v40 row_ror:1 row_mask:0xf bank_mask:0xf
	v_mov_b32_dpp v73, v41 row_ror:1 row_mask:0xf bank_mask:0xf
	v_mov_b32_dpp v76, v40 row_ror:2 row_mask:0xf bank_mask:0xf
	v_mov_b32_dpp v77, v41 row_ror:2 row_mask:0xf bank_mask:0xf
	v_cndmask_b32_e64 v49, v55, v73, s[8:9]
	v_cndmask_b32_e64 v48, v54, v72, s[8:9]
	v_cndmask_b32_e64 v55, v59, v77, s[6:7]
	v_cndmask_b32_e64 v54, v58, v76, s[6:7]
	s_waitcnt vmcnt(2)
	v_pk_fma_f32 v[54:55], v[28:29], v[54:55], v[32:33]
	v_pk_fma_f32 v[52:53], v[2:3], v[44:45], v[42:43]
	v_pk_fma_f32 v[48:49], v[24:25], v[48:49], v[54:55]
	v_lshlrev_b32_e32 v42, 16, v101
	v_pk_fma_f32 v[40:41], v[20:21], v[40:41], v[48:49]
	v_and_b32_e32 v43, 0xffff0000, v101
	v_and_b32_e32 v55, 0x7fffffff, v41
	v_and_b32_e32 v54, 0x7fffffff, v40
	s_nop 1
	v_pk_fma_f32 v[54:55], v[54:55], s[52:53], 1.0 op_sel_hi:[1,0,0]
	v_mov_b32_dpp v74, v42 row_ror:1 row_mask:0xf bank_mask:0xf
	v_mov_b32_dpp v75, v43 row_ror:1 row_mask:0xf bank_mask:0xf
	v_mov_b32_dpp v78, v42 row_ror:2 row_mask:0xf bank_mask:0xf
	v_mov_b32_dpp v79, v43 row_ror:2 row_mask:0xf bank_mask:0xf
	v_rcp_f32_e32 v54, v54
	v_rcp_f32_e32 v55, v55
	v_cndmask_b32_e64 v45, v57, v75, s[8:9]
	v_cndmask_b32_e64 v44, v56, v74, s[8:9]
	v_cndmask_b32_e64 v57, v61, v79, s[6:7]
	v_cndmask_b32_e64 v56, v60, v78, s[6:7]
	v_pk_fma_f32 v[56:57], v[30:31], v[56:57], v[34:35]
	v_pk_mul_f32 v[48:49], v[40:41], v[40:41]
	v_pk_fma_f32 v[44:45], v[26:27], v[44:45], v[56:57]
	v_mov_b64_e32 v[56:57], s[56:57]
	v_pk_mul_f32 v[48:49], v[48:49], s[42:43] op_sel_hi:[1,0]
	v_pk_fma_f32 v[58:59], v[54:55], s[54:55], v[56:57] op_sel_hi:[1,0,0]
	v_exp_f32_e32 v48, v48
	v_exp_f32_e32 v49, v49
	v_pk_fma_f32 v[58:59], v[54:55], v[58:59], s[58:59] op_sel_hi:[1,1,0]
	v_cmp_gt_f32_e64 s[0:1], 0, v40
	v_pk_fma_f32 v[58:59], v[54:55], v[58:59], s[60:61] op_sel_hi:[1,1,0]
	v_pk_fma_f32 v[42:43], v[22:23], v[42:43], v[44:45]
	v_pk_fma_f32 v[58:59], v[54:55], v[58:59], s[62:63] op_sel_hi:[1,1,0]
	v_pk_mul_f32 v[44:45], v[42:43], v[42:43]
	v_pk_mul_f32 v[54:55], v[54:55], v[58:59]
	v_pk_mul_f32 v[44:45], v[44:45], s[42:43] op_sel_hi:[1,0]
	v_pk_mul_f32 v[48:49], v[48:49], v[54:55]
	v_exp_f32_e32 v44, v44
	v_pk_mul_f32 v[54:55], v[40:41], v[48:49]
	v_pk_fma_f32 v[48:49], v[40:41], v[48:49], v[40:41] neg_lo:[1,0,0] neg_hi:[1,0,0]
	v_exp_f32_e32 v45, v45
	v_cndmask_b32_e64 v40, v48, v54, s[0:1]
	v_cmp_gt_f32_e64 s[0:1], 0, v41
	v_and_b32_e32 v48, 0x7fffffff, v42
	v_add_u32_e32 v136, v62, v46
	v_cndmask_b32_e64 v41, v49, v55, s[0:1]
	v_and_b32_e32 v49, 0x7fffffff, v43
	v_pk_fma_f32 v[48:49], v[48:49], s[52:53], 1.0 op_sel_hi:[1,0,0]
	v_cmp_gt_f32_e64 s[0:1], 0, v42
	v_rcp_f32_e32 v48, v48
	v_rcp_f32_e32 v49, v49
	v_pk_mul_f32 v[36:37], v[36:37], v[40:41]
	s_nop 1
	v_cvt_pk_bf16_f32 v36, v36, v37
	v_pk_fma_f32 v[54:55], v[48:49], s[54:55], v[56:57] op_sel_hi:[1,0,0]
	s_nop 1
	v_pk_fma_f32 v[54:55], v[48:49], v[54:55], s[58:59] op_sel_hi:[1,1,0]
	s_nop 0
	v_pk_fma_f32 v[54:55], v[48:49], v[54:55], s[60:61] op_sel_hi:[1,1,0]
	s_nop 0
	v_pk_fma_f32 v[54:55], v[48:49], v[54:55], s[62:63] op_sel_hi:[1,1,0]
	s_nop 0
	v_pk_mul_f32 v[48:49], v[48:49], v[54:55]
	s_nop 0
	v_pk_mul_f32 v[44:45], v[44:45], v[48:49]
	s_nop 0
	v_pk_mul_f32 v[48:49], v[42:43], v[44:45]
	v_pk_fma_f32 v[44:45], v[42:43], v[44:45], v[42:43] neg_lo:[1,0,0] neg_hi:[1,0,0]
	s_nop 0
	v_cndmask_b32_e64 v42, v44, v48, s[0:1]
	v_cmp_gt_f32_e64 s[0:1], 0, v43
	s_nop 1
	v_cndmask_b32_e64 v43, v45, v49, s[0:1]
	v_pk_mul_f32 v[38:39], v[38:39], v[42:43]
	s_nop 1
	v_cvt_pk_bf16_f32 v37, v38, v39
	v_lshl_add_u64 v[38:39], v[136:137], 1, s[26:27]
	s_cmp_lg_u32 s99, 0
	s_cbranch_scc1 .Lwt1403_37503
	global_store_dwordx2 v[38:39], v[36:37], off
	s_branch .Lwj1403_37503

; __device__ __forceinline__ f32x4 gelu4(f32x4 v) { const f32x2 a = gelu_pk((f32x2){v[0], v[1]}), b = gelu_pk((f32x2){v[2], v[3]}); return (f32x4){a.x, a.y, b.x, b.y}; }
; __device__ __forceinline__ f32x4 ror1v(f32x4 v) { return (f32x4){dpp_ror1(v[0]), dpp_ror1(v[1]), dpp_ror1(v[2]), dpp_ror1(v[3])}; }
; __device__ __forceinline__ f32x4 ror2v(f32x4 v) { return (f32x4){dpp_ror2(v[0]), dpp_ror2(v[1]), dpp_ror2(v[2]), dpp_ror2(v[3])}; }
; __device__ __forceinline__ u32x2 pack4(f32x4 v) { return (u32x2){pk2(v[0], v[1]), pk2(v[2], v[3])}; }
; __device__ __forceinline__ f32x4 unpack4(u32x2 w) { return (f32x4){bflo(w.x), bfhi(w.x), bflo(w.y), bfhi(w.y)}; }
;     __device__ __forceinline__ void operator()(AccRef acc, const Unit& u, int wr, int wc, int fr, int fq) const {
;     ...
;                     for (int m = 0; m < 4; ++m) { const int row = rowg + m * 16 + fr;
;                         const f32x4 ag = unpack4(pa[ai][0][m][n]);
;                         const f32x4 rg1 = ror1v(ag), rg2 = ror2v(ag);
;                         const f32x4 g1 = fr >= 1 ? rg1 : pg1, g2 = fr >= 2 ? rg2 : pg2;
;                         if (m == 0 && fr < 2) *(f32x4*)(edge + (unsigned)((grp * 4 + fr) * UPN + jn)) = ag;
;                         if (m == 3 && fr >= 14) *(f32x4*)(edge + (unsigned)((grp * 4 + (fr - 12)) * UPN + jn)) = ag;
;                         const f32x4 o = gelu4(bg + wg0 * g2 + wg1 * g1 + wg2 * ag) * cu[m];
;                         if (!(m == 0 && fr < 2)) *(u32x2*)(act + (unsigned)(row * DFF + jn)) = pack4(o);
;                         pg1 = rg1; pg2 = rg2; }
.Lwj1403_37503:
	v_lshlrev_b32_e32 v36, 16, v98
	v_and_b32_e32 v37, 0xffff0000, v98
	v_lshlrev_b32_e32 v38, 16, v99
	v_mov_b32_dpp v44, v36 row_ror:2 row_mask:0xf bank_mask:0xf
	v_mov_b32_dpp v48, v37 row_ror:2 row_mask:0xf bank_mask:0xf
	v_mov_b32_dpp v40, v36 row_ror:1 row_mask:0xf bank_mask:0xf
	v_mov_b32_dpp v41, v37 row_ror:1 row_mask:0xf bank_mask:0xf
	v_cndmask_b32_e64 v61, v77, v48, s[6:7]
	v_cndmask_b32_e64 v60, v76, v44, s[6:7]
	v_cndmask_b32_e64 v59, v73, v41, s[8:9]
	v_cndmask_b32_e64 v58, v72, v40, s[8:9]
	v_pk_fma_f32 v[60:61], v[28:29], v[60:61], v[32:33]
	v_and_b32_e32 v39, 0xffff0000, v99
	v_pk_fma_f32 v[58:59], v[24:25], v[58:59], v[60:61]
	s_nop 1
	v_pk_fma_f32 v[36:37], v[20:21], v[36:37], v[58:59]
	s_nop 1
	v_and_b32_e32 v61, 0x7fffffff, v37
	v_and_b32_e32 v60, 0x7fffffff, v36
	v_pk_fma_f32 v[60:61], v[60:61], s[52:53], 1.0 op_sel_hi:[1,0,0]
	s_nop 1
	v_rcp_f32_e32 v60, v60
	v_rcp_f32_e32 v61, v61
	v_mov_b32_dpp v45, v38 row_ror:2 row_mask:0xf bank_mask:0xf
	v_mov_b32_dpp v49, v39 row_ror:2 row_mask:0xf bank_mask:0xf
	v_mov_b32_dpp v42, v38 row_ror:1 row_mask:0xf bank_mask:0xf
	v_mov_b32_dpp v43, v39 row_ror:1 row_mask:0xf bank_mask:0xf
	v_cndmask_b32_e64 v73, v79, v49, s[6:7]
	v_cndmask_b32_e64 v72, v78, v45, s[6:7]
	v_cndmask_b32_e64 v55, v75, v43, s[8:9]
	v_cndmask_b32_e64 v54, v74, v42, s[8:9]
	v_pk_fma_f32 v[72:73], v[30:31], v[72:73], v[34:35]
	v_pk_mul_f32 v[58:59], v[36:37], v[36:37]
	v_pk_fma_f32 v[54:55], v[26:27], v[54:55], v[72:73]
	v_pk_mul_f32 v[58:59], v[58:59], s[42:43] op_sel_hi:[1,0]
	v_pk_fma_f32 v[72:73], v[60:61], s[54:55], v[56:57] op_sel_hi:[1,0,0]
	v_exp_f32_e32 v58, v58
	v_exp_f32_e32 v59, v59
	v_pk_fma_f32 v[72:73], v[60:61], v[72:73], s[58:59] op_sel_hi:[1,1,0]
	v_cmp_gt_f32_e64 s[0:1], 0, v36
	v_pk_fma_f32 v[72:73], v[60:61], v[72:73], s[60:61] op_sel_hi:[1,1,0]
	v_pk_fma_f32 v[38:39], v[22:23], v[38:39], v[54:55]
	v_pk_fma_f32 v[72:73], v[60:61], v[72:73], s[62:63] op_sel_hi:[1,1,0]
	v_pk_mul_f32 v[54:55], v[38:39], v[38:39]
	v_pk_mul_f32 v[60:61], v[60:61], v[72:73]
	v_pk_mul_f32 v[54:55], v[54:55], s[42:43] op_sel_hi:[1,0]
	v_pk_mul_f32 v[58:59], v[58:59], v[60:61]
	v_exp_f32_e32 v54, v54
	v_pk_mul_f32 v[60:61], v[36:37], v[58:59]
	v_pk_fma_f32 v[58:59], v[36:37], v[58:59], v[36:37] neg_lo:[1,0,0] neg_hi:[1,0,0]
	v_exp_f32_e32 v55, v55
	v_cndmask_b32_e64 v36, v58, v60, s[0:1]
	v_cmp_gt_f32_e64 s[0:1], 0, v37
	v_and_b32_e32 v58, 0x7fffffff, v38
	v_add_u32_e32 v136, v63, v46
	v_cndmask_b32_e64 v37, v59, v61, s[0:1]
	v_and_b32_e32 v59, 0x7fffffff, v39
	v_pk_fma_f32 v[58:59], v[58:59], s[52:53], 1.0 op_sel_hi:[1,0,0]
	v_cmp_gt_f32_e64 s[0:1], 0, v38
	v_rcp_f32_e32 v58, v58
	v_rcp_f32_e32 v59, v59
	v_pk_mul_f32 v[36:37], v[50:51], v[36:37]
	s_nop 1
	v_cvt_pk_bf16_f32 v36, v36, v37
	v_pk_fma_f32 v[56:57], v[58:59], s[54:55], v[56:57] op_sel_hi:[1,0,0]
	s_nop 1
	v_pk_fma_f32 v[56:57], v[58:59], v[56:57], s[58:59] op_sel_hi:[1,1,0]
	s_nop 0
	v_pk_fma_f32 v[56:57], v[58:59], v[56:57], s[60:61] op_sel_hi:[1,1,0]
	s_nop 0
	v_pk_fma_f32 v[56:57], v[58:59], v[56:57], s[62:63] op_sel_hi:[1,1,0]
	s_nop 0
	v_pk_mul_f32 v[56:57], v[58:59], v[56:57]
	s_nop 0
	v_pk_mul_f32 v[54:55], v[54:55], v[56:57]
	s_nop 0
	v_pk_mul_f32 v[56:57], v[38:39], v[54:55]
	v_pk_fma_f32 v[54:55], v[38:39], v[54:55], v[38:39] neg_lo:[1,0,0] neg_hi:[1,0,0]
	s_nop 0
	v_cndmask_b32_e64 v38, v54, v56, s[0:1]
	v_cmp_gt_f32_e64 s[0:1], 0, v39
	s_nop 1
	v_cndmask_b32_e64 v39, v55, v57, s[0:1]
	v_pk_mul_f32 v[38:39], v[52:53], v[38:39]
	s_nop 1
	v_cvt_pk_bf16_f32 v37, v38, v39
	v_lshl_add_u64 v[38:39], v[136:137], 1, s[26:27]
	s_cmp_lg_u32 s99, 0
	s_cbranch_scc1 .Lwt1403_37595
	global_store_dwordx2 v[38:39], v[36:37], off
	s_branch .Lwj1403_37595

; __device__ __forceinline__ f32x4 ror1v(f32x4 v) { return (f32x4){dpp_ror1(v[0]), dpp_ror1(v[1]), dpp_ror1(v[2]), dpp_ror1(v[3])}; }
; __device__ __forceinline__ f32x4 ror2v(f32x4 v) { return (f32x4){dpp_ror2(v[0]), dpp_ror2(v[1]), dpp_ror2(v[2]), dpp_ror2(v[3])}; }
; __device__ __forceinline__ f32x4 unpack4(u32x2 w) { return (f32x4){bflo(w.x), bfhi(w.x), bflo(w.y), bfhi(w.y)}; }
;     __device__ __forceinline__ void operator()(AccRef acc, const Unit& u, int wr, int wc, int fr, int fq) const {
;     ...
;                     for (int m = 0; m < 4; ++m) { const int row = rowg + m * 16 + fr;
;                         const f32x4 ag = unpack4(pa[ai][0][m][n]);
;                         const f32x4 rg1 = ror1v(ag), rg2 = ror2v(ag);
;                         const f32x4 g1 = fr >= 1 ? rg1 : pg1, g2 = fr >= 2 ? rg2 : pg2;
;                         if (m == 0 && fr < 2) *(f32x4*)(edge + (unsigned)((grp * 4 + fr) * UPN + jn)) = ag;
;                         if (m == 3 && fr >= 14) *(f32x4*)(edge + (unsigned)((grp * 4 + (fr - 12)) * UPN + jn)) = ag;
.Lwj1403_37595:
	v_lshlrev_b32_e32 v36, 16, v96
	v_and_b32_e32 v37, 0xffff0000, v96
	v_lshlrev_b32_e32 v38, 16, v97
	v_and_b32_e32 v39, 0xffff0000, v97
	s_nop 1
	v_mov_b32_dpp v50, v36 row_ror:1 row_mask:0xf bank_mask:0xf
	v_mov_b32_dpp v51, v37 row_ror:1 row_mask:0xf bank_mask:0xf
	v_mov_b32_dpp v52, v38 row_ror:1 row_mask:0xf bank_mask:0xf
	v_mov_b32_dpp v53, v39 row_ror:1 row_mask:0xf bank_mask:0xf
	v_mov_b32_dpp v54, v36 row_ror:2 row_mask:0xf bank_mask:0xf
	v_mov_b32_dpp v56, v37 row_ror:2 row_mask:0xf bank_mask:0xf
	v_mov_b32_dpp v55, v38 row_ror:2 row_mask:0xf bank_mask:0xf
	v_mov_b32_dpp v57, v39 row_ror:2 row_mask:0xf bank_mask:0xf
	s_and_saveexec_b64 s[0:1], vcc
	s_cbranch_execz .LBB0_1446
	v_add_u32_e32 v136, v46, v47
	v_lshl_add_u64 v[58:59], v[136:137], 2, s[28:29]
	s_cmp_lg_u32 s99, 0
	s_cbranch_scc1 .Lwt1403_37614
	global_store_dwordx4 v[58:59], v[36:39], off
	s_branch .Lwj1403_37614

; __device__ __forceinline__ f32x4 gelu4(f32x4 v) { const f32x2 a = gelu_pk((f32x2){v[0], v[1]}), b = gelu_pk((f32x2){v[2], v[3]}); return (f32x4){a.x, a.y, b.x, b.y}; }
; __device__ __forceinline__ f32x4 ror1v(f32x4 v) { return (f32x4){dpp_ror1(v[0]), dpp_ror1(v[1]), dpp_ror1(v[2]), dpp_ror1(v[3])}; }
; __device__ __forceinline__ f32x4 ror2v(f32x4 v) { return (f32x4){dpp_ror2(v[0]), dpp_ror2(v[1]), dpp_ror2(v[2]), dpp_ror2(v[3])}; }
; __device__ __forceinline__ u32x2 pack4(f32x4 v) { return (u32x2){pk2(v[0], v[1]), pk2(v[2], v[3])}; }
; __device__ __forceinline__ f32x4 unpack4(u32x2 w) { return (f32x4){bflo(w.x), bfhi(w.x), bflo(w.y), bfhi(w.y)}; }
; template <class Epi>
; __device__ __forceinline__ void gemm_phase(LAS unsigned char* lds, const Gemm g, const StaticOrder& S, const Epi& E) {
;     ...
;         if (!has_next) break;
;     __device__ __forceinline__ void operator()(AccRef acc, const Unit& u, int wr, int wc, int fr, int fq) const {
;     ...
;                     for (int m = 0; m < 4; ++m) { const int row = rowg + m * 16 + fr;
;                         const f32x4 ag = unpack4(pa[ai][0][m][n]);
;                         const f32x4 rg1 = ror1v(ag), rg2 = ror2v(ag);
;                         const f32x4 g1 = fr >= 1 ? rg1 : pg1, g2 = fr >= 2 ? rg2 : pg2;
;                         if (m == 0 && fr < 2) *(f32x4*)(edge + (unsigned)((grp * 4 + fr) * UPN + jn)) = ag;
;                         if (m == 3 && fr >= 14) *(f32x4*)(edge + (unsigned)((grp * 4 + (fr - 12)) * UPN + jn)) = ag;
;                         const f32x4 o = gelu4(bg + wg0 * g2 + wg1 * g1 + wg2 * ag) * cu[m];
;                         if (!(m == 0 && fr < 2)) *(u32x2*)(act + (unsigned)(row * DFF + jn)) = pack4(o);
;                         pg1 = rg1; pg2 = rg2; }
.Lwj1403_37614:
.LBB0_1446:
	s_or_b64 exec, exec, s[0:1]
	v_cndmask_b32_e64 v43, v43, v53, s[8:9]
	v_cndmask_b32_e64 v42, v42, v52, s[8:9]
	v_cndmask_b32_e64 v53, v83, v91, s[6:7]
	v_cndmask_b32_e64 v52, v71, v90, s[6:7]
	v_cndmask_b32_e64 v41, v41, v51, s[8:9]
	v_cndmask_b32_e64 v40, v40, v50, s[8:9]
	v_cndmask_b32_e64 v51, v69, v88, s[8:9]
	v_cndmask_b32_e64 v50, v66, v85, s[8:9]
	v_pk_fma_f32 v[10:11], v[10:11], v[52:53], v[14:15]
	v_cndmask_b32_e64 v59, v48, v56, s[6:7]
	v_cndmask_b32_e64 v58, v44, v54, s[6:7]
	v_pk_fma_f32 v[6:7], v[6:7], v[50:51], v[10:11]
	v_cndmask_b32_e64 v48, v45, v55, s[6:7]
	v_pk_fma_f32 v[2:3], v[2:3], v[18:19], v[6:7]
	v_pk_fma_f32 v[6:7], v[28:29], v[58:59], v[32:33]
	v_cndmask_b32_e64 v55, v70, v89, s[6:7]
	v_pk_fma_f32 v[6:7], v[24:25], v[40:41], v[6:7]
	v_cndmask_b32_e64 v54, v67, v86, s[6:7]
	v_pk_fma_f32 v[6:7], v[20:21], v[36:37], v[6:7]
	v_pk_fma_f32 v[8:9], v[8:9], v[54:55], v[12:13]
	v_and_b32_e32 v13, 0x7fffffff, v7
	v_and_b32_e32 v12, 0x7fffffff, v6
	v_pk_fma_f32 v[12:13], v[12:13], s[52:53], 1.0 op_sel_hi:[1,0,0]
	v_cndmask_b32_e64 v45, v68, v87, s[8:9]
	v_rcp_f32_e32 v12, v12
	v_rcp_f32_e32 v13, v13
	v_cndmask_b32_e64 v44, v65, v84, s[8:9]
	v_pk_fma_f32 v[4:5], v[4:5], v[44:45], v[8:9]
	v_pk_mul_f32 v[10:11], v[6:7], v[6:7]
	v_mov_b64_e32 v[14:15], s[56:57]
	v_pk_fma_f32 v[0:1], v[0:1], v[16:17], v[4:5]
	v_pk_mul_f32 v[10:11], v[10:11], s[42:43] op_sel_hi:[1,0]
	v_pk_fma_f32 v[16:17], v[12:13], s[54:55], v[14:15] op_sel_hi:[1,0,0]
	v_exp_f32_e32 v10, v10
	v_exp_f32_e32 v11, v11
	v_pk_fma_f32 v[16:17], v[12:13], v[16:17], s[58:59] op_sel_hi:[1,1,0]
	v_cndmask_b32_e64 v49, v49, v57, s[6:7]
	v_pk_fma_f32 v[16:17], v[12:13], v[16:17], s[60:61] op_sel_hi:[1,1,0]
	v_pk_fma_f32 v[4:5], v[30:31], v[48:49], v[34:35]
	v_pk_fma_f32 v[16:17], v[12:13], v[16:17], s[62:63] op_sel_hi:[1,1,0]
	v_pk_fma_f32 v[4:5], v[26:27], v[42:43], v[4:5]
	v_pk_mul_f32 v[12:13], v[12:13], v[16:17]
	v_cmp_gt_f32_e32 vcc, 0, v6
	v_pk_mul_f32 v[10:11], v[10:11], v[12:13]
	v_pk_fma_f32 v[4:5], v[22:23], v[38:39], v[4:5]
	v_pk_mul_f32 v[12:13], v[6:7], v[10:11]
	v_pk_fma_f32 v[10:11], v[6:7], v[10:11], v[6:7] neg_lo:[1,0,0] neg_hi:[1,0,0]
	v_pk_mul_f32 v[8:9], v[4:5], v[4:5]
	v_cndmask_b32_e32 v6, v10, v12, vcc
	v_cmp_gt_f32_e32 vcc, 0, v7
	v_and_b32_e32 v10, 0x7fffffff, v4
	v_pk_mul_f32 v[8:9], v[8:9], s[42:43] op_sel_hi:[1,0]
	v_cndmask_b32_e32 v7, v11, v13, vcc
	v_and_b32_e32 v11, 0x7fffffff, v5
	v_pk_fma_f32 v[10:11], v[10:11], s[52:53], 1.0 op_sel_hi:[1,0,0]
	v_exp_f32_e32 v8, v8
	v_rcp_f32_e32 v10, v10
	v_rcp_f32_e32 v11, v11
	v_exp_f32_e32 v9, v9
	v_cmp_gt_f32_e32 vcc, 0, v4
	v_pk_mul_f32 v[0:1], v[0:1], v[6:7]
	v_pk_fma_f32 v[12:13], v[10:11], s[54:55], v[14:15] op_sel_hi:[1,0,0]
	v_add_u32_e32 v136, v64, v46
	v_pk_fma_f32 v[12:13], v[10:11], v[12:13], s[58:59] op_sel_hi:[1,1,0]
	v_cvt_pk_bf16_f32 v0, v0, v1
	s_mov_b64 s[0:1], -1
	v_pk_fma_f32 v[12:13], v[10:11], v[12:13], s[60:61] op_sel_hi:[1,1,0]
	s_nop 0
	v_pk_fma_f32 v[12:13], v[10:11], v[12:13], s[62:63] op_sel_hi:[1,1,0]
	s_nop 0
	v_pk_mul_f32 v[10:11], v[10:11], v[12:13]
	s_nop 0
	v_pk_mul_f32 v[8:9], v[8:9], v[10:11]
	s_nop 0
	v_pk_mul_f32 v[10:11], v[4:5], v[8:9]
	v_pk_fma_f32 v[8:9], v[4:5], v[8:9], v[4:5] neg_lo:[1,0,0] neg_hi:[1,0,0]
	s_nop 0
	v_cndmask_b32_e32 v4, v8, v10, vcc
	v_cmp_gt_f32_e32 vcc, 0, v5
	s_nop 1
	v_cndmask_b32_e32 v5, v9, v11, vcc
	v_pk_mul_f32 v[2:3], v[2:3], v[4:5]
	s_andn2_b64 vcc, exec, s[4:5]
	v_cvt_pk_bf16_f32 v1, v2, v3
	v_lshl_add_u64 v[2:3], v[136:137], 1, s[26:27]
	s_cmp_lg_u32 s99, 0
	s_cbranch_scc1 .Lwt1403_37706
	global_store_dwordx2 v[2:3], v[0:1], off
	s_branch .Lwj1403_37706

; #define PG8_BAR __builtin_amdgcn_s_barrier()
; template <class Epi>
; __device__ __forceinline__ void gemm_phase(LAS unsigned char* lds, const Gemm g, const StaticOrder& S, const Epi& E) {
;     ...
;         if (!has_next) break;
; #pragma unroll
;         for (int a = 0; a < 2; ++a)
; #pragma unroll
;             for (int b = 0; b < 2; ++b)
; #pragma unroll
;                 for (int m = 0; m < 4; ++m)
; #pragma unroll
;                     for (int n = 0; n < 2; ++n) acc[a][b][m][n] = (f32x4){0.f, 0.f, 0.f, 0.f};
;         cur = nxt; cA = nA; cB = nB; ++ui;
;         if (wr == 1) PG8_BAR;
.Lwj1403_37706:
	s_cbranch_vccnz .LBB0_1399
	s_andn2_b64 vcc, exec, s[16:17]
	s_cbranch_vccnz .LBB0_1398
	s_barrier
	s_branch .LBB0_1398

; #define PG8_STAGE(bufoff, gbase, voff) do { _Pragma("unroll") for (int _i = 0; _i < 2; ++_i) \
;         __builtin_amdgcn_global_load_lds((const unsigned*)((const char*)(gbase) + (voff)[_i]), (LAS unsigned*)(lds + (bufoff) + ldsw + _i * 8192), 16, 0, 0); } while (0)
; #define PG8_LDA(dst, b, h) do { _Pragma("unroll") for (int m = 0; m < 4; ++m) _Pragma("unroll") for (int k = 0; k < 2; ++k) dst[m][k] = *(const LAS bf16x8*)(lds + PG8_SA(b, h) + aoff + m * 2048 + k * 1024); } while (0)
; #define PG8_LDB(dst, b, h) do { _Pragma("unroll") for (int n = 0; n < 2; ++n) _Pragma("unroll") for (int k = 0; k < 2; ++k) dst[n][k] = *(const LAS bf16x8*)(lds + PG8_SB(b, h) + boff + n * 2048 + k * 1024); } while (0)
; #define PG8_WAIT_V(n) asm volatile("s_waitcnt vmcnt(" #n ")" ::: "memory")
; #define PG8_WAIT_L(n) asm volatile("s_waitcnt lgkmcnt(" #n ")" ::: "memory")
; template <class Epi>
; __device__ __forceinline__ void gemm_phase(LAS unsigned char* lds, const Gemm g, const StaticOrder& S, const Epi& E) {
;     ...
;         for (int t = 0; t < nt; t += 2) {
;             const bool last = (t == nt - 2);
;             const char* a1 = cA + (size_t)(t + 1) * kstep;
;             const char* a2 = last ? nA : cA + (size_t)(t + 2) * kstep; const char* b2 = last ? nB : cB + (size_t)(t + 2) * kstep;
;             const char* a3 = a2 + kstep; const char* b3 = b2 + kstep;
;             PG8_LDB(B0, 0, 0); PG8_LDB(B1, 0, 1); PG8_SCHED; PG8_LDA(At, 0, 0); PG8_STAGE(PG8_SA(1, 1), a1 + hstepA, voffA);
;             PG8_WAIT_V(8); PG8_WAIT_L(0); PG8_BAR; PG8_MMA(0, 0, At, B0); PG8_MMA(0, 1, At, B1); PG8_BAR; PG8_SCHED;
;             PG8_LDA(At, 0, 1); PG8_STAGE(PG8_SB(0, 0), b2, voffB); PG8_STAGE(PG8_SB(0, 1), b2 + hstepB, voffB); PG8_STAGE(PG8_SA(0, 0), a2, voffA);
;             PG8_WAIT_V(8); PG8_WAIT_L(0); PG8_BAR; PG8_MMA(1, 0, At, B0); PG8_MMA(1, 1, At, B1); PG8_BAR; PG8_SCHED;
;             PG8_LDB(B0, 1, 0); PG8_LDB(B1, 1, 1); PG8_SCHED; PG8_LDA(At, 1, 0); PG8_STAGE(PG8_SA(0, 1), a2 + hstepA, voffA);
;             PG8_WAIT_V(8); PG8_WAIT_L(0); PG8_BAR; PG8_MMA(0, 0, At, B0); PG8_MMA(0, 1, At, B1); PG8_BAR; PG8_SCHED;
;             PG8_LDA(At, 1, 1); PG8_STAGE(PG8_SB(1, 0), b3, voffB); PG8_STAGE(PG8_SB(1, 1), b3 + hstepB, voffB); PG8_STAGE(PG8_SA(1, 0), a3, voffA);
;             PG8_WAIT_V(8); PG8_WAIT_L(0); PG8_BAR; PG8_MMA(1, 0, At, B0); PG8_MMA(1, 1, At, B1); PG8_BAR; PG8_SCHED;
.LBB0_1469:
	s_add_u32 s62, s42, s56
	s_addc_u32 s63, s43, s57
	s_add_u32 s60, s62, 0x100
	s_addc_u32 s61, s63, 0
	s_and_b64 s[58:59], s[54:55], exec
	s_cselect_b32 s59, s1, s61
	s_cselect_b32 s58, s19, s60
	s_add_u32 s56, s38, s56
	s_addc_u32 s57, s39, s57
	s_add_u32 s56, s56, 0x100
	s_addc_u32 s57, s57, 0
	s_and_b64 s[54:55], s[54:55], exec
	s_cselect_b32 s61, s17, s57
	s_cselect_b32 s60, s84, s56
	s_add_u32 s64, s62, 0x10080
	ds_read_b128 v[140:143], v145
	ds_read_b128 v[154:157], v145 offset:1024
	ds_read_b128 v[158:161], v145 offset:2048
	ds_read_b128 v[162:165], v145 offset:3072
	ds_read_b128 v[166:169], v146
	ds_read_b128 v[170:173], v146 offset:1024
	ds_read_b128 v[178:181], v146 offset:2048
	ds_read_b128 v[182:185], v146 offset:3072
	s_addc_u32 s65, s63, 0
	s_add_i32 s94, s82, s70
	s_add_i32 m0, s35, 0xc000
	s_add_i32 s95, s35, 0xe000
	s_add_i32 s91, s94, 0x2000
	s_add_u32 s62, s60, 0x10000
	s_addc_u32 s63, s61, 0
	s_add_i32 s93, s83, s70
	s_add_i32 s92, s93, 0x2000
	s_add_i32 s90, 0, 0x18000
	s_add_i32 s89, 0, 0x1c000
	s_add_u32 s56, s58, 0x10000
	s_addc_u32 s57, s59, 0
	s_add_i32 s88, s90, s70
	s_add_i32 s86, s88, 0x2000
	s_add_u32 s54, s60, 0x10080
	s_addc_u32 s55, s61, 0
	s_add_i32 s87, s89, s70
	s_add_i32 s85, s87, 0x2000
	v_lshl_add_u64 v[174:175], s[64:65], 0, v[128:129]
	ds_read_b128 v[186:189], v147
	ds_read_b128 v[190:193], v147 offset:1024
	ds_read_b128 v[194:197], v147 offset:2048
	ds_read_b128 v[198:201], v147 offset:3072
	ds_read_b128 v[202:205], v147 offset:4096
	ds_read_b128 v[206:209], v147 offset:5120
	ds_read_b128 v[210:213], v147 offset:6144
	ds_read_b128 v[214:217], v147 offset:7168
	global_load_lds_dwordx4 v[174:175], off
	v_lshl_add_u64 v[174:175], s[64:65], 0, v[132:133]
	s_mov_b32 m0, s95
	s_nop 0
	global_load_lds_dwordx4 v[174:175], off
	s_waitcnt vmcnt(8)
	s_waitcnt lgkmcnt(0)
	s_barrier
	s_setprio 1
	s_waitcnt lgkmcnt(0)
	v_mfma_f32_16x16x32_bf16 v[124:127], v[140:143], v[186:189], v[124:127]
	v_mfma_f32_16x16x32_bf16 v[120:123], v[158:161], v[186:189], v[120:123]
	v_mfma_f32_16x16x32_bf16 v[108:111], v[140:143], v[194:197], v[108:111]
	v_mfma_f32_16x16x32_bf16 v[104:107], v[158:161], v[194:197], v[104:107]
	v_mfma_f32_16x16x32_bf16 v[92:95], v[140:143], v[202:205], v[92:95]
	v_mfma_f32_16x16x32_bf16 v[88:91], v[158:161], v[202:205], v[88:91]
	v_mfma_f32_16x16x32_bf16 v[76:79], v[140:143], v[210:213], v[76:79]
	v_mfma_f32_16x16x32_bf16 v[72:75], v[158:161], v[210:213], v[72:75]
	v_mfma_f32_16x16x32_bf16 v[124:127], v[154:157], v[190:193], v[124:127]
	v_mfma_f32_16x16x32_bf16 v[120:123], v[162:165], v[190:193], v[120:123]
	v_mfma_f32_16x16x32_bf16 v[108:111], v[154:157], v[198:201], v[108:111]
	v_mfma_f32_16x16x32_bf16 v[104:107], v[162:165], v[198:201], v[104:107]
	v_mfma_f32_16x16x32_bf16 v[92:95], v[154:157], v[206:209], v[92:95]
	v_mfma_f32_16x16x32_bf16 v[88:91], v[162:165], v[206:209], v[88:91]
	v_mfma_f32_16x16x32_bf16 v[76:79], v[154:157], v[214:217], v[76:79]
	v_mfma_f32_16x16x32_bf16 v[72:75], v[162:165], v[214:217], v[72:75]
	s_setprio 0
	s_setprio 1
	v_mfma_f32_16x16x32_bf16 v[116:119], v[166:169], v[186:189], v[116:119]
	v_mfma_f32_16x16x32_bf16 v[112:115], v[178:181], v[186:189], v[112:115]
	v_mfma_f32_16x16x32_bf16 v[100:103], v[166:169], v[194:197], v[100:103]
	v_mfma_f32_16x16x32_bf16 v[96:99], v[178:181], v[194:197], v[96:99]
	v_mfma_f32_16x16x32_bf16 v[84:87], v[166:169], v[202:205], v[84:87]
	v_mfma_f32_16x16x32_bf16 v[80:83], v[178:181], v[202:205], v[80:83]
	v_mfma_f32_16x16x32_bf16 v[68:71], v[166:169], v[210:213], v[68:71]
	v_mfma_f32_16x16x32_bf16 v[64:67], v[178:181], v[210:213], v[64:67]
	v_mfma_f32_16x16x32_bf16 v[116:119], v[170:173], v[190:193], v[116:119]
	v_mfma_f32_16x16x32_bf16 v[112:115], v[182:185], v[190:193], v[112:115]
	v_mfma_f32_16x16x32_bf16 v[100:103], v[170:173], v[198:201], v[100:103]
	v_mfma_f32_16x16x32_bf16 v[96:99], v[182:185], v[198:201], v[96:99]
	v_mfma_f32_16x16x32_bf16 v[84:87], v[170:173], v[206:209], v[84:87]
	v_mfma_f32_16x16x32_bf16 v[80:83], v[182:185], v[206:209], v[80:83]
	v_mfma_f32_16x16x32_bf16 v[68:71], v[170:173], v[214:217], v[68:71]
	v_mfma_f32_16x16x32_bf16 v[64:67], v[182:185], v[214:217], v[64:67]
	s_setprio 0
	s_barrier
	s_mov_b32 m0, s94
	v_lshl_add_u64 v[174:175], s[60:61], 0, v[130:131]
	ds_read_b128 v[186:189], v147 offset:16384
	ds_read_b128 v[190:193], v147 offset:17408
	ds_read_b128 v[194:197], v147 offset:18432
	ds_read_b128 v[198:201], v147 offset:19456
	ds_read_b128 v[202:205], v147 offset:20480
	ds_read_b128 v[206:209], v147 offset:21504
	ds_read_b128 v[210:213], v147 offset:22528
	ds_read_b128 v[214:217], v147 offset:23552
	global_load_lds_dwordx4 v[174:175], off
	v_lshl_add_u64 v[218:219], s[60:61], 0, v[134:135]
	s_mov_b32 m0, s91
	v_lshl_add_u64 v[220:221], s[62:63], 0, v[130:131]
	global_load_lds_dwordx4 v[218:219], off
	s_mov_b32 m0, s93
	v_lshl_add_u64 v[222:223], s[58:59], 0, v[132:133]
	global_load_lds_dwordx4 v[220:221], off
	v_lshl_add_u64 v[220:221], s[62:63], 0, v[134:135]
	s_mov_b32 m0, s92
	s_nop 0
	global_load_lds_dwordx4 v[220:221], off
	v_lshl_add_u64 v[220:221], s[58:59], 0, v[128:129]
	s_mov_b32 m0, s35
	s_nop 0
	global_load_lds_dwordx4 v[220:221], off
	s_mov_b32 m0, s71
	s_nop 0
	global_load_lds_dwordx4 v[222:223], off
	s_waitcnt vmcnt(8)
	s_waitcnt lgkmcnt(0)
	s_barrier
; #define PG8_STAGE(bufoff, gbase, voff) do { _Pragma("unroll") for (int _i = 0; _i < 2; ++_i) \
;         __builtin_amdgcn_global_load_lds((const unsigned*)((const char*)(gbase) + (voff)[_i]), (LAS unsigned*)(lds + (bufoff) + ldsw + _i * 8192), 16, 0, 0); } while (0)
; #define PG8_LDA(dst, b, h) do { _Pragma("unroll") for (int m = 0; m < 4; ++m) _Pragma("unroll") for (int k = 0; k < 2; ++k) dst[m][k] = *(const LAS bf16x8*)(lds + PG8_SA(b, h) + aoff + m * 2048 + k * 1024); } while (0)
; #define PG8_LDB(dst, b, h) do { _Pragma("unroll") for (int n = 0; n < 2; ++n) _Pragma("unroll") for (int k = 0; k < 2; ++k) dst[n][k] = *(const LAS bf16x8*)(lds + PG8_SB(b, h) + boff + n * 2048 + k * 1024); } while (0)
; #define PG8_MMA(ai, bj, At, Bt) do { __builtin_amdgcn_s_setprio(1); _Pragma("unroll") for (int m = 0; m < 4; ++m) _Pragma("unroll") for (int n = 0; n < 2; ++n) _Pragma("unroll") for (int k = 0; k < 2; ++k) \
;         acc[ai][bj][m][n] = __builtin_amdgcn_mfma_f32_16x16x32_bf16(Bt[n][k], At[m][k], acc[ai][bj][m][n], 0, 0, 0); __builtin_amdgcn_s_setprio(0); } while (0)
; #define PG8_WAIT_V(n) asm volatile("s_waitcnt vmcnt(" #n ")" ::: "memory")
; #define PG8_BAR __builtin_amdgcn_s_barrier()
; template <class Epi>
; __device__ __forceinline__ void gemm_phase(LAS unsigned char* lds, const Gemm g, const StaticOrder& S, const Epi& E) {
;     ...
;             PG8_LDB(B0, 0, 0); PG8_LDB(B1, 0, 1); PG8_SCHED; PG8_LDA(At, 0, 0); PG8_STAGE(PG8_SA(1, 1), a1 + hstepA, voffA);
;             PG8_WAIT_V(8); PG8_WAIT_L(0); PG8_BAR; PG8_MMA(0, 0, At, B0); PG8_MMA(0, 1, At, B1); PG8_BAR; PG8_SCHED;
;             PG8_LDA(At, 0, 1); PG8_STAGE(PG8_SB(0, 0), b2, voffB); PG8_STAGE(PG8_SB(0, 1), b2 + hstepB, voffB); PG8_STAGE(PG8_SA(0, 0), a2, voffA);
;             PG8_WAIT_V(8); PG8_WAIT_L(0); PG8_BAR; PG8_MMA(1, 0, At, B0); PG8_MMA(1, 1, At, B1); PG8_BAR; PG8_SCHED;
;             PG8_LDB(B0, 1, 0); PG8_LDB(B1, 1, 1); PG8_SCHED; PG8_LDA(At, 1, 0); PG8_STAGE(PG8_SA(0, 1), a2 + hstepA, voffA);
;             PG8_WAIT_V(8); PG8_WAIT_L(0); PG8_BAR; PG8_MMA(0, 0, At, B0); PG8_MMA(0, 1, At, B1); PG8_BAR; PG8_SCHED;
;             PG8_LDA(At, 1, 1); PG8_STAGE(PG8_SB(1, 0), b3, voffB); PG8_STAGE(PG8_SB(1, 1), b3 + hstepB, voffB); PG8_STAGE(PG8_SA(1, 0), a3, voffA);
;             PG8_WAIT_V(8); PG8_WAIT_L(0); PG8_BAR; PG8_MMA(1, 0, At, B0); PG8_MMA(1, 1, At, B1); PG8_BAR; PG8_SCHED;
	s_setprio 1
	s_waitcnt lgkmcnt(0)
	v_mfma_f32_16x16x32_bf16 v[60:63], v[140:143], v[186:189], v[60:63]
	v_mfma_f32_16x16x32_bf16 v[56:59], v[158:161], v[186:189], v[56:59]
	v_mfma_f32_16x16x32_bf16 v[44:47], v[140:143], v[194:197], v[44:47]
	v_mfma_f32_16x16x32_bf16 v[40:43], v[158:161], v[194:197], v[40:43]
	v_mfma_f32_16x16x32_bf16 v[28:31], v[140:143], v[202:205], v[28:31]
	v_mfma_f32_16x16x32_bf16 v[24:27], v[158:161], v[202:205], v[24:27]
	v_mfma_f32_16x16x32_bf16 v[12:15], v[140:143], v[210:213], v[12:15]
	v_mfma_f32_16x16x32_bf16 v[8:11], v[158:161], v[210:213], v[8:11]
	v_mfma_f32_16x16x32_bf16 v[60:63], v[154:157], v[190:193], v[60:63]
	v_mfma_f32_16x16x32_bf16 v[56:59], v[162:165], v[190:193], v[56:59]
	v_mfma_f32_16x16x32_bf16 v[44:47], v[154:157], v[198:201], v[44:47]
	v_mfma_f32_16x16x32_bf16 v[40:43], v[162:165], v[198:201], v[40:43]
	v_mfma_f32_16x16x32_bf16 v[28:31], v[154:157], v[206:209], v[28:31]
	v_mfma_f32_16x16x32_bf16 v[24:27], v[162:165], v[206:209], v[24:27]
	v_mfma_f32_16x16x32_bf16 v[12:15], v[154:157], v[214:217], v[12:15]
	v_mfma_f32_16x16x32_bf16 v[8:11], v[162:165], v[214:217], v[8:11]
	s_setprio 0
	s_setprio 1
	v_mfma_f32_16x16x32_bf16 v[52:55], v[166:169], v[186:189], v[52:55]
	v_mfma_f32_16x16x32_bf16 v[48:51], v[178:181], v[186:189], v[48:51]
	v_mfma_f32_16x16x32_bf16 v[36:39], v[166:169], v[194:197], v[36:39]
	v_mfma_f32_16x16x32_bf16 v[32:35], v[178:181], v[194:197], v[32:35]
	v_mfma_f32_16x16x32_bf16 v[20:23], v[166:169], v[202:205], v[20:23]
	v_mfma_f32_16x16x32_bf16 v[16:19], v[178:181], v[202:205], v[16:19]
	v_mfma_f32_16x16x32_bf16 v[4:7], v[166:169], v[210:213], v[4:7]
	v_mfma_f32_16x16x32_bf16 v[0:3], v[178:181], v[210:213], v[0:3]
	v_mfma_f32_16x16x32_bf16 v[52:55], v[170:173], v[190:193], v[52:55]
	v_mfma_f32_16x16x32_bf16 v[48:51], v[182:185], v[190:193], v[48:51]
	v_mfma_f32_16x16x32_bf16 v[36:39], v[170:173], v[198:201], v[36:39]
	v_mfma_f32_16x16x32_bf16 v[32:35], v[182:185], v[198:201], v[32:35]
	v_mfma_f32_16x16x32_bf16 v[20:23], v[170:173], v[206:209], v[20:23]
	v_mfma_f32_16x16x32_bf16 v[16:19], v[182:185], v[206:209], v[16:19]
	v_mfma_f32_16x16x32_bf16 v[4:7], v[170:173], v[214:217], v[4:7]
	v_mfma_f32_16x16x32_bf16 v[0:3], v[182:185], v[214:217], v[0:3]
	s_setprio 0
	s_barrier
	v_add_u32_e32 v149, s90, v144
	ds_read_b128 v[140:143], v149
	ds_read_b128 v[154:157], v149 offset:1024
	ds_read_b128 v[158:161], v149 offset:2048
	ds_read_b128 v[162:165], v149 offset:3072
	v_add_u32_e32 v149, s89, v144
	ds_read_b128 v[166:169], v149
	ds_read_b128 v[170:173], v149 offset:1024
	ds_read_b128 v[178:181], v149 offset:2048
	ds_read_b128 v[182:185], v149 offset:3072
	s_mov_b32 m0, s72
	v_lshl_add_u64 v[224:225], s[56:57], 0, v[128:129]
	ds_read_b128 v[186:189], v147 offset:32768
	ds_read_b128 v[190:193], v147 offset:33792
	ds_read_b128 v[194:197], v147 offset:34816
	ds_read_b128 v[198:201], v147 offset:35840
	ds_read_b128 v[202:205], v147 offset:36864
	ds_read_b128 v[206:209], v147 offset:37888
	ds_read_b128 v[210:213], v147 offset:38912
	ds_read_b128 v[214:217], v147 offset:39936
	global_load_lds_dwordx4 v[224:225], off
	v_lshl_add_u64 v[224:225], s[56:57], 0, v[132:133]
	s_mov_b32 m0, s73
	s_nop 0
	global_load_lds_dwordx4 v[224:225], off
	s_waitcnt vmcnt(8)
	s_waitcnt lgkmcnt(0)
	s_barrier
	s_setprio 1
	s_waitcnt lgkmcnt(0)
	v_mfma_f32_16x16x32_bf16 v[124:127], v[140:143], v[186:189], v[124:127]
	v_mfma_f32_16x16x32_bf16 v[120:123], v[158:161], v[186:189], v[120:123]
	v_mfma_f32_16x16x32_bf16 v[108:111], v[140:143], v[194:197], v[108:111]
	v_mfma_f32_16x16x32_bf16 v[104:107], v[158:161], v[194:197], v[104:107]
	v_mfma_f32_16x16x32_bf16 v[92:95], v[140:143], v[202:205], v[92:95]
	v_mfma_f32_16x16x32_bf16 v[88:91], v[158:161], v[202:205], v[88:91]
	v_mfma_f32_16x16x32_bf16 v[76:79], v[140:143], v[210:213], v[76:79]
	v_mfma_f32_16x16x32_bf16 v[72:75], v[158:161], v[210:213], v[72:75]
	v_mfma_f32_16x16x32_bf16 v[124:127], v[154:157], v[190:193], v[124:127]
	v_mfma_f32_16x16x32_bf16 v[120:123], v[162:165], v[190:193], v[120:123]
	v_mfma_f32_16x16x32_bf16 v[108:111], v[154:157], v[198:201], v[108:111]
	v_mfma_f32_16x16x32_bf16 v[104:107], v[162:165], v[198:201], v[104:107]
	v_mfma_f32_16x16x32_bf16 v[92:95], v[154:157], v[206:209], v[92:95]
	v_mfma_f32_16x16x32_bf16 v[88:91], v[162:165], v[206:209], v[88:91]
	v_mfma_f32_16x16x32_bf16 v[76:79], v[154:157], v[214:217], v[76:79]
	v_mfma_f32_16x16x32_bf16 v[72:75], v[162:165], v[214:217], v[72:75]
	s_setprio 0
	s_setprio 1
	v_mfma_f32_16x16x32_bf16 v[116:119], v[166:169], v[186:189], v[116:119]
	v_mfma_f32_16x16x32_bf16 v[112:115], v[178:181], v[186:189], v[112:115]
	v_mfma_f32_16x16x32_bf16 v[100:103], v[166:169], v[194:197], v[100:103]
	v_mfma_f32_16x16x32_bf16 v[96:99], v[178:181], v[194:197], v[96:99]
	v_mfma_f32_16x16x32_bf16 v[84:87], v[166:169], v[202:205], v[84:87]
	v_mfma_f32_16x16x32_bf16 v[80:83], v[178:181], v[202:205], v[80:83]
	v_mfma_f32_16x16x32_bf16 v[68:71], v[166:169], v[210:213], v[68:71]
	v_mfma_f32_16x16x32_bf16 v[64:67], v[178:181], v[210:213], v[64:67]
	v_mfma_f32_16x16x32_bf16 v[116:119], v[170:173], v[190:193], v[116:119]
	v_mfma_f32_16x16x32_bf16 v[112:115], v[182:185], v[190:193], v[112:115]
	v_mfma_f32_16x16x32_bf16 v[100:103], v[170:173], v[198:201], v[100:103]
	v_mfma_f32_16x16x32_bf16 v[96:99], v[182:185], v[198:201], v[96:99]
	v_mfma_f32_16x16x32_bf16 v[84:87], v[170:173], v[206:209], v[84:87]
	v_mfma_f32_16x16x32_bf16 v[80:83], v[182:185], v[206:209], v[80:83]
	v_mfma_f32_16x16x32_bf16 v[68:71], v[170:173], v[214:217], v[68:71]
	v_mfma_f32_16x16x32_bf16 v[64:67], v[182:185], v[214:217], v[64:67]
	s_setprio 0
	s_barrier
; #define PG8_STAGE(bufoff, gbase, voff) do { _Pragma("unroll") for (int _i = 0; _i < 2; ++_i) \
;         __builtin_amdgcn_global_load_lds((const unsigned*)((const char*)(gbase) + (voff)[_i]), (LAS unsigned*)(lds + (bufoff) + ldsw + _i * 8192), 16, 0, 0); } while (0)
; #define PG8_LDA(dst, b, h) do { _Pragma("unroll") for (int m = 0; m < 4; ++m) _Pragma("unroll") for (int k = 0; k < 2; ++k) dst[m][k] = *(const LAS bf16x8*)(lds + PG8_SA(b, h) + aoff + m * 2048 + k * 1024); } while (0)
; #define PG8_LDB(dst, b, h) do { _Pragma("unroll") for (int n = 0; n < 2; ++n) _Pragma("unroll") for (int k = 0; k < 2; ++k) dst[n][k] = *(const LAS bf16x8*)(lds + PG8_SB(b, h) + boff + n * 2048 + k * 1024); } while (0)
; #define PG8_WAIT_V(n) asm volatile("s_waitcnt vmcnt(" #n ")" ::: "memory")
; #define PG8_WAIT_L(n) asm volatile("s_waitcnt lgkmcnt(" #n ")" ::: "memory")
; #define PG8_BAR __builtin_amdgcn_s_barrier()
; #define PG8_SCHED __builtin_amdgcn_sched_barrier(0)
; template <class Epi>
; __device__ __forceinline__ void gemm_phase(LAS unsigned char* lds, const Gemm g, const StaticOrder& S, const Epi& E) {
;     ...
;             PG8_WAIT_V(8); PG8_WAIT_L(0); PG8_BAR; PG8_MMA(1, 0, At, B0); PG8_MMA(1, 1, At, B1); PG8_BAR; PG8_SCHED;
;             PG8_LDB(B0, 1, 0); PG8_LDB(B1, 1, 1); PG8_SCHED; PG8_LDA(At, 1, 0); PG8_STAGE(PG8_SA(0, 1), a2 + hstepA, voffA);
;             PG8_WAIT_V(8); PG8_WAIT_L(0); PG8_BAR; PG8_MMA(0, 0, At, B0); PG8_MMA(0, 1, At, B1); PG8_BAR; PG8_SCHED;
;             PG8_LDA(At, 1, 1); PG8_STAGE(PG8_SB(1, 0), b3, voffB); PG8_STAGE(PG8_SB(1, 1), b3 + hstepB, voffB); PG8_STAGE(PG8_SA(1, 0), a3, voffA);
;             PG8_WAIT_V(8); PG8_WAIT_L(0); PG8_BAR; PG8_MMA(1, 0, At, B0); PG8_MMA(1, 1, At, B1); PG8_BAR; PG8_SCHED;
;         }
;         if (wr == 0) PG8_BAR;
;     __device__ __forceinline__ void operator()(AccRef acc, const Unit& u, int wr, int wc, int fr, int fq) const {
;     ...
;         for (int it = 0; it < 8; ++it) { const int ai = it >> 2, m = it & 3, row = EPI_IT_ROW(it); float q = 0.f;
; #pragma unroll
;             for (int bj = 0; bj < 2; ++bj) { const f32x4 x0 = acc[ai][bj][m][0], x1 = acc[ai][bj][m][1];
;                 *(u32x4*)(O + (size_t)row * DM + EPI_COL(bj)) = EPI_PACK8(x0, x1);
;                 q += EPI_SQ8(x0, x1); }
;             q += __shfl_xor(q, 16); q += __shfl_xor(q, 32);
;             if (fq == 0) atomicAdd(ssout + row, q); }
	s_mov_b32 m0, s88
	v_lshl_add_u64 v[174:175], v[174:175], 0, s[10:11]
	ds_read_b128 v[186:189], v147 offset:49152
	ds_read_b128 v[190:193], v147 offset:50176
	ds_read_b128 v[194:197], v147 offset:51200
	ds_read_b128 v[198:201], v147 offset:52224
	ds_read_b128 v[202:205], v147 offset:53248
	ds_read_b128 v[206:209], v147 offset:54272
	ds_read_b128 v[210:213], v147 offset:55296
	ds_read_b128 v[214:217], v147 offset:56320
	global_load_lds_dwordx4 v[174:175], off
	v_lshl_add_u64 v[174:175], v[218:219], 0, s[10:11]
	s_mov_b32 m0, s86
	s_nop 0
	global_load_lds_dwordx4 v[174:175], off
	v_lshl_add_u64 v[174:175], s[54:55], 0, v[130:131]
	s_mov_b32 m0, s87
	s_nop 0
	global_load_lds_dwordx4 v[174:175], off
	v_lshl_add_u64 v[174:175], s[54:55], 0, v[134:135]
	s_mov_b32 m0, s85
	s_nop 0
	global_load_lds_dwordx4 v[174:175], off
	v_lshl_add_u64 v[174:175], v[220:221], 0, s[10:11]
	s_mov_b32 m0, s77
	s_nop 0
	global_load_lds_dwordx4 v[174:175], off
	v_lshl_add_u64 v[174:175], v[222:223], 0, s[10:11]
	s_mov_b32 m0, s78
	s_nop 0
	global_load_lds_dwordx4 v[174:175], off
	s_waitcnt vmcnt(8)
	s_waitcnt lgkmcnt(0)
	s_barrier
	s_setprio 1
	s_waitcnt lgkmcnt(0)
	v_mfma_f32_16x16x32_bf16 v[60:63], v[140:143], v[186:189], v[60:63]
	v_mfma_f32_16x16x32_bf16 v[56:59], v[158:161], v[186:189], v[56:59]
	v_mfma_f32_16x16x32_bf16 v[44:47], v[140:143], v[194:197], v[44:47]
	v_mfma_f32_16x16x32_bf16 v[40:43], v[158:161], v[194:197], v[40:43]
	v_mfma_f32_16x16x32_bf16 v[28:31], v[140:143], v[202:205], v[28:31]
	v_mfma_f32_16x16x32_bf16 v[24:27], v[158:161], v[202:205], v[24:27]
	v_mfma_f32_16x16x32_bf16 v[12:15], v[140:143], v[210:213], v[12:15]
	v_mfma_f32_16x16x32_bf16 v[8:11], v[158:161], v[210:213], v[8:11]
	v_mfma_f32_16x16x32_bf16 v[60:63], v[154:157], v[190:193], v[60:63]
	v_mfma_f32_16x16x32_bf16 v[56:59], v[162:165], v[190:193], v[56:59]
	v_mfma_f32_16x16x32_bf16 v[44:47], v[154:157], v[198:201], v[44:47]
	v_mfma_f32_16x16x32_bf16 v[40:43], v[162:165], v[198:201], v[40:43]
	v_mfma_f32_16x16x32_bf16 v[28:31], v[154:157], v[206:209], v[28:31]
	v_mfma_f32_16x16x32_bf16 v[24:27], v[162:165], v[206:209], v[24:27]
	v_mfma_f32_16x16x32_bf16 v[12:15], v[154:157], v[214:217], v[12:15]
	v_mfma_f32_16x16x32_bf16 v[8:11], v[162:165], v[214:217], v[8:11]
	s_setprio 0
	s_setprio 1
	v_mfma_f32_16x16x32_bf16 v[52:55], v[166:169], v[186:189], v[52:55]
	v_mfma_f32_16x16x32_bf16 v[48:51], v[178:181], v[186:189], v[48:51]
	v_mfma_f32_16x16x32_bf16 v[36:39], v[166:169], v[194:197], v[36:39]
	v_mfma_f32_16x16x32_bf16 v[32:35], v[178:181], v[194:197], v[32:35]
	v_mfma_f32_16x16x32_bf16 v[20:23], v[166:169], v[202:205], v[20:23]
	v_mfma_f32_16x16x32_bf16 v[16:19], v[178:181], v[202:205], v[16:19]
	v_mfma_f32_16x16x32_bf16 v[4:7], v[166:169], v[210:213], v[4:7]
	v_mfma_f32_16x16x32_bf16 v[0:3], v[178:181], v[210:213], v[0:3]
	v_mfma_f32_16x16x32_bf16 v[52:55], v[170:173], v[190:193], v[52:55]
	v_mfma_f32_16x16x32_bf16 v[48:51], v[182:185], v[190:193], v[48:51]
	v_mfma_f32_16x16x32_bf16 v[36:39], v[170:173], v[198:201], v[36:39]
	v_mfma_f32_16x16x32_bf16 v[32:35], v[182:185], v[198:201], v[32:35]
	v_mfma_f32_16x16x32_bf16 v[20:23], v[170:173], v[206:209], v[20:23]
	v_mfma_f32_16x16x32_bf16 v[16:19], v[182:185], v[206:209], v[16:19]
	v_mfma_f32_16x16x32_bf16 v[4:7], v[170:173], v[214:217], v[4:7]
	v_mfma_f32_16x16x32_bf16 v[0:3], v[182:185], v[214:217], v[0:3]
	s_setprio 0
	s_barrier
	s_andn2_b64 vcc, exec, s[52:53]
	s_mov_b64 s[54:55], -1
	s_mov_b64 s[52:53], 0
	s_mov_b64 s[56:57], 0x100
	s_cbranch_vccz .LBB0_1469
	s_cmp_eq_u64 s[4:5], 0
	s_cselect_b32 s99, 1, 0
	s_and_b64 vcc, exec, s[12:13]
	s_cbranch_vccz .LBB0_1472
	s_barrier
.LBB0_1472:
	v_cvt_pk_bf16_f32 v154, v124, v125
	v_mul_f32_e32 v125, v125, v125
	v_fmac_f32_e32 v125, v124, v124
	v_mul_f32_e32 v124, v127, v127
	v_cvt_pk_bf16_f32 v156, v120, v121
	v_fmac_f32_e32 v124, v126, v126
	v_mul_f32_e32 v121, v121, v121
	v_add_f32_e32 v124, v125, v124
	v_fmac_f32_e32 v121, v120, v120
	v_add_f32_e32 v120, v124, v121
	v_mul_f32_e32 v121, v123, v123
	v_fmac_f32_e32 v121, v122, v122
	v_cvt_pk_bf16_f32 v157, v122, v123
	v_add_f32_e32 v120, v121, v120
	v_mul_f32_e32 v121, v117, v117
	v_mul_f32_e32 v122, v119, v119
	v_fmac_f32_e32 v121, v116, v116
	v_fmac_f32_e32 v122, v118, v118
	v_add_f32_e32 v121, v121, v122
	v_mul_f32_e32 v122, v113, v113
	v_fmac_f32_e32 v122, v112, v112
	v_add_f32_e32 v121, v121, v122
	v_mul_f32_e32 v122, v115, v115
	v_fmac_f32_e32 v122, v114, v114
	v_mov_b32_e32 v140, v151
	v_mov_b32_e32 v141, v153
	s_lshl_b32 s1, s34, 8
	s_lshl_b32 s0, s0, 8
	v_add_f32_e32 v121, v122, v121
	v_and_b32_e32 v122, 64, v148
	s_add_i32 s1, s1, s75
	s_or_b32 s0, s0, s76
	v_add_f32_e32 v121, v120, v121
	v_xor_b32_e32 v120, 16, v148
	v_add_u32_e32 v123, 64, v122
	v_add_u32_e32 v142, s1, v140
	v_lshl_add_u32 v140, v141, 3, s0
	v_cmp_lt_i32_e64 s[0:1], v120, v123
	v_cvt_pk_bf16_f32 v122, v116, v117
	v_xor_b32_e32 v116, 32, v148
	v_ashrrev_i32_e32 v143, 31, v142
	v_cndmask_b32_e64 v120, v148, v120, s[0:1]
	v_lshlrev_b32_e32 v120, 2, v120
	ds_bpermute_b32 v124, v120, v121
	v_cmp_lt_i32_e64 s[0:1], v116, v123
	v_lshlrev_b64 v[158:159], 11, v[142:143]
	v_cmp_eq_u32_e32 vcc, 0, v141
	v_cndmask_b32_e64 v116, v148, v116, s[0:1]
	s_waitcnt lgkmcnt(0)
	v_add_f32_e32 v117, v121, v124
	v_lshlrev_b32_e32 v116, 2, v116
	ds_bpermute_b32 v121, v116, v117
	v_lshl_add_u64 v[158:159], s[40:41], 0, v[158:159]
	v_ashrrev_i32_e32 v141, 31, v140
	v_cvt_pk_bf16_f32 v155, v126, v127
	v_lshl_add_u64 v[126:127], v[140:141], 1, v[158:159]
	s_cmp_lg_u32 s99, 0
	s_cbranch_scc1 .Lwt1469_38529
	global_store_dwordx4 v[126:127], v[154:157], off
	s_branch .Lwj1469_38529

; #define EPI_PACK8(v0, v1) (u32x4){pk2((v0)[0], (v0)[1]), pk2((v0)[2], (v0)[3]), pk2((v1)[0], (v1)[1]), pk2((v1)[2], (v1)[3])}
;     __device__ __forceinline__ void operator()(AccRef acc, const Unit& u, int wr, int wc, int fr, int fq) const {
;     ...
;                 *(u32x4*)(O + (size_t)row * DM + EPI_COL(bj)) = EPI_PACK8(x0, x1);
;                 q += EPI_SQ8(x0, x1); }
;             q += __shfl_xor(q, 16); q += __shfl_xor(q, 32);
;             if (fq == 0) atomicAdd(ssout + row, q); }
.Lwj1469_38539:
	s_and_saveexec_b64 s[0:1], vcc
	s_cbranch_execz .LBB0_1474
	s_waitcnt lgkmcnt(0)
	v_add_f32_e32 v114, v117, v121
	v_lshl_add_u64 v[112:113], v[142:143], 2, s[8:9]
	global_atomic_add_f32 v[112:113], v114, off

; #define EPI_PACK8(v0, v1) (u32x4){pk2((v0)[0], (v0)[1]), pk2((v0)[2], (v0)[3]), pk2((v1)[0], (v1)[1]), pk2((v1)[2], (v1)[3])}
;     __device__ __forceinline__ void operator()(AccRef acc, const Unit& u, int wr, int wc, int fr, int fq) const {
;     ...
;                 *(u32x4*)(O + (size_t)row * DM + EPI_COL(bj)) = EPI_PACK8(x0, x1);
;                 q += EPI_SQ8(x0, x1); }
;             q += __shfl_xor(q, 16); q += __shfl_xor(q, 32);
;             if (fq == 0) atomicAdd(ssout + row, q); }
.Lwj1469_38606:
	s_and_saveexec_b64 s[0:1], vcc
	s_cbranch_execz .LBB0_1476
	s_waitcnt lgkmcnt(0)
	v_add_f32_e32 v98, v100, v101
	v_lshl_add_u64 v[96:97], v[112:113], 2, s[8:9]
	global_atomic_add_f32 v[96:97], v98, off

; #define EPI_PACK8(v0, v1) (u32x4){pk2((v0)[0], (v0)[1]), pk2((v0)[2], (v0)[3]), pk2((v1)[0], (v1)[1]), pk2((v1)[2], (v1)[3])}
;     __device__ __forceinline__ void operator()(AccRef acc, const Unit& u, int wr, int wc, int fr, int fq) const {
;     ...
;                 *(u32x4*)(O + (size_t)row * DM + EPI_COL(bj)) = EPI_PACK8(x0, x1);
;                 q += EPI_SQ8(x0, x1); }
;             q += __shfl_xor(q, 16); q += __shfl_xor(q, 32);
;             if (fq == 0) atomicAdd(ssout + row, q); }
.Lwj1469_38674:
	s_and_saveexec_b64 s[0:1], vcc
	s_cbranch_execz .LBB0_1478
	s_waitcnt lgkmcnt(0)
	v_add_f32_e32 v82, v84, v85
	v_lshl_add_u64 v[80:81], v[96:97], 2, s[8:9]
	global_atomic_add_f32 v[80:81], v82, off

; #define EPI_PACK8(v0, v1) (u32x4){pk2((v0)[0], (v0)[1]), pk2((v0)[2], (v0)[3]), pk2((v1)[0], (v1)[1]), pk2((v1)[2], (v1)[3])}
;     __device__ __forceinline__ void operator()(AccRef acc, const Unit& u, int wr, int wc, int fr, int fq) const {
;     ...
;                 *(u32x4*)(O + (size_t)row * DM + EPI_COL(bj)) = EPI_PACK8(x0, x1);
;                 q += EPI_SQ8(x0, x1); }
;             q += __shfl_xor(q, 16); q += __shfl_xor(q, 32);
;             if (fq == 0) atomicAdd(ssout + row, q); }
.Lwj1469_38742:
	s_and_saveexec_b64 s[0:1], vcc
	s_cbranch_execz .LBB0_1480
	s_waitcnt lgkmcnt(0)
	v_add_f32_e32 v66, v68, v69
	v_lshl_add_u64 v[64:65], v[80:81], 2, s[8:9]
	global_atomic_add_f32 v[64:65], v66, off

; #define EPI_PACK8(v0, v1) (u32x4){pk2((v0)[0], (v0)[1]), pk2((v0)[2], (v0)[3]), pk2((v1)[0], (v1)[1]), pk2((v1)[2], (v1)[3])}
;     __device__ __forceinline__ void operator()(AccRef acc, const Unit& u, int wr, int wc, int fr, int fq) const {
;     ...
;                 *(u32x4*)(O + (size_t)row * DM + EPI_COL(bj)) = EPI_PACK8(x0, x1);
;                 q += EPI_SQ8(x0, x1); }
;             q += __shfl_xor(q, 16); q += __shfl_xor(q, 32);
;             if (fq == 0) atomicAdd(ssout + row, q); }
.Lwj1469_38810:
	s_and_saveexec_b64 s[0:1], vcc
	s_cbranch_execz .LBB0_1482
	s_waitcnt lgkmcnt(0)
	v_add_f32_e32 v50, v52, v53
	v_lshl_add_u64 v[48:49], v[64:65], 2, s[8:9]
	global_atomic_add_f32 v[48:49], v50, off

; #define EPI_PACK8(v0, v1) (u32x4){pk2((v0)[0], (v0)[1]), pk2((v0)[2], (v0)[3]), pk2((v1)[0], (v1)[1]), pk2((v1)[2], (v1)[3])}
;     __device__ __forceinline__ void operator()(AccRef acc, const Unit& u, int wr, int wc, int fr, int fq) const {
;     ...
;                 *(u32x4*)(O + (size_t)row * DM + EPI_COL(bj)) = EPI_PACK8(x0, x1);
;                 q += EPI_SQ8(x0, x1); }
;             q += __shfl_xor(q, 16); q += __shfl_xor(q, 32);
;             if (fq == 0) atomicAdd(ssout + row, q); }
.Lwj1469_38878:
	s_and_saveexec_b64 s[0:1], vcc
	s_cbranch_execz .LBB0_1484
	s_waitcnt lgkmcnt(0)
	v_add_f32_e32 v34, v36, v37
	v_lshl_add_u64 v[32:33], v[48:49], 2, s[8:9]
	global_atomic_add_f32 v[32:33], v34, off

; #define EPI_PACK8(v0, v1) (u32x4){pk2((v0)[0], (v0)[1]), pk2((v0)[2], (v0)[3]), pk2((v1)[0], (v1)[1]), pk2((v1)[2], (v1)[3])}
;     __device__ __forceinline__ void operator()(AccRef acc, const Unit& u, int wr, int wc, int fr, int fq) const {
;     ...
;                 *(u32x4*)(O + (size_t)row * DM + EPI_COL(bj)) = EPI_PACK8(x0, x1);
;                 q += EPI_SQ8(x0, x1); }
;             q += __shfl_xor(q, 16); q += __shfl_xor(q, 32);
;             if (fq == 0) atomicAdd(ssout + row, q); }
.Lwj1469_38946:
	s_and_saveexec_b64 s[0:1], vcc
	s_cbranch_execz .LBB0_1486
	s_waitcnt lgkmcnt(0)
	v_add_f32_e32 v18, v20, v21
	v_lshl_add_u64 v[16:17], v[32:33], 2, s[8:9]
	global_atomic_add_f32 v[16:17], v18, off

; #define EPI_PACK8(v0, v1) (u32x4){pk2((v0)[0], (v0)[1]), pk2((v0)[2], (v0)[3]), pk2((v1)[0], (v1)[1]), pk2((v1)[2], (v1)[3])}
;     __device__ __forceinline__ void operator()(AccRef acc, const Unit& u, int wr, int wc, int fr, int fq) const {
;     ...
;                 *(u32x4*)(O + (size_t)row * DM + EPI_COL(bj)) = EPI_PACK8(x0, x1);
;                 q += EPI_SQ8(x0, x1); }
;             q += __shfl_xor(q, 16); q += __shfl_xor(q, 32);
;             if (fq == 0) atomicAdd(ssout + row, q); }
.Lwj1469_39014:
	s_and_saveexec_b64 s[0:1], vcc
	s_cbranch_execz .LBB0_1488
	s_waitcnt lgkmcnt(0)
	v_add_f32_e32 v2, v4, v5
	v_lshl_add_u64 v[0:1], v[16:17], 2, s[8:9]
	global_atomic_add_f32 v[0:1], v2, off

; #define PG8_STAGE(bufoff, gbase, voff) do { _Pragma("unroll") for (int _i = 0; _i < 2; ++_i) \
;         __builtin_amdgcn_global_load_lds((const unsigned*)((const char*)(gbase) + (voff)[_i]), (LAS unsigned*)(lds + (bufoff) + ldsw + _i * 8192), 16, 0, 0); } while (0)
; #define PG8_LDA(dst, b, h) do { _Pragma("unroll") for (int m = 0; m < 4; ++m) _Pragma("unroll") for (int k = 0; k < 2; ++k) dst[m][k] = *(const LAS bf16x8*)(lds + PG8_SA(b, h) + aoff + m * 2048 + k * 1024); } while (0)
; #define PG8_LDB(dst, b, h) do { _Pragma("unroll") for (int n = 0; n < 2; ++n) _Pragma("unroll") for (int k = 0; k < 2; ++k) dst[n][k] = *(const LAS bf16x8*)(lds + PG8_SB(b, h) + boff + n * 2048 + k * 1024); } while (0)
; #define PG8_WAIT_V(n) asm volatile("s_waitcnt vmcnt(" #n ")" ::: "memory")
; #define PG8_WAIT_L(n) asm volatile("s_waitcnt lgkmcnt(" #n ")" ::: "memory")
; template <class Epi>
; __device__ __forceinline__ void gemm_phase(LAS unsigned char* lds, const Gemm g, const StaticOrder& S, const Epi& E) {
;     ...
;         for (int t = 0; t < nt; t += 2) {
;             const bool last = (t == nt - 2);
;             const char* a1 = cA + (size_t)(t + 1) * kstep;
;             const char* a2 = last ? nA : cA + (size_t)(t + 2) * kstep; const char* b2 = last ? nB : cB + (size_t)(t + 2) * kstep;
;             const char* a3 = a2 + kstep; const char* b3 = b2 + kstep;
;             PG8_LDB(B0, 0, 0); PG8_LDB(B1, 0, 1); PG8_SCHED; PG8_LDA(At, 0, 0); PG8_STAGE(PG8_SA(1, 1), a1 + hstepA, voffA);
;             PG8_WAIT_V(8); PG8_WAIT_L(0); PG8_BAR; PG8_MMA(0, 0, At, B0); PG8_MMA(0, 1, At, B1); PG8_BAR; PG8_SCHED;
;             PG8_LDA(At, 0, 1); PG8_STAGE(PG8_SB(0, 0), b2, voffB); PG8_STAGE(PG8_SB(0, 1), b2 + hstepB, voffB); PG8_STAGE(PG8_SA(0, 0), a2, voffA);
;             PG8_WAIT_V(8); PG8_WAIT_L(0); PG8_BAR; PG8_MMA(1, 0, At, B0); PG8_MMA(1, 1, At, B1); PG8_BAR; PG8_SCHED;
;             PG8_LDB(B0, 1, 0); PG8_LDB(B1, 1, 1); PG8_SCHED; PG8_LDA(At, 1, 0); PG8_STAGE(PG8_SA(0, 1), a2 + hstepA, voffA);
;             PG8_WAIT_V(8); PG8_WAIT_L(0); PG8_BAR; PG8_MMA(0, 0, At, B0); PG8_MMA(0, 1, At, B1); PG8_BAR; PG8_SCHED;
;             PG8_LDA(At, 1, 1); PG8_STAGE(PG8_SB(1, 0), b3, voffB); PG8_STAGE(PG8_SB(1, 1), b3 + hstepB, voffB); PG8_STAGE(PG8_SA(1, 0), a3, voffA);
;             PG8_WAIT_V(8); PG8_WAIT_L(0); PG8_BAR; PG8_MMA(1, 0, At, B0); PG8_MMA(1, 1, At, B1); PG8_BAR; PG8_SCHED;
.LBB0_1649:
	ds_read_b128 v[128:131], v182
	ds_read_b128 v[132:135], v182 offset:1024
	ds_read_b128 v[136:139], v182 offset:2048
	ds_read_b128 v[140:143], v182 offset:3072
	ds_read_b128 v[160:163], v183
	ds_read_b128 v[164:167], v183 offset:1024
	ds_read_b128 v[168:171], v183 offset:2048
	ds_read_b128 v[172:175], v183 offset:3072
	s_add_u32 s20, s0, 0xfff50080
	s_addc_u32 s21, s1, -1
	s_cmp_eq_u32 s63, 40
	s_cselect_b32 s23, s7, s21
	s_cselect_b32 s22, s6, s20
	s_cselect_b32 s21, s19, s62
	s_cselect_b32 s20, s18, s61
	v_lshl_add_u64 v[178:179], s[0:1], 0, v[152:153]
	s_add_i32 m0, s33, 0xc000
	ds_read_b128 v[186:189], v184
	ds_read_b128 v[190:193], v184 offset:1024
	ds_read_b128 v[194:197], v184 offset:2048
	ds_read_b128 v[198:201], v184 offset:3072
	ds_read_b128 v[202:205], v184 offset:4096
	ds_read_b128 v[206:209], v184 offset:5120
	ds_read_b128 v[210:213], v184 offset:6144
	ds_read_b128 v[214:217], v184 offset:7168
	global_load_lds_dwordx4 v[178:179], off
	v_lshl_add_u64 v[178:179], s[0:1], 0, v[154:155]
	s_add_i32 m0, s33, 0xe000
	s_nop 0
	global_load_lds_dwordx4 v[178:179], off
	s_waitcnt vmcnt(8)
	s_waitcnt lgkmcnt(0)
	s_barrier
	s_setprio 1
	s_waitcnt lgkmcnt(0)
	v_mfma_f32_16x16x32_bf16 v[124:127], v[128:131], v[186:189], v[124:127]
	v_mfma_f32_16x16x32_bf16 v[120:123], v[136:139], v[186:189], v[120:123]
	v_mfma_f32_16x16x32_bf16 v[108:111], v[128:131], v[194:197], v[108:111]
	v_mfma_f32_16x16x32_bf16 v[104:107], v[136:139], v[194:197], v[104:107]
	v_mfma_f32_16x16x32_bf16 v[92:95], v[128:131], v[202:205], v[92:95]
	v_mfma_f32_16x16x32_bf16 v[88:91], v[136:139], v[202:205], v[88:91]
	v_mfma_f32_16x16x32_bf16 v[76:79], v[128:131], v[210:213], v[76:79]
	v_mfma_f32_16x16x32_bf16 v[72:75], v[136:139], v[210:213], v[72:75]
	v_mfma_f32_16x16x32_bf16 v[124:127], v[132:135], v[190:193], v[124:127]
	v_mfma_f32_16x16x32_bf16 v[120:123], v[140:143], v[190:193], v[120:123]
	v_mfma_f32_16x16x32_bf16 v[108:111], v[132:135], v[198:201], v[108:111]
	v_mfma_f32_16x16x32_bf16 v[104:107], v[140:143], v[198:201], v[104:107]
	v_mfma_f32_16x16x32_bf16 v[92:95], v[132:135], v[206:209], v[92:95]
	v_mfma_f32_16x16x32_bf16 v[88:91], v[140:143], v[206:209], v[88:91]
	v_mfma_f32_16x16x32_bf16 v[76:79], v[132:135], v[214:217], v[76:79]
	v_mfma_f32_16x16x32_bf16 v[72:75], v[140:143], v[214:217], v[72:75]
	s_setprio 0
	s_setprio 1
	v_mfma_f32_16x16x32_bf16 v[116:119], v[160:163], v[186:189], v[116:119]
	v_mfma_f32_16x16x32_bf16 v[112:115], v[168:171], v[186:189], v[112:115]
	v_mfma_f32_16x16x32_bf16 v[100:103], v[160:163], v[194:197], v[100:103]
	v_mfma_f32_16x16x32_bf16 v[96:99], v[168:171], v[194:197], v[96:99]
	v_mfma_f32_16x16x32_bf16 v[84:87], v[160:163], v[202:205], v[84:87]
	v_mfma_f32_16x16x32_bf16 v[80:83], v[168:171], v[202:205], v[80:83]
	v_mfma_f32_16x16x32_bf16 v[68:71], v[160:163], v[210:213], v[68:71]
	v_mfma_f32_16x16x32_bf16 v[64:67], v[168:171], v[210:213], v[64:67]
	v_mfma_f32_16x16x32_bf16 v[116:119], v[164:167], v[190:193], v[116:119]
	v_mfma_f32_16x16x32_bf16 v[112:115], v[172:175], v[190:193], v[112:115]
	v_mfma_f32_16x16x32_bf16 v[100:103], v[164:167], v[198:201], v[100:103]
	v_mfma_f32_16x16x32_bf16 v[96:99], v[172:175], v[198:201], v[96:99]
	v_mfma_f32_16x16x32_bf16 v[84:87], v[164:167], v[206:209], v[84:87]
	v_mfma_f32_16x16x32_bf16 v[80:83], v[172:175], v[206:209], v[80:83]
	v_mfma_f32_16x16x32_bf16 v[68:71], v[164:167], v[214:217], v[68:71]
	v_mfma_f32_16x16x32_bf16 v[64:67], v[172:175], v[214:217], v[64:67]
	s_setprio 0
	s_barrier
	s_add_i32 s64, s55, s29
	v_lshl_add_u64 v[178:179], s[20:21], 0, v[146:147]
	s_mov_b32 m0, s64
	ds_read_b128 v[186:189], v184 offset:16384
	ds_read_b128 v[190:193], v184 offset:17408
	ds_read_b128 v[194:197], v184 offset:18432
	ds_read_b128 v[198:201], v184 offset:19456
	ds_read_b128 v[202:205], v184 offset:20480
	ds_read_b128 v[206:209], v184 offset:21504
	ds_read_b128 v[210:213], v184 offset:22528
	ds_read_b128 v[214:217], v184 offset:23552
	global_load_lds_dwordx4 v[178:179], off
	s_add_i32 m0, s64, 0x2000
	s_add_u32 s64, s20, 0xb0000
	v_lshl_add_u64 v[218:219], s[20:21], 0, v[150:151]
	s_addc_u32 s65, s21, 0
	s_add_i32 s66, s56, s29
	global_load_lds_dwordx4 v[218:219], off
	v_lshl_add_u64 v[220:221], s[64:65], 0, v[146:147]
	s_mov_b32 m0, s66
	v_lshl_add_u64 v[222:223], s[22:23], 0, v[148:149]
	global_load_lds_dwordx4 v[220:221], off
	v_lshl_add_u64 v[220:221], s[64:65], 0, v[150:151]
	s_add_i32 m0, s66, 0x2000
	s_nop 0
	global_load_lds_dwordx4 v[220:221], off
	v_lshl_add_u64 v[220:221], s[22:23], 0, v[144:145]
	s_mov_b32 m0, s33
	s_nop 0
	global_load_lds_dwordx4 v[220:221], off
	s_mov_b32 m0, s34
	s_nop 0
	global_load_lds_dwordx4 v[222:223], off
	s_waitcnt vmcnt(8)
	s_waitcnt lgkmcnt(0)
	s_barrier
; #define PG8_STAGE(bufoff, gbase, voff) do { _Pragma("unroll") for (int _i = 0; _i < 2; ++_i) \
;         __builtin_amdgcn_global_load_lds((const unsigned*)((const char*)(gbase) + (voff)[_i]), (LAS unsigned*)(lds + (bufoff) + ldsw + _i * 8192), 16, 0, 0); } while (0)
; #define PG8_LDA(dst, b, h) do { _Pragma("unroll") for (int m = 0; m < 4; ++m) _Pragma("unroll") for (int k = 0; k < 2; ++k) dst[m][k] = *(const LAS bf16x8*)(lds + PG8_SA(b, h) + aoff + m * 2048 + k * 1024); } while (0)
; #define PG8_LDB(dst, b, h) do { _Pragma("unroll") for (int n = 0; n < 2; ++n) _Pragma("unroll") for (int k = 0; k < 2; ++k) dst[n][k] = *(const LAS bf16x8*)(lds + PG8_SB(b, h) + boff + n * 2048 + k * 1024); } while (0)
; #define PG8_MMA(ai, bj, At, Bt) do { __builtin_amdgcn_s_setprio(1); _Pragma("unroll") for (int m = 0; m < 4; ++m) _Pragma("unroll") for (int n = 0; n < 2; ++n) _Pragma("unroll") for (int k = 0; k < 2; ++k) \
;         acc[ai][bj][m][n] = __builtin_amdgcn_mfma_f32_16x16x32_bf16(Bt[n][k], At[m][k], acc[ai][bj][m][n], 0, 0, 0); __builtin_amdgcn_s_setprio(0); } while (0)
; #define PG8_WAIT_V(n) asm volatile("s_waitcnt vmcnt(" #n ")" ::: "memory")
; #define PG8_BAR __builtin_amdgcn_s_barrier()
; template <class Epi>
; __device__ __forceinline__ void gemm_phase(LAS unsigned char* lds, const Gemm g, const StaticOrder& S, const Epi& E) {
;     ...
;             PG8_LDB(B0, 0, 0); PG8_LDB(B1, 0, 1); PG8_SCHED; PG8_LDA(At, 0, 0); PG8_STAGE(PG8_SA(1, 1), a1 + hstepA, voffA);
;             PG8_WAIT_V(8); PG8_WAIT_L(0); PG8_BAR; PG8_MMA(0, 0, At, B0); PG8_MMA(0, 1, At, B1); PG8_BAR; PG8_SCHED;
;             PG8_LDA(At, 0, 1); PG8_STAGE(PG8_SB(0, 0), b2, voffB); PG8_STAGE(PG8_SB(0, 1), b2 + hstepB, voffB); PG8_STAGE(PG8_SA(0, 0), a2, voffA);
;             PG8_WAIT_V(8); PG8_WAIT_L(0); PG8_BAR; PG8_MMA(1, 0, At, B0); PG8_MMA(1, 1, At, B1); PG8_BAR; PG8_SCHED;
;             PG8_LDB(B0, 1, 0); PG8_LDB(B1, 1, 1); PG8_SCHED; PG8_LDA(At, 1, 0); PG8_STAGE(PG8_SA(0, 1), a2 + hstepA, voffA);
;             PG8_WAIT_V(8); PG8_WAIT_L(0); PG8_BAR; PG8_MMA(0, 0, At, B0); PG8_MMA(0, 1, At, B1); PG8_BAR; PG8_SCHED;
;             PG8_LDA(At, 1, 1); PG8_STAGE(PG8_SB(1, 0), b3, voffB); PG8_STAGE(PG8_SB(1, 1), b3 + hstepB, voffB); PG8_STAGE(PG8_SA(1, 0), a3, voffA);
;             PG8_WAIT_V(8); PG8_WAIT_L(0); PG8_BAR; PG8_MMA(1, 0, At, B0); PG8_MMA(1, 1, At, B1); PG8_BAR; PG8_SCHED;
	s_setprio 1
	s_waitcnt lgkmcnt(0)
	v_mfma_f32_16x16x32_bf16 v[60:63], v[128:131], v[186:189], v[60:63]
	v_mfma_f32_16x16x32_bf16 v[56:59], v[136:139], v[186:189], v[56:59]
	v_mfma_f32_16x16x32_bf16 v[44:47], v[128:131], v[194:197], v[44:47]
	v_mfma_f32_16x16x32_bf16 v[40:43], v[136:139], v[194:197], v[40:43]
	v_mfma_f32_16x16x32_bf16 v[28:31], v[128:131], v[202:205], v[28:31]
	v_mfma_f32_16x16x32_bf16 v[24:27], v[136:139], v[202:205], v[24:27]
	v_mfma_f32_16x16x32_bf16 v[12:15], v[128:131], v[210:213], v[12:15]
	v_mfma_f32_16x16x32_bf16 v[8:11], v[136:139], v[210:213], v[8:11]
	v_mfma_f32_16x16x32_bf16 v[60:63], v[132:135], v[190:193], v[60:63]
	v_mfma_f32_16x16x32_bf16 v[56:59], v[140:143], v[190:193], v[56:59]
	v_mfma_f32_16x16x32_bf16 v[44:47], v[132:135], v[198:201], v[44:47]
	v_mfma_f32_16x16x32_bf16 v[40:43], v[140:143], v[198:201], v[40:43]
	v_mfma_f32_16x16x32_bf16 v[28:31], v[132:135], v[206:209], v[28:31]
	v_mfma_f32_16x16x32_bf16 v[24:27], v[140:143], v[206:209], v[24:27]
	v_mfma_f32_16x16x32_bf16 v[12:15], v[132:135], v[214:217], v[12:15]
	v_mfma_f32_16x16x32_bf16 v[8:11], v[140:143], v[214:217], v[8:11]
	s_setprio 0
	s_setprio 1
	v_mfma_f32_16x16x32_bf16 v[52:55], v[160:163], v[186:189], v[52:55]
	v_mfma_f32_16x16x32_bf16 v[48:51], v[168:171], v[186:189], v[48:51]
	v_mfma_f32_16x16x32_bf16 v[36:39], v[160:163], v[194:197], v[36:39]
	v_mfma_f32_16x16x32_bf16 v[32:35], v[168:171], v[194:197], v[32:35]
	v_mfma_f32_16x16x32_bf16 v[20:23], v[160:163], v[202:205], v[20:23]
	v_mfma_f32_16x16x32_bf16 v[16:19], v[168:171], v[202:205], v[16:19]
	v_mfma_f32_16x16x32_bf16 v[4:7], v[160:163], v[210:213], v[4:7]
	v_mfma_f32_16x16x32_bf16 v[0:3], v[168:171], v[210:213], v[0:3]
	v_mfma_f32_16x16x32_bf16 v[52:55], v[164:167], v[190:193], v[52:55]
	v_mfma_f32_16x16x32_bf16 v[48:51], v[172:175], v[190:193], v[48:51]
	v_mfma_f32_16x16x32_bf16 v[36:39], v[164:167], v[198:201], v[36:39]
	v_mfma_f32_16x16x32_bf16 v[32:35], v[172:175], v[198:201], v[32:35]
	v_mfma_f32_16x16x32_bf16 v[20:23], v[164:167], v[206:209], v[20:23]
	v_mfma_f32_16x16x32_bf16 v[16:19], v[172:175], v[206:209], v[16:19]
	v_mfma_f32_16x16x32_bf16 v[4:7], v[164:167], v[214:217], v[4:7]
	v_mfma_f32_16x16x32_bf16 v[0:3], v[172:175], v[214:217], v[0:3]
	s_setprio 0
	s_barrier
	s_add_i32 s64, 0, 0x18000
	s_add_i32 s65, 0, 0x1c000
	v_add_u32_e32 v140, s64, v181
	v_add_u32_e32 v172, s65, v181
	ds_read_b128 v[128:131], v140
	ds_read_b128 v[132:135], v140 offset:1024
	ds_read_b128 v[136:139], v140 offset:2048
	ds_read_b128 v[140:143], v140 offset:3072
	ds_read_b128 v[160:163], v172
	ds_read_b128 v[164:167], v172 offset:1024
	ds_read_b128 v[168:171], v172 offset:2048
	ds_read_b128 v[172:175], v172 offset:3072
	s_add_u32 s22, s22, 0xb0000
	s_addc_u32 s23, s23, 0
	s_mov_b32 m0, s35
	v_lshl_add_u64 v[224:225], s[22:23], 0, v[144:145]
	ds_read_b128 v[186:189], v184 offset:32768
	ds_read_b128 v[190:193], v184 offset:33792
	ds_read_b128 v[194:197], v184 offset:34816
	ds_read_b128 v[198:201], v184 offset:35840
	ds_read_b128 v[202:205], v184 offset:36864
	ds_read_b128 v[206:209], v184 offset:37888
	ds_read_b128 v[210:213], v184 offset:38912
	ds_read_b128 v[214:217], v184 offset:39936
	global_load_lds_dwordx4 v[224:225], off
	v_lshl_add_u64 v[224:225], s[22:23], 0, v[148:149]
	s_mov_b32 m0, s36
	s_nop 0
	global_load_lds_dwordx4 v[224:225], off
	s_waitcnt vmcnt(8)
	s_waitcnt lgkmcnt(0)
	s_barrier
	s_setprio 1
	s_waitcnt lgkmcnt(0)
	v_mfma_f32_16x16x32_bf16 v[124:127], v[128:131], v[186:189], v[124:127]
	v_mfma_f32_16x16x32_bf16 v[120:123], v[136:139], v[186:189], v[120:123]
	v_mfma_f32_16x16x32_bf16 v[108:111], v[128:131], v[194:197], v[108:111]
	v_mfma_f32_16x16x32_bf16 v[104:107], v[136:139], v[194:197], v[104:107]
	v_mfma_f32_16x16x32_bf16 v[92:95], v[128:131], v[202:205], v[92:95]
	v_mfma_f32_16x16x32_bf16 v[88:91], v[136:139], v[202:205], v[88:91]
	v_mfma_f32_16x16x32_bf16 v[76:79], v[128:131], v[210:213], v[76:79]
	v_mfma_f32_16x16x32_bf16 v[72:75], v[136:139], v[210:213], v[72:75]
	v_mfma_f32_16x16x32_bf16 v[124:127], v[132:135], v[190:193], v[124:127]
	v_mfma_f32_16x16x32_bf16 v[120:123], v[140:143], v[190:193], v[120:123]
	v_mfma_f32_16x16x32_bf16 v[108:111], v[132:135], v[198:201], v[108:111]
	v_mfma_f32_16x16x32_bf16 v[104:107], v[140:143], v[198:201], v[104:107]
	v_mfma_f32_16x16x32_bf16 v[92:95], v[132:135], v[206:209], v[92:95]
	v_mfma_f32_16x16x32_bf16 v[88:91], v[140:143], v[206:209], v[88:91]
	v_mfma_f32_16x16x32_bf16 v[76:79], v[132:135], v[214:217], v[76:79]
	v_mfma_f32_16x16x32_bf16 v[72:75], v[140:143], v[214:217], v[72:75]
	s_setprio 0
	s_setprio 1
	v_mfma_f32_16x16x32_bf16 v[116:119], v[160:163], v[186:189], v[116:119]
	v_mfma_f32_16x16x32_bf16 v[112:115], v[168:171], v[186:189], v[112:115]
	v_mfma_f32_16x16x32_bf16 v[100:103], v[160:163], v[194:197], v[100:103]
	v_mfma_f32_16x16x32_bf16 v[96:99], v[168:171], v[194:197], v[96:99]
	v_mfma_f32_16x16x32_bf16 v[84:87], v[160:163], v[202:205], v[84:87]
	v_mfma_f32_16x16x32_bf16 v[80:83], v[168:171], v[202:205], v[80:83]
	v_mfma_f32_16x16x32_bf16 v[68:71], v[160:163], v[210:213], v[68:71]
	v_mfma_f32_16x16x32_bf16 v[64:67], v[168:171], v[210:213], v[64:67]
	v_mfma_f32_16x16x32_bf16 v[116:119], v[164:167], v[190:193], v[116:119]
	v_mfma_f32_16x16x32_bf16 v[112:115], v[172:175], v[190:193], v[112:115]
	v_mfma_f32_16x16x32_bf16 v[100:103], v[164:167], v[198:201], v[100:103]
	v_mfma_f32_16x16x32_bf16 v[96:99], v[172:175], v[198:201], v[96:99]
	v_mfma_f32_16x16x32_bf16 v[84:87], v[164:167], v[206:209], v[84:87]
	v_mfma_f32_16x16x32_bf16 v[80:83], v[172:175], v[206:209], v[80:83]
	v_mfma_f32_16x16x32_bf16 v[68:71], v[164:167], v[214:217], v[68:71]
	v_mfma_f32_16x16x32_bf16 v[64:67], v[172:175], v[214:217], v[64:67]
	s_setprio 0
	s_barrier
; #define PG8_STAGE(bufoff, gbase, voff) do { _Pragma("unroll") for (int _i = 0; _i < 2; ++_i) \
;         __builtin_amdgcn_global_load_lds((const unsigned*)((const char*)(gbase) + (voff)[_i]), (LAS unsigned*)(lds + (bufoff) + ldsw + _i * 8192), 16, 0, 0); } while (0)
; #define PG8_LDA(dst, b, h) do { _Pragma("unroll") for (int m = 0; m < 4; ++m) _Pragma("unroll") for (int k = 0; k < 2; ++k) dst[m][k] = *(const LAS bf16x8*)(lds + PG8_SA(b, h) + aoff + m * 2048 + k * 1024); } while (0)
; #define PG8_LDB(dst, b, h) do { _Pragma("unroll") for (int n = 0; n < 2; ++n) _Pragma("unroll") for (int k = 0; k < 2; ++k) dst[n][k] = *(const LAS bf16x8*)(lds + PG8_SB(b, h) + boff + n * 2048 + k * 1024); } while (0)
; #define PG8_MMA(ai, bj, At, Bt) do { __builtin_amdgcn_s_setprio(1); _Pragma("unroll") for (int m = 0; m < 4; ++m) _Pragma("unroll") for (int n = 0; n < 2; ++n) _Pragma("unroll") for (int k = 0; k < 2; ++k) \
;         acc[ai][bj][m][n] = __builtin_amdgcn_mfma_f32_16x16x32_bf16(Bt[n][k], At[m][k], acc[ai][bj][m][n], 0, 0, 0); __builtin_amdgcn_s_setprio(0); } while (0)
; #define PG8_WAIT_V(n) asm volatile("s_waitcnt vmcnt(" #n ")" ::: "memory")
; #define PG8_WAIT_L(n) asm volatile("s_waitcnt lgkmcnt(" #n ")" ::: "memory")
; #define PG8_BAR __builtin_amdgcn_s_barrier()
; #define PG8_SCHED __builtin_amdgcn_sched_barrier(0)
; template <class Epi>
; __device__ __forceinline__ void gemm_phase(LAS unsigned char* lds, const Gemm g, const StaticOrder& S, const Epi& E) {
;     ...
;             PG8_WAIT_V(8); PG8_WAIT_L(0); PG8_BAR; PG8_MMA(1, 0, At, B0); PG8_MMA(1, 1, At, B1); PG8_BAR; PG8_SCHED;
;             PG8_LDB(B0, 1, 0); PG8_LDB(B1, 1, 1); PG8_SCHED; PG8_LDA(At, 1, 0); PG8_STAGE(PG8_SA(0, 1), a2 + hstepA, voffA);
;             PG8_WAIT_V(8); PG8_WAIT_L(0); PG8_BAR; PG8_MMA(0, 0, At, B0); PG8_MMA(0, 1, At, B1); PG8_BAR; PG8_SCHED;
;             PG8_LDA(At, 1, 1); PG8_STAGE(PG8_SB(1, 0), b3, voffB); PG8_STAGE(PG8_SB(1, 1), b3 + hstepB, voffB); PG8_STAGE(PG8_SA(1, 0), a3, voffA);
;             PG8_WAIT_V(8); PG8_WAIT_L(0); PG8_BAR; PG8_MMA(1, 0, At, B0); PG8_MMA(1, 1, At, B1); PG8_BAR; PG8_SCHED;
;         }
;         if (wr == 0) PG8_BAR;
	s_add_i32 s22, s64, s29
	v_lshl_add_u64 v[178:179], v[178:179], 0, s[14:15]
	s_mov_b32 m0, s22
	ds_read_b128 v[186:189], v184 offset:49152
	ds_read_b128 v[190:193], v184 offset:50176
	ds_read_b128 v[194:197], v184 offset:51200
	ds_read_b128 v[198:201], v184 offset:52224
	ds_read_b128 v[202:205], v184 offset:53248
	ds_read_b128 v[206:209], v184 offset:54272
	ds_read_b128 v[210:213], v184 offset:55296
	ds_read_b128 v[214:217], v184 offset:56320
	global_load_lds_dwordx4 v[178:179], off
	s_add_i32 m0, s22, 0x2000
	s_add_u32 s20, s20, 0xb0080
	v_lshl_add_u64 v[178:179], v[218:219], 0, s[14:15]
	s_addc_u32 s21, s21, 0
	s_add_i32 s22, s65, s29
	global_load_lds_dwordx4 v[178:179], off
	v_lshl_add_u64 v[178:179], s[20:21], 0, v[146:147]
	s_mov_b32 m0, s22
	s_nop 0
	global_load_lds_dwordx4 v[178:179], off
	v_lshl_add_u64 v[178:179], s[20:21], 0, v[150:151]
	s_add_i32 m0, s22, 0x2000
	s_nop 0
	global_load_lds_dwordx4 v[178:179], off
	v_lshl_add_u64 v[178:179], v[220:221], 0, s[14:15]
	s_mov_b32 m0, s42
	s_nop 0
	global_load_lds_dwordx4 v[178:179], off
	v_lshl_add_u64 v[178:179], v[222:223], 0, s[14:15]
	s_mov_b32 m0, s43
	s_nop 0
	global_load_lds_dwordx4 v[178:179], off
	s_waitcnt vmcnt(8)
	s_waitcnt lgkmcnt(0)
	s_barrier
	s_setprio 1
	s_waitcnt lgkmcnt(0)
	v_mfma_f32_16x16x32_bf16 v[60:63], v[128:131], v[186:189], v[60:63]
	v_mfma_f32_16x16x32_bf16 v[56:59], v[136:139], v[186:189], v[56:59]
	v_mfma_f32_16x16x32_bf16 v[44:47], v[128:131], v[194:197], v[44:47]
	v_mfma_f32_16x16x32_bf16 v[40:43], v[136:139], v[194:197], v[40:43]
	v_mfma_f32_16x16x32_bf16 v[28:31], v[128:131], v[202:205], v[28:31]
	v_mfma_f32_16x16x32_bf16 v[24:27], v[136:139], v[202:205], v[24:27]
	v_mfma_f32_16x16x32_bf16 v[12:15], v[128:131], v[210:213], v[12:15]
	v_mfma_f32_16x16x32_bf16 v[8:11], v[136:139], v[210:213], v[8:11]
	v_mfma_f32_16x16x32_bf16 v[60:63], v[132:135], v[190:193], v[60:63]
	v_mfma_f32_16x16x32_bf16 v[56:59], v[140:143], v[190:193], v[56:59]
	v_mfma_f32_16x16x32_bf16 v[44:47], v[132:135], v[198:201], v[44:47]
	v_mfma_f32_16x16x32_bf16 v[40:43], v[140:143], v[198:201], v[40:43]
	v_mfma_f32_16x16x32_bf16 v[28:31], v[132:135], v[206:209], v[28:31]
	v_mfma_f32_16x16x32_bf16 v[24:27], v[140:143], v[206:209], v[24:27]
	v_mfma_f32_16x16x32_bf16 v[12:15], v[132:135], v[214:217], v[12:15]
	v_mfma_f32_16x16x32_bf16 v[8:11], v[140:143], v[214:217], v[8:11]
	s_setprio 0
	s_setprio 1
	v_mfma_f32_16x16x32_bf16 v[52:55], v[160:163], v[186:189], v[52:55]
	v_mfma_f32_16x16x32_bf16 v[48:51], v[168:171], v[186:189], v[48:51]
	v_mfma_f32_16x16x32_bf16 v[36:39], v[160:163], v[194:197], v[36:39]
	v_mfma_f32_16x16x32_bf16 v[32:35], v[168:171], v[194:197], v[32:35]
	v_mfma_f32_16x16x32_bf16 v[20:23], v[160:163], v[202:205], v[20:23]
	v_mfma_f32_16x16x32_bf16 v[16:19], v[168:171], v[202:205], v[16:19]
	v_mfma_f32_16x16x32_bf16 v[4:7], v[160:163], v[210:213], v[4:7]
	v_mfma_f32_16x16x32_bf16 v[0:3], v[168:171], v[210:213], v[0:3]
	v_mfma_f32_16x16x32_bf16 v[52:55], v[164:167], v[190:193], v[52:55]
	v_mfma_f32_16x16x32_bf16 v[48:51], v[172:175], v[190:193], v[48:51]
	v_mfma_f32_16x16x32_bf16 v[36:39], v[164:167], v[198:201], v[36:39]
	v_mfma_f32_16x16x32_bf16 v[32:35], v[172:175], v[198:201], v[32:35]
	v_mfma_f32_16x16x32_bf16 v[20:23], v[164:167], v[206:209], v[20:23]
	v_mfma_f32_16x16x32_bf16 v[16:19], v[172:175], v[206:209], v[16:19]
	v_mfma_f32_16x16x32_bf16 v[4:7], v[164:167], v[214:217], v[4:7]
	v_mfma_f32_16x16x32_bf16 v[0:3], v[172:175], v[214:217], v[0:3]
	s_setprio 0
	s_barrier
	s_add_i32 s63, s63, 2
	s_add_u32 s0, s0, 0x100
	s_addc_u32 s1, s1, 0
	s_add_u32 s61, s61, 0x100
	s_addc_u32 s62, s62, 0
	s_cmp_gt_u32 s63, 41
	s_cbranch_scc0 .LBB0_1649
	s_cmp_eq_u64 s[10:11], 0
	s_cselect_b32 s99, 1, 0
	s_and_b64 vcc, exec, s[16:17]
	s_cbranch_vccz .LBB0_1652
	s_barrier
; #define EPI_IT_ROW(it) EPI_ROW((it) >> 2, (it) & 3)
; #define EPI_PACK8(v0, v1) (u32x4){pk2((v0)[0], (v0)[1]), pk2((v0)[2], (v0)[3]), pk2((v1)[0], (v1)[1]), pk2((v1)[2], (v1)[3])}
;     __device__ __forceinline__ void operator()(AccRef acc, const Unit& u, int wr, int wc, int fr, int fq) const {
;     ...
;         f32x4 xc[2][2], xn[2][2];
; #pragma unroll
;         for (int bj = 0; bj < 2; ++bj) { const size_t p = (size_t)EPI_IT_ROW(0) * DM + EPI_COL(bj); xc[bj][0] = *(const f32x4*)(xin + p); xc[bj][1] = *(const f32x4*)(xin + p + 4); }
; #pragma unroll
;         for (int it = 0; it < 8; ++it) { const int ai = it >> 2, m = it & 3, row = EPI_IT_ROW(it);
;             if (it + 1 < 8) {
; #pragma unroll
;                 for (int bj = 0; bj < 2; ++bj) { const size_t p = (size_t)EPI_IT_ROW(it + 1) * DM + EPI_COL(bj); xn[bj][0] = *(const f32x4*)(xin + p); xn[bj][1] = *(const f32x4*)(xin + p + 4); } }
;             float q = 0.f;
; #pragma unroll
;             for (int bj = 0; bj < 2; ++bj) { const size_t p = (size_t)row * DM + EPI_COL(bj);
;                 const f32x4 x0 = xc[bj][0] + acc[ai][bj][m][0], x1 = xc[bj][1] + acc[ai][bj][m][1];
;                 __builtin_nontemporal_store(x0, (f32x4*)(xout + p)); __builtin_nontemporal_store(x1, (f32x4*)(xout + p + 4));
;                 *(u32x4*)(xb + p) = EPI_PACK8(x0, x1);
;                 q += EPI_SQ8(x0, x1); }
.LBB0_1652:
	s_lshl_b32 s0, s60, 8
	v_mov_b32_e32 v128, v180
	v_mov_b32_e32 v186, v177
	s_add_i32 s0, s0, s38
	v_and_b32_e32 v202, 64, v185
	v_add_u32_e32 v164, s0, v128
	s_lshl_b32 s0, s59, 8
	s_or_b32 s0, s0, s39
	v_ashrrev_i32_e32 v165, 31, v164
	v_lshl_add_u32 v162, v186, 3, s0
	v_lshlrev_b64 v[128:129], 12, v[164:165]
	v_ashrrev_i32_e32 v163, 31, v162
	v_add_u32_e32 v160, 0x80, v162
	v_lshl_add_u64 v[128:129], s[48:49], 0, v[128:129]
	v_lshlrev_b64 v[130:131], 2, v[162:163]
	v_ashrrev_i32_e32 v161, 31, v160
	v_lshl_add_u64 v[178:179], v[128:129], 0, v[130:131]
	v_lshlrev_b64 v[132:133], 2, v[160:161]
	global_load_dwordx4 v[170:173], v[178:179], off offset:16
	global_load_dwordx4 v[188:191], v[178:179], off
	v_lshl_add_u64 v[200:201], v[128:129], 0, v[132:133]
	global_load_dwordx4 v[192:195], v[200:201], off
	global_load_dwordx4 v[196:199], v[200:201], off offset:16
	v_add_u32_e32 v166, 16, v164
	v_ashrrev_i32_e32 v167, 31, v166
	v_lshlrev_b64 v[128:129], 12, v[166:167]
	v_lshl_add_u64 v[128:129], s[48:49], 0, v[128:129]
	v_lshl_add_u64 v[174:175], v[128:129], 0, v[130:131]
	v_lshl_add_u64 v[168:169], v[128:129], 0, v[132:133]
	global_load_dwordx4 v[136:139], v[174:175], off offset:16
	global_load_dwordx4 v[140:143], v[174:175], off
	global_load_dwordx4 v[128:131], v[168:169], off offset:16
	global_load_dwordx4 v[132:135], v[168:169], off
	v_xor_b32_e32 v187, 16, v185
	v_add_u32_e32 v202, 64, v202
	v_cmp_lt_i32_e64 s[0:1], v187, v202
	v_cmp_eq_u32_e32 vcc, 0, v186
	v_xor_b32_e32 v203, 32, v185
	v_cndmask_b32_e64 v186, v185, v187, s[0:1]
	v_lshlrev_b32_e32 v186, 2, v186
	v_cmp_lt_i32_e64 s[0:1], v203, v202
	s_waitcnt vmcnt(0)
	v_pk_add_f32 v[122:123], v[122:123], v[172:173]
	v_pk_add_f32 v[126:127], v[126:127], v[190:191]
	v_pk_add_f32 v[124:125], v[124:125], v[188:189]
	v_pk_add_f32 v[118:119], v[118:119], v[194:195]
	v_pk_add_f32 v[116:117], v[116:117], v[192:193]
	v_pk_add_f32 v[120:121], v[120:121], v[170:171]
	v_pk_add_f32 v[170:171], v[112:113], v[196:197]
	global_store_dwordx4 v[178:179], v[124:127], off nt
	global_store_dwordx4 v[178:179], v[120:123], off offset:16 nt
	v_cvt_pk_bf16_f32 v112, v124, v125
	v_cvt_pk_bf16_f32 v113, v126, v127
	v_mul_f32_e32 v178, v117, v117
	v_mul_f32_e32 v125, v125, v125
	v_mul_f32_e32 v127, v127, v127
	v_mul_f32_e32 v179, v119, v119
	v_pk_add_f32 v[172:173], v[114:115], v[198:199]
	v_cvt_pk_bf16_f32 v114, v120, v121
	v_cvt_pk_bf16_f32 v115, v122, v123
	v_mul_f32_e32 v121, v121, v121
	v_mul_f32_e32 v123, v123, v123
	v_mul_f32_e32 v189, v171, v171
	v_fmac_f32_e32 v125, v124, v124
	v_fmac_f32_e32 v127, v126, v126
	v_fmac_f32_e32 v178, v116, v116
	v_fmac_f32_e32 v179, v118, v118
	v_mul_f32_e32 v190, v173, v173
	v_fmac_f32_e32 v121, v120, v120
	v_fmac_f32_e32 v123, v122, v122
	v_fmac_f32_e32 v189, v170, v170
	v_add_f32_e32 v120, v125, v127
	v_add_f32_e32 v122, v178, v179
	v_fmac_f32_e32 v190, v172, v172
	v_add_f32_e32 v120, v120, v121
	v_add_f32_e32 v121, v122, v189
	v_add_f32_e32 v120, v123, v120
	v_add_f32_e32 v121, v190, v121
	v_add_f32_e32 v120, v120, v121
	ds_bpermute_b32 v121, v186, v120
	v_cndmask_b32_e64 v187, v185, v203, s[0:1]
	v_lshlrev_b64 v[202:203], 10, v[164:165]
	v_lshl_add_u64 v[204:205], v[202:203], 0, v[162:163]
	v_lshl_add_u64 v[204:205], v[204:205], 1, s[30:31]
	s_cmp_lg_u32 s99, 0
	s_cbranch_scc1 .Lwt1649_41555
	global_store_dwordx4 v[204:205], v[112:115], off
	s_branch .Lwj1649_41555

; #define PG8_STAGE(bufoff, gbase, voff) do { _Pragma("unroll") for (int _i = 0; _i < 2; ++_i) \
;         __builtin_amdgcn_global_load_lds((const unsigned*)((const char*)(gbase) + (voff)[_i]), (LAS unsigned*)(lds + (bufoff) + ldsw + _i * 8192), 16, 0, 0); } while (0)
; #define PG8_LDA(dst, b, h) do { _Pragma("unroll") for (int m = 0; m < 4; ++m) _Pragma("unroll") for (int k = 0; k < 2; ++k) dst[m][k] = *(const LAS bf16x8*)(lds + PG8_SA(b, h) + aoff + m * 2048 + k * 1024); } while (0)
; #define PG8_LDB(dst, b, h) do { _Pragma("unroll") for (int n = 0; n < 2; ++n) _Pragma("unroll") for (int k = 0; k < 2; ++k) dst[n][k] = *(const LAS bf16x8*)(lds + PG8_SB(b, h) + boff + n * 2048 + k * 1024); } while (0)
; #define PG8_MMA(ai, bj, At, Bt) do { __builtin_amdgcn_s_setprio(1); _Pragma("unroll") for (int m = 0; m < 4; ++m) _Pragma("unroll") for (int n = 0; n < 2; ++n) _Pragma("unroll") for (int k = 0; k < 2; ++k) \
;         acc[ai][bj][m][n] = __builtin_amdgcn_mfma_f32_16x16x32_bf16(Bt[n][k], At[m][k], acc[ai][bj][m][n], 0, 0, 0); __builtin_amdgcn_s_setprio(0); } while (0)
; #define PG8_WAIT_V(n) asm volatile("s_waitcnt vmcnt(" #n ")" ::: "memory")
; #define PG8_WAIT_L(n) asm volatile("s_waitcnt lgkmcnt(" #n ")" ::: "memory")
; #define PG8_BAR __builtin_amdgcn_s_barrier()
; #define PG8_SCHED __builtin_amdgcn_sched_barrier(0)
; template <class Epi>
; __device__ __forceinline__ void gemm_phase(LAS unsigned char* lds, const Gemm g, const StaticOrder& S, const Epi& E) {
;     ...
;             PG8_LDB(B0, 0, 0); PG8_LDB(B1, 0, 1); PG8_SCHED; PG8_LDA(At, 0, 0); PG8_STAGE(PG8_SA(1, 1), a1 + hstepA, voffA);
;             PG8_WAIT_V(8); PG8_WAIT_L(0); PG8_BAR; PG8_MMA(0, 0, At, B0); PG8_MMA(0, 1, At, B1); PG8_BAR; PG8_SCHED;
;             PG8_LDA(At, 0, 1); PG8_STAGE(PG8_SB(0, 0), b2, voffB); PG8_STAGE(PG8_SB(0, 1), b2 + hstepB, voffB); PG8_STAGE(PG8_SA(0, 0), a2, voffA);
;             PG8_WAIT_V(8); PG8_WAIT_L(0); PG8_BAR; PG8_MMA(1, 0, At, B0); PG8_MMA(1, 1, At, B1); PG8_BAR; PG8_SCHED;
.LBB0_1746:
	ds_read_b128 v[40:43], v208
	ds_read_b128 v[44:47], v208 offset:1024
	ds_read_b128 v[56:59], v208 offset:2048
	ds_read_b128 v[60:63], v208 offset:3072
	ds_read_b128 v[144:147], v209
	ds_read_b128 v[148:151], v209 offset:1024
	ds_read_b128 v[152:155], v209 offset:2048
	ds_read_b128 v[156:159], v209 offset:3072
	s_add_u32 s44, s42, 0xfffc0080
	s_addc_u32 s45, s43, -1
	s_cmp_eq_u32 s71, 12
	s_cselect_b32 s53, s7, s45
	s_cselect_b32 s52, s9, s44
	s_cselect_b32 s45, s29, s70
	s_cselect_b32 s44, s35, s69
	v_lshl_add_u64 v[218:219], s[42:43], 0, v[178:179]
	s_add_i32 m0, s55, 0xc000
	ds_read_b128 v[160:163], v210
	ds_read_b128 v[164:167], v210 offset:1024
	ds_read_b128 v[186:189], v210 offset:2048
	ds_read_b128 v[190:193], v210 offset:3072
	ds_read_b128 v[194:197], v210 offset:4096
	ds_read_b128 v[198:201], v210 offset:5120
	ds_read_b128 v[202:205], v210 offset:6144
	ds_read_b128 v[214:217], v210 offset:7168
	global_load_lds_dwordx4 v[218:219], off
	v_lshl_add_u64 v[218:219], s[42:43], 0, v[180:181]
	s_add_i32 m0, s55, 0xe000
	s_nop 0
	global_load_lds_dwordx4 v[218:219], off
	s_waitcnt vmcnt(8)
	s_waitcnt lgkmcnt(0)
	s_barrier
	s_setprio 1
	s_waitcnt lgkmcnt(0)
	v_mfma_f32_16x16x32_bf16 v[140:143], v[40:43], v[160:163], v[140:143]
	v_mfma_f32_16x16x32_bf16 v[136:139], v[56:59], v[160:163], v[136:139]
	v_mfma_f32_16x16x32_bf16 v[124:127], v[40:43], v[186:189], v[124:127]
	v_mfma_f32_16x16x32_bf16 v[120:123], v[56:59], v[186:189], v[120:123]
	v_mfma_f32_16x16x32_bf16 v[108:111], v[40:43], v[194:197], v[108:111]
	v_mfma_f32_16x16x32_bf16 v[104:107], v[56:59], v[194:197], v[104:107]
	v_mfma_f32_16x16x32_bf16 v[92:95], v[40:43], v[202:205], v[92:95]
	v_mfma_f32_16x16x32_bf16 v[88:91], v[56:59], v[202:205], v[88:91]
	v_mfma_f32_16x16x32_bf16 v[140:143], v[44:47], v[164:167], v[140:143]
	v_mfma_f32_16x16x32_bf16 v[136:139], v[60:63], v[164:167], v[136:139]
	v_mfma_f32_16x16x32_bf16 v[124:127], v[44:47], v[190:193], v[124:127]
	v_mfma_f32_16x16x32_bf16 v[120:123], v[60:63], v[190:193], v[120:123]
	v_mfma_f32_16x16x32_bf16 v[108:111], v[44:47], v[198:201], v[108:111]
	v_mfma_f32_16x16x32_bf16 v[104:107], v[60:63], v[198:201], v[104:107]
	v_mfma_f32_16x16x32_bf16 v[92:95], v[44:47], v[214:217], v[92:95]
	v_mfma_f32_16x16x32_bf16 v[88:91], v[60:63], v[214:217], v[88:91]
	s_setprio 0
	s_setprio 1
	v_mfma_f32_16x16x32_bf16 v[132:135], v[144:147], v[160:163], v[132:135]
	v_mfma_f32_16x16x32_bf16 v[128:131], v[152:155], v[160:163], v[128:131]
	v_mfma_f32_16x16x32_bf16 v[116:119], v[144:147], v[186:189], v[116:119]
	v_mfma_f32_16x16x32_bf16 v[112:115], v[152:155], v[186:189], v[112:115]
	v_mfma_f32_16x16x32_bf16 v[100:103], v[144:147], v[194:197], v[100:103]
	v_mfma_f32_16x16x32_bf16 v[96:99], v[152:155], v[194:197], v[96:99]
	v_mfma_f32_16x16x32_bf16 v[84:87], v[144:147], v[202:205], v[84:87]
	v_mfma_f32_16x16x32_bf16 v[80:83], v[152:155], v[202:205], v[80:83]
	v_mfma_f32_16x16x32_bf16 v[132:135], v[148:151], v[164:167], v[132:135]
	v_mfma_f32_16x16x32_bf16 v[128:131], v[156:159], v[164:167], v[128:131]
	v_mfma_f32_16x16x32_bf16 v[116:119], v[148:151], v[190:193], v[116:119]
	v_mfma_f32_16x16x32_bf16 v[112:115], v[156:159], v[190:193], v[112:115]
	v_mfma_f32_16x16x32_bf16 v[100:103], v[148:151], v[198:201], v[100:103]
	v_mfma_f32_16x16x32_bf16 v[96:99], v[156:159], v[198:201], v[96:99]
	v_mfma_f32_16x16x32_bf16 v[84:87], v[148:151], v[214:217], v[84:87]
	v_mfma_f32_16x16x32_bf16 v[80:83], v[156:159], v[214:217], v[80:83]
	s_setprio 0
	s_barrier
	s_add_i32 s72, s67, s54
	v_lshl_add_u64 v[218:219], s[44:45], 0, v[170:171]
	s_mov_b32 m0, s72
	ds_read_b128 v[160:163], v210 offset:16384
	ds_read_b128 v[164:167], v210 offset:17408
	ds_read_b128 v[186:189], v210 offset:18432
	ds_read_b128 v[190:193], v210 offset:19456
	ds_read_b128 v[194:197], v210 offset:20480
	ds_read_b128 v[198:201], v210 offset:21504
	ds_read_b128 v[202:205], v210 offset:22528
	ds_read_b128 v[214:217], v210 offset:23552
	global_load_lds_dwordx4 v[218:219], off
	s_add_i32 m0, s72, 0x2000
	s_add_u32 s72, s44, 0x40000
	v_lshl_add_u64 v[220:221], s[44:45], 0, v[174:175]
	s_addc_u32 s73, s45, 0
	s_add_i32 s74, s68, s54
	global_load_lds_dwordx4 v[220:221], off
	v_lshl_add_u64 v[222:223], s[72:73], 0, v[170:171]
	s_mov_b32 m0, s74
	v_lshl_add_u64 v[224:225], s[52:53], 0, v[172:173]
	global_load_lds_dwordx4 v[222:223], off
	v_lshl_add_u64 v[222:223], s[72:73], 0, v[174:175]
	s_add_i32 m0, s74, 0x2000
	s_nop 0
	global_load_lds_dwordx4 v[222:223], off
	v_lshl_add_u64 v[222:223], s[52:53], 0, v[168:169]
	s_mov_b32 m0, s55
	s_nop 0
	global_load_lds_dwordx4 v[222:223], off
	s_mov_b32 m0, s56
	s_nop 0
	global_load_lds_dwordx4 v[224:225], off
	s_waitcnt vmcnt(8)
	s_waitcnt lgkmcnt(0)
	s_barrier
; #define PG8_STAGE(bufoff, gbase, voff) do { _Pragma("unroll") for (int _i = 0; _i < 2; ++_i) \
;         __builtin_amdgcn_global_load_lds((const unsigned*)((const char*)(gbase) + (voff)[_i]), (LAS unsigned*)(lds + (bufoff) + ldsw + _i * 8192), 16, 0, 0); } while (0)
; #define PG8_LDA(dst, b, h) do { _Pragma("unroll") for (int m = 0; m < 4; ++m) _Pragma("unroll") for (int k = 0; k < 2; ++k) dst[m][k] = *(const LAS bf16x8*)(lds + PG8_SA(b, h) + aoff + m * 2048 + k * 1024); } while (0)
; #define PG8_LDB(dst, b, h) do { _Pragma("unroll") for (int n = 0; n < 2; ++n) _Pragma("unroll") for (int k = 0; k < 2; ++k) dst[n][k] = *(const LAS bf16x8*)(lds + PG8_SB(b, h) + boff + n * 2048 + k * 1024); } while (0)
; #define PG8_MMA(ai, bj, At, Bt) do { __builtin_amdgcn_s_setprio(1); _Pragma("unroll") for (int m = 0; m < 4; ++m) _Pragma("unroll") for (int n = 0; n < 2; ++n) _Pragma("unroll") for (int k = 0; k < 2; ++k) \
;         acc[ai][bj][m][n] = __builtin_amdgcn_mfma_f32_16x16x32_bf16(Bt[n][k], At[m][k], acc[ai][bj][m][n], 0, 0, 0); __builtin_amdgcn_s_setprio(0); } while (0)
; #define PG8_WAIT_V(n) asm volatile("s_waitcnt vmcnt(" #n ")" ::: "memory")
; #define PG8_WAIT_L(n) asm volatile("s_waitcnt lgkmcnt(" #n ")" ::: "memory")
; #define PG8_BAR __builtin_amdgcn_s_barrier()
; #define PG8_SCHED __builtin_amdgcn_sched_barrier(0)
; template <class Epi>
; __device__ __forceinline__ void gemm_phase(LAS unsigned char* lds, const Gemm g, const StaticOrder& S, const Epi& E) {
;     ...
;             PG8_WAIT_V(8); PG8_WAIT_L(0); PG8_BAR; PG8_MMA(1, 0, At, B0); PG8_MMA(1, 1, At, B1); PG8_BAR; PG8_SCHED;
;             PG8_LDB(B0, 1, 0); PG8_LDB(B1, 1, 1); PG8_SCHED; PG8_LDA(At, 1, 0); PG8_STAGE(PG8_SA(0, 1), a2 + hstepA, voffA);
;             PG8_WAIT_V(8); PG8_WAIT_L(0); PG8_BAR; PG8_MMA(0, 0, At, B0); PG8_MMA(0, 1, At, B1); PG8_BAR; PG8_SCHED;
	s_setprio 1
	s_waitcnt lgkmcnt(0)
	v_mfma_f32_16x16x32_bf16 v[76:79], v[40:43], v[160:163], v[76:79]
	v_mfma_f32_16x16x32_bf16 v[72:75], v[56:59], v[160:163], v[72:75]
	v_mfma_f32_16x16x32_bf16 v[52:55], v[40:43], v[186:189], v[52:55]
	v_mfma_f32_16x16x32_bf16 v[48:51], v[56:59], v[186:189], v[48:51]
	v_mfma_f32_16x16x32_bf16 v[28:31], v[40:43], v[194:197], v[28:31]
	v_mfma_f32_16x16x32_bf16 v[24:27], v[56:59], v[194:197], v[24:27]
	v_mfma_f32_16x16x32_bf16 v[12:15], v[40:43], v[202:205], v[12:15]
	v_mfma_f32_16x16x32_bf16 v[8:11], v[56:59], v[202:205], v[8:11]
	v_mfma_f32_16x16x32_bf16 v[76:79], v[44:47], v[164:167], v[76:79]
	v_mfma_f32_16x16x32_bf16 v[72:75], v[60:63], v[164:167], v[72:75]
	v_mfma_f32_16x16x32_bf16 v[52:55], v[44:47], v[190:193], v[52:55]
	v_mfma_f32_16x16x32_bf16 v[48:51], v[60:63], v[190:193], v[48:51]
	v_mfma_f32_16x16x32_bf16 v[28:31], v[44:47], v[198:201], v[28:31]
	v_mfma_f32_16x16x32_bf16 v[24:27], v[60:63], v[198:201], v[24:27]
	v_mfma_f32_16x16x32_bf16 v[12:15], v[44:47], v[214:217], v[12:15]
	v_mfma_f32_16x16x32_bf16 v[8:11], v[60:63], v[214:217], v[8:11]
	s_setprio 0
	s_setprio 1
	v_mfma_f32_16x16x32_bf16 v[36:39], v[144:147], v[186:189], v[36:39]
	v_mfma_f32_16x16x32_bf16 v[32:35], v[152:155], v[186:189], v[32:35]
	v_mfma_f32_16x16x32_bf16 v[20:23], v[144:147], v[194:197], v[20:23]
	v_mfma_f32_16x16x32_bf16 v[16:19], v[152:155], v[194:197], v[16:19]
	v_mfma_f32_16x16x32_bf16 v[4:7], v[144:147], v[202:205], v[4:7]
	v_mfma_f32_16x16x32_bf16 v[0:3], v[152:155], v[202:205], v[0:3]
	v_mfma_f32_16x16x32_bf16 v[40:43], v[144:147], v[160:163], v[68:71]
	v_mfma_f32_16x16x32_bf16 v[44:47], v[152:155], v[160:163], v[64:67]
	v_mfma_f32_16x16x32_bf16 v[36:39], v[148:151], v[190:193], v[36:39]
	v_mfma_f32_16x16x32_bf16 v[32:35], v[156:159], v[190:193], v[32:35]
	v_mfma_f32_16x16x32_bf16 v[20:23], v[148:151], v[198:201], v[20:23]
	v_mfma_f32_16x16x32_bf16 v[16:19], v[156:159], v[198:201], v[16:19]
	v_mfma_f32_16x16x32_bf16 v[4:7], v[148:151], v[214:217], v[4:7]
	v_mfma_f32_16x16x32_bf16 v[0:3], v[156:159], v[214:217], v[0:3]
	v_mfma_f32_16x16x32_bf16 v[40:43], v[148:151], v[164:167], v[40:43]
	v_mfma_f32_16x16x32_bf16 v[44:47], v[156:159], v[164:167], v[44:47]
	s_setprio 0
	s_barrier
	s_add_i32 s72, 0, 0x18000
	s_add_i32 s73, 0, 0x1c000
	v_add_u32_e32 v68, s72, v207
	v_add_u32_e32 v156, s73, v207
	ds_read_b128 v[56:59], v68
	ds_read_b128 v[60:63], v68 offset:1024
	ds_read_b128 v[64:67], v68 offset:2048
	ds_read_b128 v[68:71], v68 offset:3072
	ds_read_b128 v[144:147], v156
	ds_read_b128 v[148:151], v156 offset:1024
	ds_read_b128 v[152:155], v156 offset:2048
	ds_read_b128 v[156:159], v156 offset:3072
	s_add_u32 s52, s52, 0x40000
	s_addc_u32 s53, s53, 0
	s_mov_b32 m0, s57
	v_lshl_add_u64 v[226:227], s[52:53], 0, v[168:169]
	ds_read_b128 v[160:163], v210 offset:32768
	ds_read_b128 v[164:167], v210 offset:33792
	ds_read_b128 v[186:189], v210 offset:34816
	ds_read_b128 v[190:193], v210 offset:35840
	ds_read_b128 v[194:197], v210 offset:36864
	ds_read_b128 v[198:201], v210 offset:37888
	ds_read_b128 v[202:205], v210 offset:38912
	ds_read_b128 v[214:217], v210 offset:39936
	global_load_lds_dwordx4 v[226:227], off
	v_lshl_add_u64 v[226:227], s[52:53], 0, v[172:173]
	s_mov_b32 m0, s58
	s_nop 0
	global_load_lds_dwordx4 v[226:227], off
	s_waitcnt vmcnt(8)
	s_waitcnt lgkmcnt(0)
	s_barrier
	s_setprio 1
	s_waitcnt lgkmcnt(0)
	v_mfma_f32_16x16x32_bf16 v[140:143], v[56:59], v[160:163], v[140:143]
	v_mfma_f32_16x16x32_bf16 v[136:139], v[64:67], v[160:163], v[136:139]
	v_mfma_f32_16x16x32_bf16 v[124:127], v[56:59], v[186:189], v[124:127]
	v_mfma_f32_16x16x32_bf16 v[120:123], v[64:67], v[186:189], v[120:123]
	v_mfma_f32_16x16x32_bf16 v[108:111], v[56:59], v[194:197], v[108:111]
	v_mfma_f32_16x16x32_bf16 v[104:107], v[64:67], v[194:197], v[104:107]
	v_mfma_f32_16x16x32_bf16 v[92:95], v[56:59], v[202:205], v[92:95]
	v_mfma_f32_16x16x32_bf16 v[88:91], v[64:67], v[202:205], v[88:91]
	v_mfma_f32_16x16x32_bf16 v[140:143], v[60:63], v[164:167], v[140:143]
	v_mfma_f32_16x16x32_bf16 v[136:139], v[68:71], v[164:167], v[136:139]
	v_mfma_f32_16x16x32_bf16 v[124:127], v[60:63], v[190:193], v[124:127]
	v_mfma_f32_16x16x32_bf16 v[120:123], v[68:71], v[190:193], v[120:123]
	v_mfma_f32_16x16x32_bf16 v[108:111], v[60:63], v[198:201], v[108:111]
	v_mfma_f32_16x16x32_bf16 v[104:107], v[68:71], v[198:201], v[104:107]
	v_mfma_f32_16x16x32_bf16 v[92:95], v[60:63], v[214:217], v[92:95]
	v_mfma_f32_16x16x32_bf16 v[88:91], v[68:71], v[214:217], v[88:91]
	s_setprio 0
	s_setprio 1
	v_mfma_f32_16x16x32_bf16 v[132:135], v[144:147], v[160:163], v[132:135]
	v_mfma_f32_16x16x32_bf16 v[128:131], v[152:155], v[160:163], v[128:131]
	v_mfma_f32_16x16x32_bf16 v[116:119], v[144:147], v[186:189], v[116:119]
	v_mfma_f32_16x16x32_bf16 v[112:115], v[152:155], v[186:189], v[112:115]
	v_mfma_f32_16x16x32_bf16 v[100:103], v[144:147], v[194:197], v[100:103]
	v_mfma_f32_16x16x32_bf16 v[96:99], v[152:155], v[194:197], v[96:99]
	v_mfma_f32_16x16x32_bf16 v[84:87], v[144:147], v[202:205], v[84:87]
	v_mfma_f32_16x16x32_bf16 v[80:83], v[152:155], v[202:205], v[80:83]
	v_mfma_f32_16x16x32_bf16 v[132:135], v[148:151], v[164:167], v[132:135]
	v_mfma_f32_16x16x32_bf16 v[128:131], v[156:159], v[164:167], v[128:131]
	v_mfma_f32_16x16x32_bf16 v[116:119], v[148:151], v[190:193], v[116:119]
	v_mfma_f32_16x16x32_bf16 v[112:115], v[156:159], v[190:193], v[112:115]
	v_mfma_f32_16x16x32_bf16 v[100:103], v[148:151], v[198:201], v[100:103]
	v_mfma_f32_16x16x32_bf16 v[96:99], v[156:159], v[198:201], v[96:99]
	v_mfma_f32_16x16x32_bf16 v[84:87], v[148:151], v[214:217], v[84:87]
	v_mfma_f32_16x16x32_bf16 v[80:83], v[156:159], v[214:217], v[80:83]
	s_setprio 0
	s_barrier
; #define PG8_STAGE(bufoff, gbase, voff) do { _Pragma("unroll") for (int _i = 0; _i < 2; ++_i) \
;         __builtin_amdgcn_global_load_lds((const unsigned*)((const char*)(gbase) + (voff)[_i]), (LAS unsigned*)(lds + (bufoff) + ldsw + _i * 8192), 16, 0, 0); } while (0)
; #define PG8_LDA(dst, b, h) do { _Pragma("unroll") for (int m = 0; m < 4; ++m) _Pragma("unroll") for (int k = 0; k < 2; ++k) dst[m][k] = *(const LAS bf16x8*)(lds + PG8_SA(b, h) + aoff + m * 2048 + k * 1024); } while (0)
; #define PG8_MMA(ai, bj, At, Bt) do { __builtin_amdgcn_s_setprio(1); _Pragma("unroll") for (int m = 0; m < 4; ++m) _Pragma("unroll") for (int n = 0; n < 2; ++n) _Pragma("unroll") for (int k = 0; k < 2; ++k) \
;         acc[ai][bj][m][n] = __builtin_amdgcn_mfma_f32_16x16x32_bf16(Bt[n][k], At[m][k], acc[ai][bj][m][n], 0, 0, 0); __builtin_amdgcn_s_setprio(0); } while (0)
; #define PG8_WAIT_V(n) asm volatile("s_waitcnt vmcnt(" #n ")" ::: "memory")
; #define PG8_WAIT_L(n) asm volatile("s_waitcnt lgkmcnt(" #n ")" ::: "memory")
; #define PG8_BAR __builtin_amdgcn_s_barrier()
; #define PG8_SCHED __builtin_amdgcn_sched_barrier(0)
; template <class Epi>
; __device__ __forceinline__ void gemm_phase(LAS unsigned char* lds, const Gemm g, const StaticOrder& S, const Epi& E) {
;     ...
;             PG8_LDA(At, 1, 1); PG8_STAGE(PG8_SB(1, 0), b3, voffB); PG8_STAGE(PG8_SB(1, 1), b3 + hstepB, voffB); PG8_STAGE(PG8_SA(1, 0), a3, voffA);
;             PG8_WAIT_V(8); PG8_WAIT_L(0); PG8_BAR; PG8_MMA(1, 0, At, B0); PG8_MMA(1, 1, At, B1); PG8_BAR; PG8_SCHED;
;         }
;         if (wr == 0) PG8_BAR;
;         E(acc, cur, wr, wc, fr, fq);
;         if (!has_next) break;
	s_add_i32 s52, s72, s54
	v_lshl_add_u64 v[218:219], v[218:219], 0, s[20:21]
	s_mov_b32 m0, s52
	ds_read_b128 v[160:163], v210 offset:49152
	ds_read_b128 v[164:167], v210 offset:50176
	ds_read_b128 v[186:189], v210 offset:51200
	ds_read_b128 v[190:193], v210 offset:52224
	ds_read_b128 v[194:197], v210 offset:53248
	ds_read_b128 v[198:201], v210 offset:54272
	ds_read_b128 v[202:205], v210 offset:55296
	ds_read_b128 v[214:217], v210 offset:56320
	global_load_lds_dwordx4 v[218:219], off
	s_add_i32 m0, s52, 0x2000
	s_add_u32 s44, s44, 0x40080
	v_lshl_add_u64 v[218:219], v[220:221], 0, s[20:21]
	s_addc_u32 s45, s45, 0
	s_add_i32 s52, s73, s54
	global_load_lds_dwordx4 v[218:219], off
	v_lshl_add_u64 v[218:219], s[44:45], 0, v[170:171]
	s_mov_b32 m0, s52
	s_nop 0
	global_load_lds_dwordx4 v[218:219], off
	v_lshl_add_u64 v[218:219], s[44:45], 0, v[174:175]
	s_add_i32 m0, s52, 0x2000
	s_nop 0
	global_load_lds_dwordx4 v[218:219], off
	v_lshl_add_u64 v[218:219], v[222:223], 0, s[20:21]
	s_mov_b32 m0, s62
	s_nop 0
	global_load_lds_dwordx4 v[218:219], off
	v_lshl_add_u64 v[218:219], v[224:225], 0, s[20:21]
	s_mov_b32 m0, s63
	s_nop 0
	global_load_lds_dwordx4 v[218:219], off
	s_waitcnt vmcnt(8)
	s_waitcnt lgkmcnt(0)
	s_barrier
	s_setprio 1
	s_waitcnt lgkmcnt(0)
	v_mfma_f32_16x16x32_bf16 v[76:79], v[56:59], v[160:163], v[76:79]
	v_mfma_f32_16x16x32_bf16 v[72:75], v[64:67], v[160:163], v[72:75]
	v_mfma_f32_16x16x32_bf16 v[52:55], v[56:59], v[186:189], v[52:55]
	v_mfma_f32_16x16x32_bf16 v[48:51], v[64:67], v[186:189], v[48:51]
	v_mfma_f32_16x16x32_bf16 v[28:31], v[56:59], v[194:197], v[28:31]
	v_mfma_f32_16x16x32_bf16 v[24:27], v[64:67], v[194:197], v[24:27]
	v_mfma_f32_16x16x32_bf16 v[12:15], v[56:59], v[202:205], v[12:15]
	v_mfma_f32_16x16x32_bf16 v[8:11], v[64:67], v[202:205], v[8:11]
	v_mfma_f32_16x16x32_bf16 v[76:79], v[60:63], v[164:167], v[76:79]
	v_mfma_f32_16x16x32_bf16 v[72:75], v[68:71], v[164:167], v[72:75]
	v_mfma_f32_16x16x32_bf16 v[52:55], v[60:63], v[190:193], v[52:55]
	v_mfma_f32_16x16x32_bf16 v[48:51], v[68:71], v[190:193], v[48:51]
	v_mfma_f32_16x16x32_bf16 v[28:31], v[60:63], v[198:201], v[28:31]
	v_mfma_f32_16x16x32_bf16 v[24:27], v[68:71], v[198:201], v[24:27]
	v_mfma_f32_16x16x32_bf16 v[12:15], v[60:63], v[214:217], v[12:15]
	v_mfma_f32_16x16x32_bf16 v[8:11], v[68:71], v[214:217], v[8:11]
	s_setprio 0
	s_setprio 1
	v_mfma_f32_16x16x32_bf16 v[40:43], v[144:147], v[160:163], v[40:43]
	v_mfma_f32_16x16x32_bf16 v[68:71], v[148:151], v[164:167], v[40:43]
	v_mfma_f32_16x16x32_bf16 v[40:43], v[152:155], v[160:163], v[44:47]
	v_mfma_f32_16x16x32_bf16 v[36:39], v[144:147], v[186:189], v[36:39]
	v_mfma_f32_16x16x32_bf16 v[32:35], v[152:155], v[186:189], v[32:35]
	v_mfma_f32_16x16x32_bf16 v[20:23], v[144:147], v[194:197], v[20:23]
	v_mfma_f32_16x16x32_bf16 v[16:19], v[152:155], v[194:197], v[16:19]
	v_mfma_f32_16x16x32_bf16 v[4:7], v[144:147], v[202:205], v[4:7]
	v_mfma_f32_16x16x32_bf16 v[0:3], v[152:155], v[202:205], v[0:3]
	v_mfma_f32_16x16x32_bf16 v[64:67], v[156:159], v[164:167], v[40:43]
	v_mfma_f32_16x16x32_bf16 v[36:39], v[148:151], v[190:193], v[36:39]
	v_mfma_f32_16x16x32_bf16 v[32:35], v[156:159], v[190:193], v[32:35]
	v_mfma_f32_16x16x32_bf16 v[20:23], v[148:151], v[198:201], v[20:23]
	v_mfma_f32_16x16x32_bf16 v[16:19], v[156:159], v[198:201], v[16:19]
	v_mfma_f32_16x16x32_bf16 v[4:7], v[148:151], v[214:217], v[4:7]
	v_mfma_f32_16x16x32_bf16 v[0:3], v[156:159], v[214:217], v[0:3]
	s_setprio 0
	s_barrier
	s_add_i32 s71, s71, 2
	s_add_u32 s42, s42, 0x100
	s_addc_u32 s43, s43, 0
	s_add_u32 s69, s69, 0x100
	s_addc_u32 s70, s70, 0
	s_cmp_gt_u32 s71, 13
	s_cbranch_scc0 .LBB0_1746
	s_cmp_eq_u64 s[4:5], 0
	s_cselect_b32 s99, 1, 0
	s_and_b64 vcc, exec, s[22:23]
	s_cbranch_vccz .LBB0_1749
	s_barrier
